# v13: + f32->bf16 pair packing via v_cvt_pk_bf16_f32 (same RNE) + rcp-based division in finish/prologue silu/gelu
# speedup vs baseline: 1.0264x; 1.0097x over previous
.LBB0_177:
	s_or_b64 exec, exec, s[38:39]
	v_add_u32_e32 v146, 0x400, v113
	v_add_u32_e32 v147, 0x800, v113
	v_add_u32_e32 v148, 0xc00, v113
	v_add_u32_e32 v149, 0x1000, v113
	v_add_u32_e32 v150, 0x1400, v113
	v_add_u32_e32 v151, 0x1800, v113
	v_add_u32_e32 v152, 0x1c00, v113
	s_waitcnt vmcnt(0)
	ds_write2_b32 v113, v2, v3 offset1:66
	ds_write2_b32 v113, v4, v5 offset0:132 offset1:198
	ds_write2_b32 v146, v6, v7 offset0:8 offset1:74
	ds_write2_b32 v146, v8, v9 offset0:140 offset1:206
	ds_write2_b32 v147, v10, v11 offset0:16 offset1:82
	ds_write2_b32 v147, v12, v13 offset0:148 offset1:214
	ds_write2_b32 v148, v14, v15 offset0:24 offset1:90
	ds_write2_b32 v148, v16, v17 offset0:156 offset1:222
	ds_write2_b32 v149, v18, v19 offset0:32 offset1:98
	ds_write2_b32 v149, v20, v21 offset0:164 offset1:230
	ds_write2_b32 v150, v22, v23 offset0:40 offset1:106
	ds_write2_b32 v150, v24, v25 offset0:172 offset1:238
	ds_write2_b32 v151, v26, v27 offset0:48 offset1:114
	ds_write2_b32 v151, v28, v29 offset0:180 offset1:246
	ds_write2_b32 v152, v30, v31 offset0:56 offset1:122
	ds_write2_b32 v152, v32, v33 offset0:188 offset1:254
	s_waitcnt lgkmcnt(0)
	ds_read2_b32 v[6:7], v106 offset1:8
	ds_read2_b32 v[8:9], v106 offset0:33 offset1:41
	ds_read2_b32 v[10:11], v106 offset0:66 offset1:74
	ds_read2_b32 v[12:13], v106 offset0:99 offset1:107
	ds_read2_b32 v[14:15], v106 offset0:132 offset1:140
	s_waitcnt lgkmcnt(4)
	s_waitcnt lgkmcnt(3)
	ds_read2_b32 v[16:17], v106 offset0:165 offset1:173
	v_cvt_pk_bf16_f32 v2, v6, v8
	s_waitcnt lgkmcnt(3)
	s_waitcnt lgkmcnt(2)
	ds_read2_b32 v[18:19], v106 offset0:198 offset1:206
	ds_read2_b32 v[20:21], v106 offset0:231 offset1:239
	v_cvt_pk_bf16_f32 v3, v10, v12
	s_waitcnt lgkmcnt(3)
	s_waitcnt lgkmcnt(2)
	v_cvt_pk_bf16_f32 v4, v14, v16
	s_waitcnt lgkmcnt(1)
	s_waitcnt lgkmcnt(0)
	v_cvt_pk_bf16_f32 v5, v18, v20
	v_add_u32_e32 v6, s4, v105
	v_ashrrev_i32_e32 v8, 31, v6
	v_mul_lo_u32 v8, s10, v8
	v_mul_lo_u32 v10, s11, v6
	v_mad_u64_u32 v[22:23], s[36:37], s10, v6, 0
	s_add_i32 s18, s30, s13
	v_add3_u32 v23, v23, v8, v10
	s_ashr_i32 s13, s12, 31
	v_lshl_add_u64 v[22:23], v[22:23], 1, s[8:9]
	s_lshl_b64 s[12:13], s[12:13], 1
	v_lshl_add_u64 v[22:23], v[22:23], 0, s[12:13]
	v_lshl_add_u64 v[22:23], v[22:23], 0, v[100:101]
	global_store_dwordx4 v[22:23], v[2:5], off
	s_nop 1
	v_cvt_pk_bf16_f32 v2, v7, v9
	v_cvt_pk_bf16_f32 v3, v11, v13
	v_cvt_pk_bf16_f32 v4, v15, v17
	v_cvt_pk_bf16_f32 v5, v19, v21
	v_add_u32_e32 v6, s4, v107
	v_ashrrev_i32_e32 v7, 31, v6
	v_mul_lo_u32 v8, s10, v7
	v_mul_lo_u32 v9, s11, v6
	v_mad_u64_u32 v[6:7], s[36:37], s10, v6, 0
	v_add3_u32 v7, v7, v8, v9
	v_lshl_add_u64 v[6:7], v[6:7], 1, s[8:9]
	v_lshl_add_u64 v[6:7], v[6:7], 0, s[12:13]
	ds_read2_b32 v[8:9], v106 offset0:16 offset1:24
	v_lshl_add_u64 v[6:7], v[6:7], 0, v[100:101]
	global_store_dwordx4 v[6:7], v[2:5], off
	ds_read2_b32 v[6:7], v106 offset0:49 offset1:57
	ds_read2_b32 v[10:11], v106 offset0:82 offset1:90
	ds_read2_b32 v[12:13], v106 offset0:115 offset1:123
	s_waitcnt lgkmcnt(3)
	s_waitcnt lgkmcnt(2)
	ds_read2_b32 v[14:15], v106 offset0:148 offset1:156
	ds_read2_b32 v[16:17], v106 offset0:181 offset1:189
	v_cvt_pk_bf16_f32 v2, v8, v6
	s_waitcnt lgkmcnt(3)
	s_waitcnt lgkmcnt(2)
	ds_read2_b32 v[18:19], v106 offset0:214 offset1:222
	ds_read2_b32 v[20:21], v106 offset0:247 offset1:255
	v_cvt_pk_bf16_f32 v3, v10, v12
	s_waitcnt lgkmcnt(3)
	s_waitcnt lgkmcnt(2)
	v_cvt_pk_bf16_f32 v4, v14, v16
	s_waitcnt lgkmcnt(1)
	s_waitcnt lgkmcnt(0)
	v_cvt_pk_bf16_f32 v5, v18, v20
	v_add_u32_e32 v6, s4, v108
	v_ashrrev_i32_e32 v8, 31, v6
	v_mul_lo_u32 v8, s10, v8
	v_mul_lo_u32 v10, s11, v6
	v_mad_u64_u32 v[22:23], s[36:37], s10, v6, 0
	v_add3_u32 v23, v23, v8, v10
	v_lshl_add_u64 v[22:23], v[22:23], 1, s[8:9]
	v_lshl_add_u64 v[22:23], v[22:23], 0, s[12:13]
	v_lshl_add_u64 v[22:23], v[22:23], 0, v[100:101]
	global_store_dwordx4 v[22:23], v[2:5], off
	s_nop 1
	v_cvt_pk_bf16_f32 v2, v9, v7
	v_cvt_pk_bf16_f32 v3, v11, v13
	v_cvt_pk_bf16_f32 v4, v15, v17
	v_cvt_pk_bf16_f32 v5, v19, v21
	v_add_u32_e32 v6, s4, v109
	v_ashrrev_i32_e32 v7, 31, v6
	v_mul_lo_u32 v8, s10, v7
	v_mul_lo_u32 v9, s11, v6
	v_mad_u64_u32 v[6:7], s[10:11], s10, v6, 0
	v_add3_u32 v7, v7, v8, v9
	v_lshl_add_u64 v[6:7], v[6:7], 1, s[8:9]
	v_lshl_add_u64 v[6:7], v[6:7], 0, s[12:13]
	v_lshl_add_u64 v[6:7], v[6:7], 0, v[100:101]
	global_store_dwordx4 v[6:7], v[2:5], off
	s_waitcnt lgkmcnt(0)
	s_min_i32 s27, s18, 0x53ff
	s_cmpk_lt_i32 s18, 0x5200
	s_mov_b64 s[38:39], -1
	s_cbranch_scc0 .LBB0_206
	s_mul_hi_i32 s4, s27, 0x63e7063f
	s_lshr_b32 s8, s4, 31
	s_ashr_i32 s4, s4, 12
	s_add_i32 s40, s4, s8
	s_mul_i32 s4, s40, 0x2900
	s_sub_i32 s18, s27, s4
	s_ashr_i32 s41, s40, 31
	s_mul_i32 s8, s40, 0x2a00000
	s_mul_hi_i32 s4, s40, 0x2a00000
	s_add_u32 s38, s5, s8
	s_addc_u32 s39, s7, s4
	s_cmpk_gt_i32 s18, 0xaff
	s_mov_b64 s[42:43], -1
	s_cbranch_scc0 .LBB0_199
	s_cmpk_gt_u32 s18, 0x107f
	s_cbranch_scc0 .LBB0_196
	s_cmpk_gt_u32 s18, 0x167f
	s_cbranch_scc0 .LBB0_193
	s_cmpk_gt_u32 s18, 0x187f
	s_cbranch_scc0 .LBB0_190
	s_cmpk_gt_u32 s18, 0x237f
	s_mov_b64 s[10:11], -1
	s_cbranch_scc0 .LBB0_184
	v_mov_b64_e32 v[2:3], s[0:1]
	global_load_dwordx2 v[2:3], v[2:3], off offset:192 sc0 sc1
	s_waitcnt vmcnt(0)
	s_add_u32 s8, s38, 0x2380000
	s_addc_u32 s9, s39, 0
	s_lshl_b32 s4, s18, 5
	s_lshl_b32 s10, s18, 1
	s_and_b32 s36, s4, 0x3e0
	s_and_b32 s4, s10, 0x7fffffc0
	s_add_i32 s12, s4, 0xffffb900
	s_waitcnt lgkmcnt(0)
	v_mad_i64_i32 v[34:35], s[10:11], s40, v110, v[2:3]
	s_mov_b64 s[10:11], 0

.LBB0_273:
	s_waitcnt vmcnt(4)
	ds_write2_b32 v113, v115, v116 offset1:66
	ds_write2_b32 v113, v114, v117 offset0:132 offset1:198
	ds_write2_b32 v146, v119, v120 offset0:8 offset1:74
	ds_write2_b32 v146, v118, v121 offset0:140 offset1:206
	ds_write2_b32 v147, v123, v124 offset0:16 offset1:82
	ds_write2_b32 v147, v122, v125 offset0:148 offset1:214
	ds_write2_b32 v148, v127, v128 offset0:24 offset1:90
	ds_write2_b32 v148, v126, v129 offset0:156 offset1:222
	ds_write2_b32 v149, v131, v132 offset0:32 offset1:98
	ds_write2_b32 v149, v130, v133 offset0:164 offset1:230
	ds_write2_b32 v150, v135, v136 offset0:40 offset1:106
	ds_write2_b32 v150, v134, v137 offset0:172 offset1:238
	ds_write2_b32 v151, v139, v140 offset0:48 offset1:114
	ds_write2_b32 v151, v138, v141 offset0:180 offset1:246
	ds_write2_b32 v152, v143, v144 offset0:56 offset1:122
	ds_write2_b32 v152, v142, v145 offset0:188 offset1:254
	s_waitcnt lgkmcnt(0)
	ds_read2_b32 v[38:39], v106 offset1:8
	ds_read2_b32 v[40:41], v106 offset0:33 offset1:41
	ds_read2_b32 v[42:43], v106 offset0:66 offset1:74
	ds_read2_b32 v[44:45], v106 offset0:99 offset1:107
	ds_read2_b32 v[46:47], v106 offset0:132 offset1:140
	s_waitcnt lgkmcnt(4)
	s_waitcnt lgkmcnt(3)
	ds_read2_b32 v[48:49], v106 offset0:165 offset1:173
	v_cvt_pk_bf16_f32 v34, v38, v40
	s_waitcnt lgkmcnt(3)
	s_waitcnt lgkmcnt(2)
	ds_read2_b32 v[50:51], v106 offset0:198 offset1:206
	ds_read2_b32 v[52:53], v106 offset0:231 offset1:239
	v_cvt_pk_bf16_f32 v35, v42, v44
	s_waitcnt lgkmcnt(3)
	s_waitcnt lgkmcnt(2)
	v_cvt_pk_bf16_f32 v36, v46, v48
	s_waitcnt lgkmcnt(1)
	s_waitcnt lgkmcnt(0)
	v_cvt_pk_bf16_f32 v37, v50, v52
	v_add_u32_e32 v38, s35, v105
	v_ashrrev_i32_e32 v40, 31, v38
	v_mul_lo_u32 v40, s24, v40
	v_mul_lo_u32 v42, s25, v38
	v_mad_u64_u32 v[54:55], s[20:21], s24, v38, 0
	v_add3_u32 v55, v55, v40, v42
	s_ashr_i32 s27, s26, 31
	v_lshl_add_u64 v[54:55], v[54:55], 1, s[22:23]
	s_lshl_b64 s[20:21], s[26:27], 1
	v_lshl_add_u64 v[54:55], v[54:55], 0, s[20:21]
	v_lshl_add_u64 v[54:55], v[54:55], 0, v[100:101]
	global_store_dwordx4 v[54:55], v[34:37], off
	s_nop 1
	v_cvt_pk_bf16_f32 v34, v39, v41
	v_cvt_pk_bf16_f32 v35, v43, v45
	v_cvt_pk_bf16_f32 v36, v47, v49
	v_cvt_pk_bf16_f32 v37, v51, v53
	v_add_u32_e32 v38, s35, v107
	v_ashrrev_i32_e32 v39, 31, v38
	v_mul_lo_u32 v40, s24, v39
	v_mul_lo_u32 v41, s25, v38
	v_mad_u64_u32 v[38:39], s[26:27], s24, v38, 0
	v_add3_u32 v39, v39, v40, v41
	v_lshl_add_u64 v[38:39], v[38:39], 1, s[22:23]
	v_lshl_add_u64 v[38:39], v[38:39], 0, s[20:21]
	ds_read2_b32 v[40:41], v106 offset0:16 offset1:24
	v_lshl_add_u64 v[38:39], v[38:39], 0, v[100:101]
	global_store_dwordx4 v[38:39], v[34:37], off
	ds_read2_b32 v[38:39], v106 offset0:49 offset1:57
	ds_read2_b32 v[42:43], v106 offset0:82 offset1:90
	ds_read2_b32 v[44:45], v106 offset0:115 offset1:123
	s_waitcnt lgkmcnt(3)
	s_waitcnt lgkmcnt(2)
	ds_read2_b32 v[46:47], v106 offset0:148 offset1:156
	ds_read2_b32 v[48:49], v106 offset0:181 offset1:189
	v_cvt_pk_bf16_f32 v34, v40, v38
	s_waitcnt lgkmcnt(3)
	s_waitcnt lgkmcnt(2)
	ds_read2_b32 v[50:51], v106 offset0:214 offset1:222
	ds_read2_b32 v[52:53], v106 offset0:247 offset1:255
	v_cvt_pk_bf16_f32 v35, v42, v44
	s_waitcnt lgkmcnt(3)
	s_waitcnt lgkmcnt(2)
	v_cvt_pk_bf16_f32 v36, v46, v48
	s_waitcnt lgkmcnt(1)
	s_waitcnt lgkmcnt(0)
	v_cvt_pk_bf16_f32 v37, v50, v52
	v_add_u32_e32 v38, s35, v108
	v_ashrrev_i32_e32 v40, 31, v38
	v_mul_lo_u32 v40, s24, v40
	v_mul_lo_u32 v42, s25, v38
	v_mad_u64_u32 v[54:55], s[26:27], s24, v38, 0
	v_add3_u32 v55, v55, v40, v42
	v_lshl_add_u64 v[54:55], v[54:55], 1, s[22:23]
	v_lshl_add_u64 v[54:55], v[54:55], 0, s[20:21]
	v_lshl_add_u64 v[54:55], v[54:55], 0, v[100:101]
	global_store_dwordx4 v[54:55], v[34:37], off
	s_nop 1
	v_cvt_pk_bf16_f32 v34, v41, v39
	v_cvt_pk_bf16_f32 v35, v43, v45
	v_cvt_pk_bf16_f32 v36, v47, v49
	v_cvt_pk_bf16_f32 v37, v51, v53
	v_add_u32_e32 v38, s35, v109
	v_ashrrev_i32_e32 v39, 31, v38
	v_mul_lo_u32 v40, s24, v39
	v_mul_lo_u32 v41, s25, v38
	v_mad_u64_u32 v[38:39], s[24:25], s24, v38, 0
	v_add3_u32 v39, v39, v40, v41
	v_lshl_add_u64 v[38:39], v[38:39], 1, s[22:23]
	v_lshl_add_u64 v[38:39], v[38:39], 0, s[20:21]
	v_lshl_add_u64 v[38:39], v[38:39], 0, v[100:101]
	global_store_dwordx4 v[38:39], v[34:37], off
	s_waitcnt lgkmcnt(0)
	s_branch .LBB0_113

.LBB0_283:
	s_waitcnt vmcnt(0)
	v_mov_b64_e32 v[2:3], s[0:1]
	global_load_dwordx2 v[4:5], v[2:3], off offset:16 sc0 sc1
	s_waitcnt vmcnt(0)
	global_load_dwordx2 v[6:7], v[2:3], off offset:24 sc0 sc1
	s_waitcnt vmcnt(0)
	global_load_dwordx2 v[8:9], v[2:3], off offset:72 sc0 sc1
	s_waitcnt vmcnt(0)
	s_and_b32 s4, s60, 0x7f
	s_mul_i32 s4, s4, 9
	s_lshr_b32 s8, s4, 1
	s_add_i32 s4, s4, 9
	s_ashr_i32 s2, s60, 7
	v_min_i32_e32 v16, 0xff, v0
	s_lshr_b32 s4, s4, 1
	s_add_i32 s3, s3, s8
	v_lshrrev_b32_e32 v22, 4, v16
	s_cmp_lt_u32 s3, s4
	s_movk_i32 s5, 0x200
	v_or_b32_e32 v22, 0x80, v22
	s_cselect_b64 s[12:13], -1, 0
	v_mov_b32_e32 v19, 0
	v_lshrrev_b32_e32 v27, 4, v0
	v_or_b32_e32 v13, 0x200, v0
	v_or_b32_e32 v14, 0x600, v0
	v_lshlrev_b32_e32 v16, 2, v16
	v_cmp_gt_u32_e32 vcc, s5, v0
	v_min_u32_e32 v22, 0x81, v22
	s_and_b64 s[4:5], s[12:13], exec
	v_mov_b32_e32 v24, 0x2400000
	v_lshlrev_b32_e32 v12, 4, v0
	v_lshlrev_b32_e32 v10, 12, v27
	v_lshrrev_b32_e32 v28, 4, v13
	v_lshrrev_b32_e32 v73, 4, v14
	v_mov_b32_e32 v23, v19
	v_and_b32_e32 v26, 60, v16
	v_lshlrev_b32_e32 v22, 12, v22
	s_cselect_b32 s3, s3, s8
	v_and_b32_e32 v72, 15, v0
	s_mov_b32 s19, 0
	v_mov_b32_e32 v11, v19
	v_and_b32_e32 v20, 0xf0, v12
	v_mov_b32_e32 v13, v19
	v_mov_b32_e32 v15, v19
	v_mov_b32_e32 v59, v19
	v_lshlrev_b32_e32 v12, 12, v28
	v_or_b32_e32 v14, 0x40000, v10
	v_or_b32_e32 v25, 0xffffff80, v73
	v_lshlrev_b32_e32 v58, 2, v26
	s_lshl_b32 s18, s3, 4
	v_lshrrev_b32_e32 v1, 4, v98
	s_mov_b32 s6, 0xfff80000
	v_lshlrev_b32_e32 v2, 2, v72
	v_mov_b32_e32 v3, v19
	v_cndmask_b32_e32 v16, v25, v73, vcc
	v_mul_u32_u24_e32 v18, 0x48000, v1
	s_mov_b32 s7, 0x9000
	s_mov_b32 s3, 0x12000
	v_mov_b32_e32 v21, v19
	v_mov_b32_e32 v17, v19
	v_lshlrev_b64 v[16:17], 12, v[16:17]
	s_waitcnt lgkmcnt(0)
	s_barrier
	v_and_b32_e32 v74, 0x78, v99
	v_lshl_add_u64 v[60:61], v[4:5], 0, v[22:23]
	v_lshl_add_u64 v[10:11], v[6:7], 0, v[10:11]
	v_mad_i64_i32 v[8:9], s[4:5], s2, v24, v[8:9]
	v_lshl_add_u64 v[12:13], v[6:7], 0, v[12:13]
	v_lshl_add_u64 v[14:15], v[6:7], 0, v[14:15]
	v_cndmask_b32_e32 v7, v5, v7, vcc
	v_cndmask_b32_e32 v6, v4, v6, vcc
	v_lshl_add_u64 v[4:5], s[18:19], 2, v[8:9]
	v_lshl_add_u64 v[24:25], v[60:61], 0, v[58:59]
	v_lshl_add_u64 v[30:31], v[4:5], 0, v[2:3]
	v_add_co_u32_e32 v2, vcc, s6, v24
	v_lshl_add_u64 v[70:71], v[30:31], 0, v[18:19]
	s_nop 0
	v_addc_co_u32_e32 v3, vcc, -1, v25, vcc
	v_add_co_u32_e32 v30, vcc, s7, v70
	v_lshl_add_u64 v[66:67], v[10:11], 0, v[20:21]
	s_nop 0
	v_addc_co_u32_e32 v31, vcc, 0, v71, vcc
	v_add_co_u32_e32 v32, vcc, s3, v70
	s_mov_b32 s3, 0x1b000
	s_nop 0
	v_addc_co_u32_e32 v33, vcc, 0, v71, vcc
	v_add_co_u32_e32 v34, vcc, s3, v70
	s_mov_b32 s3, 0x24000
	s_nop 0
	v_addc_co_u32_e32 v35, vcc, 0, v71, vcc
	v_lshl_add_u64 v[62:63], v[12:13], 0, v[20:21]
	v_lshl_add_u64 v[64:65], v[14:15], 0, v[20:21]
	v_lshl_add_u64 v[22:23], v[6:7], 0, v[16:17]
	global_load_dwordx4 v[14:17], v[66:67], off
	global_load_dwordx4 v[10:13], v[62:63], off
	global_load_dwordx4 v[6:9], v[64:65], off
	v_add_co_u32_e32 v36, vcc, s3, v70
	s_mov_b32 s3, 0x2d000
	s_nop 0
	v_addc_co_u32_e32 v37, vcc, 0, v71, vcc
	v_add_co_u32_e32 v38, vcc, s3, v70
	s_mov_b32 s3, 0x36000
	s_nop 0
	v_addc_co_u32_e32 v39, vcc, 0, v71, vcc
	v_add_co_u32_e32 v40, vcc, s3, v70
	s_mov_b32 s3, 0x3f000
	s_nop 0
	v_addc_co_u32_e32 v41, vcc, 0, v71, vcc
	v_add_co_u32_e32 v42, vcc, s3, v70
	s_mov_b32 s3, 0x120000
	s_nop 0
	v_addc_co_u32_e32 v43, vcc, 0, v71, vcc
	v_add_co_u32_e32 v44, vcc, s3, v70
	s_mov_b32 s3, 0x129000
	s_nop 0
	v_addc_co_u32_e32 v45, vcc, 0, v71, vcc
	v_lshl_add_u64 v[68:69], v[22:23], 0, v[20:21]
	global_load_dwordx4 v[2:5], v[2:3], off
	s_waitcnt vmcnt(3)
	v_mul_f32_e32 v29, 0xbfb8aa3b, v14
	global_load_dword v20, v[70:71], off
	global_load_dword v26, v[30:31], off
	global_load_dword v25, v[32:33], off
	global_load_dword v24, v[34:35], off
	global_load_dword v23, v[36:37], off
	global_load_dword v22, v[38:39], off
	global_load_dword v21, v[40:41], off
	global_load_dword v18, v[42:43], off
	global_load_dword v117, v[44:45], off
	v_add_co_u32_e32 v30, vcc, s3, v70
	s_mov_b32 s3, 0x132000
	s_nop 0
	v_addc_co_u32_e32 v31, vcc, 0, v71, vcc
	v_add_co_u32_e32 v32, vcc, s3, v70
	s_mov_b32 s3, 0x13b000
	s_nop 0
	v_addc_co_u32_e32 v33, vcc, 0, v71, vcc
	v_add_co_u32_e32 v34, vcc, s3, v70
	s_mov_b32 s3, 0x144000
	s_nop 0
	v_addc_co_u32_e32 v35, vcc, 0, v71, vcc
	v_add_co_u32_e32 v36, vcc, s3, v70
	s_mov_b32 s3, 0x14d000
	s_nop 0
	v_addc_co_u32_e32 v37, vcc, 0, v71, vcc
	v_add_co_u32_e32 v38, vcc, s3, v70
	s_mov_b32 s3, 0x156000
	s_nop 0
	v_addc_co_u32_e32 v39, vcc, 0, v71, vcc
	v_add_co_u32_e32 v40, vcc, s3, v70
	s_mov_b32 s3, 0x15f000
	s_nop 0
	v_addc_co_u32_e32 v41, vcc, 0, v71, vcc
	v_add_co_u32_e32 v42, vcc, s3, v70
	s_mov_b32 s3, 0x240000
	s_nop 0
	v_addc_co_u32_e32 v43, vcc, 0, v71, vcc
	v_add_co_u32_e32 v44, vcc, s3, v70
	s_mov_b32 s3, 0x249000
	s_nop 0
	v_addc_co_u32_e32 v45, vcc, 0, v71, vcc
	global_load_dword v135, v[30:31], off
	global_load_dword v132, v[32:33], off
	global_load_dword v129, v[34:35], off
	global_load_dword v126, v[36:37], off
	global_load_dword v123, v[38:39], off
	global_load_dword v120, v[40:41], off
	global_load_dword v113, v[42:43], off
	global_load_dword v85, v[44:45], off
	v_add_co_u32_e32 v30, vcc, s3, v70
	s_mov_b32 s3, 0x252000
	s_nop 0
	v_addc_co_u32_e32 v31, vcc, 0, v71, vcc
	v_add_co_u32_e32 v32, vcc, s3, v70
	s_mov_b32 s3, 0x25b000
	s_nop 0
	v_addc_co_u32_e32 v33, vcc, 0, v71, vcc
	v_add_co_u32_e32 v34, vcc, s3, v70
	s_mov_b32 s3, 0x264000
	s_nop 0
	v_addc_co_u32_e32 v35, vcc, 0, v71, vcc
	v_add_co_u32_e32 v36, vcc, s3, v70
	s_mov_b32 s3, 0x26d000
	s_nop 0
	v_addc_co_u32_e32 v37, vcc, 0, v71, vcc
	v_add_co_u32_e32 v38, vcc, s3, v70
	s_mov_b32 s3, 0x276000
	s_nop 0
	v_addc_co_u32_e32 v39, vcc, 0, v71, vcc
	v_add_co_u32_e32 v40, vcc, s3, v70
	s_mov_b32 s3, 0x27f000
	s_nop 0
	v_addc_co_u32_e32 v41, vcc, 0, v71, vcc
	v_add_co_u32_e32 v42, vcc, s3, v70
	s_mov_b32 s3, 0x360000
	s_nop 0
	v_addc_co_u32_e32 v43, vcc, 0, v71, vcc
	v_add_co_u32_e32 v44, vcc, s3, v70
	s_mov_b32 s3, 0x369000
	s_nop 0
	v_addc_co_u32_e32 v45, vcc, 0, v71, vcc
	global_load_dword v110, v[30:31], off
	global_load_dword v106, v[32:33], off
	global_load_dword v102, v[34:35], off
	global_load_dword v97, v[36:37], off
	global_load_dword v92, v[38:39], off
	global_load_dword v89, v[40:41], off
	global_load_dword v80, v[42:43], off
	global_load_dword v121, v[44:45], off
	v_add_co_u32_e32 v30, vcc, s3, v70
	s_mov_b32 s3, 0x372000
	s_nop 0
	v_addc_co_u32_e32 v31, vcc, 0, v71, vcc
	v_add_co_u32_e32 v32, vcc, s3, v70
	s_mov_b32 s3, 0x37b000
	s_nop 0
	v_addc_co_u32_e32 v33, vcc, 0, v71, vcc
	v_add_co_u32_e32 v34, vcc, s3, v70
	s_mov_b32 s3, 0x384000
	s_nop 0
	v_addc_co_u32_e32 v35, vcc, 0, v71, vcc
	v_add_co_u32_e32 v36, vcc, s3, v70
	s_mov_b32 s3, 0x38d000
	s_nop 0
	v_addc_co_u32_e32 v37, vcc, 0, v71, vcc
	v_add_co_u32_e32 v38, vcc, s3, v70
	s_mov_b32 s3, 0x396000
	s_nop 0
	v_addc_co_u32_e32 v39, vcc, 0, v71, vcc
	v_add_co_u32_e32 v40, vcc, s3, v70
	s_mov_b32 s3, 0x39f000
	s_nop 0
	v_addc_co_u32_e32 v41, vcc, 0, v71, vcc
	v_add_co_u32_e32 v42, vcc, s3, v70
	s_mov_b32 s3, 0x480000
	s_nop 0
	v_addc_co_u32_e32 v43, vcc, 0, v71, vcc
	v_add_co_u32_e32 v44, vcc, s3, v70
	s_mov_b32 s3, 0x489000
	s_nop 0
	v_addc_co_u32_e32 v45, vcc, 0, v71, vcc
	global_load_dword v137, v[30:31], off
	global_load_dword v136, v[32:33], off
	global_load_dword v133, v[34:35], off
	global_load_dword v130, v[36:37], off
	global_load_dword v127, v[38:39], off
	global_load_dword v125, v[40:41], off
	global_load_dword v118, v[42:43], off
	global_load_dword v86, v[44:45], off
	v_add_co_u32_e32 v30, vcc, s3, v70
	s_mov_b32 s3, 0x492000
	s_nop 0
	v_addc_co_u32_e32 v31, vcc, 0, v71, vcc
	v_add_co_u32_e32 v32, vcc, s3, v70
	s_mov_b32 s3, 0x49b000
	s_nop 0
	v_addc_co_u32_e32 v33, vcc, 0, v71, vcc
	v_add_co_u32_e32 v34, vcc, s3, v70
	s_mov_b32 s3, 0x4a4000
	s_nop 0
	v_addc_co_u32_e32 v35, vcc, 0, v71, vcc
	v_add_co_u32_e32 v36, vcc, s3, v70
	s_mov_b32 s3, 0x4ad000
	s_nop 0
	v_addc_co_u32_e32 v37, vcc, 0, v71, vcc
	v_add_co_u32_e32 v38, vcc, s3, v70
	s_mov_b32 s3, 0x4b6000
	s_nop 0
	v_addc_co_u32_e32 v39, vcc, 0, v71, vcc
	v_add_co_u32_e32 v40, vcc, s3, v70
	s_mov_b32 s3, 0x4bf000
	s_nop 0
	v_addc_co_u32_e32 v41, vcc, 0, v71, vcc
	v_add_co_u32_e32 v42, vcc, s3, v70
	s_mov_b32 s3, 0x5a0000
	s_nop 0
	v_addc_co_u32_e32 v43, vcc, 0, v71, vcc
	v_add_co_u32_e32 v44, vcc, s3, v70
	s_mov_b32 s3, 0x5a9000
	s_nop 0
	v_addc_co_u32_e32 v45, vcc, 0, v71, vcc
	global_load_dword v115, v[30:31], off
	global_load_dword v111, v[32:33], off
	global_load_dword v107, v[34:35], off
	global_load_dword v103, v[36:37], off
	global_load_dword v95, v[38:39], off
	global_load_dword v90, v[40:41], off
	global_load_dword v83, v[42:43], off
	global_load_dword v87, v[44:45], off
	v_add_co_u32_e32 v30, vcc, s3, v70
	s_mov_b32 s3, 0x5b2000
	s_nop 0
	v_addc_co_u32_e32 v31, vcc, 0, v71, vcc
	v_add_co_u32_e32 v32, vcc, s3, v70
	s_mov_b32 s3, 0x5bb000
	s_nop 0
	v_addc_co_u32_e32 v33, vcc, 0, v71, vcc
	v_add_co_u32_e32 v34, vcc, s3, v70
	s_mov_b32 s3, 0x5c4000
	s_nop 0
	v_addc_co_u32_e32 v35, vcc, 0, v71, vcc
	v_exp_f32_e32 v29, v29
	v_add_co_u32_e32 v36, vcc, s3, v70
	s_mov_b32 s3, 0x5cd000
	s_nop 0
	v_addc_co_u32_e32 v37, vcc, 0, v71, vcc
	v_add_co_u32_e32 v38, vcc, s3, v70
	s_mov_b32 s3, 0x5d6000
	s_nop 0
	v_addc_co_u32_e32 v39, vcc, 0, v71, vcc
	v_add_f32_e32 v29, 1.0, v29
	v_add_co_u32_e32 v40, vcc, s3, v70
	s_nop 0
	v_addc_co_u32_e32 v41, vcc, 0, v71, vcc
	s_mov_b32 s3, 0x5df000
	v_add_co_u32_e32 v42, vcc, s3, v70
	s_movk_i32 s3, 0x90
	s_nop 0
	v_addc_co_u32_e32 v43, vcc, 0, v71, vcc
	global_load_dword v112, v[30:31], off
	global_load_dword v108, v[32:33], off
	global_load_dword v104, v[34:35], off
	global_load_dword v100, v[36:37], off
	global_load_dword v93, v[38:39], off
	global_load_dword v91, v[40:41], off
	global_load_dword v81, v[42:43], off
	v_mul_f32_e32 v32, 0xbfb8aa3b, v15
	v_exp_f32_e32 v32, v32
	s_nop 0
	v_add_f32_e32 v32, 1.0, v32
	v_mul_f32_e32 v31, 0xbfb8aa3b, v16
	v_rcp_f32_e32 v30, v29
	s_nop 0
	v_mul_f32_e32 v29, v14, v30
	v_exp_f32_e32 v31, v31
	s_nop 0
	v_add_f32_e32 v31, 1.0, v31
	v_rcp_f32_e32 v14, v32
	s_nop 0
	v_mul_f32_e32 v30, v15, v14
	v_mul_f32_e32 v32, 0xbfb8aa3b, v17
	v_exp_f32_e32 v32, v32
	s_nop 0
	v_add_f32_e32 v32, 1.0, v32
	v_rcp_f32_e32 v14, v31
	s_nop 0
	v_mul_f32_e32 v31, v16, v14
	v_rcp_f32_e32 v14, v32
	s_nop 0
	v_mul_f32_e32 v17, v17, v14
	v_cvt_pk_bf16_f32 v14, v29, v30
	v_cvt_pk_bf16_f32 v15, v31, v17
	s_nop 0
	v_lshlrev_b32_e32 v16, 16, v14
	v_sub_f32_e32 v16, v29, v16
	v_and_b32_e32 v29, 0xffff0000, v14
	v_sub_f32_e32 v29, v30, v29
	v_cvt_pk_bf16_f32 v16, v16, v29
	v_lshlrev_b32_e32 v29, 16, v15
	v_and_b32_e32 v30, 0xffff0000, v15
	v_sub_f32_e32 v29, v31, v29
	v_sub_f32_e32 v17, v17, v30
	v_cvt_pk_bf16_f32 v17, v29, v17
	s_waitcnt vmcnt(50)
	v_mul_f32_e32 v29, 0xbfb8aa3b, v10
	v_exp_f32_e32 v29, v29
	v_mad_u32_u24 v30, v27, s3, 0
	v_add_u32_e32 v76, v30, v74
	ds_write_b64 v76, v[14:15]
	ds_write_b64 v76, v[16:17] offset:20736
	v_add_f32_e32 v29, 1.0, v29
	v_mul_f32_e32 v16, 0xbfb8aa3b, v11
	v_exp_f32_e32 v16, v16
	s_nop 0
	v_add_f32_e32 v16, 1.0, v16
	v_rcp_f32_e32 v14, v29
	s_nop 0
	v_mul_f32_e32 v14, v10, v14
	v_mul_f32_e32 v29, 0xbfb8aa3b, v12
	v_exp_f32_e32 v29, v29
	s_nop 0
	v_add_f32_e32 v17, 1.0, v29
	v_rcp_f32_e32 v10, v16
	s_nop 0
	v_mul_f32_e32 v15, v11, v10
	v_mul_f32_e32 v16, 0xbfb8aa3b, v13
	v_exp_f32_e32 v16, v16
	s_nop 0
	v_add_f32_e32 v16, 1.0, v16
	v_rcp_f32_e32 v10, v17
	s_nop 0
	v_mul_f32_e32 v17, v12, v10
	v_rcp_f32_e32 v10, v16
	s_nop 0
	v_mul_f32_e32 v13, v13, v10
	s_waitcnt vmcnt(49)
	v_mul_f32_e32 v16, 0xbfb8aa3b, v6
	v_exp_f32_e32 v16, v16
	v_cvt_pk_bf16_f32 v10, v14, v15
	v_cvt_pk_bf16_f32 v11, v17, v13
	s_nop 0
	v_lshlrev_b32_e32 v12, 16, v10
	v_sub_f32_e32 v12, v14, v12
	v_and_b32_e32 v14, 0xffff0000, v10
	v_sub_f32_e32 v14, v15, v14
	v_and_b32_e32 v15, 0xffff0000, v11
	v_cvt_pk_bf16_f32 v12, v12, v14
	v_lshlrev_b32_e32 v14, 16, v11
	v_sub_f32_e32 v13, v13, v15
	v_add_f32_e32 v15, 1.0, v16
	v_sub_f32_e32 v14, v17, v14
	v_cvt_pk_bf16_f32 v13, v14, v13
	v_mad_u32_u24 v14, v28, s3, 0
	v_add_u32_e32 v79, v14, v74
	ds_write_b64 v79, v[10:11]
	ds_write_b64 v79, v[12:13] offset:20736
	v_mul_f32_e32 v12, 0xbfb8aa3b, v7
	v_exp_f32_e32 v12, v12
	s_nop 0
	v_add_f32_e32 v12, 1.0, v12
	v_rcp_f32_e32 v10, v15
	s_nop 0
	v_mul_f32_e32 v10, v6, v10
	v_mul_f32_e32 v15, 0xbfb8aa3b, v8
	v_exp_f32_e32 v15, v15
	s_nop 0
	v_add_f32_e32 v13, 1.0, v15
	v_rcp_f32_e32 v6, v12
	s_nop 0
	v_mul_f32_e32 v11, v7, v6
	v_mul_f32_e32 v12, 0xbfb8aa3b, v9
	v_exp_f32_e32 v12, v12
	s_nop 0
	v_add_f32_e32 v12, 1.0, v12
	v_rcp_f32_e32 v6, v13
	s_nop 0
	v_mul_f32_e32 v13, v8, v6
	s_movk_i32 s3, 0x300
	v_rcp_f32_e32 v6, v12
	s_nop 0
	v_mul_f32_e32 v9, v9, v6
	v_cvt_pk_bf16_f32 v6, v10, v11
	v_cvt_pk_bf16_f32 v7, v13, v9
	v_cmp_gt_u32_e64 s[8:9], s3, v0
	v_lshlrev_b32_e32 v8, 16, v6
	v_sub_f32_e32 v8, v10, v8
	v_and_b32_e32 v10, 0xffff0000, v6
	v_sub_f32_e32 v10, v11, v10
	v_cvt_pk_bf16_f32 v8, v8, v10
	v_lshlrev_b32_e32 v10, 16, v7
	v_and_b32_e32 v11, 0xffff0000, v7
	v_sub_f32_e32 v10, v13, v10
	v_sub_f32_e32 v9, v9, v11
	v_cvt_pk_bf16_f32 v9, v10, v9
	v_add_u32_e32 v10, 0x2400, v30
	v_add_u32_e32 v78, v10, v74
	ds_write_b64 v78, v[6:7]
	ds_write_b64 v78, v[8:9] offset:20736
	s_and_saveexec_b64 s[10:11], s[8:9]
	s_cbranch_execz .LBB0_291
	global_load_dwordx4 v[6:9], v[68:69], off
	s_movk_i32 s3, 0x220
	v_cmp_gt_u32_e64 s[6:7], s3, v0
	s_and_saveexec_b64 s[20:21], s[6:7]
	s_cbranch_execz .LBB0_286
	s_waitcnt vmcnt(0)
	v_mul_f32_e32 v10, 0xbfb8aa3b, v6
	v_exp_f32_e32 v10, v10
	s_nop 0
	v_add_f32_e32 v10, 1.0, v10
	v_rcp_f32_e32 v11, v10
	s_nop 0
	v_mul_f32_e32 v19, v6, v11
.LBB0_286:
	s_or_b64 exec, exec, s[20:21]
	s_waitcnt vmcnt(0)
	v_mov_b32_e32 v6, 0
	v_mov_b32_e32 v10, 0
	s_and_saveexec_b64 s[20:21], s[6:7]
	s_cbranch_execz .LBB0_303
	v_mul_f32_e32 v10, 0xbfb8aa3b, v7
	v_exp_f32_e32 v10, v10
	s_nop 0
	v_add_f32_e32 v10, 1.0, v10
	v_rcp_f32_e32 v11, v10
	s_nop 0
	v_mul_f32_e32 v10, v7, v11
	s_or_b64 exec, exec, s[20:21]
	s_and_saveexec_b64 s[20:21], s[6:7]
	s_cbranch_execnz .LBB0_304

.LBB0_289:
	v_mul_f32_e32 v7, 0xbfb8aa3b, v9
	v_exp_f32_e32 v7, v7
	s_nop 0
	v_add_f32_e32 v7, 1.0, v7
	v_rcp_f32_e32 v8, v7
	s_nop 0
	v_mul_f32_e32 v7, v9, v8

.LBB0_291:
	s_or_b64 exec, exec, s[10:11]
	s_movk_i32 s3, 0x100
	v_or_b32_e32 v77, 0x80, v27
	v_cmp_gt_u32_e64 s[10:11], s3, v0
	s_and_saveexec_b64 s[20:21], s[10:11]
	s_cbranch_execz .LBB0_301
	s_movk_i32 s3, 0x82
	v_cmp_gt_u32_e64 s[6:7], s3, v77
	v_mov_b32_e32 v6, 0
	v_mov_b32_e32 v7, 0
	s_and_saveexec_b64 s[22:23], s[6:7]
	s_cbranch_execz .LBB0_294
	s_waitcnt vmcnt(48)
	v_mul_f32_e32 v7, 0xbfb8aa3b, v2
	v_exp_f32_e32 v7, v7
	s_nop 0
	v_add_f32_e32 v7, 1.0, v7
	v_rcp_f32_e32 v8, v7
	s_nop 0
	v_mul_f32_e32 v7, v2, v8
.LBB0_294:
	s_or_b64 exec, exec, s[22:23]
	s_and_saveexec_b64 s[22:23], s[6:7]
	s_cbranch_execz .LBB0_296
	s_waitcnt vmcnt(48)
	v_mul_f32_e32 v2, 0xbfb8aa3b, v3
	v_exp_f32_e32 v2, v2
	s_nop 0
	v_add_f32_e32 v2, 1.0, v2
	v_rcp_f32_e32 v6, v2
	s_nop 0
	v_mul_f32_e32 v6, v3, v6
.LBB0_296:
	s_or_b64 exec, exec, s[22:23]
	s_waitcnt vmcnt(48)
	v_mov_b32_e32 v2, 0
	v_mov_b32_e32 v3, 0
	s_and_saveexec_b64 s[22:23], s[6:7]
	s_cbranch_execz .LBB0_298
	v_mul_f32_e32 v3, 0xbfb8aa3b, v4
	v_exp_f32_e32 v3, v3
	s_nop 0
	v_add_f32_e32 v3, 1.0, v3
	v_rcp_f32_e32 v8, v3
	s_nop 0
	v_mul_f32_e32 v3, v4, v8
.LBB0_298:
	s_or_b64 exec, exec, s[22:23]
	s_and_saveexec_b64 s[22:23], s[6:7]
	s_cbranch_execz .LBB0_300
	v_mul_f32_e32 v2, 0xbfb8aa3b, v5
	v_exp_f32_e32 v2, v2
	s_nop 0
	v_add_f32_e32 v2, 1.0, v2
	v_rcp_f32_e32 v4, v2
	s_nop 0
	v_mul_f32_e32 v2, v5, v4

.LBB0_304:
	v_mul_f32_e32 v6, 0xbfb8aa3b, v8
	v_exp_f32_e32 v6, v6
	s_nop 0
	v_add_f32_e32 v6, 1.0, v6
	v_rcp_f32_e32 v7, v6
	s_nop 0
	v_mul_f32_e32 v6, v8, v7
	s_or_b64 exec, exec, s[20:21]
	v_mov_b32_e32 v7, 0
	s_and_saveexec_b64 s[20:21], s[6:7]
	s_cbranch_execnz .LBB0_289
	s_branch .LBB0_290

.LBB0_308:
	s_waitcnt vmcnt(20)
	v_mul_f32_e32 v59, 0xbfb8aa3b, v54
	v_exp_f32_e32 v59, v59
	v_mul_f32_e32 v99, 0xbfb8aa3b, v55
	v_exp_f32_e32 v99, v99
	v_add_f32_e32 v59, 1.0, v59
	v_add_f32_e32 v99, 1.0, v99
	v_mul_f32_e32 v117, 0xbfb8aa3b, v56
	v_rcp_f32_e32 v113, v59
	s_nop 0
	v_mul_f32_e32 v59, v54, v113
	v_exp_f32_e32 v117, v117
	s_nop 0
	v_add_f32_e32 v117, 1.0, v117
	v_mul_f32_e32 v113, 0xbfb8aa3b, v57
	v_rcp_f32_e32 v54, v99
	s_nop 0
	v_mul_f32_e32 v99, v55, v54
	v_exp_f32_e32 v113, v113
	s_nop 0
	v_add_f32_e32 v113, 1.0, v113
	v_rcp_f32_e32 v54, v117
	s_nop 0
	v_mul_f32_e32 v117, v56, v54
	v_rcp_f32_e32 v54, v113
	s_nop 0
	v_mul_f32_e32 v57, v57, v54
	v_cvt_pk_bf16_f32 v54, v59, v99
	v_cvt_pk_bf16_f32 v55, v117, v57
	s_nop 0
	v_lshlrev_b32_e32 v56, 16, v54
	v_sub_f32_e32 v56, v59, v56
	v_and_b32_e32 v59, 0xffff0000, v54
	v_sub_f32_e32 v59, v99, v59
	s_waitcnt vmcnt(19)
	v_mul_f32_e32 v99, 0xbfb8aa3b, v50
	v_exp_f32_e32 v99, v99
	v_and_b32_e32 v113, 0xffff0000, v55
	v_cvt_pk_bf16_f32 v56, v56, v59
	v_lshlrev_b32_e32 v59, 16, v55
	v_add_f32_e32 v99, 1.0, v99
	v_sub_f32_e32 v57, v57, v113
	v_sub_f32_e32 v59, v117, v59
	v_cvt_pk_bf16_f32 v57, v59, v57
	ds_write_b64 v76, v[54:55] offset:41472
	ds_write_b64 v76, v[56:57] offset:62208
	v_mul_f32_e32 v56, 0xbfb8aa3b, v51
	v_exp_f32_e32 v56, v56
	s_nop 0
	v_add_f32_e32 v56, 1.0, v56
	v_rcp_f32_e32 v54, v99
	s_nop 0
	v_mul_f32_e32 v54, v50, v54
	v_mul_f32_e32 v99, 0xbfb8aa3b, v52
	v_exp_f32_e32 v99, v99
	s_nop 0
	v_add_f32_e32 v57, 1.0, v99
	v_rcp_f32_e32 v50, v56
	s_nop 0
	v_mul_f32_e32 v55, v51, v50
	v_mul_f32_e32 v56, 0xbfb8aa3b, v53
	v_exp_f32_e32 v56, v56
	s_nop 0
	v_add_f32_e32 v56, 1.0, v56
	v_rcp_f32_e32 v50, v57
	s_nop 0
	v_mul_f32_e32 v57, v52, v50
	v_rcp_f32_e32 v50, v56
	s_nop 0
	v_mul_f32_e32 v53, v53, v50
	v_cvt_pk_bf16_f32 v50, v54, v55
	v_cvt_pk_bf16_f32 v51, v57, v53
	s_nop 0
	v_lshlrev_b32_e32 v52, 16, v50
	v_sub_f32_e32 v52, v54, v52
	v_and_b32_e32 v54, 0xffff0000, v50
	v_sub_f32_e32 v54, v55, v54
	s_waitcnt vmcnt(18)
	v_mul_f32_e32 v55, 0xbfb8aa3b, v46
	v_exp_f32_e32 v55, v55
	v_and_b32_e32 v56, 0xffff0000, v51
	v_cvt_pk_bf16_f32 v52, v52, v54
	v_lshlrev_b32_e32 v54, 16, v51
	v_add_f32_e32 v55, 1.0, v55
	v_sub_f32_e32 v53, v53, v56
	v_sub_f32_e32 v54, v57, v54
	v_cvt_pk_bf16_f32 v53, v54, v53
	ds_write_b64 v79, v[50:51] offset:41472
	ds_write_b64 v79, v[52:53] offset:62208
	v_mul_f32_e32 v52, 0xbfb8aa3b, v47
	v_exp_f32_e32 v52, v52
	s_nop 0
	v_add_f32_e32 v52, 1.0, v52
	v_rcp_f32_e32 v50, v55
	s_nop 0
	v_mul_f32_e32 v50, v46, v50
	v_mul_f32_e32 v55, 0xbfb8aa3b, v48
	v_exp_f32_e32 v55, v55
	s_nop 0
	v_add_f32_e32 v53, 1.0, v55
	v_rcp_f32_e32 v46, v52
	s_nop 0
	v_mul_f32_e32 v51, v47, v46
	v_mul_f32_e32 v52, 0xbfb8aa3b, v49
	v_exp_f32_e32 v52, v52
	s_nop 0
	v_add_f32_e32 v52, 1.0, v52
	v_rcp_f32_e32 v46, v53
	s_nop 0
	v_mul_f32_e32 v53, v48, v46
	v_rcp_f32_e32 v46, v52
	s_nop 0
	v_mul_f32_e32 v49, v49, v46
	v_cvt_pk_bf16_f32 v46, v50, v51
	v_cvt_pk_bf16_f32 v47, v53, v49
	s_nop 0
	v_lshlrev_b32_e32 v48, 16, v46
	v_sub_f32_e32 v48, v50, v48
	v_and_b32_e32 v50, 0xffff0000, v46
	v_sub_f32_e32 v50, v51, v50
	v_and_b32_e32 v51, 0xffff0000, v47
	v_cvt_pk_bf16_f32 v48, v48, v50
	v_lshlrev_b32_e32 v50, 16, v47
	v_sub_f32_e32 v49, v49, v51
	v_sub_f32_e32 v50, v53, v50
	v_cvt_pk_bf16_f32 v49, v50, v49
	ds_write_b64 v76, v[46:47] offset:50688
	ds_write_b64 v78, v[48:49] offset:62208
	s_and_saveexec_b64 s[20:21], s[8:9]
	s_cbranch_execz .LBB0_318
	s_movk_i32 s3, 0x220
	v_cmp_gt_u32_e64 s[12:13], s3, v0
	v_mov_b32_e32 v46, 0
	v_mov_b32_e32 v47, 0
	s_and_saveexec_b64 s[22:23], s[12:13]
	s_cbranch_execz .LBB0_311
	s_waitcnt vmcnt(17)
	v_mul_f32_e32 v47, 0xbfb8aa3b, v42
	v_exp_f32_e32 v47, v47
	s_nop 0
	v_add_f32_e32 v47, 1.0, v47
	v_rcp_f32_e32 v48, v47
	s_nop 0
	v_mul_f32_e32 v47, v42, v48
.LBB0_311:
	s_or_b64 exec, exec, s[22:23]
	s_and_saveexec_b64 s[22:23], s[12:13]
	s_cbranch_execz .LBB0_313
	s_waitcnt vmcnt(17)
	v_mul_f32_e32 v42, 0xbfb8aa3b, v43
	v_exp_f32_e32 v42, v42
	s_nop 0
	v_add_f32_e32 v42, 1.0, v42
	v_rcp_f32_e32 v46, v42
	s_nop 0
	v_mul_f32_e32 v46, v43, v46
.LBB0_313:
	s_or_b64 exec, exec, s[22:23]
	s_waitcnt vmcnt(17)
	v_mov_b32_e32 v42, 0
	v_mov_b32_e32 v43, 0
	s_and_saveexec_b64 s[22:23], s[12:13]
	s_cbranch_execz .LBB0_315
	v_mul_f32_e32 v43, 0xbfb8aa3b, v44
	v_exp_f32_e32 v43, v43
	s_nop 0
	v_add_f32_e32 v43, 1.0, v43
	v_rcp_f32_e32 v48, v43
	s_nop 0
	v_mul_f32_e32 v43, v44, v48
.LBB0_315:
	s_or_b64 exec, exec, s[22:23]
	s_and_saveexec_b64 s[22:23], s[12:13]
	s_cbranch_execz .LBB0_317
	v_mul_f32_e32 v42, 0xbfb8aa3b, v45
	v_exp_f32_e32 v42, v42
	s_nop 0
	v_add_f32_e32 v42, 1.0, v42
	v_rcp_f32_e32 v44, v42
	s_nop 0
	v_mul_f32_e32 v42, v45, v44

.LBB0_318:
	s_or_b64 exec, exec, s[20:21]
	s_and_saveexec_b64 s[20:21], s[10:11]
	s_cbranch_execz .LBB0_328
	s_movk_i32 s3, 0x82
	v_cmp_gt_u32_e64 s[12:13], s3, v77
	s_waitcnt vmcnt(17)
	v_mov_b32_e32 v42, 0
	v_mov_b32_e32 v43, 0
	s_and_saveexec_b64 s[22:23], s[12:13]
	s_cbranch_execz .LBB0_321
	s_waitcnt vmcnt(16)
	v_mul_f32_e32 v43, 0xbfb8aa3b, v38
	v_exp_f32_e32 v43, v43
	s_nop 0
	v_add_f32_e32 v43, 1.0, v43
	v_rcp_f32_e32 v44, v43
	s_nop 0
	v_mul_f32_e32 v43, v38, v44
.LBB0_321:
	s_or_b64 exec, exec, s[22:23]
	s_and_saveexec_b64 s[22:23], s[12:13]
	s_cbranch_execz .LBB0_323
	s_waitcnt vmcnt(16)
	v_mul_f32_e32 v38, 0xbfb8aa3b, v39
	v_exp_f32_e32 v38, v38
	s_nop 0
	v_add_f32_e32 v38, 1.0, v38
	v_rcp_f32_e32 v42, v38
	s_nop 0
	v_mul_f32_e32 v42, v39, v42
.LBB0_323:
	s_or_b64 exec, exec, s[22:23]
	s_waitcnt vmcnt(16)
	v_mov_b32_e32 v38, 0
	v_mov_b32_e32 v39, 0
	s_and_saveexec_b64 s[22:23], s[12:13]
	s_cbranch_execz .LBB0_325
	v_mul_f32_e32 v39, 0xbfb8aa3b, v40
	v_exp_f32_e32 v39, v39
	s_nop 0
	v_add_f32_e32 v39, 1.0, v39
	v_rcp_f32_e32 v44, v39
	s_nop 0
	v_mul_f32_e32 v39, v40, v44
.LBB0_325:
	s_or_b64 exec, exec, s[22:23]
	s_and_saveexec_b64 s[22:23], s[12:13]
	s_cbranch_execz .LBB0_327
	v_mul_f32_e32 v38, 0xbfb8aa3b, v41
	v_exp_f32_e32 v38, v38
	s_nop 0
	v_add_f32_e32 v38, 1.0, v38
	v_rcp_f32_e32 v40, v38
	s_nop 0
	v_mul_f32_e32 v38, v41, v40

.LBB0_332:
	s_waitcnt vmcnt(20)
	v_mul_f32_e32 v59, 0xbfb8aa3b, v54
	v_exp_f32_e32 v59, v59
	v_mul_f32_e32 v99, 0xbfb8aa3b, v55
	v_exp_f32_e32 v99, v99
	v_add_f32_e32 v59, 1.0, v59
	v_add_f32_e32 v99, 1.0, v99
	v_mul_f32_e32 v121, 0xbfb8aa3b, v56
	v_rcp_f32_e32 v118, v59
	s_nop 0
	v_mul_f32_e32 v59, v54, v118
	v_exp_f32_e32 v121, v121
	s_nop 0
	v_add_f32_e32 v121, 1.0, v121
	v_mul_f32_e32 v118, 0xbfb8aa3b, v57
	v_rcp_f32_e32 v54, v99
	s_nop 0
	v_mul_f32_e32 v99, v55, v54
	v_exp_f32_e32 v118, v118
	s_nop 0
	v_add_f32_e32 v118, 1.0, v118
	v_rcp_f32_e32 v54, v121
	s_nop 0
	v_mul_f32_e32 v121, v56, v54
	v_rcp_f32_e32 v54, v118
	s_nop 0
	v_mul_f32_e32 v57, v57, v54
	v_cvt_pk_bf16_f32 v54, v59, v99
	v_cvt_pk_bf16_f32 v55, v121, v57
	s_nop 0
	v_lshlrev_b32_e32 v56, 16, v54
	v_sub_f32_e32 v56, v59, v56
	v_and_b32_e32 v59, 0xffff0000, v54
	v_sub_f32_e32 v59, v99, v59
	s_waitcnt vmcnt(19)
	v_mul_f32_e32 v99, 0xbfb8aa3b, v50
	v_exp_f32_e32 v99, v99
	v_and_b32_e32 v118, 0xffff0000, v55
	v_cvt_pk_bf16_f32 v56, v56, v59
	v_lshlrev_b32_e32 v59, 16, v55
	v_add_f32_e32 v99, 1.0, v99
	v_sub_f32_e32 v57, v57, v118
	v_sub_f32_e32 v59, v121, v59
	v_cvt_pk_bf16_f32 v57, v59, v57
	ds_write_b64 v76, v[54:55]
	ds_write_b64 v76, v[56:57] offset:20736
	v_mul_f32_e32 v56, 0xbfb8aa3b, v51
	v_exp_f32_e32 v56, v56
	s_nop 0
	v_add_f32_e32 v56, 1.0, v56
	v_rcp_f32_e32 v54, v99
	s_nop 0
	v_mul_f32_e32 v54, v50, v54
	v_mul_f32_e32 v99, 0xbfb8aa3b, v52
	v_exp_f32_e32 v99, v99
	s_nop 0
	v_add_f32_e32 v57, 1.0, v99
	v_rcp_f32_e32 v50, v56
	s_nop 0
	v_mul_f32_e32 v55, v51, v50
	v_mul_f32_e32 v56, 0xbfb8aa3b, v53
	v_exp_f32_e32 v56, v56
	s_nop 0
	v_add_f32_e32 v56, 1.0, v56
	v_rcp_f32_e32 v50, v57
	s_nop 0
	v_mul_f32_e32 v57, v52, v50
	v_rcp_f32_e32 v50, v56
	s_nop 0
	v_mul_f32_e32 v53, v53, v50
	v_cvt_pk_bf16_f32 v50, v54, v55
	v_cvt_pk_bf16_f32 v51, v57, v53
	s_nop 0
	v_lshlrev_b32_e32 v52, 16, v50
	v_sub_f32_e32 v52, v54, v52
	v_and_b32_e32 v54, 0xffff0000, v50
	v_sub_f32_e32 v54, v55, v54
	s_waitcnt vmcnt(18)
	v_mul_f32_e32 v55, 0xbfb8aa3b, v46
	v_exp_f32_e32 v55, v55
	v_and_b32_e32 v56, 0xffff0000, v51
	v_cvt_pk_bf16_f32 v52, v52, v54
	v_lshlrev_b32_e32 v54, 16, v51
	v_add_f32_e32 v55, 1.0, v55
	v_sub_f32_e32 v53, v53, v56
	v_sub_f32_e32 v54, v57, v54
	v_cvt_pk_bf16_f32 v53, v54, v53
	ds_write_b64 v79, v[50:51]
	ds_write_b64 v79, v[52:53] offset:20736
	v_mul_f32_e32 v52, 0xbfb8aa3b, v47
	v_exp_f32_e32 v52, v52
	s_nop 0
	v_add_f32_e32 v52, 1.0, v52
	v_rcp_f32_e32 v50, v55
	s_nop 0
	v_mul_f32_e32 v50, v46, v50
	v_mul_f32_e32 v55, 0xbfb8aa3b, v48
	v_exp_f32_e32 v55, v55
	s_nop 0
	v_add_f32_e32 v53, 1.0, v55
	v_rcp_f32_e32 v46, v52
	s_nop 0
	v_mul_f32_e32 v51, v47, v46
	v_mul_f32_e32 v52, 0xbfb8aa3b, v49
	v_exp_f32_e32 v52, v52
	s_nop 0
	v_add_f32_e32 v52, 1.0, v52
	v_rcp_f32_e32 v46, v53
	s_nop 0
	v_mul_f32_e32 v53, v48, v46
	v_rcp_f32_e32 v46, v52
	s_nop 0
	v_mul_f32_e32 v49, v49, v46
	v_cvt_pk_bf16_f32 v46, v50, v51
	v_cvt_pk_bf16_f32 v47, v53, v49
	s_nop 0
	v_lshlrev_b32_e32 v48, 16, v46
	v_sub_f32_e32 v48, v50, v48
	v_and_b32_e32 v50, 0xffff0000, v46
	v_sub_f32_e32 v50, v51, v50
	v_and_b32_e32 v51, 0xffff0000, v47
	v_cvt_pk_bf16_f32 v48, v48, v50
	v_lshlrev_b32_e32 v50, 16, v47
	v_sub_f32_e32 v49, v49, v51
	v_sub_f32_e32 v50, v53, v50
	v_cvt_pk_bf16_f32 v49, v50, v49
	ds_write_b64 v76, v[46:47] offset:9216
	ds_write_b64 v76, v[48:49] offset:29952
	s_and_saveexec_b64 s[20:21], s[8:9]
	s_cbranch_execz .LBB0_342
	s_movk_i32 s3, 0x220
	v_cmp_gt_u32_e64 s[12:13], s3, v0
	v_mov_b32_e32 v46, 0
	v_mov_b32_e32 v47, 0
	s_and_saveexec_b64 s[22:23], s[12:13]
	s_cbranch_execz .LBB0_335
	s_waitcnt vmcnt(17)
	v_mul_f32_e32 v47, 0xbfb8aa3b, v42
	v_exp_f32_e32 v47, v47
	s_nop 0
	v_add_f32_e32 v47, 1.0, v47
	v_rcp_f32_e32 v48, v47
	s_nop 0
	v_mul_f32_e32 v47, v42, v48

.LBB0_356:
	s_waitcnt vmcnt(20)
	v_mul_f32_e32 v59, 0xbfb8aa3b, v54
	v_exp_f32_e32 v59, v59
	v_mul_f32_e32 v81, 0xbfb8aa3b, v55
	v_exp_f32_e32 v81, v81
	v_add_f32_e32 v59, 1.0, v59
	v_add_f32_e32 v81, 1.0, v81
	v_mul_f32_e32 v91, 0xbfb8aa3b, v56
	v_rcp_f32_e32 v87, v59
	s_nop 0
	v_mul_f32_e32 v59, v54, v87
	v_exp_f32_e32 v91, v91
	s_nop 0
	v_add_f32_e32 v91, 1.0, v91
	v_mul_f32_e32 v87, 0xbfb8aa3b, v57
	v_rcp_f32_e32 v54, v81
	s_nop 0
	v_mul_f32_e32 v81, v55, v54
	v_exp_f32_e32 v87, v87
	s_nop 0
	v_add_f32_e32 v87, 1.0, v87
	v_rcp_f32_e32 v54, v91
	s_nop 0
	v_mul_f32_e32 v91, v56, v54
	v_rcp_f32_e32 v54, v87
	s_nop 0
	v_mul_f32_e32 v57, v57, v54
	v_cvt_pk_bf16_f32 v54, v59, v81
	v_cvt_pk_bf16_f32 v55, v91, v57
	s_nop 0
	v_lshlrev_b32_e32 v56, 16, v54
	v_sub_f32_e32 v56, v59, v56
	v_and_b32_e32 v59, 0xffff0000, v54
	v_sub_f32_e32 v59, v81, v59
	s_waitcnt vmcnt(19)
	v_mul_f32_e32 v81, 0xbfb8aa3b, v50
	v_exp_f32_e32 v81, v81
	v_and_b32_e32 v87, 0xffff0000, v55
	v_cvt_pk_bf16_f32 v56, v56, v59
	v_lshlrev_b32_e32 v59, 16, v55
	v_add_f32_e32 v81, 1.0, v81
	v_sub_f32_e32 v57, v57, v87
	v_sub_f32_e32 v59, v91, v59
	v_cvt_pk_bf16_f32 v57, v59, v57
	ds_write_b64 v76, v[54:55] offset:41472
	ds_write_b64 v76, v[56:57] offset:62208
	v_mul_f32_e32 v56, 0xbfb8aa3b, v51
	v_exp_f32_e32 v56, v56
	s_nop 0
	v_add_f32_e32 v56, 1.0, v56
	v_rcp_f32_e32 v54, v81
	s_nop 0
	v_mul_f32_e32 v54, v50, v54
	v_mul_f32_e32 v81, 0xbfb8aa3b, v52
	v_exp_f32_e32 v81, v81
	s_nop 0
	v_add_f32_e32 v57, 1.0, v81
	v_rcp_f32_e32 v50, v56
	s_nop 0
	v_mul_f32_e32 v55, v51, v50
	v_mul_f32_e32 v56, 0xbfb8aa3b, v53
	v_exp_f32_e32 v56, v56
	s_nop 0
	v_add_f32_e32 v56, 1.0, v56
	v_rcp_f32_e32 v50, v57
	s_nop 0
	v_mul_f32_e32 v57, v52, v50
	v_rcp_f32_e32 v50, v56
	s_nop 0
	v_mul_f32_e32 v53, v53, v50
	v_cvt_pk_bf16_f32 v50, v54, v55
	v_cvt_pk_bf16_f32 v51, v57, v53
	s_nop 0
	v_lshlrev_b32_e32 v52, 16, v50
	v_sub_f32_e32 v52, v54, v52
	v_and_b32_e32 v54, 0xffff0000, v50
	v_sub_f32_e32 v54, v55, v54
	s_waitcnt vmcnt(18)
	v_mul_f32_e32 v55, 0xbfb8aa3b, v46
	v_exp_f32_e32 v55, v55
	v_and_b32_e32 v56, 0xffff0000, v51
	v_cvt_pk_bf16_f32 v52, v52, v54
	v_lshlrev_b32_e32 v54, 16, v51
	v_add_f32_e32 v55, 1.0, v55
	v_sub_f32_e32 v53, v53, v56
	v_sub_f32_e32 v54, v57, v54
	v_cvt_pk_bf16_f32 v53, v54, v53
	ds_write_b64 v79, v[50:51] offset:41472
	ds_write_b64 v79, v[52:53] offset:62208
	v_mul_f32_e32 v52, 0xbfb8aa3b, v47
	v_exp_f32_e32 v52, v52
	s_nop 0
	v_add_f32_e32 v52, 1.0, v52
	v_rcp_f32_e32 v50, v55
	s_nop 0
	v_mul_f32_e32 v50, v46, v50
	v_mul_f32_e32 v55, 0xbfb8aa3b, v48
	v_exp_f32_e32 v55, v55
	s_nop 0
	v_add_f32_e32 v53, 1.0, v55
	v_rcp_f32_e32 v46, v52
	s_nop 0
	v_mul_f32_e32 v51, v47, v46
	v_mul_f32_e32 v52, 0xbfb8aa3b, v49
	v_exp_f32_e32 v52, v52
	s_nop 0
	v_add_f32_e32 v52, 1.0, v52
	v_rcp_f32_e32 v46, v53
	s_nop 0
	v_mul_f32_e32 v53, v48, v46
	v_rcp_f32_e32 v46, v52
	s_nop 0
	v_mul_f32_e32 v49, v49, v46
	v_cvt_pk_bf16_f32 v46, v50, v51
	v_cvt_pk_bf16_f32 v47, v53, v49
	s_nop 0
	v_lshlrev_b32_e32 v48, 16, v46
	v_sub_f32_e32 v48, v50, v48
	v_and_b32_e32 v50, 0xffff0000, v46
	v_sub_f32_e32 v50, v51, v50
	v_and_b32_e32 v51, 0xffff0000, v47
	v_cvt_pk_bf16_f32 v48, v48, v50
	v_lshlrev_b32_e32 v50, 16, v47
	v_sub_f32_e32 v49, v49, v51
	v_sub_f32_e32 v50, v53, v50
	v_cvt_pk_bf16_f32 v49, v50, v49
	ds_write_b64 v76, v[46:47] offset:50688
	ds_write_b64 v78, v[48:49] offset:62208
	s_and_saveexec_b64 s[20:21], s[8:9]
	s_cbranch_execz .LBB0_366
	s_movk_i32 s3, 0x220
	v_cmp_gt_u32_e64 s[12:13], s3, v0
	v_mov_b32_e32 v46, 0
	v_mov_b32_e32 v47, 0
	s_and_saveexec_b64 s[22:23], s[12:13]
	s_cbranch_execz .LBB0_359
	s_waitcnt vmcnt(17)
	v_mul_f32_e32 v47, 0xbfb8aa3b, v42
	v_exp_f32_e32 v47, v47
	s_nop 0
	v_add_f32_e32 v47, 1.0, v47
	v_rcp_f32_e32 v48, v47
	s_nop 0
	v_mul_f32_e32 v47, v42, v48

.LBB0_380:
	s_waitcnt vmcnt(20)
	v_mul_f32_e32 v59, 0xbfb8aa3b, v54
	v_exp_f32_e32 v59, v59
	v_mul_f32_e32 v82, 0xbfb8aa3b, v55
	v_exp_f32_e32 v82, v82
	v_add_f32_e32 v59, 1.0, v59
	v_add_f32_e32 v82, 1.0, v82
	v_mul_f32_e32 v88, 0xbfb8aa3b, v56
	v_rcp_f32_e32 v84, v59
	s_nop 0
	v_mul_f32_e32 v59, v54, v84
	v_exp_f32_e32 v88, v88
	s_nop 0
	v_add_f32_e32 v88, 1.0, v88
	v_mul_f32_e32 v84, 0xbfb8aa3b, v57
	v_rcp_f32_e32 v54, v82
	s_nop 0
	v_mul_f32_e32 v82, v55, v54
	v_exp_f32_e32 v84, v84
	s_nop 0
	v_add_f32_e32 v84, 1.0, v84
	v_rcp_f32_e32 v54, v88
	s_nop 0
	v_mul_f32_e32 v88, v56, v54
	v_rcp_f32_e32 v54, v84
	s_nop 0
	v_mul_f32_e32 v57, v57, v54
	v_cvt_pk_bf16_f32 v54, v59, v82
	v_cvt_pk_bf16_f32 v55, v88, v57
	s_nop 0
	v_lshlrev_b32_e32 v56, 16, v54
	v_sub_f32_e32 v56, v59, v56
	v_and_b32_e32 v59, 0xffff0000, v54
	v_sub_f32_e32 v59, v82, v59
	s_waitcnt vmcnt(19)
	v_mul_f32_e32 v82, 0xbfb8aa3b, v50
	v_exp_f32_e32 v82, v82
	v_and_b32_e32 v84, 0xffff0000, v55
	v_cvt_pk_bf16_f32 v56, v56, v59
	v_lshlrev_b32_e32 v59, 16, v55
	v_add_f32_e32 v82, 1.0, v82
	v_sub_f32_e32 v57, v57, v84
	v_sub_f32_e32 v59, v88, v59
	v_cvt_pk_bf16_f32 v57, v59, v57
	ds_write_b64 v76, v[54:55]
	ds_write_b64 v76, v[56:57] offset:20736
	v_mul_f32_e32 v56, 0xbfb8aa3b, v51
	v_exp_f32_e32 v56, v56
	s_nop 0
	v_add_f32_e32 v56, 1.0, v56
	v_rcp_f32_e32 v54, v82
	s_nop 0
	v_mul_f32_e32 v54, v50, v54
	v_mul_f32_e32 v82, 0xbfb8aa3b, v52
	v_exp_f32_e32 v82, v82
	s_nop 0
	v_add_f32_e32 v57, 1.0, v82
	v_rcp_f32_e32 v50, v56
	s_nop 0
	v_mul_f32_e32 v55, v51, v50
	v_mul_f32_e32 v56, 0xbfb8aa3b, v53
	v_exp_f32_e32 v56, v56
	s_nop 0
	v_add_f32_e32 v56, 1.0, v56
	v_rcp_f32_e32 v50, v57
	s_nop 0
	v_mul_f32_e32 v57, v52, v50
	v_rcp_f32_e32 v50, v56
	s_nop 0
	v_mul_f32_e32 v53, v53, v50
	v_cvt_pk_bf16_f32 v50, v54, v55
	v_cvt_pk_bf16_f32 v51, v57, v53
	s_nop 0
	v_lshlrev_b32_e32 v52, 16, v50
	v_sub_f32_e32 v52, v54, v52
	v_and_b32_e32 v54, 0xffff0000, v50
	v_sub_f32_e32 v54, v55, v54
	s_waitcnt vmcnt(18)
	v_mul_f32_e32 v55, 0xbfb8aa3b, v46
	v_exp_f32_e32 v55, v55
	v_and_b32_e32 v56, 0xffff0000, v51
	v_cvt_pk_bf16_f32 v52, v52, v54
	v_lshlrev_b32_e32 v54, 16, v51
	v_add_f32_e32 v55, 1.0, v55
	v_sub_f32_e32 v53, v53, v56
	v_sub_f32_e32 v54, v57, v54
	v_cvt_pk_bf16_f32 v53, v54, v53
	ds_write_b64 v79, v[50:51]
	ds_write_b64 v79, v[52:53] offset:20736
	v_mul_f32_e32 v52, 0xbfb8aa3b, v47
	v_exp_f32_e32 v52, v52
	s_nop 0
	v_add_f32_e32 v52, 1.0, v52
	v_rcp_f32_e32 v50, v55
	s_nop 0
	v_mul_f32_e32 v50, v46, v50
	v_mul_f32_e32 v55, 0xbfb8aa3b, v48
	v_exp_f32_e32 v55, v55
	s_nop 0
	v_add_f32_e32 v53, 1.0, v55
	v_rcp_f32_e32 v46, v52
	s_nop 0
	v_mul_f32_e32 v51, v47, v46
	v_mul_f32_e32 v52, 0xbfb8aa3b, v49
	v_exp_f32_e32 v52, v52
	s_nop 0
	v_add_f32_e32 v52, 1.0, v52
	v_rcp_f32_e32 v46, v53
	s_nop 0
	v_mul_f32_e32 v53, v48, v46
	v_rcp_f32_e32 v46, v52
	s_nop 0
	v_mul_f32_e32 v49, v49, v46
	v_cvt_pk_bf16_f32 v46, v50, v51
	v_cvt_pk_bf16_f32 v47, v53, v49
	s_nop 0
	v_lshlrev_b32_e32 v48, 16, v46
	v_sub_f32_e32 v48, v50, v48
	v_and_b32_e32 v50, 0xffff0000, v46
	v_sub_f32_e32 v50, v51, v50
	v_and_b32_e32 v51, 0xffff0000, v47
	v_cvt_pk_bf16_f32 v48, v48, v50
	v_lshlrev_b32_e32 v50, 16, v47
	v_sub_f32_e32 v49, v49, v51
	v_sub_f32_e32 v50, v53, v50
	v_cvt_pk_bf16_f32 v49, v50, v49
	ds_write_b64 v76, v[46:47] offset:9216
	ds_write_b64 v76, v[48:49] offset:29952
	s_and_saveexec_b64 s[20:21], s[8:9]
	s_cbranch_execz .LBB0_390
	s_movk_i32 s3, 0x220
	v_cmp_gt_u32_e64 s[12:13], s3, v0
	v_mov_b32_e32 v46, 0
	v_mov_b32_e32 v47, 0
	s_and_saveexec_b64 s[22:23], s[12:13]
	s_cbranch_execz .LBB0_383
	s_waitcnt vmcnt(17)
	v_mul_f32_e32 v47, 0xbfb8aa3b, v42
	v_exp_f32_e32 v47, v47
	s_nop 0
	v_add_f32_e32 v47, 1.0, v47
	v_rcp_f32_e32 v48, v47
	s_nop 0
	v_mul_f32_e32 v47, v42, v48

.LBB0_404:
	s_waitcnt vmcnt(20)
	v_mul_f32_e32 v59, 0xbfb8aa3b, v54
	v_exp_f32_e32 v59, v59
	v_mul_f32_e32 v80, 0xbfb8aa3b, v55
	v_exp_f32_e32 v80, v80
	v_add_f32_e32 v59, 1.0, v59
	v_add_f32_e32 v80, 1.0, v80
	v_mul_f32_e32 v89, 0xbfb8aa3b, v56
	v_rcp_f32_e32 v85, v59
	s_nop 0
	v_mul_f32_e32 v59, v54, v85
	v_exp_f32_e32 v89, v89
	s_nop 0
	v_add_f32_e32 v89, 1.0, v89
	v_mul_f32_e32 v85, 0xbfb8aa3b, v57
	v_rcp_f32_e32 v54, v80
	s_nop 0
	v_mul_f32_e32 v80, v55, v54
	v_exp_f32_e32 v85, v85
	s_nop 0
	v_add_f32_e32 v85, 1.0, v85
	v_rcp_f32_e32 v54, v89
	s_nop 0
	v_mul_f32_e32 v89, v56, v54
	v_rcp_f32_e32 v54, v85
	s_nop 0
	v_mul_f32_e32 v57, v57, v54
	v_cvt_pk_bf16_f32 v54, v59, v80
	v_cvt_pk_bf16_f32 v55, v89, v57
	s_nop 0
	v_lshlrev_b32_e32 v56, 16, v54
	v_sub_f32_e32 v56, v59, v56
	v_and_b32_e32 v59, 0xffff0000, v54
	v_sub_f32_e32 v59, v80, v59
	s_waitcnt vmcnt(19)
	v_mul_f32_e32 v80, 0xbfb8aa3b, v50
	v_exp_f32_e32 v80, v80
	v_and_b32_e32 v85, 0xffff0000, v55
	v_cvt_pk_bf16_f32 v56, v56, v59
	v_lshlrev_b32_e32 v59, 16, v55
	v_add_f32_e32 v80, 1.0, v80
	v_sub_f32_e32 v57, v57, v85
	v_sub_f32_e32 v59, v89, v59
	v_cvt_pk_bf16_f32 v57, v59, v57
	ds_write_b64 v76, v[54:55] offset:41472
	ds_write_b64 v76, v[56:57] offset:62208
	v_mul_f32_e32 v56, 0xbfb8aa3b, v51
	v_exp_f32_e32 v56, v56
	s_nop 0
	v_add_f32_e32 v56, 1.0, v56
	v_rcp_f32_e32 v54, v80
	s_nop 0
	v_mul_f32_e32 v54, v50, v54
	v_mul_f32_e32 v80, 0xbfb8aa3b, v52
	v_exp_f32_e32 v80, v80
	s_nop 0
	v_add_f32_e32 v57, 1.0, v80
	v_rcp_f32_e32 v50, v56
	s_nop 0
	v_mul_f32_e32 v55, v51, v50
	v_mul_f32_e32 v56, 0xbfb8aa3b, v53
	v_exp_f32_e32 v56, v56
	s_nop 0
	v_add_f32_e32 v56, 1.0, v56
	v_rcp_f32_e32 v50, v57
	s_nop 0
	v_mul_f32_e32 v57, v52, v50
	v_rcp_f32_e32 v50, v56
	s_nop 0
	v_mul_f32_e32 v53, v53, v50
	v_cvt_pk_bf16_f32 v50, v54, v55
	v_cvt_pk_bf16_f32 v51, v57, v53
	s_nop 0
	v_lshlrev_b32_e32 v52, 16, v50
	v_sub_f32_e32 v52, v54, v52
	v_and_b32_e32 v54, 0xffff0000, v50
	v_sub_f32_e32 v54, v55, v54
	s_waitcnt vmcnt(18)
	v_mul_f32_e32 v55, 0xbfb8aa3b, v46
	v_exp_f32_e32 v55, v55
	v_and_b32_e32 v56, 0xffff0000, v51
	v_cvt_pk_bf16_f32 v52, v52, v54
	v_lshlrev_b32_e32 v54, 16, v51
	v_add_f32_e32 v55, 1.0, v55
	v_sub_f32_e32 v53, v53, v56
	v_sub_f32_e32 v54, v57, v54
	v_cvt_pk_bf16_f32 v53, v54, v53
	ds_write_b64 v79, v[50:51] offset:41472
	ds_write_b64 v79, v[52:53] offset:62208
	v_mul_f32_e32 v52, 0xbfb8aa3b, v47
	v_exp_f32_e32 v52, v52
	s_nop 0
	v_add_f32_e32 v52, 1.0, v52
	v_rcp_f32_e32 v50, v55
	s_nop 0
	v_mul_f32_e32 v50, v46, v50
	v_mul_f32_e32 v55, 0xbfb8aa3b, v48
	v_exp_f32_e32 v55, v55
	s_nop 0
	v_add_f32_e32 v53, 1.0, v55
	v_rcp_f32_e32 v46, v52
	s_nop 0
	v_mul_f32_e32 v51, v47, v46
	v_mul_f32_e32 v52, 0xbfb8aa3b, v49
	v_exp_f32_e32 v52, v52
	s_nop 0
	v_add_f32_e32 v52, 1.0, v52
	v_rcp_f32_e32 v46, v53
	s_nop 0
	v_mul_f32_e32 v53, v48, v46
	v_rcp_f32_e32 v46, v52
	s_nop 0
	v_mul_f32_e32 v49, v49, v46
	v_cvt_pk_bf16_f32 v46, v50, v51
	v_cvt_pk_bf16_f32 v47, v53, v49
	s_nop 0
	v_lshlrev_b32_e32 v48, 16, v46
	v_sub_f32_e32 v48, v50, v48
	v_and_b32_e32 v50, 0xffff0000, v46
	v_sub_f32_e32 v50, v51, v50
	v_and_b32_e32 v51, 0xffff0000, v47
	v_cvt_pk_bf16_f32 v48, v48, v50
	v_lshlrev_b32_e32 v50, 16, v47
	v_sub_f32_e32 v49, v49, v51
	v_sub_f32_e32 v50, v53, v50
	v_cvt_pk_bf16_f32 v49, v50, v49
	ds_write_b64 v76, v[46:47] offset:50688
	ds_write_b64 v78, v[48:49] offset:62208
	s_and_saveexec_b64 s[20:21], s[8:9]
	s_cbranch_execz .LBB0_414
	s_movk_i32 s3, 0x220
	v_cmp_gt_u32_e64 s[12:13], s3, v0
	v_mov_b32_e32 v46, 0
	v_mov_b32_e32 v47, 0
	s_and_saveexec_b64 s[22:23], s[12:13]
	s_cbranch_execz .LBB0_407
	s_waitcnt vmcnt(17)
	v_mul_f32_e32 v47, 0xbfb8aa3b, v42
	v_exp_f32_e32 v47, v47
	s_nop 0
	v_add_f32_e32 v47, 1.0, v47
	v_rcp_f32_e32 v48, v47
	s_nop 0
	v_mul_f32_e32 v47, v42, v48

.LBB0_428:
	s_waitcnt vmcnt(20)
	v_mul_f32_e32 v59, 0xbfb8aa3b, v54
	v_exp_f32_e32 v59, v59
	v_mul_f32_e32 v83, 0xbfb8aa3b, v55
	v_exp_f32_e32 v83, v83
	v_add_f32_e32 v59, 1.0, v59
	v_add_f32_e32 v83, 1.0, v83
	v_mul_f32_e32 v90, 0xbfb8aa3b, v56
	v_rcp_f32_e32 v86, v59
	s_nop 0
	v_mul_f32_e32 v59, v54, v86
	v_exp_f32_e32 v90, v90
	s_nop 0
	v_add_f32_e32 v90, 1.0, v90
	v_mul_f32_e32 v86, 0xbfb8aa3b, v57
	v_rcp_f32_e32 v54, v83
	s_nop 0
	v_mul_f32_e32 v83, v55, v54
	v_exp_f32_e32 v86, v86
	s_nop 0
	v_add_f32_e32 v86, 1.0, v86
	v_rcp_f32_e32 v54, v90
	s_nop 0
	v_mul_f32_e32 v90, v56, v54
	v_rcp_f32_e32 v54, v86
	s_nop 0
	v_mul_f32_e32 v57, v57, v54
	v_cvt_pk_bf16_f32 v54, v59, v83
	v_cvt_pk_bf16_f32 v55, v90, v57
	s_nop 0
	v_lshlrev_b32_e32 v56, 16, v54
	v_sub_f32_e32 v56, v59, v56
	v_and_b32_e32 v59, 0xffff0000, v54
	v_sub_f32_e32 v59, v83, v59
	s_waitcnt vmcnt(19)
	v_mul_f32_e32 v83, 0xbfb8aa3b, v50
	v_exp_f32_e32 v83, v83
	v_and_b32_e32 v86, 0xffff0000, v55
	v_cvt_pk_bf16_f32 v56, v56, v59
	v_lshlrev_b32_e32 v59, 16, v55
	v_add_f32_e32 v83, 1.0, v83
	v_sub_f32_e32 v57, v57, v86
	v_sub_f32_e32 v59, v90, v59
	v_cvt_pk_bf16_f32 v57, v59, v57
	ds_write_b64 v76, v[54:55]
	ds_write_b64 v76, v[56:57] offset:20736
	v_mul_f32_e32 v56, 0xbfb8aa3b, v51
	v_exp_f32_e32 v56, v56
	s_nop 0
	v_add_f32_e32 v56, 1.0, v56
	v_rcp_f32_e32 v54, v83
	s_nop 0
	v_mul_f32_e32 v54, v50, v54
	v_mul_f32_e32 v83, 0xbfb8aa3b, v52
	v_exp_f32_e32 v83, v83
	s_nop 0
	v_add_f32_e32 v57, 1.0, v83
	v_rcp_f32_e32 v50, v56
	s_nop 0
	v_mul_f32_e32 v55, v51, v50
	v_mul_f32_e32 v56, 0xbfb8aa3b, v53
	v_exp_f32_e32 v56, v56
	s_nop 0
	v_add_f32_e32 v56, 1.0, v56
	v_rcp_f32_e32 v50, v57
	s_nop 0
	v_mul_f32_e32 v57, v52, v50
	v_rcp_f32_e32 v50, v56
	s_nop 0
	v_mul_f32_e32 v53, v53, v50
	v_cvt_pk_bf16_f32 v50, v54, v55
	v_cvt_pk_bf16_f32 v51, v57, v53
	s_nop 0
	v_lshlrev_b32_e32 v52, 16, v50
	v_sub_f32_e32 v52, v54, v52
	v_and_b32_e32 v54, 0xffff0000, v50
	v_sub_f32_e32 v54, v55, v54
	s_waitcnt vmcnt(18)
	v_mul_f32_e32 v55, 0xbfb8aa3b, v46
	v_exp_f32_e32 v55, v55
	v_and_b32_e32 v56, 0xffff0000, v51
	v_cvt_pk_bf16_f32 v52, v52, v54
	v_lshlrev_b32_e32 v54, 16, v51
	v_add_f32_e32 v55, 1.0, v55
	v_sub_f32_e32 v53, v53, v56
	v_sub_f32_e32 v54, v57, v54
	v_cvt_pk_bf16_f32 v53, v54, v53
	ds_write_b64 v79, v[50:51]
	ds_write_b64 v79, v[52:53] offset:20736
	v_mul_f32_e32 v52, 0xbfb8aa3b, v47
	v_exp_f32_e32 v52, v52
	s_nop 0
	v_add_f32_e32 v52, 1.0, v52
	v_rcp_f32_e32 v50, v55
	s_nop 0
	v_mul_f32_e32 v50, v46, v50
	v_mul_f32_e32 v55, 0xbfb8aa3b, v48
	v_exp_f32_e32 v55, v55
	s_nop 0
	v_add_f32_e32 v53, 1.0, v55
	v_rcp_f32_e32 v46, v52
	s_nop 0
	v_mul_f32_e32 v51, v47, v46
	v_mul_f32_e32 v52, 0xbfb8aa3b, v49
	v_exp_f32_e32 v52, v52
	s_nop 0
	v_add_f32_e32 v52, 1.0, v52
	v_rcp_f32_e32 v46, v53
	s_nop 0
	v_mul_f32_e32 v53, v48, v46
	v_rcp_f32_e32 v46, v52
	s_nop 0
	v_mul_f32_e32 v49, v49, v46
	v_cvt_pk_bf16_f32 v46, v50, v51
	v_cvt_pk_bf16_f32 v47, v53, v49
	s_nop 0
	v_lshlrev_b32_e32 v48, 16, v46
	v_sub_f32_e32 v48, v50, v48
	v_and_b32_e32 v50, 0xffff0000, v46
	v_sub_f32_e32 v50, v51, v50
	v_and_b32_e32 v51, 0xffff0000, v47
	v_cvt_pk_bf16_f32 v48, v48, v50
	v_lshlrev_b32_e32 v50, 16, v47
	v_sub_f32_e32 v49, v49, v51
	v_sub_f32_e32 v50, v53, v50
	v_cvt_pk_bf16_f32 v49, v50, v49
	ds_write_b64 v76, v[46:47] offset:9216
	ds_write_b64 v76, v[48:49] offset:29952
	s_and_saveexec_b64 s[20:21], s[8:9]
	s_cbranch_execz .LBB0_438
	s_movk_i32 s3, 0x220
	v_cmp_gt_u32_e64 s[12:13], s3, v0
	v_mov_b32_e32 v46, 0
	v_mov_b32_e32 v47, 0
	s_and_saveexec_b64 s[22:23], s[12:13]
	s_cbranch_execz .LBB0_431
	s_waitcnt vmcnt(17)
	v_mul_f32_e32 v47, 0xbfb8aa3b, v42
	v_exp_f32_e32 v47, v47
	s_nop 0
	v_add_f32_e32 v47, 1.0, v47
	v_rcp_f32_e32 v48, v47
	s_nop 0
	v_mul_f32_e32 v47, v42, v48

.LBB0_620:
	s_waitcnt vmcnt(4)
	v_mul_f32_e32 v59, 0xbfb8aa3b, v54
	v_exp_f32_e32 v59, v59
	v_mul_f32_e32 v80, 0xbfb8aa3b, v55
	v_exp_f32_e32 v80, v80
	v_add_f32_e32 v59, 1.0, v59
	v_add_f32_e32 v80, 1.0, v80
	v_mul_f32_e32 v85, 0xbfb8aa3b, v56
	v_rcp_f32_e32 v83, v59
	s_nop 0
	v_mul_f32_e32 v59, v54, v83
	v_exp_f32_e32 v85, v85
	s_nop 0
	v_add_f32_e32 v85, 1.0, v85
	v_mul_f32_e32 v83, 0xbfb8aa3b, v57
	v_rcp_f32_e32 v54, v80
	s_nop 0
	v_mul_f32_e32 v80, v55, v54
	v_exp_f32_e32 v83, v83
	s_nop 0
	v_add_f32_e32 v83, 1.0, v83
	v_rcp_f32_e32 v54, v85
	s_nop 0
	v_mul_f32_e32 v85, v56, v54
	v_rcp_f32_e32 v54, v83
	s_nop 0
	v_mul_f32_e32 v57, v57, v54
	v_cvt_pk_bf16_f32 v54, v59, v80
	v_cvt_pk_bf16_f32 v55, v85, v57
	s_nop 0
	v_lshlrev_b32_e32 v56, 16, v54
	v_sub_f32_e32 v56, v59, v56
	v_and_b32_e32 v59, 0xffff0000, v54
	v_sub_f32_e32 v59, v80, v59
	s_waitcnt vmcnt(3)
	v_mul_f32_e32 v80, 0xbfb8aa3b, v50
	v_exp_f32_e32 v80, v80
	v_and_b32_e32 v83, 0xffff0000, v55
	v_cvt_pk_bf16_f32 v56, v56, v59
	v_lshlrev_b32_e32 v59, 16, v55
	v_add_f32_e32 v80, 1.0, v80
	v_sub_f32_e32 v57, v57, v83
	v_sub_f32_e32 v59, v85, v59
	v_cvt_pk_bf16_f32 v57, v59, v57
	ds_write_b64 v76, v[54:55]
	ds_write_b64 v76, v[56:57] offset:20736
	v_mul_f32_e32 v56, 0xbfb8aa3b, v51
	v_exp_f32_e32 v56, v56
	s_nop 0
	v_add_f32_e32 v56, 1.0, v56
	v_rcp_f32_e32 v54, v80
	s_nop 0
	v_mul_f32_e32 v54, v50, v54
	v_mul_f32_e32 v80, 0xbfb8aa3b, v52
	v_exp_f32_e32 v80, v80
	s_nop 0
	v_add_f32_e32 v57, 1.0, v80
	v_rcp_f32_e32 v50, v56
	s_nop 0
	v_mul_f32_e32 v55, v51, v50
	v_mul_f32_e32 v56, 0xbfb8aa3b, v53
	v_exp_f32_e32 v56, v56
	s_nop 0
	v_add_f32_e32 v56, 1.0, v56
	v_rcp_f32_e32 v50, v57
	s_nop 0
	v_mul_f32_e32 v57, v52, v50
	v_rcp_f32_e32 v50, v56
	s_nop 0
	v_mul_f32_e32 v53, v53, v50
	v_cvt_pk_bf16_f32 v50, v54, v55
	v_cvt_pk_bf16_f32 v51, v57, v53
	s_nop 0
	v_lshlrev_b32_e32 v52, 16, v50
	v_sub_f32_e32 v52, v54, v52
	v_and_b32_e32 v54, 0xffff0000, v50
	v_sub_f32_e32 v54, v55, v54
	s_waitcnt vmcnt(2)
	v_mul_f32_e32 v55, 0xbfb8aa3b, v46
	v_exp_f32_e32 v55, v55
	v_and_b32_e32 v56, 0xffff0000, v51
	v_cvt_pk_bf16_f32 v52, v52, v54
	v_lshlrev_b32_e32 v54, 16, v51
	v_add_f32_e32 v55, 1.0, v55
	v_sub_f32_e32 v53, v53, v56
	v_sub_f32_e32 v54, v57, v54
	v_cvt_pk_bf16_f32 v53, v54, v53
	ds_write_b64 v79, v[50:51]
	ds_write_b64 v79, v[52:53] offset:20736
	v_mul_f32_e32 v52, 0xbfb8aa3b, v47
	v_exp_f32_e32 v52, v52
	s_nop 0
	v_add_f32_e32 v52, 1.0, v52
	v_rcp_f32_e32 v50, v55
	s_nop 0
	v_mul_f32_e32 v50, v46, v50
	v_mul_f32_e32 v55, 0xbfb8aa3b, v48
	v_exp_f32_e32 v55, v55
	s_nop 0
	v_add_f32_e32 v53, 1.0, v55
	v_rcp_f32_e32 v46, v52
	s_nop 0
	v_mul_f32_e32 v51, v47, v46
	v_mul_f32_e32 v52, 0xbfb8aa3b, v49
	v_exp_f32_e32 v52, v52
	s_nop 0
	v_add_f32_e32 v52, 1.0, v52
	v_rcp_f32_e32 v46, v53
	s_nop 0
	v_mul_f32_e32 v53, v48, v46
	v_rcp_f32_e32 v46, v52
	s_nop 0
	v_mul_f32_e32 v49, v49, v46
	v_cvt_pk_bf16_f32 v46, v50, v51
	v_cvt_pk_bf16_f32 v47, v53, v49
	s_nop 0
	v_lshlrev_b32_e32 v48, 16, v46
	v_sub_f32_e32 v48, v50, v48
	v_and_b32_e32 v50, 0xffff0000, v46
	v_sub_f32_e32 v50, v51, v50
	v_and_b32_e32 v51, 0xffff0000, v47
	v_cvt_pk_bf16_f32 v48, v48, v50
	v_lshlrev_b32_e32 v50, 16, v47
	v_sub_f32_e32 v49, v49, v51
	v_sub_f32_e32 v50, v53, v50
	v_cvt_pk_bf16_f32 v49, v50, v49
	ds_write_b64 v76, v[46:47] offset:9216
	ds_write_b64 v76, v[48:49] offset:29952
	s_and_saveexec_b64 s[20:21], s[8:9]
	s_cbranch_execz .LBB0_630
	s_movk_i32 s3, 0x220
	v_cmp_gt_u32_e64 s[12:13], s3, v0
	v_mov_b32_e32 v46, 0
	v_mov_b32_e32 v47, 0
	s_and_saveexec_b64 s[22:23], s[12:13]
	s_cbranch_execz .LBB0_623
	s_waitcnt vmcnt(1)
	v_mul_f32_e32 v47, 0xbfb8aa3b, v42
	v_exp_f32_e32 v47, v47
	s_nop 0
	v_add_f32_e32 v47, 1.0, v47
	v_rcp_f32_e32 v48, v47
	s_nop 0
	v_mul_f32_e32 v47, v42, v48
.LBB0_623:
	s_or_b64 exec, exec, s[22:23]
	s_and_saveexec_b64 s[22:23], s[12:13]
	s_cbranch_execz .LBB0_625
	s_waitcnt vmcnt(1)
	v_mul_f32_e32 v42, 0xbfb8aa3b, v43
	v_exp_f32_e32 v42, v42
	s_nop 0
	v_add_f32_e32 v42, 1.0, v42
	v_rcp_f32_e32 v46, v42
	s_nop 0
	v_mul_f32_e32 v46, v43, v46
.LBB0_625:
	s_or_b64 exec, exec, s[22:23]
	s_waitcnt vmcnt(1)
	v_mov_b32_e32 v42, 0
	v_mov_b32_e32 v43, 0
	s_and_saveexec_b64 s[22:23], s[12:13]
	s_cbranch_execz .LBB0_627
	v_mul_f32_e32 v43, 0xbfb8aa3b, v44
	v_exp_f32_e32 v43, v43
	s_nop 0
	v_add_f32_e32 v43, 1.0, v43
	v_rcp_f32_e32 v48, v43
	s_nop 0
	v_mul_f32_e32 v43, v44, v48

.LBB0_630:
	s_or_b64 exec, exec, s[20:21]
	s_and_saveexec_b64 s[20:21], s[10:11]
	s_cbranch_execz .LBB0_640
	s_movk_i32 s3, 0x82
	v_cmp_gt_u32_e64 s[12:13], s3, v77
	s_waitcnt vmcnt(1)
	v_mov_b32_e32 v42, 0
	v_mov_b32_e32 v43, 0
	s_and_saveexec_b64 s[22:23], s[12:13]
	s_cbranch_execz .LBB0_633
	s_waitcnt vmcnt(0)
	v_mul_f32_e32 v43, 0xbfb8aa3b, v38
	v_exp_f32_e32 v43, v43
	s_nop 0
	v_add_f32_e32 v43, 1.0, v43
	v_rcp_f32_e32 v44, v43
	s_nop 0
	v_mul_f32_e32 v43, v38, v44
.LBB0_633:
	s_or_b64 exec, exec, s[22:23]
	s_and_saveexec_b64 s[22:23], s[12:13]
	s_cbranch_execz .LBB0_635
	s_waitcnt vmcnt(0)
	v_mul_f32_e32 v38, 0xbfb8aa3b, v39
	v_exp_f32_e32 v38, v38
	s_nop 0
	v_add_f32_e32 v38, 1.0, v38
	v_rcp_f32_e32 v42, v38
	s_nop 0
	v_mul_f32_e32 v42, v39, v42
.LBB0_635:
	s_or_b64 exec, exec, s[22:23]
	s_waitcnt vmcnt(0)
	v_mov_b32_e32 v38, 0
	v_mov_b32_e32 v39, 0
	s_and_saveexec_b64 s[22:23], s[12:13]
	s_cbranch_execz .LBB0_637
	v_mul_f32_e32 v39, 0xbfb8aa3b, v40
	v_exp_f32_e32 v39, v39
	s_nop 0
	v_add_f32_e32 v39, 1.0, v39
	v_rcp_f32_e32 v44, v39
	s_nop 0
	v_mul_f32_e32 v39, v40, v44

.LBB0_644:
	s_waitcnt vmcnt(4)
	v_mul_f32_e32 v58, 0xbfb8aa3b, v54
	v_exp_f32_e32 v58, v58
	v_mul_f32_e32 v59, 0xbfb8aa3b, v55
	v_exp_f32_e32 v59, v59
	v_add_f32_e32 v58, 1.0, v58
	v_add_f32_e32 v59, 1.0, v59
	v_mul_f32_e32 v61, 0xbfb8aa3b, v56
	v_rcp_f32_e32 v60, v58
	s_nop 0
	v_mul_f32_e32 v58, v54, v60
	v_exp_f32_e32 v61, v61
	s_nop 0
	v_add_f32_e32 v61, 1.0, v61
	v_mul_f32_e32 v60, 0xbfb8aa3b, v57
	v_rcp_f32_e32 v54, v59
	s_nop 0
	v_mul_f32_e32 v59, v55, v54
	v_exp_f32_e32 v60, v60
	s_nop 0
	v_add_f32_e32 v60, 1.0, v60
	v_rcp_f32_e32 v54, v61
	s_nop 0
	v_mul_f32_e32 v61, v56, v54
	v_rcp_f32_e32 v54, v60
	s_nop 0
	v_mul_f32_e32 v57, v57, v54
	v_cvt_pk_bf16_f32 v54, v58, v59
	v_cvt_pk_bf16_f32 v55, v61, v57
	s_nop 0
	v_lshlrev_b32_e32 v56, 16, v54
	v_sub_f32_e32 v56, v58, v56
	v_and_b32_e32 v58, 0xffff0000, v54
	v_sub_f32_e32 v58, v59, v58
	s_waitcnt vmcnt(3)
	v_mul_f32_e32 v59, 0xbfb8aa3b, v50
	v_exp_f32_e32 v59, v59
	v_and_b32_e32 v60, 0xffff0000, v55
	v_cvt_pk_bf16_f32 v56, v56, v58
	v_lshlrev_b32_e32 v58, 16, v55
	v_add_f32_e32 v59, 1.0, v59
	v_sub_f32_e32 v57, v57, v60
	v_sub_f32_e32 v58, v61, v58
	v_cvt_pk_bf16_f32 v57, v58, v57
	ds_write_b64 v76, v[54:55] offset:41472
	ds_write_b64 v76, v[56:57] offset:62208
	v_mul_f32_e32 v56, 0xbfb8aa3b, v51
	v_exp_f32_e32 v56, v56
	s_nop 0
	v_add_f32_e32 v56, 1.0, v56
	v_rcp_f32_e32 v54, v59
	s_nop 0
	v_mul_f32_e32 v54, v50, v54
	v_mul_f32_e32 v59, 0xbfb8aa3b, v52
	v_exp_f32_e32 v59, v59
	s_nop 0
	v_add_f32_e32 v57, 1.0, v59
	v_rcp_f32_e32 v50, v56
	s_nop 0
	v_mul_f32_e32 v55, v51, v50
	v_mul_f32_e32 v56, 0xbfb8aa3b, v53
	v_exp_f32_e32 v56, v56
	s_nop 0
	v_add_f32_e32 v56, 1.0, v56
	v_rcp_f32_e32 v50, v57
	s_nop 0
	v_mul_f32_e32 v57, v52, v50
	v_rcp_f32_e32 v50, v56
	s_nop 0
	v_mul_f32_e32 v53, v53, v50
	v_cvt_pk_bf16_f32 v50, v54, v55
	v_cvt_pk_bf16_f32 v51, v57, v53
	s_nop 0
	v_lshlrev_b32_e32 v52, 16, v50
	v_sub_f32_e32 v52, v54, v52
	v_and_b32_e32 v54, 0xffff0000, v50
	v_sub_f32_e32 v54, v55, v54
	s_waitcnt vmcnt(2)
	v_mul_f32_e32 v55, 0xbfb8aa3b, v46
	v_exp_f32_e32 v55, v55
	v_and_b32_e32 v56, 0xffff0000, v51
	v_cvt_pk_bf16_f32 v52, v52, v54
	v_lshlrev_b32_e32 v54, 16, v51
	v_add_f32_e32 v55, 1.0, v55
	v_sub_f32_e32 v53, v53, v56
	v_sub_f32_e32 v54, v57, v54
	v_cvt_pk_bf16_f32 v53, v54, v53
	ds_write_b64 v79, v[50:51] offset:41472
	ds_write_b64 v79, v[52:53] offset:62208
	v_mul_f32_e32 v52, 0xbfb8aa3b, v47
	v_exp_f32_e32 v52, v52
	s_nop 0
	v_add_f32_e32 v52, 1.0, v52
	v_rcp_f32_e32 v50, v55
	s_nop 0
	v_mul_f32_e32 v50, v46, v50
	v_mul_f32_e32 v55, 0xbfb8aa3b, v48
	v_exp_f32_e32 v55, v55
	s_nop 0
	v_add_f32_e32 v53, 1.0, v55
	v_rcp_f32_e32 v46, v52
	s_nop 0
	v_mul_f32_e32 v51, v47, v46
	v_mul_f32_e32 v52, 0xbfb8aa3b, v49
	v_exp_f32_e32 v52, v52
	s_nop 0
	v_add_f32_e32 v52, 1.0, v52
	v_rcp_f32_e32 v46, v53
	s_nop 0
	v_mul_f32_e32 v53, v48, v46
	v_rcp_f32_e32 v46, v52
	s_nop 0
	v_mul_f32_e32 v49, v49, v46
	v_cvt_pk_bf16_f32 v46, v50, v51
	v_cvt_pk_bf16_f32 v47, v53, v49
	s_nop 0
	v_lshlrev_b32_e32 v48, 16, v46
	v_sub_f32_e32 v48, v50, v48
	v_and_b32_e32 v50, 0xffff0000, v46
	v_sub_f32_e32 v50, v51, v50
	v_and_b32_e32 v51, 0xffff0000, v47
	v_cvt_pk_bf16_f32 v48, v48, v50
	v_lshlrev_b32_e32 v50, 16, v47
	v_sub_f32_e32 v49, v49, v51
	v_sub_f32_e32 v50, v53, v50
	v_cvt_pk_bf16_f32 v49, v50, v49
	ds_write_b64 v76, v[46:47] offset:50688
	ds_write_b64 v78, v[48:49] offset:62208
	s_and_saveexec_b64 s[12:13], s[8:9]
	s_cbranch_execz .LBB0_654
	s_movk_i32 s3, 0x220
	v_cmp_gt_u32_e64 s[8:9], s3, v0
	v_mov_b32_e32 v46, 0
	v_mov_b32_e32 v47, 0
	s_and_saveexec_b64 s[20:21], s[8:9]
	s_cbranch_execz .LBB0_647
	s_waitcnt vmcnt(1)
	v_mul_f32_e32 v47, 0xbfb8aa3b, v42
	v_exp_f32_e32 v47, v47
	s_nop 0
	v_add_f32_e32 v47, 1.0, v47
	v_rcp_f32_e32 v48, v47
	s_nop 0
	v_mul_f32_e32 v47, v42, v48
.LBB0_647:
	s_or_b64 exec, exec, s[20:21]
	s_and_saveexec_b64 s[20:21], s[8:9]
	s_cbranch_execz .LBB0_649
	s_waitcnt vmcnt(1)
	v_mul_f32_e32 v42, 0xbfb8aa3b, v43
	v_exp_f32_e32 v42, v42
	s_nop 0
	v_add_f32_e32 v42, 1.0, v42
	v_rcp_f32_e32 v46, v42
	s_nop 0
	v_mul_f32_e32 v46, v43, v46
.LBB0_649:
	s_or_b64 exec, exec, s[20:21]
	s_waitcnt vmcnt(1)
	v_mov_b32_e32 v42, 0
	v_mov_b32_e32 v43, 0
	s_and_saveexec_b64 s[20:21], s[8:9]
	s_cbranch_execz .LBB0_651
	v_mul_f32_e32 v43, 0xbfb8aa3b, v44
	v_exp_f32_e32 v43, v43
	s_nop 0
	v_add_f32_e32 v43, 1.0, v43
	v_rcp_f32_e32 v48, v43
	s_nop 0
	v_mul_f32_e32 v43, v44, v48
.LBB0_651:
	s_or_b64 exec, exec, s[20:21]
	s_and_saveexec_b64 s[20:21], s[8:9]
	s_cbranch_execz .LBB0_653
	v_mul_f32_e32 v42, 0xbfb8aa3b, v45
	v_exp_f32_e32 v42, v42
	s_nop 0
	v_add_f32_e32 v42, 1.0, v42
	v_rcp_f32_e32 v44, v42
	s_nop 0
	v_mul_f32_e32 v42, v45, v44

.LBB0_654:
	s_or_b64 exec, exec, s[12:13]
	s_and_saveexec_b64 s[12:13], s[10:11]
	s_cbranch_execz .LBB0_664
	s_movk_i32 s3, 0x82
	v_cmp_gt_u32_e64 s[8:9], s3, v77
	s_waitcnt vmcnt(1)
	v_mov_b32_e32 v42, 0
	v_mov_b32_e32 v43, 0
	s_and_saveexec_b64 s[10:11], s[8:9]
	s_cbranch_execz .LBB0_657
	s_waitcnt vmcnt(0)
	v_mul_f32_e32 v43, 0xbfb8aa3b, v38
	v_exp_f32_e32 v43, v43
	s_nop 0
	v_add_f32_e32 v43, 1.0, v43
	v_rcp_f32_e32 v44, v43
	s_nop 0
	v_mul_f32_e32 v43, v38, v44
.LBB0_657:
	s_or_b64 exec, exec, s[10:11]
	s_and_saveexec_b64 s[10:11], s[8:9]
	s_cbranch_execz .LBB0_659
	s_waitcnt vmcnt(0)
	v_mul_f32_e32 v38, 0xbfb8aa3b, v39
	v_exp_f32_e32 v38, v38
	s_nop 0
	v_add_f32_e32 v38, 1.0, v38
	v_rcp_f32_e32 v42, v38
	s_nop 0
	v_mul_f32_e32 v42, v39, v42
.LBB0_659:
	s_or_b64 exec, exec, s[10:11]
	s_waitcnt vmcnt(0)
	v_mov_b32_e32 v38, 0
	v_mov_b32_e32 v39, 0
	s_and_saveexec_b64 s[10:11], s[8:9]
	s_cbranch_execz .LBB0_661
	v_mul_f32_e32 v39, 0xbfb8aa3b, v40
	v_exp_f32_e32 v39, v39
	s_nop 0
	v_add_f32_e32 v39, 1.0, v39
	v_rcp_f32_e32 v44, v39
	s_nop 0
	v_mul_f32_e32 v39, v40, v44
.LBB0_661:
	s_or_b64 exec, exec, s[10:11]
	s_and_saveexec_b64 s[10:11], s[8:9]
	s_cbranch_execz .LBB0_663
	v_mul_f32_e32 v38, 0xbfb8aa3b, v41
	v_exp_f32_e32 v38, v38
	s_nop 0
	v_add_f32_e32 v38, 1.0, v38
	v_rcp_f32_e32 v40, v38
	s_nop 0
	v_mul_f32_e32 v38, v41, v40

.LBB0_730:
	v_pk_mul_f32 v[24:25], v[80:81], v[80:81]
	v_pk_mul_f32 v[26:27], v[78:79], v[78:79]
	s_ashr_i32 s27, s10, 13
	v_pk_mov_b32 v[28:29], v[26:27], v[24:25] op_sel:[1,0]
	v_mov_b32_e32 v27, v25
	v_pk_add_f32 v[24:25], v[28:29], v[26:27]
	v_pk_mul_f32 v[26:27], v[76:77], v[76:77]
	v_pk_mul_f32 v[28:29], v[74:75], v[74:75]
	s_and_b64 s[6:7], s[6:7], exec
	v_pk_mov_b32 v[34:35], v[28:29], v[26:27] op_sel:[1,0]
	v_mov_b32_e32 v29, v27
	v_pk_add_f32 v[26:27], v[34:35], v[28:29]
	v_mul_f32_e32 v28, v66, v66
	v_mul_f32_e32 v29, v67, v67
	v_pk_add_f32 v[24:25], v[24:25], v[24:25] op_sel:[0,1] op_sel_hi:[1,0]
	v_pk_add_f32 v[26:27], v[26:27], v[26:27] op_sel:[0,1] op_sel_hi:[1,0]
	s_cselect_b32 s6, s27, s28
	v_mov_b32_e32 v25, v28
	v_mov_b32_e32 v27, v29
	s_mul_hi_i32 s7, s6, 0x9000
	s_mul_i32 s6, s6, 0x9000
	v_pk_add_f32 v[24:25], v[24:25], v[26:27]
	v_mul_f32_e32 v26, v71, v71
	v_mul_f32_e32 v28, v73, v73
	s_add_u32 s6, s42, s6
	v_mul_f32_e32 v34, v68, v68
	v_mul_f32_e32 v35, v69, v69
	v_pk_fma_f32 v[26:27], v[70:71], v[70:71], v[26:27] op_sel_hi:[1,1,0]
	v_pk_fma_f32 v[28:29], v[72:73], v[72:73], v[28:29] op_sel_hi:[1,1,0]
	s_addc_u32 s7, s43, s7
	v_mov_b32_e32 v27, v34
	v_mov_b32_e32 v29, v35
	s_add_u32 s50, s6, 0x1000
	v_mov_b32_e32 v89, v83
	v_pk_add_f32 v[26:27], v[26:27], v[28:29]
	s_addc_u32 s51, s7, 0
	v_lshl_add_u64 v[112:113], s[6:7], 0, v[88:89]
	v_pk_add_f32 v[24:25], v[24:25], v[26:27]
	v_lshl_add_u64 v[26:27], s[50:51], 0, v[88:89]
	global_load_dwordx4 v[104:107], v[112:113], off
	global_load_dwordx4 v[108:111], v[26:27], off
	v_add_f32_e32 v24, v24, v25
	ds_bpermute_b32 v25, v1, v24
	v_lshl_add_u64 v[22:23], v[22:23], 0, v[82:83]
	v_mul_f32_e32 v116, v53, v53
	s_waitcnt lgkmcnt(0)
	v_add_f32_e32 v24, v24, v25
	ds_bpermute_b32 v25, v97, v24
	s_waitcnt lgkmcnt(0)
	v_add_f32_e32 v24, v24, v25
	ds_bpermute_b32 v25, v98, v24
	s_waitcnt lgkmcnt(0)
	v_add_f32_e32 v24, v24, v25
	ds_bpermute_b32 v25, v99, v24
	s_waitcnt lgkmcnt(0)
	v_add_f32_e32 v24, v24, v25
	ds_bpermute_b32 v25, v100, v24
	s_waitcnt lgkmcnt(0)
	v_add_f32_e32 v24, v24, v25
	ds_bpermute_b32 v25, v101, v24
	s_waitcnt lgkmcnt(0)
	v_add_f32_e32 v24, v24, v25
	v_fmamk_f32 v24, v24, 0x3a800000, v102
	v_mul_f32_e32 v25, 0x4f800000, v24
	v_cmp_gt_f32_e32 vcc, s4, v24
	s_waitcnt vmcnt(0)
	v_pk_add_f32 v[108:109], v[108:109], 1.0 op_sel_hi:[1,0]
	v_cndmask_b32_e32 v24, v24, v25, vcc
	v_sqrt_f32_e32 v25, v24
	v_pk_add_f32 v[110:111], v[110:111], 1.0 op_sel_hi:[1,0]
	v_add_u32_e32 v26, -1, v25
	v_fma_f32 v27, -v26, v25, v24
	v_cmp_ge_f32_e64 s[6:7], 0, v27
	v_add_u32_e32 v27, 1, v25
	s_nop 0
	v_cndmask_b32_e64 v26, v25, v26, s[6:7]
	v_fma_f32 v25, -v27, v25, v24
	v_cmp_lt_f32_e64 s[6:7], 0, v25
	s_nop 1
	v_cndmask_b32_e64 v25, v26, v27, s[6:7]
	v_mul_f32_e32 v26, 0x37800000, v25
	v_cndmask_b32_e32 v25, v25, v26, vcc
	v_cmp_class_f32_e32 vcc, v24, v103
	s_and_b64 s[6:7], s[48:49], exec
	s_nop 0
	v_cndmask_b32_e32 v91, v25, v24, vcc
	v_div_scale_f32 v93, s[6:7], v91, v91, 1.0
	v_rcp_f32_e32 v95, v93
	global_load_dwordx4 v[42:45], v[22:23], off
	global_load_dwordx4 v[34:37], v[22:23], off offset:1024
	global_load_dwordx4 v[26:29], v[22:23], off offset:2048
	s_nop 0
	global_load_dwordx4 v[22:25], v[22:23], off offset:3072
	s_cselect_b32 s6, s27, s14
	s_mul_hi_i32 s7, s6, 0x9000
	v_fma_f32 v96, -v93, v95, 1.0
	v_fmac_f32_e32 v95, v96, v95
	v_div_scale_f32 v96, vcc, 1.0, v91, 1.0
	v_mul_f32_e32 v114, v96, v95
	v_fma_f32 v115, -v93, v114, v96
	v_fmac_f32_e32 v114, v115, v95
	v_fma_f32 v93, -v93, v114, v96
	v_div_fmas_f32 v93, v93, v95, v114
	v_div_fixup_f32 v96, v93, v91, 1.0
	v_pk_mul_f32 v[78:79], v[78:79], v[96:97] op_sel_hi:[1,0]
	v_pk_mul_f32 v[80:81], v[80:81], v[96:97] op_sel_hi:[1,0]
	v_pk_mul_f32 v[78:79], v[2:3], v[78:79]
	v_pk_mul_f32 v[80:81], v[4:5], v[80:81]
	v_pk_fma_f32 v[78:79], v[108:109], v[78:79], v[104:105]
	v_pk_fma_f32 v[80:81], v[110:111], v[80:81], v[106:107]
	v_cvt_pk_bf16_f32 v78, v78, v79
	v_cvt_pk_bf16_f32 v79, v80, v81
	v_mov_b32_e32 v91, v83
	global_store_dwordx2 v[86:87], v[78:79], off
	v_lshl_add_u64 v[78:79], s[50:51], 0, v[90:91]
	global_load_dwordx4 v[78:81], v[78:79], off
	s_nop 0
	global_load_dwordx4 v[104:107], v[112:113], off offset:1024
	v_pk_mul_f32 v[76:77], v[76:77], v[96:97] op_sel_hi:[1,0]
	v_pk_mul_f32 v[74:75], v[74:75], v[96:97] op_sel_hi:[1,0]
	v_pk_mul_f32 v[76:77], v[8:9], v[76:77]
	v_pk_mul_f32 v[74:75], v[6:7], v[74:75]
	v_mov_b32_e32 v93, v83
	v_lshl_add_u64 v[108:109], s[50:51], 0, v[92:93]
	v_pk_mul_f32 v[72:73], v[72:73], v[96:97] op_sel_hi:[1,0]
	v_pk_mul_f32 v[70:71], v[70:71], v[96:97] op_sel_hi:[1,0]
	v_pk_mul_f32 v[72:73], v[12:13], v[72:73]
	v_pk_mul_f32 v[70:71], v[10:11], v[70:71]
	v_mov_b32_e32 v95, v83
	v_pk_mul_f32 v[68:69], v[68:69], v[96:97] op_sel_hi:[1,0]
	v_pk_mul_f32 v[66:67], v[66:67], v[96:97] op_sel_hi:[1,0]
	v_pk_mul_f32 v[68:69], v[68:69], v[16:17]
	v_pk_mul_f32 v[66:67], v[66:67], v[14:15]
	s_mul_i32 s6, s6, 0x9000
	s_add_u32 s6, s42, s6
	v_mul_f32_e32 v111, v50, v50
	v_mul_f32_e32 v110, v57, v57
	s_addc_u32 s7, s43, s7
	v_mul_f32_e32 v115, v52, v52
	s_add_u32 s48, s6, 0x1000
	s_addc_u32 s49, s7, 0
	v_mul_f32_e32 v114, v51, v51
	s_add_i32 s14, s10, 0xffffc004
	s_waitcnt vmcnt(0) lgkmcnt(0)
	v_pk_add_f32 v[80:81], v[80:81], 1.0 op_sel_hi:[1,0]
	v_pk_add_f32 v[78:79], v[78:79], 1.0 op_sel_hi:[1,0]
	v_pk_fma_f32 v[76:77], v[80:81], v[76:77], v[106:107]
	v_pk_fma_f32 v[74:75], v[78:79], v[74:75], v[104:105]
	v_cvt_pk_bf16_f32 v74, v74, v75
	v_cvt_pk_bf16_f32 v75, v76, v77
	global_store_dwordx2 v[86:87], v[74:75], off offset:512
	global_load_dwordx4 v[74:77], v[108:109], off
	s_nop 0
	global_load_dwordx4 v[78:81], v[112:113], off offset:2048
	v_lshl_add_u64 v[104:105], s[50:51], 0, v[94:95]
	v_pk_mul_f32 v[106:107], v[58:59], v[58:59]
	v_mul_f32_e32 v108, v55, v55
	s_waitcnt vmcnt(0) lgkmcnt(0)
	v_pk_add_f32 v[76:77], v[76:77], 1.0 op_sel_hi:[1,0]
	v_pk_add_f32 v[74:75], v[74:75], 1.0 op_sel_hi:[1,0]
	v_pk_fma_f32 v[72:73], v[72:73], v[76:77], v[80:81]
	v_pk_fma_f32 v[70:71], v[70:71], v[74:75], v[78:79]
	v_cvt_pk_bf16_f32 v70, v70, v71
	v_cvt_pk_bf16_f32 v71, v72, v73
	global_store_dwordx2 v[86:87], v[70:71], off offset:1024
	global_load_dwordx4 v[70:73], v[104:105], off
	s_nop 0
	global_load_dwordx4 v[74:77], v[112:113], off offset:3072
	v_pk_mul_f32 v[78:79], v[64:65], v[64:65]
	v_pk_mul_f32 v[80:81], v[62:63], v[62:63]
	v_pk_mul_f32 v[104:105], v[60:61], v[60:61]
	v_pk_mov_b32 v[112:113], v[80:81], v[78:79] op_sel:[1,0]
	v_mov_b32_e32 v81, v79
	v_pk_mov_b32 v[78:79], v[106:107], v[104:105] op_sel:[1,0]
	v_mov_b32_e32 v107, v105
	v_pk_fma_f32 v[104:105], v[54:55], v[54:55], v[108:109] op_sel_hi:[1,1,0]
	v_pk_fma_f32 v[108:109], v[56:57], v[56:57], v[110:111] op_sel_hi:[1,1,0]
	v_pk_add_f32 v[78:79], v[78:79], v[106:107]
	v_mov_b32_e32 v105, v115
	v_mov_b32_e32 v109, v116
	v_lshl_add_u64 v[106:107], s[6:7], 0, v[88:89]
	v_pk_add_f32 v[104:105], v[104:105], v[108:109]
	v_lshl_add_u64 v[108:109], s[48:49], 0, v[88:89]
	v_pk_add_f32 v[80:81], v[112:113], v[80:81]
	v_pk_add_f32 v[78:79], v[78:79], v[78:79] op_sel:[0,1] op_sel_hi:[1,0]
	v_pk_add_f32 v[80:81], v[80:81], v[80:81] op_sel:[0,1] op_sel_hi:[1,0]
	v_mov_b32_e32 v79, v114
	v_mov_b32_e32 v81, v111
	s_waitcnt vmcnt(0) lgkmcnt(0)
	v_pk_add_f32 v[72:73], v[72:73], 1.0 op_sel_hi:[1,0]
	v_pk_add_f32 v[70:71], v[70:71], 1.0 op_sel_hi:[1,0]
	v_pk_fma_f32 v[68:69], v[68:69], v[72:73], v[76:77]
	v_pk_fma_f32 v[66:67], v[66:67], v[70:71], v[74:75]
	v_cvt_pk_bf16_f32 v66, v66, v67
	v_cvt_pk_bf16_f32 v67, v68, v69
	global_store_dwordx2 v[86:87], v[66:67], off offset:1536
	global_load_dwordx4 v[66:69], v[106:107], off
	s_nop 0
	global_load_dwordx4 v[70:73], v[108:109], off
	v_pk_add_f32 v[74:75], v[80:81], v[78:79]
	s_waitcnt vmcnt(0) lgkmcnt(0)
	v_pk_add_f32 v[72:73], v[72:73], 1.0 op_sel_hi:[1,0]
	v_pk_add_f32 v[74:75], v[74:75], v[104:105]
	v_pk_add_f32 v[70:71], v[70:71], 1.0 op_sel_hi:[1,0]
	v_add_f32_e32 v74, v74, v75
	ds_bpermute_b32 v75, v1, v74
	s_waitcnt lgkmcnt(0)
	v_add_f32_e32 v74, v74, v75
	ds_bpermute_b32 v75, v97, v74
	s_waitcnt lgkmcnt(0)
	v_add_f32_e32 v74, v74, v75
	ds_bpermute_b32 v75, v98, v74
	s_waitcnt lgkmcnt(0)
	v_add_f32_e32 v74, v74, v75
	ds_bpermute_b32 v75, v99, v74
	s_waitcnt lgkmcnt(0)
	v_add_f32_e32 v74, v74, v75
	ds_bpermute_b32 v75, v100, v74
	s_waitcnt lgkmcnt(0)
	v_add_f32_e32 v74, v74, v75
	ds_bpermute_b32 v75, v101, v74
	s_waitcnt lgkmcnt(0)
	v_add_f32_e32 v74, v74, v75
	v_fmamk_f32 v74, v74, 0x3a800000, v102
	v_mul_f32_e32 v75, 0x4f800000, v74
	v_cmp_gt_f32_e32 vcc, s4, v74
	s_nop 1
	v_cndmask_b32_e32 v74, v74, v75, vcc
	v_sqrt_f32_e32 v75, v74
	s_nop 0
	v_add_u32_e32 v76, -1, v75
	v_add_u32_e32 v77, 1, v75
	v_fma_f32 v78, -v76, v75, v74
	v_fma_f32 v79, -v77, v75, v74
	v_cmp_ge_f32_e64 s[6:7], 0, v78
	s_nop 1
	v_cndmask_b32_e64 v75, v75, v76, s[6:7]
	v_cmp_lt_f32_e64 s[6:7], 0, v79
	s_nop 1
	v_cndmask_b32_e64 v75, v75, v77, s[6:7]
	v_mul_f32_e32 v76, 0x37800000, v75
	v_cndmask_b32_e32 v75, v75, v76, vcc
	v_cmp_class_f32_e32 vcc, v74, v103
	s_and_b64 s[6:7], s[46:47], exec
	s_nop 0
	v_cndmask_b32_e32 v76, v75, v74, vcc
	v_div_scale_f32 v77, s[6:7], v76, v76, 1.0
	v_rcp_f32_e32 v78, v77
	v_div_scale_f32 v79, vcc, 1.0, v76, 1.0
	v_lshl_add_u64 v[74:75], s[48:49], 0, v[90:91]
	v_fma_f32 v80, -v77, v78, 1.0
	v_fmac_f32_e32 v78, v80, v78
	v_mul_f32_e32 v80, v79, v78
	v_fma_f32 v81, -v77, v80, v79
	v_fmac_f32_e32 v80, v81, v78
	v_fma_f32 v77, -v77, v80, v79
	v_div_fmas_f32 v77, v77, v78, v80
	v_div_fixup_f32 v76, v77, v76, 1.0
	v_pk_mul_f32 v[64:65], v[64:65], v[76:77] op_sel_hi:[1,0]
	v_pk_mul_f32 v[62:63], v[62:63], v[76:77] op_sel_hi:[1,0]
	v_pk_mul_f32 v[64:65], v[4:5], v[64:65]
	v_pk_mul_f32 v[62:63], v[2:3], v[62:63]
	v_pk_fma_f32 v[64:65], v[72:73], v[64:65], v[68:69]
	v_pk_fma_f32 v[62:63], v[70:71], v[62:63], v[66:67]
	v_cvt_pk_bf16_f32 v62, v62, v63
	v_cvt_pk_bf16_f32 v63, v64, v65
	global_store_dwordx2 v[86:87], v[62:63], off offset:2048
	global_load_dwordx4 v[62:65], v[74:75], off
	s_nop 0
	global_load_dwordx4 v[66:69], v[106:107], off offset:1024
	v_pk_mul_f32 v[60:61], v[60:61], v[76:77] op_sel_hi:[1,0]
	v_pk_mul_f32 v[58:59], v[58:59], v[76:77] op_sel_hi:[1,0]
	v_pk_mul_f32 v[60:61], v[8:9], v[60:61]
	v_pk_mul_f32 v[58:59], v[6:7], v[58:59]
	v_lshl_add_u64 v[70:71], s[48:49], 0, v[92:93]
	v_pk_mul_f32 v[56:57], v[56:57], v[76:77] op_sel_hi:[1,0]
	v_pk_mul_f32 v[54:55], v[54:55], v[76:77] op_sel_hi:[1,0]
	v_pk_mul_f32 v[56:57], v[12:13], v[56:57]
	v_pk_mul_f32 v[54:55], v[10:11], v[54:55]
	v_mul_f32_e32 v77, v19, v19
	v_pk_mul_f32 v[52:53], v[52:53], v[76:77] op_sel_hi:[1,0]
	v_pk_mul_f32 v[50:51], v[50:51], v[76:77] op_sel_hi:[1,0]
	v_pk_mul_f32 v[52:53], v[16:17], v[52:53]
	v_pk_mul_f32 v[50:51], v[14:15], v[50:51]
	s_cselect_b32 s6, s27, s14
	s_mul_hi_i32 s7, s6, 0x9000
	s_mul_i32 s6, s6, 0x9000
	s_add_u32 s6, s42, s6
	v_mul_f32_e32 v73, v18, v18
	v_mul_f32_e32 v72, v33, v33
	s_addc_u32 s7, s43, s7
	v_mul_f32_e32 v78, v20, v20
	v_mul_f32_e32 v79, v21, v21
	s_add_u32 s46, s6, 0x1000
	s_addc_u32 s47, s7, 0
	s_add_i32 s14, s10, 0xffffc005
	s_waitcnt vmcnt(0) lgkmcnt(0)
	v_pk_add_f32 v[64:65], v[64:65], 1.0 op_sel_hi:[1,0]
	v_pk_add_f32 v[62:63], v[62:63], 1.0 op_sel_hi:[1,0]
	v_pk_fma_f32 v[60:61], v[64:65], v[60:61], v[68:69]
	v_pk_fma_f32 v[58:59], v[62:63], v[58:59], v[66:67]
	v_cvt_pk_bf16_f32 v58, v58, v59
	v_cvt_pk_bf16_f32 v59, v60, v61
	global_store_dwordx2 v[86:87], v[58:59], off offset:2560
	global_load_dwordx4 v[58:61], v[70:71], off
	s_nop 0
	global_load_dwordx4 v[62:65], v[106:107], off offset:2048
	v_lshl_add_u64 v[66:67], s[48:49], 0, v[94:95]
	v_pk_mul_f32 v[68:69], v[38:39], v[38:39]
	v_mul_f32_e32 v70, v31, v31
	s_waitcnt vmcnt(0) lgkmcnt(0)
	v_pk_add_f32 v[60:61], v[60:61], 1.0 op_sel_hi:[1,0]
	v_pk_add_f32 v[58:59], v[58:59], 1.0 op_sel_hi:[1,0]
	v_pk_fma_f32 v[56:57], v[60:61], v[56:57], v[64:65]
	v_pk_fma_f32 v[54:55], v[58:59], v[54:55], v[62:63]
	v_cvt_pk_bf16_f32 v54, v54, v55
	v_cvt_pk_bf16_f32 v55, v56, v57
	global_store_dwordx2 v[86:87], v[54:55], off offset:3072
	global_load_dwordx4 v[54:57], v[66:67], off
	s_nop 0
	global_load_dwordx4 v[58:61], v[106:107], off offset:3072
	v_pk_mul_f32 v[62:63], v[48:49], v[48:49]
	v_pk_mul_f32 v[64:65], v[46:47], v[46:47]
	v_pk_mul_f32 v[66:67], v[40:41], v[40:41]
	v_pk_mov_b32 v[74:75], v[64:65], v[62:63] op_sel:[1,0]
	v_mov_b32_e32 v65, v63
	v_pk_mov_b32 v[62:63], v[68:69], v[66:67] op_sel:[1,0]
	v_mov_b32_e32 v69, v67
	v_pk_fma_f32 v[66:67], v[30:31], v[30:31], v[70:71] op_sel_hi:[1,1,0]
	v_pk_fma_f32 v[70:71], v[32:33], v[32:33], v[72:73] op_sel_hi:[1,1,0]
	v_pk_add_f32 v[62:63], v[62:63], v[68:69]
	v_mov_b32_e32 v67, v78
	v_mov_b32_e32 v71, v79
	v_lshl_add_u64 v[68:69], s[6:7], 0, v[88:89]
	v_pk_add_f32 v[66:67], v[66:67], v[70:71]
	v_lshl_add_u64 v[70:71], s[46:47], 0, v[88:89]
	v_pk_add_f32 v[64:65], v[74:75], v[64:65]
	v_pk_add_f32 v[62:63], v[62:63], v[62:63] op_sel:[0,1] op_sel_hi:[1,0]
	v_pk_add_f32 v[64:65], v[64:65], v[64:65] op_sel:[0,1] op_sel_hi:[1,0]
	v_mov_b32_e32 v63, v77
	v_mov_b32_e32 v65, v73
	s_waitcnt vmcnt(0) lgkmcnt(0)
	v_pk_add_f32 v[56:57], v[56:57], 1.0 op_sel_hi:[1,0]
	v_pk_add_f32 v[54:55], v[54:55], 1.0 op_sel_hi:[1,0]
	v_pk_fma_f32 v[52:53], v[52:53], v[56:57], v[60:61]
	v_pk_fma_f32 v[50:51], v[50:51], v[54:55], v[58:59]
	v_cvt_pk_bf16_f32 v50, v50, v51
	v_cvt_pk_bf16_f32 v51, v52, v53
	global_store_dwordx2 v[86:87], v[50:51], off offset:3584
	global_load_dwordx4 v[52:55], v[68:69], off
	global_load_dwordx4 v[56:59], v[70:71], off
	v_pk_add_f32 v[50:51], v[64:65], v[62:63]
	s_waitcnt vmcnt(0) lgkmcnt(0)
	v_pk_add_f32 v[58:59], v[58:59], 1.0 op_sel_hi:[1,0]
	v_pk_add_f32 v[50:51], v[50:51], v[66:67]
	v_pk_add_f32 v[56:57], v[56:57], 1.0 op_sel_hi:[1,0]
	v_add_f32_e32 v50, v50, v51
	ds_bpermute_b32 v51, v1, v50
	s_waitcnt lgkmcnt(0)
	v_add_f32_e32 v50, v50, v51
	ds_bpermute_b32 v51, v97, v50
	s_waitcnt lgkmcnt(0)
	v_add_f32_e32 v50, v50, v51
	ds_bpermute_b32 v51, v98, v50
	s_waitcnt lgkmcnt(0)
	v_add_f32_e32 v50, v50, v51
	ds_bpermute_b32 v51, v99, v50
	s_waitcnt lgkmcnt(0)
	v_add_f32_e32 v50, v50, v51
	ds_bpermute_b32 v51, v100, v50
	s_waitcnt lgkmcnt(0)
	v_add_f32_e32 v50, v50, v51
	ds_bpermute_b32 v51, v101, v50
	s_waitcnt lgkmcnt(0)
	v_add_f32_e32 v50, v50, v51
	v_fmamk_f32 v50, v50, 0x3a800000, v102
	v_mul_f32_e32 v51, 0x4f800000, v50
	v_cmp_gt_f32_e32 vcc, s4, v50
	s_nop 1
	v_cndmask_b32_e32 v60, v50, v51, vcc
	v_sqrt_f32_e32 v61, v60
	v_add_co_u32_e64 v50, s[6:7], s26, v86
	v_add_u32_e32 v62, -1, v61
	s_nop 0
	v_addc_co_u32_e64 v51, s[6:7], 0, v87, s[6:7]
	v_add_u32_e32 v63, 1, v61
	v_fma_f32 v64, -v62, v61, v60
	v_fma_f32 v65, -v63, v61, v60
	v_cmp_ge_f32_e64 s[6:7], 0, v64
	v_lshl_add_u64 v[86:87], v[86:87], 0, s[18:19]
	s_nop 0
	v_cndmask_b32_e64 v61, v61, v62, s[6:7]
	v_cmp_lt_f32_e64 s[6:7], 0, v65
	s_nop 1
	v_cndmask_b32_e64 v61, v61, v63, s[6:7]
	v_mul_f32_e32 v62, 0x37800000, v61
	v_cndmask_b32_e32 v61, v61, v62, vcc
	v_cmp_class_f32_e32 vcc, v60, v103
	s_and_b64 s[6:7], exec, s[24:25]
	s_nop 0
	v_cndmask_b32_e32 v62, v61, v60, vcc
	v_div_scale_f32 v63, s[6:7], v62, v62, 1.0
	v_rcp_f32_e32 v64, v63
	v_div_scale_f32 v65, vcc, 1.0, v62, 1.0
	v_lshl_add_u64 v[60:61], s[46:47], 0, v[90:91]
	v_fma_f32 v66, -v63, v64, 1.0
	v_fmac_f32_e32 v64, v66, v64
	v_mul_f32_e32 v66, v65, v64
	v_fma_f32 v67, -v63, v66, v65
	v_fmac_f32_e32 v66, v67, v64
	v_fma_f32 v63, -v63, v66, v65
	v_div_fmas_f32 v63, v63, v64, v66
	v_div_fixup_f32 v62, v63, v62, 1.0
	v_pk_mul_f32 v[48:49], v[48:49], v[62:63] op_sel_hi:[1,0]
	v_pk_mul_f32 v[46:47], v[46:47], v[62:63] op_sel_hi:[1,0]
	v_pk_mul_f32 v[48:49], v[4:5], v[48:49]
	v_pk_mul_f32 v[46:47], v[2:3], v[46:47]
	v_pk_fma_f32 v[48:49], v[58:59], v[48:49], v[54:55]
	v_pk_fma_f32 v[46:47], v[56:57], v[46:47], v[52:53]
	v_cvt_pk_bf16_f32 v46, v46, v47
	v_cvt_pk_bf16_f32 v47, v48, v49
	global_store_dwordx2 v[50:51], v[46:47], off
	global_load_dwordx4 v[46:49], v[60:61], off
	s_nop 0
	global_load_dwordx4 v[52:55], v[68:69], off offset:1024
	v_pk_mul_f32 v[40:41], v[40:41], v[62:63] op_sel_hi:[1,0]
	v_pk_mul_f32 v[38:39], v[38:39], v[62:63] op_sel_hi:[1,0]
	v_pk_mul_f32 v[40:41], v[8:9], v[40:41]
	v_pk_mul_f32 v[38:39], v[6:7], v[38:39]
	v_lshl_add_u64 v[56:57], s[46:47], 0, v[92:93]
	v_pk_mul_f32 v[32:33], v[32:33], v[62:63] op_sel_hi:[1,0]
	v_pk_mul_f32 v[30:31], v[30:31], v[62:63] op_sel_hi:[1,0]
	v_pk_mul_f32 v[32:33], v[12:13], v[32:33]
	v_pk_mul_f32 v[30:31], v[10:11], v[30:31]
	v_pk_mul_f32 v[20:21], v[20:21], v[62:63] op_sel_hi:[1,0]
	v_pk_mul_f32 v[18:19], v[18:19], v[62:63] op_sel_hi:[1,0]
	v_pk_mul_f32 v[20:21], v[16:17], v[20:21]
	v_pk_mul_f32 v[18:19], v[14:15], v[18:19]
	s_cselect_b32 s6, s27, s14
	s_mul_hi_i32 s7, s6, 0x9000
	s_mul_i32 s6, s6, 0x9000
	s_add_u32 s6, s42, s6
	s_addc_u32 s7, s43, s7
	s_lshl_b64 s[28:29], s[44:45], 11
	s_add_u32 s24, s6, 0x1000
	s_addc_u32 s25, s7, 0
	v_pk_mul_f32 v[58:59], v[34:35], v[34:35]
	v_mul_f32_e32 v63, v22, v22
	v_mul_f32_e32 v60, v27, v27
	v_mul_f32_e32 v62, v29, v29
	v_mul_f32_e32 v66, v23, v23
	v_mul_f32_e32 v67, v24, v24
	s_add_u32 s10, s10, s16
	s_addc_u32 s11, s11, s17
	s_add_u32 s20, s20, s22
	s_addc_u32 s21, s21, s23
	s_cmpk_lt_i32 s10, 0x4080
	s_waitcnt vmcnt(0) lgkmcnt(0)
	v_pk_add_f32 v[48:49], v[48:49], 1.0 op_sel_hi:[1,0]
	v_pk_add_f32 v[46:47], v[46:47], 1.0 op_sel_hi:[1,0]
	v_pk_fma_f32 v[40:41], v[48:49], v[40:41], v[54:55]
	v_pk_fma_f32 v[38:39], v[46:47], v[38:39], v[52:53]
	v_cvt_pk_bf16_f32 v38, v38, v39
	v_cvt_pk_bf16_f32 v39, v40, v41
	global_store_dwordx2 v[50:51], v[38:39], off offset:512
	global_load_dwordx4 v[38:41], v[56:57], off
	s_nop 0
	global_load_dwordx4 v[46:49], v[68:69], off offset:2048
	v_lshl_add_u64 v[52:53], s[46:47], 0, v[94:95]
	v_pk_mul_f32 v[54:55], v[42:43], v[42:43]
	v_pk_mul_f32 v[56:57], v[36:37], v[36:37]
	s_waitcnt vmcnt(0) lgkmcnt(0)
	v_pk_add_f32 v[40:41], v[40:41], 1.0 op_sel_hi:[1,0]
	v_pk_add_f32 v[38:39], v[38:39], 1.0 op_sel_hi:[1,0]
	v_pk_fma_f32 v[32:33], v[40:41], v[32:33], v[48:49]
	v_pk_fma_f32 v[30:31], v[38:39], v[30:31], v[46:47]
	v_cvt_pk_bf16_f32 v30, v30, v31
	v_cvt_pk_bf16_f32 v31, v32, v33
	global_store_dwordx2 v[50:51], v[30:31], off offset:1024
	global_load_dwordx4 v[38:41], v[52:53], off
	global_load_dwordx4 v[46:49], v[68:69], off offset:3072
	v_lshl_add_u64 v[30:31], s[6:7], 0, v[88:89]
	v_lshl_add_u64 v[32:33], s[24:25], 0, v[88:89]
	v_pk_mul_f32 v[52:53], v[44:45], v[44:45]
	v_mul_f32_e32 v68, v25, v25
	v_pk_mov_b32 v[64:65], v[54:55], v[52:53] op_sel:[1,0]
	v_mov_b32_e32 v55, v53
	v_pk_mov_b32 v[52:53], v[58:59], v[56:57] op_sel:[1,0]
	v_mov_b32_e32 v59, v57
	v_pk_add_f32 v[54:55], v[64:65], v[54:55]
	v_pk_add_f32 v[52:53], v[52:53], v[58:59]
	v_pk_fma_f32 v[56:57], v[26:27], v[26:27], v[60:61] op_sel_hi:[1,1,0]
	v_pk_fma_f32 v[60:61], v[28:29], v[28:29], v[62:63] op_sel_hi:[1,1,0]
	v_pk_add_f32 v[54:55], v[54:55], v[54:55] op_sel:[0,1] op_sel_hi:[1,0]
	v_pk_add_f32 v[52:53], v[52:53], v[52:53] op_sel:[0,1] op_sel_hi:[1,0]
	v_mov_b32_e32 v57, v67
	v_mov_b32_e32 v61, v68
	v_mov_b32_e32 v55, v63
	v_mov_b32_e32 v53, v66
	v_pk_add_f32 v[56:57], v[56:57], v[60:61]
	s_waitcnt vmcnt(0) lgkmcnt(0)
	v_pk_add_f32 v[40:41], v[40:41], 1.0 op_sel_hi:[1,0]
	v_pk_add_f32 v[38:39], v[38:39], 1.0 op_sel_hi:[1,0]
	v_pk_fma_f32 v[20:21], v[20:21], v[40:41], v[48:49]
	v_pk_fma_f32 v[18:19], v[18:19], v[38:39], v[46:47]
	v_cvt_pk_bf16_f32 v18, v18, v19
	v_cvt_pk_bf16_f32 v19, v20, v21
	global_store_dwordx2 v[50:51], v[18:19], off offset:1536
	global_load_dwordx4 v[18:21], v[30:31], off
	s_nop 0
	global_load_dwordx4 v[38:41], v[32:33], off
	v_pk_add_f32 v[32:33], v[54:55], v[52:53]
	v_lshl_add_u64 v[46:47], v[84:85], 0, s[28:29]
	v_pk_add_f32 v[32:33], v[32:33], v[56:57]
	s_waitcnt vmcnt(0) lgkmcnt(0)
	v_pk_add_f32 v[40:41], v[40:41], 1.0 op_sel_hi:[1,0]
	v_add_f32_e32 v32, v32, v33
	ds_bpermute_b32 v33, v1, v32
	v_pk_add_f32 v[38:39], v[38:39], 1.0 op_sel_hi:[1,0]
	s_waitcnt lgkmcnt(0)
	v_add_f32_e32 v32, v32, v33
	ds_bpermute_b32 v33, v97, v32
	s_waitcnt lgkmcnt(0)
	v_add_f32_e32 v32, v32, v33
	ds_bpermute_b32 v33, v98, v32
	s_waitcnt lgkmcnt(0)
	v_add_f32_e32 v32, v32, v33
	ds_bpermute_b32 v33, v99, v32
	s_waitcnt lgkmcnt(0)
	v_add_f32_e32 v32, v32, v33
	ds_bpermute_b32 v33, v100, v32
	s_waitcnt lgkmcnt(0)
	v_add_f32_e32 v32, v32, v33
	ds_bpermute_b32 v33, v101, v32
	s_waitcnt lgkmcnt(0)
	v_add_f32_e32 v32, v32, v33
	v_fmamk_f32 v32, v32, 0x3a800000, v102
	v_mul_f32_e32 v33, 0x4f800000, v32
	v_cmp_gt_f32_e32 vcc, s4, v32
	s_nop 1
	v_cndmask_b32_e32 v32, v32, v33, vcc
	v_sqrt_f32_e32 v33, v32
	s_nop 0
	v_add_u32_e32 v48, -1, v33
	v_add_u32_e32 v49, 1, v33
	v_fma_f32 v50, -v48, v33, v32
	v_fma_f32 v51, -v49, v33, v32
	v_cmp_ge_f32_e64 s[6:7], 0, v50
	s_nop 1
	v_cndmask_b32_e64 v33, v33, v48, s[6:7]
	v_cmp_lt_f32_e64 s[6:7], 0, v51
	s_nop 1
	v_cndmask_b32_e64 v33, v33, v49, s[6:7]
	v_mul_f32_e32 v48, 0x37800000, v33
	v_cndmask_b32_e32 v33, v33, v48, vcc
	v_cmp_class_f32_e32 vcc, v32, v103
	s_nop 1
	v_cndmask_b32_e32 v48, v33, v32, vcc
	v_div_scale_f32 v49, s[6:7], v48, v48, 1.0
	v_rcp_f32_e32 v50, v49
	v_div_scale_f32 v51, vcc, 1.0, v48, 1.0
	v_lshl_add_u64 v[32:33], s[24:25], 0, v[90:91]
	v_fma_f32 v52, -v49, v50, 1.0
	v_fmac_f32_e32 v50, v52, v50
	v_mul_f32_e32 v52, v51, v50
	v_fma_f32 v53, -v49, v52, v51
	v_fmac_f32_e32 v52, v53, v50
	v_fma_f32 v49, -v49, v52, v51
	v_div_fmas_f32 v49, v49, v50, v52
	v_div_fixup_f32 v48, v49, v48, 1.0
	v_pk_mul_f32 v[44:45], v[44:45], v[48:49] op_sel_hi:[1,0]
	v_pk_mul_f32 v[42:43], v[42:43], v[48:49] op_sel_hi:[1,0]
	v_pk_mul_f32 v[44:45], v[4:5], v[44:45]
	v_pk_mul_f32 v[42:43], v[2:3], v[42:43]
	v_pk_fma_f32 v[20:21], v[40:41], v[44:45], v[20:21]
	v_pk_fma_f32 v[18:19], v[38:39], v[42:43], v[18:19]
	v_cvt_pk_bf16_f32 v18, v18, v19
	v_cvt_pk_bf16_f32 v19, v20, v21
	global_store_dwordx2 v[46:47], v[18:19], off
	global_load_dwordx4 v[18:21], v[32:33], off
	s_nop 0
	global_load_dwordx4 v[38:41], v[30:31], off offset:1024
	v_pk_mul_f32 v[32:33], v[36:37], v[48:49] op_sel_hi:[1,0]
	v_pk_mul_f32 v[34:35], v[34:35], v[48:49] op_sel_hi:[1,0]
	v_pk_mul_f32 v[32:33], v[8:9], v[32:33]
	v_pk_mul_f32 v[34:35], v[6:7], v[34:35]
	v_lshl_add_u64 v[42:43], s[24:25], 0, v[92:93]
	v_pk_mul_f32 v[28:29], v[28:29], v[48:49] op_sel_hi:[1,0]
	v_pk_mul_f32 v[26:27], v[26:27], v[48:49] op_sel_hi:[1,0]
	v_pk_mul_f32 v[28:29], v[12:13], v[28:29]
	v_pk_mul_f32 v[26:27], v[10:11], v[26:27]
	v_lshl_add_u64 v[36:37], s[24:25], 0, v[94:95]
	v_pk_mul_f32 v[24:25], v[24:25], v[48:49] op_sel_hi:[1,0]
	v_pk_mul_f32 v[22:23], v[22:23], v[48:49] op_sel_hi:[1,0]
	v_pk_mul_f32 v[24:25], v[16:17], v[24:25]
	v_pk_mul_f32 v[22:23], v[14:15], v[22:23]
	s_waitcnt vmcnt(0) lgkmcnt(0)
	v_pk_add_f32 v[20:21], v[20:21], 1.0 op_sel_hi:[1,0]
	v_pk_add_f32 v[18:19], v[18:19], 1.0 op_sel_hi:[1,0]
	v_pk_fma_f32 v[20:21], v[20:21], v[32:33], v[40:41]
	v_pk_fma_f32 v[18:19], v[18:19], v[34:35], v[38:39]
	v_cvt_pk_bf16_f32 v18, v18, v19
	v_cvt_pk_bf16_f32 v19, v20, v21
	global_store_dwordx2 v[46:47], v[18:19], off offset:512
	global_load_dwordx4 v[18:21], v[42:43], off
	s_nop 0
	global_load_dwordx4 v[32:35], v[30:31], off offset:2048
	s_waitcnt vmcnt(0) lgkmcnt(0)
	v_pk_add_f32 v[20:21], v[20:21], 1.0 op_sel_hi:[1,0]
	v_pk_add_f32 v[18:19], v[18:19], 1.0 op_sel_hi:[1,0]
	v_pk_fma_f32 v[20:21], v[20:21], v[28:29], v[34:35]
	v_pk_fma_f32 v[18:19], v[18:19], v[26:27], v[32:33]
	v_cvt_pk_bf16_f32 v18, v18, v19
	v_cvt_pk_bf16_f32 v19, v20, v21
	global_store_dwordx2 v[46:47], v[18:19], off offset:1024
	global_load_dwordx4 v[18:21], v[36:37], off
	s_nop 0
	global_load_dwordx4 v[26:29], v[30:31], off offset:3072
	s_waitcnt vmcnt(0) lgkmcnt(0)
	v_pk_add_f32 v[20:21], v[20:21], 1.0 op_sel_hi:[1,0]
	v_pk_add_f32 v[18:19], v[18:19], 1.0 op_sel_hi:[1,0]
	v_pk_fma_f32 v[20:21], v[24:25], v[20:21], v[28:29]
	v_pk_fma_f32 v[18:19], v[22:23], v[18:19], v[26:27]
	v_cvt_pk_bf16_f32 v18, v18, v19
	v_cvt_pk_bf16_f32 v19, v20, v21
	global_store_dwordx2 v[46:47], v[18:19], off offset:1536
	s_cbranch_scc0 .LBB0_735

.LBB0_842:
	v_lshl_add_u64 v[18:19], s[38:39], 0, v[94:95]
	v_lshl_add_u64 v[22:23], s[38:39], 0, v[92:93]
	v_add_co_u32_e32 v20, vcc, 0x7800000, v18
	v_add_co_u32_e64 v102, s[6:7], s31, v22
	s_nop 0
	v_addc_co_u32_e32 v21, vcc, 0, v19, vcc
	v_addc_co_u32_e64 v103, s[6:7], 0, v23, s[6:7]
	v_add_co_u32_e64 v104, s[6:7], s33, v22
	v_add_co_u32_e32 v22, vcc, 0x7801000, v18
	s_nop 0
	v_addc_co_u32_e64 v105, s[6:7], 0, v23, s[6:7]
	global_load_dwordx4 v[78:81], v[20:21], off
	global_load_dwordx4 v[74:77], v[20:21], off offset:1024
	global_load_dwordx4 v[70:73], v[20:21], off offset:2048
	global_load_dwordx4 v[66:69], v[20:21], off offset:3072
	v_addc_co_u32_e32 v23, vcc, 0, v19, vcc
	v_add_co_u32_e32 v20, vcc, 0x7802000, v18
	global_load_dwordx4 v[62:65], v[22:23], off
	global_load_dwordx4 v[58:61], v[22:23], off offset:1024
	global_load_dwordx4 v[54:57], v[22:23], off offset:2048
	global_load_dwordx4 v[50:53], v[22:23], off offset:3072
	v_addc_co_u32_e32 v21, vcc, 0, v19, vcc
	global_load_dwordx4 v[46:49], v[20:21], off
	global_load_dwordx4 v[42:45], v[20:21], off offset:1024
	global_load_dwordx4 v[38:41], v[20:21], off offset:2048
	global_load_dwordx4 v[34:37], v[20:21], off offset:3072
	v_add_co_u32_e32 v18, vcc, 0x7803000, v18
	s_ashr_i32 s8, s18, 13
	s_nop 0
	v_addc_co_u32_e32 v19, vcc, 0, v19, vcc
	global_load_dwordx4 v[30:33], v[18:19], off
	global_load_dwordx4 v[26:29], v[18:19], off offset:1024
	global_load_dwordx4 v[22:25], v[18:19], off offset:2048
	s_nop 0
	global_load_dwordx4 v[18:21], v[18:19], off offset:3072
	s_add_i32 s9, s18, 0xffffc002
	s_cmpk_lt_i32 s18, 0x4000
	s_cselect_b32 s6, s8, s9
	s_mul_hi_i32 s7, s6, 0x9000
	s_mul_i32 s6, s6, 0x9000
	s_add_u32 s6, s27, s6
	s_addc_u32 s7, s28, s7
	s_add_u32 s10, s6, 0x1000
	s_addc_u32 s11, s7, 0
	v_lshl_add_u64 v[122:123], s[6:7], 0, v[90:91]
	v_lshl_add_u64 v[86:87], s[10:11], 0, v[90:91]
	global_load_dwordx4 v[82:85], v[122:123], off
	s_add_i32 s6, s18, 0xffffc003
	global_load_dwordx4 v[86:89], v[86:87], off
	s_cmpk_lt_i32 s18, 0x3fff
	s_cselect_b32 s6, s8, s6
	s_mul_hi_i32 s7, s6, 0x9000
	s_mul_i32 s6, s6, 0x9000
	s_add_u32 s6, s27, s6
	s_addc_u32 s7, s28, s7
	v_lshl_add_u64 v[142:143], s[10:11], 0, v[96:97]
	v_lshl_add_u64 v[138:139], s[10:11], 0, v[98:99]
	v_lshl_add_u64 v[128:129], s[10:11], 0, v[100:101]
	s_add_u32 s10, s6, 0x1000
	v_lshl_add_u64 v[110:111], s[6:7], 0, v[90:91]
	s_addc_u32 s11, s7, 0
	s_add_i32 s6, s18, 0xffffc004
	s_cmpk_lt_i32 s18, 0x3ffe
	s_cselect_b32 s6, s8, s6
	s_mul_hi_i32 s7, s6, 0x9000
	s_mul_i32 s6, s6, 0x9000
	v_lshl_add_u64 v[124:125], s[10:11], 0, v[90:91]
	v_lshl_add_u64 v[118:119], s[10:11], 0, v[96:97]
	v_lshl_add_u64 v[114:115], s[10:11], 0, v[98:99]
	v_lshl_add_u64 v[112:113], s[10:11], 0, v[100:101]
	s_add_u32 s10, s27, s6
	s_addc_u32 s11, s28, s7
	s_add_u32 s6, s10, 0x1000
	s_addc_u32 s7, s11, 0
	s_add_i32 s9, s18, 0xffffc005
	s_cmpk_lt_i32 s18, 0x3ffd
	v_lshl_add_u64 v[146:147], s[6:7], 0, v[90:91]
	v_lshl_add_u64 v[144:145], s[6:7], 0, v[96:97]
	v_lshl_add_u64 v[140:141], s[6:7], 0, v[98:99]
	v_lshl_add_u64 v[126:127], s[6:7], 0, v[100:101]
	s_cselect_b32 s6, s8, s9
	s_mul_hi_i32 s7, s6, 0x9000
	s_mul_i32 s6, s6, 0x9000
	s_add_u32 s6, s27, s6
	s_addc_u32 s7, s28, s7
	s_add_u32 s24, s6, 0x1000
	v_lshl_add_u64 v[106:107], s[6:7], 0, v[90:91]
	s_addc_u32 s25, s7, 0
	v_lshl_add_u64 v[108:109], s[10:11], 0, v[90:91]
	v_lshl_add_u64 v[120:121], s[24:25], 0, v[90:91]
	v_lshl_add_u64 v[116:117], s[24:25], 0, v[96:97]
	s_add_i32 s18, s18, 32
	v_lshl_add_u64 v[92:93], v[92:93], 0, s[20:21]
	v_lshl_add_u64 v[94:95], v[94:95], 0, s[22:23]
	s_cmp_lt_i32 s18, s26
	s_waitcnt vmcnt(0) lgkmcnt(0)
	v_pk_mul_f32 v[148:149], v[80:81], v[80:81]
	v_pk_mul_f32 v[150:151], v[78:79], v[78:79]
	v_pk_mul_f32 v[152:153], v[76:77], v[76:77]
	v_pk_mul_f32 v[154:155], v[74:75], v[74:75]
	v_mul_f32_e32 v164, v71, v71
	v_mul_f32_e32 v166, v73, v73
	v_pk_mov_b32 v[168:169], v[150:151], v[148:149] op_sel:[1,0]
	v_mov_b32_e32 v151, v149
	v_pk_mov_b32 v[148:149], v[154:155], v[152:153] op_sel:[1,0]
	v_mov_b32_e32 v155, v153
	v_mul_f32_e32 v177, v68, v68
	v_mul_f32_e32 v179, v69, v69
	v_pk_fma_f32 v[152:153], v[70:71], v[70:71], v[164:165] op_sel_hi:[1,1,0]
	v_pk_fma_f32 v[164:165], v[72:73], v[72:73], v[166:167] op_sel_hi:[1,1,0]
	v_pk_mul_f32 v[166:167], v[64:65], v[64:65]
	v_pk_mul_f32 v[170:171], v[62:63], v[62:63]
	v_pk_mul_f32 v[172:173], v[60:61], v[60:61]
	v_pk_mul_f32 v[174:175], v[58:59], v[58:59]
	v_mul_f32_e32 v176, v55, v55
	v_mul_f32_e32 v178, v57, v57
	v_pk_add_f32 v[150:151], v[168:169], v[150:151]
	v_pk_add_f32 v[148:149], v[148:149], v[154:155]
	v_mul_f32_e32 v163, v66, v66
	v_mul_f32_e32 v187, v67, v67
	v_mov_b32_e32 v153, v177
	v_mov_b32_e32 v165, v179
	v_pk_mov_b32 v[154:155], v[170:171], v[166:167] op_sel:[1,0]
	v_mov_b32_e32 v171, v167
	v_pk_mov_b32 v[166:167], v[174:175], v[172:173] op_sel:[1,0]
	v_mov_b32_e32 v175, v173
	v_pk_fma_f32 v[168:169], v[54:55], v[54:55], v[176:177] op_sel_hi:[1,1,0]
	v_pk_fma_f32 v[172:173], v[56:57], v[56:57], v[178:179] op_sel_hi:[1,1,0]
	v_pk_mul_f32 v[176:177], v[48:49], v[48:49]
	v_pk_mul_f32 v[178:179], v[46:47], v[46:47]
	v_pk_add_f32 v[188:189], v[150:151], v[150:151] op_sel:[0,1] op_sel_hi:[1,0]
	v_pk_add_f32 v[190:191], v[148:149], v[148:149] op_sel:[0,1] op_sel_hi:[1,0]
	v_mul_f32_e32 v185, v52, v52
	v_pk_mul_f32 v[180:181], v[44:45], v[44:45]
	v_pk_mul_f32 v[182:183], v[42:43], v[42:43]
	v_mul_f32_e32 v184, v39, v39
	v_mul_f32_e32 v186, v41, v41
	v_pk_add_f32 v[164:165], v[152:153], v[164:165]
	v_pk_add_f32 v[148:149], v[154:155], v[170:171]
	v_pk_add_f32 v[150:151], v[166:167], v[174:175]
	v_pk_mov_b32 v[152:153], v[178:179], v[176:177] op_sel:[1,0]
	v_mov_b32_e32 v179, v177
	v_mov_b32_e32 v189, v163
	v_mov_b32_e32 v191, v187
	v_mul_f32_e32 v193, v50, v50
	v_mul_f32_e32 v198, v51, v51
	v_mul_f32_e32 v192, v53, v53
	v_mul_f32_e32 v201, v36, v36
	v_mul_f32_e32 v202, v37, v37
	v_pk_mov_b32 v[154:155], v[182:183], v[180:181] op_sel:[1,0]
	v_mov_b32_e32 v183, v181
	v_pk_fma_f32 v[166:167], v[38:39], v[38:39], v[184:185] op_sel_hi:[1,1,0]
	v_pk_fma_f32 v[170:171], v[40:41], v[40:41], v[186:187] op_sel_hi:[1,1,0]
	v_pk_add_f32 v[194:195], v[148:149], v[148:149] op_sel:[0,1] op_sel_hi:[1,0]
	v_pk_add_f32 v[196:197], v[150:151], v[150:151] op_sel:[0,1] op_sel_hi:[1,0]
	v_pk_add_f32 v[152:153], v[152:153], v[178:179]
	v_pk_add_f32 v[178:179], v[188:189], v[190:191]
	v_mov_b32_e32 v169, v185
	v_mov_b32_e32 v173, v192
	v_pk_mul_f32 v[174:175], v[32:33], v[32:33]
	v_pk_mul_f32 v[176:177], v[30:31], v[30:31]
	v_pk_mul_f32 v[180:181], v[28:29], v[28:29]
	v_pk_mul_f32 v[184:185], v[26:27], v[26:27]
	v_pk_add_f32 v[154:155], v[154:155], v[182:183]
	v_mov_b32_e32 v167, v201
	v_mov_b32_e32 v171, v202
	v_mov_b32_e32 v195, v193
	v_mov_b32_e32 v197, v198
	v_pk_add_f32 v[164:165], v[178:179], v[164:165]
	v_mul_f32_e32 v199, v34, v34
	v_mul_f32_e32 v200, v35, v35
	v_pk_add_f32 v[168:169], v[168:169], v[172:173]
	v_pk_mov_b32 v[172:173], v[176:177], v[174:175] op_sel:[1,0]
	v_mov_b32_e32 v177, v175
	v_pk_mov_b32 v[174:175], v[184:185], v[180:181] op_sel:[1,0]
	v_mov_b32_e32 v185, v181
	v_pk_add_f32 v[180:181], v[152:153], v[152:153] op_sel:[0,1] op_sel_hi:[1,0]
	v_pk_add_f32 v[182:183], v[154:155], v[154:155] op_sel:[0,1] op_sel_hi:[1,0]
	v_pk_add_f32 v[166:167], v[166:167], v[170:171]
	v_pk_add_f32 v[170:171], v[194:195], v[196:197]
	v_add_f32_e32 v163, v164, v165
	v_mov_b32_e32 v181, v199
	v_mov_b32_e32 v183, v200
	v_pk_add_f32 v[164:165], v[170:171], v[168:169]
	ds_bpermute_b32 v171, v133, v163
	v_pk_add_f32 v[168:169], v[180:181], v[182:183]
	v_add_f32_e32 v170, v164, v165
	v_pk_add_f32 v[164:165], v[168:169], v[166:167]
	ds_bpermute_b32 v166, v133, v170
	v_add_f32_e32 v164, v164, v165
	ds_bpermute_b32 v165, v133, v164
	s_waitcnt lgkmcnt(2)
	v_add_f32_e32 v163, v163, v171
	ds_bpermute_b32 v167, v156, v163
	s_waitcnt lgkmcnt(2)
	v_add_f32_e32 v166, v170, v166
	ds_bpermute_b32 v168, v156, v166
	s_waitcnt lgkmcnt(2)
	v_add_f32_e32 v164, v164, v165
	ds_bpermute_b32 v165, v156, v164
	s_waitcnt lgkmcnt(2)
	v_add_f32_e32 v163, v163, v167
	ds_bpermute_b32 v167, v157, v163
	s_waitcnt lgkmcnt(2)
	v_add_f32_e32 v166, v166, v168
	ds_bpermute_b32 v168, v157, v166
	s_waitcnt lgkmcnt(2)
	v_add_f32_e32 v164, v164, v165
	ds_bpermute_b32 v165, v157, v164
	s_waitcnt lgkmcnt(2)
	v_add_f32_e32 v163, v163, v167
	ds_bpermute_b32 v167, v158, v163
	s_waitcnt lgkmcnt(2)
	v_add_f32_e32 v166, v166, v168
	ds_bpermute_b32 v168, v158, v166
	s_waitcnt lgkmcnt(2)
	v_add_f32_e32 v164, v164, v165
	ds_bpermute_b32 v165, v158, v164
	s_waitcnt lgkmcnt(2)
	v_add_f32_e32 v163, v163, v167
	ds_bpermute_b32 v167, v159, v163
	s_waitcnt lgkmcnt(2)
	v_add_f32_e32 v166, v166, v168
	ds_bpermute_b32 v168, v159, v166
	s_waitcnt lgkmcnt(2)
	v_add_f32_e32 v164, v164, v165
	ds_bpermute_b32 v165, v159, v164
	s_waitcnt lgkmcnt(2)
	v_add_f32_e32 v163, v163, v167
	ds_bpermute_b32 v167, v160, v163
	s_waitcnt lgkmcnt(2)
	v_add_f32_e32 v166, v166, v168
	ds_bpermute_b32 v168, v160, v166
	s_waitcnt lgkmcnt(2)
	v_add_f32_e32 v164, v164, v165
	ds_bpermute_b32 v165, v160, v164
	s_waitcnt lgkmcnt(2)
	v_add_f32_e32 v163, v163, v167
	v_fmamk_f32 v163, v163, 0x3a800000, v161
	s_waitcnt lgkmcnt(1)
	v_add_f32_e32 v166, v166, v168
	v_mul_f32_e32 v167, 0x4f800000, v163
	v_cmp_gt_f32_e32 vcc, s19, v163
	v_fmamk_f32 v166, v166, 0x3a800000, v161
	s_waitcnt lgkmcnt(0)
	v_add_f32_e32 v164, v164, v165
	v_cndmask_b32_e32 v163, v163, v167, vcc
	v_mul_f32_e32 v165, 0x4f800000, v166
	v_cmp_gt_f32_e64 s[6:7], s19, v166
	v_sqrt_f32_e32 v167, v163
	v_fmamk_f32 v164, v164, 0x3a800000, v161
	v_cndmask_b32_e64 v165, v166, v165, s[6:7]
	v_mul_f32_e32 v166, 0x4f800000, v164
	v_cmp_gt_f32_e64 s[8:9], s19, v164
	v_sqrt_f32_e32 v168, v165
	v_add_u32_e32 v169, -1, v167
	v_cndmask_b32_e64 v164, v164, v166, s[8:9]
	v_sqrt_f32_e32 v166, v164
	v_add_u32_e32 v170, 1, v167
	v_fma_f32 v171, -v169, v167, v163
	v_pk_add_f32 v[152:153], v[172:173], v[176:177]
	v_fma_f32 v172, -v170, v167, v163
	v_add_u32_e32 v173, -1, v168
	v_cmp_ge_f32_e64 s[10:11], 0, v171
	v_pk_add_f32 v[154:155], v[174:175], v[184:185]
	v_add_u32_e32 v174, 1, v168
	v_cndmask_b32_e64 v167, v167, v169, s[10:11]
	v_fma_f32 v169, -v173, v168, v165
	v_cmp_lt_f32_e64 s[10:11], 0, v172
	v_fma_f32 v171, -v174, v168, v165
	v_add_u32_e32 v175, -1, v166
	v_cndmask_b32_e64 v167, v167, v170, s[10:11]
	v_cmp_ge_f32_e64 s[10:11], 0, v169
	v_add_u32_e32 v176, 1, v166
	v_fma_f32 v169, -v175, v166, v164
	v_cndmask_b32_e64 v168, v168, v173, s[10:11]
	v_cmp_lt_f32_e64 s[10:11], 0, v171
	v_fma_f32 v170, -v176, v166, v164
	v_mul_f32_e32 v171, 0x37800000, v167
	v_cndmask_b32_e64 v168, v168, v174, s[10:11]
	v_cmp_ge_f32_e64 s[10:11], 0, v169
	v_cndmask_b32_e32 v167, v167, v171, vcc
	v_cmp_class_f32_e32 vcc, v163, v162
	v_cndmask_b32_e64 v166, v166, v175, s[10:11]
	v_cmp_lt_f32_e64 s[10:11], 0, v170
	v_mul_f32_e32 v169, 0x37800000, v168
	v_cndmask_b32_e32 v163, v167, v163, vcc
	v_cndmask_b32_e64 v166, v166, v176, s[10:11]
	v_cndmask_b32_e64 v167, v168, v169, s[6:7]
	v_cmp_class_f32_e32 vcc, v165, v162
	v_mul_f32_e32 v168, 0x37800000, v166
	v_div_scale_f32 v169, s[6:7], v163, v163, 1.0
	v_cndmask_b32_e32 v165, v167, v165, vcc
	v_cndmask_b32_e64 v166, v166, v168, s[8:9]
	v_cmp_class_f32_e32 vcc, v164, v162
	v_rcp_f32_e32 v167, v169
	v_div_scale_f32 v168, s[8:9], v165, v165, 1.0
	v_cndmask_b32_e32 v166, v166, v164, vcc
	v_rcp_f32_e32 v172, v168
	v_div_scale_f32 v173, s[10:11], v166, v166, 1.0
	v_rcp_f32_e32 v175, v173
	v_fma_f32 v164, -v169, v167, 1.0
	v_div_scale_f32 v170, s[6:7], 1.0, v163, 1.0
	v_fmac_f32_e32 v167, v164, v167
	v_fma_f32 v164, -v168, v172, 1.0
	v_mul_f32_e32 v176, v170, v167
	v_div_scale_f32 v171, s[8:9], 1.0, v165, 1.0
	v_fmac_f32_e32 v172, v164, v172
	v_fma_f32 v164, -v173, v175, 1.0
	v_fma_f32 v177, -v169, v176, v170
	v_div_scale_f32 v174, s[10:11], 1.0, v166, 1.0
	v_mul_f32_e32 v178, v171, v172
	v_fmac_f32_e32 v175, v164, v175
	v_fmac_f32_e32 v176, v177, v167
	v_fma_f32 v164, -v168, v178, v171
	v_mul_f32_e32 v177, v174, v175
	v_fma_f32 v169, -v169, v176, v170
	s_mov_b64 vcc, s[6:7]
	v_fmac_f32_e32 v178, v164, v172
	v_fma_f32 v164, -v173, v177, v174
	v_div_fmas_f32 v167, v169, v167, v176
	v_fma_f32 v168, -v168, v178, v171
	v_fmac_f32_e32 v177, v164, v175
	v_div_fixup_f32 v164, v167, v163, 1.0
	s_mov_b64 vcc, s[8:9]
	v_div_fmas_f32 v163, v168, v172, v178
	v_fma_f32 v167, -v173, v177, v174
	v_pk_mul_f32 v[80:81], v[80:81], v[164:165] op_sel_hi:[1,0]
	v_pk_mul_f32 v[78:79], v[78:79], v[164:165] op_sel_hi:[1,0]
	s_mov_b64 vcc, s[10:11]
	v_pk_add_f32 v[88:89], v[88:89], 1.0 op_sel_hi:[1,0]
	v_pk_add_f32 v[86:87], v[86:87], 1.0 op_sel_hi:[1,0]
	v_pk_mul_f32 v[76:77], v[76:77], v[164:165] op_sel_hi:[1,0]
	v_pk_mul_f32 v[74:75], v[74:75], v[164:165] op_sel_hi:[1,0]
	v_pk_mul_f32 v[72:73], v[72:73], v[164:165] op_sel_hi:[1,0]
	v_pk_mul_f32 v[70:71], v[70:71], v[164:165] op_sel_hi:[1,0]
	v_pk_mul_f32 v[68:69], v[68:69], v[164:165] op_sel_hi:[1,0]
	v_pk_mul_f32 v[66:67], v[66:67], v[164:165] op_sel_hi:[1,0]
	v_div_fixup_f32 v164, v163, v165, 1.0
	v_div_fmas_f32 v163, v167, v175, v177
	v_pk_mul_f32 v[78:79], v[78:79], v[2:3]
	v_pk_mul_f32 v[80:81], v[80:81], v[4:5]
	v_pk_mul_f32 v[64:65], v[64:65], v[164:165] op_sel_hi:[1,0]
	v_pk_mul_f32 v[62:63], v[62:63], v[164:165] op_sel_hi:[1,0]
	v_pk_mul_f32 v[60:61], v[60:61], v[164:165] op_sel_hi:[1,0]
	v_pk_mul_f32 v[58:59], v[58:59], v[164:165] op_sel_hi:[1,0]
	v_pk_mul_f32 v[56:57], v[56:57], v[164:165] op_sel_hi:[1,0]
	v_pk_mul_f32 v[54:55], v[54:55], v[164:165] op_sel_hi:[1,0]
	v_pk_mul_f32 v[52:53], v[52:53], v[164:165] op_sel_hi:[1,0]
	v_pk_mul_f32 v[50:51], v[50:51], v[164:165] op_sel_hi:[1,0]
	v_div_fixup_f32 v164, v163, v166, 1.0
	v_pk_fma_f32 v[80:81], v[80:81], v[88:89], v[84:85]
	v_pk_fma_f32 v[78:79], v[78:79], v[86:87], v[82:83]
	v_pk_mul_f32 v[82:83], v[50:51], v[14:15]
	v_pk_mul_f32 v[84:85], v[52:53], v[16:17]
	v_pk_mul_f32 v[48:49], v[48:49], v[164:165] op_sel_hi:[1,0]
	v_pk_mul_f32 v[46:47], v[46:47], v[164:165] op_sel_hi:[1,0]
	v_pk_mul_f32 v[86:87], v[46:47], v[2:3]
	v_pk_mul_f32 v[88:89], v[48:49], v[4:5]
	v_cvt_pk_bf16_f32 v46, v78, v79
	v_cvt_pk_bf16_f32 v47, v80, v81
	global_store_dwordx2 v[102:103], v[46:47], off
	global_load_dwordx4 v[46:49], v[142:143], off
	s_nop 0
	global_load_dwordx4 v[50:53], v[122:123], off offset:1024
	v_pk_mul_f32 v[74:75], v[74:75], v[6:7]
	v_pk_mul_f32 v[76:77], v[76:77], v[8:9]
	v_pk_mul_f32 v[70:71], v[70:71], v[10:11]
	v_pk_mul_f32 v[72:73], v[72:73], v[12:13]
	v_pk_mul_f32 v[66:67], v[66:67], v[14:15]
	v_pk_mul_f32 v[68:69], v[68:69], v[16:17]
	v_pk_mul_f32 v[62:63], v[62:63], v[2:3]
	v_pk_mul_f32 v[64:65], v[64:65], v[4:5]
	v_pk_mul_f32 v[58:59], v[58:59], v[6:7]
	v_pk_mul_f32 v[60:61], v[60:61], v[8:9]
	v_pk_mul_f32 v[54:55], v[54:55], v[10:11]
	v_pk_mul_f32 v[56:57], v[56:57], v[12:13]
	v_pk_mul_f32 v[44:45], v[44:45], v[164:165] op_sel_hi:[1,0]
	v_pk_mul_f32 v[42:43], v[42:43], v[164:165] op_sel_hi:[1,0]
	v_pk_mul_f32 v[44:45], v[44:45], v[8:9]
	v_pk_mul_f32 v[42:43], v[42:43], v[6:7]
	v_pk_mul_f32 v[40:41], v[40:41], v[164:165] op_sel_hi:[1,0]
	v_pk_mul_f32 v[38:39], v[38:39], v[164:165] op_sel_hi:[1,0]
	v_pk_mul_f32 v[40:41], v[40:41], v[12:13]
	v_pk_mul_f32 v[38:39], v[38:39], v[10:11]
	v_pk_mul_f32 v[36:37], v[36:37], v[164:165] op_sel_hi:[1,0]
	v_pk_mul_f32 v[34:35], v[34:35], v[164:165] op_sel_hi:[1,0]
	v_pk_mul_f32 v[36:37], v[36:37], v[16:17]
	v_pk_mul_f32 v[34:35], v[34:35], v[14:15]
	v_mul_f32_e32 v186, v23, v23
	v_mul_f32_e32 v192, v25, v25
	v_mul_f32_e32 v203, v18, v18
	v_mul_f32_e32 v204, v19, v19
	v_mul_f32_e32 v205, v20, v20
	v_mul_f32_e32 v206, v21, v21
	v_pk_fma_f32 v[148:149], v[22:23], v[22:23], v[186:187] op_sel_hi:[1,1,0]
	v_pk_fma_f32 v[150:151], v[24:25], v[24:25], v[192:193] op_sel_hi:[1,1,0]
	v_mov_b32_e32 v149, v205
	v_mov_b32_e32 v151, v206
	s_waitcnt vmcnt(0) lgkmcnt(0)
	v_pk_add_f32 v[48:49], v[48:49], 1.0 op_sel_hi:[1,0]
	v_pk_add_f32 v[46:47], v[46:47], 1.0 op_sel_hi:[1,0]
	v_pk_fma_f32 v[48:49], v[76:77], v[48:49], v[52:53]
	v_pk_fma_f32 v[46:47], v[74:75], v[46:47], v[50:51]
	v_cvt_pk_bf16_f32 v46, v46, v47
	v_cvt_pk_bf16_f32 v47, v48, v49
	global_store_dwordx2 v[102:103], v[46:47], off offset:512
	global_load_dwordx4 v[46:49], v[138:139], off
	s_nop 0
	global_load_dwordx4 v[50:53], v[122:123], off offset:2048
	s_waitcnt vmcnt(0) lgkmcnt(0)
	v_pk_add_f32 v[48:49], v[48:49], 1.0 op_sel_hi:[1,0]
	v_pk_add_f32 v[46:47], v[46:47], 1.0 op_sel_hi:[1,0]
	v_pk_fma_f32 v[48:49], v[72:73], v[48:49], v[52:53]
	v_pk_fma_f32 v[46:47], v[70:71], v[46:47], v[50:51]
	v_cvt_pk_bf16_f32 v46, v46, v47
	v_cvt_pk_bf16_f32 v47, v48, v49
	global_store_dwordx2 v[102:103], v[46:47], off offset:1024
	global_load_dwordx4 v[46:49], v[128:129], off
	s_nop 0
	global_load_dwordx4 v[50:53], v[122:123], off offset:3072
	s_waitcnt vmcnt(0) lgkmcnt(0)
	v_pk_add_f32 v[48:49], v[48:49], 1.0 op_sel_hi:[1,0]
	v_pk_add_f32 v[46:47], v[46:47], 1.0 op_sel_hi:[1,0]
	v_pk_fma_f32 v[48:49], v[68:69], v[48:49], v[52:53]
	v_pk_fma_f32 v[46:47], v[66:67], v[46:47], v[50:51]
	v_cvt_pk_bf16_f32 v46, v46, v47
	v_cvt_pk_bf16_f32 v47, v48, v49
	global_store_dwordx2 v[102:103], v[46:47], off offset:1536
	global_load_dwordx4 v[46:49], v[124:125], off
	s_nop 0
	global_load_dwordx4 v[50:53], v[110:111], off
	s_waitcnt vmcnt(0) lgkmcnt(0)
	v_pk_add_f32 v[48:49], v[48:49], 1.0 op_sel_hi:[1,0]
	v_pk_add_f32 v[46:47], v[46:47], 1.0 op_sel_hi:[1,0]
	v_pk_fma_f32 v[48:49], v[64:65], v[48:49], v[52:53]
	v_pk_fma_f32 v[46:47], v[62:63], v[46:47], v[50:51]
	v_cvt_pk_bf16_f32 v46, v46, v47
	v_cvt_pk_bf16_f32 v47, v48, v49
	global_store_dwordx2 v[102:103], v[46:47], off offset:2048
	global_load_dwordx4 v[46:49], v[118:119], off
	s_nop 0
	global_load_dwordx4 v[50:53], v[110:111], off offset:1024
	s_waitcnt vmcnt(0) lgkmcnt(0)
	v_pk_add_f32 v[48:49], v[48:49], 1.0 op_sel_hi:[1,0]
	v_pk_add_f32 v[46:47], v[46:47], 1.0 op_sel_hi:[1,0]
	v_pk_fma_f32 v[48:49], v[60:61], v[48:49], v[52:53]
	v_pk_fma_f32 v[46:47], v[58:59], v[46:47], v[50:51]
	v_cvt_pk_bf16_f32 v46, v46, v47
	v_cvt_pk_bf16_f32 v47, v48, v49
	global_store_dwordx2 v[102:103], v[46:47], off offset:2560
	global_load_dwordx4 v[46:49], v[114:115], off
	s_nop 0
	global_load_dwordx4 v[50:53], v[110:111], off offset:2048
	v_pk_add_f32 v[58:59], v[148:149], v[150:151]
	s_waitcnt vmcnt(0) lgkmcnt(0)
	v_pk_add_f32 v[48:49], v[48:49], 1.0 op_sel_hi:[1,0]
	v_pk_add_f32 v[46:47], v[46:47], 1.0 op_sel_hi:[1,0]
	v_pk_fma_f32 v[48:49], v[56:57], v[48:49], v[52:53]
	v_pk_fma_f32 v[46:47], v[54:55], v[46:47], v[50:51]
	v_cvt_pk_bf16_f32 v46, v46, v47
	v_cvt_pk_bf16_f32 v47, v48, v49
	global_store_dwordx2 v[102:103], v[46:47], off offset:3072
	global_load_dwordx4 v[46:49], v[112:113], off
	s_nop 0
	global_load_dwordx4 v[50:53], v[110:111], off offset:3072
	v_pk_add_f32 v[54:55], v[152:153], v[152:153] op_sel:[0,1] op_sel_hi:[1,0]
	v_pk_add_f32 v[56:57], v[154:155], v[154:155] op_sel:[0,1] op_sel_hi:[1,0]
	v_mov_b32_e32 v55, v203
	v_mov_b32_e32 v57, v204
	s_waitcnt vmcnt(0) lgkmcnt(0)
	v_pk_add_f32 v[48:49], v[48:49], 1.0 op_sel_hi:[1,0]
	v_pk_add_f32 v[46:47], v[46:47], 1.0 op_sel_hi:[1,0]
	v_pk_fma_f32 v[48:49], v[84:85], v[48:49], v[52:53]
	v_pk_fma_f32 v[46:47], v[82:83], v[46:47], v[50:51]
	v_cvt_pk_bf16_f32 v46, v46, v47
	v_cvt_pk_bf16_f32 v47, v48, v49
	global_store_dwordx2 v[102:103], v[46:47], off offset:3584
	global_load_dwordx4 v[46:49], v[146:147], off
	s_nop 0
	global_load_dwordx4 v[50:53], v[108:109], off
	s_waitcnt vmcnt(0) lgkmcnt(0)
	v_pk_add_f32 v[48:49], v[48:49], 1.0 op_sel_hi:[1,0]
	v_pk_add_f32 v[46:47], v[46:47], 1.0 op_sel_hi:[1,0]
	v_pk_fma_f32 v[48:49], v[88:89], v[48:49], v[52:53]
	v_pk_fma_f32 v[46:47], v[86:87], v[46:47], v[50:51]
	v_cvt_pk_bf16_f32 v46, v46, v47
	v_cvt_pk_bf16_f32 v47, v48, v49
	global_store_dwordx2 v[104:105], v[46:47], off
	global_load_dwordx4 v[46:49], v[144:145], off
	s_nop 0
	global_load_dwordx4 v[50:53], v[108:109], off offset:1024
	s_waitcnt vmcnt(0) lgkmcnt(0)
	v_pk_add_f32 v[48:49], v[48:49], 1.0 op_sel_hi:[1,0]
	v_pk_add_f32 v[46:47], v[46:47], 1.0 op_sel_hi:[1,0]
	v_pk_fma_f32 v[44:45], v[44:45], v[48:49], v[52:53]
	v_pk_fma_f32 v[42:43], v[42:43], v[46:47], v[50:51]
	v_cvt_pk_bf16_f32 v42, v42, v43
	v_cvt_pk_bf16_f32 v43, v44, v45
	global_store_dwordx2 v[104:105], v[42:43], off offset:512
	global_load_dwordx4 v[42:45], v[140:141], off
	s_nop 0
	global_load_dwordx4 v[46:49], v[108:109], off offset:2048
	v_pk_add_f32 v[50:51], v[54:55], v[56:57]
	s_waitcnt vmcnt(0) lgkmcnt(0)
	v_pk_add_f32 v[44:45], v[44:45], 1.0 op_sel_hi:[1,0]
	v_pk_add_f32 v[42:43], v[42:43], 1.0 op_sel_hi:[1,0]
	v_pk_fma_f32 v[40:41], v[40:41], v[44:45], v[48:49]
	v_pk_fma_f32 v[38:39], v[38:39], v[42:43], v[46:47]
	v_cvt_pk_bf16_f32 v38, v38, v39
	v_cvt_pk_bf16_f32 v39, v40, v41
	global_store_dwordx2 v[104:105], v[38:39], off offset:1024
	global_load_dwordx4 v[38:41], v[126:127], off
	s_nop 0
	global_load_dwordx4 v[42:45], v[108:109], off offset:3072
	v_pk_add_f32 v[50:51], v[50:51], v[58:59]
	s_waitcnt vmcnt(0) lgkmcnt(0)
	v_pk_add_f32 v[40:41], v[40:41], 1.0 op_sel_hi:[1,0]
	v_pk_add_f32 v[38:39], v[38:39], 1.0 op_sel_hi:[1,0]
	v_pk_fma_f32 v[36:37], v[36:37], v[40:41], v[44:45]
	v_pk_fma_f32 v[34:35], v[34:35], v[38:39], v[42:43]
	v_cvt_pk_bf16_f32 v34, v34, v35
	v_cvt_pk_bf16_f32 v35, v36, v37
	global_store_dwordx2 v[104:105], v[34:35], off offset:1536
	global_load_dwordx4 v[34:37], v[120:121], off
	s_nop 0
	global_load_dwordx4 v[38:41], v[106:107], off
	v_add_f32_e32 v50, v50, v51
	ds_bpermute_b32 v51, v133, v50
	s_waitcnt lgkmcnt(0)
	v_add_f32_e32 v50, v50, v51
	ds_bpermute_b32 v51, v156, v50
	s_waitcnt lgkmcnt(0)
	v_add_f32_e32 v50, v50, v51
	ds_bpermute_b32 v46, v157, v50
	s_waitcnt lgkmcnt(0)
	v_add_f32_e32 v46, v50, v46
	ds_bpermute_b32 v47, v158, v46
	s_waitcnt lgkmcnt(0)
	v_add_f32_e32 v46, v46, v47
	ds_bpermute_b32 v47, v159, v46
	s_waitcnt lgkmcnt(0)
	v_add_f32_e32 v46, v46, v47
	ds_bpermute_b32 v47, v160, v46
	s_waitcnt lgkmcnt(0)
	v_add_f32_e32 v46, v46, v47
	v_fmamk_f32 v46, v46, 0x3a800000, v161
	v_mul_f32_e32 v47, 0x4f800000, v46
	v_cmp_gt_f32_e32 vcc, s19, v46
	s_waitcnt vmcnt(0)
	v_pk_add_f32 v[36:37], v[36:37], 1.0 op_sel_hi:[1,0]
	v_cndmask_b32_e32 v42, v46, v47, vcc
	v_sqrt_f32_e32 v43, v42
	v_pk_add_f32 v[34:35], v[34:35], 1.0 op_sel_hi:[1,0]
	v_add_u32_e32 v44, -1, v43
	v_add_u32_e32 v45, 1, v43
	v_fma_f32 v46, -v44, v43, v42
	v_fma_f32 v47, -v45, v43, v42
	v_cmp_ge_f32_e64 s[6:7], 0, v46
	s_nop 1
	v_cndmask_b32_e64 v43, v43, v44, s[6:7]
	v_cmp_lt_f32_e64 s[6:7], 0, v47
	s_nop 1
	v_cndmask_b32_e64 v43, v43, v45, s[6:7]
	v_mul_f32_e32 v44, 0x37800000, v43
	v_cndmask_b32_e32 v43, v43, v44, vcc
	v_cmp_class_f32_e32 vcc, v42, v162
	s_nop 1
	v_cndmask_b32_e32 v42, v43, v42, vcc
	v_div_scale_f32 v43, s[6:7], v42, v42, 1.0
	v_rcp_f32_e32 v45, v43
	v_div_scale_f32 v44, vcc, 1.0, v42, 1.0
	v_fma_f32 v46, -v43, v45, 1.0
	v_fmac_f32_e32 v45, v46, v45
	v_mul_f32_e32 v46, v44, v45
	v_fma_f32 v47, -v43, v46, v44
	v_fmac_f32_e32 v46, v47, v45
	v_fma_f32 v43, -v43, v46, v44
	v_div_fmas_f32 v43, v43, v45, v46
	v_div_fixup_f32 v42, v43, v42, 1.0
	v_pk_mul_f32 v[32:33], v[32:33], v[42:43] op_sel_hi:[1,0]
	v_pk_mul_f32 v[30:31], v[30:31], v[42:43] op_sel_hi:[1,0]
	v_pk_mul_f32 v[32:33], v[32:33], v[4:5]
	v_pk_mul_f32 v[30:31], v[30:31], v[2:3]
	v_pk_fma_f32 v[32:33], v[32:33], v[36:37], v[40:41]
	v_pk_fma_f32 v[30:31], v[30:31], v[34:35], v[38:39]
	v_cvt_pk_bf16_f32 v30, v30, v31
	v_cvt_pk_bf16_f32 v31, v32, v33
	global_store_dwordx2 v[104:105], v[30:31], off offset:2048
	global_load_dwordx4 v[30:33], v[116:117], off
	s_nop 0
	global_load_dwordx4 v[34:37], v[106:107], off offset:1024
	v_pk_mul_f32 v[28:29], v[28:29], v[42:43] op_sel_hi:[1,0]
	v_pk_mul_f32 v[26:27], v[26:27], v[42:43] op_sel_hi:[1,0]
	v_pk_mul_f32 v[28:29], v[28:29], v[8:9]
	v_pk_mul_f32 v[26:27], v[26:27], v[6:7]
	v_lshl_add_u64 v[38:39], s[24:25], 0, v[98:99]
	v_pk_mul_f32 v[24:25], v[24:25], v[42:43] op_sel_hi:[1,0]
	v_pk_mul_f32 v[22:23], v[22:23], v[42:43] op_sel_hi:[1,0]
	v_pk_mul_f32 v[24:25], v[24:25], v[12:13]
	v_pk_mul_f32 v[22:23], v[22:23], v[10:11]
	v_pk_mul_f32 v[20:21], v[20:21], v[42:43] op_sel_hi:[1,0]
	v_pk_mul_f32 v[18:19], v[18:19], v[42:43] op_sel_hi:[1,0]
	v_pk_mul_f32 v[20:21], v[20:21], v[16:17]
	v_pk_mul_f32 v[18:19], v[18:19], v[14:15]
	s_waitcnt vmcnt(0) lgkmcnt(0)
	v_pk_add_f32 v[32:33], v[32:33], 1.0 op_sel_hi:[1,0]
	v_pk_add_f32 v[30:31], v[30:31], 1.0 op_sel_hi:[1,0]
	v_pk_fma_f32 v[28:29], v[28:29], v[32:33], v[36:37]
	v_pk_fma_f32 v[26:27], v[26:27], v[30:31], v[34:35]
	v_cvt_pk_bf16_f32 v26, v26, v27
	v_cvt_pk_bf16_f32 v27, v28, v29
	global_store_dwordx2 v[104:105], v[26:27], off offset:2560
	global_load_dwordx4 v[26:29], v[38:39], off
	s_nop 0
	global_load_dwordx4 v[30:33], v[106:107], off offset:2048
	v_lshl_add_u64 v[34:35], s[24:25], 0, v[100:101]
	s_waitcnt vmcnt(0) lgkmcnt(0)
	v_pk_add_f32 v[28:29], v[28:29], 1.0 op_sel_hi:[1,0]
	v_pk_add_f32 v[26:27], v[26:27], 1.0 op_sel_hi:[1,0]
	v_pk_fma_f32 v[24:25], v[24:25], v[28:29], v[32:33]
	v_pk_fma_f32 v[22:23], v[22:23], v[26:27], v[30:31]
	v_cvt_pk_bf16_f32 v22, v22, v23
	v_cvt_pk_bf16_f32 v23, v24, v25
	global_store_dwordx2 v[104:105], v[22:23], off offset:3072
	global_load_dwordx4 v[22:25], v[34:35], off
	s_nop 0
	global_load_dwordx4 v[26:29], v[106:107], off offset:3072
	s_waitcnt vmcnt(0) lgkmcnt(0)
	v_pk_add_f32 v[24:25], v[24:25], 1.0 op_sel_hi:[1,0]
	v_pk_add_f32 v[22:23], v[22:23], 1.0 op_sel_hi:[1,0]
	v_pk_fma_f32 v[20:21], v[20:21], v[24:25], v[28:29]
	v_pk_fma_f32 v[18:19], v[18:19], v[22:23], v[26:27]
	v_cvt_pk_bf16_f32 v18, v18, v19
	v_cvt_pk_bf16_f32 v19, v20, v21
	global_store_dwordx2 v[104:105], v[18:19], off offset:3584
	s_cbranch_scc1 .LBB0_842

.LBB0_1004:
	v_lshl_add_u64 v[18:19], s[38:39], 0, v[94:95]
	v_lshl_add_u64 v[22:23], s[38:39], 0, v[92:93]
	v_add_co_u32_e32 v20, vcc, 0x7800000, v18
	v_add_co_u32_e64 v102, s[6:7], s24, v22
	s_nop 0
	v_addc_co_u32_e32 v21, vcc, 0, v19, vcc
	v_addc_co_u32_e64 v103, s[6:7], 0, v23, s[6:7]
	v_add_co_u32_e64 v104, s[6:7], s25, v22
	v_add_co_u32_e32 v22, vcc, 0x7801000, v18
	s_nop 0
	v_addc_co_u32_e64 v105, s[6:7], 0, v23, s[6:7]
	global_load_dwordx4 v[78:81], v[20:21], off
	global_load_dwordx4 v[74:77], v[20:21], off offset:1024
	global_load_dwordx4 v[70:73], v[20:21], off offset:2048
	global_load_dwordx4 v[66:69], v[20:21], off offset:3072
	v_addc_co_u32_e32 v23, vcc, 0, v19, vcc
	v_add_co_u32_e32 v20, vcc, 0x7802000, v18
	global_load_dwordx4 v[62:65], v[22:23], off
	global_load_dwordx4 v[58:61], v[22:23], off offset:1024
	global_load_dwordx4 v[54:57], v[22:23], off offset:2048
	global_load_dwordx4 v[50:53], v[22:23], off offset:3072
	v_addc_co_u32_e32 v21, vcc, 0, v19, vcc
	global_load_dwordx4 v[46:49], v[20:21], off
	global_load_dwordx4 v[42:45], v[20:21], off offset:1024
	global_load_dwordx4 v[38:41], v[20:21], off offset:2048
	global_load_dwordx4 v[34:37], v[20:21], off offset:3072
	v_add_co_u32_e32 v82, vcc, 0x7803000, v18
	s_add_i32 s26, s8, 32
	s_nop 0
	v_addc_co_u32_e32 v83, vcc, 0, v19, vcc
	global_load_dwordx4 v[30:33], v[82:83], off
	global_load_dwordx4 v[26:29], v[82:83], off offset:1024
	global_load_dwordx4 v[22:25], v[82:83], off offset:2048
	global_load_dwordx4 v[18:21], v[82:83], off offset:3072
	s_add_i32 s10, s8, 0xffffc022
	s_ashr_i32 s9, s26, 13
	s_cmpk_lt_i32 s26, 0x4000
	s_cselect_b32 s6, s9, s10
	s_mul_hi_i32 s7, s6, 0x9000
	s_mul_i32 s6, s6, 0x9000
	s_add_u32 s6, s2, s6
	s_addc_u32 s7, s13, s7
	s_add_u32 s10, s6, 0x1000
	s_addc_u32 s11, s7, 0
	v_lshl_add_u64 v[124:125], s[6:7], 0, v[90:91]
	v_lshl_add_u64 v[86:87], s[10:11], 0, v[90:91]
	global_load_dwordx4 v[82:85], v[124:125], off
	s_add_i32 s6, s8, 0xffffc023
	global_load_dwordx4 v[86:89], v[86:87], off
	s_cmpk_lt_i32 s26, 0x3fff
	s_cselect_b32 s6, s9, s6
	s_mul_hi_i32 s7, s6, 0x9000
	s_mul_i32 s6, s6, 0x9000
	s_add_u32 s6, s2, s6
	s_addc_u32 s7, s13, s7
	v_lshl_add_u64 v[138:139], s[10:11], 0, v[96:97]
	v_lshl_add_u64 v[134:135], s[10:11], 0, v[98:99]
	v_lshl_add_u64 v[128:129], s[10:11], 0, v[100:101]
	s_add_u32 s10, s6, 0x1000
	v_lshl_add_u64 v[110:111], s[6:7], 0, v[90:91]
	s_addc_u32 s11, s7, 0
	s_add_i32 s6, s8, 0xffffc024
	s_cmpk_lt_i32 s26, 0x3ffe
	s_cselect_b32 s6, s9, s6
	s_mul_hi_i32 s7, s6, 0x9000
	s_mul_i32 s6, s6, 0x9000
	v_lshl_add_u64 v[126:127], s[10:11], 0, v[90:91]
	v_lshl_add_u64 v[120:121], s[10:11], 0, v[96:97]
	v_lshl_add_u64 v[116:117], s[10:11], 0, v[98:99]
	v_lshl_add_u64 v[112:113], s[10:11], 0, v[100:101]
	s_add_u32 s10, s2, s6
	s_addc_u32 s11, s13, s7
	s_add_u32 s6, s10, 0x1000
	s_addc_u32 s7, s11, 0
	s_addk_i32 s8, 0xc025
	s_cmpk_lt_i32 s26, 0x3ffd
	v_lshl_add_u64 v[142:143], s[6:7], 0, v[90:91]
	v_lshl_add_u64 v[140:141], s[6:7], 0, v[96:97]
	v_lshl_add_u64 v[136:137], s[6:7], 0, v[98:99]
	v_lshl_add_u64 v[122:123], s[6:7], 0, v[100:101]
	s_cselect_b32 s6, s9, s8
	s_mul_hi_i32 s7, s6, 0x9000
	s_mul_i32 s6, s6, 0x9000
	s_add_u32 s6, s2, s6
	s_addc_u32 s7, s13, s7
	s_add_u32 s20, s6, 0x1000
	v_lshl_add_u64 v[106:107], s[6:7], 0, v[90:91]
	s_addc_u32 s21, s7, 0
	v_lshl_add_u64 v[108:109], s[10:11], 0, v[90:91]
	v_lshl_add_u64 v[118:119], s[20:21], 0, v[90:91]
	v_lshl_add_u64 v[114:115], s[20:21], 0, v[96:97]
	v_lshl_add_u64 v[92:93], v[92:93], 0, s[16:17]
	v_lshl_add_u64 v[94:95], v[94:95], 0, s[18:19]
	s_cmp_lt_i32 s26, s22
	s_waitcnt vmcnt(0) lgkmcnt(0)
	v_pk_mul_f32 v[144:145], v[80:81], v[80:81]
	v_pk_mul_f32 v[146:147], v[78:79], v[78:79]
	v_pk_mul_f32 v[148:149], v[76:77], v[76:77]
	v_pk_mul_f32 v[150:151], v[74:75], v[74:75]
	v_mul_f32_e32 v158, v71, v71
	v_mul_f32_e32 v160, v73, v73
	v_pk_mov_b32 v[162:163], v[146:147], v[144:145] op_sel:[1,0]
	v_mov_b32_e32 v147, v145
	v_pk_mov_b32 v[144:145], v[150:151], v[148:149] op_sel:[1,0]
	v_mov_b32_e32 v151, v149
	v_mul_f32_e32 v171, v68, v68
	v_mul_f32_e32 v173, v69, v69
	v_pk_fma_f32 v[148:149], v[70:71], v[70:71], v[158:159] op_sel_hi:[1,1,0]
	v_pk_fma_f32 v[158:159], v[72:73], v[72:73], v[160:161] op_sel_hi:[1,1,0]
	v_pk_mul_f32 v[160:161], v[64:65], v[64:65]
	v_pk_mul_f32 v[164:165], v[62:63], v[62:63]
	v_pk_mul_f32 v[166:167], v[60:61], v[60:61]
	v_pk_mul_f32 v[168:169], v[58:59], v[58:59]
	v_mul_f32_e32 v170, v55, v55
	v_mul_f32_e32 v172, v57, v57
	v_pk_add_f32 v[146:147], v[162:163], v[146:147]
	v_pk_add_f32 v[144:145], v[144:145], v[150:151]
	v_mul_f32_e32 v157, v66, v66
	v_mul_f32_e32 v181, v67, v67
	v_mov_b32_e32 v149, v171
	v_mov_b32_e32 v159, v173
	v_pk_mov_b32 v[150:151], v[164:165], v[160:161] op_sel:[1,0]
	v_mov_b32_e32 v165, v161
	v_pk_mov_b32 v[160:161], v[168:169], v[166:167] op_sel:[1,0]
	v_mov_b32_e32 v169, v167
	v_pk_fma_f32 v[162:163], v[54:55], v[54:55], v[170:171] op_sel_hi:[1,1,0]
	v_pk_fma_f32 v[166:167], v[56:57], v[56:57], v[172:173] op_sel_hi:[1,1,0]
	v_pk_mul_f32 v[170:171], v[48:49], v[48:49]
	v_pk_mul_f32 v[172:173], v[46:47], v[46:47]
	v_pk_add_f32 v[182:183], v[146:147], v[146:147] op_sel:[0,1] op_sel_hi:[1,0]
	v_pk_add_f32 v[184:185], v[144:145], v[144:145] op_sel:[0,1] op_sel_hi:[1,0]
	v_mul_f32_e32 v179, v52, v52
	v_pk_mul_f32 v[174:175], v[44:45], v[44:45]
	v_pk_mul_f32 v[176:177], v[42:43], v[42:43]
	v_mul_f32_e32 v178, v39, v39
	v_mul_f32_e32 v180, v41, v41
	v_pk_add_f32 v[158:159], v[148:149], v[158:159]
	v_pk_add_f32 v[144:145], v[150:151], v[164:165]
	v_pk_add_f32 v[146:147], v[160:161], v[168:169]
	v_pk_mov_b32 v[148:149], v[172:173], v[170:171] op_sel:[1,0]
	v_mov_b32_e32 v173, v171
	v_mov_b32_e32 v183, v157
	v_mov_b32_e32 v185, v181
	v_mul_f32_e32 v187, v50, v50
	v_mul_f32_e32 v192, v51, v51
	v_mul_f32_e32 v186, v53, v53
	v_mul_f32_e32 v195, v36, v36
	v_mul_f32_e32 v196, v37, v37
	v_pk_mov_b32 v[150:151], v[176:177], v[174:175] op_sel:[1,0]
	v_mov_b32_e32 v177, v175
	v_pk_fma_f32 v[160:161], v[38:39], v[38:39], v[178:179] op_sel_hi:[1,1,0]
	v_pk_fma_f32 v[164:165], v[40:41], v[40:41], v[180:181] op_sel_hi:[1,1,0]
	v_pk_add_f32 v[188:189], v[144:145], v[144:145] op_sel:[0,1] op_sel_hi:[1,0]
	v_pk_add_f32 v[190:191], v[146:147], v[146:147] op_sel:[0,1] op_sel_hi:[1,0]
	v_pk_add_f32 v[148:149], v[148:149], v[172:173]
	v_pk_add_f32 v[172:173], v[182:183], v[184:185]
	v_mov_b32_e32 v163, v179
	v_mov_b32_e32 v167, v186
	v_pk_mul_f32 v[168:169], v[32:33], v[32:33]
	v_pk_mul_f32 v[170:171], v[30:31], v[30:31]
	v_pk_mul_f32 v[174:175], v[28:29], v[28:29]
	v_pk_mul_f32 v[178:179], v[26:27], v[26:27]
	v_pk_add_f32 v[150:151], v[150:151], v[176:177]
	v_mov_b32_e32 v161, v195
	v_mov_b32_e32 v165, v196
	v_mov_b32_e32 v189, v187
	v_mov_b32_e32 v191, v192
	v_pk_add_f32 v[158:159], v[172:173], v[158:159]
	v_mul_f32_e32 v193, v34, v34
	v_mul_f32_e32 v194, v35, v35
	v_pk_add_f32 v[162:163], v[162:163], v[166:167]
	v_pk_mov_b32 v[166:167], v[170:171], v[168:169] op_sel:[1,0]
	v_mov_b32_e32 v171, v169
	v_pk_mov_b32 v[168:169], v[178:179], v[174:175] op_sel:[1,0]
	v_mov_b32_e32 v179, v175
	v_pk_add_f32 v[174:175], v[148:149], v[148:149] op_sel:[0,1] op_sel_hi:[1,0]
	v_pk_add_f32 v[176:177], v[150:151], v[150:151] op_sel:[0,1] op_sel_hi:[1,0]
	v_pk_add_f32 v[160:161], v[160:161], v[164:165]
	v_pk_add_f32 v[164:165], v[188:189], v[190:191]
	v_add_f32_e32 v157, v158, v159
	v_mov_b32_e32 v175, v193
	v_mov_b32_e32 v177, v194
	v_pk_add_f32 v[158:159], v[164:165], v[162:163]
	ds_bpermute_b32 v165, v1, v157
	v_pk_add_f32 v[162:163], v[174:175], v[176:177]
	v_add_f32_e32 v164, v158, v159
	v_pk_add_f32 v[158:159], v[162:163], v[160:161]
	ds_bpermute_b32 v160, v1, v164
	v_add_f32_e32 v158, v158, v159
	ds_bpermute_b32 v159, v1, v158
	s_waitcnt lgkmcnt(2)
	v_add_f32_e32 v157, v157, v165
	ds_bpermute_b32 v161, v131, v157
	s_waitcnt lgkmcnt(2)
	v_add_f32_e32 v160, v164, v160
	ds_bpermute_b32 v162, v131, v160
	s_waitcnt lgkmcnt(2)
	v_add_f32_e32 v158, v158, v159
	ds_bpermute_b32 v159, v131, v158
	s_waitcnt lgkmcnt(2)
	v_add_f32_e32 v157, v157, v161
	ds_bpermute_b32 v161, v133, v157
	s_waitcnt lgkmcnt(2)
	v_add_f32_e32 v160, v160, v162
	ds_bpermute_b32 v162, v133, v160
	s_waitcnt lgkmcnt(2)
	v_add_f32_e32 v158, v158, v159
	ds_bpermute_b32 v159, v133, v158
	s_waitcnt lgkmcnt(2)
	v_add_f32_e32 v157, v157, v161
	ds_bpermute_b32 v161, v152, v157
	s_waitcnt lgkmcnt(2)
	v_add_f32_e32 v160, v160, v162
	ds_bpermute_b32 v162, v152, v160
	s_waitcnt lgkmcnt(2)
	v_add_f32_e32 v158, v158, v159
	ds_bpermute_b32 v159, v152, v158
	s_waitcnt lgkmcnt(2)
	v_add_f32_e32 v157, v157, v161
	ds_bpermute_b32 v161, v153, v157
	s_waitcnt lgkmcnt(2)
	v_add_f32_e32 v160, v160, v162
	ds_bpermute_b32 v162, v153, v160
	s_waitcnt lgkmcnt(2)
	v_add_f32_e32 v158, v158, v159
	ds_bpermute_b32 v159, v153, v158
	s_waitcnt lgkmcnt(2)
	v_add_f32_e32 v157, v157, v161
	ds_bpermute_b32 v161, v154, v157
	s_waitcnt lgkmcnt(2)
	v_add_f32_e32 v160, v160, v162
	ds_bpermute_b32 v162, v154, v160
	s_waitcnt lgkmcnt(2)
	v_add_f32_e32 v158, v158, v159
	ds_bpermute_b32 v159, v154, v158
	s_waitcnt lgkmcnt(2)
	v_add_f32_e32 v157, v157, v161
	v_fmamk_f32 v157, v157, 0x3a800000, v155
	s_waitcnt lgkmcnt(1)
	v_add_f32_e32 v160, v160, v162
	v_mul_f32_e32 v161, 0x4f800000, v157
	v_cmp_gt_f32_e32 vcc, s4, v157
	v_fmamk_f32 v160, v160, 0x3a800000, v155
	s_waitcnt lgkmcnt(0)
	v_add_f32_e32 v158, v158, v159
	v_cndmask_b32_e32 v157, v157, v161, vcc
	v_mul_f32_e32 v159, 0x4f800000, v160
	v_cmp_gt_f32_e64 s[6:7], s4, v160
	v_sqrt_f32_e32 v161, v157
	v_fmamk_f32 v158, v158, 0x3a800000, v155
	v_cndmask_b32_e64 v159, v160, v159, s[6:7]
	v_mul_f32_e32 v160, 0x4f800000, v158
	v_cmp_gt_f32_e64 s[8:9], s4, v158
	v_sqrt_f32_e32 v162, v159
	v_add_u32_e32 v163, -1, v161
	v_cndmask_b32_e64 v158, v158, v160, s[8:9]
	v_sqrt_f32_e32 v160, v158
	v_add_u32_e32 v164, 1, v161
	v_fma_f32 v165, -v163, v161, v157
	v_pk_add_f32 v[148:149], v[166:167], v[170:171]
	v_fma_f32 v166, -v164, v161, v157
	v_add_u32_e32 v167, -1, v162
	v_cmp_ge_f32_e64 s[10:11], 0, v165
	v_pk_add_f32 v[150:151], v[168:169], v[178:179]
	v_add_u32_e32 v168, 1, v162
	v_cndmask_b32_e64 v161, v161, v163, s[10:11]
	v_fma_f32 v163, -v167, v162, v159
	v_cmp_lt_f32_e64 s[10:11], 0, v166
	v_fma_f32 v165, -v168, v162, v159
	v_add_u32_e32 v169, -1, v160
	v_cndmask_b32_e64 v161, v161, v164, s[10:11]
	v_cmp_ge_f32_e64 s[10:11], 0, v163
	v_add_u32_e32 v170, 1, v160
	v_fma_f32 v163, -v169, v160, v158
	v_cndmask_b32_e64 v162, v162, v167, s[10:11]
	v_cmp_lt_f32_e64 s[10:11], 0, v165
	v_fma_f32 v164, -v170, v160, v158
	v_mul_f32_e32 v165, 0x37800000, v161
	v_cndmask_b32_e64 v162, v162, v168, s[10:11]
	v_cmp_ge_f32_e64 s[10:11], 0, v163
	v_cndmask_b32_e32 v161, v161, v165, vcc
	v_cmp_class_f32_e32 vcc, v157, v156
	v_cndmask_b32_e64 v160, v160, v169, s[10:11]
	v_cmp_lt_f32_e64 s[10:11], 0, v164
	v_mul_f32_e32 v163, 0x37800000, v162
	v_cndmask_b32_e32 v157, v161, v157, vcc
	v_cndmask_b32_e64 v160, v160, v170, s[10:11]
	v_cndmask_b32_e64 v161, v162, v163, s[6:7]
	v_cmp_class_f32_e32 vcc, v159, v156
	v_mul_f32_e32 v162, 0x37800000, v160
	v_div_scale_f32 v163, s[6:7], v157, v157, 1.0
	v_cndmask_b32_e32 v159, v161, v159, vcc
	v_cndmask_b32_e64 v160, v160, v162, s[8:9]
	v_cmp_class_f32_e32 vcc, v158, v156
	v_rcp_f32_e32 v161, v163
	v_div_scale_f32 v162, s[8:9], v159, v159, 1.0
	v_cndmask_b32_e32 v160, v160, v158, vcc
	v_rcp_f32_e32 v166, v162
	v_div_scale_f32 v167, s[10:11], v160, v160, 1.0
	v_rcp_f32_e32 v169, v167
	v_fma_f32 v158, -v163, v161, 1.0
	v_div_scale_f32 v164, s[6:7], 1.0, v157, 1.0
	v_fmac_f32_e32 v161, v158, v161
	v_fma_f32 v158, -v162, v166, 1.0
	v_mul_f32_e32 v170, v164, v161
	v_div_scale_f32 v165, s[8:9], 1.0, v159, 1.0
	v_fmac_f32_e32 v166, v158, v166
	v_fma_f32 v158, -v167, v169, 1.0
	v_fma_f32 v171, -v163, v170, v164
	v_div_scale_f32 v168, s[10:11], 1.0, v160, 1.0
	v_mul_f32_e32 v172, v165, v166
	v_fmac_f32_e32 v169, v158, v169
	v_fmac_f32_e32 v170, v171, v161
	v_fma_f32 v158, -v162, v172, v165
	v_mul_f32_e32 v171, v168, v169
	v_fma_f32 v163, -v163, v170, v164
	s_mov_b64 vcc, s[6:7]
	v_fmac_f32_e32 v172, v158, v166
	v_fma_f32 v158, -v167, v171, v168
	v_div_fmas_f32 v161, v163, v161, v170
	v_fma_f32 v162, -v162, v172, v165
	v_fmac_f32_e32 v171, v158, v169
	v_div_fixup_f32 v158, v161, v157, 1.0
	s_mov_b64 vcc, s[8:9]
	v_div_fmas_f32 v157, v162, v166, v172
	v_fma_f32 v161, -v167, v171, v168
	v_pk_mul_f32 v[80:81], v[80:81], v[158:159] op_sel_hi:[1,0]
	v_pk_mul_f32 v[78:79], v[78:79], v[158:159] op_sel_hi:[1,0]
	s_mov_b64 vcc, s[10:11]
	v_pk_add_f32 v[88:89], v[88:89], 1.0 op_sel_hi:[1,0]
	v_pk_add_f32 v[86:87], v[86:87], 1.0 op_sel_hi:[1,0]
	v_pk_mul_f32 v[76:77], v[76:77], v[158:159] op_sel_hi:[1,0]
	v_pk_mul_f32 v[74:75], v[74:75], v[158:159] op_sel_hi:[1,0]
	v_pk_mul_f32 v[72:73], v[72:73], v[158:159] op_sel_hi:[1,0]
	v_pk_mul_f32 v[70:71], v[70:71], v[158:159] op_sel_hi:[1,0]
	v_pk_mul_f32 v[68:69], v[68:69], v[158:159] op_sel_hi:[1,0]
	v_pk_mul_f32 v[66:67], v[66:67], v[158:159] op_sel_hi:[1,0]
	v_div_fixup_f32 v158, v157, v159, 1.0
	v_div_fmas_f32 v157, v161, v169, v171
	v_pk_mul_f32 v[78:79], v[78:79], v[2:3]
	v_pk_mul_f32 v[80:81], v[80:81], v[4:5]
	v_pk_mul_f32 v[64:65], v[64:65], v[158:159] op_sel_hi:[1,0]
	v_pk_mul_f32 v[62:63], v[62:63], v[158:159] op_sel_hi:[1,0]
	v_pk_mul_f32 v[60:61], v[60:61], v[158:159] op_sel_hi:[1,0]
	v_pk_mul_f32 v[58:59], v[58:59], v[158:159] op_sel_hi:[1,0]
	v_pk_mul_f32 v[56:57], v[56:57], v[158:159] op_sel_hi:[1,0]
	v_pk_mul_f32 v[54:55], v[54:55], v[158:159] op_sel_hi:[1,0]
	v_pk_mul_f32 v[52:53], v[52:53], v[158:159] op_sel_hi:[1,0]
	v_pk_mul_f32 v[158:159], v[50:51], v[158:159] op_sel_hi:[1,0]
	v_div_fixup_f32 v50, v157, v160, 1.0
	v_pk_fma_f32 v[80:81], v[80:81], v[88:89], v[84:85]
	v_pk_fma_f32 v[78:79], v[78:79], v[86:87], v[82:83]
	v_pk_mul_f32 v[86:87], v[52:53], v[16:17]
	v_pk_mul_f32 v[48:49], v[48:49], v[50:51] op_sel_hi:[1,0]
	v_pk_mul_f32 v[46:47], v[46:47], v[50:51] op_sel_hi:[1,0]
	v_pk_mul_f32 v[82:83], v[54:55], v[10:11]
	v_pk_mul_f32 v[84:85], v[158:159], v[14:15]
	v_pk_mul_f32 v[88:89], v[46:47], v[2:3]
	v_pk_mul_f32 v[158:159], v[48:49], v[4:5]
	v_cvt_pk_bf16_f32 v46, v78, v79
	v_cvt_pk_bf16_f32 v47, v80, v81
	global_store_dwordx2 v[102:103], v[46:47], off
	global_load_dwordx4 v[46:49], v[138:139], off
	s_nop 0
	global_load_dwordx4 v[52:55], v[124:125], off offset:1024
	v_pk_mul_f32 v[74:75], v[74:75], v[6:7]
	v_pk_mul_f32 v[76:77], v[76:77], v[8:9]
	v_pk_mul_f32 v[70:71], v[70:71], v[10:11]
	v_pk_mul_f32 v[72:73], v[72:73], v[12:13]
	v_pk_mul_f32 v[66:67], v[66:67], v[14:15]
	v_pk_mul_f32 v[68:69], v[68:69], v[16:17]
	v_pk_mul_f32 v[62:63], v[62:63], v[2:3]
	v_pk_mul_f32 v[64:65], v[64:65], v[4:5]
	v_pk_mul_f32 v[58:59], v[58:59], v[6:7]
	v_pk_mul_f32 v[60:61], v[60:61], v[8:9]
	v_pk_mul_f32 v[56:57], v[56:57], v[12:13]
	v_mul_f32_e32 v180, v23, v23
	v_mul_f32_e32 v186, v25, v25
	v_mul_f32_e32 v197, v18, v18
	v_mul_f32_e32 v198, v19, v19
	v_mul_f32_e32 v199, v20, v20
	v_mul_f32_e32 v200, v21, v21
	v_pk_fma_f32 v[144:145], v[22:23], v[22:23], v[180:181] op_sel_hi:[1,1,0]
	v_pk_fma_f32 v[146:147], v[24:25], v[24:25], v[186:187] op_sel_hi:[1,1,0]
	v_mov_b32_e32 v145, v199
	v_mov_b32_e32 v147, v200
	s_mov_b32 s8, s26
	s_waitcnt vmcnt(0) lgkmcnt(0)
	v_pk_add_f32 v[48:49], v[48:49], 1.0 op_sel_hi:[1,0]
	v_pk_add_f32 v[46:47], v[46:47], 1.0 op_sel_hi:[1,0]
	v_pk_fma_f32 v[48:49], v[76:77], v[48:49], v[54:55]
	v_pk_fma_f32 v[46:47], v[74:75], v[46:47], v[52:53]
	v_cvt_pk_bf16_f32 v46, v46, v47
	v_cvt_pk_bf16_f32 v47, v48, v49
	global_store_dwordx2 v[102:103], v[46:47], off offset:512
	global_load_dwordx4 v[46:49], v[134:135], off
	s_nop 0
	global_load_dwordx4 v[52:55], v[124:125], off offset:2048
	s_waitcnt vmcnt(0) lgkmcnt(0)
	v_pk_add_f32 v[48:49], v[48:49], 1.0 op_sel_hi:[1,0]
	v_pk_add_f32 v[46:47], v[46:47], 1.0 op_sel_hi:[1,0]
	v_pk_fma_f32 v[48:49], v[72:73], v[48:49], v[54:55]
	v_pk_fma_f32 v[46:47], v[70:71], v[46:47], v[52:53]
	v_cvt_pk_bf16_f32 v46, v46, v47
	v_cvt_pk_bf16_f32 v47, v48, v49
	global_store_dwordx2 v[102:103], v[46:47], off offset:1024
	global_load_dwordx4 v[46:49], v[128:129], off
	s_nop 0
	global_load_dwordx4 v[52:55], v[124:125], off offset:3072
	s_waitcnt vmcnt(0) lgkmcnt(0)
	v_pk_add_f32 v[48:49], v[48:49], 1.0 op_sel_hi:[1,0]
	v_pk_add_f32 v[46:47], v[46:47], 1.0 op_sel_hi:[1,0]
	v_pk_fma_f32 v[48:49], v[68:69], v[48:49], v[54:55]
	v_pk_fma_f32 v[46:47], v[66:67], v[46:47], v[52:53]
	v_cvt_pk_bf16_f32 v46, v46, v47
	v_cvt_pk_bf16_f32 v47, v48, v49
	global_store_dwordx2 v[102:103], v[46:47], off offset:1536
	global_load_dwordx4 v[46:49], v[126:127], off
	s_nop 0
	global_load_dwordx4 v[52:55], v[110:111], off
	s_waitcnt vmcnt(0) lgkmcnt(0)
	v_pk_add_f32 v[48:49], v[48:49], 1.0 op_sel_hi:[1,0]
	v_pk_add_f32 v[46:47], v[46:47], 1.0 op_sel_hi:[1,0]
	v_pk_fma_f32 v[48:49], v[64:65], v[48:49], v[54:55]
	v_pk_fma_f32 v[46:47], v[62:63], v[46:47], v[52:53]
	v_cvt_pk_bf16_f32 v46, v46, v47
	v_cvt_pk_bf16_f32 v47, v48, v49
	global_store_dwordx2 v[102:103], v[46:47], off offset:2048
	global_load_dwordx4 v[46:49], v[120:121], off
	s_nop 0
	global_load_dwordx4 v[52:55], v[110:111], off offset:1024
	s_waitcnt vmcnt(0) lgkmcnt(0)
	v_pk_add_f32 v[48:49], v[48:49], 1.0 op_sel_hi:[1,0]
	v_pk_add_f32 v[46:47], v[46:47], 1.0 op_sel_hi:[1,0]
	v_pk_fma_f32 v[48:49], v[60:61], v[48:49], v[54:55]
	v_pk_fma_f32 v[46:47], v[58:59], v[46:47], v[52:53]
	v_cvt_pk_bf16_f32 v46, v46, v47
	v_cvt_pk_bf16_f32 v47, v48, v49
	global_store_dwordx2 v[102:103], v[46:47], off offset:2560
	global_load_dwordx4 v[46:49], v[116:117], off
	s_nop 0
	global_load_dwordx4 v[52:55], v[110:111], off offset:2048
	v_pk_add_f32 v[58:59], v[150:151], v[150:151] op_sel:[0,1] op_sel_hi:[1,0]
	v_pk_add_f32 v[60:61], v[144:145], v[146:147]
	v_mov_b32_e32 v59, v198
	s_waitcnt vmcnt(0) lgkmcnt(0)
	v_pk_add_f32 v[48:49], v[48:49], 1.0 op_sel_hi:[1,0]
	v_pk_add_f32 v[46:47], v[46:47], 1.0 op_sel_hi:[1,0]
	v_pk_fma_f32 v[48:49], v[56:57], v[48:49], v[54:55]
	v_pk_fma_f32 v[46:47], v[82:83], v[46:47], v[52:53]
	v_cvt_pk_bf16_f32 v46, v46, v47
	v_cvt_pk_bf16_f32 v47, v48, v49
	global_store_dwordx2 v[102:103], v[46:47], off offset:3072
	global_load_dwordx4 v[46:49], v[112:113], off
	s_nop 0
	global_load_dwordx4 v[52:55], v[110:111], off offset:3072
	v_pk_add_f32 v[56:57], v[148:149], v[148:149] op_sel:[0,1] op_sel_hi:[1,0]
	s_waitcnt vmcnt(0) lgkmcnt(0)
	v_pk_add_f32 v[48:49], v[48:49], 1.0 op_sel_hi:[1,0]
	v_pk_add_f32 v[46:47], v[46:47], 1.0 op_sel_hi:[1,0]
	v_pk_fma_f32 v[48:49], v[86:87], v[48:49], v[54:55]
	v_pk_fma_f32 v[46:47], v[84:85], v[46:47], v[52:53]
	v_cvt_pk_bf16_f32 v46, v46, v47
	v_cvt_pk_bf16_f32 v47, v48, v49
	global_store_dwordx2 v[102:103], v[46:47], off offset:3584
	global_load_dwordx4 v[46:49], v[142:143], off
	s_nop 0
	global_load_dwordx4 v[52:55], v[108:109], off
	v_mov_b32_e32 v57, v197
	s_waitcnt vmcnt(0) lgkmcnt(0)
	v_pk_add_f32 v[48:49], v[48:49], 1.0 op_sel_hi:[1,0]
	v_pk_add_f32 v[46:47], v[46:47], 1.0 op_sel_hi:[1,0]
	v_pk_fma_f32 v[48:49], v[158:159], v[48:49], v[54:55]
	v_pk_fma_f32 v[46:47], v[88:89], v[46:47], v[52:53]
	v_bfe_u32 v51, v46, 16, 1
	v_bfe_u32 v52, v47, 16, 1
	v_add3_u32 v46, v46, v51, s5
	v_add3_u32 v47, v47, v52, s5
	v_lshrrev_b32_e32 v46, 16, v46
	v_and_or_b32 v46, v47, s23, v46
	v_cvt_pk_bf16_f32 v47, v48, v49
	global_store_dwordx2 v[104:105], v[46:47], off
	global_load_dwordx4 v[46:49], v[140:141], off
	s_nop 0
	global_load_dwordx4 v[52:55], v[108:109], off offset:1024
	v_pk_mul_f32 v[44:45], v[44:45], v[50:51] op_sel_hi:[1,0]
	v_pk_mul_f32 v[42:43], v[42:43], v[50:51] op_sel_hi:[1,0]
	v_pk_mul_f32 v[44:45], v[44:45], v[8:9]
	v_pk_mul_f32 v[42:43], v[42:43], v[6:7]
	s_waitcnt vmcnt(0) lgkmcnt(0)
	v_pk_add_f32 v[48:49], v[48:49], 1.0 op_sel_hi:[1,0]
	v_pk_add_f32 v[46:47], v[46:47], 1.0 op_sel_hi:[1,0]
	v_pk_fma_f32 v[44:45], v[44:45], v[48:49], v[54:55]
	v_pk_fma_f32 v[42:43], v[42:43], v[46:47], v[52:53]
	v_cvt_pk_bf16_f32 v42, v42, v43
	v_cvt_pk_bf16_f32 v43, v44, v45
	global_store_dwordx2 v[104:105], v[42:43], off offset:512
	global_load_dwordx4 v[42:45], v[136:137], off
	s_nop 0
	global_load_dwordx4 v[46:49], v[108:109], off offset:2048
	v_pk_add_f32 v[52:53], v[56:57], v[58:59]
	s_waitcnt vmcnt(0) lgkmcnt(0)
	v_pk_add_f32 v[44:45], v[44:45], 1.0 op_sel_hi:[1,0]
	v_pk_add_f32 v[52:53], v[52:53], v[60:61]
	v_pk_add_f32 v[42:43], v[42:43], 1.0 op_sel_hi:[1,0]
	v_add_f32_e32 v51, v52, v53
	ds_bpermute_b32 v52, v1, v51
	s_waitcnt lgkmcnt(0)
	v_add_f32_e32 v51, v51, v52
	ds_bpermute_b32 v52, v131, v51
	s_waitcnt lgkmcnt(0)
	v_add_f32_e32 v51, v51, v52
	v_pk_mul_f32 v[40:41], v[40:41], v[50:51] op_sel_hi:[1,0]
	v_pk_mul_f32 v[38:39], v[38:39], v[50:51] op_sel_hi:[1,0]
	v_pk_mul_f32 v[40:41], v[40:41], v[12:13]
	v_pk_mul_f32 v[38:39], v[38:39], v[10:11]
	v_pk_fma_f32 v[40:41], v[40:41], v[44:45], v[48:49]
	v_pk_fma_f32 v[38:39], v[38:39], v[42:43], v[46:47]
	v_cvt_pk_bf16_f32 v38, v38, v39
	v_cvt_pk_bf16_f32 v39, v40, v41
	global_store_dwordx2 v[104:105], v[38:39], off offset:1024
	global_load_dwordx4 v[38:41], v[122:123], off
	s_nop 0
	global_load_dwordx4 v[42:45], v[108:109], off offset:3072
	v_pk_mul_f32 v[36:37], v[36:37], v[50:51] op_sel_hi:[1,0]
	v_pk_mul_f32 v[34:35], v[34:35], v[50:51] op_sel_hi:[1,0]
	v_pk_mul_f32 v[36:37], v[36:37], v[16:17]
	v_pk_mul_f32 v[34:35], v[34:35], v[14:15]
	ds_bpermute_b32 v46, v133, v51
	s_waitcnt lgkmcnt(0)
	v_add_f32_e32 v46, v51, v46
	ds_bpermute_b32 v47, v152, v46
	s_waitcnt lgkmcnt(0)
	v_add_f32_e32 v46, v46, v47
	ds_bpermute_b32 v47, v153, v46
	s_waitcnt lgkmcnt(0)
	v_add_f32_e32 v46, v46, v47
	ds_bpermute_b32 v47, v154, v46
	s_waitcnt lgkmcnt(0)
	v_add_f32_e32 v46, v46, v47
	v_fmamk_f32 v46, v46, 0x3a800000, v155
	v_mul_f32_e32 v47, 0x4f800000, v46
	v_cmp_gt_f32_e32 vcc, s4, v46
	s_waitcnt vmcnt(0)
	v_pk_add_f32 v[40:41], v[40:41], 1.0 op_sel_hi:[1,0]
	v_pk_add_f32 v[38:39], v[38:39], 1.0 op_sel_hi:[1,0]
	v_pk_fma_f32 v[36:37], v[36:37], v[40:41], v[44:45]
	v_pk_fma_f32 v[34:35], v[34:35], v[38:39], v[42:43]
	v_cvt_pk_bf16_f32 v34, v34, v35
	v_cvt_pk_bf16_f32 v35, v36, v37
	global_store_dwordx2 v[104:105], v[34:35], off offset:1536
	global_load_dwordx4 v[34:37], v[118:119], off
	s_nop 0
	global_load_dwordx4 v[38:41], v[106:107], off
	v_cndmask_b32_e32 v42, v46, v47, vcc
	v_sqrt_f32_e32 v43, v42
	s_waitcnt vmcnt(0) lgkmcnt(0)
	v_pk_add_f32 v[36:37], v[36:37], 1.0 op_sel_hi:[1,0]
	v_add_u32_e32 v44, -1, v43
	v_add_u32_e32 v45, 1, v43
	v_fma_f32 v46, -v44, v43, v42
	v_fma_f32 v47, -v45, v43, v42
	v_cmp_ge_f32_e64 s[6:7], 0, v46
	v_pk_add_f32 v[34:35], v[34:35], 1.0 op_sel_hi:[1,0]
	s_nop 0
	v_cndmask_b32_e64 v43, v43, v44, s[6:7]
	v_cmp_lt_f32_e64 s[6:7], 0, v47
	s_nop 1
	v_cndmask_b32_e64 v43, v43, v45, s[6:7]
	v_mul_f32_e32 v44, 0x37800000, v43
	v_cndmask_b32_e32 v43, v43, v44, vcc
	v_cmp_class_f32_e32 vcc, v42, v156
	s_nop 1
	v_cndmask_b32_e32 v42, v43, v42, vcc
	v_div_scale_f32 v43, s[6:7], v42, v42, 1.0
	v_rcp_f32_e32 v45, v43
	v_div_scale_f32 v44, vcc, 1.0, v42, 1.0
	v_fma_f32 v46, -v43, v45, 1.0
	v_fmac_f32_e32 v45, v46, v45
	v_mul_f32_e32 v46, v44, v45
	v_fma_f32 v47, -v43, v46, v44
	v_fmac_f32_e32 v46, v47, v45
	v_fma_f32 v43, -v43, v46, v44
	v_div_fmas_f32 v43, v43, v45, v46
	v_div_fixup_f32 v42, v43, v42, 1.0
	v_pk_mul_f32 v[32:33], v[32:33], v[42:43] op_sel_hi:[1,0]
	v_pk_mul_f32 v[30:31], v[30:31], v[42:43] op_sel_hi:[1,0]
	v_pk_mul_f32 v[32:33], v[32:33], v[4:5]
	v_pk_mul_f32 v[30:31], v[30:31], v[2:3]
	v_pk_fma_f32 v[32:33], v[32:33], v[36:37], v[40:41]
	v_pk_fma_f32 v[30:31], v[30:31], v[34:35], v[38:39]
	v_cvt_pk_bf16_f32 v30, v30, v31
	v_cvt_pk_bf16_f32 v31, v32, v33
	global_store_dwordx2 v[104:105], v[30:31], off offset:2048
	global_load_dwordx4 v[30:33], v[114:115], off
	s_nop 0
	global_load_dwordx4 v[34:37], v[106:107], off offset:1024
	v_pk_mul_f32 v[28:29], v[28:29], v[42:43] op_sel_hi:[1,0]
	v_pk_mul_f32 v[26:27], v[26:27], v[42:43] op_sel_hi:[1,0]
	v_pk_mul_f32 v[28:29], v[28:29], v[8:9]
	v_pk_mul_f32 v[26:27], v[26:27], v[6:7]
	v_lshl_add_u64 v[38:39], s[20:21], 0, v[98:99]
	v_pk_mul_f32 v[24:25], v[24:25], v[42:43] op_sel_hi:[1,0]
	v_pk_mul_f32 v[22:23], v[22:23], v[42:43] op_sel_hi:[1,0]
	v_pk_mul_f32 v[24:25], v[24:25], v[12:13]
	v_pk_mul_f32 v[22:23], v[22:23], v[10:11]
	v_pk_mul_f32 v[20:21], v[20:21], v[42:43] op_sel_hi:[1,0]
	v_pk_mul_f32 v[18:19], v[18:19], v[42:43] op_sel_hi:[1,0]
	v_pk_mul_f32 v[20:21], v[20:21], v[16:17]
	v_pk_mul_f32 v[18:19], v[18:19], v[14:15]
	s_waitcnt vmcnt(0) lgkmcnt(0)
	v_pk_add_f32 v[32:33], v[32:33], 1.0 op_sel_hi:[1,0]
	v_pk_add_f32 v[30:31], v[30:31], 1.0 op_sel_hi:[1,0]
	v_pk_fma_f32 v[28:29], v[28:29], v[32:33], v[36:37]
	v_pk_fma_f32 v[26:27], v[26:27], v[30:31], v[34:35]
	v_cvt_pk_bf16_f32 v26, v26, v27
	v_cvt_pk_bf16_f32 v27, v28, v29
	global_store_dwordx2 v[104:105], v[26:27], off offset:2560
	global_load_dwordx4 v[26:29], v[38:39], off
	s_nop 0
	global_load_dwordx4 v[30:33], v[106:107], off offset:2048
	v_lshl_add_u64 v[34:35], s[20:21], 0, v[100:101]
	s_waitcnt vmcnt(0) lgkmcnt(0)
	v_pk_add_f32 v[28:29], v[28:29], 1.0 op_sel_hi:[1,0]
	v_pk_add_f32 v[26:27], v[26:27], 1.0 op_sel_hi:[1,0]
	v_pk_fma_f32 v[24:25], v[24:25], v[28:29], v[32:33]
	v_pk_fma_f32 v[22:23], v[22:23], v[26:27], v[30:31]
	v_cvt_pk_bf16_f32 v22, v22, v23
	v_cvt_pk_bf16_f32 v23, v24, v25
	global_store_dwordx2 v[104:105], v[22:23], off offset:3072
	global_load_dwordx4 v[22:25], v[34:35], off
	s_nop 0
	global_load_dwordx4 v[26:29], v[106:107], off offset:3072
	s_waitcnt vmcnt(0) lgkmcnt(0)
	v_pk_add_f32 v[24:25], v[24:25], 1.0 op_sel_hi:[1,0]
	v_pk_add_f32 v[22:23], v[22:23], 1.0 op_sel_hi:[1,0]
	v_pk_fma_f32 v[20:21], v[20:21], v[24:25], v[28:29]
	v_pk_fma_f32 v[18:19], v[18:19], v[22:23], v[26:27]
	v_cvt_pk_bf16_f32 v18, v18, v19
	v_cvt_pk_bf16_f32 v19, v20, v21
	global_store_dwordx2 v[104:105], v[18:19], off offset:3584
	s_cbranch_scc1 .LBB0_1004

.LBB0_1078:
	v_mov_b32_e32 v138, v1
	v_mov_b32_e32 v145, v131
	s_lshl_b32 s6, s14, 8
	s_add_i32 s6, s6, s71
	v_add_u32_e32 v154, s6, v138
	v_lshlrev_b32_e32 v138, 6, v138
	v_lshl_add_u32 v146, v145, 2, s72
	v_and_b32_e32 v145, 0x3c0, v138
	v_ashrrev_i32_e32 v138, 10, v154
	v_ashrrev_i32_e32 v155, 31, v154
	v_and_b32_e32 v168, -2, v138
	v_lshrrev_b32_e32 v138, 3, v154
	s_cmp_gt_i32 s10, 1
	v_lshlrev_b64 v[158:159], 9, v[154:155]
	v_lshlrev_b64 v[156:157], 10, v[154:155]
	v_and_b32_e32 v155, 0xfe, v138
	v_and_b32_e32 v138, 0x1fff, v154
	s_cselect_b64 s[68:69], -1, 0
	v_cmp_lt_u32_e64 s[8:9], s79, v138
	v_add_u32_e32 v138, 0xffffe200, v138
	v_ashrrev_i32_e32 v160, 13, v154
	v_lshlrev_b64 v[162:163], 10, v[138:139]
	s_mov_b64 s[6:7], -1
	s_and_b64 vcc, exec, s[68:69]
	s_cbranch_vccz .LBB0_1090
	v_cvt_pk_bf16_f32 v148, v126, v127
	v_cvt_pk_bf16_f32 v149, v128, v129
	s_cmp_lt_i32 s10, 3
	s_cbranch_scc1 .LBB0_1087
	s_cmp_lg_u32 s10, 3
	s_cbranch_scc0 .LBB0_1084
	v_lshlrev_b32_e32 v152, 1, v146
	v_lshl_add_u64 v[150:151], s[50:51], 0, v[158:159]
	v_ashrrev_i32_e32 v153, 31, v152
	v_lshl_add_u64 v[150:151], v[150:151], 0, v[152:153]
	global_store_dwordx2 v[150:151], v[148:149], off
	s_and_saveexec_b64 s[6:7], s[8:9]
	s_cbranch_execz .LBB0_1083
	v_ashrrev_i32_e32 v161, 31, v160
	v_lshlrev_b64 v[150:151], 19, v[160:161]
	v_lshl_add_u64 v[150:151], s[52:53], 0, v[150:151]
	v_lshl_add_u64 v[150:151], v[150:151], 0, v[162:163]
	v_ashrrev_i32_e32 v147, 31, v146
	v_lshl_add_u64 v[150:151], v[146:147], 2, v[150:151]
	global_store_dwordx4 v[150:151], v[126:129], off

.LBB0_1090:
	s_lshl_b32 s26, s10, 8
	v_add_u32_e32 v148, s26, v146
	s_and_b64 vcc, exec, s[6:7]
	v_lshl_add_u64 v[164:165], s[54:55], 0, v[156:157]
	v_ashrrev_i32_e32 v149, 31, v148
	s_cbranch_vccz .LBB0_1092
	v_pk_mul_f32 v[152:153], v[126:127], s[56:57] op_sel_hi:[1,0]
	v_pk_mul_f32 v[150:151], v[128:129], s[56:57] op_sel_hi:[1,0]
	v_cvt_pk_bf16_f32 v152, v152, v153
	v_cvt_pk_bf16_f32 v153, v150, v151
	v_lshl_add_u64 v[150:151], v[148:149], 1, v[164:165]
	global_store_dwordx2 v[150:151], v[152:153], off
.LBB0_1092:
	v_cndmask_b32_e64 v138, 0, 1, s[68:69]
	v_add_u32_e32 v178, 16, v146
	v_cmp_ne_u32_e64 s[6:7], 1, v138
	s_andn2_b64 vcc, exec, s[68:69]
	s_mov_b64 s[68:69], -1
	s_cbranch_vccnz .LBB0_1128
	v_cvt_pk_bf16_f32 v150, v122, v123
	v_cvt_pk_bf16_f32 v151, v124, v125
	s_cmp_lt_i32 s10, 3
	s_cbranch_scc1 .LBB0_1101
	s_cmp_lg_u32 s10, 3
	s_cbranch_scc0 .LBB0_1098
	v_lshlrev_b32_e32 v166, 1, v178
	v_lshl_add_u64 v[152:153], s[50:51], 0, v[158:159]
	v_ashrrev_i32_e32 v167, 31, v166
	v_lshl_add_u64 v[152:153], v[152:153], 0, v[166:167]
	global_store_dwordx2 v[152:153], v[150:151], off
	s_and_saveexec_b64 s[68:69], s[8:9]
	s_cbranch_execz .LBB0_1097
	v_ashrrev_i32_e32 v161, 31, v160
	v_lshlrev_b64 v[152:153], 19, v[160:161]
	v_lshl_add_u64 v[152:153], s[52:53], 0, v[152:153]
	v_lshl_add_u64 v[152:153], v[152:153], 0, v[162:163]
	v_ashrrev_i32_e32 v147, 31, v146
	v_lshl_add_u64 v[152:153], v[146:147], 2, v[152:153]
	global_store_dwordx4 v[152:153], v[122:125], off offset:64

.LBB0_1105:
	v_cvt_pk_bf16_f32 v152, v106, v107
	v_cvt_pk_bf16_f32 v153, v108, v109
	s_cmp_lt_i32 s10, 3
	s_cbranch_scc1 .LBB0_1113
	s_cmp_lg_u32 s10, 3
	s_cbranch_scc0 .LBB0_1110
	v_lshlrev_b32_e32 v182, 1, v180
	v_lshl_add_u64 v[166:167], s[50:51], 0, v[158:159]
	v_ashrrev_i32_e32 v183, 31, v182
	v_lshl_add_u64 v[166:167], v[166:167], 0, v[182:183]
	global_store_dwordx2 v[166:167], v[152:153], off
	s_and_saveexec_b64 s[68:69], s[8:9]
	s_cbranch_execz .LBB0_1109
	v_ashrrev_i32_e32 v161, 31, v160
	v_lshlrev_b64 v[166:167], 19, v[160:161]
	v_lshl_add_u64 v[166:167], s[52:53], 0, v[166:167]
	v_lshl_add_u64 v[166:167], v[166:167], 0, v[162:163]
	v_ashrrev_i32_e32 v147, 31, v146
	v_lshl_add_u64 v[166:167], v[146:147], 2, v[166:167]
	global_store_dwordx4 v[166:167], v[106:109], off offset:512

.LBB0_1117:
	v_cvt_pk_bf16_f32 v166, v98, v99
	v_cvt_pk_bf16_f32 v167, v100, v101
	s_cmp_lt_i32 s10, 3
	s_cbranch_scc1 .LBB0_1125
	s_cmp_lg_u32 s10, 3
	s_cbranch_scc0 .LBB0_1122
	v_lshlrev_b32_e32 v184, 1, v179
	v_lshl_add_u64 v[182:183], s[50:51], 0, v[158:159]
	v_ashrrev_i32_e32 v185, 31, v184
	v_lshl_add_u64 v[182:183], v[182:183], 0, v[184:185]
	global_store_dwordx2 v[182:183], v[166:167], off
	s_and_saveexec_b64 s[68:69], s[8:9]
	s_cbranch_execz .LBB0_1121
	v_ashrrev_i32_e32 v161, 31, v160
	v_lshlrev_b64 v[160:161], 19, v[160:161]
	v_lshl_add_u64 v[160:161], s[52:53], 0, v[160:161]
	v_lshl_add_u64 v[160:161], v[160:161], 0, v[162:163]
	v_ashrrev_i32_e32 v147, 31, v146
	v_lshl_add_u64 v[160:161], v[146:147], 2, v[160:161]
	global_store_dwordx4 v[160:161], v[98:101], off offset:576

.LBB0_1128:
	v_add_u32_e32 v150, s26, v178
	s_and_b64 vcc, exec, s[68:69]
	v_ashrrev_i32_e32 v151, 31, v150
	s_cbranch_vccz .LBB0_1104
	v_pk_mul_f32 v[166:167], v[122:123], s[56:57] op_sel_hi:[1,0]
	v_pk_mul_f32 v[152:153], v[124:125], s[56:57] op_sel_hi:[1,0]
	v_cvt_pk_bf16_f32 v166, v166, v167
	v_cvt_pk_bf16_f32 v167, v152, v153
	v_lshl_add_u64 v[152:153], v[150:151], 1, v[164:165]
	global_store_dwordx2 v[152:153], v[166:167], off
	v_add_u32_e32 v180, 0x80, v146
	s_and_b64 vcc, exec, s[6:7]
	s_mov_b64 s[68:69], -1
	s_cbranch_vccz .LBB0_1105
.LBB0_1130:
	v_add_u32_e32 v152, s26, v180
	s_and_b64 vcc, exec, s[68:69]
	v_ashrrev_i32_e32 v153, 31, v152
	s_cbranch_vccz .LBB0_1116
	v_pk_mul_f32 v[182:183], v[106:107], s[56:57] op_sel_hi:[1,0]
	v_pk_mul_f32 v[166:167], v[108:109], s[56:57] op_sel_hi:[1,0]
	v_cvt_pk_bf16_f32 v182, v182, v183
	v_cvt_pk_bf16_f32 v183, v166, v167
	v_lshl_add_u64 v[166:167], v[152:153], 1, v[164:165]
	global_store_dwordx2 v[166:167], v[182:183], off
	v_add_u32_e32 v179, 0x90, v146
	s_and_b64 vcc, exec, s[6:7]
	s_mov_b64 s[68:69], -1
	s_cbranch_vccz .LBB0_1117
.LBB0_1132:
	v_add_u32_e32 v156, s26, v179
	s_and_b64 vcc, exec, s[68:69]
	v_ashrrev_i32_e32 v157, 31, v156
	s_cbranch_vccz .LBB0_1134
	v_pk_mul_f32 v[160:161], v[98:99], s[56:57] op_sel_hi:[1,0]
	v_pk_mul_f32 v[158:159], v[100:101], s[56:57] op_sel_hi:[1,0]
	v_cvt_pk_bf16_f32 v160, v160, v161
	v_cvt_pk_bf16_f32 v161, v158, v159
	v_lshl_add_u64 v[158:159], v[156:157], 1, v[164:165]
	global_store_dwordx2 v[158:159], v[160:161], off
.LBB0_1134:
	v_add_u32_e32 v162, 16, v154
	v_ashrrev_i32_e32 v138, 10, v162
	v_and_b32_e32 v181, -2, v138
	v_lshrrev_b32_e32 v138, 3, v162
	v_and_b32_e32 v155, 0xfe, v138
	v_and_b32_e32 v138, 0x1fff, v162
	v_ashrrev_i32_e32 v163, 31, v162
	v_cmp_lt_u32_e64 s[8:9], s79, v138
	v_add_u32_e32 v138, 0xffffe200, v138
	v_lshlrev_b64 v[160:161], 9, v[162:163]
	v_lshlrev_b64 v[158:159], 10, v[162:163]
	v_ashrrev_i32_e32 v162, 13, v162
	v_lshlrev_b64 v[164:165], 10, v[138:139]
	s_and_b64 vcc, exec, s[6:7]
	s_mov_b64 s[68:69], -1
	s_cbranch_vccnz .LBB0_1182
	v_cvt_pk_bf16_f32 v166, v118, v119
	v_cvt_pk_bf16_f32 v167, v120, v121
	s_cmp_lt_i32 s10, 3
	s_cbranch_scc1 .LBB0_1143
	s_cmp_lg_u32 s10, 3
	s_cbranch_scc0 .LBB0_1140
	v_lshlrev_b32_e32 v182, 1, v146
	v_lshl_add_u64 v[168:169], s[50:51], 0, v[160:161]
	v_ashrrev_i32_e32 v183, 31, v182
	v_lshl_add_u64 v[168:169], v[168:169], 0, v[182:183]
	global_store_dwordx2 v[168:169], v[166:167], off
	s_and_saveexec_b64 s[68:69], s[8:9]
	s_cbranch_execz .LBB0_1139
	v_ashrrev_i32_e32 v163, 31, v162
	v_lshlrev_b64 v[168:169], 19, v[162:163]
	v_lshl_add_u64 v[168:169], s[52:53], 0, v[168:169]
	v_lshl_add_u64 v[168:169], v[168:169], 0, v[164:165]
	v_ashrrev_i32_e32 v147, 31, v146
	v_lshl_add_u64 v[168:169], v[146:147], 2, v[168:169]
	global_store_dwordx4 v[168:169], v[118:121], off

.LBB0_1147:
	v_cvt_pk_bf16_f32 v168, v114, v115
	v_cvt_pk_bf16_f32 v169, v116, v117
	s_cmp_lt_i32 s10, 3
	s_cbranch_scc1 .LBB0_1155
	s_cmp_lg_u32 s10, 3
	s_cbranch_scc0 .LBB0_1152
	v_lshlrev_b32_e32 v184, 1, v178
	v_lshl_add_u64 v[182:183], s[50:51], 0, v[160:161]
	v_ashrrev_i32_e32 v185, 31, v184
	v_lshl_add_u64 v[182:183], v[182:183], 0, v[184:185]
	global_store_dwordx2 v[182:183], v[168:169], off
	s_and_saveexec_b64 s[68:69], s[8:9]
	s_cbranch_execz .LBB0_1151
	v_ashrrev_i32_e32 v163, 31, v162
	v_lshlrev_b64 v[182:183], 19, v[162:163]
	v_lshl_add_u64 v[182:183], s[52:53], 0, v[182:183]
	v_lshl_add_u64 v[182:183], v[182:183], 0, v[164:165]
	v_ashrrev_i32_e32 v147, 31, v146
	v_lshl_add_u64 v[182:183], v[146:147], 2, v[182:183]
	global_store_dwordx4 v[182:183], v[114:117], off offset:64

.LBB0_1159:
	v_cvt_pk_bf16_f32 v168, v90, v91
	v_cvt_pk_bf16_f32 v169, v92, v93
	s_cmp_lt_i32 s10, 3
	s_cbranch_scc1 .LBB0_1167
	s_cmp_lg_u32 s10, 3
	s_cbranch_scc0 .LBB0_1164
	v_lshlrev_b32_e32 v184, 1, v180
	v_lshl_add_u64 v[182:183], s[50:51], 0, v[160:161]
	v_ashrrev_i32_e32 v185, 31, v184
	v_lshl_add_u64 v[182:183], v[182:183], 0, v[184:185]
	global_store_dwordx2 v[182:183], v[168:169], off
	s_and_saveexec_b64 s[68:69], s[8:9]
	s_cbranch_execz .LBB0_1163
	v_ashrrev_i32_e32 v163, 31, v162
	v_lshlrev_b64 v[182:183], 19, v[162:163]
	v_lshl_add_u64 v[182:183], s[52:53], 0, v[182:183]
	v_lshl_add_u64 v[182:183], v[182:183], 0, v[164:165]
	v_ashrrev_i32_e32 v147, 31, v146
	v_lshl_add_u64 v[182:183], v[146:147], 2, v[182:183]
	global_store_dwordx4 v[182:183], v[90:93], off offset:512

.LBB0_1171:
	v_cvt_pk_bf16_f32 v168, v82, v83
	v_cvt_pk_bf16_f32 v169, v84, v85
	s_cmp_lt_i32 s10, 3
	s_cbranch_scc1 .LBB0_1179
	s_cmp_lg_u32 s10, 3
	s_cbranch_scc0 .LBB0_1176
	v_lshlrev_b32_e32 v184, 1, v179
	v_lshl_add_u64 v[182:183], s[50:51], 0, v[160:161]
	v_ashrrev_i32_e32 v185, 31, v184
	v_lshl_add_u64 v[182:183], v[182:183], 0, v[184:185]
	global_store_dwordx2 v[182:183], v[168:169], off
	s_and_saveexec_b64 s[68:69], s[8:9]
	s_cbranch_execz .LBB0_1175
	v_ashrrev_i32_e32 v163, 31, v162
	v_lshlrev_b64 v[162:163], 19, v[162:163]
	v_lshl_add_u64 v[162:163], s[52:53], 0, v[162:163]
	v_lshl_add_u64 v[162:163], v[162:163], 0, v[164:165]
	v_ashrrev_i32_e32 v147, 31, v146
	v_lshl_add_u64 v[162:163], v[146:147], 2, v[162:163]
	global_store_dwordx4 v[162:163], v[82:85], off offset:576

.LBB0_1182:
	s_and_b64 vcc, exec, s[68:69]
	v_lshl_add_u64 v[166:167], s[54:55], 0, v[158:159]
	s_cbranch_vccz .LBB0_1146
	v_pk_mul_f32 v[182:183], v[118:119], s[56:57] op_sel_hi:[1,0]
	v_pk_mul_f32 v[168:169], v[120:121], s[56:57] op_sel_hi:[1,0]
	v_cvt_pk_bf16_f32 v182, v182, v183
	v_cvt_pk_bf16_f32 v183, v168, v169
	v_lshl_add_u64 v[168:169], v[148:149], 1, v[166:167]
	global_store_dwordx2 v[168:169], v[182:183], off
	s_and_b64 vcc, exec, s[6:7]
	s_mov_b64 s[68:69], -1
	s_cbranch_vccz .LBB0_1147
.LBB0_1184:
	s_and_b64 vcc, exec, s[68:69]
	s_cbranch_vccz .LBB0_1158
	v_pk_mul_f32 v[182:183], v[114:115], s[56:57] op_sel_hi:[1,0]
	v_pk_mul_f32 v[168:169], v[116:117], s[56:57] op_sel_hi:[1,0]
	v_cvt_pk_bf16_f32 v182, v182, v183
	v_cvt_pk_bf16_f32 v183, v168, v169
	v_lshl_add_u64 v[168:169], v[150:151], 1, v[166:167]
	global_store_dwordx2 v[168:169], v[182:183], off
	s_and_b64 vcc, exec, s[6:7]
	s_mov_b64 s[68:69], -1
	s_cbranch_vccz .LBB0_1159
.LBB0_1186:
	s_and_b64 vcc, exec, s[68:69]
	s_cbranch_vccz .LBB0_1170
	v_pk_mul_f32 v[182:183], v[90:91], s[56:57] op_sel_hi:[1,0]
	v_pk_mul_f32 v[168:169], v[92:93], s[56:57] op_sel_hi:[1,0]
	v_cvt_pk_bf16_f32 v182, v182, v183
	v_cvt_pk_bf16_f32 v183, v168, v169
	v_lshl_add_u64 v[168:169], v[152:153], 1, v[166:167]
	global_store_dwordx2 v[168:169], v[182:183], off
	s_and_b64 vcc, exec, s[6:7]
	s_mov_b64 s[68:69], -1
	s_cbranch_vccz .LBB0_1171
.LBB0_1188:
	s_and_b64 vcc, exec, s[68:69]
	s_cbranch_vccz .LBB0_1190
	v_pk_mul_f32 v[160:161], v[82:83], s[56:57] op_sel_hi:[1,0]
	v_pk_mul_f32 v[158:159], v[84:85], s[56:57] op_sel_hi:[1,0]
	v_cvt_pk_bf16_f32 v160, v160, v161
	v_cvt_pk_bf16_f32 v161, v158, v159
	v_lshl_add_u64 v[158:159], v[156:157], 1, v[166:167]
	global_store_dwordx2 v[158:159], v[160:161], off
.LBB0_1190:
	v_add_u32_e32 v162, 32, v154
	v_ashrrev_i32_e32 v138, 10, v162
	v_and_b32_e32 v181, -2, v138
	v_lshrrev_b32_e32 v138, 3, v162
	v_and_b32_e32 v155, 0xfe, v138
	v_and_b32_e32 v138, 0x1fff, v162
	v_ashrrev_i32_e32 v163, 31, v162
	v_cmp_lt_u32_e64 s[8:9], s79, v138
	v_add_u32_e32 v138, 0xffffe200, v138
	v_lshlrev_b64 v[160:161], 9, v[162:163]
	v_lshlrev_b64 v[158:159], 10, v[162:163]
	v_ashrrev_i32_e32 v162, 13, v162
	v_lshlrev_b64 v[164:165], 10, v[138:139]
	s_and_b64 vcc, exec, s[6:7]
	s_mov_b64 s[68:69], -1
	s_cbranch_vccnz .LBB0_1238
	v_cvt_pk_bf16_f32 v166, v110, v111
	v_cvt_pk_bf16_f32 v167, v112, v113
	s_cmp_lt_i32 s10, 3
	s_cbranch_scc1 .LBB0_1199
	s_cmp_lg_u32 s10, 3
	s_cbranch_scc0 .LBB0_1196
	v_lshlrev_b32_e32 v182, 1, v146
	v_lshl_add_u64 v[168:169], s[50:51], 0, v[160:161]
	v_ashrrev_i32_e32 v183, 31, v182
	v_lshl_add_u64 v[168:169], v[168:169], 0, v[182:183]
	global_store_dwordx2 v[168:169], v[166:167], off
	s_and_saveexec_b64 s[68:69], s[8:9]
	s_cbranch_execz .LBB0_1195
	v_ashrrev_i32_e32 v163, 31, v162
	v_lshlrev_b64 v[168:169], 19, v[162:163]
	v_lshl_add_u64 v[168:169], s[52:53], 0, v[168:169]
	v_lshl_add_u64 v[168:169], v[168:169], 0, v[164:165]
	v_ashrrev_i32_e32 v147, 31, v146
	v_lshl_add_u64 v[168:169], v[146:147], 2, v[168:169]
	global_store_dwordx4 v[168:169], v[110:113], off

.LBB0_1203:
	v_cvt_pk_bf16_f32 v168, v102, v103
	v_cvt_pk_bf16_f32 v169, v104, v105
	s_cmp_lt_i32 s10, 3
	s_cbranch_scc1 .LBB0_1211
	s_cmp_lg_u32 s10, 3
	s_cbranch_scc0 .LBB0_1208
	v_lshlrev_b32_e32 v184, 1, v178
	v_lshl_add_u64 v[182:183], s[50:51], 0, v[160:161]
	v_ashrrev_i32_e32 v185, 31, v184
	v_lshl_add_u64 v[182:183], v[182:183], 0, v[184:185]
	global_store_dwordx2 v[182:183], v[168:169], off
	s_and_saveexec_b64 s[68:69], s[8:9]
	s_cbranch_execz .LBB0_1207
	v_ashrrev_i32_e32 v163, 31, v162
	v_lshlrev_b64 v[182:183], 19, v[162:163]
	v_lshl_add_u64 v[182:183], s[52:53], 0, v[182:183]
	v_lshl_add_u64 v[182:183], v[182:183], 0, v[164:165]
	v_ashrrev_i32_e32 v147, 31, v146
	v_lshl_add_u64 v[182:183], v[146:147], 2, v[182:183]
	global_store_dwordx4 v[182:183], v[102:105], off offset:64

.LBB0_1215:
	v_cvt_pk_bf16_f32 v168, v78, v79
	v_cvt_pk_bf16_f32 v169, v80, v81
	s_cmp_lt_i32 s10, 3
	s_cbranch_scc1 .LBB0_1223
	s_cmp_lg_u32 s10, 3
	s_cbranch_scc0 .LBB0_1220
	v_lshlrev_b32_e32 v184, 1, v180
	v_lshl_add_u64 v[182:183], s[50:51], 0, v[160:161]
	v_ashrrev_i32_e32 v185, 31, v184
	v_lshl_add_u64 v[182:183], v[182:183], 0, v[184:185]
	global_store_dwordx2 v[182:183], v[168:169], off
	s_and_saveexec_b64 s[68:69], s[8:9]
	s_cbranch_execz .LBB0_1219
	v_ashrrev_i32_e32 v163, 31, v162
	v_lshlrev_b64 v[182:183], 19, v[162:163]
	v_lshl_add_u64 v[182:183], s[52:53], 0, v[182:183]
	v_lshl_add_u64 v[182:183], v[182:183], 0, v[164:165]
	v_ashrrev_i32_e32 v147, 31, v146
	v_lshl_add_u64 v[182:183], v[146:147], 2, v[182:183]
	global_store_dwordx4 v[182:183], v[78:81], off offset:512

.LBB0_1227:
	v_cvt_pk_bf16_f32 v168, v74, v75
	v_cvt_pk_bf16_f32 v169, v76, v77
	s_cmp_lt_i32 s10, 3
	s_cbranch_scc1 .LBB0_1235
	s_cmp_lg_u32 s10, 3
	s_cbranch_scc0 .LBB0_1232
	v_lshlrev_b32_e32 v184, 1, v179
	v_lshl_add_u64 v[182:183], s[50:51], 0, v[160:161]
	v_ashrrev_i32_e32 v185, 31, v184
	v_lshl_add_u64 v[182:183], v[182:183], 0, v[184:185]
	global_store_dwordx2 v[182:183], v[168:169], off
	s_and_saveexec_b64 s[68:69], s[8:9]
	s_cbranch_execz .LBB0_1231
	v_ashrrev_i32_e32 v163, 31, v162
	v_lshlrev_b64 v[162:163], 19, v[162:163]
	v_lshl_add_u64 v[162:163], s[52:53], 0, v[162:163]
	v_lshl_add_u64 v[162:163], v[162:163], 0, v[164:165]
	v_ashrrev_i32_e32 v147, 31, v146
	v_lshl_add_u64 v[162:163], v[146:147], 2, v[162:163]
	global_store_dwordx4 v[162:163], v[74:77], off offset:576

.LBB0_1238:
	s_and_b64 vcc, exec, s[68:69]
	v_lshl_add_u64 v[166:167], s[54:55], 0, v[158:159]
	s_cbranch_vccz .LBB0_1202
	v_pk_mul_f32 v[182:183], v[110:111], s[56:57] op_sel_hi:[1,0]
	v_pk_mul_f32 v[168:169], v[112:113], s[56:57] op_sel_hi:[1,0]
	v_cvt_pk_bf16_f32 v182, v182, v183
	v_cvt_pk_bf16_f32 v183, v168, v169
	v_lshl_add_u64 v[168:169], v[148:149], 1, v[166:167]
	global_store_dwordx2 v[168:169], v[182:183], off
	s_and_b64 vcc, exec, s[6:7]
	s_mov_b64 s[68:69], -1
	s_cbranch_vccz .LBB0_1203
.LBB0_1240:
	s_and_b64 vcc, exec, s[68:69]
	s_cbranch_vccz .LBB0_1214
	v_pk_mul_f32 v[182:183], v[102:103], s[56:57] op_sel_hi:[1,0]
	v_pk_mul_f32 v[168:169], v[104:105], s[56:57] op_sel_hi:[1,0]
	v_cvt_pk_bf16_f32 v182, v182, v183
	v_cvt_pk_bf16_f32 v183, v168, v169
	v_lshl_add_u64 v[168:169], v[150:151], 1, v[166:167]
	global_store_dwordx2 v[168:169], v[182:183], off
	s_and_b64 vcc, exec, s[6:7]
	s_mov_b64 s[68:69], -1
	s_cbranch_vccz .LBB0_1215
.LBB0_1242:
	s_and_b64 vcc, exec, s[68:69]
	s_cbranch_vccz .LBB0_1226
	v_pk_mul_f32 v[182:183], v[78:79], s[56:57] op_sel_hi:[1,0]
	v_pk_mul_f32 v[168:169], v[80:81], s[56:57] op_sel_hi:[1,0]
	v_cvt_pk_bf16_f32 v182, v182, v183
	v_cvt_pk_bf16_f32 v183, v168, v169
	v_lshl_add_u64 v[168:169], v[152:153], 1, v[166:167]
	global_store_dwordx2 v[168:169], v[182:183], off
	s_and_b64 vcc, exec, s[6:7]
	s_mov_b64 s[68:69], -1
	s_cbranch_vccz .LBB0_1227
.LBB0_1244:
	s_and_b64 vcc, exec, s[68:69]
	s_cbranch_vccz .LBB0_1246
	v_pk_mul_f32 v[160:161], v[74:75], s[56:57] op_sel_hi:[1,0]
	v_pk_mul_f32 v[158:159], v[76:77], s[56:57] op_sel_hi:[1,0]
	v_cvt_pk_bf16_f32 v160, v160, v161
	v_cvt_pk_bf16_f32 v161, v158, v159
	v_lshl_add_u64 v[158:159], v[156:157], 1, v[166:167]
	global_store_dwordx2 v[158:159], v[160:161], off
.LBB0_1246:
	v_add_u32_e32 v162, 48, v154
	v_ashrrev_i32_e32 v138, 10, v162
	v_and_b32_e32 v181, -2, v138
	v_lshrrev_b32_e32 v138, 3, v162
	v_and_b32_e32 v155, 0xfe, v138
	v_and_b32_e32 v138, 0x1fff, v162
	v_ashrrev_i32_e32 v163, 31, v162
	v_cmp_lt_u32_e64 s[8:9], s79, v138
	v_add_u32_e32 v138, 0xffffe200, v138
	v_lshlrev_b64 v[160:161], 9, v[162:163]
	v_lshlrev_b64 v[158:159], 10, v[162:163]
	v_ashrrev_i32_e32 v162, 13, v162
	v_lshlrev_b64 v[164:165], 10, v[138:139]
	s_and_b64 vcc, exec, s[6:7]
	s_mov_b64 s[68:69], -1
	s_cbranch_vccnz .LBB0_1294
	v_cvt_pk_bf16_f32 v166, v94, v95
	v_cvt_pk_bf16_f32 v167, v96, v97
	s_cmp_lt_i32 s10, 3
	s_cbranch_scc1 .LBB0_1255
	s_cmp_lg_u32 s10, 3
	s_cbranch_scc0 .LBB0_1252
	v_lshlrev_b32_e32 v182, 1, v146
	v_lshl_add_u64 v[168:169], s[50:51], 0, v[160:161]
	v_ashrrev_i32_e32 v183, 31, v182
	v_lshl_add_u64 v[168:169], v[168:169], 0, v[182:183]
	global_store_dwordx2 v[168:169], v[166:167], off
	s_and_saveexec_b64 s[68:69], s[8:9]
	s_cbranch_execz .LBB0_1251
	v_ashrrev_i32_e32 v163, 31, v162
	v_lshlrev_b64 v[168:169], 19, v[162:163]
	v_lshl_add_u64 v[168:169], s[52:53], 0, v[168:169]
	v_lshl_add_u64 v[168:169], v[168:169], 0, v[164:165]
	v_ashrrev_i32_e32 v147, 31, v146
	v_lshl_add_u64 v[168:169], v[146:147], 2, v[168:169]
	global_store_dwordx4 v[168:169], v[94:97], off

.LBB0_1259:
	v_cvt_pk_bf16_f32 v168, v86, v87
	v_cvt_pk_bf16_f32 v169, v88, v89
	s_cmp_lt_i32 s10, 3
	s_cbranch_scc1 .LBB0_1267
	s_cmp_lg_u32 s10, 3
	s_cbranch_scc0 .LBB0_1264
	v_lshlrev_b32_e32 v184, 1, v178
	v_lshl_add_u64 v[182:183], s[50:51], 0, v[160:161]
	v_ashrrev_i32_e32 v185, 31, v184
	v_lshl_add_u64 v[182:183], v[182:183], 0, v[184:185]
	global_store_dwordx2 v[182:183], v[168:169], off
	s_and_saveexec_b64 s[68:69], s[8:9]
	s_cbranch_execz .LBB0_1263
	v_ashrrev_i32_e32 v163, 31, v162
	v_lshlrev_b64 v[182:183], 19, v[162:163]
	v_lshl_add_u64 v[182:183], s[52:53], 0, v[182:183]
	v_lshl_add_u64 v[182:183], v[182:183], 0, v[164:165]
	v_ashrrev_i32_e32 v147, 31, v146
	v_lshl_add_u64 v[182:183], v[146:147], 2, v[182:183]
	global_store_dwordx4 v[182:183], v[86:89], off offset:64

.LBB0_1271:
	v_cvt_pk_bf16_f32 v168, v70, v71
	v_cvt_pk_bf16_f32 v169, v72, v73
	s_cmp_lt_i32 s10, 3
	s_cbranch_scc1 .LBB0_1279
	s_cmp_lg_u32 s10, 3
	s_cbranch_scc0 .LBB0_1276
	v_lshlrev_b32_e32 v184, 1, v180
	v_lshl_add_u64 v[182:183], s[50:51], 0, v[160:161]
	v_ashrrev_i32_e32 v185, 31, v184
	v_lshl_add_u64 v[182:183], v[182:183], 0, v[184:185]
	global_store_dwordx2 v[182:183], v[168:169], off
	s_and_saveexec_b64 s[68:69], s[8:9]
	s_cbranch_execz .LBB0_1275
	v_ashrrev_i32_e32 v163, 31, v162
	v_lshlrev_b64 v[182:183], 19, v[162:163]
	v_lshl_add_u64 v[182:183], s[52:53], 0, v[182:183]
	v_lshl_add_u64 v[182:183], v[182:183], 0, v[164:165]
	v_ashrrev_i32_e32 v147, 31, v146
	v_lshl_add_u64 v[182:183], v[146:147], 2, v[182:183]
	global_store_dwordx4 v[182:183], v[70:73], off offset:512

.LBB0_1283:
	v_cvt_pk_bf16_f32 v168, v66, v67
	v_cvt_pk_bf16_f32 v169, v68, v69
	s_cmp_lt_i32 s10, 3
	s_cbranch_scc1 .LBB0_1291
	s_cmp_lg_u32 s10, 3
	s_cbranch_scc0 .LBB0_1288
	v_lshlrev_b32_e32 v184, 1, v179
	v_lshl_add_u64 v[182:183], s[50:51], 0, v[160:161]
	v_ashrrev_i32_e32 v185, 31, v184
	v_lshl_add_u64 v[182:183], v[182:183], 0, v[184:185]
	global_store_dwordx2 v[182:183], v[168:169], off
	s_and_saveexec_b64 s[68:69], s[8:9]
	s_cbranch_execz .LBB0_1287
	v_ashrrev_i32_e32 v163, 31, v162
	v_lshlrev_b64 v[162:163], 19, v[162:163]
	v_lshl_add_u64 v[162:163], s[52:53], 0, v[162:163]
	v_lshl_add_u64 v[162:163], v[162:163], 0, v[164:165]
	v_ashrrev_i32_e32 v147, 31, v146
	v_lshl_add_u64 v[162:163], v[146:147], 2, v[162:163]
	global_store_dwordx4 v[162:163], v[66:69], off offset:576

.LBB0_1294:
	s_and_b64 vcc, exec, s[68:69]
	v_lshl_add_u64 v[166:167], s[54:55], 0, v[158:159]
	s_cbranch_vccz .LBB0_1258
	v_pk_mul_f32 v[182:183], v[94:95], s[56:57] op_sel_hi:[1,0]
	v_pk_mul_f32 v[168:169], v[96:97], s[56:57] op_sel_hi:[1,0]
	v_cvt_pk_bf16_f32 v182, v182, v183
	v_cvt_pk_bf16_f32 v183, v168, v169
	v_lshl_add_u64 v[168:169], v[148:149], 1, v[166:167]
	global_store_dwordx2 v[168:169], v[182:183], off
	s_and_b64 vcc, exec, s[6:7]
	s_mov_b64 s[68:69], -1
	s_cbranch_vccz .LBB0_1259
.LBB0_1296:
	s_and_b64 vcc, exec, s[68:69]
	s_cbranch_vccz .LBB0_1270
	v_pk_mul_f32 v[182:183], v[86:87], s[56:57] op_sel_hi:[1,0]
	v_pk_mul_f32 v[168:169], v[88:89], s[56:57] op_sel_hi:[1,0]
	v_cvt_pk_bf16_f32 v182, v182, v183
	v_cvt_pk_bf16_f32 v183, v168, v169
	v_lshl_add_u64 v[168:169], v[150:151], 1, v[166:167]
	global_store_dwordx2 v[168:169], v[182:183], off
	s_and_b64 vcc, exec, s[6:7]
	s_mov_b64 s[68:69], -1
	s_cbranch_vccz .LBB0_1271
.LBB0_1298:
	s_and_b64 vcc, exec, s[68:69]
	s_cbranch_vccz .LBB0_1282
	v_pk_mul_f32 v[182:183], v[70:71], s[56:57] op_sel_hi:[1,0]
	v_pk_mul_f32 v[168:169], v[72:73], s[56:57] op_sel_hi:[1,0]
	v_cvt_pk_bf16_f32 v182, v182, v183
	v_cvt_pk_bf16_f32 v183, v168, v169
	v_lshl_add_u64 v[168:169], v[152:153], 1, v[166:167]
	global_store_dwordx2 v[168:169], v[182:183], off
	s_and_b64 vcc, exec, s[6:7]
	s_mov_b64 s[68:69], -1
	s_cbranch_vccz .LBB0_1283
.LBB0_1300:
	s_and_b64 vcc, exec, s[68:69]
	s_cbranch_vccz .LBB0_1302
	v_pk_mul_f32 v[160:161], v[66:67], s[56:57] op_sel_hi:[1,0]
	v_pk_mul_f32 v[158:159], v[68:69], s[56:57] op_sel_hi:[1,0]
	v_cvt_pk_bf16_f32 v160, v160, v161
	v_cvt_pk_bf16_f32 v161, v158, v159
	v_lshl_add_u64 v[158:159], v[156:157], 1, v[166:167]
	global_store_dwordx2 v[158:159], v[160:161], off
.LBB0_1302:
	v_add_u32_e32 v162, 0x80, v154
	v_ashrrev_i32_e32 v138, 10, v162
	v_and_b32_e32 v181, -2, v138
	v_lshrrev_b32_e32 v138, 3, v162
	v_and_b32_e32 v155, 0xfe, v138
	v_and_b32_e32 v138, 0x1fff, v162
	v_ashrrev_i32_e32 v163, 31, v162
	v_cmp_lt_u32_e64 s[8:9], s79, v138
	v_add_u32_e32 v138, 0xffffe200, v138
	v_lshlrev_b64 v[160:161], 9, v[162:163]
	v_lshlrev_b64 v[158:159], 10, v[162:163]
	v_ashrrev_i32_e32 v162, 13, v162
	v_lshlrev_b64 v[164:165], 10, v[138:139]
	s_and_b64 vcc, exec, s[6:7]
	s_mov_b64 s[68:69], -1
	s_cbranch_vccnz .LBB0_1350
	v_cvt_pk_bf16_f32 v166, v62, v63
	v_cvt_pk_bf16_f32 v167, v64, v65
	s_cmp_lt_i32 s10, 3
	s_cbranch_scc1 .LBB0_1311
	s_cmp_lg_u32 s10, 3
	s_cbranch_scc0 .LBB0_1308
	v_lshlrev_b32_e32 v182, 1, v146
	v_lshl_add_u64 v[168:169], s[50:51], 0, v[160:161]
	v_ashrrev_i32_e32 v183, 31, v182
	v_lshl_add_u64 v[168:169], v[168:169], 0, v[182:183]
	global_store_dwordx2 v[168:169], v[166:167], off
	s_and_saveexec_b64 s[68:69], s[8:9]
	s_cbranch_execz .LBB0_1307
	v_ashrrev_i32_e32 v163, 31, v162
	v_lshlrev_b64 v[168:169], 19, v[162:163]
	v_lshl_add_u64 v[168:169], s[52:53], 0, v[168:169]
	v_lshl_add_u64 v[168:169], v[168:169], 0, v[164:165]
	v_ashrrev_i32_e32 v147, 31, v146
	v_lshl_add_u64 v[168:169], v[146:147], 2, v[168:169]
	global_store_dwordx4 v[168:169], v[62:65], off

.LBB0_1315:
	v_cvt_pk_bf16_f32 v168, v58, v59
	v_cvt_pk_bf16_f32 v169, v60, v61
	s_cmp_lt_i32 s10, 3
	s_cbranch_scc1 .LBB0_1323
	s_cmp_lg_u32 s10, 3
	s_cbranch_scc0 .LBB0_1320
	v_lshlrev_b32_e32 v184, 1, v178
	v_lshl_add_u64 v[182:183], s[50:51], 0, v[160:161]
	v_ashrrev_i32_e32 v185, 31, v184
	v_lshl_add_u64 v[182:183], v[182:183], 0, v[184:185]
	global_store_dwordx2 v[182:183], v[168:169], off
	s_and_saveexec_b64 s[68:69], s[8:9]
	s_cbranch_execz .LBB0_1319
	v_ashrrev_i32_e32 v163, 31, v162
	v_lshlrev_b64 v[182:183], 19, v[162:163]
	v_lshl_add_u64 v[182:183], s[52:53], 0, v[182:183]
	v_lshl_add_u64 v[182:183], v[182:183], 0, v[164:165]
	v_ashrrev_i32_e32 v147, 31, v146
	v_lshl_add_u64 v[182:183], v[146:147], 2, v[182:183]
	global_store_dwordx4 v[182:183], v[58:61], off offset:64

.LBB0_1327:
	v_cvt_pk_bf16_f32 v168, v42, v43
	v_cvt_pk_bf16_f32 v169, v44, v45
	s_cmp_lt_i32 s10, 3
	s_cbranch_scc1 .LBB0_1335
	s_cmp_lg_u32 s10, 3
	s_cbranch_scc0 .LBB0_1332
	v_lshlrev_b32_e32 v184, 1, v180
	v_lshl_add_u64 v[182:183], s[50:51], 0, v[160:161]
	v_ashrrev_i32_e32 v185, 31, v184
	v_lshl_add_u64 v[182:183], v[182:183], 0, v[184:185]
	global_store_dwordx2 v[182:183], v[168:169], off
	s_and_saveexec_b64 s[68:69], s[8:9]
	s_cbranch_execz .LBB0_1331
	v_ashrrev_i32_e32 v163, 31, v162
	v_lshlrev_b64 v[182:183], 19, v[162:163]
	v_lshl_add_u64 v[182:183], s[52:53], 0, v[182:183]
	v_lshl_add_u64 v[182:183], v[182:183], 0, v[164:165]
	v_ashrrev_i32_e32 v147, 31, v146
	v_lshl_add_u64 v[182:183], v[146:147], 2, v[182:183]
	global_store_dwordx4 v[182:183], v[42:45], off offset:512

.LBB0_1339:
	v_cvt_pk_bf16_f32 v168, v34, v35
	v_cvt_pk_bf16_f32 v169, v36, v37
	s_cmp_lt_i32 s10, 3
	s_cbranch_scc1 .LBB0_1347
	s_cmp_lg_u32 s10, 3
	s_cbranch_scc0 .LBB0_1344
	v_lshlrev_b32_e32 v184, 1, v179
	v_lshl_add_u64 v[182:183], s[50:51], 0, v[160:161]
	v_ashrrev_i32_e32 v185, 31, v184
	v_lshl_add_u64 v[182:183], v[182:183], 0, v[184:185]
	global_store_dwordx2 v[182:183], v[168:169], off
	s_and_saveexec_b64 s[68:69], s[8:9]
	s_cbranch_execz .LBB0_1343
	v_ashrrev_i32_e32 v163, 31, v162
	v_lshlrev_b64 v[162:163], 19, v[162:163]
	v_lshl_add_u64 v[162:163], s[52:53], 0, v[162:163]
	v_lshl_add_u64 v[162:163], v[162:163], 0, v[164:165]
	v_ashrrev_i32_e32 v147, 31, v146
	v_lshl_add_u64 v[162:163], v[146:147], 2, v[162:163]
	global_store_dwordx4 v[162:163], v[34:37], off offset:576

.LBB0_1350:
	s_and_b64 vcc, exec, s[68:69]
	v_lshl_add_u64 v[166:167], s[54:55], 0, v[158:159]
	s_cbranch_vccz .LBB0_1314
	v_pk_mul_f32 v[182:183], v[62:63], s[56:57] op_sel_hi:[1,0]
	v_pk_mul_f32 v[168:169], v[64:65], s[56:57] op_sel_hi:[1,0]
	v_cvt_pk_bf16_f32 v182, v182, v183
	v_cvt_pk_bf16_f32 v183, v168, v169
	v_lshl_add_u64 v[168:169], v[148:149], 1, v[166:167]
	global_store_dwordx2 v[168:169], v[182:183], off
	s_and_b64 vcc, exec, s[6:7]
	s_mov_b64 s[68:69], -1
	s_cbranch_vccz .LBB0_1315
.LBB0_1352:
	s_and_b64 vcc, exec, s[68:69]
	s_cbranch_vccz .LBB0_1326
	v_pk_mul_f32 v[182:183], v[58:59], s[56:57] op_sel_hi:[1,0]
	v_pk_mul_f32 v[168:169], v[60:61], s[56:57] op_sel_hi:[1,0]
	v_cvt_pk_bf16_f32 v182, v182, v183
	v_cvt_pk_bf16_f32 v183, v168, v169
	v_lshl_add_u64 v[168:169], v[150:151], 1, v[166:167]
	global_store_dwordx2 v[168:169], v[182:183], off
	s_and_b64 vcc, exec, s[6:7]
	s_mov_b64 s[68:69], -1
	s_cbranch_vccz .LBB0_1327
.LBB0_1354:
	s_and_b64 vcc, exec, s[68:69]
	s_cbranch_vccz .LBB0_1338
	v_pk_mul_f32 v[182:183], v[42:43], s[56:57] op_sel_hi:[1,0]
	v_pk_mul_f32 v[168:169], v[44:45], s[56:57] op_sel_hi:[1,0]
	v_cvt_pk_bf16_f32 v182, v182, v183
	v_cvt_pk_bf16_f32 v183, v168, v169
	v_lshl_add_u64 v[168:169], v[152:153], 1, v[166:167]
	global_store_dwordx2 v[168:169], v[182:183], off
	s_and_b64 vcc, exec, s[6:7]
	s_mov_b64 s[68:69], -1
	s_cbranch_vccz .LBB0_1339
.LBB0_1356:
	s_and_b64 vcc, exec, s[68:69]
	s_cbranch_vccz .LBB0_1358
	v_pk_mul_f32 v[160:161], v[34:35], s[56:57] op_sel_hi:[1,0]
	v_pk_mul_f32 v[158:159], v[36:37], s[56:57] op_sel_hi:[1,0]
	v_cvt_pk_bf16_f32 v160, v160, v161
	v_cvt_pk_bf16_f32 v161, v158, v159
	v_lshl_add_u64 v[158:159], v[156:157], 1, v[166:167]
	global_store_dwordx2 v[158:159], v[160:161], off
.LBB0_1358:
	v_add_u32_e32 v162, 0x90, v154
	v_ashrrev_i32_e32 v138, 10, v162
	v_and_b32_e32 v181, -2, v138
	v_lshrrev_b32_e32 v138, 3, v162
	v_and_b32_e32 v155, 0xfe, v138
	v_and_b32_e32 v138, 0x1fff, v162
	v_ashrrev_i32_e32 v163, 31, v162
	v_cmp_lt_u32_e64 s[8:9], s79, v138
	v_add_u32_e32 v138, 0xffffe200, v138
	v_lshlrev_b64 v[160:161], 9, v[162:163]
	v_lshlrev_b64 v[158:159], 10, v[162:163]
	v_ashrrev_i32_e32 v162, 13, v162
	v_lshlrev_b64 v[164:165], 10, v[138:139]
	s_and_b64 vcc, exec, s[6:7]
	s_mov_b64 s[68:69], -1
	s_cbranch_vccnz .LBB0_1406
	v_cvt_pk_bf16_f32 v166, v54, v55
	v_cvt_pk_bf16_f32 v167, v56, v57
	s_cmp_lt_i32 s10, 3
	s_cbranch_scc1 .LBB0_1367
	s_cmp_lg_u32 s10, 3
	s_cbranch_scc0 .LBB0_1364
	v_lshlrev_b32_e32 v182, 1, v146
	v_lshl_add_u64 v[168:169], s[50:51], 0, v[160:161]
	v_ashrrev_i32_e32 v183, 31, v182
	v_lshl_add_u64 v[168:169], v[168:169], 0, v[182:183]
	global_store_dwordx2 v[168:169], v[166:167], off
	s_and_saveexec_b64 s[68:69], s[8:9]
	s_cbranch_execz .LBB0_1363
	v_ashrrev_i32_e32 v163, 31, v162
	v_lshlrev_b64 v[168:169], 19, v[162:163]
	v_lshl_add_u64 v[168:169], s[52:53], 0, v[168:169]
	v_lshl_add_u64 v[168:169], v[168:169], 0, v[164:165]
	v_ashrrev_i32_e32 v147, 31, v146
	v_lshl_add_u64 v[168:169], v[146:147], 2, v[168:169]
	global_store_dwordx4 v[168:169], v[54:57], off

.LBB0_1371:
	v_cvt_pk_bf16_f32 v168, v50, v51
	v_cvt_pk_bf16_f32 v169, v52, v53
	s_cmp_lt_i32 s10, 3
	s_cbranch_scc1 .LBB0_1379
	s_cmp_lg_u32 s10, 3
	s_cbranch_scc0 .LBB0_1376
	v_lshlrev_b32_e32 v184, 1, v178
	v_lshl_add_u64 v[182:183], s[50:51], 0, v[160:161]
	v_ashrrev_i32_e32 v185, 31, v184
	v_lshl_add_u64 v[182:183], v[182:183], 0, v[184:185]
	global_store_dwordx2 v[182:183], v[168:169], off
	s_and_saveexec_b64 s[68:69], s[8:9]
	s_cbranch_execz .LBB0_1375
	v_ashrrev_i32_e32 v163, 31, v162
	v_lshlrev_b64 v[182:183], 19, v[162:163]
	v_lshl_add_u64 v[182:183], s[52:53], 0, v[182:183]
	v_lshl_add_u64 v[182:183], v[182:183], 0, v[164:165]
	v_ashrrev_i32_e32 v147, 31, v146
	v_lshl_add_u64 v[182:183], v[146:147], 2, v[182:183]
	global_store_dwordx4 v[182:183], v[50:53], off offset:64

.LBB0_1383:
	v_cvt_pk_bf16_f32 v168, v26, v27
	v_cvt_pk_bf16_f32 v169, v28, v29
	s_cmp_lt_i32 s10, 3
	s_cbranch_scc1 .LBB0_1391
	s_cmp_lg_u32 s10, 3
	s_cbranch_scc0 .LBB0_1388
	v_lshlrev_b32_e32 v184, 1, v180
	v_lshl_add_u64 v[182:183], s[50:51], 0, v[160:161]
	v_ashrrev_i32_e32 v185, 31, v184
	v_lshl_add_u64 v[182:183], v[182:183], 0, v[184:185]
	global_store_dwordx2 v[182:183], v[168:169], off
	s_and_saveexec_b64 s[68:69], s[8:9]
	s_cbranch_execz .LBB0_1387
	v_ashrrev_i32_e32 v163, 31, v162
	v_lshlrev_b64 v[182:183], 19, v[162:163]
	v_lshl_add_u64 v[182:183], s[52:53], 0, v[182:183]
	v_lshl_add_u64 v[182:183], v[182:183], 0, v[164:165]
	v_ashrrev_i32_e32 v147, 31, v146
	v_lshl_add_u64 v[182:183], v[146:147], 2, v[182:183]
	global_store_dwordx4 v[182:183], v[26:29], off offset:512

.LBB0_1395:
	v_cvt_pk_bf16_f32 v168, v18, v19
	v_cvt_pk_bf16_f32 v169, v20, v21
	s_cmp_lt_i32 s10, 3
	s_cbranch_scc1 .LBB0_1403
	s_cmp_lg_u32 s10, 3
	s_cbranch_scc0 .LBB0_1400
	v_lshlrev_b32_e32 v184, 1, v179
	v_lshl_add_u64 v[182:183], s[50:51], 0, v[160:161]
	v_ashrrev_i32_e32 v185, 31, v184
	v_lshl_add_u64 v[182:183], v[182:183], 0, v[184:185]
	global_store_dwordx2 v[182:183], v[168:169], off
	s_and_saveexec_b64 s[68:69], s[8:9]
	s_cbranch_execz .LBB0_1399
	v_ashrrev_i32_e32 v163, 31, v162
	v_lshlrev_b64 v[162:163], 19, v[162:163]
	v_lshl_add_u64 v[162:163], s[52:53], 0, v[162:163]
	v_lshl_add_u64 v[162:163], v[162:163], 0, v[164:165]
	v_ashrrev_i32_e32 v147, 31, v146
	v_lshl_add_u64 v[162:163], v[146:147], 2, v[162:163]
	global_store_dwordx4 v[162:163], v[18:21], off offset:576

.LBB0_1406:
	s_and_b64 vcc, exec, s[68:69]
	v_lshl_add_u64 v[166:167], s[54:55], 0, v[158:159]
	s_cbranch_vccz .LBB0_1370
	v_pk_mul_f32 v[182:183], v[54:55], s[56:57] op_sel_hi:[1,0]
	v_pk_mul_f32 v[168:169], v[56:57], s[56:57] op_sel_hi:[1,0]
	v_cvt_pk_bf16_f32 v182, v182, v183
	v_cvt_pk_bf16_f32 v183, v168, v169
	v_lshl_add_u64 v[168:169], v[148:149], 1, v[166:167]
	global_store_dwordx2 v[168:169], v[182:183], off
	s_and_b64 vcc, exec, s[6:7]
	s_mov_b64 s[68:69], -1
	s_cbranch_vccz .LBB0_1371
.LBB0_1408:
	s_and_b64 vcc, exec, s[68:69]
	s_cbranch_vccz .LBB0_1382
	v_pk_mul_f32 v[182:183], v[50:51], s[56:57] op_sel_hi:[1,0]
	v_pk_mul_f32 v[168:169], v[52:53], s[56:57] op_sel_hi:[1,0]
	v_cvt_pk_bf16_f32 v182, v182, v183
	v_cvt_pk_bf16_f32 v183, v168, v169
	v_lshl_add_u64 v[168:169], v[150:151], 1, v[166:167]
	global_store_dwordx2 v[168:169], v[182:183], off
	s_and_b64 vcc, exec, s[6:7]
	s_mov_b64 s[68:69], -1
	s_cbranch_vccz .LBB0_1383
.LBB0_1410:
	s_and_b64 vcc, exec, s[68:69]
	s_cbranch_vccz .LBB0_1394
	v_pk_mul_f32 v[182:183], v[26:27], s[56:57] op_sel_hi:[1,0]
	v_pk_mul_f32 v[168:169], v[28:29], s[56:57] op_sel_hi:[1,0]
	v_cvt_pk_bf16_f32 v182, v182, v183
	v_cvt_pk_bf16_f32 v183, v168, v169
	v_lshl_add_u64 v[168:169], v[152:153], 1, v[166:167]
	global_store_dwordx2 v[168:169], v[182:183], off
	s_and_b64 vcc, exec, s[6:7]
	s_mov_b64 s[68:69], -1
	s_cbranch_vccz .LBB0_1395
.LBB0_1412:
	s_and_b64 vcc, exec, s[68:69]
	s_cbranch_vccz .LBB0_1414
	v_pk_mul_f32 v[160:161], v[18:19], s[56:57] op_sel_hi:[1,0]
	v_pk_mul_f32 v[158:159], v[20:21], s[56:57] op_sel_hi:[1,0]
	v_cvt_pk_bf16_f32 v160, v160, v161
	v_cvt_pk_bf16_f32 v161, v158, v159
	v_lshl_add_u64 v[158:159], v[156:157], 1, v[166:167]
	global_store_dwordx2 v[158:159], v[160:161], off
.LBB0_1414:
	v_add_u32_e32 v162, 0xa0, v154
	v_ashrrev_i32_e32 v138, 10, v162
	v_and_b32_e32 v181, -2, v138
	v_lshrrev_b32_e32 v138, 3, v162
	v_and_b32_e32 v155, 0xfe, v138
	v_and_b32_e32 v138, 0x1fff, v162
	v_ashrrev_i32_e32 v163, 31, v162
	v_cmp_lt_u32_e64 s[8:9], s79, v138
	v_add_u32_e32 v138, 0xffffe200, v138
	v_lshlrev_b64 v[160:161], 9, v[162:163]
	v_lshlrev_b64 v[158:159], 10, v[162:163]
	v_ashrrev_i32_e32 v162, 13, v162
	v_lshlrev_b64 v[164:165], 10, v[138:139]
	s_and_b64 vcc, exec, s[6:7]
	s_mov_b64 s[68:69], -1
	s_cbranch_vccnz .LBB0_1462
	v_cvt_pk_bf16_f32 v166, v46, v47
	v_cvt_pk_bf16_f32 v167, v48, v49
	s_cmp_lt_i32 s10, 3
	s_cbranch_scc1 .LBB0_1423
	s_cmp_lg_u32 s10, 3
	s_cbranch_scc0 .LBB0_1420
	v_lshlrev_b32_e32 v182, 1, v146
	v_lshl_add_u64 v[168:169], s[50:51], 0, v[160:161]
	v_ashrrev_i32_e32 v183, 31, v182
	v_lshl_add_u64 v[168:169], v[168:169], 0, v[182:183]
	global_store_dwordx2 v[168:169], v[166:167], off
	s_and_saveexec_b64 s[68:69], s[8:9]
	s_cbranch_execz .LBB0_1419
	v_ashrrev_i32_e32 v163, 31, v162
	v_lshlrev_b64 v[168:169], 19, v[162:163]
	v_lshl_add_u64 v[168:169], s[52:53], 0, v[168:169]
	v_lshl_add_u64 v[168:169], v[168:169], 0, v[164:165]
	v_ashrrev_i32_e32 v147, 31, v146
	v_lshl_add_u64 v[168:169], v[146:147], 2, v[168:169]
	global_store_dwordx4 v[168:169], v[46:49], off

.LBB0_1427:
	v_cvt_pk_bf16_f32 v168, v38, v39
	v_cvt_pk_bf16_f32 v169, v40, v41
	s_cmp_lt_i32 s10, 3
	s_cbranch_scc1 .LBB0_1435
	s_cmp_lg_u32 s10, 3
	s_cbranch_scc0 .LBB0_1432
	v_lshlrev_b32_e32 v184, 1, v178
	v_lshl_add_u64 v[182:183], s[50:51], 0, v[160:161]
	v_ashrrev_i32_e32 v185, 31, v184
	v_lshl_add_u64 v[182:183], v[182:183], 0, v[184:185]
	global_store_dwordx2 v[182:183], v[168:169], off
	s_and_saveexec_b64 s[68:69], s[8:9]
	s_cbranch_execz .LBB0_1431
	v_ashrrev_i32_e32 v163, 31, v162
	v_lshlrev_b64 v[182:183], 19, v[162:163]
	v_lshl_add_u64 v[182:183], s[52:53], 0, v[182:183]
	v_lshl_add_u64 v[182:183], v[182:183], 0, v[164:165]
	v_ashrrev_i32_e32 v147, 31, v146
	v_lshl_add_u64 v[182:183], v[146:147], 2, v[182:183]
	global_store_dwordx4 v[182:183], v[38:41], off offset:64

.LBB0_1439:
	v_cvt_pk_bf16_f32 v168, v14, v15
	v_cvt_pk_bf16_f32 v169, v16, v17
	s_cmp_lt_i32 s10, 3
	s_cbranch_scc1 .LBB0_1447
	s_cmp_lg_u32 s10, 3
	s_cbranch_scc0 .LBB0_1444
	v_lshlrev_b32_e32 v184, 1, v180
	v_lshl_add_u64 v[182:183], s[50:51], 0, v[160:161]
	v_ashrrev_i32_e32 v185, 31, v184
	v_lshl_add_u64 v[182:183], v[182:183], 0, v[184:185]
	global_store_dwordx2 v[182:183], v[168:169], off
	s_and_saveexec_b64 s[68:69], s[8:9]
	s_cbranch_execz .LBB0_1443
	v_ashrrev_i32_e32 v163, 31, v162
	v_lshlrev_b64 v[182:183], 19, v[162:163]
	v_lshl_add_u64 v[182:183], s[52:53], 0, v[182:183]
	v_lshl_add_u64 v[182:183], v[182:183], 0, v[164:165]
	v_ashrrev_i32_e32 v147, 31, v146
	v_lshl_add_u64 v[182:183], v[146:147], 2, v[182:183]
	global_store_dwordx4 v[182:183], v[14:17], off offset:512

.LBB0_1451:
	v_cvt_pk_bf16_f32 v168, v10, v11
	v_cvt_pk_bf16_f32 v169, v12, v13
	s_cmp_lt_i32 s10, 3
	s_cbranch_scc1 .LBB0_1459
	s_cmp_lg_u32 s10, 3
	s_cbranch_scc0 .LBB0_1456
	v_lshlrev_b32_e32 v184, 1, v179
	v_lshl_add_u64 v[182:183], s[50:51], 0, v[160:161]
	v_ashrrev_i32_e32 v185, 31, v184
	v_lshl_add_u64 v[182:183], v[182:183], 0, v[184:185]
	global_store_dwordx2 v[182:183], v[168:169], off
	s_and_saveexec_b64 s[68:69], s[8:9]
	s_cbranch_execz .LBB0_1455
	v_ashrrev_i32_e32 v163, 31, v162
	v_lshlrev_b64 v[162:163], 19, v[162:163]
	v_lshl_add_u64 v[162:163], s[52:53], 0, v[162:163]
	v_lshl_add_u64 v[162:163], v[162:163], 0, v[164:165]
	v_ashrrev_i32_e32 v147, 31, v146
	v_lshl_add_u64 v[162:163], v[146:147], 2, v[162:163]
	global_store_dwordx4 v[162:163], v[10:13], off offset:576

.LBB0_1462:
	s_and_b64 vcc, exec, s[68:69]
	v_lshl_add_u64 v[166:167], s[54:55], 0, v[158:159]
	s_cbranch_vccz .LBB0_1426
	v_pk_mul_f32 v[182:183], v[46:47], s[56:57] op_sel_hi:[1,0]
	v_pk_mul_f32 v[168:169], v[48:49], s[56:57] op_sel_hi:[1,0]
	v_cvt_pk_bf16_f32 v182, v182, v183
	v_cvt_pk_bf16_f32 v183, v168, v169
	v_lshl_add_u64 v[168:169], v[148:149], 1, v[166:167]
	global_store_dwordx2 v[168:169], v[182:183], off
	s_and_b64 vcc, exec, s[6:7]
	s_mov_b64 s[68:69], -1
	s_cbranch_vccz .LBB0_1427
.LBB0_1464:
	s_and_b64 vcc, exec, s[68:69]
	s_cbranch_vccz .LBB0_1438
	v_pk_mul_f32 v[182:183], v[38:39], s[56:57] op_sel_hi:[1,0]
	v_pk_mul_f32 v[168:169], v[40:41], s[56:57] op_sel_hi:[1,0]
	v_cvt_pk_bf16_f32 v182, v182, v183
	v_cvt_pk_bf16_f32 v183, v168, v169
	v_lshl_add_u64 v[168:169], v[150:151], 1, v[166:167]
	global_store_dwordx2 v[168:169], v[182:183], off
	s_and_b64 vcc, exec, s[6:7]
	s_mov_b64 s[68:69], -1
	s_cbranch_vccz .LBB0_1439
.LBB0_1466:
	s_and_b64 vcc, exec, s[68:69]
	s_cbranch_vccz .LBB0_1450
	v_pk_mul_f32 v[182:183], v[14:15], s[56:57] op_sel_hi:[1,0]
	v_pk_mul_f32 v[168:169], v[16:17], s[56:57] op_sel_hi:[1,0]
	v_cvt_pk_bf16_f32 v182, v182, v183
	v_cvt_pk_bf16_f32 v183, v168, v169
	v_lshl_add_u64 v[168:169], v[152:153], 1, v[166:167]
	global_store_dwordx2 v[168:169], v[182:183], off
	s_and_b64 vcc, exec, s[6:7]
	s_mov_b64 s[68:69], -1
	s_cbranch_vccz .LBB0_1451
.LBB0_1468:
	s_and_b64 vcc, exec, s[68:69]
	s_cbranch_vccz .LBB0_1470
	v_pk_mul_f32 v[160:161], v[10:11], s[56:57] op_sel_hi:[1,0]
	v_pk_mul_f32 v[158:159], v[12:13], s[56:57] op_sel_hi:[1,0]
	v_cvt_pk_bf16_f32 v160, v160, v161
	v_cvt_pk_bf16_f32 v161, v158, v159
	v_lshl_add_u64 v[158:159], v[156:157], 1, v[166:167]
	global_store_dwordx2 v[158:159], v[160:161], off
.LBB0_1470:
	v_add_u32_e32 v160, 0xb0, v154
	v_ashrrev_i32_e32 v138, 10, v160
	v_and_b32_e32 v169, -2, v138
	v_lshrrev_b32_e32 v138, 3, v160
	v_and_b32_e32 v168, 0xfe, v138
	v_and_b32_e32 v138, 0x1fff, v160
	v_ashrrev_i32_e32 v161, 31, v160
	v_cmp_lt_u32_e64 s[8:9], s79, v138
	v_add_u32_e32 v138, 0xffffe200, v138
	v_lshlrev_b64 v[158:159], 9, v[160:161]
	v_lshlrev_b64 v[154:155], 10, v[160:161]
	v_ashrrev_i32_e32 v160, 13, v160
	v_lshlrev_b64 v[162:163], 10, v[138:139]
	s_and_b64 vcc, exec, s[6:7]
	s_mov_b64 s[68:69], -1
	s_cbranch_vccnz .LBB0_1518
	v_cvt_pk_bf16_f32 v164, v30, v31
	v_cvt_pk_bf16_f32 v165, v32, v33
	s_cmp_lt_i32 s10, 3
	s_cbranch_scc1 .LBB0_1479
	v_lshlrev_b32_e32 v166, 1, v146
	s_cmp_lg_u32 s10, 3
	v_ashrrev_i32_e32 v167, 31, v166
	s_cbranch_scc0 .LBB0_1476
	v_lshl_add_u64 v[182:183], s[50:51], 0, v[158:159]
	v_lshl_add_u64 v[182:183], v[182:183], 0, v[166:167]
	global_store_dwordx2 v[182:183], v[164:165], off
	s_and_saveexec_b64 s[68:69], s[8:9]
	s_cbranch_execz .LBB0_1475
	v_ashrrev_i32_e32 v161, 31, v160
	v_lshlrev_b64 v[182:183], 19, v[160:161]
	v_lshl_add_u64 v[182:183], s[52:53], 0, v[182:183]
	v_lshl_add_u64 v[182:183], v[182:183], 0, v[162:163]
	v_ashrrev_i32_e32 v147, 31, v146
	v_lshl_add_u64 v[182:183], v[146:147], 2, v[182:183]
	global_store_dwordx4 v[182:183], v[30:33], off

.LBB0_1483:
	v_cvt_pk_bf16_f32 v148, v22, v23
	v_cvt_pk_bf16_f32 v149, v24, v25
	s_cmp_lt_i32 s10, 3
	s_cbranch_scc1 .LBB0_1491
	v_lshlrev_b32_e32 v166, 1, v178
	s_cmp_lg_u32 s10, 3
	v_ashrrev_i32_e32 v167, 31, v166
	s_cbranch_scc0 .LBB0_1488
	v_lshl_add_u64 v[182:183], s[50:51], 0, v[158:159]
	v_lshl_add_u64 v[182:183], v[182:183], 0, v[166:167]
	global_store_dwordx2 v[182:183], v[148:149], off
	s_and_saveexec_b64 s[68:69], s[8:9]
	s_cbranch_execz .LBB0_1487
	v_ashrrev_i32_e32 v161, 31, v160
	v_lshlrev_b64 v[182:183], 19, v[160:161]
	v_lshl_add_u64 v[182:183], s[52:53], 0, v[182:183]
	v_lshl_add_u64 v[182:183], v[182:183], 0, v[162:163]
	v_ashrrev_i32_e32 v147, 31, v146
	v_lshl_add_u64 v[182:183], v[146:147], 2, v[182:183]
	global_store_dwordx4 v[182:183], v[22:25], off offset:64

.LBB0_1495:
	v_cvt_pk_bf16_f32 v148, v6, v7
	v_cvt_pk_bf16_f32 v149, v8, v9
	s_cmp_lt_i32 s10, 3
	s_cbranch_scc1 .LBB0_1503
	v_lshlrev_b32_e32 v150, 1, v180
	s_cmp_lg_u32 s10, 3
	v_ashrrev_i32_e32 v151, 31, v150
	s_cbranch_scc0 .LBB0_1500
	v_lshl_add_u64 v[166:167], s[50:51], 0, v[158:159]
	v_lshl_add_u64 v[166:167], v[166:167], 0, v[150:151]
	global_store_dwordx2 v[166:167], v[148:149], off
	s_and_saveexec_b64 s[68:69], s[8:9]
	s_cbranch_execz .LBB0_1499
	v_ashrrev_i32_e32 v161, 31, v160
	v_lshlrev_b64 v[166:167], 19, v[160:161]
	v_lshl_add_u64 v[166:167], s[52:53], 0, v[166:167]
	v_lshl_add_u64 v[166:167], v[166:167], 0, v[162:163]
	v_ashrrev_i32_e32 v147, 31, v146
	v_lshl_add_u64 v[166:167], v[146:147], 2, v[166:167]
	global_store_dwordx4 v[166:167], v[6:9], off offset:512

.LBB0_1507:
	v_cvt_pk_bf16_f32 v148, v2, v3
	v_cvt_pk_bf16_f32 v149, v4, v5
	s_cmp_lt_i32 s10, 3
	s_cbranch_scc1 .LBB0_1515
	v_lshlrev_b32_e32 v150, 1, v179
	s_cmp_lg_u32 s10, 3
	v_ashrrev_i32_e32 v151, 31, v150
	s_cbranch_scc0 .LBB0_1512
	v_lshl_add_u64 v[152:153], s[50:51], 0, v[158:159]
	v_lshl_add_u64 v[152:153], v[152:153], 0, v[150:151]
	global_store_dwordx2 v[152:153], v[148:149], off
	s_and_saveexec_b64 s[6:7], s[8:9]
	s_cbranch_execz .LBB0_1511
	v_ashrrev_i32_e32 v161, 31, v160
	v_lshlrev_b64 v[152:153], 19, v[160:161]
	v_lshl_add_u64 v[152:153], s[52:53], 0, v[152:153]
	v_lshl_add_u64 v[152:153], v[152:153], 0, v[162:163]
	v_ashrrev_i32_e32 v147, 31, v146
	v_lshl_add_u64 v[152:153], v[146:147], 2, v[152:153]
	global_store_dwordx4 v[152:153], v[2:5], off offset:576

.LBB0_1518:
	s_and_b64 vcc, exec, s[68:69]
	v_lshl_add_u64 v[164:165], s[54:55], 0, v[154:155]
	s_cbranch_vccz .LBB0_1482
	v_pk_mul_f32 v[182:183], v[30:31], s[56:57] op_sel_hi:[1,0]
	v_pk_mul_f32 v[166:167], v[32:33], s[56:57] op_sel_hi:[1,0]
	v_cvt_pk_bf16_f32 v182, v182, v183
	v_cvt_pk_bf16_f32 v183, v166, v167
	v_lshl_add_u64 v[148:149], v[148:149], 1, v[164:165]
	global_store_dwordx2 v[148:149], v[182:183], off
	s_and_b64 vcc, exec, s[6:7]
	s_mov_b64 s[68:69], -1
	s_cbranch_vccz .LBB0_1483
.LBB0_1520:
	s_and_b64 vcc, exec, s[68:69]
	s_cbranch_vccz .LBB0_1494
	v_pk_mul_f32 v[166:167], v[22:23], s[56:57] op_sel_hi:[1,0]
	v_pk_mul_f32 v[148:149], v[24:25], s[56:57] op_sel_hi:[1,0]
	v_cvt_pk_bf16_f32 v166, v166, v167
	v_cvt_pk_bf16_f32 v167, v148, v149
	v_lshl_add_u64 v[148:149], v[150:151], 1, v[164:165]
	global_store_dwordx2 v[148:149], v[166:167], off
	s_and_b64 vcc, exec, s[6:7]
	s_mov_b64 s[68:69], -1
	s_cbranch_vccz .LBB0_1495
.LBB0_1522:
	s_and_b64 vcc, exec, s[68:69]
	s_cbranch_vccz .LBB0_1506
	v_pk_mul_f32 v[150:151], v[6:7], s[56:57] op_sel_hi:[1,0]
	v_pk_mul_f32 v[148:149], v[8:9], s[56:57] op_sel_hi:[1,0]
	v_cvt_pk_bf16_f32 v150, v150, v151
	v_cvt_pk_bf16_f32 v151, v148, v149
	v_lshl_add_u64 v[148:149], v[152:153], 1, v[164:165]
	global_store_dwordx2 v[148:149], v[150:151], off
	s_and_b64 vcc, exec, s[6:7]
	s_mov_b64 s[6:7], -1
	s_cbranch_vccz .LBB0_1507
.LBB0_1524:
	s_and_b64 vcc, exec, s[6:7]
	s_cbranch_vccz .LBB0_1526
	v_pk_mul_f32 v[148:149], v[2:3], s[56:57] op_sel_hi:[1,0]
	v_pk_mul_f32 v[146:147], v[4:5], s[56:57] op_sel_hi:[1,0]
	v_cvt_pk_bf16_f32 v148, v148, v149
	v_cvt_pk_bf16_f32 v149, v146, v147
	v_lshl_add_u64 v[146:147], v[156:157], 1, v[164:165]
	global_store_dwordx2 v[146:147], v[148:149], off

.LBB0_1594:
	s_waitcnt vmcnt(0)
	v_cvt_pk_bf16_f32 v208, v130, v131
	v_cvt_pk_bf16_f32 v209, v132, v133
	v_cvt_pk_bf16_f32 v210, v134, v135
	v_cvt_pk_bf16_f32 v211, v136, v137
	s_waitcnt lgkmcnt(0)
	s_barrier
	ds_write2st64_b64 v178, v[208:209], v[210:211] offset1:9
	v_cvt_pk_bf16_f32 v208, v138, v139
	v_cvt_pk_bf16_f32 v209, v140, v141
	v_cvt_pk_bf16_f32 v210, v142, v143
	v_cvt_pk_bf16_f32 v211, v144, v145
	ds_write2st64_b64 v178, v[208:209], v[210:211] offset0:18 offset1:27
	v_cvt_pk_bf16_f32 v208, v146, v147
	v_cvt_pk_bf16_f32 v209, v148, v149
	v_cvt_pk_bf16_f32 v210, v150, v151
	v_cvt_pk_bf16_f32 v211, v152, v153
	ds_write2st64_b64 v178, v[208:209], v[210:211] offset0:36 offset1:45
	v_cvt_pk_bf16_f32 v208, v154, v155
	v_cvt_pk_bf16_f32 v209, v156, v157
	v_cvt_pk_bf16_f32 v210, v158, v159
	v_cvt_pk_bf16_f32 v211, v160, v161
	s_cmpk_eq_i32 s8, 0x3c00
	ds_write2st64_b64 v178, v[208:209], v[210:211] offset0:54 offset1:63
	ds_write_b128 v204, v[162:165] offset:36864
	ds_write_b128 v204, v[166:169] offset:46080
	ds_write_b128 v204, v[170:173] offset:55296
	ds_write_b128 v204, v[174:177] offset:64512
	s_waitcnt lgkmcnt(0)
	s_barrier
	s_cbranch_scc1 .LBB0_1593
	v_add_co_u32_e32 v162, vcc, 0xfffa0000, v184
	v_lshl_add_u64 v[130:131], v[200:201], 0, s[8:9]
	s_nop 0
	v_addc_co_u32_e32 v163, vcc, -1, v185, vcc
	v_add_co_u32_e32 v166, vcc, 0xfffc0000, v184
	v_lshl_add_u64 v[134:135], v[198:199], 0, s[8:9]
	s_nop 0
	v_addc_co_u32_e32 v167, vcc, -1, v185, vcc
	v_add_co_u32_e32 v170, vcc, 0xfffe0000, v184
	v_lshl_add_u64 v[138:139], v[196:197], 0, s[8:9]
	v_lshl_add_u64 v[142:143], v[194:195], 0, s[8:9]
	v_lshl_add_u64 v[146:147], v[192:193], 0, s[8:9]
	v_lshl_add_u64 v[150:151], v[190:191], 0, s[8:9]
	v_lshl_add_u64 v[154:155], v[188:189], 0, s[8:9]
	v_lshl_add_u64 v[158:159], v[186:187], 0, s[8:9]
	v_addc_co_u32_e32 v171, vcc, -1, v185, vcc
	global_load_dwordx4 v[130:133], v[130:131], off nt
	s_nop 0
	global_load_dwordx4 v[134:137], v[134:135], off nt
	s_nop 0
	global_load_dwordx4 v[138:141], v[138:139], off nt
	s_nop 0
	global_load_dwordx4 v[142:145], v[142:143], off nt
	s_nop 0
	global_load_dwordx4 v[146:149], v[146:147], off nt
	s_nop 0
	global_load_dwordx4 v[150:153], v[150:151], off nt
	s_nop 0
	global_load_dwordx4 v[154:157], v[154:155], off nt
	s_nop 0
	global_load_dwordx4 v[158:161], v[158:159], off nt
	s_nop 0
	global_load_dwordx4 v[162:165], v[162:163], off
	s_nop 0
	global_load_dwordx4 v[166:169], v[166:167], off
	s_nop 0
	global_load_dwordx4 v[170:173], v[170:171], off
	s_nop 0
	global_load_dwordx4 v[174:177], v[184:185], off
	s_branch .LBB0_1593

.LBB0_1721:
	s_or_b64 exec, exec, s[14:15]
	s_ashr_i32 s13, s40, 1
	s_cmp_lt_i32 s13, 8
	s_cselect_b64 s[72:73], -1, 0
	s_cmp_gt_i32 s13, 7
	s_cselect_b64 s[14:15], -1, 0
	s_and_b32 s17, s13, 3
	s_cmp_eq_u32 s17, 3
	s_cselect_b64 s[26:27], -1, 0
	v_lshl_add_u32 v2, v132, 2, s96
	s_or_b64 s[14:15], s[14:15], s[26:27]
	s_waitcnt lgkmcnt(0)
	s_barrier
	ds_read2st64_b32 v[18:19], v2 offset0:128 offset1:129
	s_xor_b64 s[68:69], s[14:15], -1
	s_cmp_lt_i32 s3, 8
	s_cselect_b64 s[26:27], -1, 0
	s_or_b64 s[94:95], s[68:69], s[26:27]
	s_mov_b64 s[92:93], -1
	v_mov_b32_e32 v2, 0
	s_and_b64 vcc, exec, s[94:95]
	v_mov_b32_e32 v3, 0
	s_cbranch_vccz .LBB0_1723
	s_waitcnt lgkmcnt(0)
	v_pk_add_f32 v[2:3], v[20:21], v[18:19]
	s_nop 0
	v_pk_add_f32 v[2:3], v[22:23], v[2:3]
	s_nop 0
	v_mul_f32_e32 v4, 0x3d372713, v2
	v_mul_f32_e32 v5, 0x3d372713, v3
	v_mul_f32_e32 v4, v2, v4
	v_mul_f32_e32 v5, v3, v5
	v_fma_f32 v4, v2, v4, v2
	v_fma_f32 v5, v3, v5, v3
	v_mul_f32_e32 v4, 0x3f4c422a, v4
	v_mul_f32_e32 v5, 0x3f4c422a, v5
	v_mul_f32_e32 v4, -2.0, v4
	v_mul_f32_e32 v5, -2.0, v5
	v_mul_f32_e32 v4, 0x3fb8aa3b, v4
	v_mul_f32_e32 v5, 0x3fb8aa3b, v5
	v_exp_f32_e32 v4, v4
	v_exp_f32_e32 v5, v5
	s_nop 0
	v_pk_add_f32 v[4:5], v[4:5], 1.0 op_sel_hi:[1,0]
	s_nop 0
	s_nop 0
	v_rcp_f32_e32 v6, v4
	s_nop 0
	v_mul_f32_e32 v2, v2, v6
	v_rcp_f32_e32 v4, v5
	s_nop 0
	v_mul_f32_e32 v3, v3, v4
.LBB0_1723:
	s_mul_i32 s9, s3, 0x2040
	s_add_i32 s7, s96, s9
	v_lshl_add_u32 v75, v132, 2, s7
	s_andn2_b64 vcc, exec, s[94:95]
	ds_write2st64_b32 v75, v2, v3 offset0:130 offset1:131
	s_cbranch_vccnz .LBB0_1725
	s_waitcnt lgkmcnt(1)
	v_add_f32_e32 v2, v107, v18
	v_add_f32_e32 v2, v108, v2
	v_mul_f32_e32 v3, 0x3d372713, v2
	v_mul_f32_e32 v3, v2, v3
	v_fma_f32 v3, v2, v3, v2
	v_mul_f32_e32 v3, 0x3f4c422a, v3
	v_mul_f32_e32 v3, -2.0, v3
	v_mul_f32_e32 v3, 0x3fb8aa3b, v3
	v_exp_f32_e32 v3, v3
	v_add_f32_e32 v4, v105, v19
	v_add_f32_e32 v4, v106, v4
	v_mul_f32_e32 v7, 0x3d372713, v4
	v_add_f32_e32 v3, 1.0, v3
	v_mul_f32_e32 v7, v4, v7
	v_fma_f32 v7, v4, v7, v4
	v_mul_f32_e32 v7, 0x3f4c422a, v7
	v_mul_f32_e32 v7, -2.0, v7
	v_mul_f32_e32 v7, 0x3fb8aa3b, v7
	v_exp_f32_e32 v7, v7
	s_nop 0
	v_add_f32_e32 v7, 1.0, v7
	v_rcp_f32_e32 v5, v3
	s_nop 0
	v_mul_f32_e32 v2, v2, v5
	ds_write_b32 v75, v2 offset:33796
	v_rcp_f32_e32 v2, v7
	s_nop 0
	v_mul_f32_e32 v2, v4, v2
	s_mov_b64 s[92:93], 0

.LBB0_1727:
	s_load_dwordx4 s[92:95], s[0:1], 0xd0
	s_cmpk_gt_i32 s90, 0xfd
	s_cselect_b64 s[26:27], -1, 0
	s_and_b64 s[26:27], s[14:15], s[26:27]
	s_and_b64 vcc, exec, s[26:27]
	ds_write_b32 v75, v2 offset:34052
	s_cbranch_vccnz .LBB0_1729
	s_waitcnt lgkmcnt(0)
	v_add_f32_e32 v2, v103, v18
	v_add_f32_e32 v2, v104, v2
	v_mul_f32_e32 v3, 0x3d372713, v2
	v_mul_f32_e32 v3, v2, v3
	v_fma_f32 v3, v2, v3, v2
	v_mul_f32_e32 v3, 0x3f4c422a, v3
	v_mul_f32_e32 v3, -2.0, v3
	v_mul_f32_e32 v3, 0x3fb8aa3b, v3
	v_exp_f32_e32 v3, v3
	v_add_f32_e32 v4, v100, v19
	v_add_f32_e32 v4, v102, v4
	v_mul_f32_e32 v7, 0x3d372713, v4
	v_add_f32_e32 v3, 1.0, v3
	v_mul_f32_e32 v7, v4, v7
	v_fma_f32 v7, v4, v7, v4
	v_mul_f32_e32 v7, 0x3f4c422a, v7
	v_mul_f32_e32 v7, -2.0, v7
	v_mul_f32_e32 v7, 0x3fb8aa3b, v7
	v_exp_f32_e32 v7, v7
	s_nop 0
	v_add_f32_e32 v7, 1.0, v7
	v_rcp_f32_e32 v5, v3
	s_nop 0
	v_mul_f32_e32 v2, v2, v5
	ds_write_b32 v75, v2 offset:34312
	v_rcp_f32_e32 v2, v7
	s_nop 0
	v_mul_f32_e32 v2, v4, v2
	s_cbranch_execz .LBB0_1730
	s_branch .LBB0_1731

.LBB0_1731:
	s_load_dwordx2 s[90:91], s[0:1], 0xe0
	s_cmpk_gt_i32 s88, 0xfd
	s_cselect_b64 s[26:27], -1, 0
	s_and_b64 s[26:27], s[14:15], s[26:27]
	s_and_b64 vcc, exec, s[26:27]
	ds_write_b32 v75, v2 offset:34568
	s_cbranch_vccnz .LBB0_1733
	s_waitcnt lgkmcnt(0)
	v_add_f32_e32 v2, v98, v18
	v_add_f32_e32 v2, v101, v2
	v_mul_f32_e32 v3, 0x3d372713, v2
	v_mul_f32_e32 v3, v2, v3
	v_fma_f32 v3, v2, v3, v2
	v_mul_f32_e32 v3, 0x3f4c422a, v3
	v_mul_f32_e32 v3, -2.0, v3
	v_mul_f32_e32 v3, 0x3fb8aa3b, v3
	v_exp_f32_e32 v3, v3
	v_add_f32_e32 v4, v97, v19
	v_add_f32_e32 v4, v99, v4
	v_mul_f32_e32 v7, 0x3d372713, v4
	v_add_f32_e32 v3, 1.0, v3
	v_mul_f32_e32 v7, v4, v7
	v_fma_f32 v7, v4, v7, v4
	v_mul_f32_e32 v7, 0x3f4c422a, v7
	v_mul_f32_e32 v7, -2.0, v7
	v_mul_f32_e32 v7, 0x3fb8aa3b, v7
	v_exp_f32_e32 v7, v7
	s_nop 0
	v_add_f32_e32 v7, 1.0, v7
	v_rcp_f32_e32 v5, v3
	s_nop 0
	v_mul_f32_e32 v2, v2, v5
	ds_write_b32 v75, v2 offset:34828
	v_rcp_f32_e32 v2, v7
	s_nop 0
	v_mul_f32_e32 v2, v4, v2
	s_cbranch_execz .LBB0_1734
	s_branch .LBB0_1735

.LBB0_1735:
	s_cmpk_gt_i32 s86, 0xfd
	s_cselect_b64 s[26:27], -1, 0
	s_and_b64 s[26:27], s[14:15], s[26:27]
	s_and_b64 vcc, exec, s[26:27]
	ds_write_b32 v75, v2 offset:35084
	s_cbranch_vccnz .LBB0_1737
	s_waitcnt lgkmcnt(0)
	v_add_f32_e32 v2, v94, v18
	v_add_f32_e32 v2, v96, v2
	v_mul_f32_e32 v3, 0x3d372713, v2
	v_mul_f32_e32 v3, v2, v3
	v_fma_f32 v3, v2, v3, v2
	v_mul_f32_e32 v3, 0x3f4c422a, v3
	v_mul_f32_e32 v3, -2.0, v3
	v_mul_f32_e32 v3, 0x3fb8aa3b, v3
	v_exp_f32_e32 v3, v3
	v_add_f32_e32 v4, v93, v19
	v_add_f32_e32 v4, v95, v4
	v_mul_f32_e32 v7, 0x3d372713, v4
	v_add_f32_e32 v3, 1.0, v3
	v_mul_f32_e32 v7, v4, v7
	v_fma_f32 v7, v4, v7, v4
	v_mul_f32_e32 v7, 0x3f4c422a, v7
	v_mul_f32_e32 v7, -2.0, v7
	v_mul_f32_e32 v7, 0x3fb8aa3b, v7
	v_exp_f32_e32 v7, v7
	s_nop 0
	v_add_f32_e32 v7, 1.0, v7
	v_rcp_f32_e32 v5, v3
	s_nop 0
	v_mul_f32_e32 v2, v2, v5
	ds_write_b32 v75, v2 offset:35344
	v_rcp_f32_e32 v2, v7
	s_nop 0
	v_mul_f32_e32 v2, v4, v2
	s_cbranch_execz .LBB0_1738
	s_branch .LBB0_1739

.LBB0_1739:
	s_cmpk_gt_i32 s84, 0xfd
	s_cselect_b64 s[26:27], -1, 0
	s_and_b64 s[26:27], s[14:15], s[26:27]
	s_and_b64 vcc, exec, s[26:27]
	ds_write_b32 v75, v2 offset:35600
	s_cbranch_vccnz .LBB0_1741
	s_waitcnt lgkmcnt(0)
	v_add_f32_e32 v2, v90, v18
	v_add_f32_e32 v2, v92, v2
	v_mul_f32_e32 v3, 0x3d372713, v2
	v_mul_f32_e32 v3, v2, v3
	v_fma_f32 v3, v2, v3, v2
	v_mul_f32_e32 v3, 0x3f4c422a, v3
	v_mul_f32_e32 v3, -2.0, v3
	v_mul_f32_e32 v3, 0x3fb8aa3b, v3
	v_exp_f32_e32 v3, v3
	v_add_f32_e32 v4, v89, v19
	v_add_f32_e32 v4, v91, v4
	v_mul_f32_e32 v7, 0x3d372713, v4
	v_add_f32_e32 v3, 1.0, v3
	v_mul_f32_e32 v7, v4, v7
	v_fma_f32 v7, v4, v7, v4
	v_mul_f32_e32 v7, 0x3f4c422a, v7
	v_mul_f32_e32 v7, -2.0, v7
	v_mul_f32_e32 v7, 0x3fb8aa3b, v7
	v_exp_f32_e32 v7, v7
	s_nop 0
	v_add_f32_e32 v7, 1.0, v7
	v_rcp_f32_e32 v5, v3
	s_nop 0
	v_mul_f32_e32 v2, v2, v5
	ds_write_b32 v75, v2 offset:35860
	v_rcp_f32_e32 v2, v7
	s_nop 0
	v_mul_f32_e32 v2, v4, v2
	s_cbranch_execz .LBB0_1742
	s_branch .LBB0_1743

.LBB0_1743:
	s_cmpk_gt_i32 s82, 0xfd
	s_cselect_b64 s[26:27], -1, 0
	s_and_b64 s[26:27], s[14:15], s[26:27]
	s_and_b64 vcc, exec, s[26:27]
	ds_write_b32 v75, v2 offset:36116
	s_cbranch_vccnz .LBB0_1745
	s_waitcnt lgkmcnt(0)
	v_add_f32_e32 v2, v87, v18
	v_add_f32_e32 v2, v88, v2
	v_mul_f32_e32 v3, 0x3d372713, v2
	v_mul_f32_e32 v3, v2, v3
	v_fma_f32 v3, v2, v3, v2
	v_mul_f32_e32 v3, 0x3f4c422a, v3
	v_mul_f32_e32 v3, -2.0, v3
	v_mul_f32_e32 v3, 0x3fb8aa3b, v3
	v_exp_f32_e32 v3, v3
	v_add_f32_e32 v4, v85, v19
	v_add_f32_e32 v4, v86, v4
	v_mul_f32_e32 v7, 0x3d372713, v4
	v_add_f32_e32 v3, 1.0, v3
	v_mul_f32_e32 v7, v4, v7
	v_fma_f32 v7, v4, v7, v4
	v_mul_f32_e32 v7, 0x3f4c422a, v7
	v_mul_f32_e32 v7, -2.0, v7
	v_mul_f32_e32 v7, 0x3fb8aa3b, v7
	v_exp_f32_e32 v7, v7
	s_nop 0
	v_add_f32_e32 v7, 1.0, v7
	v_rcp_f32_e32 v5, v3
	s_nop 0
	v_mul_f32_e32 v2, v2, v5
	ds_write_b32 v75, v2 offset:36376
	v_rcp_f32_e32 v2, v7
	s_nop 0
	v_mul_f32_e32 v2, v4, v2
	s_cbranch_execz .LBB0_1746
	s_branch .LBB0_1747

.LBB0_1747:
	s_cmpk_gt_i32 s80, 0xfd
	s_cselect_b64 s[26:27], -1, 0
	s_and_b64 s[26:27], s[14:15], s[26:27]
	s_and_b64 vcc, exec, s[26:27]
	ds_write_b32 v75, v2 offset:36632
	s_cbranch_vccnz .LBB0_1749
	s_waitcnt lgkmcnt(0)
	v_add_f32_e32 v2, v82, v18
	v_add_f32_e32 v2, v84, v2
	v_mul_f32_e32 v3, 0x3d372713, v2
	v_mul_f32_e32 v3, v2, v3
	v_fma_f32 v3, v2, v3, v2
	v_mul_f32_e32 v3, 0x3f4c422a, v3
	v_mul_f32_e32 v3, -2.0, v3
	v_mul_f32_e32 v3, 0x3fb8aa3b, v3
	v_exp_f32_e32 v3, v3
	v_add_f32_e32 v4, v81, v19
	v_add_f32_e32 v4, v83, v4
	v_mul_f32_e32 v7, 0x3d372713, v4
	v_add_f32_e32 v3, 1.0, v3
	v_mul_f32_e32 v7, v4, v7
	v_fma_f32 v7, v4, v7, v4
	v_mul_f32_e32 v7, 0x3f4c422a, v7
	v_mul_f32_e32 v7, -2.0, v7
	v_mul_f32_e32 v7, 0x3fb8aa3b, v7
	v_exp_f32_e32 v7, v7
	s_nop 0
	v_add_f32_e32 v7, 1.0, v7
	v_rcp_f32_e32 v5, v3
	s_nop 0
	v_mul_f32_e32 v2, v2, v5
	ds_write_b32 v75, v2 offset:36892
	v_rcp_f32_e32 v2, v7
	s_nop 0
	v_mul_f32_e32 v2, v4, v2
	s_cbranch_execz .LBB0_1750
	s_branch .LBB0_1751

.LBB0_1751:
	s_cmpk_gt_i32 s78, 0xfd
	s_cselect_b64 s[26:27], -1, 0
	s_and_b64 s[26:27], s[14:15], s[26:27]
	s_and_b64 vcc, exec, s[26:27]
	ds_write_b32 v75, v2 offset:37148
	s_cbranch_vccnz .LBB0_1753
	s_waitcnt lgkmcnt(0)
	v_add_f32_e32 v2, v79, v18
	v_add_f32_e32 v2, v80, v2
	v_mul_f32_e32 v3, 0x3d372713, v2
	v_mul_f32_e32 v3, v2, v3
	v_fma_f32 v3, v2, v3, v2
	v_mul_f32_e32 v3, 0x3f4c422a, v3
	v_mul_f32_e32 v3, -2.0, v3
	v_mul_f32_e32 v3, 0x3fb8aa3b, v3
	v_exp_f32_e32 v3, v3
	v_add_f32_e32 v4, v77, v19
	v_add_f32_e32 v4, v78, v4
	v_mul_f32_e32 v7, 0x3d372713, v4
	v_add_f32_e32 v3, 1.0, v3
	v_mul_f32_e32 v7, v4, v7
	v_fma_f32 v7, v4, v7, v4
	v_mul_f32_e32 v7, 0x3f4c422a, v7
	v_mul_f32_e32 v7, -2.0, v7
	v_mul_f32_e32 v7, 0x3fb8aa3b, v7
	v_exp_f32_e32 v7, v7
	s_nop 0
	v_add_f32_e32 v7, 1.0, v7
	v_rcp_f32_e32 v5, v3
	s_nop 0
	v_mul_f32_e32 v2, v2, v5
	ds_write_b32 v75, v2 offset:37408
	v_rcp_f32_e32 v2, v7
	s_nop 0
	v_mul_f32_e32 v2, v4, v2
	s_cbranch_execz .LBB0_1754
	s_branch .LBB0_1755

.LBB0_1755:
	s_cmpk_gt_i32 s76, 0xfd
	s_cselect_b64 s[26:27], -1, 0
	s_and_b64 s[26:27], s[14:15], s[26:27]
	s_and_b64 vcc, exec, s[26:27]
	ds_write_b32 v75, v2 offset:37664
	s_cbranch_vccnz .LBB0_1757
	s_waitcnt lgkmcnt(0)
	v_add_f32_e32 v2, v73, v18
	v_add_f32_e32 v2, v76, v2
	v_mul_f32_e32 v3, 0x3d372713, v2
	v_mul_f32_e32 v3, v2, v3
	v_fma_f32 v3, v2, v3, v2
	v_mul_f32_e32 v3, 0x3f4c422a, v3
	v_mul_f32_e32 v3, -2.0, v3
	v_mul_f32_e32 v3, 0x3fb8aa3b, v3
	v_exp_f32_e32 v3, v3
	v_add_f32_e32 v4, v72, v19
	v_add_f32_e32 v4, v74, v4
	v_mul_f32_e32 v7, 0x3d372713, v4
	v_add_f32_e32 v3, 1.0, v3
	v_mul_f32_e32 v7, v4, v7
	v_fma_f32 v7, v4, v7, v4
	v_mul_f32_e32 v7, 0x3f4c422a, v7
	v_mul_f32_e32 v7, -2.0, v7
	v_mul_f32_e32 v7, 0x3fb8aa3b, v7
	v_exp_f32_e32 v7, v7
	s_nop 0
	v_add_f32_e32 v7, 1.0, v7
	v_rcp_f32_e32 v5, v3
	s_nop 0
	v_mul_f32_e32 v2, v2, v5
	ds_write_b32 v75, v2 offset:37924
	v_rcp_f32_e32 v2, v7
	s_nop 0
	v_mul_f32_e32 v2, v4, v2
	s_cbranch_execz .LBB0_1758
	s_branch .LBB0_1759

.LBB0_1759:
	s_cmpk_gt_i32 s74, 0xfd
	s_cselect_b64 s[26:27], -1, 0
	s_and_b64 s[26:27], s[14:15], s[26:27]
	s_and_b64 vcc, exec, s[26:27]
	ds_write_b32 v75, v2 offset:38180
	s_cbranch_vccnz .LBB0_1761
	s_waitcnt lgkmcnt(0)
	v_add_f32_e32 v2, v70, v18
	v_add_f32_e32 v2, v71, v2
	v_mul_f32_e32 v3, 0x3d372713, v2
	v_mul_f32_e32 v3, v2, v3
	v_fma_f32 v3, v2, v3, v2
	v_mul_f32_e32 v3, 0x3f4c422a, v3
	v_mul_f32_e32 v3, -2.0, v3
	v_mul_f32_e32 v3, 0x3fb8aa3b, v3
	v_exp_f32_e32 v3, v3
	v_add_f32_e32 v4, v68, v19
	v_add_f32_e32 v4, v69, v4
	v_mul_f32_e32 v7, 0x3d372713, v4
	v_add_f32_e32 v3, 1.0, v3
	v_mul_f32_e32 v7, v4, v7
	v_fma_f32 v7, v4, v7, v4
	v_mul_f32_e32 v7, 0x3f4c422a, v7
	v_mul_f32_e32 v7, -2.0, v7
	v_mul_f32_e32 v7, 0x3fb8aa3b, v7
	v_exp_f32_e32 v7, v7
	s_nop 0
	v_add_f32_e32 v7, 1.0, v7
	v_rcp_f32_e32 v5, v3
	s_nop 0
	v_mul_f32_e32 v2, v2, v5
	ds_write_b32 v75, v2 offset:38440
	v_rcp_f32_e32 v2, v7
	s_nop 0
	v_mul_f32_e32 v2, v4, v2
	s_cbranch_execz .LBB0_1762
	s_branch .LBB0_1763

.LBB0_1763:
	s_cmpk_gt_i32 s70, 0xfd
	s_cselect_b64 s[26:27], -1, 0
	s_and_b64 s[26:27], s[14:15], s[26:27]
	s_and_b64 vcc, exec, s[26:27]
	ds_write_b32 v75, v2 offset:38696
	s_cbranch_vccnz .LBB0_1765
	s_waitcnt lgkmcnt(0)
	v_add_f32_e32 v2, v65, v18
	v_add_f32_e32 v2, v67, v2
	v_mul_f32_e32 v3, 0x3d372713, v2
	v_mul_f32_e32 v3, v2, v3
	v_fma_f32 v3, v2, v3, v2
	v_mul_f32_e32 v3, 0x3f4c422a, v3
	v_mul_f32_e32 v3, -2.0, v3
	v_mul_f32_e32 v3, 0x3fb8aa3b, v3
	v_exp_f32_e32 v3, v3
	v_add_f32_e32 v4, v64, v19
	v_add_f32_e32 v4, v66, v4
	v_mul_f32_e32 v7, 0x3d372713, v4
	v_add_f32_e32 v3, 1.0, v3
	v_mul_f32_e32 v7, v4, v7
	v_fma_f32 v7, v4, v7, v4
	v_mul_f32_e32 v7, 0x3f4c422a, v7
	v_mul_f32_e32 v7, -2.0, v7
	v_mul_f32_e32 v7, 0x3fb8aa3b, v7
	v_exp_f32_e32 v7, v7
	s_nop 0
	v_add_f32_e32 v7, 1.0, v7
	v_rcp_f32_e32 v5, v3
	s_nop 0
	v_mul_f32_e32 v2, v2, v5
	ds_write_b32 v75, v2 offset:38956
	v_rcp_f32_e32 v2, v7
	s_nop 0
	v_mul_f32_e32 v2, v4, v2
	s_cbranch_execz .LBB0_1766
	s_branch .LBB0_1767

.LBB0_1767:
	s_cmpk_gt_i32 s66, 0xfd
	s_cselect_b64 s[26:27], -1, 0
	s_and_b64 s[26:27], s[14:15], s[26:27]
	s_and_b64 vcc, exec, s[26:27]
	ds_write_b32 v75, v2 offset:39212
	s_cbranch_vccnz .LBB0_1769
	s_waitcnt lgkmcnt(0)
	v_add_f32_e32 v2, v62, v18
	v_add_f32_e32 v2, v63, v2
	v_mul_f32_e32 v3, 0x3d372713, v2
	v_mul_f32_e32 v3, v2, v3
	v_fma_f32 v3, v2, v3, v2
	v_mul_f32_e32 v3, 0x3f4c422a, v3
	v_mul_f32_e32 v3, -2.0, v3
	v_mul_f32_e32 v3, 0x3fb8aa3b, v3
	v_exp_f32_e32 v3, v3
	v_add_f32_e32 v4, v60, v19
	v_add_f32_e32 v4, v61, v4
	v_mul_f32_e32 v7, 0x3d372713, v4
	v_add_f32_e32 v3, 1.0, v3
	v_mul_f32_e32 v7, v4, v7
	v_fma_f32 v7, v4, v7, v4
	v_mul_f32_e32 v7, 0x3f4c422a, v7
	v_mul_f32_e32 v7, -2.0, v7
	v_mul_f32_e32 v7, 0x3fb8aa3b, v7
	v_exp_f32_e32 v7, v7
	s_nop 0
	v_add_f32_e32 v7, 1.0, v7
	v_rcp_f32_e32 v5, v3
	s_nop 0
	v_mul_f32_e32 v2, v2, v5
	ds_write_b32 v75, v2 offset:39472
	v_rcp_f32_e32 v2, v7
	s_nop 0
	v_mul_f32_e32 v2, v4, v2
	s_cbranch_execz .LBB0_1770
	s_branch .LBB0_1771

.LBB0_1771:
	s_cmpk_gt_i32 s64, 0xfd
	s_cselect_b64 s[26:27], -1, 0
	s_and_b64 s[26:27], s[14:15], s[26:27]
	s_and_b64 vcc, exec, s[26:27]
	ds_write_b32 v75, v2 offset:39728
	s_cbranch_vccnz .LBB0_1773
	s_waitcnt lgkmcnt(0)
	v_add_f32_e32 v2, v56, v18
	v_add_f32_e32 v2, v59, v2
	v_mul_f32_e32 v3, 0x3d372713, v2
	v_mul_f32_e32 v3, v2, v3
	v_fma_f32 v3, v2, v3, v2
	v_mul_f32_e32 v3, 0x3f4c422a, v3
	v_mul_f32_e32 v3, -2.0, v3
	v_mul_f32_e32 v3, 0x3fb8aa3b, v3
	v_exp_f32_e32 v3, v3
	v_add_f32_e32 v4, v55, v19
	v_add_f32_e32 v4, v57, v4
	v_mul_f32_e32 v7, 0x3d372713, v4
	v_add_f32_e32 v3, 1.0, v3
	v_mul_f32_e32 v7, v4, v7
	v_fma_f32 v7, v4, v7, v4
	v_mul_f32_e32 v7, 0x3f4c422a, v7
	v_mul_f32_e32 v7, -2.0, v7
	v_mul_f32_e32 v7, 0x3fb8aa3b, v7
	v_exp_f32_e32 v7, v7
	s_nop 0
	v_add_f32_e32 v7, 1.0, v7
	v_rcp_f32_e32 v5, v3
	s_nop 0
	v_mul_f32_e32 v2, v2, v5
	ds_write_b32 v75, v2 offset:39988
	v_rcp_f32_e32 v2, v7
	s_nop 0
	v_mul_f32_e32 v2, v4, v2
	s_cbranch_execz .LBB0_1774
	s_branch .LBB0_1775

.LBB0_1775:
	s_cmpk_gt_i32 s10, 0xfd
	s_cselect_b64 s[10:11], -1, 0
	s_and_b64 s[10:11], s[14:15], s[10:11]
	s_and_b64 vcc, exec, s[10:11]
	ds_write_b32 v75, v2 offset:40244
	s_cbranch_vccnz .LBB0_1777
	s_waitcnt lgkmcnt(0)
	v_add_f32_e32 v2, v53, v18
	v_add_f32_e32 v2, v54, v2
	v_mul_f32_e32 v3, 0x3d372713, v2
	v_mul_f32_e32 v3, v2, v3
	v_fma_f32 v3, v2, v3, v2
	v_mul_f32_e32 v3, 0x3f4c422a, v3
	v_mul_f32_e32 v3, -2.0, v3
	v_mul_f32_e32 v3, 0x3fb8aa3b, v3
	v_exp_f32_e32 v3, v3
	v_add_f32_e32 v4, v51, v19
	v_add_f32_e32 v4, v52, v4
	v_mul_f32_e32 v7, 0x3d372713, v4
	v_add_f32_e32 v3, 1.0, v3
	v_mul_f32_e32 v7, v4, v7
	v_fma_f32 v7, v4, v7, v4
	v_mul_f32_e32 v7, 0x3f4c422a, v7
	v_mul_f32_e32 v7, -2.0, v7
	v_mul_f32_e32 v7, 0x3fb8aa3b, v7
	v_exp_f32_e32 v7, v7
	s_nop 0
	v_add_f32_e32 v7, 1.0, v7
	v_rcp_f32_e32 v5, v3
	s_nop 0
	v_mul_f32_e32 v2, v2, v5
	ds_write_b32 v75, v2 offset:40504
	v_rcp_f32_e32 v2, v7
	s_nop 0
	v_mul_f32_e32 v2, v4, v2
	s_cbranch_execz .LBB0_1778
	s_branch .LBB0_1779

.LBB0_1779:
	s_cmpk_gt_i32 s6, 0xfd
	s_cselect_b64 s[6:7], -1, 0
	s_and_b64 s[6:7], s[14:15], s[6:7]
	s_and_b64 vcc, exec, s[6:7]
	ds_write_b32 v75, v2 offset:40760
	s_cbranch_vccnz .LBB0_1781
	s_waitcnt lgkmcnt(0)
	v_add_f32_e32 v2, v49, v18
	v_add_f32_e32 v2, v50, v2
	v_mul_f32_e32 v3, 0x3d372713, v2
	v_mul_f32_e32 v3, v2, v3
	v_fma_f32 v3, v2, v3, v2
	v_mul_f32_e32 v3, 0x3f4c422a, v3
	v_mul_f32_e32 v3, -2.0, v3
	v_mul_f32_e32 v3, 0x3fb8aa3b, v3
	v_exp_f32_e32 v3, v3
	v_add_f32_e32 v4, v1, v19
	v_add_f32_e32 v4, v48, v4
	v_mul_f32_e32 v7, 0x3d372713, v4
	v_add_f32_e32 v3, 1.0, v3
	v_mul_f32_e32 v7, v4, v7
	v_fma_f32 v7, v4, v7, v4
	v_mul_f32_e32 v7, 0x3f4c422a, v7
	v_mul_f32_e32 v7, -2.0, v7
	v_mul_f32_e32 v7, 0x3fb8aa3b, v7
	v_exp_f32_e32 v7, v7
	s_nop 0
	v_add_f32_e32 v7, 1.0, v7
	v_rcp_f32_e32 v5, v3
	s_nop 0
	v_mul_f32_e32 v2, v2, v5
	ds_write_b32 v75, v2 offset:41020
	v_rcp_f32_e32 v2, v7
	s_nop 0
	v_mul_f32_e32 v2, v4, v2
	s_cbranch_execz .LBB0_1782
	s_branch .LBB0_1783

.LBB0_1881:
	s_cmpk_lt_i32 s12, 0xfe
	s_cselect_b64 s[30:31], -1, 0
	s_or_b64 s[30:31], s[68:69], s[30:31]
	s_mov_b64 s[70:71], -1
	v_mov_b32_e32 v2, 0
	s_and_b64 vcc, exec, s[30:31]
	v_mov_b32_e32 v3, 0
	s_cbranch_vccz .LBB0_1883
	v_pk_add_f32 v[2:3], v[38:39], v[18:19]
	s_nop 0
	v_pk_add_f32 v[2:3], v[36:37], v[2:3]
	s_nop 0
	v_mul_f32_e32 v4, 0x3d372713, v2
	v_mul_f32_e32 v5, 0x3d372713, v3
	v_mul_f32_e32 v4, v2, v4
	v_mul_f32_e32 v5, v3, v5
	v_fma_f32 v4, v2, v4, v2
	v_fma_f32 v5, v3, v5, v3
	v_mul_f32_e32 v4, 0x3f4c422a, v4
	v_mul_f32_e32 v5, 0x3f4c422a, v5
	v_mul_f32_e32 v4, -2.0, v4
	v_mul_f32_e32 v5, -2.0, v5
	v_mul_f32_e32 v4, 0x3fb8aa3b, v4
	v_mul_f32_e32 v5, 0x3fb8aa3b, v5
	v_exp_f32_e32 v4, v4
	v_exp_f32_e32 v5, v5
	s_nop 0
	v_pk_add_f32 v[4:5], v[4:5], 1.0 op_sel_hi:[1,0]
	s_nop 0
	s_nop 0
	v_rcp_f32_e32 v6, v4
	s_nop 0
	v_mul_f32_e32 v2, v2, v6
	v_rcp_f32_e32 v4, v5
	s_nop 0
	v_mul_f32_e32 v3, v3, v4
.LBB0_1883:
	s_cmpk_gt_i32 s62, 0xfd
	s_cselect_b64 s[30:31], -1, 0
	s_and_b64 s[30:31], s[14:15], s[30:31]
	s_and_b64 vcc, exec, s[30:31]
	ds_write2st64_b32 v75, v2, v3 offset0:130 offset1:131
	s_cbranch_vccnz .LBB0_1885
	v_add_f32_e32 v2, v177, v18
	v_add_f32_e32 v2, v178, v2
	v_mul_f32_e32 v3, 0x3d372713, v2
	v_mul_f32_e32 v3, v2, v3
	v_fma_f32 v3, v2, v3, v2
	v_mul_f32_e32 v3, 0x3f4c422a, v3
	v_mul_f32_e32 v3, -2.0, v3
	v_mul_f32_e32 v3, 0x3fb8aa3b, v3
	v_exp_f32_e32 v3, v3
	v_add_f32_e32 v4, v175, v19
	v_add_f32_e32 v4, v176, v4
	v_mul_f32_e32 v7, 0x3d372713, v4
	v_add_f32_e32 v3, 1.0, v3
	v_mul_f32_e32 v7, v4, v7
	v_fma_f32 v7, v4, v7, v4
	v_mul_f32_e32 v7, 0x3f4c422a, v7
	v_mul_f32_e32 v7, -2.0, v7
	v_mul_f32_e32 v7, 0x3fb8aa3b, v7
	v_exp_f32_e32 v7, v7
	s_nop 0
	v_add_f32_e32 v7, 1.0, v7
	v_rcp_f32_e32 v5, v3
	s_nop 0
	v_mul_f32_e32 v2, v2, v5
	ds_write_b32 v75, v2 offset:33796
	v_rcp_f32_e32 v2, v7
	s_nop 0
	v_mul_f32_e32 v2, v4, v2
	s_mov_b64 s[70:71], 0

.LBB0_1887:
	s_cmpk_gt_i32 s60, 0xfd
	s_cselect_b64 s[30:31], -1, 0
	s_and_b64 s[30:31], s[14:15], s[30:31]
	s_and_b64 vcc, exec, s[30:31]
	ds_write_b32 v75, v2 offset:34052
	s_cbranch_vccnz .LBB0_1889
	v_add_f32_e32 v2, v173, v18
	v_add_f32_e32 v2, v174, v2
	v_mul_f32_e32 v3, 0x3d372713, v2
	v_mul_f32_e32 v3, v2, v3
	v_fma_f32 v3, v2, v3, v2
	v_mul_f32_e32 v3, 0x3f4c422a, v3
	v_mul_f32_e32 v3, -2.0, v3
	v_mul_f32_e32 v3, 0x3fb8aa3b, v3
	v_exp_f32_e32 v3, v3
	v_add_f32_e32 v4, v171, v19
	v_add_f32_e32 v4, v172, v4
	v_mul_f32_e32 v7, 0x3d372713, v4
	v_add_f32_e32 v3, 1.0, v3
	v_mul_f32_e32 v7, v4, v7
	v_fma_f32 v7, v4, v7, v4
	v_mul_f32_e32 v7, 0x3f4c422a, v7
	v_mul_f32_e32 v7, -2.0, v7
	v_mul_f32_e32 v7, 0x3fb8aa3b, v7
	v_exp_f32_e32 v7, v7
	s_nop 0
	v_add_f32_e32 v7, 1.0, v7
	v_rcp_f32_e32 v5, v3
	s_nop 0
	v_mul_f32_e32 v2, v2, v5
	ds_write_b32 v75, v2 offset:34312
	v_rcp_f32_e32 v2, v7
	s_nop 0
	v_mul_f32_e32 v2, v4, v2
	s_cbranch_execz .LBB0_1890
	s_branch .LBB0_1891

.LBB0_1891:
	s_cmpk_gt_i32 s58, 0xfd
	s_cselect_b64 s[30:31], -1, 0
	s_and_b64 s[30:31], s[14:15], s[30:31]
	s_and_b64 vcc, exec, s[30:31]
	ds_write_b32 v75, v2 offset:34568
	s_cbranch_vccnz .LBB0_1893
	v_add_f32_e32 v2, v169, v18
	v_add_f32_e32 v2, v170, v2
	v_mul_f32_e32 v3, 0x3d372713, v2
	v_mul_f32_e32 v3, v2, v3
	v_fma_f32 v3, v2, v3, v2
	v_mul_f32_e32 v3, 0x3f4c422a, v3
	v_mul_f32_e32 v3, -2.0, v3
	v_mul_f32_e32 v3, 0x3fb8aa3b, v3
	v_exp_f32_e32 v3, v3
	v_add_f32_e32 v4, v167, v19
	v_add_f32_e32 v4, v168, v4
	v_mul_f32_e32 v7, 0x3d372713, v4
	v_add_f32_e32 v3, 1.0, v3
	v_mul_f32_e32 v7, v4, v7
	v_fma_f32 v7, v4, v7, v4
	v_mul_f32_e32 v7, 0x3f4c422a, v7
	v_mul_f32_e32 v7, -2.0, v7
	v_mul_f32_e32 v7, 0x3fb8aa3b, v7
	v_exp_f32_e32 v7, v7
	s_nop 0
	v_add_f32_e32 v7, 1.0, v7
	v_rcp_f32_e32 v5, v3
	s_nop 0
	v_mul_f32_e32 v2, v2, v5
	ds_write_b32 v75, v2 offset:34828
	v_rcp_f32_e32 v2, v7
	s_nop 0
	v_mul_f32_e32 v2, v4, v2
	s_cbranch_execz .LBB0_1894
	s_branch .LBB0_1895

.LBB0_1895:
	s_cmpk_gt_i32 s56, 0xfd
	s_cselect_b64 s[30:31], -1, 0
	s_and_b64 s[30:31], s[14:15], s[30:31]
	s_and_b64 vcc, exec, s[30:31]
	ds_write_b32 v75, v2 offset:35084
	s_cbranch_vccnz .LBB0_1897
	v_add_f32_e32 v2, v165, v18
	v_add_f32_e32 v2, v166, v2
	v_mul_f32_e32 v3, 0x3d372713, v2
	v_mul_f32_e32 v3, v2, v3
	v_fma_f32 v3, v2, v3, v2
	v_mul_f32_e32 v3, 0x3f4c422a, v3
	v_mul_f32_e32 v3, -2.0, v3
	v_mul_f32_e32 v3, 0x3fb8aa3b, v3
	v_exp_f32_e32 v3, v3
	v_add_f32_e32 v4, v163, v19
	v_add_f32_e32 v4, v164, v4
	v_mul_f32_e32 v7, 0x3d372713, v4
	v_add_f32_e32 v3, 1.0, v3
	v_mul_f32_e32 v7, v4, v7
	v_fma_f32 v7, v4, v7, v4
	v_mul_f32_e32 v7, 0x3f4c422a, v7
	v_mul_f32_e32 v7, -2.0, v7
	v_mul_f32_e32 v7, 0x3fb8aa3b, v7
	v_exp_f32_e32 v7, v7
	s_nop 0
	v_add_f32_e32 v7, 1.0, v7
	v_rcp_f32_e32 v5, v3
	s_nop 0
	v_mul_f32_e32 v2, v2, v5
	ds_write_b32 v75, v2 offset:35344
	v_rcp_f32_e32 v2, v7
	s_nop 0
	v_mul_f32_e32 v2, v4, v2
	s_cbranch_execz .LBB0_1898
	s_branch .LBB0_1899

.LBB0_1899:
	s_cmpk_gt_i32 s54, 0xfd
	s_cselect_b64 s[30:31], -1, 0
	s_and_b64 s[30:31], s[14:15], s[30:31]
	s_and_b64 vcc, exec, s[30:31]
	ds_write_b32 v75, v2 offset:35600
	s_cbranch_vccnz .LBB0_1901
	v_add_f32_e32 v2, v161, v18
	v_add_f32_e32 v2, v162, v2
	v_mul_f32_e32 v3, 0x3d372713, v2
	v_mul_f32_e32 v3, v2, v3
	v_fma_f32 v3, v2, v3, v2
	v_mul_f32_e32 v3, 0x3f4c422a, v3
	v_mul_f32_e32 v3, -2.0, v3
	v_mul_f32_e32 v3, 0x3fb8aa3b, v3
	v_exp_f32_e32 v3, v3
	v_add_f32_e32 v4, v159, v19
	v_add_f32_e32 v4, v160, v4
	v_mul_f32_e32 v7, 0x3d372713, v4
	v_add_f32_e32 v3, 1.0, v3
	v_mul_f32_e32 v7, v4, v7
	v_fma_f32 v7, v4, v7, v4
	v_mul_f32_e32 v7, 0x3f4c422a, v7
	v_mul_f32_e32 v7, -2.0, v7
	v_mul_f32_e32 v7, 0x3fb8aa3b, v7
	v_exp_f32_e32 v7, v7
	s_nop 0
	v_add_f32_e32 v7, 1.0, v7
	v_rcp_f32_e32 v5, v3
	s_nop 0
	v_mul_f32_e32 v2, v2, v5
	ds_write_b32 v75, v2 offset:35860
	v_rcp_f32_e32 v2, v7
	s_nop 0
	v_mul_f32_e32 v2, v4, v2
	s_cbranch_execz .LBB0_1902
	s_branch .LBB0_1903

.LBB0_1903:
	s_cmpk_gt_i32 s52, 0xfd
	s_cselect_b64 s[30:31], -1, 0
	s_and_b64 s[30:31], s[14:15], s[30:31]
	s_and_b64 vcc, exec, s[30:31]
	ds_write_b32 v75, v2 offset:36116
	s_cbranch_vccnz .LBB0_1905
	v_add_f32_e32 v2, v157, v18
	v_add_f32_e32 v2, v158, v2
	v_mul_f32_e32 v3, 0x3d372713, v2
	v_mul_f32_e32 v3, v2, v3
	v_fma_f32 v3, v2, v3, v2
	v_mul_f32_e32 v3, 0x3f4c422a, v3
	v_mul_f32_e32 v3, -2.0, v3
	v_mul_f32_e32 v3, 0x3fb8aa3b, v3
	v_exp_f32_e32 v3, v3
	v_add_f32_e32 v4, v155, v19
	v_add_f32_e32 v4, v156, v4
	v_mul_f32_e32 v7, 0x3d372713, v4
	v_add_f32_e32 v3, 1.0, v3
	v_mul_f32_e32 v7, v4, v7
	v_fma_f32 v7, v4, v7, v4
	v_mul_f32_e32 v7, 0x3f4c422a, v7
	v_mul_f32_e32 v7, -2.0, v7
	v_mul_f32_e32 v7, 0x3fb8aa3b, v7
	v_exp_f32_e32 v7, v7
	s_nop 0
	v_add_f32_e32 v7, 1.0, v7
	v_rcp_f32_e32 v5, v3
	s_nop 0
	v_mul_f32_e32 v2, v2, v5
	ds_write_b32 v75, v2 offset:36376
	v_rcp_f32_e32 v2, v7
	s_nop 0
	v_mul_f32_e32 v2, v4, v2
	s_cbranch_execz .LBB0_1906
	s_branch .LBB0_1907

.LBB0_1907:
	s_cmpk_gt_i32 s50, 0xfd
	s_cselect_b64 s[30:31], -1, 0
	s_and_b64 s[30:31], s[14:15], s[30:31]
	s_and_b64 vcc, exec, s[30:31]
	ds_write_b32 v75, v2 offset:36632
	s_cbranch_vccnz .LBB0_1909
	v_add_f32_e32 v2, v153, v18
	v_add_f32_e32 v2, v154, v2
	v_mul_f32_e32 v3, 0x3d372713, v2
	v_mul_f32_e32 v3, v2, v3
	v_fma_f32 v3, v2, v3, v2
	v_mul_f32_e32 v3, 0x3f4c422a, v3
	v_mul_f32_e32 v3, -2.0, v3
	v_mul_f32_e32 v3, 0x3fb8aa3b, v3
	v_exp_f32_e32 v3, v3
	v_add_f32_e32 v4, v151, v19
	v_add_f32_e32 v4, v152, v4
	v_mul_f32_e32 v7, 0x3d372713, v4
	v_add_f32_e32 v3, 1.0, v3
	v_mul_f32_e32 v7, v4, v7
	v_fma_f32 v7, v4, v7, v4
	v_mul_f32_e32 v7, 0x3f4c422a, v7
	v_mul_f32_e32 v7, -2.0, v7
	v_mul_f32_e32 v7, 0x3fb8aa3b, v7
	v_exp_f32_e32 v7, v7
	s_nop 0
	v_add_f32_e32 v7, 1.0, v7
	v_rcp_f32_e32 v5, v3
	s_nop 0
	v_mul_f32_e32 v2, v2, v5
	ds_write_b32 v75, v2 offset:36892
	v_rcp_f32_e32 v2, v7
	s_nop 0
	v_mul_f32_e32 v2, v4, v2
	s_cbranch_execz .LBB0_1910
	s_branch .LBB0_1911

.LBB0_1911:
	s_cmpk_gt_i32 s48, 0xfd
	s_cselect_b64 s[30:31], -1, 0
	s_and_b64 s[30:31], s[14:15], s[30:31]
	s_and_b64 vcc, exec, s[30:31]
	ds_write_b32 v75, v2 offset:37148
	s_cbranch_vccnz .LBB0_1913
	v_add_f32_e32 v2, v149, v18
	v_add_f32_e32 v2, v150, v2
	v_mul_f32_e32 v3, 0x3d372713, v2
	v_mul_f32_e32 v3, v2, v3
	v_fma_f32 v3, v2, v3, v2
	v_mul_f32_e32 v3, 0x3f4c422a, v3
	v_mul_f32_e32 v3, -2.0, v3
	v_mul_f32_e32 v3, 0x3fb8aa3b, v3
	v_exp_f32_e32 v3, v3
	v_add_f32_e32 v4, v147, v19
	v_add_f32_e32 v4, v148, v4
	v_mul_f32_e32 v7, 0x3d372713, v4
	v_add_f32_e32 v3, 1.0, v3
	v_mul_f32_e32 v7, v4, v7
	v_fma_f32 v7, v4, v7, v4
	v_mul_f32_e32 v7, 0x3f4c422a, v7
	v_mul_f32_e32 v7, -2.0, v7
	v_mul_f32_e32 v7, 0x3fb8aa3b, v7
	v_exp_f32_e32 v7, v7
	s_nop 0
	v_add_f32_e32 v7, 1.0, v7
	v_rcp_f32_e32 v5, v3
	s_nop 0
	v_mul_f32_e32 v2, v2, v5
	ds_write_b32 v75, v2 offset:37408
	v_rcp_f32_e32 v2, v7
	s_nop 0
	v_mul_f32_e32 v2, v4, v2
	s_cbranch_execz .LBB0_1914
	s_branch .LBB0_1915

.LBB0_1915:
	s_cmpk_gt_i32 s46, 0xfd
	s_cselect_b64 s[30:31], -1, 0
	s_and_b64 s[30:31], s[14:15], s[30:31]
	s_and_b64 vcc, exec, s[30:31]
	ds_write_b32 v75, v2 offset:37664
	s_cbranch_vccnz .LBB0_1917
	v_add_f32_e32 v2, v145, v18
	v_add_f32_e32 v2, v146, v2
	v_mul_f32_e32 v3, 0x3d372713, v2
	v_mul_f32_e32 v3, v2, v3
	v_fma_f32 v3, v2, v3, v2
	v_mul_f32_e32 v3, 0x3f4c422a, v3
	v_mul_f32_e32 v3, -2.0, v3
	v_mul_f32_e32 v3, 0x3fb8aa3b, v3
	v_exp_f32_e32 v3, v3
	v_add_f32_e32 v4, v143, v19
	v_add_f32_e32 v4, v144, v4
	v_mul_f32_e32 v7, 0x3d372713, v4
	v_add_f32_e32 v3, 1.0, v3
	v_mul_f32_e32 v7, v4, v7
	v_fma_f32 v7, v4, v7, v4
	v_mul_f32_e32 v7, 0x3f4c422a, v7
	v_mul_f32_e32 v7, -2.0, v7
	v_mul_f32_e32 v7, 0x3fb8aa3b, v7
	v_exp_f32_e32 v7, v7
	s_nop 0
	v_add_f32_e32 v7, 1.0, v7
	v_rcp_f32_e32 v5, v3
	s_nop 0
	v_mul_f32_e32 v2, v2, v5
	ds_write_b32 v75, v2 offset:37924
	v_rcp_f32_e32 v2, v7
	s_nop 0
	v_mul_f32_e32 v2, v4, v2
	s_cbranch_execz .LBB0_1918
	s_branch .LBB0_1919

.LBB0_1919:
	s_cmpk_gt_i32 s44, 0xfd
	s_cselect_b64 s[30:31], -1, 0
	s_and_b64 s[30:31], s[14:15], s[30:31]
	s_and_b64 vcc, exec, s[30:31]
	ds_write_b32 v75, v2 offset:38180
	s_cbranch_vccnz .LBB0_1921
	v_add_f32_e32 v2, v141, v18
	v_add_f32_e32 v2, v142, v2
	v_mul_f32_e32 v3, 0x3d372713, v2
	v_mul_f32_e32 v3, v2, v3
	v_fma_f32 v3, v2, v3, v2
	v_mul_f32_e32 v3, 0x3f4c422a, v3
	v_mul_f32_e32 v3, -2.0, v3
	v_mul_f32_e32 v3, 0x3fb8aa3b, v3
	v_exp_f32_e32 v3, v3
	v_add_f32_e32 v4, v139, v19
	v_add_f32_e32 v4, v140, v4
	v_mul_f32_e32 v7, 0x3d372713, v4
	v_add_f32_e32 v3, 1.0, v3
	v_mul_f32_e32 v7, v4, v7
	v_fma_f32 v7, v4, v7, v4
	v_mul_f32_e32 v7, 0x3f4c422a, v7
	v_mul_f32_e32 v7, -2.0, v7
	v_mul_f32_e32 v7, 0x3fb8aa3b, v7
	v_exp_f32_e32 v7, v7
	s_nop 0
	v_add_f32_e32 v7, 1.0, v7
	v_rcp_f32_e32 v5, v3
	s_nop 0
	v_mul_f32_e32 v2, v2, v5
	ds_write_b32 v75, v2 offset:38440
	v_rcp_f32_e32 v2, v7
	s_nop 0
	v_mul_f32_e32 v2, v4, v2
	s_cbranch_execz .LBB0_1922
	s_branch .LBB0_1923

.LBB0_1923:
	s_cmpk_gt_i32 s24, 0xfd
	s_cselect_b64 s[24:25], -1, 0
	s_and_b64 s[24:25], s[14:15], s[24:25]
	s_and_b64 vcc, exec, s[24:25]
	ds_write_b32 v75, v2 offset:38696
	s_cbranch_vccnz .LBB0_1925
	v_add_f32_e32 v2, v137, v18
	v_add_f32_e32 v2, v138, v2
	v_mul_f32_e32 v3, 0x3d372713, v2
	v_mul_f32_e32 v3, v2, v3
	v_fma_f32 v3, v2, v3, v2
	v_mul_f32_e32 v3, 0x3f4c422a, v3
	v_mul_f32_e32 v3, -2.0, v3
	v_mul_f32_e32 v3, 0x3fb8aa3b, v3
	v_exp_f32_e32 v3, v3
	v_add_f32_e32 v4, v135, v19
	v_add_f32_e32 v4, v136, v4
	v_mul_f32_e32 v7, 0x3d372713, v4
	v_add_f32_e32 v3, 1.0, v3
	v_mul_f32_e32 v7, v4, v7
	v_fma_f32 v7, v4, v7, v4
	v_mul_f32_e32 v7, 0x3f4c422a, v7
	v_mul_f32_e32 v7, -2.0, v7
	v_mul_f32_e32 v7, 0x3fb8aa3b, v7
	v_exp_f32_e32 v7, v7
	s_nop 0
	v_add_f32_e32 v7, 1.0, v7
	v_rcp_f32_e32 v5, v3
	s_nop 0
	v_mul_f32_e32 v2, v2, v5
	ds_write_b32 v75, v2 offset:38956
	v_rcp_f32_e32 v2, v7
	s_nop 0
	v_mul_f32_e32 v2, v4, v2
	s_cbranch_execz .LBB0_1926
	s_branch .LBB0_1927

.LBB0_1927:
	s_cmpk_gt_i32 s22, 0xfd
	s_cselect_b64 s[22:23], -1, 0
	s_and_b64 s[22:23], s[14:15], s[22:23]
	s_and_b64 vcc, exec, s[22:23]
	ds_write_b32 v75, v2 offset:39212
	s_cbranch_vccnz .LBB0_1929
	v_add_f32_e32 v2, v129, v18
	v_add_f32_e32 v2, v134, v2
	v_mul_f32_e32 v3, 0x3d372713, v2
	v_mul_f32_e32 v3, v2, v3
	v_fma_f32 v3, v2, v3, v2
	v_mul_f32_e32 v3, 0x3f4c422a, v3
	v_mul_f32_e32 v3, -2.0, v3
	v_mul_f32_e32 v3, 0x3fb8aa3b, v3
	v_exp_f32_e32 v3, v3
	v_add_f32_e32 v4, v127, v19
	v_add_f32_e32 v4, v128, v4
	v_mul_f32_e32 v7, 0x3d372713, v4
	v_add_f32_e32 v3, 1.0, v3
	v_mul_f32_e32 v7, v4, v7
	v_fma_f32 v7, v4, v7, v4
	v_mul_f32_e32 v7, 0x3f4c422a, v7
	v_mul_f32_e32 v7, -2.0, v7
	v_mul_f32_e32 v7, 0x3fb8aa3b, v7
	v_exp_f32_e32 v7, v7
	s_nop 0
	v_add_f32_e32 v7, 1.0, v7
	v_rcp_f32_e32 v5, v3
	s_nop 0
	v_mul_f32_e32 v2, v2, v5
	ds_write_b32 v75, v2 offset:39472
	v_rcp_f32_e32 v2, v7
	s_nop 0
	v_mul_f32_e32 v2, v4, v2
	s_cbranch_execz .LBB0_1930
	s_branch .LBB0_1931

.LBB0_1931:
	s_cmpk_gt_i32 s20, 0xfd
	s_cselect_b64 s[20:21], -1, 0
	s_and_b64 s[20:21], s[14:15], s[20:21]
	s_and_b64 vcc, exec, s[20:21]
	ds_write_b32 v75, v2 offset:39728
	s_cbranch_vccnz .LBB0_1933
	v_add_f32_e32 v2, v125, v18
	v_add_f32_e32 v2, v126, v2
	v_mul_f32_e32 v3, 0x3d372713, v2
	v_mul_f32_e32 v3, v2, v3
	v_fma_f32 v3, v2, v3, v2
	v_mul_f32_e32 v3, 0x3f4c422a, v3
	v_mul_f32_e32 v3, -2.0, v3
	v_mul_f32_e32 v3, 0x3fb8aa3b, v3
	v_exp_f32_e32 v3, v3
	v_add_f32_e32 v4, v123, v19
	v_add_f32_e32 v4, v124, v4
	v_mul_f32_e32 v7, 0x3d372713, v4
	v_add_f32_e32 v3, 1.0, v3
	v_mul_f32_e32 v7, v4, v7
	v_fma_f32 v7, v4, v7, v4
	v_mul_f32_e32 v7, 0x3f4c422a, v7
	v_mul_f32_e32 v7, -2.0, v7
	v_mul_f32_e32 v7, 0x3fb8aa3b, v7
	v_exp_f32_e32 v7, v7
	s_nop 0
	v_add_f32_e32 v7, 1.0, v7
	v_rcp_f32_e32 v5, v3
	s_nop 0
	v_mul_f32_e32 v2, v2, v5
	ds_write_b32 v75, v2 offset:39988
	v_rcp_f32_e32 v2, v7
	s_nop 0
	v_mul_f32_e32 v2, v4, v2
	s_cbranch_execz .LBB0_1934
	s_branch .LBB0_1935

.LBB0_1935:
	s_cmpk_gt_i32 s18, 0xfd
	s_cselect_b64 s[18:19], -1, 0
	s_and_b64 s[18:19], s[14:15], s[18:19]
	s_and_b64 vcc, exec, s[18:19]
	ds_write_b32 v75, v2 offset:40244
	s_cbranch_vccnz .LBB0_1937
	v_add_f32_e32 v2, v121, v18
	v_add_f32_e32 v2, v122, v2
	v_mul_f32_e32 v3, 0x3d372713, v2
	v_mul_f32_e32 v3, v2, v3
	v_fma_f32 v3, v2, v3, v2
	v_mul_f32_e32 v3, 0x3f4c422a, v3
	v_mul_f32_e32 v3, -2.0, v3
	v_mul_f32_e32 v3, 0x3fb8aa3b, v3
	v_exp_f32_e32 v3, v3
	v_add_f32_e32 v4, v119, v19
	v_add_f32_e32 v4, v120, v4
	v_mul_f32_e32 v7, 0x3d372713, v4
	v_add_f32_e32 v3, 1.0, v3
	v_mul_f32_e32 v7, v4, v7
	v_fma_f32 v7, v4, v7, v4
	v_mul_f32_e32 v7, 0x3f4c422a, v7
	v_mul_f32_e32 v7, -2.0, v7
	v_mul_f32_e32 v7, 0x3fb8aa3b, v7
	v_exp_f32_e32 v7, v7
	s_nop 0
	v_add_f32_e32 v7, 1.0, v7
	v_rcp_f32_e32 v5, v3
	s_nop 0
	v_mul_f32_e32 v2, v2, v5
	ds_write_b32 v75, v2 offset:40504
	v_rcp_f32_e32 v2, v7
	s_nop 0
	v_mul_f32_e32 v2, v4, v2
	s_cbranch_execz .LBB0_1938
	s_branch .LBB0_1939

.LBB0_1939:
	s_cmpk_gt_i32 s16, 0xfd
	s_cselect_b64 s[16:17], -1, 0
	s_and_b64 s[16:17], s[14:15], s[16:17]
	s_and_b64 vcc, exec, s[16:17]
	ds_write_b32 v75, v2 offset:40760
	s_cbranch_vccnz .LBB0_1941
	v_add_f32_e32 v2, v117, v18
	v_add_f32_e32 v2, v118, v2
	v_mul_f32_e32 v3, 0x3d372713, v2
	v_mul_f32_e32 v3, v2, v3
	v_fma_f32 v3, v2, v3, v2
	v_mul_f32_e32 v3, 0x3f4c422a, v3
	v_mul_f32_e32 v3, -2.0, v3
	v_mul_f32_e32 v3, 0x3fb8aa3b, v3
	v_exp_f32_e32 v3, v3
	v_add_f32_e32 v4, v115, v19
	v_add_f32_e32 v4, v116, v4
	v_mul_f32_e32 v7, 0x3d372713, v4
	v_add_f32_e32 v3, 1.0, v3
	v_mul_f32_e32 v7, v4, v7
	v_fma_f32 v7, v4, v7, v4
	v_mul_f32_e32 v7, 0x3f4c422a, v7
	v_mul_f32_e32 v7, -2.0, v7
	v_mul_f32_e32 v7, 0x3fb8aa3b, v7
	v_exp_f32_e32 v7, v7
	s_nop 0
	v_add_f32_e32 v7, 1.0, v7
	v_rcp_f32_e32 v5, v3
	s_nop 0
	v_mul_f32_e32 v2, v2, v5
	ds_write_b32 v75, v2 offset:41020
	v_rcp_f32_e32 v2, v7
	s_nop 0
	v_mul_f32_e32 v2, v4, v2
	s_cbranch_execz .LBB0_1942
	s_branch .LBB0_1943

.LBB0_2044:
	s_ashr_i32 s2, s6, 1
	s_cmp_lt_i32 s2, 8
	s_cselect_b64 s[14:15], -1, 0
	s_cmp_gt_i32 s2, 7
	s_cselect_b64 s[4:5], -1, 0
	s_and_b32 s3, s2, 3
	s_cmp_eq_u32 s3, 3
	s_cselect_b64 s[12:13], -1, 0
	s_or_b64 s[12:13], s[4:5], s[12:13]
	s_cmpk_gt_i32 s8, 0xfd
	s_cselect_b64 s[4:5], -1, 0
	s_and_b64 s[4:5], s[4:5], s[12:13]
	v_mov_b32_e32 v2, 0
	s_and_b64 vcc, exec, s[4:5]
	v_mov_b32_e32 v3, 0
	s_cbranch_vccnz .LBB0_2046
	s_waitcnt vmcnt(0) lgkmcnt(0)
	v_pk_add_f32 v[2:3], v[18:19], v[20:21]
	s_nop 0
	v_pk_add_f32 v[2:3], v[2:3], v[22:23]
	s_nop 0
	v_mul_f32_e32 v4, 0x3d372713, v2
	v_mul_f32_e32 v5, 0x3d372713, v3
	v_mul_f32_e32 v4, v2, v4
	v_mul_f32_e32 v5, v3, v5
	v_fma_f32 v4, v2, v4, v2
	v_fma_f32 v5, v3, v5, v3
	v_mul_f32_e32 v4, 0x3f4c422a, v4
	v_mul_f32_e32 v5, 0x3f4c422a, v5
	v_mul_f32_e32 v4, -2.0, v4
	v_mul_f32_e32 v5, -2.0, v5
	v_mul_f32_e32 v4, 0x3fb8aa3b, v4
	v_mul_f32_e32 v5, 0x3fb8aa3b, v5
	v_exp_f32_e32 v4, v4
	v_exp_f32_e32 v5, v5
	s_nop 0
	v_pk_add_f32 v[4:5], v[4:5], 1.0 op_sel_hi:[1,0]
	s_nop 0
	s_nop 0
	v_rcp_f32_e32 v6, v4
	s_nop 0
	v_mul_f32_e32 v2, v2, v6
	v_rcp_f32_e32 v4, v5
	s_nop 0
	v_mul_f32_e32 v3, v3, v4
.LBB0_2046:
	s_cmpk_gt_i32 s8, 0xfc
	s_cselect_b64 s[4:5], -1, 0
	s_and_b64 s[4:5], s[4:5], s[12:13]
	s_and_b64 vcc, exec, s[4:5]
	ds_write2st64_b32 v75, v2, v3 offset0:130 offset1:131
	s_cbranch_vccnz .LBB0_2048
	s_waitcnt vmcnt(0) lgkmcnt(0)
	v_add_f32_e32 v2, v18, v107
	v_add_f32_e32 v2, v2, v108
	v_mul_f32_e32 v3, 0x3d372713, v2
	v_mul_f32_e32 v3, v2, v3
	v_fma_f32 v3, v2, v3, v2
	v_mul_f32_e32 v3, 0x3f4c422a, v3
	v_mul_f32_e32 v3, -2.0, v3
	v_mul_f32_e32 v3, 0x3fb8aa3b, v3
	v_exp_f32_e32 v3, v3
	v_add_f32_e32 v4, v19, v105
	v_add_f32_e32 v4, v4, v106
	v_mul_f32_e32 v7, 0x3d372713, v4
	v_add_f32_e32 v3, 1.0, v3
	v_mul_f32_e32 v7, v4, v7
	v_fma_f32 v7, v4, v7, v4
	v_mul_f32_e32 v7, 0x3f4c422a, v7
	v_mul_f32_e32 v7, -2.0, v7
	v_mul_f32_e32 v7, 0x3fb8aa3b, v7
	v_exp_f32_e32 v7, v7
	s_nop 0
	v_add_f32_e32 v7, 1.0, v7
	v_rcp_f32_e32 v5, v3
	s_nop 0
	v_mul_f32_e32 v2, v2, v5
	ds_write_b32 v75, v2 offset:33796
	v_rcp_f32_e32 v2, v7
	s_nop 0
	v_mul_f32_e32 v2, v4, v2
	s_cbranch_execz .LBB0_2049
	s_branch .LBB0_2050

.LBB0_2050:
	s_or_b32 s4, s8, 2
	s_cmpk_gt_i32 s4, 0xfd
	s_cselect_b64 s[4:5], -1, 0
	s_and_b64 s[4:5], s[4:5], s[12:13]
	s_and_b64 vcc, exec, s[4:5]
	ds_write_b32 v75, v2 offset:34052
	s_cbranch_vccnz .LBB0_2052
	s_waitcnt vmcnt(0) lgkmcnt(0)
	v_add_f32_e32 v2, v18, v103
	v_add_f32_e32 v2, v2, v104
	v_mul_f32_e32 v3, 0x3d372713, v2
	v_mul_f32_e32 v3, v2, v3
	v_fma_f32 v3, v2, v3, v2
	v_mul_f32_e32 v3, 0x3f4c422a, v3
	v_mul_f32_e32 v3, -2.0, v3
	v_mul_f32_e32 v3, 0x3fb8aa3b, v3
	v_exp_f32_e32 v3, v3
	v_add_f32_e32 v4, v19, v100
	v_add_f32_e32 v4, v4, v102
	v_mul_f32_e32 v7, 0x3d372713, v4
	v_add_f32_e32 v3, 1.0, v3
	v_mul_f32_e32 v7, v4, v7
	v_fma_f32 v7, v4, v7, v4
	v_mul_f32_e32 v7, 0x3f4c422a, v7
	v_mul_f32_e32 v7, -2.0, v7
	v_mul_f32_e32 v7, 0x3fb8aa3b, v7
	v_exp_f32_e32 v7, v7
	s_nop 0
	v_add_f32_e32 v7, 1.0, v7
	v_rcp_f32_e32 v5, v3
	s_nop 0
	v_mul_f32_e32 v2, v2, v5
	ds_write_b32 v75, v2 offset:34312
	v_rcp_f32_e32 v2, v7
	s_nop 0
	v_mul_f32_e32 v2, v4, v2
	s_cbranch_execz .LBB0_2053
	s_branch .LBB0_2054

.LBB0_2054:
	s_or_b32 s4, s8, 3
	s_cmpk_gt_i32 s4, 0xfd
	s_cselect_b64 s[4:5], -1, 0
	s_and_b64 s[4:5], s[4:5], s[12:13]
	s_and_b64 vcc, exec, s[4:5]
	ds_write_b32 v75, v2 offset:34568
	s_cbranch_vccnz .LBB0_2056
	s_waitcnt vmcnt(0) lgkmcnt(0)
	v_add_f32_e32 v2, v18, v98
	v_add_f32_e32 v2, v2, v101
	v_mul_f32_e32 v3, 0x3d372713, v2
	v_mul_f32_e32 v3, v2, v3
	v_fma_f32 v3, v2, v3, v2
	v_mul_f32_e32 v3, 0x3f4c422a, v3
	v_mul_f32_e32 v3, -2.0, v3
	v_mul_f32_e32 v3, 0x3fb8aa3b, v3
	v_exp_f32_e32 v3, v3
	v_add_f32_e32 v4, v19, v97
	v_add_f32_e32 v4, v4, v99
	v_mul_f32_e32 v7, 0x3d372713, v4
	v_add_f32_e32 v3, 1.0, v3
	v_mul_f32_e32 v7, v4, v7
	v_fma_f32 v7, v4, v7, v4
	v_mul_f32_e32 v7, 0x3f4c422a, v7
	v_mul_f32_e32 v7, -2.0, v7
	v_mul_f32_e32 v7, 0x3fb8aa3b, v7
	v_exp_f32_e32 v7, v7
	s_nop 0
	v_add_f32_e32 v7, 1.0, v7
	v_rcp_f32_e32 v5, v3
	s_nop 0
	v_mul_f32_e32 v2, v2, v5
	ds_write_b32 v75, v2 offset:34828
	v_rcp_f32_e32 v2, v7
	s_nop 0
	v_mul_f32_e32 v2, v4, v2
	s_cbranch_execz .LBB0_2057
	s_branch .LBB0_2058

.LBB0_2058:
	s_or_b32 s4, s8, 4
	s_cmpk_gt_i32 s4, 0xfd
	s_cselect_b64 s[4:5], -1, 0
	s_and_b64 s[4:5], s[4:5], s[12:13]
	s_and_b64 vcc, exec, s[4:5]
	ds_write_b32 v75, v2 offset:35084
	s_cbranch_vccnz .LBB0_2060
	s_waitcnt vmcnt(0) lgkmcnt(0)
	v_add_f32_e32 v2, v18, v94
	v_add_f32_e32 v2, v2, v96
	v_mul_f32_e32 v3, 0x3d372713, v2
	v_mul_f32_e32 v3, v2, v3
	v_fma_f32 v3, v2, v3, v2
	v_mul_f32_e32 v3, 0x3f4c422a, v3
	v_mul_f32_e32 v3, -2.0, v3
	v_mul_f32_e32 v3, 0x3fb8aa3b, v3
	v_exp_f32_e32 v3, v3
	v_add_f32_e32 v4, v19, v93
	v_add_f32_e32 v4, v4, v95
	v_mul_f32_e32 v7, 0x3d372713, v4
	v_add_f32_e32 v3, 1.0, v3
	v_mul_f32_e32 v7, v4, v7
	v_fma_f32 v7, v4, v7, v4
	v_mul_f32_e32 v7, 0x3f4c422a, v7
	v_mul_f32_e32 v7, -2.0, v7
	v_mul_f32_e32 v7, 0x3fb8aa3b, v7
	v_exp_f32_e32 v7, v7
	s_nop 0
	v_add_f32_e32 v7, 1.0, v7
	v_rcp_f32_e32 v5, v3
	s_nop 0
	v_mul_f32_e32 v2, v2, v5
	ds_write_b32 v75, v2 offset:35344
	v_rcp_f32_e32 v2, v7
	s_nop 0
	v_mul_f32_e32 v2, v4, v2
	s_cbranch_execz .LBB0_2061
	s_branch .LBB0_2062

.LBB0_2062:
	s_or_b32 s4, s8, 5
	s_cmpk_gt_i32 s4, 0xfd
	s_cselect_b64 s[4:5], -1, 0
	s_and_b64 s[4:5], s[4:5], s[12:13]
	s_and_b64 vcc, exec, s[4:5]
	ds_write_b32 v75, v2 offset:35600
	s_cbranch_vccnz .LBB0_2064
	s_waitcnt vmcnt(0) lgkmcnt(0)
	v_add_f32_e32 v2, v18, v90
	v_add_f32_e32 v2, v2, v92
	v_mul_f32_e32 v3, 0x3d372713, v2
	v_mul_f32_e32 v3, v2, v3
	v_fma_f32 v3, v2, v3, v2
	v_mul_f32_e32 v3, 0x3f4c422a, v3
	v_mul_f32_e32 v3, -2.0, v3
	v_mul_f32_e32 v3, 0x3fb8aa3b, v3
	v_exp_f32_e32 v3, v3
	v_add_f32_e32 v4, v19, v89
	v_add_f32_e32 v4, v4, v91
	v_mul_f32_e32 v7, 0x3d372713, v4
	v_add_f32_e32 v3, 1.0, v3
	v_mul_f32_e32 v7, v4, v7
	v_fma_f32 v7, v4, v7, v4
	v_mul_f32_e32 v7, 0x3f4c422a, v7
	v_mul_f32_e32 v7, -2.0, v7
	v_mul_f32_e32 v7, 0x3fb8aa3b, v7
	v_exp_f32_e32 v7, v7
	s_nop 0
	v_add_f32_e32 v7, 1.0, v7
	v_rcp_f32_e32 v5, v3
	s_nop 0
	v_mul_f32_e32 v2, v2, v5
	ds_write_b32 v75, v2 offset:35860
	v_rcp_f32_e32 v2, v7
	s_nop 0
	v_mul_f32_e32 v2, v4, v2
	s_cbranch_execz .LBB0_2065
	s_branch .LBB0_2066

.LBB0_2066:
	s_or_b32 s4, s8, 6
	s_cmpk_gt_i32 s4, 0xfd
	s_cselect_b64 s[4:5], -1, 0
	s_and_b64 s[4:5], s[4:5], s[12:13]
	s_and_b64 vcc, exec, s[4:5]
	ds_write_b32 v75, v2 offset:36116
	s_cbranch_vccnz .LBB0_2068
	s_waitcnt vmcnt(0) lgkmcnt(0)
	v_add_f32_e32 v2, v18, v87
	v_add_f32_e32 v2, v2, v88
	v_mul_f32_e32 v3, 0x3d372713, v2
	v_mul_f32_e32 v3, v2, v3
	v_fma_f32 v3, v2, v3, v2
	v_mul_f32_e32 v3, 0x3f4c422a, v3
	v_mul_f32_e32 v3, -2.0, v3
	v_mul_f32_e32 v3, 0x3fb8aa3b, v3
	v_exp_f32_e32 v3, v3
	v_add_f32_e32 v4, v19, v85
	v_add_f32_e32 v4, v4, v86
	v_mul_f32_e32 v7, 0x3d372713, v4
	v_add_f32_e32 v3, 1.0, v3
	v_mul_f32_e32 v7, v4, v7
	v_fma_f32 v7, v4, v7, v4
	v_mul_f32_e32 v7, 0x3f4c422a, v7
	v_mul_f32_e32 v7, -2.0, v7
	v_mul_f32_e32 v7, 0x3fb8aa3b, v7
	v_exp_f32_e32 v7, v7
	s_nop 0
	v_add_f32_e32 v7, 1.0, v7
	v_rcp_f32_e32 v5, v3
	s_nop 0
	v_mul_f32_e32 v2, v2, v5
	ds_write_b32 v75, v2 offset:36376
	v_rcp_f32_e32 v2, v7
	s_nop 0
	v_mul_f32_e32 v2, v4, v2
	s_cbranch_execz .LBB0_2069
	s_branch .LBB0_2070

.LBB0_2070:
	s_or_b32 s4, s8, 7
	s_cmpk_gt_i32 s4, 0xfd
	s_cselect_b64 s[4:5], -1, 0
	s_and_b64 s[4:5], s[4:5], s[12:13]
	s_and_b64 vcc, exec, s[4:5]
	ds_write_b32 v75, v2 offset:36632
	s_cbranch_vccnz .LBB0_2072
	s_waitcnt vmcnt(0) lgkmcnt(0)
	v_add_f32_e32 v2, v18, v82
	v_add_f32_e32 v2, v2, v84
	v_mul_f32_e32 v3, 0x3d372713, v2
	v_mul_f32_e32 v3, v2, v3
	v_fma_f32 v3, v2, v3, v2
	v_mul_f32_e32 v3, 0x3f4c422a, v3
	v_mul_f32_e32 v3, -2.0, v3
	v_mul_f32_e32 v3, 0x3fb8aa3b, v3
	v_exp_f32_e32 v3, v3
	v_add_f32_e32 v4, v19, v81
	v_add_f32_e32 v4, v4, v83
	v_mul_f32_e32 v7, 0x3d372713, v4
	v_add_f32_e32 v3, 1.0, v3
	v_mul_f32_e32 v7, v4, v7
	v_fma_f32 v7, v4, v7, v4
	v_mul_f32_e32 v7, 0x3f4c422a, v7
	v_mul_f32_e32 v7, -2.0, v7
	v_mul_f32_e32 v7, 0x3fb8aa3b, v7
	v_exp_f32_e32 v7, v7
	s_nop 0
	v_add_f32_e32 v7, 1.0, v7
	v_rcp_f32_e32 v5, v3
	s_nop 0
	v_mul_f32_e32 v2, v2, v5
	ds_write_b32 v75, v2 offset:36892
	v_rcp_f32_e32 v2, v7
	s_nop 0
	v_mul_f32_e32 v2, v4, v2
	s_cbranch_execz .LBB0_2073
	s_branch .LBB0_2074

.LBB0_2074:
	s_or_b32 s4, s8, 8
	s_cmpk_gt_i32 s4, 0xfd
	s_cselect_b64 s[4:5], -1, 0
	s_and_b64 s[4:5], s[4:5], s[12:13]
	s_and_b64 vcc, exec, s[4:5]
	ds_write_b32 v75, v2 offset:37148
	s_cbranch_vccnz .LBB0_2076
	s_waitcnt vmcnt(0) lgkmcnt(0)
	v_add_f32_e32 v2, v18, v79
	v_add_f32_e32 v2, v2, v80
	v_mul_f32_e32 v3, 0x3d372713, v2
	v_mul_f32_e32 v3, v2, v3
	v_fma_f32 v3, v2, v3, v2
	v_mul_f32_e32 v3, 0x3f4c422a, v3
	v_mul_f32_e32 v3, -2.0, v3
	v_mul_f32_e32 v3, 0x3fb8aa3b, v3
	v_exp_f32_e32 v3, v3
	v_add_f32_e32 v4, v19, v77
	v_add_f32_e32 v4, v4, v78
	v_mul_f32_e32 v7, 0x3d372713, v4
	v_add_f32_e32 v3, 1.0, v3
	v_mul_f32_e32 v7, v4, v7
	v_fma_f32 v7, v4, v7, v4
	v_mul_f32_e32 v7, 0x3f4c422a, v7
	v_mul_f32_e32 v7, -2.0, v7
	v_mul_f32_e32 v7, 0x3fb8aa3b, v7
	v_exp_f32_e32 v7, v7
	s_nop 0
	v_add_f32_e32 v7, 1.0, v7
	v_rcp_f32_e32 v5, v3
	s_nop 0
	v_mul_f32_e32 v2, v2, v5
	ds_write_b32 v75, v2 offset:37408
	v_rcp_f32_e32 v2, v7
	s_nop 0
	v_mul_f32_e32 v2, v4, v2
	s_cbranch_execz .LBB0_2077
	s_branch .LBB0_2078

.LBB0_2078:
	s_or_b32 s4, s8, 9
	s_cmpk_gt_i32 s4, 0xfd
	s_cselect_b64 s[4:5], -1, 0
	s_and_b64 s[4:5], s[4:5], s[12:13]
	s_and_b64 vcc, exec, s[4:5]
	ds_write_b32 v75, v2 offset:37664
	s_cbranch_vccnz .LBB0_2080
	s_waitcnt vmcnt(0) lgkmcnt(0)
	v_add_f32_e32 v2, v18, v73
	v_add_f32_e32 v2, v2, v76
	v_mul_f32_e32 v3, 0x3d372713, v2
	v_mul_f32_e32 v3, v2, v3
	v_fma_f32 v3, v2, v3, v2
	v_mul_f32_e32 v3, 0x3f4c422a, v3
	v_mul_f32_e32 v3, -2.0, v3
	v_mul_f32_e32 v3, 0x3fb8aa3b, v3
	v_exp_f32_e32 v3, v3
	v_add_f32_e32 v4, v19, v72
	v_add_f32_e32 v4, v4, v74
	v_mul_f32_e32 v7, 0x3d372713, v4
	v_add_f32_e32 v3, 1.0, v3
	v_mul_f32_e32 v7, v4, v7
	v_fma_f32 v7, v4, v7, v4
	v_mul_f32_e32 v7, 0x3f4c422a, v7
	v_mul_f32_e32 v7, -2.0, v7
	v_mul_f32_e32 v7, 0x3fb8aa3b, v7
	v_exp_f32_e32 v7, v7
	s_nop 0
	v_add_f32_e32 v7, 1.0, v7
	v_rcp_f32_e32 v5, v3
	s_nop 0
	v_mul_f32_e32 v2, v2, v5
	ds_write_b32 v75, v2 offset:37924
	v_rcp_f32_e32 v2, v7
	s_nop 0
	v_mul_f32_e32 v2, v4, v2
	s_cbranch_execz .LBB0_2081
	s_branch .LBB0_2082

.LBB0_2082:
	s_or_b32 s4, s8, 10
	s_cmpk_gt_i32 s4, 0xfd
	s_cselect_b64 s[4:5], -1, 0
	s_and_b64 s[4:5], s[4:5], s[12:13]
	s_and_b64 vcc, exec, s[4:5]
	ds_write_b32 v75, v2 offset:38180
	s_cbranch_vccnz .LBB0_2084
	s_waitcnt vmcnt(0) lgkmcnt(0)
	v_add_f32_e32 v2, v18, v70
	v_add_f32_e32 v2, v2, v71
	v_mul_f32_e32 v3, 0x3d372713, v2
	v_mul_f32_e32 v3, v2, v3
	v_fma_f32 v3, v2, v3, v2
	v_mul_f32_e32 v3, 0x3f4c422a, v3
	v_mul_f32_e32 v3, -2.0, v3
	v_mul_f32_e32 v3, 0x3fb8aa3b, v3
	v_exp_f32_e32 v3, v3
	v_add_f32_e32 v4, v19, v68
	v_add_f32_e32 v4, v4, v69
	v_mul_f32_e32 v7, 0x3d372713, v4
	v_add_f32_e32 v3, 1.0, v3
	v_mul_f32_e32 v7, v4, v7
	v_fma_f32 v7, v4, v7, v4
	v_mul_f32_e32 v7, 0x3f4c422a, v7
	v_mul_f32_e32 v7, -2.0, v7
	v_mul_f32_e32 v7, 0x3fb8aa3b, v7
	v_exp_f32_e32 v7, v7
	s_nop 0
	v_add_f32_e32 v7, 1.0, v7
	v_rcp_f32_e32 v5, v3
	s_nop 0
	v_mul_f32_e32 v2, v2, v5
	ds_write_b32 v75, v2 offset:38440
	v_rcp_f32_e32 v2, v7
	s_nop 0
	v_mul_f32_e32 v2, v4, v2
	s_cbranch_execz .LBB0_2085
	s_branch .LBB0_2086

.LBB0_2086:
	s_or_b32 s4, s8, 11
	s_cmpk_gt_i32 s4, 0xfd
	s_cselect_b64 s[4:5], -1, 0
	s_and_b64 s[4:5], s[4:5], s[12:13]
	s_and_b64 vcc, exec, s[4:5]
	ds_write_b32 v75, v2 offset:38696
	s_cbranch_vccnz .LBB0_2088
	s_waitcnt vmcnt(0) lgkmcnt(0)
	v_add_f32_e32 v2, v18, v65
	v_add_f32_e32 v2, v2, v67
	v_mul_f32_e32 v3, 0x3d372713, v2
	v_mul_f32_e32 v3, v2, v3
	v_fma_f32 v3, v2, v3, v2
	v_mul_f32_e32 v3, 0x3f4c422a, v3
	v_mul_f32_e32 v3, -2.0, v3
	v_mul_f32_e32 v3, 0x3fb8aa3b, v3
	v_exp_f32_e32 v3, v3
	v_add_f32_e32 v4, v19, v64
	v_add_f32_e32 v4, v4, v66
	v_mul_f32_e32 v7, 0x3d372713, v4
	v_add_f32_e32 v3, 1.0, v3
	v_mul_f32_e32 v7, v4, v7
	v_fma_f32 v7, v4, v7, v4
	v_mul_f32_e32 v7, 0x3f4c422a, v7
	v_mul_f32_e32 v7, -2.0, v7
	v_mul_f32_e32 v7, 0x3fb8aa3b, v7
	v_exp_f32_e32 v7, v7
	s_nop 0
	v_add_f32_e32 v7, 1.0, v7
	v_rcp_f32_e32 v5, v3
	s_nop 0
	v_mul_f32_e32 v2, v2, v5
	ds_write_b32 v75, v2 offset:38956
	v_rcp_f32_e32 v2, v7
	s_nop 0
	v_mul_f32_e32 v2, v4, v2
	s_cbranch_execz .LBB0_2089
	s_branch .LBB0_2090

.LBB0_2090:
	s_or_b32 s4, s8, 12
	s_cmpk_gt_i32 s4, 0xfd
	s_cselect_b64 s[4:5], -1, 0
	s_and_b64 s[4:5], s[4:5], s[12:13]
	s_and_b64 vcc, exec, s[4:5]
	ds_write_b32 v75, v2 offset:39212
	s_cbranch_vccnz .LBB0_2092
	s_waitcnt vmcnt(0) lgkmcnt(0)
	v_add_f32_e32 v2, v18, v62
	v_add_f32_e32 v2, v2, v63
	v_mul_f32_e32 v3, 0x3d372713, v2
	v_mul_f32_e32 v3, v2, v3
	v_fma_f32 v3, v2, v3, v2
	v_mul_f32_e32 v3, 0x3f4c422a, v3
	v_mul_f32_e32 v3, -2.0, v3
	v_mul_f32_e32 v3, 0x3fb8aa3b, v3
	v_exp_f32_e32 v3, v3
	v_add_f32_e32 v4, v19, v60
	v_add_f32_e32 v4, v4, v61
	v_mul_f32_e32 v7, 0x3d372713, v4
	v_add_f32_e32 v3, 1.0, v3
	v_mul_f32_e32 v7, v4, v7
	v_fma_f32 v7, v4, v7, v4
	v_mul_f32_e32 v7, 0x3f4c422a, v7
	v_mul_f32_e32 v7, -2.0, v7
	v_mul_f32_e32 v7, 0x3fb8aa3b, v7
	v_exp_f32_e32 v7, v7
	s_nop 0
	v_add_f32_e32 v7, 1.0, v7
	v_rcp_f32_e32 v5, v3
	s_nop 0
	v_mul_f32_e32 v2, v2, v5
	ds_write_b32 v75, v2 offset:39472
	v_rcp_f32_e32 v2, v7
	s_nop 0
	v_mul_f32_e32 v2, v4, v2
	s_cbranch_execz .LBB0_2093
	s_branch .LBB0_2094

.LBB0_2094:
	s_or_b32 s4, s8, 13
	s_cmpk_gt_i32 s4, 0xfd
	s_cselect_b64 s[4:5], -1, 0
	s_and_b64 s[4:5], s[4:5], s[12:13]
	s_and_b64 vcc, exec, s[4:5]
	ds_write_b32 v75, v2 offset:39728
	s_cbranch_vccnz .LBB0_2096
	s_waitcnt vmcnt(0) lgkmcnt(0)
	v_add_f32_e32 v2, v18, v56
	v_add_f32_e32 v2, v2, v59
	v_mul_f32_e32 v3, 0x3d372713, v2
	v_mul_f32_e32 v3, v2, v3
	v_fma_f32 v3, v2, v3, v2
	v_mul_f32_e32 v3, 0x3f4c422a, v3
	v_mul_f32_e32 v3, -2.0, v3
	v_mul_f32_e32 v3, 0x3fb8aa3b, v3
	v_exp_f32_e32 v3, v3
	v_add_f32_e32 v4, v19, v55
	v_add_f32_e32 v4, v4, v57
	v_mul_f32_e32 v7, 0x3d372713, v4
	v_add_f32_e32 v3, 1.0, v3
	v_mul_f32_e32 v7, v4, v7
	v_fma_f32 v7, v4, v7, v4
	v_mul_f32_e32 v7, 0x3f4c422a, v7
	v_mul_f32_e32 v7, -2.0, v7
	v_mul_f32_e32 v7, 0x3fb8aa3b, v7
	v_exp_f32_e32 v7, v7
	s_nop 0
	v_add_f32_e32 v7, 1.0, v7
	v_rcp_f32_e32 v5, v3
	s_nop 0
	v_mul_f32_e32 v2, v2, v5
	ds_write_b32 v75, v2 offset:39988
	v_rcp_f32_e32 v2, v7
	s_nop 0
	v_mul_f32_e32 v2, v4, v2
	s_cbranch_execz .LBB0_2097
	s_branch .LBB0_2098

.LBB0_2098:
	s_or_b32 s4, s8, 14
	s_cmpk_gt_i32 s4, 0xfd
	s_cselect_b64 s[4:5], -1, 0
	s_and_b64 s[4:5], s[4:5], s[12:13]
	s_and_b64 vcc, exec, s[4:5]
	ds_write_b32 v75, v2 offset:40244
	s_cbranch_vccnz .LBB0_2100
	s_waitcnt vmcnt(0) lgkmcnt(0)
	v_add_f32_e32 v2, v18, v53
	v_add_f32_e32 v2, v2, v54
	v_mul_f32_e32 v3, 0x3d372713, v2
	v_mul_f32_e32 v3, v2, v3
	v_fma_f32 v3, v2, v3, v2
	v_mul_f32_e32 v3, 0x3f4c422a, v3
	v_mul_f32_e32 v3, -2.0, v3
	v_mul_f32_e32 v3, 0x3fb8aa3b, v3
	v_exp_f32_e32 v3, v3
	v_add_f32_e32 v4, v19, v51
	v_add_f32_e32 v4, v4, v52
	v_mul_f32_e32 v7, 0x3d372713, v4
	v_add_f32_e32 v3, 1.0, v3
	v_mul_f32_e32 v7, v4, v7
	v_fma_f32 v7, v4, v7, v4
	v_mul_f32_e32 v7, 0x3f4c422a, v7
	v_mul_f32_e32 v7, -2.0, v7
	v_mul_f32_e32 v7, 0x3fb8aa3b, v7
	v_exp_f32_e32 v7, v7
	s_nop 0
	v_add_f32_e32 v7, 1.0, v7
	v_rcp_f32_e32 v5, v3
	s_nop 0
	v_mul_f32_e32 v2, v2, v5
	ds_write_b32 v75, v2 offset:40504
	v_rcp_f32_e32 v2, v7
	s_nop 0
	v_mul_f32_e32 v2, v4, v2
	s_cbranch_execz .LBB0_2101
	s_branch .LBB0_2102

.LBB0_2102:
	s_or_b32 s4, s8, 15
	s_cmpk_gt_i32 s4, 0xfd
	s_cselect_b64 s[4:5], -1, 0
	s_and_b64 s[4:5], s[4:5], s[12:13]
	s_and_b64 vcc, exec, s[4:5]
	ds_write_b32 v75, v2 offset:40760
	s_cbranch_vccnz .LBB0_2104
	s_waitcnt vmcnt(0) lgkmcnt(0)
	v_add_f32_e32 v2, v18, v49
	v_add_f32_e32 v2, v2, v50
	v_mul_f32_e32 v3, 0x3d372713, v2
	v_mul_f32_e32 v3, v2, v3
	v_fma_f32 v3, v2, v3, v2
	v_mul_f32_e32 v3, 0x3f4c422a, v3
	v_mul_f32_e32 v3, -2.0, v3
	v_mul_f32_e32 v3, 0x3fb8aa3b, v3
	v_exp_f32_e32 v3, v3
	v_add_f32_e32 v1, v19, v1
	v_add_f32_e32 v1, v1, v48
	v_mul_f32_e32 v6, 0x3d372713, v1
	v_add_f32_e32 v3, 1.0, v3
	v_mul_f32_e32 v6, v1, v6
	v_fma_f32 v6, v1, v6, v1
	v_mul_f32_e32 v6, 0x3f4c422a, v6
	v_mul_f32_e32 v6, -2.0, v6
	v_mul_f32_e32 v6, 0x3fb8aa3b, v6
	v_exp_f32_e32 v6, v6
	s_nop 0
	v_add_f32_e32 v6, 1.0, v6
	v_rcp_f32_e32 v4, v3
	s_nop 0
	v_mul_f32_e32 v2, v2, v4
	ds_write_b32 v75, v2 offset:41020
	v_rcp_f32_e32 v2, v6
	s_nop 0
	v_mul_f32_e32 v1, v1, v2
	s_cbranch_execz .LBB0_2105
	s_branch .LBB0_2106

.LBB0_2892:
	s_or_b64 exec, exec, s[8:9]
	s_and_saveexec_b64 s[8:9], s[6:7]
	ds_write_b32 v141, v35 offset:33024
	s_or_b64 exec, exec, s[8:9]
	s_waitcnt lgkmcnt(0)
	ds_read_b32 v38, v1 offset:33024
	ds_read2_b32 v[34:35], v142 offset1:32
	ds_read2_b32 v[36:37], v106 offset1:32
	s_or_b32 s6, s50, s52
	s_add_u32 s6, s6, s70
	s_addc_u32 s7, 0, s71
	s_waitcnt lgkmcnt(0)
	v_fma_f32 v18, v18, v38, v34
	v_fmac_f32_e32 v35, v2, v38
	ds_write2_b32 v142, v18, v35 offset1:32
	ds_read_b32 v2, v1 offset:33028
	ds_read2_b32 v[34:35], v107 offset1:32
	s_mov_b64 s[8:9], 0xdc00000
	s_waitcnt lgkmcnt(0)
	v_fma_f32 v18, v19, v2, v36
	v_fmac_f32_e32 v37, v3, v2
	ds_write2_b32 v106, v18, v37 offset1:32
	ds_read_b32 v18, v1 offset:33032
	ds_read2_b32 v[2:3], v108 offset1:32
	s_waitcnt lgkmcnt(0)
	v_fma_f32 v19, v20, v18, v34
	v_fmac_f32_e32 v35, v4, v18
	ds_write2_b32 v107, v19, v35 offset1:32
	ds_read_b32 v4, v1 offset:33036
	ds_read2_b32 v[18:19], v109 offset1:32
	s_waitcnt lgkmcnt(0)
	v_fma_f32 v2, v21, v4, v2
	v_fmac_f32_e32 v3, v5, v4
	ds_write2_b32 v108, v2, v3 offset1:32
	ds_read_b32 v4, v1 offset:33056
	ds_read2_b32 v[2:3], v110 offset1:32
	s_waitcnt lgkmcnt(0)
	v_fma_f32 v5, v22, v4, v18
	v_fmac_f32_e32 v19, v6, v4
	ds_write2_b32 v109, v5, v19 offset1:32
	ds_read_b32 v6, v1 offset:33060
	ds_read2_b32 v[4:5], v112 offset1:32
	s_waitcnt lgkmcnt(0)
	v_fma_f32 v2, v23, v6, v2
	v_fmac_f32_e32 v3, v7, v6
	ds_write2_b32 v110, v2, v3 offset1:32
	ds_read_b32 v6, v1 offset:33064
	ds_read2_b32 v[2:3], v113 offset1:32
	v_lshlrev_b32_e32 v7, 3, v139
	s_waitcnt lgkmcnt(0)
	v_fma_f32 v4, v24, v6, v4
	v_fmac_f32_e32 v5, v8, v6
	ds_write2_b32 v112, v4, v5 offset1:32
	ds_read_b32 v6, v1 offset:33068
	ds_read2_b32 v[4:5], v114 offset1:32
	v_and_or_b32 v8, v93, 3, s75
	v_lshlrev_b32_e32 v98, 7, v8
	s_waitcnt lgkmcnt(0)
	v_fma_f32 v2, v25, v6, v2
	v_fmac_f32_e32 v3, v9, v6
	ds_write2_b32 v113, v2, v3 offset1:32
	ds_read_b32 v6, v1 offset:33088
	ds_read2_b32 v[2:3], v115 offset1:32
	v_and_b32_e32 v9, 56, v7
	s_waitcnt lgkmcnt(0)
	v_fma_f32 v4, v26, v6, v4
	v_fmac_f32_e32 v5, v10, v6
	ds_write2_b32 v114, v4, v5 offset1:32
	ds_read_b32 v6, v1 offset:33092
	ds_read2_b32 v[4:5], v117 offset1:32
	s_waitcnt lgkmcnt(0)
	v_fma_f32 v2, v27, v6, v2
	v_fmac_f32_e32 v3, v11, v6
	ds_write2_b32 v115, v2, v3 offset1:32
	ds_read_b32 v6, v1 offset:33096
	ds_read2_b32 v[2:3], v118 offset1:32
	s_waitcnt lgkmcnt(0)
	v_fma_f32 v4, v28, v6, v4
	v_fmac_f32_e32 v5, v12, v6
	ds_write2_b32 v117, v4, v5 offset1:32
	ds_read_b32 v6, v1 offset:33100
	ds_read2_b32 v[4:5], v91 offset1:32
	s_waitcnt lgkmcnt(0)
	v_fma_f32 v2, v29, v6, v2
	v_fmac_f32_e32 v3, v13, v6
	ds_write2_b32 v118, v2, v3 offset1:32
	ds_read_b32 v6, v1 offset:33120
	ds_read2_b32 v[2:3], v102 offset1:32
	s_waitcnt lgkmcnt(0)
	v_fma_f32 v4, v30, v6, v4
	v_fmac_f32_e32 v5, v14, v6
	ds_write2_b32 v91, v4, v5 offset1:32
	ds_read_b32 v6, v1 offset:33124
	ds_read2_b32 v[4:5], v111 offset1:32
	v_lshl_add_u32 v14, v9, 2, s54
	v_lshl_add_u32 v8, v93, 8, v14
	s_waitcnt lgkmcnt(0)
	v_fma_f32 v2, v31, v6, v2
	v_fmac_f32_e32 v3, v15, v6
	ds_write2_b32 v102, v2, v3 offset1:32
	ds_read_b32 v6, v1 offset:33128
	ds_read2_b32 v[2:3], v116 offset1:32
	s_waitcnt lgkmcnt(0)
	v_fma_f32 v4, v32, v6, v4
	v_fmac_f32_e32 v5, v16, v6
	ds_write2_b32 v111, v4, v5 offset1:32
	ds_read_b32 v1, v1 offset:33132
	v_lshl_add_u64 v[6:7], s[68:69], 0, v[98:99]
	v_lshlrev_b32_e32 v98, 1, v9
	v_lshl_add_u64 v[6:7], v[6:7], 0, v[98:99]
	v_lshl_add_u64 v[6:7], v[6:7], 0, s[8:9]
	s_waitcnt lgkmcnt(0)
	v_fma_f32 v2, v33, v1, v2
	v_fmac_f32_e32 v3, v17, v1
	ds_write2_b32 v116, v2, v3 offset1:32
	s_waitcnt lgkmcnt(0)
	ds_read_b128 v[2:5], v8 offset:36864
	ds_read_b128 v[8:11], v8 offset:36880
	s_waitcnt lgkmcnt(0)
	v_bfe_u32 v1, v2, 16, 1
	v_bfe_u32 v12, v3, 16, 1
	v_add3_u32 v1, v2, v1, s2
	v_bfe_u32 v13, v4, 16, 1
	v_bfe_u32 v15, v5, 16, 1
	v_add3_u32 v2, v3, v12, s2
	v_lshrrev_b32_e32 v1, 16, v1
	v_add3_u32 v3, v4, v13, s2
	v_add3_u32 v4, v5, v15, s2
	v_and_or_b32 v2, v2, s33, v1
	v_lshrrev_b32_e32 v1, 5, v139
	v_lshrrev_b32_e32 v3, 16, v3
	v_or_b32_e32 v12, s6, v1
	v_mov_b32_e32 v13, s7
	v_and_or_b32 v3, v4, s33, v3
	v_cvt_pk_bf16_f32 v4, v8, v9
	v_cvt_pk_bf16_f32 v5, v10, v11
	v_lshlrev_b64 v[8:9], 11, v[12:13]
	v_lshl_add_u64 v[8:9], v[6:7], 0, v[8:9]
	v_or_b32_e32 v1, 8, v93
	global_store_dwordx4 v[8:9], v[2:5], off
	v_lshl_add_u32 v8, v1, 8, v14
	ds_read_b128 v[2:5], v8 offset:36864
	ds_read_b128 v[8:11], v8 offset:36880
	v_lshrrev_b32_e32 v1, 2, v1
	s_waitcnt lgkmcnt(0)
	v_cvt_pk_bf16_f32 v2, v2, v3
	v_cvt_pk_bf16_f32 v3, v4, v5
	v_cvt_pk_bf16_f32 v4, v8, v9
	v_or_b32_e32 v12, s6, v1
	v_cvt_pk_bf16_f32 v5, v10, v11
	v_lshlrev_b64 v[8:9], 11, v[12:13]
	v_lshl_add_u64 v[8:9], v[6:7], 0, v[8:9]
	v_or_b32_e32 v1, 16, v93
	global_store_dwordx4 v[8:9], v[2:5], off
	v_lshl_add_u32 v8, v1, 8, v14
	ds_read_b128 v[2:5], v8 offset:36864
	ds_read_b128 v[8:11], v8 offset:36880
	v_lshrrev_b32_e32 v1, 2, v1
	s_waitcnt lgkmcnt(0)
	v_cvt_pk_bf16_f32 v2, v2, v3
	v_cvt_pk_bf16_f32 v3, v4, v5
	v_cvt_pk_bf16_f32 v4, v8, v9
	v_or_b32_e32 v12, s6, v1
	v_cvt_pk_bf16_f32 v5, v10, v11
	v_lshlrev_b64 v[8:9], 11, v[12:13]
	v_lshl_add_u64 v[8:9], v[6:7], 0, v[8:9]
	v_or_b32_e32 v1, 24, v93
	global_store_dwordx4 v[8:9], v[2:5], off
	v_lshl_add_u32 v8, v1, 8, v14
	ds_read_b128 v[2:5], v8 offset:36864
	ds_read_b128 v[8:11], v8 offset:36880
	v_lshrrev_b32_e32 v1, 2, v1
	s_waitcnt lgkmcnt(0)
	v_cvt_pk_bf16_f32 v2, v2, v3
	v_cvt_pk_bf16_f32 v3, v4, v5
	v_cvt_pk_bf16_f32 v4, v8, v9
	v_or_b32_e32 v12, s6, v1
	v_cvt_pk_bf16_f32 v5, v10, v11
	v_lshlrev_b64 v[8:9], 11, v[12:13]
	v_lshl_add_u64 v[6:7], v[6:7], 0, v[8:9]
	global_store_dwordx4 v[6:7], v[2:5], off
	s_waitcnt lgkmcnt(0)
	s_waitcnt lgkmcnt(0)
	s_barrier

.LBB0_2937:
	v_lshl_add_u64 v[18:19], s[68:69], 0, v[94:95]
	v_lshl_add_u64 v[22:23], s[68:69], 0, v[92:93]
	v_add_co_u32_e32 v20, vcc, 0x7800000, v18
	v_add_co_u32_e64 v102, s[6:7], s24, v22
	s_nop 0
	v_addc_co_u32_e32 v21, vcc, 0, v19, vcc
	v_addc_co_u32_e64 v103, s[6:7], 0, v23, s[6:7]
	v_add_co_u32_e64 v104, s[6:7], s25, v22
	v_add_co_u32_e32 v22, vcc, 0x7801000, v18
	s_nop 0
	v_addc_co_u32_e64 v105, s[6:7], 0, v23, s[6:7]
	global_load_dwordx4 v[78:81], v[20:21], off
	global_load_dwordx4 v[74:77], v[20:21], off offset:1024
	global_load_dwordx4 v[70:73], v[20:21], off offset:2048
	global_load_dwordx4 v[66:69], v[20:21], off offset:3072
	v_addc_co_u32_e32 v23, vcc, 0, v19, vcc
	v_add_co_u32_e32 v20, vcc, 0x7802000, v18
	global_load_dwordx4 v[62:65], v[22:23], off
	global_load_dwordx4 v[58:61], v[22:23], off offset:1024
	global_load_dwordx4 v[54:57], v[22:23], off offset:2048
	global_load_dwordx4 v[50:53], v[22:23], off offset:3072
	v_addc_co_u32_e32 v21, vcc, 0, v19, vcc
	v_add_co_u32_e32 v82, vcc, 0x7803000, v18
	global_load_dwordx4 v[46:49], v[20:21], off
	global_load_dwordx4 v[42:45], v[20:21], off offset:1024
	global_load_dwordx4 v[38:41], v[20:21], off offset:2048
	global_load_dwordx4 v[34:37], v[20:21], off offset:3072
	v_addc_co_u32_e32 v83, vcc, 0, v19, vcc
	global_load_dwordx4 v[30:33], v[82:83], off
	global_load_dwordx4 v[26:29], v[82:83], off offset:1024
	global_load_dwordx4 v[22:25], v[82:83], off offset:2048
	global_load_dwordx4 v[18:21], v[82:83], off offset:3072
	s_ashr_i32 s8, s12, 13
	s_add_i32 s9, s12, 0xffffc002
	s_cmpk_lt_i32 s12, 0x4000
	s_cselect_b32 s6, s8, s9
	s_mul_hi_i32 s7, s6, 0x9000
	s_mul_i32 s6, s6, 0x9000
	s_add_u32 s9, s3, s6
	s_addc_u32 s11, s4, s7
	s_add_u32 s6, s9, 0x6000
	s_addc_u32 s7, s11, 0
	s_add_u32 s10, s9, 0x7000
	s_addc_u32 s11, s11, 0
	v_lshl_add_u64 v[82:83], s[6:7], 0, v[90:91]
	v_lshl_add_u64 v[86:87], s[10:11], 0, v[90:91]
	global_load_dwordx4 v[82:85], v[82:83], off
	v_lshl_add_u64 v[148:149], s[6:7], 0, v[96:97]
	global_load_dwordx4 v[86:89], v[86:87], off
	v_lshl_add_u64 v[142:143], s[6:7], 0, v[98:99]
	v_lshl_add_u64 v[134:135], s[6:7], 0, v[100:101]
	s_add_i32 s6, s12, 0xffffc003
	s_cmpk_lt_i32 s12, 0x3fff
	s_cselect_b32 s6, s8, s6
	s_mul_hi_i32 s7, s6, 0x9000
	s_mul_i32 s6, s6, 0x9000
	s_add_u32 s9, s3, s6
	v_lshl_add_u64 v[152:153], s[10:11], 0, v[96:97]
	v_lshl_add_u64 v[146:147], s[10:11], 0, v[98:99]
	v_lshl_add_u64 v[140:141], s[10:11], 0, v[100:101]
	s_addc_u32 s11, s4, s7
	s_add_u32 s6, s9, 0x6000
	s_addc_u32 s7, s11, 0
	s_add_u32 s10, s9, 0x7000
	v_lshl_add_u64 v[132:133], s[6:7], 0, v[90:91]
	v_lshl_add_u64 v[126:127], s[6:7], 0, v[96:97]
	v_lshl_add_u64 v[118:119], s[6:7], 0, v[98:99]
	v_lshl_add_u64 v[114:115], s[6:7], 0, v[100:101]
	s_addc_u32 s11, s11, 0
	s_add_i32 s6, s12, 0xffffc004
	s_cmpk_lt_i32 s12, 0x3ffe
	s_cselect_b32 s6, s8, s6
	s_mul_hi_i32 s7, s6, 0x9000
	s_mul_i32 s6, s6, 0x9000
	s_add_u32 s6, s3, s6
	s_addc_u32 s7, s4, s7
	v_lshl_add_u64 v[138:139], s[10:11], 0, v[90:91]
	v_lshl_add_u64 v[130:131], s[10:11], 0, v[96:97]
	v_lshl_add_u64 v[122:123], s[10:11], 0, v[98:99]
	v_lshl_add_u64 v[116:117], s[10:11], 0, v[100:101]
	s_add_u32 s10, s6, 0x6000
	s_addc_u32 s11, s7, 0
	s_add_u32 s6, s6, 0x7000
	s_addc_u32 s7, s7, 0
	s_add_i32 s9, s12, 0xffffc005
	s_cmpk_lt_i32 s12, 0x3ffd
	v_lshl_add_u64 v[156:157], s[6:7], 0, v[90:91]
	v_lshl_add_u64 v[154:155], s[6:7], 0, v[96:97]
	v_lshl_add_u64 v[150:151], s[6:7], 0, v[98:99]
	v_lshl_add_u64 v[136:137], s[6:7], 0, v[100:101]
	s_cselect_b32 s6, s8, s9
	s_mul_hi_i32 s7, s6, 0x9000
	s_mul_i32 s6, s6, 0x9000
	s_add_u32 s6, s3, s6
	s_addc_u32 s7, s4, s7
	s_waitcnt vmcnt(0) lgkmcnt(0)
	v_pk_mul_f32 v[158:159], v[80:81], v[80:81]
	v_pk_mul_f32 v[160:161], v[78:79], v[78:79]
	v_pk_mul_f32 v[162:163], v[76:77], v[76:77]
	v_pk_mul_f32 v[164:165], v[74:75], v[74:75]
	v_mul_f32_e32 v174, v71, v71
	v_mul_f32_e32 v176, v73, v73
	v_mul_f32_e32 v187, v68, v68
	v_mul_f32_e32 v189, v69, v69
	v_pk_mov_b32 v[178:179], v[160:161], v[158:159] op_sel:[1,0]
	v_mov_b32_e32 v161, v159
	v_pk_mov_b32 v[158:159], v[164:165], v[162:163] op_sel:[1,0]
	v_mov_b32_e32 v165, v163
	v_pk_fma_f32 v[162:163], v[70:71], v[70:71], v[174:175] op_sel_hi:[1,1,0]
	v_pk_fma_f32 v[174:175], v[72:73], v[72:73], v[176:177] op_sel_hi:[1,1,0]
	v_pk_mul_f32 v[176:177], v[64:65], v[64:65]
	v_pk_mul_f32 v[180:181], v[62:63], v[62:63]
	v_pk_mul_f32 v[182:183], v[60:61], v[60:61]
	v_pk_mul_f32 v[184:185], v[58:59], v[58:59]
	v_mul_f32_e32 v186, v55, v55
	v_mul_f32_e32 v188, v57, v57
	v_pk_add_f32 v[160:161], v[178:179], v[160:161]
	v_pk_add_f32 v[158:159], v[158:159], v[164:165]
	v_mov_b32_e32 v163, v187
	v_mov_b32_e32 v175, v189
	v_pk_mov_b32 v[164:165], v[180:181], v[176:177] op_sel:[1,0]
	v_mov_b32_e32 v181, v177
	v_pk_mov_b32 v[176:177], v[184:185], v[182:183] op_sel:[1,0]
	v_mov_b32_e32 v185, v183
	v_pk_fma_f32 v[178:179], v[54:55], v[54:55], v[186:187] op_sel_hi:[1,1,0]
	v_pk_fma_f32 v[182:183], v[56:57], v[56:57], v[188:189] op_sel_hi:[1,1,0]
	v_pk_mul_f32 v[186:187], v[48:49], v[48:49]
	v_pk_mul_f32 v[188:189], v[46:47], v[46:47]
	v_pk_mul_f32 v[190:191], v[44:45], v[44:45]
	v_pk_mul_f32 v[192:193], v[42:43], v[42:43]
	v_mul_f32_e32 v197, v66, v66
	v_mul_f32_e32 v203, v67, v67
	v_mul_f32_e32 v195, v52, v52
	v_mul_f32_e32 v202, v53, v53
	v_mul_f32_e32 v194, v39, v39
	v_mul_f32_e32 v196, v41, v41
	v_pk_add_f32 v[198:199], v[160:161], v[160:161] op_sel:[0,1] op_sel_hi:[1,0]
	v_pk_add_f32 v[200:201], v[158:159], v[158:159] op_sel:[0,1] op_sel_hi:[1,0]
	v_pk_add_f32 v[174:175], v[162:163], v[174:175]
	v_pk_add_f32 v[158:159], v[164:165], v[180:181]
	v_pk_add_f32 v[160:161], v[176:177], v[184:185]
	v_pk_mov_b32 v[162:163], v[188:189], v[186:187] op_sel:[1,0]
	v_mov_b32_e32 v189, v187
	v_pk_mov_b32 v[164:165], v[192:193], v[190:191] op_sel:[1,0]
	v_mov_b32_e32 v193, v191
	v_mul_f32_e32 v208, v50, v50
	v_mul_f32_e32 v209, v51, v51
	v_mul_f32_e32 v212, v36, v36
	v_mul_f32_e32 v213, v37, v37
	v_mov_b32_e32 v179, v195
	v_mov_b32_e32 v183, v202
	v_pk_fma_f32 v[176:177], v[38:39], v[38:39], v[194:195] op_sel_hi:[1,1,0]
	v_pk_fma_f32 v[180:181], v[40:41], v[40:41], v[196:197] op_sel_hi:[1,1,0]
	v_pk_mul_f32 v[184:185], v[32:33], v[32:33]
	v_pk_mul_f32 v[186:187], v[30:31], v[30:31]
	v_pk_mul_f32 v[190:191], v[28:29], v[28:29]
	v_pk_mul_f32 v[194:195], v[26:27], v[26:27]
	v_mov_b32_e32 v199, v197
	v_mov_b32_e32 v201, v203
	v_pk_add_f32 v[204:205], v[158:159], v[158:159] op_sel:[0,1] op_sel_hi:[1,0]
	v_pk_add_f32 v[206:207], v[160:161], v[160:161] op_sel:[0,1] op_sel_hi:[1,0]
	v_pk_add_f32 v[162:163], v[162:163], v[188:189]
	v_pk_add_f32 v[164:165], v[164:165], v[192:193]
	v_mul_f32_e32 v210, v34, v34
	v_mul_f32_e32 v211, v35, v35
	v_pk_add_f32 v[178:179], v[178:179], v[182:183]
	v_mov_b32_e32 v177, v212
	v_mov_b32_e32 v181, v213
	v_pk_mov_b32 v[182:183], v[186:187], v[184:185] op_sel:[1,0]
	v_mov_b32_e32 v187, v185
	v_pk_mov_b32 v[184:185], v[194:195], v[190:191] op_sel:[1,0]
	v_mov_b32_e32 v195, v191
	v_pk_add_f32 v[188:189], v[198:199], v[200:201]
	v_mov_b32_e32 v205, v208
	v_mov_b32_e32 v207, v209
	v_pk_add_f32 v[190:191], v[162:163], v[162:163] op_sel:[0,1] op_sel_hi:[1,0]
	v_pk_add_f32 v[192:193], v[164:165], v[164:165] op_sel:[0,1] op_sel_hi:[1,0]
	v_pk_add_f32 v[176:177], v[176:177], v[180:181]
	v_pk_add_f32 v[174:175], v[188:189], v[174:175]
	v_pk_add_f32 v[180:181], v[204:205], v[206:207]
	v_mov_b32_e32 v191, v210
	v_mov_b32_e32 v193, v211
	v_pk_add_f32 v[162:163], v[182:183], v[186:187]
	v_add_f32_e32 v182, v174, v175
	v_pk_add_f32 v[174:175], v[180:181], v[178:179]
	v_pk_add_f32 v[178:179], v[190:191], v[192:193]
	v_add_f32_e32 v180, v174, v175
	v_pk_add_f32 v[174:175], v[178:179], v[176:177]
	ds_bpermute_b32 v176, v1, v182
	ds_bpermute_b32 v177, v1, v180
	v_add_f32_e32 v174, v174, v175
	ds_bpermute_b32 v175, v1, v174
	s_add_u32 s18, s6, 0x6000
	s_waitcnt lgkmcnt(2)
	v_add_f32_e32 v176, v182, v176
	ds_bpermute_b32 v178, v167, v176
	s_waitcnt lgkmcnt(2)
	v_add_f32_e32 v177, v180, v177
	ds_bpermute_b32 v179, v167, v177
	s_waitcnt lgkmcnt(2)
	v_add_f32_e32 v174, v174, v175
	ds_bpermute_b32 v175, v167, v174
	s_waitcnt lgkmcnt(2)
	v_add_f32_e32 v176, v176, v178
	ds_bpermute_b32 v178, v168, v176
	s_waitcnt lgkmcnt(2)
	v_add_f32_e32 v177, v177, v179
	ds_bpermute_b32 v179, v168, v177
	s_waitcnt lgkmcnt(2)
	v_add_f32_e32 v174, v174, v175
	ds_bpermute_b32 v175, v168, v174
	s_waitcnt lgkmcnt(2)
	v_add_f32_e32 v176, v176, v178
	ds_bpermute_b32 v178, v169, v176
	s_waitcnt lgkmcnt(2)
	v_add_f32_e32 v177, v177, v179
	ds_bpermute_b32 v179, v169, v177
	s_waitcnt lgkmcnt(2)
	v_add_f32_e32 v174, v174, v175
	ds_bpermute_b32 v175, v169, v174
	s_waitcnt lgkmcnt(2)
	v_add_f32_e32 v176, v176, v178
	ds_bpermute_b32 v178, v170, v176
	s_waitcnt lgkmcnt(2)
	v_add_f32_e32 v177, v177, v179
	ds_bpermute_b32 v179, v170, v177
	s_waitcnt lgkmcnt(2)
	v_add_f32_e32 v174, v174, v175
	ds_bpermute_b32 v175, v170, v174
	s_waitcnt lgkmcnt(2)
	v_add_f32_e32 v176, v176, v178
	ds_bpermute_b32 v178, v171, v176
	s_waitcnt lgkmcnt(2)
	v_add_f32_e32 v177, v177, v179
	ds_bpermute_b32 v179, v171, v177
	s_waitcnt lgkmcnt(2)
	v_add_f32_e32 v174, v174, v175
	ds_bpermute_b32 v175, v171, v174
	s_waitcnt lgkmcnt(2)
	v_add_f32_e32 v176, v176, v178
	v_fmamk_f32 v176, v176, 0x3a800000, v172
	s_addc_u32 s19, s7, 0
	s_waitcnt lgkmcnt(1)
	v_add_f32_e32 v177, v177, v179
	v_mul_f32_e32 v178, 0x4f800000, v176
	v_cmp_gt_f32_e32 vcc, s13, v176
	s_add_u32 s20, s6, 0x7000
	v_fmamk_f32 v177, v177, 0x3a800000, v172
	s_waitcnt lgkmcnt(0)
	v_add_f32_e32 v174, v174, v175
	v_cndmask_b32_e32 v175, v176, v178, vcc
	s_addc_u32 s21, s7, 0
	v_mul_f32_e32 v176, 0x4f800000, v177
	v_cmp_gt_f32_e64 s[6:7], s13, v177
	v_sqrt_f32_e32 v178, v175
	v_fmamk_f32 v174, v174, 0x3a800000, v172
	v_cndmask_b32_e64 v176, v177, v176, s[6:7]
	v_mul_f32_e32 v177, 0x4f800000, v174
	v_cmp_gt_f32_e64 s[8:9], s13, v174
	v_sqrt_f32_e32 v179, v176
	v_add_u32_e32 v180, -1, v178
	v_cndmask_b32_e64 v174, v174, v177, s[8:9]
	v_sqrt_f32_e32 v177, v174
	v_add_u32_e32 v181, 1, v178
	v_fma_f32 v182, -v180, v178, v175
	v_lshl_add_u64 v[112:113], s[10:11], 0, v[90:91]
	v_lshl_add_u64 v[106:107], s[10:11], 0, v[96:97]
	v_lshl_add_u64 v[110:111], s[10:11], 0, v[98:99]
	v_lshl_add_u64 v[108:109], s[10:11], 0, v[100:101]
	v_pk_add_f32 v[164:165], v[184:185], v[194:195]
	v_fma_f32 v183, -v181, v178, v175
	v_add_u32_e32 v184, -1, v179
	v_cmp_ge_f32_e64 s[10:11], 0, v182
	v_add_u32_e32 v185, 1, v179
	v_fma_f32 v182, -v185, v179, v176
	v_cndmask_b32_e64 v178, v178, v180, s[10:11]
	v_fma_f32 v180, -v184, v179, v176
	v_cmp_lt_f32_e64 s[10:11], 0, v183
	v_add_u32_e32 v186, -1, v177
	v_add_u32_e32 v187, 1, v177
	v_cndmask_b32_e64 v178, v178, v181, s[10:11]
	v_cmp_ge_f32_e64 s[10:11], 0, v180
	v_fma_f32 v180, -v186, v177, v174
	v_fma_f32 v181, -v187, v177, v174
	v_cndmask_b32_e64 v179, v179, v184, s[10:11]
	v_cmp_lt_f32_e64 s[10:11], 0, v182
	v_mul_f32_e32 v182, 0x37800000, v178
	v_cndmask_b32_e32 v178, v178, v182, vcc
	v_cndmask_b32_e64 v179, v179, v185, s[10:11]
	v_cmp_ge_f32_e64 s[10:11], 0, v180
	v_mul_f32_e32 v180, 0x37800000, v179
	v_cmp_class_f32_e32 vcc, v175, v173
	v_cndmask_b32_e64 v177, v177, v186, s[10:11]
	v_cmp_lt_f32_e64 s[10:11], 0, v181
	v_cndmask_b32_e32 v175, v178, v175, vcc
	v_cndmask_b32_e64 v178, v179, v180, s[6:7]
	v_cndmask_b32_e64 v177, v177, v187, s[10:11]
	v_cmp_class_f32_e32 vcc, v176, v173
	v_mul_f32_e32 v179, 0x37800000, v177
	v_div_scale_f32 v180, s[6:7], v175, v175, 1.0
	v_cndmask_b32_e32 v176, v178, v176, vcc
	v_cndmask_b32_e64 v177, v177, v179, s[8:9]
	v_cmp_class_f32_e32 vcc, v174, v173
	v_rcp_f32_e32 v178, v180
	v_div_scale_f32 v179, s[8:9], v176, v176, 1.0
	v_cndmask_b32_e32 v177, v177, v174, vcc
	v_rcp_f32_e32 v183, v179
	v_div_scale_f32 v184, s[10:11], v177, v177, 1.0
	v_rcp_f32_e32 v186, v184
	v_fma_f32 v174, -v180, v178, 1.0
	v_div_scale_f32 v181, s[6:7], 1.0, v175, 1.0
	v_fmac_f32_e32 v178, v174, v178
	v_fma_f32 v174, -v179, v183, 1.0
	v_div_scale_f32 v182, s[8:9], 1.0, v176, 1.0
	v_mul_f32_e32 v187, v181, v178
	v_fmac_f32_e32 v183, v174, v183
	v_fma_f32 v174, -v184, v186, 1.0
	v_fma_f32 v188, -v180, v187, v181
	v_mul_f32_e32 v189, v182, v183
	v_div_scale_f32 v185, s[10:11], 1.0, v177, 1.0
	v_fmac_f32_e32 v186, v174, v186
	v_fmac_f32_e32 v187, v188, v178
	v_fma_f32 v174, -v179, v189, v182
	v_mul_f32_e32 v188, v185, v186
	v_fma_f32 v180, -v180, v187, v181
	v_fmac_f32_e32 v189, v174, v183
	s_mov_b64 vcc, s[6:7]
	v_fma_f32 v174, -v184, v188, v185
	v_div_fmas_f32 v178, v180, v178, v187
	v_fma_f32 v179, -v179, v189, v182
	s_mov_b64 vcc, s[8:9]
	v_fmac_f32_e32 v188, v174, v186
	v_div_fixup_f32 v174, v178, v175, 1.0
	v_div_fmas_f32 v175, v179, v183, v189
	v_fma_f32 v178, -v184, v188, v185
	v_pk_mul_f32 v[80:81], v[80:81], v[174:175] op_sel_hi:[1,0]
	v_pk_mul_f32 v[78:79], v[78:79], v[174:175] op_sel_hi:[1,0]
	s_mov_b64 vcc, s[10:11]
	v_pk_add_f32 v[88:89], v[88:89], 1.0 op_sel_hi:[1,0]
	v_pk_add_f32 v[86:87], v[86:87], 1.0 op_sel_hi:[1,0]
	v_pk_mul_f32 v[76:77], v[76:77], v[174:175] op_sel_hi:[1,0]
	v_pk_mul_f32 v[74:75], v[74:75], v[174:175] op_sel_hi:[1,0]
	v_pk_mul_f32 v[72:73], v[72:73], v[174:175] op_sel_hi:[1,0]
	v_pk_mul_f32 v[70:71], v[70:71], v[174:175] op_sel_hi:[1,0]
	v_pk_mul_f32 v[68:69], v[68:69], v[174:175] op_sel_hi:[1,0]
	v_pk_mul_f32 v[66:67], v[66:67], v[174:175] op_sel_hi:[1,0]
	v_div_fixup_f32 v174, v175, v176, 1.0
	v_div_fmas_f32 v176, v178, v186, v188
	v_pk_mul_f32 v[78:79], v[2:3], v[78:79]
	v_pk_mul_f32 v[80:81], v[4:5], v[80:81]
	v_pk_mul_f32 v[64:65], v[64:65], v[174:175] op_sel_hi:[1,0]
	v_pk_mul_f32 v[62:63], v[62:63], v[174:175] op_sel_hi:[1,0]
	v_pk_mul_f32 v[60:61], v[60:61], v[174:175] op_sel_hi:[1,0]
	v_pk_mul_f32 v[58:59], v[58:59], v[174:175] op_sel_hi:[1,0]
	v_pk_mul_f32 v[56:57], v[56:57], v[174:175] op_sel_hi:[1,0]
	v_pk_mul_f32 v[54:55], v[54:55], v[174:175] op_sel_hi:[1,0]
	v_pk_mul_f32 v[52:53], v[52:53], v[174:175] op_sel_hi:[1,0]
	v_pk_mul_f32 v[174:175], v[50:51], v[174:175] op_sel_hi:[1,0]
	v_div_fixup_f32 v50, v176, v177, 1.0
	v_pk_fma_f32 v[80:81], v[88:89], v[80:81], v[84:85]
	v_pk_fma_f32 v[78:79], v[86:87], v[78:79], v[82:83]
	v_pk_mul_f32 v[86:87], v[16:17], v[52:53]
	v_pk_mul_f32 v[48:49], v[48:49], v[50:51] op_sel_hi:[1,0]
	v_pk_mul_f32 v[46:47], v[46:47], v[50:51] op_sel_hi:[1,0]
	v_pk_mul_f32 v[82:83], v[10:11], v[54:55]
	v_pk_mul_f32 v[84:85], v[14:15], v[174:175]
	v_pk_mul_f32 v[88:89], v[2:3], v[46:47]
	v_pk_mul_f32 v[174:175], v[4:5], v[48:49]
	v_cvt_pk_bf16_f32 v46, v78, v79
	v_cvt_pk_bf16_f32 v47, v80, v81
	global_store_dwordx2 v[102:103], v[46:47], off
	global_load_dwordx4 v[46:49], v[152:153], off
	s_nop 0
	global_load_dwordx4 v[52:55], v[148:149], off
	v_pk_mul_f32 v[74:75], v[6:7], v[74:75]
	v_pk_mul_f32 v[76:77], v[8:9], v[76:77]
	v_pk_mul_f32 v[70:71], v[10:11], v[70:71]
	v_pk_mul_f32 v[72:73], v[12:13], v[72:73]
	v_pk_mul_f32 v[66:67], v[66:67], v[14:15]
	v_pk_mul_f32 v[68:69], v[68:69], v[16:17]
	v_pk_mul_f32 v[62:63], v[2:3], v[62:63]
	v_pk_mul_f32 v[64:65], v[4:5], v[64:65]
	v_pk_mul_f32 v[58:59], v[6:7], v[58:59]
	v_pk_mul_f32 v[60:61], v[8:9], v[60:61]
	v_pk_mul_f32 v[56:57], v[12:13], v[56:57]
	v_mul_f32_e32 v196, v23, v23
	v_mul_f32_e32 v202, v25, v25
	v_mul_f32_e32 v214, v18, v18
	v_mul_f32_e32 v215, v19, v19
	v_mul_f32_e32 v216, v20, v20
	v_mul_f32_e32 v217, v21, v21
	v_pk_fma_f32 v[158:159], v[22:23], v[22:23], v[196:197] op_sel_hi:[1,1,0]
	v_pk_fma_f32 v[160:161], v[24:25], v[24:25], v[202:203] op_sel_hi:[1,1,0]
	v_mov_b32_e32 v159, v216
	v_mov_b32_e32 v161, v217
	v_lshl_add_u64 v[144:145], s[20:21], 0, v[90:91]
	v_lshl_add_u64 v[128:129], s[18:19], 0, v[90:91]
	v_lshl_add_u64 v[124:125], s[20:21], 0, v[96:97]
	v_lshl_add_u64 v[120:121], s[18:19], 0, v[96:97]
	s_add_i32 s12, s12, 32
	v_lshl_add_u64 v[92:93], v[92:93], 0, s[14:15]
	v_lshl_add_u64 v[94:95], v[94:95], 0, s[16:17]
	s_cmp_lt_i32 s12, s2
	s_waitcnt vmcnt(0) lgkmcnt(0)
	v_pk_add_f32 v[48:49], v[48:49], 1.0 op_sel_hi:[1,0]
	v_pk_add_f32 v[46:47], v[46:47], 1.0 op_sel_hi:[1,0]
	v_pk_fma_f32 v[48:49], v[48:49], v[76:77], v[54:55]
	v_pk_fma_f32 v[46:47], v[46:47], v[74:75], v[52:53]
	v_cvt_pk_bf16_f32 v46, v46, v47
	v_cvt_pk_bf16_f32 v47, v48, v49
	global_store_dwordx2 v[102:103], v[46:47], off offset:512
	global_load_dwordx4 v[46:49], v[146:147], off
	s_nop 0
	global_load_dwordx4 v[52:55], v[142:143], off
	s_waitcnt vmcnt(0) lgkmcnt(0)
	v_pk_add_f32 v[48:49], v[48:49], 1.0 op_sel_hi:[1,0]
	v_pk_add_f32 v[46:47], v[46:47], 1.0 op_sel_hi:[1,0]
	v_pk_fma_f32 v[48:49], v[72:73], v[48:49], v[54:55]
	v_pk_fma_f32 v[46:47], v[70:71], v[46:47], v[52:53]
	v_cvt_pk_bf16_f32 v46, v46, v47
	v_cvt_pk_bf16_f32 v47, v48, v49
	global_store_dwordx2 v[102:103], v[46:47], off offset:1024
	global_load_dwordx4 v[46:49], v[140:141], off
	s_nop 0
	global_load_dwordx4 v[52:55], v[134:135], off
	s_waitcnt vmcnt(0) lgkmcnt(0)
	v_pk_add_f32 v[48:49], v[48:49], 1.0 op_sel_hi:[1,0]
	v_pk_add_f32 v[46:47], v[46:47], 1.0 op_sel_hi:[1,0]
	v_pk_fma_f32 v[48:49], v[68:69], v[48:49], v[54:55]
	v_pk_fma_f32 v[46:47], v[66:67], v[46:47], v[52:53]
	v_cvt_pk_bf16_f32 v46, v46, v47
	v_cvt_pk_bf16_f32 v47, v48, v49
	global_store_dwordx2 v[102:103], v[46:47], off offset:1536
	global_load_dwordx4 v[46:49], v[138:139], off
	s_nop 0
	global_load_dwordx4 v[52:55], v[132:133], off
	s_waitcnt vmcnt(0) lgkmcnt(0)
	v_pk_add_f32 v[48:49], v[48:49], 1.0 op_sel_hi:[1,0]
	v_pk_add_f32 v[46:47], v[46:47], 1.0 op_sel_hi:[1,0]
	v_pk_fma_f32 v[48:49], v[48:49], v[64:65], v[54:55]
	v_pk_fma_f32 v[46:47], v[46:47], v[62:63], v[52:53]
	v_cvt_pk_bf16_f32 v46, v46, v47
	v_cvt_pk_bf16_f32 v47, v48, v49
	global_store_dwordx2 v[102:103], v[46:47], off offset:2048
	global_load_dwordx4 v[46:49], v[130:131], off
	s_nop 0
	global_load_dwordx4 v[52:55], v[126:127], off
	s_waitcnt vmcnt(0) lgkmcnt(0)
	v_pk_add_f32 v[48:49], v[48:49], 1.0 op_sel_hi:[1,0]
	v_pk_add_f32 v[46:47], v[46:47], 1.0 op_sel_hi:[1,0]
	v_pk_fma_f32 v[48:49], v[48:49], v[60:61], v[54:55]
	v_pk_fma_f32 v[46:47], v[46:47], v[58:59], v[52:53]
	v_cvt_pk_bf16_f32 v46, v46, v47
	v_cvt_pk_bf16_f32 v47, v48, v49
	global_store_dwordx2 v[102:103], v[46:47], off offset:2560
	global_load_dwordx4 v[46:49], v[122:123], off
	s_nop 0
	global_load_dwordx4 v[52:55], v[118:119], off
	v_pk_add_f32 v[58:59], v[164:165], v[164:165] op_sel:[0,1] op_sel_hi:[1,0]
	v_pk_add_f32 v[60:61], v[158:159], v[160:161]
	v_mov_b32_e32 v59, v215
	s_waitcnt vmcnt(0) lgkmcnt(0)
	v_pk_add_f32 v[48:49], v[48:49], 1.0 op_sel_hi:[1,0]
	v_pk_add_f32 v[46:47], v[46:47], 1.0 op_sel_hi:[1,0]
	v_pk_fma_f32 v[48:49], v[48:49], v[56:57], v[54:55]
	v_pk_fma_f32 v[46:47], v[46:47], v[82:83], v[52:53]
	v_cvt_pk_bf16_f32 v46, v46, v47
	v_cvt_pk_bf16_f32 v47, v48, v49
	global_store_dwordx2 v[102:103], v[46:47], off offset:3072
	global_load_dwordx4 v[46:49], v[116:117], off
	s_nop 0
	global_load_dwordx4 v[52:55], v[114:115], off
	v_pk_add_f32 v[56:57], v[162:163], v[162:163] op_sel:[0,1] op_sel_hi:[1,0]
	s_waitcnt vmcnt(0) lgkmcnt(0)
	v_pk_add_f32 v[48:49], v[48:49], 1.0 op_sel_hi:[1,0]
	v_pk_add_f32 v[46:47], v[46:47], 1.0 op_sel_hi:[1,0]
	v_pk_fma_f32 v[48:49], v[86:87], v[48:49], v[54:55]
	v_pk_fma_f32 v[46:47], v[84:85], v[46:47], v[52:53]
	v_cvt_pk_bf16_f32 v46, v46, v47
	v_cvt_pk_bf16_f32 v47, v48, v49
	global_store_dwordx2 v[102:103], v[46:47], off offset:3584
	global_load_dwordx4 v[46:49], v[156:157], off
	s_nop 0
	global_load_dwordx4 v[52:55], v[112:113], off
	v_mov_b32_e32 v57, v214
	s_waitcnt vmcnt(0) lgkmcnt(0)
	v_pk_add_f32 v[48:49], v[48:49], 1.0 op_sel_hi:[1,0]
	v_pk_add_f32 v[46:47], v[46:47], 1.0 op_sel_hi:[1,0]
	v_pk_fma_f32 v[48:49], v[48:49], v[174:175], v[54:55]
	v_pk_fma_f32 v[46:47], v[46:47], v[88:89], v[52:53]
	v_bfe_u32 v51, v46, 16, 1
	v_bfe_u32 v52, v47, 16, 1
	v_add3_u32 v46, v46, v51, s22
	v_add3_u32 v47, v47, v52, s22
	v_lshrrev_b32_e32 v46, 16, v46
	v_and_or_b32 v46, v47, s23, v46
	v_cvt_pk_bf16_f32 v47, v48, v49
	global_store_dwordx2 v[104:105], v[46:47], off
	global_load_dwordx4 v[46:49], v[154:155], off
	s_nop 0
	global_load_dwordx4 v[52:55], v[106:107], off
	v_pk_mul_f32 v[44:45], v[44:45], v[50:51] op_sel_hi:[1,0]
	v_pk_mul_f32 v[42:43], v[42:43], v[50:51] op_sel_hi:[1,0]
	v_pk_mul_f32 v[44:45], v[8:9], v[44:45]
	v_pk_mul_f32 v[42:43], v[6:7], v[42:43]
	s_waitcnt vmcnt(0) lgkmcnt(0)
	v_pk_add_f32 v[48:49], v[48:49], 1.0 op_sel_hi:[1,0]
	v_pk_add_f32 v[46:47], v[46:47], 1.0 op_sel_hi:[1,0]
	v_pk_fma_f32 v[44:45], v[48:49], v[44:45], v[54:55]
	v_pk_fma_f32 v[42:43], v[46:47], v[42:43], v[52:53]
	v_cvt_pk_bf16_f32 v42, v42, v43
	v_cvt_pk_bf16_f32 v43, v44, v45
	global_store_dwordx2 v[104:105], v[42:43], off offset:512
	global_load_dwordx4 v[42:45], v[150:151], off
	s_nop 0
	global_load_dwordx4 v[46:49], v[110:111], off
	v_pk_add_f32 v[52:53], v[56:57], v[58:59]
	s_waitcnt vmcnt(0) lgkmcnt(0)
	v_pk_add_f32 v[44:45], v[44:45], 1.0 op_sel_hi:[1,0]
	v_pk_add_f32 v[52:53], v[52:53], v[60:61]
	v_pk_add_f32 v[42:43], v[42:43], 1.0 op_sel_hi:[1,0]
	v_add_f32_e32 v51, v52, v53
	ds_bpermute_b32 v52, v1, v51
	s_waitcnt lgkmcnt(0)
	v_add_f32_e32 v51, v51, v52
	ds_bpermute_b32 v52, v167, v51
	s_waitcnt lgkmcnt(0)
	v_add_f32_e32 v51, v51, v52
	v_pk_mul_f32 v[40:41], v[40:41], v[50:51] op_sel_hi:[1,0]
	v_pk_mul_f32 v[38:39], v[38:39], v[50:51] op_sel_hi:[1,0]
	v_pk_mul_f32 v[40:41], v[12:13], v[40:41]
	v_pk_mul_f32 v[38:39], v[10:11], v[38:39]
	v_pk_fma_f32 v[40:41], v[44:45], v[40:41], v[48:49]
	v_pk_fma_f32 v[38:39], v[42:43], v[38:39], v[46:47]
	v_cvt_pk_bf16_f32 v38, v38, v39
	v_cvt_pk_bf16_f32 v39, v40, v41
	global_store_dwordx2 v[104:105], v[38:39], off offset:1024
	global_load_dwordx4 v[38:41], v[136:137], off
	s_nop 0
	global_load_dwordx4 v[42:45], v[108:109], off
	v_pk_mul_f32 v[36:37], v[36:37], v[50:51] op_sel_hi:[1,0]
	v_pk_mul_f32 v[34:35], v[34:35], v[50:51] op_sel_hi:[1,0]
	v_pk_mul_f32 v[36:37], v[16:17], v[36:37]
	v_pk_mul_f32 v[34:35], v[14:15], v[34:35]
	ds_bpermute_b32 v46, v168, v51
	s_waitcnt lgkmcnt(0)
	v_add_f32_e32 v46, v51, v46
	ds_bpermute_b32 v47, v169, v46
	s_waitcnt lgkmcnt(0)
	v_add_f32_e32 v46, v46, v47
	ds_bpermute_b32 v47, v170, v46
	s_waitcnt lgkmcnt(0)
	v_add_f32_e32 v46, v46, v47
	ds_bpermute_b32 v47, v171, v46
	s_waitcnt lgkmcnt(0)
	v_add_f32_e32 v46, v46, v47
	v_fmamk_f32 v46, v46, 0x3a800000, v172
	v_mul_f32_e32 v47, 0x4f800000, v46
	v_cmp_gt_f32_e32 vcc, s13, v46
	s_waitcnt vmcnt(0)
	v_pk_add_f32 v[40:41], v[40:41], 1.0 op_sel_hi:[1,0]
	v_pk_add_f32 v[38:39], v[38:39], 1.0 op_sel_hi:[1,0]
	v_pk_fma_f32 v[36:37], v[36:37], v[40:41], v[44:45]
	v_pk_fma_f32 v[34:35], v[34:35], v[38:39], v[42:43]
	v_cvt_pk_bf16_f32 v34, v34, v35
	v_cvt_pk_bf16_f32 v35, v36, v37
	global_store_dwordx2 v[104:105], v[34:35], off offset:1536
	global_load_dwordx4 v[34:37], v[144:145], off
	s_nop 0
	global_load_dwordx4 v[38:41], v[128:129], off
	v_cndmask_b32_e32 v42, v46, v47, vcc
	v_sqrt_f32_e32 v43, v42
	s_waitcnt vmcnt(0) lgkmcnt(0)
	v_pk_add_f32 v[36:37], v[36:37], 1.0 op_sel_hi:[1,0]
	v_add_u32_e32 v44, -1, v43
	v_add_u32_e32 v45, 1, v43
	v_fma_f32 v46, -v44, v43, v42
	v_fma_f32 v47, -v45, v43, v42
	v_cmp_ge_f32_e64 s[6:7], 0, v46
	v_pk_add_f32 v[34:35], v[34:35], 1.0 op_sel_hi:[1,0]
	s_nop 0
	v_cndmask_b32_e64 v43, v43, v44, s[6:7]
	v_cmp_lt_f32_e64 s[6:7], 0, v47
	s_nop 1
	v_cndmask_b32_e64 v43, v43, v45, s[6:7]
	v_mul_f32_e32 v44, 0x37800000, v43
	v_cndmask_b32_e32 v43, v43, v44, vcc
	v_cmp_class_f32_e32 vcc, v42, v173
	s_nop 1
	v_cndmask_b32_e32 v42, v43, v42, vcc
	v_div_scale_f32 v43, s[6:7], v42, v42, 1.0
	v_rcp_f32_e32 v45, v43
	v_div_scale_f32 v44, vcc, 1.0, v42, 1.0
	v_fma_f32 v46, -v43, v45, 1.0
	v_fmac_f32_e32 v45, v46, v45
	v_mul_f32_e32 v46, v44, v45
	v_fma_f32 v47, -v43, v46, v44
	v_fmac_f32_e32 v46, v47, v45
	v_fma_f32 v43, -v43, v46, v44
	v_div_fmas_f32 v43, v43, v45, v46
	v_div_fixup_f32 v42, v43, v42, 1.0
	v_pk_mul_f32 v[32:33], v[32:33], v[42:43] op_sel_hi:[1,0]
	v_pk_mul_f32 v[30:31], v[30:31], v[42:43] op_sel_hi:[1,0]
	v_pk_mul_f32 v[32:33], v[4:5], v[32:33]
	v_pk_mul_f32 v[30:31], v[2:3], v[30:31]
	v_pk_fma_f32 v[32:33], v[36:37], v[32:33], v[40:41]
	v_pk_fma_f32 v[30:31], v[34:35], v[30:31], v[38:39]
	v_cvt_pk_bf16_f32 v30, v30, v31
	v_cvt_pk_bf16_f32 v31, v32, v33
	global_store_dwordx2 v[104:105], v[30:31], off offset:2048
	global_load_dwordx4 v[30:33], v[124:125], off
	s_nop 0
	global_load_dwordx4 v[34:37], v[120:121], off
	v_pk_mul_f32 v[28:29], v[28:29], v[42:43] op_sel_hi:[1,0]
	v_pk_mul_f32 v[26:27], v[26:27], v[42:43] op_sel_hi:[1,0]
	v_pk_mul_f32 v[28:29], v[8:9], v[28:29]
	v_pk_mul_f32 v[26:27], v[6:7], v[26:27]
	v_lshl_add_u64 v[40:41], s[20:21], 0, v[98:99]
	v_lshl_add_u64 v[38:39], s[18:19], 0, v[98:99]
	v_pk_mul_f32 v[24:25], v[24:25], v[42:43] op_sel_hi:[1,0]
	v_pk_mul_f32 v[22:23], v[22:23], v[42:43] op_sel_hi:[1,0]
	v_pk_mul_f32 v[24:25], v[12:13], v[24:25]
	v_pk_mul_f32 v[22:23], v[10:11], v[22:23]
	v_pk_mul_f32 v[20:21], v[20:21], v[42:43] op_sel_hi:[1,0]
	v_pk_mul_f32 v[18:19], v[18:19], v[42:43] op_sel_hi:[1,0]
	v_pk_mul_f32 v[20:21], v[16:17], v[20:21]
	v_pk_mul_f32 v[18:19], v[14:15], v[18:19]
	s_waitcnt vmcnt(0) lgkmcnt(0)
	v_pk_add_f32 v[32:33], v[32:33], 1.0 op_sel_hi:[1,0]
	v_pk_add_f32 v[30:31], v[30:31], 1.0 op_sel_hi:[1,0]
	v_pk_fma_f32 v[28:29], v[32:33], v[28:29], v[36:37]
	v_pk_fma_f32 v[26:27], v[30:31], v[26:27], v[34:35]
	v_cvt_pk_bf16_f32 v26, v26, v27
	v_cvt_pk_bf16_f32 v27, v28, v29
	global_store_dwordx2 v[104:105], v[26:27], off offset:2560
	global_load_dwordx4 v[26:29], v[40:41], off
	s_nop 0
	global_load_dwordx4 v[30:33], v[38:39], off
	v_lshl_add_u64 v[36:37], s[20:21], 0, v[100:101]
	v_lshl_add_u64 v[34:35], s[18:19], 0, v[100:101]
	s_waitcnt vmcnt(0) lgkmcnt(0)
	v_pk_add_f32 v[28:29], v[28:29], 1.0 op_sel_hi:[1,0]
	v_pk_add_f32 v[26:27], v[26:27], 1.0 op_sel_hi:[1,0]
	v_pk_fma_f32 v[24:25], v[28:29], v[24:25], v[32:33]
	v_pk_fma_f32 v[22:23], v[26:27], v[22:23], v[30:31]
	v_cvt_pk_bf16_f32 v22, v22, v23
	v_cvt_pk_bf16_f32 v23, v24, v25
	global_store_dwordx2 v[104:105], v[22:23], off offset:3072
	global_load_dwordx4 v[22:25], v[36:37], off
	s_nop 0
	global_load_dwordx4 v[26:29], v[34:35], off
	s_waitcnt vmcnt(0) lgkmcnt(0)
	v_pk_add_f32 v[24:25], v[24:25], 1.0 op_sel_hi:[1,0]
	v_pk_add_f32 v[22:23], v[22:23], 1.0 op_sel_hi:[1,0]
	v_pk_fma_f32 v[20:21], v[20:21], v[24:25], v[28:29]
	v_pk_fma_f32 v[18:19], v[18:19], v[22:23], v[26:27]
	v_cvt_pk_bf16_f32 v18, v18, v19
	v_cvt_pk_bf16_f32 v19, v20, v21
	global_store_dwordx2 v[104:105], v[18:19], off offset:3584
	s_cbranch_scc1 .LBB0_2937

.LBB0_2965:
	ds_read2_b32 v[20:21], v18 offset1:2
	ds_read2st64_b32 v[22:23], v19 offset1:4
	s_add_i32 s8, s8, -8
	s_cmp_eq_u32 s8, 0
	s_waitcnt lgkmcnt(0)
	v_mfma_f32_32x32x2_f32 v[2:17], v20, v22, v[2:17]
	v_mfma_f32_32x32x2_f32 v[2:17], v21, v23, v[2:17]
	ds_read2_b32 v[20:21], v18 offset0:4 offset1:6
	ds_read2st64_b32 v[22:23], v19 offset0:8 offset1:12
	s_waitcnt lgkmcnt(0)
	v_mfma_f32_32x32x2_f32 v[2:17], v20, v22, v[2:17]
	v_mfma_f32_32x32x2_f32 v[2:17], v21, v23, v[2:17]
	ds_read2_b32 v[20:21], v18 offset0:8 offset1:10
	ds_read2st64_b32 v[22:23], v19 offset0:16 offset1:20
	s_waitcnt lgkmcnt(0)
	v_mfma_f32_32x32x2_f32 v[2:17], v20, v22, v[2:17]
	v_mfma_f32_32x32x2_f32 v[2:17], v21, v23, v[2:17]
	ds_read2_b32 v[20:21], v18 offset0:12 offset1:14
	ds_read2st64_b32 v[22:23], v19 offset0:24 offset1:28
	v_add_u32_e32 v19, 0x2000, v19
	v_add_u32_e32 v18, 64, v18
	s_waitcnt lgkmcnt(0)
	v_mfma_f32_32x32x2_f32 v[2:17], v20, v22, v[2:17]
	v_mfma_f32_32x32x2_f32 v[2:17], v21, v23, v[2:17]
	s_cbranch_scc0 .LBB0_2965
	v_add_u32_e32 v18, 0xc200, v103
	s_barrier
	s_nop 14
	ds_write2_b32 v18, v2, v3 offset0:64 offset1:196
	v_add_u32_e32 v2, 0xc600, v103
	ds_write2_b32 v2, v4, v5 offset0:72 offset1:204
	v_add_u32_e32 v2, 0xd200, v103
	ds_write2_b32 v2, v6, v7 offset0:96 offset1:228
	v_add_u32_e32 v2, 0xd600, v103
	ds_write2_b32 v2, v8, v9 offset0:104 offset1:236
	v_add_u32_e32 v2, 0xe400, v103
	ds_write2_b32 v2, v10, v11 offset1:132
	v_add_u32_e32 v2, 0xe800, v103
	ds_write2_b32 v2, v12, v13 offset0:8 offset1:140
	v_add_u32_e32 v2, 0xf400, v103
	ds_write2_b32 v2, v14, v15 offset0:32 offset1:164
	v_add_u32_e32 v2, 0xf800, v103
	v_mov_b64_e32 v[18:19], s[0:1]
	ds_write2_b32 v2, v16, v17 offset0:40 offset1:172
	s_waitcnt lgkmcnt(0)
	s_barrier
	ds_read_b128 v[14:17], v95 offset:49920
	ds_read_b128 v[10:13], v95 offset:49936
	ds_read_b128 v[6:9], v95 offset:49952
	ds_read_b128 v[2:5], v95 offset:49968
	global_load_dwordx2 v[22:23], v[18:19], off offset:168 sc0 sc1
	s_waitcnt vmcnt(0)
	v_add_u32_e32 v60, s36, v94
	v_mov_b64_e32 v[18:19], s[12:13]
	v_and_b32_e32 v21, 64, v166
	s_lshl_b32 s70, s35, 2
	v_mad_i64_i32 v[18:19], s[8:9], v60, s29, v[18:19]
	v_xor_b32_e32 v20, 1, v166
	v_lshlrev_b32_e32 v42, 2, v54
	v_add_u32_e32 v59, 64, v21
	v_lshl_add_u64 v[18:19], v[18:19], 0, s[70:71]
	v_cmp_lt_i32_e32 vcc, v20, v59
	v_lshl_add_u64 v[30:31], v[18:19], 0, v[42:43]
	s_waitcnt lgkmcnt(0)
	v_mov_b32_e32 v26, v15
	v_cndmask_b32_e32 v20, v166, v20, vcc
	v_add_co_u32_e32 v18, vcc, s4, v30
	v_lshlrev_b32_e32 v61, 2, v20
	s_nop 0
	v_addc_co_u32_e32 v19, vcc, 0, v31, vcc
	global_load_dwordx4 v[18:21], v[18:19], off offset:1184
	v_mov_b32_e32 v27, v11
	v_mov_b32_e32 v24, v14
	v_mov_b32_e32 v25, v10
	v_mov_b32_e32 v36, v7
	v_mov_b32_e32 v37, v3
	v_pk_mul_f32 v[26:27], v[26:27], v[26:27]
	v_mov_b32_e32 v28, v16
	v_mov_b32_e32 v29, v12
	v_mov_b32_e32 v34, v6
	v_mov_b32_e32 v35, v2
	v_pk_mul_f32 v[36:37], v[36:37], v[36:37]
	v_pk_fma_f32 v[24:25], v[24:25], v[24:25], v[26:27]
	v_mov_b32_e32 v32, v17
	v_mov_b32_e32 v33, v13
	v_mov_b32_e32 v38, v8
	v_mov_b32_e32 v39, v4
	v_pk_fma_f32 v[26:27], v[34:35], v[34:35], v[36:37]
	v_pk_fma_f32 v[24:25], v[28:29], v[28:29], v[24:25]
	v_mov_b32_e32 v40, v9
	v_mov_b32_e32 v41, v5
	v_pk_fma_f32 v[26:27], v[38:39], v[38:39], v[26:27]
	v_pk_fma_f32 v[24:25], v[32:33], v[32:33], v[24:25]
	v_pk_fma_f32 v[26:27], v[40:41], v[40:41], v[26:27]
	v_add_f32_e32 v24, v24, v25
	v_add_f32_e32 v24, v24, v26
	v_add_f32_e32 v24, v24, v27
	ds_bpermute_b32 v25, v61, v24
	v_xor_b32_e32 v26, 2, v166
	v_cmp_lt_i32_e32 vcc, v26, v59
	v_lshl_add_u64 v[62:63], v[30:31], 0, s[72:73]
	v_mov_b32_e32 v38, v14
	v_cndmask_b32_e32 v26, v166, v26, vcc
	v_lshlrev_b32_e32 v26, 2, v26
	s_waitcnt lgkmcnt(0)
	v_add_f32_e32 v24, v24, v25
	ds_bpermute_b32 v25, v26, v24
	v_ashrrev_i32_e32 v61, 31, v60
	s_lshl_b32 s70, s35, 1
	s_mov_b64 s[76:77], 0
	s_waitcnt lgkmcnt(0)
	v_add_f32_e32 v32, v24, v25
	v_lshl_add_u64 v[64:65], v[22:23], 0, v[42:43]
	global_load_dwordx4 v[26:29], v[64:65], off
	v_xor_b32_e32 v22, 4, v166
	v_cmp_lt_i32_e32 vcc, v22, v59
	s_nop 1
	v_cndmask_b32_e32 v22, v166, v22, vcc
	v_lshlrev_b32_e32 v22, 2, v22
	ds_bpermute_b32 v33, v22, v32
	global_load_dwordx4 v[22:25], v[64:65], off offset:16
	s_waitcnt lgkmcnt(0)
	v_add_f32_e32 v30, v32, v33
	v_fmamk_f32 v30, v30, 0x3c000000, v104
	v_mul_f32_e32 v31, 0x4f800000, v30
	v_cmp_gt_f32_e32 vcc, s31, v30
	s_nop 1
	v_cndmask_b32_e32 v39, v30, v31, vcc
	v_sqrt_f32_e32 v40, v39
	global_load_dwordx4 v[30:33], v[62:63], off offset:16
	global_load_dwordx4 v[34:37], v[62:63], off offset:48
	v_add_u32_e32 v14, -1, v40
	v_add_u32_e32 v41, 1, v40
	v_fma_f32 v42, -v14, v40, v39
	v_fma_f32 v59, -v41, v40, v39
	v_cmp_ge_f32_e64 s[8:9], 0, v42
	s_nop 1
	v_cndmask_b32_e64 v14, v40, v14, s[8:9]
	v_cmp_lt_f32_e64 s[8:9], 0, v59
	s_nop 1
	v_cndmask_b32_e64 v14, v14, v41, s[8:9]
	v_mul_f32_e32 v40, 0x37800000, v14
	v_cndmask_b32_e32 v14, v14, v40, vcc
	v_cmp_class_f32_e32 vcc, v39, v105
	s_nop 1
	v_cndmask_b32_e32 v14, v14, v39, vcc
	v_div_scale_f32 v40, s[8:9], v14, v14, 1.0
	v_rcp_f32_e32 v41, v40
	v_mov_b32_e32 v39, v16
	v_div_scale_f32 v16, vcc, 1.0, v14, 1.0
	v_fma_f32 v42, -v40, v41, 1.0
	v_fmac_f32_e32 v41, v42, v41
	v_mul_f32_e32 v42, v16, v41
	v_fma_f32 v59, -v40, v42, v16
	v_fmac_f32_e32 v42, v59, v41
	v_fma_f32 v16, -v40, v42, v16
	v_div_fmas_f32 v16, v16, v41, v42
	v_div_fixup_f32 v14, v16, v14, 1.0
	v_pk_mul_f32 v[110:111], v[38:39], v[14:15] op_sel_hi:[1,0]
	s_waitcnt vmcnt(0)
	v_mul_f32_e32 v16, 0xbfb8aa3b, v18
	v_mul_f32_e32 v38, 0xbfb8aa3b, v20
	v_exp_f32_e32 v112, v16
	v_exp_f32_e32 v113, v38
	v_mul_f32_e32 v16, 0xbfb8aa3b, v19
	global_load_dwordx4 v[38:41], v[64:65], off offset:48
	global_load_dwordx4 v[106:109], v[64:65], off offset:32
	v_exp_f32_e32 v64, v16
	v_pk_add_f32 v[112:113], v[112:113], 1.0 op_sel_hi:[1,0]
	s_nop 0
	v_div_scale_f32 v16, s[8:9], v113, v113, v20
	v_rcp_f32_e32 v65, v16
	v_div_scale_f32 v59, s[8:9], v112, v112, v18
	v_rcp_f32_e32 v116, v59
	v_fma_f32 v114, -v16, v65, 1.0
	v_div_scale_f32 v42, vcc, v20, v113, v20
	v_fmac_f32_e32 v65, v114, v65
	v_fma_f32 v115, -v59, v116, 1.0
	v_mul_f32_e32 v114, v42, v65
	v_fmac_f32_e32 v116, v115, v116
	v_fma_f32 v115, -v16, v114, v42
	v_fmac_f32_e32 v114, v115, v65
	v_fma_f32 v16, -v16, v114, v42
	v_div_fmas_f32 v16, v16, v65, v114
	v_div_scale_f32 v117, s[8:9], v18, v112, v18
	v_div_fixup_f32 v113, v16, v113, v20
	v_mul_f32_e32 v20, 0xbfb8aa3b, v21
	v_mul_f32_e32 v118, v117, v116
	v_exp_f32_e32 v65, v20
	v_fma_f32 v119, -v59, v118, v117
	v_fmac_f32_e32 v118, v119, v116
	v_fma_f32 v16, -v59, v118, v117
	s_mov_b64 vcc, s[8:9]
	v_div_fmas_f32 v16, v16, v116, v118
	v_pk_add_f32 v[64:65], v[64:65], 1.0 op_sel_hi:[1,0]
	v_div_fixup_f32 v112, v16, v112, v18
	v_mov_b32_e32 v16, v15
	v_div_scale_f32 v15, s[8:9], v65, v65, v21
	v_rcp_f32_e32 v18, v15
	v_mov_b32_e32 v114, v26
	v_mov_b32_e32 v115, v28
	v_mov_b32_e32 v28, v27
	v_fma_f32 v20, -v15, v18, 1.0
	v_fmac_f32_e32 v18, v20, v18
	v_div_scale_f32 v20, vcc, v21, v65, v21
	v_mul_f32_e32 v26, v20, v18
	v_fma_f32 v27, -v15, v26, v20
	v_fmac_f32_e32 v26, v27, v18
	v_pk_mul_f32 v[16:17], v[16:17], v[14:15] op_sel_hi:[1,0]
	v_fma_f32 v15, -v15, v26, v20
	v_div_scale_f32 v20, s[8:9], v64, v64, v19
	v_rcp_f32_e32 v27, v20
	v_div_fmas_f32 v15, v15, v18, v26
	v_div_fixup_f32 v21, v15, v65, v21
	v_pk_mul_f32 v[16:17], v[28:29], v[16:17]
	v_fma_f32 v15, -v20, v27, 1.0
	v_fmac_f32_e32 v27, v15, v27
	v_div_scale_f32 v15, vcc, v19, v64, v19
	v_mul_f32_e32 v18, v15, v27
	v_fma_f32 v26, -v20, v18, v15
	v_fmac_f32_e32 v18, v26, v27
	v_fma_f32 v15, -v20, v18, v15
	v_div_fmas_f32 v15, v15, v27, v18
	v_div_fixup_f32 v20, v15, v64, v19
	v_pk_mul_f32 v[20:21], v[20:21], v[16:17]
	global_load_dwordx4 v[16:19], v[62:63], off offset:32
	s_waitcnt lgkmcnt(0)
	v_mul_f32_e32 v15, 0xbfb8aa3b, v30
	v_exp_f32_e32 v26, v15
	v_mul_f32_e32 v15, 0xbfb8aa3b, v31
	v_exp_f32_e32 v28, v15
	v_mul_f32_e32 v15, 0xbfb8aa3b, v32
	v_exp_f32_e32 v27, v15
	v_mov_b32_e32 v62, v10
	v_mov_b32_e32 v63, v12
	v_pk_mul_f32 v[62:63], v[62:63], v[14:15] op_sel_hi:[1,0]
	v_pk_add_f32 v[26:27], v[26:27], 1.0 op_sel_hi:[1,0]
	v_mov_b32_e32 v64, v22
	v_div_scale_f32 v10, s[8:9], v27, v27, v32
	v_rcp_f32_e32 v12, v10
	v_mov_b32_e32 v65, v24
	v_pk_mul_f32 v[110:111], v[114:115], v[110:111]
	v_pk_mul_f32 v[62:63], v[62:63], v[64:65]
	v_fma_f32 v15, -v10, v12, 1.0
	v_fmac_f32_e32 v12, v15, v12
	v_div_scale_f32 v15, vcc, v32, v27, v32
	v_mul_f32_e32 v22, v15, v12
	v_fma_f32 v24, -v10, v22, v15
	v_fmac_f32_e32 v22, v24, v12
	v_fma_f32 v10, -v10, v22, v15
	v_div_scale_f32 v15, s[8:9], v26, v26, v30
	v_rcp_f32_e32 v24, v15
	v_div_fmas_f32 v10, v10, v12, v22
	v_div_fixup_f32 v27, v10, v27, v32
	v_pk_mul_f32 v[110:111], v[112:113], v[110:111]
	v_fma_f32 v10, -v15, v24, 1.0
	v_fmac_f32_e32 v24, v10, v24
	v_div_scale_f32 v10, vcc, v30, v26, v30
	v_mul_f32_e32 v12, v10, v24
	v_fma_f32 v22, -v15, v12, v10
	v_fmac_f32_e32 v12, v22, v24
	v_fma_f32 v10, -v15, v12, v10
	v_div_fmas_f32 v10, v10, v24, v12
	v_mul_f32_e32 v12, 0xbfb8aa3b, v33
	v_exp_f32_e32 v29, v12
	v_div_fixup_f32 v26, v10, v26, v30
	v_mov_b32_e32 v12, v11
	v_mov_b32_e32 v24, v23
	v_pk_add_f32 v[10:11], v[28:29], 1.0 op_sel_hi:[1,0]
	v_pk_mul_f32 v[26:27], v[62:63], v[26:27]
	v_div_scale_f32 v15, s[8:9], v11, v11, v33
	v_rcp_f32_e32 v22, v15
	v_pk_mul_f32 v[12:13], v[12:13], v[14:15] op_sel_hi:[1,0]
	v_lshlrev_b32_e32 v42, 1, v54
	v_pk_mul_f32 v[12:13], v[12:13], v[24:25]
	v_fma_f32 v23, -v15, v22, 1.0
	v_fmac_f32_e32 v22, v23, v22
	v_div_scale_f32 v23, vcc, v33, v11, v33
	v_mul_f32_e32 v24, v23, v22
	v_fma_f32 v25, -v15, v24, v23
	v_fmac_f32_e32 v24, v25, v22
	v_fma_f32 v15, -v15, v24, v23
	v_div_scale_f32 v23, s[8:9], v10, v10, v31
	v_rcp_f32_e32 v25, v23
	v_div_fmas_f32 v15, v15, v22, v24
	v_div_fixup_f32 v11, v15, v11, v33
	v_fma_f32 v15, -v23, v25, 1.0
	v_fmac_f32_e32 v25, v15, v25
	v_div_scale_f32 v15, vcc, v31, v10, v31
	v_mul_f32_e32 v22, v15, v25
	v_fma_f32 v24, -v23, v22, v15
	v_fmac_f32_e32 v22, v24, v25
	v_fma_f32 v15, -v23, v22, v15
	v_div_fmas_f32 v15, v15, v25, v22
	v_div_fixup_f32 v10, v15, v10, v31
	v_pk_mul_f32 v[10:11], v[12:13], v[10:11]
	v_cvt_pk_bf16_f32 v13, v27, v11
	v_cvt_pk_bf16_f32 v11, v111, v21
	s_waitcnt vmcnt(0)
	v_mul_f32_e32 v15, 0xbfb8aa3b, v16
	v_cvt_pk_bf16_f32 v12, v26, v10
	v_cvt_pk_bf16_f32 v10, v110, v20
	v_exp_f32_e32 v20, v15
	v_mul_f32_e32 v15, 0xbfb8aa3b, v17
	v_exp_f32_e32 v22, v15
	v_mul_f32_e32 v15, 0xbfb8aa3b, v18
	v_exp_f32_e32 v21, v15
	v_mov_b32_e32 v24, v6
	v_mov_b32_e32 v25, v8
	v_pk_mul_f32 v[24:25], v[24:25], v[14:15] op_sel_hi:[1,0]
	v_pk_add_f32 v[20:21], v[20:21], 1.0 op_sel_hi:[1,0]
	v_mov_b32_e32 v26, v106
	v_div_scale_f32 v6, s[8:9], v21, v21, v18
	v_rcp_f32_e32 v8, v6
	v_mov_b32_e32 v27, v108
	v_pk_mul_f32 v[24:25], v[24:25], v[26:27]
	v_mov_b32_e32 v108, v107
	v_fma_f32 v15, -v6, v8, 1.0
	v_fmac_f32_e32 v8, v15, v8
	v_div_scale_f32 v15, vcc, v18, v21, v18
	v_mul_f32_e32 v23, v15, v8
	v_fma_f32 v26, -v6, v23, v15
	v_fmac_f32_e32 v23, v26, v8
	v_fma_f32 v6, -v6, v23, v15
	v_div_scale_f32 v15, s[8:9], v20, v20, v16
	v_rcp_f32_e32 v26, v15
	v_div_fmas_f32 v6, v6, v8, v23
	v_div_fixup_f32 v21, v6, v21, v18
	v_fma_f32 v6, -v15, v26, 1.0
	v_fmac_f32_e32 v26, v6, v26
	v_div_scale_f32 v6, vcc, v16, v20, v16
	v_mul_f32_e32 v8, v6, v26
	v_fma_f32 v18, -v15, v8, v6
	v_fmac_f32_e32 v8, v18, v26
	v_fma_f32 v6, -v15, v8, v6
	v_div_fmas_f32 v6, v6, v26, v8
	v_mul_f32_e32 v8, 0xbfb8aa3b, v19
	v_exp_f32_e32 v23, v8
	v_div_fixup_f32 v20, v6, v20, v16
	v_mov_b32_e32 v8, v7
	v_pk_mul_f32 v[20:21], v[24:25], v[20:21]
	v_pk_add_f32 v[6:7], v[22:23], 1.0 op_sel_hi:[1,0]
	s_nop 0
	v_div_scale_f32 v15, s[8:9], v7, v7, v19
	v_rcp_f32_e32 v16, v15
	v_pk_mul_f32 v[8:9], v[8:9], v[14:15] op_sel_hi:[1,0]
	v_fma_f32 v18, -v15, v16, 1.0
	v_fmac_f32_e32 v16, v18, v16
	v_div_scale_f32 v18, vcc, v19, v7, v19
	v_mul_f32_e32 v22, v18, v16
	v_fma_f32 v23, -v15, v22, v18
	v_fmac_f32_e32 v22, v23, v16
	v_fma_f32 v15, -v15, v22, v18
	v_div_scale_f32 v18, s[8:9], v6, v6, v17
	v_rcp_f32_e32 v23, v18
	v_div_fmas_f32 v15, v15, v16, v22
	v_div_fixup_f32 v7, v15, v7, v19
	v_pk_mul_f32 v[8:9], v[8:9], v[108:109]
	v_fma_f32 v15, -v18, v23, 1.0
	v_fmac_f32_e32 v23, v15, v23
	v_div_scale_f32 v15, vcc, v17, v6, v17
	v_mul_f32_e32 v16, v15, v23
	v_fma_f32 v19, -v18, v16, v15
	v_fmac_f32_e32 v16, v19, v23
	v_fma_f32 v15, -v18, v16, v15
	v_div_fmas_f32 v15, v15, v23, v16
	v_div_fixup_f32 v6, v15, v6, v17
	v_pk_mul_f32 v[6:7], v[8:9], v[6:7]
	v_mul_f32_e32 v9, 0xbfb8aa3b, v35
	v_mul_f32_e32 v8, 0xbfb8aa3b, v34
	v_exp_f32_e32 v16, v9
	v_mul_f32_e32 v9, 0xbfb8aa3b, v36
	v_exp_f32_e32 v8, v8
	v_exp_f32_e32 v9, v9
	v_mov_b32_e32 v18, v2
	v_mov_b32_e32 v19, v4
	v_pk_mul_f32 v[18:19], v[18:19], v[14:15] op_sel_hi:[1,0]
	v_pk_add_f32 v[8:9], v[8:9], 1.0 op_sel_hi:[1,0]
	v_mov_b32_e32 v22, v38
	v_div_scale_f32 v2, s[8:9], v9, v9, v36
	v_rcp_f32_e32 v4, v2
	v_mov_b32_e32 v23, v40
	v_pk_mul_f32 v[18:19], v[18:19], v[22:23]
	v_mov_b32_e32 v40, v39
	v_fma_f32 v15, -v2, v4, 1.0
	v_fmac_f32_e32 v4, v15, v4
	v_div_scale_f32 v15, vcc, v36, v9, v36
	v_mul_f32_e32 v17, v15, v4
	v_fma_f32 v22, -v2, v17, v15
	v_fmac_f32_e32 v17, v22, v4
	v_fma_f32 v2, -v2, v17, v15
	v_div_scale_f32 v15, s[8:9], v8, v8, v34
	v_rcp_f32_e32 v22, v15
	v_div_fmas_f32 v2, v2, v4, v17
	v_div_fixup_f32 v9, v2, v9, v36
	v_fma_f32 v2, -v15, v22, 1.0
	v_fmac_f32_e32 v22, v2, v22
	v_div_scale_f32 v2, vcc, v34, v8, v34
	v_mul_f32_e32 v4, v2, v22
	v_fma_f32 v17, -v15, v4, v2
	v_fmac_f32_e32 v4, v17, v22
	v_fma_f32 v2, -v15, v4, v2
	v_div_fmas_f32 v2, v2, v22, v4
	v_mul_f32_e32 v4, 0xbfb8aa3b, v37
	v_exp_f32_e32 v17, v4
	v_div_fixup_f32 v8, v2, v8, v34
	v_mov_b32_e32 v4, v3
	v_pk_mul_f32 v[8:9], v[18:19], v[8:9]
	v_pk_add_f32 v[2:3], v[16:17], 1.0 op_sel_hi:[1,0]
	s_nop 0
	v_div_scale_f32 v15, s[8:9], v3, v3, v37
	v_rcp_f32_e32 v16, v15
	v_pk_mul_f32 v[4:5], v[4:5], v[14:15] op_sel_hi:[1,0]
	v_fma_f32 v14, -v15, v16, 1.0
	v_fmac_f32_e32 v16, v14, v16
	v_div_scale_f32 v14, vcc, v37, v3, v37
	v_mul_f32_e32 v17, v14, v16
	v_fma_f32 v18, -v15, v17, v14
	v_fmac_f32_e32 v17, v18, v16
	v_fma_f32 v14, -v15, v17, v14
	v_div_scale_f32 v15, s[8:9], v2, v2, v35
	v_rcp_f32_e32 v18, v15
	v_div_fmas_f32 v14, v14, v16, v17
	v_div_fixup_f32 v3, v14, v3, v37
	v_pk_mul_f32 v[4:5], v[4:5], v[40:41]
	v_fma_f32 v14, -v15, v18, 1.0
	v_fmac_f32_e32 v18, v14, v18
	v_div_scale_f32 v14, vcc, v35, v2, v35
	v_mul_f32_e32 v16, v14, v18
	v_fma_f32 v17, -v15, v16, v14
	v_fmac_f32_e32 v16, v17, v18
	v_fma_f32 v14, -v15, v16, v14
	v_div_fmas_f32 v14, v14, v18, v16
	v_div_fixup_f32 v2, v14, v2, v35
	v_pk_mul_f32 v[2:3], v[4:5], v[2:3]
	v_bfe_u32 v5, v2, 16, 1
	v_add3_u32 v2, v2, v5, s33
	v_bfe_u32 v14, v8, 16, 1
	v_add3_u32 v8, v8, v14, s33
	v_lshrrev_b32_e32 v4, 16, v8
	v_cvt_pk_bf16_f32 v5, v9, v3
	v_and_or_b32 v4, v2, s34, v4
	v_cvt_pk_bf16_f32 v3, v21, v7
	v_cvt_pk_bf16_f32 v2, v20, v6
	v_lshlrev_b64 v[6:7], 11, v[60:61]
	v_lshl_add_u64 v[6:7], s[68:69], 0, v[6:7]
	v_lshl_add_u64 v[6:7], v[6:7], 0, s[70:71]
	v_lshl_add_u64 v[6:7], v[6:7], 0, v[42:43]
	v_lshl_add_u64 v[8:9], v[6:7], 0, s[74:75]
	v_add_co_u32_e32 v6, vcc, 0xdc00000, v6
	s_nop 1
	v_addc_co_u32_e32 v7, vcc, 0, v7, vcc
	global_store_dwordx4 v[6:7], v[10:13], off offset:1024
	global_store_dwordx4 v[8:9], v[2:5], off offset:16
	s_branch .LBB0_2949

.LBB0_3086:
	v_lshl_add_u64 v[18:19], s[68:69], 0, v[94:95]
	v_lshl_add_u64 v[22:23], s[68:69], 0, v[92:93]
	v_add_co_u32_e32 v20, vcc, 0x7800000, v18
	v_add_co_u32_e64 v102, s[6:7], s22, v22
	s_nop 0
	v_addc_co_u32_e32 v21, vcc, 0, v19, vcc
	v_addc_co_u32_e64 v103, s[6:7], 0, v23, s[6:7]
	v_add_co_u32_e64 v104, s[6:7], s23, v22
	v_add_co_u32_e32 v22, vcc, 0x7801000, v18
	s_nop 0
	v_addc_co_u32_e64 v105, s[6:7], 0, v23, s[6:7]
	global_load_dwordx4 v[78:81], v[20:21], off
	global_load_dwordx4 v[74:77], v[20:21], off offset:1024
	global_load_dwordx4 v[70:73], v[20:21], off offset:2048
	global_load_dwordx4 v[66:69], v[20:21], off offset:3072
	v_addc_co_u32_e32 v23, vcc, 0, v19, vcc
	v_add_co_u32_e32 v20, vcc, 0x7802000, v18
	global_load_dwordx4 v[62:65], v[22:23], off
	global_load_dwordx4 v[58:61], v[22:23], off offset:1024
	global_load_dwordx4 v[54:57], v[22:23], off offset:2048
	global_load_dwordx4 v[50:53], v[22:23], off offset:3072
	v_addc_co_u32_e32 v21, vcc, 0, v19, vcc
	v_add_co_u32_e32 v82, vcc, 0x7803000, v18
	global_load_dwordx4 v[46:49], v[20:21], off
	global_load_dwordx4 v[42:45], v[20:21], off offset:1024
	global_load_dwordx4 v[38:41], v[20:21], off offset:2048
	global_load_dwordx4 v[34:37], v[20:21], off offset:3072
	v_addc_co_u32_e32 v83, vcc, 0, v19, vcc
	global_load_dwordx4 v[30:33], v[82:83], off
	global_load_dwordx4 v[26:29], v[82:83], off offset:1024
	global_load_dwordx4 v[22:25], v[82:83], off offset:2048
	global_load_dwordx4 v[18:21], v[82:83], off offset:3072
	s_add_i32 s24, s8, 32
	s_add_i32 s10, s8, 0xffffc022
	s_ashr_i32 s9, s24, 13
	s_cmpk_lt_i32 s24, 0x4000
	s_cselect_b32 s6, s9, s10
	s_mul_hi_i32 s7, s6, 0x9000
	s_mul_i32 s6, s6, 0x9000
	s_add_u32 s10, s4, s6
	s_addc_u32 s11, s5, s7
	s_add_u32 s6, s10, 0x6000
	s_addc_u32 s7, s11, 0
	s_add_u32 s10, s10, 0x7000
	s_addc_u32 s11, s11, 0
	v_lshl_add_u64 v[82:83], s[6:7], 0, v[90:91]
	v_lshl_add_u64 v[86:87], s[10:11], 0, v[90:91]
	global_load_dwordx4 v[82:85], v[82:83], off
	v_lshl_add_u64 v[148:149], s[6:7], 0, v[96:97]
	global_load_dwordx4 v[86:89], v[86:87], off
	v_lshl_add_u64 v[142:143], s[6:7], 0, v[98:99]
	v_lshl_add_u64 v[134:135], s[6:7], 0, v[100:101]
	s_add_i32 s6, s8, 0xffffc023
	s_cmpk_lt_i32 s24, 0x3fff
	s_cselect_b32 s6, s9, s6
	s_mul_hi_i32 s7, s6, 0x9000
	s_mul_i32 s6, s6, 0x9000
	v_lshl_add_u64 v[152:153], s[10:11], 0, v[96:97]
	v_lshl_add_u64 v[146:147], s[10:11], 0, v[98:99]
	v_lshl_add_u64 v[140:141], s[10:11], 0, v[100:101]
	s_add_u32 s10, s4, s6
	s_addc_u32 s11, s5, s7
	s_add_u32 s6, s10, 0x6000
	s_addc_u32 s7, s11, 0
	s_add_u32 s10, s10, 0x7000
	v_lshl_add_u64 v[132:133], s[6:7], 0, v[90:91]
	v_lshl_add_u64 v[126:127], s[6:7], 0, v[96:97]
	v_lshl_add_u64 v[118:119], s[6:7], 0, v[98:99]
	v_lshl_add_u64 v[114:115], s[6:7], 0, v[100:101]
	s_addc_u32 s11, s11, 0
	s_add_i32 s6, s8, 0xffffc024
	s_cmpk_lt_i32 s24, 0x3ffe
	s_cselect_b32 s6, s9, s6
	s_mul_hi_i32 s7, s6, 0x9000
	s_mul_i32 s6, s6, 0x9000
	s_add_u32 s6, s4, s6
	s_addc_u32 s7, s5, s7
	v_lshl_add_u64 v[138:139], s[10:11], 0, v[90:91]
	v_lshl_add_u64 v[130:131], s[10:11], 0, v[96:97]
	v_lshl_add_u64 v[124:125], s[10:11], 0, v[98:99]
	v_lshl_add_u64 v[116:117], s[10:11], 0, v[100:101]
	s_add_u32 s10, s6, 0x6000
	s_addc_u32 s11, s7, 0
	s_add_u32 s6, s6, 0x7000
	s_addc_u32 s7, s7, 0
	s_addk_i32 s8, 0xc025
	s_cmpk_lt_i32 s24, 0x3ffd
	v_lshl_add_u64 v[156:157], s[6:7], 0, v[90:91]
	v_lshl_add_u64 v[154:155], s[6:7], 0, v[96:97]
	v_lshl_add_u64 v[150:151], s[6:7], 0, v[98:99]
	v_lshl_add_u64 v[136:137], s[6:7], 0, v[100:101]
	s_cselect_b32 s6, s9, s8
	s_mul_hi_i32 s7, s6, 0x9000
	s_mul_i32 s6, s6, 0x9000
	s_add_u32 s6, s4, s6
	s_waitcnt vmcnt(0) lgkmcnt(0)
	v_pk_mul_f32 v[158:159], v[80:81], v[80:81]
	v_pk_mul_f32 v[160:161], v[78:79], v[78:79]
	v_pk_mul_f32 v[162:163], v[76:77], v[76:77]
	v_pk_mul_f32 v[164:165], v[74:75], v[74:75]
	v_mul_f32_e32 v174, v71, v71
	v_mul_f32_e32 v176, v73, v73
	v_mul_f32_e32 v187, v68, v68
	v_mul_f32_e32 v189, v69, v69
	v_pk_mov_b32 v[178:179], v[160:161], v[158:159] op_sel:[1,0]
	v_mov_b32_e32 v161, v159
	v_pk_mov_b32 v[158:159], v[164:165], v[162:163] op_sel:[1,0]
	v_mov_b32_e32 v165, v163
	v_pk_fma_f32 v[162:163], v[70:71], v[70:71], v[174:175] op_sel_hi:[1,1,0]
	v_pk_fma_f32 v[174:175], v[72:73], v[72:73], v[176:177] op_sel_hi:[1,1,0]
	v_pk_mul_f32 v[176:177], v[64:65], v[64:65]
	v_pk_mul_f32 v[180:181], v[62:63], v[62:63]
	v_pk_mul_f32 v[182:183], v[60:61], v[60:61]
	v_pk_mul_f32 v[184:185], v[58:59], v[58:59]
	v_mul_f32_e32 v186, v55, v55
	v_mul_f32_e32 v188, v57, v57
	v_pk_add_f32 v[160:161], v[178:179], v[160:161]
	v_pk_add_f32 v[158:159], v[158:159], v[164:165]
	v_mov_b32_e32 v163, v187
	v_mov_b32_e32 v175, v189
	v_pk_mov_b32 v[164:165], v[180:181], v[176:177] op_sel:[1,0]
	v_mov_b32_e32 v181, v177
	v_pk_mov_b32 v[176:177], v[184:185], v[182:183] op_sel:[1,0]
	v_mov_b32_e32 v185, v183
	v_pk_fma_f32 v[178:179], v[54:55], v[54:55], v[186:187] op_sel_hi:[1,1,0]
	v_pk_fma_f32 v[182:183], v[56:57], v[56:57], v[188:189] op_sel_hi:[1,1,0]
	v_pk_mul_f32 v[186:187], v[48:49], v[48:49]
	v_pk_mul_f32 v[188:189], v[46:47], v[46:47]
	v_pk_mul_f32 v[190:191], v[44:45], v[44:45]
	v_pk_mul_f32 v[192:193], v[42:43], v[42:43]
	v_mul_f32_e32 v173, v66, v66
	v_mul_f32_e32 v197, v67, v67
	v_mul_f32_e32 v195, v52, v52
	v_mul_f32_e32 v202, v53, v53
	v_mul_f32_e32 v194, v39, v39
	v_mul_f32_e32 v196, v41, v41
	v_pk_add_f32 v[198:199], v[160:161], v[160:161] op_sel:[0,1] op_sel_hi:[1,0]
	v_pk_add_f32 v[200:201], v[158:159], v[158:159] op_sel:[0,1] op_sel_hi:[1,0]
	v_pk_add_f32 v[174:175], v[162:163], v[174:175]
	v_pk_add_f32 v[158:159], v[164:165], v[180:181]
	v_pk_add_f32 v[160:161], v[176:177], v[184:185]
	v_pk_mov_b32 v[162:163], v[188:189], v[186:187] op_sel:[1,0]
	v_mov_b32_e32 v189, v187
	v_pk_mov_b32 v[164:165], v[192:193], v[190:191] op_sel:[1,0]
	v_mov_b32_e32 v193, v191
	v_mul_f32_e32 v203, v50, v50
	v_mul_f32_e32 v208, v51, v51
	v_mul_f32_e32 v211, v36, v36
	v_mul_f32_e32 v212, v37, v37
	v_mov_b32_e32 v179, v195
	v_mov_b32_e32 v183, v202
	v_pk_fma_f32 v[176:177], v[38:39], v[38:39], v[194:195] op_sel_hi:[1,1,0]
	v_pk_fma_f32 v[180:181], v[40:41], v[40:41], v[196:197] op_sel_hi:[1,1,0]
	v_pk_mul_f32 v[184:185], v[32:33], v[32:33]
	v_pk_mul_f32 v[186:187], v[30:31], v[30:31]
	v_pk_mul_f32 v[190:191], v[28:29], v[28:29]
	v_pk_mul_f32 v[194:195], v[26:27], v[26:27]
	v_mov_b32_e32 v199, v173
	v_mov_b32_e32 v201, v197
	v_pk_add_f32 v[204:205], v[158:159], v[158:159] op_sel:[0,1] op_sel_hi:[1,0]
	v_pk_add_f32 v[206:207], v[160:161], v[160:161] op_sel:[0,1] op_sel_hi:[1,0]
	v_pk_add_f32 v[162:163], v[162:163], v[188:189]
	v_pk_add_f32 v[164:165], v[164:165], v[192:193]
	v_mul_f32_e32 v209, v34, v34
	v_mul_f32_e32 v210, v35, v35
	v_pk_add_f32 v[178:179], v[178:179], v[182:183]
	v_mov_b32_e32 v177, v211
	v_mov_b32_e32 v181, v212
	v_pk_mov_b32 v[182:183], v[186:187], v[184:185] op_sel:[1,0]
	v_mov_b32_e32 v187, v185
	v_pk_mov_b32 v[184:185], v[194:195], v[190:191] op_sel:[1,0]
	v_mov_b32_e32 v195, v191
	v_pk_add_f32 v[188:189], v[198:199], v[200:201]
	v_mov_b32_e32 v205, v203
	v_mov_b32_e32 v207, v208
	v_pk_add_f32 v[190:191], v[162:163], v[162:163] op_sel:[0,1] op_sel_hi:[1,0]
	v_pk_add_f32 v[192:193], v[164:165], v[164:165] op_sel:[0,1] op_sel_hi:[1,0]
	v_pk_add_f32 v[176:177], v[176:177], v[180:181]
	v_pk_add_f32 v[174:175], v[188:189], v[174:175]
	v_pk_add_f32 v[180:181], v[204:205], v[206:207]
	v_mov_b32_e32 v191, v209
	v_mov_b32_e32 v193, v210
	v_add_f32_e32 v173, v174, v175
	v_pk_add_f32 v[174:175], v[180:181], v[178:179]
	v_pk_add_f32 v[178:179], v[190:191], v[192:193]
	v_add_f32_e32 v180, v174, v175
	v_pk_add_f32 v[174:175], v[178:179], v[176:177]
	ds_bpermute_b32 v176, v1, v173
	v_add_f32_e32 v174, v174, v175
	ds_bpermute_b32 v175, v1, v180
	ds_bpermute_b32 v177, v1, v174
	s_addc_u32 s7, s5, s7
	s_waitcnt lgkmcnt(2)
	v_add_f32_e32 v173, v173, v176
	ds_bpermute_b32 v176, v166, v173
	s_waitcnt lgkmcnt(2)
	v_add_f32_e32 v175, v180, v175
	ds_bpermute_b32 v178, v166, v175
	s_waitcnt lgkmcnt(2)
	v_add_f32_e32 v174, v174, v177
	ds_bpermute_b32 v177, v166, v174
	s_waitcnt lgkmcnt(2)
	v_add_f32_e32 v173, v173, v176
	ds_bpermute_b32 v176, v167, v173
	s_waitcnt lgkmcnt(2)
	v_add_f32_e32 v175, v175, v178
	ds_bpermute_b32 v178, v167, v175
	s_waitcnt lgkmcnt(2)
	v_add_f32_e32 v174, v174, v177
	ds_bpermute_b32 v177, v167, v174
	s_waitcnt lgkmcnt(2)
	v_add_f32_e32 v173, v173, v176
	ds_bpermute_b32 v176, v168, v173
	s_waitcnt lgkmcnt(2)
	v_add_f32_e32 v175, v175, v178
	ds_bpermute_b32 v178, v168, v175
	s_waitcnt lgkmcnt(2)
	v_add_f32_e32 v174, v174, v177
	ds_bpermute_b32 v177, v168, v174
	s_waitcnt lgkmcnt(2)
	v_add_f32_e32 v173, v173, v176
	ds_bpermute_b32 v176, v169, v173
	s_waitcnt lgkmcnt(2)
	v_add_f32_e32 v175, v175, v178
	ds_bpermute_b32 v178, v169, v175
	s_waitcnt lgkmcnt(2)
	v_add_f32_e32 v174, v174, v177
	ds_bpermute_b32 v177, v169, v174
	s_waitcnt lgkmcnt(2)
	v_add_f32_e32 v173, v173, v176
	ds_bpermute_b32 v176, v170, v173
	s_waitcnt lgkmcnt(2)
	v_add_f32_e32 v175, v175, v178
	ds_bpermute_b32 v178, v170, v175
	s_waitcnt lgkmcnt(2)
	v_add_f32_e32 v174, v174, v177
	ds_bpermute_b32 v177, v170, v174
	s_waitcnt lgkmcnt(2)
	v_add_f32_e32 v173, v173, v176
	s_add_u32 s16, s6, 0x6000
	v_fmamk_f32 v173, v173, 0x3a800000, v171
	s_addc_u32 s17, s7, 0
	s_waitcnt lgkmcnt(1)
	v_add_f32_e32 v175, v175, v178
	v_mul_f32_e32 v176, 0x4f800000, v173
	v_cmp_gt_f32_e32 vcc, s2, v173
	s_add_u32 s18, s6, 0x7000
	v_fmamk_f32 v175, v175, 0x3a800000, v171
	v_cndmask_b32_e32 v173, v173, v176, vcc
	s_addc_u32 s19, s7, 0
	s_waitcnt lgkmcnt(0)
	v_add_f32_e32 v174, v174, v177
	v_mul_f32_e32 v176, 0x4f800000, v175
	v_cmp_gt_f32_e64 s[6:7], s2, v175
	v_sqrt_f32_e32 v177, v173
	v_fmamk_f32 v174, v174, 0x3a800000, v171
	v_cndmask_b32_e64 v175, v175, v176, s[6:7]
	v_mul_f32_e32 v176, 0x4f800000, v174
	v_cmp_gt_f32_e64 s[8:9], s2, v174
	v_sqrt_f32_e32 v178, v175
	v_add_u32_e32 v179, -1, v177
	v_cndmask_b32_e64 v174, v174, v176, s[8:9]
	v_sqrt_f32_e32 v176, v174
	v_add_u32_e32 v180, 1, v177
	v_fma_f32 v181, -v179, v177, v173
	v_lshl_add_u64 v[112:113], s[10:11], 0, v[90:91]
	v_lshl_add_u64 v[106:107], s[10:11], 0, v[96:97]
	v_lshl_add_u64 v[108:109], s[10:11], 0, v[98:99]
	v_lshl_add_u64 v[110:111], s[10:11], 0, v[100:101]
	v_pk_add_f32 v[162:163], v[182:183], v[186:187]
	v_fma_f32 v182, -v180, v177, v173
	v_add_u32_e32 v183, -1, v178
	v_cmp_ge_f32_e64 s[10:11], 0, v181
	v_pk_add_f32 v[164:165], v[184:185], v[194:195]
	v_add_u32_e32 v184, 1, v178
	v_cndmask_b32_e64 v177, v177, v179, s[10:11]
	v_fma_f32 v179, -v183, v178, v175
	v_cmp_lt_f32_e64 s[10:11], 0, v182
	v_fma_f32 v181, -v184, v178, v175
	v_add_u32_e32 v185, -1, v176
	v_cndmask_b32_e64 v177, v177, v180, s[10:11]
	v_cmp_ge_f32_e64 s[10:11], 0, v179
	v_add_u32_e32 v186, 1, v176
	v_fma_f32 v179, -v185, v176, v174
	v_cndmask_b32_e64 v178, v178, v183, s[10:11]
	v_cmp_lt_f32_e64 s[10:11], 0, v181
	v_fma_f32 v180, -v186, v176, v174
	v_mul_f32_e32 v181, 0x37800000, v177
	v_cndmask_b32_e64 v178, v178, v184, s[10:11]
	v_cmp_ge_f32_e64 s[10:11], 0, v179
	v_cndmask_b32_e32 v177, v177, v181, vcc
	v_cmp_class_f32_e32 vcc, v173, v172
	v_cndmask_b32_e64 v176, v176, v185, s[10:11]
	v_cmp_lt_f32_e64 s[10:11], 0, v180
	v_mul_f32_e32 v179, 0x37800000, v178
	v_cndmask_b32_e32 v173, v177, v173, vcc
	v_cndmask_b32_e64 v176, v176, v186, s[10:11]
	v_cndmask_b32_e64 v177, v178, v179, s[6:7]
	v_cmp_class_f32_e32 vcc, v175, v172
	v_mul_f32_e32 v178, 0x37800000, v176
	v_div_scale_f32 v179, s[6:7], v173, v173, 1.0
	v_cndmask_b32_e32 v175, v177, v175, vcc
	v_cndmask_b32_e64 v176, v176, v178, s[8:9]
	v_cmp_class_f32_e32 vcc, v174, v172
	v_rcp_f32_e32 v177, v179
	v_div_scale_f32 v178, s[8:9], v175, v175, 1.0
	v_cndmask_b32_e32 v176, v176, v174, vcc
	v_rcp_f32_e32 v182, v178
	v_div_scale_f32 v183, s[10:11], v176, v176, 1.0
	v_rcp_f32_e32 v185, v183
	v_fma_f32 v174, -v179, v177, 1.0
	v_div_scale_f32 v180, s[6:7], 1.0, v173, 1.0
	v_fmac_f32_e32 v177, v174, v177
	v_fma_f32 v174, -v178, v182, 1.0
	v_mul_f32_e32 v186, v180, v177
	v_div_scale_f32 v181, s[8:9], 1.0, v175, 1.0
	v_fmac_f32_e32 v182, v174, v182
	v_fma_f32 v174, -v183, v185, 1.0
	v_fma_f32 v187, -v179, v186, v180
	v_div_scale_f32 v184, s[10:11], 1.0, v176, 1.0
	v_mul_f32_e32 v188, v181, v182
	v_fmac_f32_e32 v185, v174, v185
	v_fmac_f32_e32 v186, v187, v177
	v_fma_f32 v174, -v178, v188, v181
	v_mul_f32_e32 v187, v184, v185
	v_fma_f32 v179, -v179, v186, v180
	s_mov_b64 vcc, s[6:7]
	v_fmac_f32_e32 v188, v174, v182
	v_fma_f32 v174, -v183, v187, v184
	v_div_fmas_f32 v177, v179, v177, v186
	v_fma_f32 v178, -v178, v188, v181
	v_fmac_f32_e32 v187, v174, v185
	v_div_fixup_f32 v174, v177, v173, 1.0
	s_mov_b64 vcc, s[8:9]
	v_div_fmas_f32 v173, v178, v182, v188
	v_fma_f32 v177, -v183, v187, v184
	v_pk_mul_f32 v[80:81], v[80:81], v[174:175] op_sel_hi:[1,0]
	v_pk_mul_f32 v[78:79], v[78:79], v[174:175] op_sel_hi:[1,0]
	s_mov_b64 vcc, s[10:11]
	v_pk_add_f32 v[88:89], v[88:89], 1.0 op_sel_hi:[1,0]
	v_pk_add_f32 v[86:87], v[86:87], 1.0 op_sel_hi:[1,0]
	v_pk_mul_f32 v[76:77], v[76:77], v[174:175] op_sel_hi:[1,0]
	v_pk_mul_f32 v[74:75], v[74:75], v[174:175] op_sel_hi:[1,0]
	v_pk_mul_f32 v[72:73], v[72:73], v[174:175] op_sel_hi:[1,0]
	v_pk_mul_f32 v[70:71], v[70:71], v[174:175] op_sel_hi:[1,0]
	v_pk_mul_f32 v[68:69], v[68:69], v[174:175] op_sel_hi:[1,0]
	v_pk_mul_f32 v[66:67], v[66:67], v[174:175] op_sel_hi:[1,0]
	v_div_fixup_f32 v174, v173, v175, 1.0
	v_div_fmas_f32 v173, v177, v185, v187
	v_pk_mul_f32 v[78:79], v[2:3], v[78:79]
	v_pk_mul_f32 v[80:81], v[4:5], v[80:81]
	v_pk_mul_f32 v[64:65], v[64:65], v[174:175] op_sel_hi:[1,0]
	v_pk_mul_f32 v[62:63], v[62:63], v[174:175] op_sel_hi:[1,0]
	v_pk_mul_f32 v[60:61], v[60:61], v[174:175] op_sel_hi:[1,0]
	v_pk_mul_f32 v[58:59], v[58:59], v[174:175] op_sel_hi:[1,0]
	v_pk_mul_f32 v[56:57], v[56:57], v[174:175] op_sel_hi:[1,0]
	v_pk_mul_f32 v[54:55], v[54:55], v[174:175] op_sel_hi:[1,0]
	v_pk_mul_f32 v[52:53], v[52:53], v[174:175] op_sel_hi:[1,0]
	v_pk_mul_f32 v[174:175], v[50:51], v[174:175] op_sel_hi:[1,0]
	v_div_fixup_f32 v50, v173, v176, 1.0
	v_pk_fma_f32 v[80:81], v[88:89], v[80:81], v[84:85]
	v_pk_fma_f32 v[78:79], v[86:87], v[78:79], v[82:83]
	v_pk_mul_f32 v[86:87], v[16:17], v[52:53]
	v_pk_mul_f32 v[48:49], v[48:49], v[50:51] op_sel_hi:[1,0]
	v_pk_mul_f32 v[46:47], v[46:47], v[50:51] op_sel_hi:[1,0]
	v_pk_mul_f32 v[82:83], v[10:11], v[54:55]
	v_pk_mul_f32 v[84:85], v[14:15], v[174:175]
	v_pk_mul_f32 v[88:89], v[2:3], v[46:47]
	v_pk_mul_f32 v[174:175], v[4:5], v[48:49]
	v_cvt_pk_bf16_f32 v46, v78, v79
	v_cvt_pk_bf16_f32 v47, v80, v81
	global_store_dwordx2 v[102:103], v[46:47], off
	global_load_dwordx4 v[46:49], v[152:153], off
	s_nop 0
	global_load_dwordx4 v[52:55], v[148:149], off
	v_pk_mul_f32 v[74:75], v[6:7], v[74:75]
	v_pk_mul_f32 v[76:77], v[8:9], v[76:77]
	v_pk_mul_f32 v[70:71], v[10:11], v[70:71]
	v_pk_mul_f32 v[72:73], v[12:13], v[72:73]
	v_pk_mul_f32 v[66:67], v[66:67], v[14:15]
	v_pk_mul_f32 v[68:69], v[68:69], v[16:17]
	v_pk_mul_f32 v[62:63], v[2:3], v[62:63]
	v_pk_mul_f32 v[64:65], v[4:5], v[64:65]
	v_pk_mul_f32 v[58:59], v[6:7], v[58:59]
	v_pk_mul_f32 v[60:61], v[8:9], v[60:61]
	v_pk_mul_f32 v[56:57], v[12:13], v[56:57]
	v_mul_f32_e32 v196, v23, v23
	v_mul_f32_e32 v202, v25, v25
	v_mul_f32_e32 v213, v18, v18
	v_mul_f32_e32 v214, v19, v19
	v_mul_f32_e32 v215, v20, v20
	v_mul_f32_e32 v216, v21, v21
	v_pk_fma_f32 v[158:159], v[22:23], v[22:23], v[196:197] op_sel_hi:[1,1,0]
	v_pk_fma_f32 v[160:161], v[24:25], v[24:25], v[202:203] op_sel_hi:[1,1,0]
	v_mov_b32_e32 v159, v215
	v_mov_b32_e32 v161, v216
	v_lshl_add_u64 v[144:145], s[18:19], 0, v[90:91]
	v_lshl_add_u64 v[128:129], s[16:17], 0, v[90:91]
	v_lshl_add_u64 v[122:123], s[18:19], 0, v[96:97]
	v_lshl_add_u64 v[120:121], s[16:17], 0, v[96:97]
	v_lshl_add_u64 v[92:93], v[92:93], 0, s[12:13]
	v_lshl_add_u64 v[94:95], v[94:95], 0, s[14:15]
	s_mov_b32 s8, s24
	s_cmp_lt_i32 s24, s20
	s_waitcnt vmcnt(0) lgkmcnt(0)
	v_pk_add_f32 v[48:49], v[48:49], 1.0 op_sel_hi:[1,0]
	v_pk_add_f32 v[46:47], v[46:47], 1.0 op_sel_hi:[1,0]
	v_pk_fma_f32 v[48:49], v[48:49], v[76:77], v[54:55]
	v_pk_fma_f32 v[46:47], v[46:47], v[74:75], v[52:53]
	v_cvt_pk_bf16_f32 v46, v46, v47
	v_cvt_pk_bf16_f32 v47, v48, v49
	global_store_dwordx2 v[102:103], v[46:47], off offset:512
	global_load_dwordx4 v[46:49], v[146:147], off
	s_nop 0
	global_load_dwordx4 v[52:55], v[142:143], off
	s_waitcnt vmcnt(0) lgkmcnt(0)
	v_pk_add_f32 v[48:49], v[48:49], 1.0 op_sel_hi:[1,0]
	v_pk_add_f32 v[46:47], v[46:47], 1.0 op_sel_hi:[1,0]
	v_pk_fma_f32 v[48:49], v[72:73], v[48:49], v[54:55]
	v_pk_fma_f32 v[46:47], v[70:71], v[46:47], v[52:53]
	v_cvt_pk_bf16_f32 v46, v46, v47
	v_cvt_pk_bf16_f32 v47, v48, v49
	global_store_dwordx2 v[102:103], v[46:47], off offset:1024
	global_load_dwordx4 v[46:49], v[140:141], off
	s_nop 0
	global_load_dwordx4 v[52:55], v[134:135], off
	s_waitcnt vmcnt(0) lgkmcnt(0)
	v_pk_add_f32 v[48:49], v[48:49], 1.0 op_sel_hi:[1,0]
	v_pk_add_f32 v[46:47], v[46:47], 1.0 op_sel_hi:[1,0]
	v_pk_fma_f32 v[48:49], v[68:69], v[48:49], v[54:55]
	v_pk_fma_f32 v[46:47], v[66:67], v[46:47], v[52:53]
	v_cvt_pk_bf16_f32 v46, v46, v47
	v_cvt_pk_bf16_f32 v47, v48, v49
	global_store_dwordx2 v[102:103], v[46:47], off offset:1536
	global_load_dwordx4 v[46:49], v[138:139], off
	s_nop 0
	global_load_dwordx4 v[52:55], v[132:133], off
	s_waitcnt vmcnt(0) lgkmcnt(0)
	v_pk_add_f32 v[48:49], v[48:49], 1.0 op_sel_hi:[1,0]
	v_pk_add_f32 v[46:47], v[46:47], 1.0 op_sel_hi:[1,0]
	v_pk_fma_f32 v[48:49], v[48:49], v[64:65], v[54:55]
	v_pk_fma_f32 v[46:47], v[46:47], v[62:63], v[52:53]
	v_cvt_pk_bf16_f32 v46, v46, v47
	v_cvt_pk_bf16_f32 v47, v48, v49
	global_store_dwordx2 v[102:103], v[46:47], off offset:2048
	global_load_dwordx4 v[46:49], v[130:131], off
	s_nop 0
	global_load_dwordx4 v[52:55], v[126:127], off
	s_waitcnt vmcnt(0) lgkmcnt(0)
	v_pk_add_f32 v[48:49], v[48:49], 1.0 op_sel_hi:[1,0]
	v_pk_add_f32 v[46:47], v[46:47], 1.0 op_sel_hi:[1,0]
	v_pk_fma_f32 v[48:49], v[48:49], v[60:61], v[54:55]
	v_pk_fma_f32 v[46:47], v[46:47], v[58:59], v[52:53]
	v_cvt_pk_bf16_f32 v46, v46, v47
	v_cvt_pk_bf16_f32 v47, v48, v49
	global_store_dwordx2 v[102:103], v[46:47], off offset:2560
	global_load_dwordx4 v[46:49], v[124:125], off
	s_nop 0
	global_load_dwordx4 v[52:55], v[118:119], off
	v_pk_add_f32 v[58:59], v[164:165], v[164:165] op_sel:[0,1] op_sel_hi:[1,0]
	v_pk_add_f32 v[60:61], v[158:159], v[160:161]
	v_mov_b32_e32 v59, v214
	s_waitcnt vmcnt(0) lgkmcnt(0)
	v_pk_add_f32 v[48:49], v[48:49], 1.0 op_sel_hi:[1,0]
	v_pk_add_f32 v[46:47], v[46:47], 1.0 op_sel_hi:[1,0]
	v_pk_fma_f32 v[48:49], v[48:49], v[56:57], v[54:55]
	v_pk_fma_f32 v[46:47], v[46:47], v[82:83], v[52:53]
	v_cvt_pk_bf16_f32 v46, v46, v47
	v_cvt_pk_bf16_f32 v47, v48, v49
	global_store_dwordx2 v[102:103], v[46:47], off offset:3072
	global_load_dwordx4 v[46:49], v[116:117], off
	s_nop 0
	global_load_dwordx4 v[52:55], v[114:115], off
	v_pk_add_f32 v[56:57], v[162:163], v[162:163] op_sel:[0,1] op_sel_hi:[1,0]
	s_waitcnt vmcnt(0) lgkmcnt(0)
	v_pk_add_f32 v[48:49], v[48:49], 1.0 op_sel_hi:[1,0]
	v_pk_add_f32 v[46:47], v[46:47], 1.0 op_sel_hi:[1,0]
	v_pk_fma_f32 v[48:49], v[86:87], v[48:49], v[54:55]
	v_pk_fma_f32 v[46:47], v[84:85], v[46:47], v[52:53]
	v_cvt_pk_bf16_f32 v46, v46, v47
	v_cvt_pk_bf16_f32 v47, v48, v49
	global_store_dwordx2 v[102:103], v[46:47], off offset:3584
	global_load_dwordx4 v[46:49], v[156:157], off
	s_nop 0
	global_load_dwordx4 v[52:55], v[112:113], off
	v_mov_b32_e32 v57, v213
	s_waitcnt vmcnt(0) lgkmcnt(0)
	v_pk_add_f32 v[48:49], v[48:49], 1.0 op_sel_hi:[1,0]
	v_pk_add_f32 v[46:47], v[46:47], 1.0 op_sel_hi:[1,0]
	v_pk_fma_f32 v[48:49], v[48:49], v[174:175], v[54:55]
	v_pk_fma_f32 v[46:47], v[46:47], v[88:89], v[52:53]
	v_bfe_u32 v51, v46, 16, 1
	v_bfe_u32 v52, v47, 16, 1
	v_add3_u32 v46, v46, v51, s3
	v_add3_u32 v47, v47, v52, s3
	v_lshrrev_b32_e32 v46, 16, v46
	v_and_or_b32 v46, v47, s21, v46
	v_cvt_pk_bf16_f32 v47, v48, v49
	global_store_dwordx2 v[104:105], v[46:47], off
	global_load_dwordx4 v[46:49], v[154:155], off
	s_nop 0
	global_load_dwordx4 v[52:55], v[106:107], off
	v_pk_mul_f32 v[44:45], v[44:45], v[50:51] op_sel_hi:[1,0]
	v_pk_mul_f32 v[42:43], v[42:43], v[50:51] op_sel_hi:[1,0]
	v_pk_mul_f32 v[44:45], v[8:9], v[44:45]
	v_pk_mul_f32 v[42:43], v[6:7], v[42:43]
	s_waitcnt vmcnt(0) lgkmcnt(0)
	v_pk_add_f32 v[48:49], v[48:49], 1.0 op_sel_hi:[1,0]
	v_pk_add_f32 v[46:47], v[46:47], 1.0 op_sel_hi:[1,0]
	v_pk_fma_f32 v[44:45], v[48:49], v[44:45], v[54:55]
	v_pk_fma_f32 v[42:43], v[46:47], v[42:43], v[52:53]
	v_cvt_pk_bf16_f32 v42, v42, v43
	v_cvt_pk_bf16_f32 v43, v44, v45
	global_store_dwordx2 v[104:105], v[42:43], off offset:512
	global_load_dwordx4 v[42:45], v[150:151], off
	s_nop 0
	global_load_dwordx4 v[46:49], v[108:109], off
	v_pk_add_f32 v[52:53], v[56:57], v[58:59]
	s_waitcnt vmcnt(0) lgkmcnt(0)
	v_pk_add_f32 v[44:45], v[44:45], 1.0 op_sel_hi:[1,0]
	v_pk_add_f32 v[52:53], v[52:53], v[60:61]
	v_pk_add_f32 v[42:43], v[42:43], 1.0 op_sel_hi:[1,0]
	v_add_f32_e32 v51, v52, v53
	ds_bpermute_b32 v52, v1, v51
	s_waitcnt lgkmcnt(0)
	v_add_f32_e32 v51, v51, v52
	ds_bpermute_b32 v52, v166, v51
	s_waitcnt lgkmcnt(0)
	v_add_f32_e32 v51, v51, v52
	v_pk_mul_f32 v[40:41], v[40:41], v[50:51] op_sel_hi:[1,0]
	v_pk_mul_f32 v[38:39], v[38:39], v[50:51] op_sel_hi:[1,0]
	v_pk_mul_f32 v[40:41], v[12:13], v[40:41]
	v_pk_mul_f32 v[38:39], v[10:11], v[38:39]
	v_pk_fma_f32 v[40:41], v[44:45], v[40:41], v[48:49]
	v_pk_fma_f32 v[38:39], v[42:43], v[38:39], v[46:47]
	v_cvt_pk_bf16_f32 v38, v38, v39
	v_cvt_pk_bf16_f32 v39, v40, v41
	global_store_dwordx2 v[104:105], v[38:39], off offset:1024
	global_load_dwordx4 v[38:41], v[136:137], off
	s_nop 0
	global_load_dwordx4 v[42:45], v[110:111], off
	v_pk_mul_f32 v[36:37], v[36:37], v[50:51] op_sel_hi:[1,0]
	v_pk_mul_f32 v[34:35], v[34:35], v[50:51] op_sel_hi:[1,0]
	v_pk_mul_f32 v[36:37], v[16:17], v[36:37]
	v_pk_mul_f32 v[34:35], v[14:15], v[34:35]
	ds_bpermute_b32 v46, v167, v51
	s_waitcnt lgkmcnt(0)
	v_add_f32_e32 v46, v51, v46
	ds_bpermute_b32 v47, v168, v46
	s_waitcnt lgkmcnt(0)
	v_add_f32_e32 v46, v46, v47
	ds_bpermute_b32 v47, v169, v46
	s_waitcnt lgkmcnt(0)
	v_add_f32_e32 v46, v46, v47
	ds_bpermute_b32 v47, v170, v46
	s_waitcnt lgkmcnt(0)
	v_add_f32_e32 v46, v46, v47
	v_fmamk_f32 v46, v46, 0x3a800000, v171
	v_mul_f32_e32 v47, 0x4f800000, v46
	v_cmp_gt_f32_e32 vcc, s2, v46
	s_waitcnt vmcnt(0)
	v_pk_add_f32 v[40:41], v[40:41], 1.0 op_sel_hi:[1,0]
	v_pk_add_f32 v[38:39], v[38:39], 1.0 op_sel_hi:[1,0]
	v_pk_fma_f32 v[36:37], v[36:37], v[40:41], v[44:45]
	v_pk_fma_f32 v[34:35], v[34:35], v[38:39], v[42:43]
	v_cvt_pk_bf16_f32 v34, v34, v35
	v_cvt_pk_bf16_f32 v35, v36, v37
	global_store_dwordx2 v[104:105], v[34:35], off offset:1536
	global_load_dwordx4 v[34:37], v[144:145], off
	s_nop 0
	global_load_dwordx4 v[38:41], v[128:129], off
	v_cndmask_b32_e32 v42, v46, v47, vcc
	v_sqrt_f32_e32 v43, v42
	s_waitcnt vmcnt(0) lgkmcnt(0)
	v_pk_add_f32 v[36:37], v[36:37], 1.0 op_sel_hi:[1,0]
	v_add_u32_e32 v44, -1, v43
	v_add_u32_e32 v45, 1, v43
	v_fma_f32 v46, -v44, v43, v42
	v_fma_f32 v47, -v45, v43, v42
	v_cmp_ge_f32_e64 s[6:7], 0, v46
	v_pk_add_f32 v[34:35], v[34:35], 1.0 op_sel_hi:[1,0]
	s_nop 0
	v_cndmask_b32_e64 v43, v43, v44, s[6:7]
	v_cmp_lt_f32_e64 s[6:7], 0, v47
	s_nop 1
	v_cndmask_b32_e64 v43, v43, v45, s[6:7]
	v_mul_f32_e32 v44, 0x37800000, v43
	v_cndmask_b32_e32 v43, v43, v44, vcc
	v_cmp_class_f32_e32 vcc, v42, v172
	s_nop 1
	v_cndmask_b32_e32 v42, v43, v42, vcc
	v_div_scale_f32 v43, s[6:7], v42, v42, 1.0
	v_rcp_f32_e32 v45, v43
	v_div_scale_f32 v44, vcc, 1.0, v42, 1.0
	v_fma_f32 v46, -v43, v45, 1.0
	v_fmac_f32_e32 v45, v46, v45
	v_mul_f32_e32 v46, v44, v45
	v_fma_f32 v47, -v43, v46, v44
	v_fmac_f32_e32 v46, v47, v45
	v_fma_f32 v43, -v43, v46, v44
	v_div_fmas_f32 v43, v43, v45, v46
	v_div_fixup_f32 v42, v43, v42, 1.0
	v_pk_mul_f32 v[32:33], v[32:33], v[42:43] op_sel_hi:[1,0]
	v_pk_mul_f32 v[30:31], v[30:31], v[42:43] op_sel_hi:[1,0]
	v_pk_mul_f32 v[32:33], v[4:5], v[32:33]
	v_pk_mul_f32 v[30:31], v[2:3], v[30:31]
	v_pk_fma_f32 v[32:33], v[36:37], v[32:33], v[40:41]
	v_pk_fma_f32 v[30:31], v[34:35], v[30:31], v[38:39]
	v_cvt_pk_bf16_f32 v30, v30, v31
	v_cvt_pk_bf16_f32 v31, v32, v33
	global_store_dwordx2 v[104:105], v[30:31], off offset:2048
	global_load_dwordx4 v[30:33], v[122:123], off
	s_nop 0
	global_load_dwordx4 v[34:37], v[120:121], off
	v_pk_mul_f32 v[28:29], v[28:29], v[42:43] op_sel_hi:[1,0]
	v_pk_mul_f32 v[26:27], v[26:27], v[42:43] op_sel_hi:[1,0]
	v_pk_mul_f32 v[28:29], v[8:9], v[28:29]
	v_pk_mul_f32 v[26:27], v[6:7], v[26:27]
	v_lshl_add_u64 v[40:41], s[18:19], 0, v[98:99]
	v_lshl_add_u64 v[38:39], s[16:17], 0, v[98:99]
	v_pk_mul_f32 v[24:25], v[24:25], v[42:43] op_sel_hi:[1,0]
	v_pk_mul_f32 v[22:23], v[22:23], v[42:43] op_sel_hi:[1,0]
	v_pk_mul_f32 v[24:25], v[12:13], v[24:25]
	v_pk_mul_f32 v[22:23], v[10:11], v[22:23]
	v_pk_mul_f32 v[20:21], v[20:21], v[42:43] op_sel_hi:[1,0]
	v_pk_mul_f32 v[18:19], v[18:19], v[42:43] op_sel_hi:[1,0]
	v_pk_mul_f32 v[20:21], v[16:17], v[20:21]
	v_pk_mul_f32 v[18:19], v[14:15], v[18:19]
	s_waitcnt vmcnt(0) lgkmcnt(0)
	v_pk_add_f32 v[32:33], v[32:33], 1.0 op_sel_hi:[1,0]
	v_pk_add_f32 v[30:31], v[30:31], 1.0 op_sel_hi:[1,0]
	v_pk_fma_f32 v[28:29], v[32:33], v[28:29], v[36:37]
	v_pk_fma_f32 v[26:27], v[30:31], v[26:27], v[34:35]
	v_cvt_pk_bf16_f32 v26, v26, v27
	v_cvt_pk_bf16_f32 v27, v28, v29
	global_store_dwordx2 v[104:105], v[26:27], off offset:2560
	global_load_dwordx4 v[26:29], v[40:41], off
	s_nop 0
	global_load_dwordx4 v[30:33], v[38:39], off
	v_lshl_add_u64 v[36:37], s[18:19], 0, v[100:101]
	v_lshl_add_u64 v[34:35], s[16:17], 0, v[100:101]
	s_waitcnt vmcnt(0) lgkmcnt(0)
	v_pk_add_f32 v[28:29], v[28:29], 1.0 op_sel_hi:[1,0]
	v_pk_add_f32 v[26:27], v[26:27], 1.0 op_sel_hi:[1,0]
	v_pk_fma_f32 v[24:25], v[28:29], v[24:25], v[32:33]
	v_pk_fma_f32 v[22:23], v[26:27], v[22:23], v[30:31]
	v_cvt_pk_bf16_f32 v22, v22, v23
	v_cvt_pk_bf16_f32 v23, v24, v25
	global_store_dwordx2 v[104:105], v[22:23], off offset:3072
	global_load_dwordx4 v[22:25], v[36:37], off
	s_nop 0
	global_load_dwordx4 v[26:29], v[34:35], off
	s_waitcnt vmcnt(0) lgkmcnt(0)
	v_pk_add_f32 v[24:25], v[24:25], 1.0 op_sel_hi:[1,0]
	v_pk_add_f32 v[22:23], v[22:23], 1.0 op_sel_hi:[1,0]
	v_pk_fma_f32 v[20:21], v[20:21], v[24:25], v[28:29]
	v_pk_fma_f32 v[18:19], v[18:19], v[22:23], v[26:27]
	v_cvt_pk_bf16_f32 v18, v18, v19
	v_cvt_pk_bf16_f32 v19, v20, v21
	global_store_dwordx2 v[104:105], v[18:19], off offset:3584
	s_cbranch_scc1 .LBB0_3086

.LBB0_3194:
	v_lshl_add_u64 v[18:19], s[12:13], 0, v[94:95]
	v_lshl_add_u64 v[22:23], s[12:13], 0, v[92:93]
	v_add_co_u32_e32 v20, vcc, 0x7800000, v18
	v_add_co_u32_e64 v102, s[6:7], s29, v22
	s_nop 0
	v_addc_co_u32_e32 v21, vcc, 0, v19, vcc
	v_addc_co_u32_e64 v103, s[6:7], 0, v23, s[6:7]
	v_add_co_u32_e64 v104, s[6:7], s30, v22
	v_add_co_u32_e32 v22, vcc, 0x7801000, v18
	s_nop 0
	v_addc_co_u32_e64 v105, s[6:7], 0, v23, s[6:7]
	global_load_dwordx4 v[78:81], v[20:21], off
	global_load_dwordx4 v[74:77], v[20:21], off offset:1024
	global_load_dwordx4 v[70:73], v[20:21], off offset:2048
	global_load_dwordx4 v[66:69], v[20:21], off offset:3072
	v_addc_co_u32_e32 v23, vcc, 0, v19, vcc
	v_add_co_u32_e32 v20, vcc, 0x7802000, v18
	global_load_dwordx4 v[62:65], v[22:23], off
	global_load_dwordx4 v[58:61], v[22:23], off offset:1024
	global_load_dwordx4 v[54:57], v[22:23], off offset:2048
	global_load_dwordx4 v[50:53], v[22:23], off offset:3072
	v_addc_co_u32_e32 v21, vcc, 0, v19, vcc
	global_load_dwordx4 v[46:49], v[20:21], off
	global_load_dwordx4 v[42:45], v[20:21], off offset:1024
	global_load_dwordx4 v[38:41], v[20:21], off offset:2048
	global_load_dwordx4 v[34:37], v[20:21], off offset:3072
	v_add_co_u32_e32 v82, vcc, 0x7803000, v18
	s_ashr_i32 s8, s24, 13
	s_nop 0
	v_addc_co_u32_e32 v83, vcc, 0, v19, vcc
	global_load_dwordx4 v[30:33], v[82:83], off
	global_load_dwordx4 v[26:29], v[82:83], off offset:1024
	global_load_dwordx4 v[22:25], v[82:83], off offset:2048
	global_load_dwordx4 v[18:21], v[82:83], off offset:3072
	s_add_i32 s9, s24, 0xffffc002
	s_cmpk_lt_i32 s24, 0x4000
	s_cselect_b32 s6, s8, s9
	s_addk_i32 s6, 0x82
	s_mul_hi_i32 s7, s6, 0x9000
	s_mul_i32 s6, s6, 0x9000
	s_add_u32 s6, s14, s6
	s_addc_u32 s7, s15, s7
	s_add_u32 s10, s6, 0x1000
	s_addc_u32 s11, s7, 0
	v_lshl_add_u64 v[124:125], s[6:7], 0, v[90:91]
	v_lshl_add_u64 v[86:87], s[10:11], 0, v[90:91]
	global_load_dwordx4 v[82:85], v[124:125], off
	s_add_i32 s6, s24, 0xffffc003
	global_load_dwordx4 v[86:89], v[86:87], off
	s_cmpk_lt_i32 s24, 0x3fff
	s_cselect_b32 s6, s8, s6
	s_addk_i32 s6, 0x82
	s_mul_hi_i32 s7, s6, 0x9000
	s_mul_i32 s6, s6, 0x9000
	s_add_u32 s6, s14, s6
	s_addc_u32 s7, s15, s7
	v_lshl_add_u64 v[134:135], s[10:11], 0, v[96:97]
	v_lshl_add_u64 v[130:131], s[10:11], 0, v[98:99]
	v_lshl_add_u64 v[128:129], s[10:11], 0, v[100:101]
	s_add_u32 s10, s6, 0x1000
	v_lshl_add_u64 v[110:111], s[6:7], 0, v[90:91]
	s_addc_u32 s11, s7, 0
	s_add_i32 s6, s24, 0xffffc004
	s_cmpk_lt_i32 s24, 0x3ffe
	s_cselect_b32 s6, s8, s6
	s_addk_i32 s6, 0x82
	s_mul_hi_i32 s7, s6, 0x9000
	s_mul_i32 s6, s6, 0x9000
	v_lshl_add_u64 v[126:127], s[10:11], 0, v[90:91]
	v_lshl_add_u64 v[120:121], s[10:11], 0, v[96:97]
	v_lshl_add_u64 v[116:117], s[10:11], 0, v[98:99]
	v_lshl_add_u64 v[112:113], s[10:11], 0, v[100:101]
	s_add_u32 s10, s14, s6
	s_addc_u32 s11, s15, s7
	s_add_u32 s6, s10, 0x1000
	s_addc_u32 s7, s11, 0
	s_add_i32 s9, s24, 0xffffc005
	s_cmpk_lt_i32 s24, 0x3ffd
	v_lshl_add_u64 v[138:139], s[6:7], 0, v[90:91]
	v_lshl_add_u64 v[136:137], s[6:7], 0, v[96:97]
	v_lshl_add_u64 v[132:133], s[6:7], 0, v[98:99]
	v_lshl_add_u64 v[122:123], s[6:7], 0, v[100:101]
	s_cselect_b32 s6, s8, s9
	s_addk_i32 s6, 0x82
	s_mul_hi_i32 s7, s6, 0x9000
	s_mul_i32 s6, s6, 0x9000
	s_add_u32 s6, s14, s6
	s_addc_u32 s7, s15, s7
	s_add_u32 s40, s6, 0x1000
	v_lshl_add_u64 v[106:107], s[6:7], 0, v[90:91]
	s_addc_u32 s41, s7, 0
	v_lshl_add_u64 v[108:109], s[10:11], 0, v[90:91]
	v_lshl_add_u64 v[118:119], s[40:41], 0, v[90:91]
	v_lshl_add_u64 v[114:115], s[40:41], 0, v[96:97]
	s_add_i32 s24, s24, 32
	v_lshl_add_u64 v[92:93], v[92:93], 0, s[26:27]
	s_waitcnt vmcnt(0) lgkmcnt(0)
	v_pk_mul_f32 v[140:141], v[80:81], v[80:81]
	v_pk_mul_f32 v[142:143], v[78:79], v[78:79]
	v_pk_mul_f32 v[144:145], v[76:77], v[76:77]
	v_pk_mul_f32 v[146:147], v[74:75], v[74:75]
	v_mul_f32_e32 v156, v71, v71
	v_mul_f32_e32 v158, v73, v73
	v_pk_mov_b32 v[160:161], v[142:143], v[140:141] op_sel:[1,0]
	v_mov_b32_e32 v143, v141
	v_pk_mov_b32 v[140:141], v[146:147], v[144:145] op_sel:[1,0]
	v_mov_b32_e32 v147, v145
	v_mul_f32_e32 v169, v68, v68
	v_mul_f32_e32 v171, v69, v69
	v_pk_fma_f32 v[144:145], v[70:71], v[70:71], v[156:157] op_sel_hi:[1,1,0]
	v_pk_fma_f32 v[156:157], v[72:73], v[72:73], v[158:159] op_sel_hi:[1,1,0]
	v_pk_mul_f32 v[158:159], v[64:65], v[64:65]
	v_pk_mul_f32 v[162:163], v[62:63], v[62:63]
	v_pk_mul_f32 v[164:165], v[60:61], v[60:61]
	v_pk_mul_f32 v[166:167], v[58:59], v[58:59]
	v_mul_f32_e32 v168, v55, v55
	v_mul_f32_e32 v170, v57, v57
	v_pk_add_f32 v[142:143], v[160:161], v[142:143]
	v_pk_add_f32 v[140:141], v[140:141], v[146:147]
	v_mul_f32_e32 v155, v66, v66
	v_mul_f32_e32 v179, v67, v67
	v_mov_b32_e32 v145, v169
	v_mov_b32_e32 v157, v171
	v_pk_mov_b32 v[146:147], v[162:163], v[158:159] op_sel:[1,0]
	v_mov_b32_e32 v163, v159
	v_pk_mov_b32 v[158:159], v[166:167], v[164:165] op_sel:[1,0]
	v_mov_b32_e32 v167, v165
	v_pk_fma_f32 v[160:161], v[54:55], v[54:55], v[168:169] op_sel_hi:[1,1,0]
	v_pk_fma_f32 v[164:165], v[56:57], v[56:57], v[170:171] op_sel_hi:[1,1,0]
	v_pk_mul_f32 v[168:169], v[48:49], v[48:49]
	v_pk_mul_f32 v[170:171], v[46:47], v[46:47]
	v_pk_add_f32 v[180:181], v[142:143], v[142:143] op_sel:[0,1] op_sel_hi:[1,0]
	v_pk_add_f32 v[182:183], v[140:141], v[140:141] op_sel:[0,1] op_sel_hi:[1,0]
	v_mul_f32_e32 v177, v52, v52
	v_pk_mul_f32 v[172:173], v[44:45], v[44:45]
	v_pk_mul_f32 v[174:175], v[42:43], v[42:43]
	v_mul_f32_e32 v176, v39, v39
	v_mul_f32_e32 v178, v41, v41
	v_pk_add_f32 v[156:157], v[144:145], v[156:157]
	v_pk_add_f32 v[140:141], v[146:147], v[162:163]
	v_pk_add_f32 v[142:143], v[158:159], v[166:167]
	v_pk_mov_b32 v[144:145], v[170:171], v[168:169] op_sel:[1,0]
	v_mov_b32_e32 v171, v169
	v_mov_b32_e32 v181, v155
	v_mov_b32_e32 v183, v179
	v_mul_f32_e32 v185, v50, v50
	v_mul_f32_e32 v190, v51, v51
	v_mul_f32_e32 v184, v53, v53
	v_mul_f32_e32 v193, v36, v36
	v_mul_f32_e32 v194, v37, v37
	v_pk_mov_b32 v[146:147], v[174:175], v[172:173] op_sel:[1,0]
	v_mov_b32_e32 v175, v173
	v_pk_fma_f32 v[158:159], v[38:39], v[38:39], v[176:177] op_sel_hi:[1,1,0]
	v_pk_fma_f32 v[162:163], v[40:41], v[40:41], v[178:179] op_sel_hi:[1,1,0]
	v_pk_add_f32 v[186:187], v[140:141], v[140:141] op_sel:[0,1] op_sel_hi:[1,0]
	v_pk_add_f32 v[188:189], v[142:143], v[142:143] op_sel:[0,1] op_sel_hi:[1,0]
	v_pk_add_f32 v[144:145], v[144:145], v[170:171]
	v_pk_add_f32 v[170:171], v[180:181], v[182:183]
	v_mov_b32_e32 v161, v177
	v_mov_b32_e32 v165, v184
	v_pk_mul_f32 v[166:167], v[32:33], v[32:33]
	v_pk_mul_f32 v[168:169], v[30:31], v[30:31]
	v_pk_mul_f32 v[172:173], v[28:29], v[28:29]
	v_pk_mul_f32 v[176:177], v[26:27], v[26:27]
	v_pk_add_f32 v[146:147], v[146:147], v[174:175]
	v_mov_b32_e32 v159, v193
	v_mov_b32_e32 v163, v194
	v_mov_b32_e32 v187, v185
	v_mov_b32_e32 v189, v190
	v_pk_add_f32 v[156:157], v[170:171], v[156:157]
	v_mul_f32_e32 v191, v34, v34
	v_mul_f32_e32 v192, v35, v35
	v_pk_add_f32 v[160:161], v[160:161], v[164:165]
	v_pk_mov_b32 v[164:165], v[168:169], v[166:167] op_sel:[1,0]
	v_mov_b32_e32 v169, v167
	v_pk_mov_b32 v[166:167], v[176:177], v[172:173] op_sel:[1,0]
	v_mov_b32_e32 v177, v173
	v_pk_add_f32 v[172:173], v[144:145], v[144:145] op_sel:[0,1] op_sel_hi:[1,0]
	v_pk_add_f32 v[174:175], v[146:147], v[146:147] op_sel:[0,1] op_sel_hi:[1,0]
	v_pk_add_f32 v[158:159], v[158:159], v[162:163]
	v_pk_add_f32 v[162:163], v[186:187], v[188:189]
	v_add_f32_e32 v155, v156, v157
	v_mov_b32_e32 v173, v191
	v_mov_b32_e32 v175, v192
	v_pk_add_f32 v[156:157], v[162:163], v[160:161]
	ds_bpermute_b32 v163, v1, v155
	v_pk_add_f32 v[160:161], v[172:173], v[174:175]
	v_add_f32_e32 v162, v156, v157
	v_pk_add_f32 v[156:157], v[160:161], v[158:159]
	ds_bpermute_b32 v158, v1, v162
	v_add_f32_e32 v156, v156, v157
	ds_bpermute_b32 v157, v1, v156
	s_waitcnt lgkmcnt(2)
	v_add_f32_e32 v155, v155, v163
	ds_bpermute_b32 v159, v148, v155
	s_waitcnt lgkmcnt(2)
	v_add_f32_e32 v158, v162, v158
	ds_bpermute_b32 v160, v148, v158
	s_waitcnt lgkmcnt(2)
	v_add_f32_e32 v156, v156, v157
	ds_bpermute_b32 v157, v148, v156
	s_waitcnt lgkmcnt(2)
	v_add_f32_e32 v155, v155, v159
	ds_bpermute_b32 v159, v149, v155
	s_waitcnt lgkmcnt(2)
	v_add_f32_e32 v158, v158, v160
	ds_bpermute_b32 v160, v149, v158
	s_waitcnt lgkmcnt(2)
	v_add_f32_e32 v156, v156, v157
	ds_bpermute_b32 v157, v149, v156
	s_waitcnt lgkmcnt(2)
	v_add_f32_e32 v155, v155, v159
	ds_bpermute_b32 v159, v150, v155
	s_waitcnt lgkmcnt(2)
	v_add_f32_e32 v158, v158, v160
	ds_bpermute_b32 v160, v150, v158
	s_waitcnt lgkmcnt(2)
	v_add_f32_e32 v156, v156, v157
	ds_bpermute_b32 v157, v150, v156
	s_waitcnt lgkmcnt(2)
	v_add_f32_e32 v155, v155, v159
	ds_bpermute_b32 v159, v151, v155
	s_waitcnt lgkmcnt(2)
	v_add_f32_e32 v158, v158, v160
	ds_bpermute_b32 v160, v151, v158
	s_waitcnt lgkmcnt(2)
	v_add_f32_e32 v156, v156, v157
	ds_bpermute_b32 v157, v151, v156
	s_waitcnt lgkmcnt(2)
	v_add_f32_e32 v155, v155, v159
	ds_bpermute_b32 v159, v152, v155
	s_waitcnt lgkmcnt(2)
	v_add_f32_e32 v158, v158, v160
	ds_bpermute_b32 v160, v152, v158
	s_waitcnt lgkmcnt(2)
	v_add_f32_e32 v156, v156, v157
	ds_bpermute_b32 v157, v152, v156
	s_waitcnt lgkmcnt(2)
	v_add_f32_e32 v155, v155, v159
	v_fmamk_f32 v155, v155, 0x3a800000, v153
	s_waitcnt lgkmcnt(1)
	v_add_f32_e32 v158, v158, v160
	v_mul_f32_e32 v159, 0x4f800000, v155
	v_cmp_gt_f32_e32 vcc, s17, v155
	v_fmamk_f32 v158, v158, 0x3a800000, v153
	s_waitcnt lgkmcnt(0)
	v_add_f32_e32 v156, v156, v157
	v_cndmask_b32_e32 v155, v155, v159, vcc
	v_mul_f32_e32 v157, 0x4f800000, v158
	v_cmp_gt_f32_e64 s[6:7], s17, v158
	v_sqrt_f32_e32 v159, v155
	v_fmamk_f32 v156, v156, 0x3a800000, v153
	v_cndmask_b32_e64 v157, v158, v157, s[6:7]
	v_mul_f32_e32 v158, 0x4f800000, v156
	v_cmp_gt_f32_e64 s[8:9], s17, v156
	v_sqrt_f32_e32 v160, v157
	v_add_u32_e32 v161, -1, v159
	v_cndmask_b32_e64 v156, v156, v158, s[8:9]
	v_sqrt_f32_e32 v158, v156
	v_add_u32_e32 v162, 1, v159
	v_fma_f32 v163, -v161, v159, v155
	v_pk_add_f32 v[144:145], v[164:165], v[168:169]
	v_fma_f32 v164, -v162, v159, v155
	v_add_u32_e32 v165, -1, v160
	v_cmp_ge_f32_e64 s[10:11], 0, v163
	v_pk_add_f32 v[146:147], v[166:167], v[176:177]
	v_add_u32_e32 v166, 1, v160
	v_cndmask_b32_e64 v159, v159, v161, s[10:11]
	v_fma_f32 v161, -v165, v160, v157
	v_cmp_lt_f32_e64 s[10:11], 0, v164
	v_fma_f32 v163, -v166, v160, v157
	v_add_u32_e32 v167, -1, v158
	v_cndmask_b32_e64 v159, v159, v162, s[10:11]
	v_cmp_ge_f32_e64 s[10:11], 0, v161
	v_add_u32_e32 v168, 1, v158
	v_fma_f32 v161, -v167, v158, v156
	v_cndmask_b32_e64 v160, v160, v165, s[10:11]
	v_cmp_lt_f32_e64 s[10:11], 0, v163
	v_fma_f32 v162, -v168, v158, v156
	v_mul_f32_e32 v163, 0x37800000, v159
	v_cndmask_b32_e64 v160, v160, v166, s[10:11]
	v_cmp_ge_f32_e64 s[10:11], 0, v161
	v_cndmask_b32_e32 v159, v159, v163, vcc
	v_cmp_class_f32_e32 vcc, v155, v154
	v_cndmask_b32_e64 v158, v158, v167, s[10:11]
	v_cmp_lt_f32_e64 s[10:11], 0, v162
	v_mul_f32_e32 v161, 0x37800000, v160
	v_cndmask_b32_e32 v155, v159, v155, vcc
	v_cndmask_b32_e64 v158, v158, v168, s[10:11]
	v_cndmask_b32_e64 v159, v160, v161, s[6:7]
	v_cmp_class_f32_e32 vcc, v157, v154
	v_mul_f32_e32 v160, 0x37800000, v158
	v_div_scale_f32 v161, s[6:7], v155, v155, 1.0
	v_cndmask_b32_e32 v157, v159, v157, vcc
	v_cndmask_b32_e64 v158, v158, v160, s[8:9]
	v_cmp_class_f32_e32 vcc, v156, v154
	v_rcp_f32_e32 v159, v161
	v_div_scale_f32 v160, s[8:9], v157, v157, 1.0
	v_cndmask_b32_e32 v158, v158, v156, vcc
	v_rcp_f32_e32 v164, v160
	v_div_scale_f32 v165, s[10:11], v158, v158, 1.0
	v_rcp_f32_e32 v167, v165
	v_fma_f32 v156, -v161, v159, 1.0
	v_div_scale_f32 v162, s[6:7], 1.0, v155, 1.0
	v_fmac_f32_e32 v159, v156, v159
	v_fma_f32 v156, -v160, v164, 1.0
	v_mul_f32_e32 v168, v162, v159
	v_div_scale_f32 v163, s[8:9], 1.0, v157, 1.0
	v_fmac_f32_e32 v164, v156, v164
	v_fma_f32 v156, -v165, v167, 1.0
	v_fma_f32 v169, -v161, v168, v162
	v_div_scale_f32 v166, s[10:11], 1.0, v158, 1.0
	v_mul_f32_e32 v170, v163, v164
	v_fmac_f32_e32 v167, v156, v167
	v_fmac_f32_e32 v168, v169, v159
	v_fma_f32 v156, -v160, v170, v163
	v_mul_f32_e32 v169, v166, v167
	v_fma_f32 v161, -v161, v168, v162
	s_mov_b64 vcc, s[6:7]
	v_fmac_f32_e32 v170, v156, v164
	v_fma_f32 v156, -v165, v169, v166
	v_div_fmas_f32 v159, v161, v159, v168
	v_fma_f32 v160, -v160, v170, v163
	v_fmac_f32_e32 v169, v156, v167
	v_div_fixup_f32 v156, v159, v155, 1.0
	s_mov_b64 vcc, s[8:9]
	v_div_fmas_f32 v155, v160, v164, v170
	v_fma_f32 v159, -v165, v169, v166
	v_pk_mul_f32 v[80:81], v[80:81], v[156:157] op_sel_hi:[1,0]
	v_pk_mul_f32 v[78:79], v[78:79], v[156:157] op_sel_hi:[1,0]
	s_mov_b64 vcc, s[10:11]
	v_pk_add_f32 v[88:89], v[88:89], 1.0 op_sel_hi:[1,0]
	v_pk_add_f32 v[86:87], v[86:87], 1.0 op_sel_hi:[1,0]
	v_pk_mul_f32 v[76:77], v[76:77], v[156:157] op_sel_hi:[1,0]
	v_pk_mul_f32 v[74:75], v[74:75], v[156:157] op_sel_hi:[1,0]
	v_pk_mul_f32 v[72:73], v[72:73], v[156:157] op_sel_hi:[1,0]
	v_pk_mul_f32 v[70:71], v[70:71], v[156:157] op_sel_hi:[1,0]
	v_pk_mul_f32 v[68:69], v[68:69], v[156:157] op_sel_hi:[1,0]
	v_pk_mul_f32 v[66:67], v[66:67], v[156:157] op_sel_hi:[1,0]
	v_div_fixup_f32 v156, v155, v157, 1.0
	v_div_fmas_f32 v155, v159, v167, v169
	v_pk_mul_f32 v[78:79], v[78:79], v[2:3]
	v_pk_mul_f32 v[80:81], v[80:81], v[4:5]
	v_pk_mul_f32 v[64:65], v[64:65], v[156:157] op_sel_hi:[1,0]
	v_pk_mul_f32 v[62:63], v[62:63], v[156:157] op_sel_hi:[1,0]
	v_pk_mul_f32 v[60:61], v[60:61], v[156:157] op_sel_hi:[1,0]
	v_pk_mul_f32 v[58:59], v[58:59], v[156:157] op_sel_hi:[1,0]
	v_pk_mul_f32 v[56:57], v[56:57], v[156:157] op_sel_hi:[1,0]
	v_pk_mul_f32 v[54:55], v[54:55], v[156:157] op_sel_hi:[1,0]
	v_pk_mul_f32 v[52:53], v[52:53], v[156:157] op_sel_hi:[1,0]
	v_pk_mul_f32 v[156:157], v[50:51], v[156:157] op_sel_hi:[1,0]
	v_div_fixup_f32 v50, v155, v158, 1.0
	v_pk_fma_f32 v[80:81], v[80:81], v[88:89], v[84:85]
	v_pk_fma_f32 v[78:79], v[78:79], v[86:87], v[82:83]
	v_pk_mul_f32 v[86:87], v[52:53], v[16:17]
	v_pk_mul_f32 v[48:49], v[48:49], v[50:51] op_sel_hi:[1,0]
	v_pk_mul_f32 v[46:47], v[46:47], v[50:51] op_sel_hi:[1,0]
	v_pk_mul_f32 v[82:83], v[54:55], v[10:11]
	v_pk_mul_f32 v[84:85], v[156:157], v[14:15]
	v_pk_mul_f32 v[88:89], v[46:47], v[2:3]
	v_pk_mul_f32 v[156:157], v[48:49], v[4:5]
	v_cvt_pk_bf16_f32 v46, v78, v79
	v_cvt_pk_bf16_f32 v47, v80, v81
	global_store_dwordx2 v[102:103], v[46:47], off
	global_load_dwordx4 v[46:49], v[134:135], off
	s_nop 0
	global_load_dwordx4 v[52:55], v[124:125], off offset:1024
	v_pk_mul_f32 v[74:75], v[74:75], v[6:7]
	v_pk_mul_f32 v[76:77], v[76:77], v[8:9]
	v_pk_mul_f32 v[70:71], v[70:71], v[10:11]
	v_pk_mul_f32 v[72:73], v[72:73], v[12:13]
	v_pk_mul_f32 v[66:67], v[66:67], v[14:15]
	v_pk_mul_f32 v[68:69], v[68:69], v[16:17]
	v_pk_mul_f32 v[62:63], v[62:63], v[2:3]
	v_pk_mul_f32 v[64:65], v[64:65], v[4:5]
	v_pk_mul_f32 v[58:59], v[58:59], v[6:7]
	v_pk_mul_f32 v[60:61], v[60:61], v[8:9]
	v_pk_mul_f32 v[56:57], v[56:57], v[12:13]
	v_mul_f32_e32 v178, v23, v23
	v_mul_f32_e32 v184, v25, v25
	v_mul_f32_e32 v195, v18, v18
	v_mul_f32_e32 v196, v19, v19
	v_mul_f32_e32 v197, v20, v20
	v_mul_f32_e32 v198, v21, v21
	v_pk_fma_f32 v[140:141], v[22:23], v[22:23], v[178:179] op_sel_hi:[1,1,0]
	v_pk_fma_f32 v[142:143], v[24:25], v[24:25], v[184:185] op_sel_hi:[1,1,0]
	v_mov_b32_e32 v141, v197
	v_mov_b32_e32 v143, v198
	v_lshl_add_u64 v[94:95], v[94:95], 0, s[38:39]
	s_cmp_lt_i32 s24, s5
	s_waitcnt vmcnt(0) lgkmcnt(0)
	v_pk_add_f32 v[48:49], v[48:49], 1.0 op_sel_hi:[1,0]
	v_pk_add_f32 v[46:47], v[46:47], 1.0 op_sel_hi:[1,0]
	v_pk_fma_f32 v[48:49], v[76:77], v[48:49], v[54:55]
	v_pk_fma_f32 v[46:47], v[74:75], v[46:47], v[52:53]
	v_cvt_pk_bf16_f32 v46, v46, v47
	v_cvt_pk_bf16_f32 v47, v48, v49
	global_store_dwordx2 v[102:103], v[46:47], off offset:512
	global_load_dwordx4 v[46:49], v[130:131], off
	s_nop 0
	global_load_dwordx4 v[52:55], v[124:125], off offset:2048
	s_waitcnt vmcnt(0) lgkmcnt(0)
	v_pk_add_f32 v[48:49], v[48:49], 1.0 op_sel_hi:[1,0]
	v_pk_add_f32 v[46:47], v[46:47], 1.0 op_sel_hi:[1,0]
	v_pk_fma_f32 v[48:49], v[72:73], v[48:49], v[54:55]
	v_pk_fma_f32 v[46:47], v[70:71], v[46:47], v[52:53]
	v_cvt_pk_bf16_f32 v46, v46, v47
	v_cvt_pk_bf16_f32 v47, v48, v49
	global_store_dwordx2 v[102:103], v[46:47], off offset:1024
	global_load_dwordx4 v[46:49], v[128:129], off
	s_nop 0
	global_load_dwordx4 v[52:55], v[124:125], off offset:3072
	s_waitcnt vmcnt(0) lgkmcnt(0)
	v_pk_add_f32 v[48:49], v[48:49], 1.0 op_sel_hi:[1,0]
	v_pk_add_f32 v[46:47], v[46:47], 1.0 op_sel_hi:[1,0]
	v_pk_fma_f32 v[48:49], v[68:69], v[48:49], v[54:55]
	v_pk_fma_f32 v[46:47], v[66:67], v[46:47], v[52:53]
	v_cvt_pk_bf16_f32 v46, v46, v47
	v_cvt_pk_bf16_f32 v47, v48, v49
	global_store_dwordx2 v[102:103], v[46:47], off offset:1536
	global_load_dwordx4 v[46:49], v[126:127], off
	s_nop 0
	global_load_dwordx4 v[52:55], v[110:111], off
	s_waitcnt vmcnt(0) lgkmcnt(0)
	v_pk_add_f32 v[48:49], v[48:49], 1.0 op_sel_hi:[1,0]
	v_pk_add_f32 v[46:47], v[46:47], 1.0 op_sel_hi:[1,0]
	v_pk_fma_f32 v[48:49], v[64:65], v[48:49], v[54:55]
	v_pk_fma_f32 v[46:47], v[62:63], v[46:47], v[52:53]
	v_cvt_pk_bf16_f32 v46, v46, v47
	v_cvt_pk_bf16_f32 v47, v48, v49
	global_store_dwordx2 v[102:103], v[46:47], off offset:2048
	global_load_dwordx4 v[46:49], v[120:121], off
	s_nop 0
	global_load_dwordx4 v[52:55], v[110:111], off offset:1024
	s_waitcnt vmcnt(0) lgkmcnt(0)
	v_pk_add_f32 v[48:49], v[48:49], 1.0 op_sel_hi:[1,0]
	v_pk_add_f32 v[46:47], v[46:47], 1.0 op_sel_hi:[1,0]
	v_pk_fma_f32 v[48:49], v[60:61], v[48:49], v[54:55]
	v_pk_fma_f32 v[46:47], v[58:59], v[46:47], v[52:53]
	v_cvt_pk_bf16_f32 v46, v46, v47
	v_cvt_pk_bf16_f32 v47, v48, v49
	global_store_dwordx2 v[102:103], v[46:47], off offset:2560
	global_load_dwordx4 v[46:49], v[116:117], off
	s_nop 0
	global_load_dwordx4 v[52:55], v[110:111], off offset:2048
	v_pk_add_f32 v[58:59], v[146:147], v[146:147] op_sel:[0,1] op_sel_hi:[1,0]
	v_pk_add_f32 v[60:61], v[140:141], v[142:143]
	v_mov_b32_e32 v59, v196
	s_waitcnt vmcnt(0) lgkmcnt(0)
	v_pk_add_f32 v[48:49], v[48:49], 1.0 op_sel_hi:[1,0]
	v_pk_add_f32 v[46:47], v[46:47], 1.0 op_sel_hi:[1,0]
	v_pk_fma_f32 v[48:49], v[56:57], v[48:49], v[54:55]
	v_pk_fma_f32 v[46:47], v[82:83], v[46:47], v[52:53]
	v_cvt_pk_bf16_f32 v46, v46, v47
	v_cvt_pk_bf16_f32 v47, v48, v49
	global_store_dwordx2 v[102:103], v[46:47], off offset:3072
	global_load_dwordx4 v[46:49], v[112:113], off
	s_nop 0
	global_load_dwordx4 v[52:55], v[110:111], off offset:3072
	v_pk_add_f32 v[56:57], v[144:145], v[144:145] op_sel:[0,1] op_sel_hi:[1,0]
	s_waitcnt vmcnt(0) lgkmcnt(0)
	v_pk_add_f32 v[48:49], v[48:49], 1.0 op_sel_hi:[1,0]
	v_pk_add_f32 v[46:47], v[46:47], 1.0 op_sel_hi:[1,0]
	v_pk_fma_f32 v[48:49], v[86:87], v[48:49], v[54:55]
	v_pk_fma_f32 v[46:47], v[84:85], v[46:47], v[52:53]
	v_cvt_pk_bf16_f32 v46, v46, v47
	v_cvt_pk_bf16_f32 v47, v48, v49
	global_store_dwordx2 v[102:103], v[46:47], off offset:3584
	global_load_dwordx4 v[46:49], v[138:139], off
	s_nop 0
	global_load_dwordx4 v[52:55], v[108:109], off
	v_mov_b32_e32 v57, v195
	s_waitcnt vmcnt(0) lgkmcnt(0)
	v_pk_add_f32 v[48:49], v[48:49], 1.0 op_sel_hi:[1,0]
	v_pk_add_f32 v[46:47], v[46:47], 1.0 op_sel_hi:[1,0]
	v_pk_fma_f32 v[48:49], v[156:157], v[48:49], v[54:55]
	v_pk_fma_f32 v[46:47], v[88:89], v[46:47], v[52:53]
	v_bfe_u32 v51, v46, 16, 1
	v_bfe_u32 v52, v47, 16, 1
	v_add3_u32 v46, v46, v51, s25
	v_add3_u32 v47, v47, v52, s25
	v_lshrrev_b32_e32 v46, 16, v46
	v_and_or_b32 v46, v47, s28, v46
	v_cvt_pk_bf16_f32 v47, v48, v49
	global_store_dwordx2 v[104:105], v[46:47], off
	global_load_dwordx4 v[46:49], v[136:137], off
	s_nop 0
	global_load_dwordx4 v[52:55], v[108:109], off offset:1024
	v_pk_mul_f32 v[44:45], v[44:45], v[50:51] op_sel_hi:[1,0]
	v_pk_mul_f32 v[42:43], v[42:43], v[50:51] op_sel_hi:[1,0]
	v_pk_mul_f32 v[44:45], v[44:45], v[8:9]
	v_pk_mul_f32 v[42:43], v[42:43], v[6:7]
	s_waitcnt vmcnt(0) lgkmcnt(0)
	v_pk_add_f32 v[48:49], v[48:49], 1.0 op_sel_hi:[1,0]
	v_pk_add_f32 v[46:47], v[46:47], 1.0 op_sel_hi:[1,0]
	v_pk_fma_f32 v[44:45], v[44:45], v[48:49], v[54:55]
	v_pk_fma_f32 v[42:43], v[42:43], v[46:47], v[52:53]
	v_cvt_pk_bf16_f32 v42, v42, v43
	v_cvt_pk_bf16_f32 v43, v44, v45
	global_store_dwordx2 v[104:105], v[42:43], off offset:512
	global_load_dwordx4 v[42:45], v[132:133], off
	s_nop 0
	global_load_dwordx4 v[46:49], v[108:109], off offset:2048
	v_pk_add_f32 v[52:53], v[56:57], v[58:59]
	s_waitcnt vmcnt(0) lgkmcnt(0)
	v_pk_add_f32 v[44:45], v[44:45], 1.0 op_sel_hi:[1,0]
	v_pk_add_f32 v[52:53], v[52:53], v[60:61]
	v_pk_add_f32 v[42:43], v[42:43], 1.0 op_sel_hi:[1,0]
	v_add_f32_e32 v51, v52, v53
	ds_bpermute_b32 v52, v1, v51
	s_waitcnt lgkmcnt(0)
	v_add_f32_e32 v51, v51, v52
	ds_bpermute_b32 v52, v148, v51
	s_waitcnt lgkmcnt(0)
	v_add_f32_e32 v51, v51, v52
	v_pk_mul_f32 v[40:41], v[40:41], v[50:51] op_sel_hi:[1,0]
	v_pk_mul_f32 v[38:39], v[38:39], v[50:51] op_sel_hi:[1,0]
	v_pk_mul_f32 v[40:41], v[40:41], v[12:13]
	v_pk_mul_f32 v[38:39], v[38:39], v[10:11]
	v_pk_fma_f32 v[40:41], v[40:41], v[44:45], v[48:49]
	v_pk_fma_f32 v[38:39], v[38:39], v[42:43], v[46:47]
	v_cvt_pk_bf16_f32 v38, v38, v39
	v_cvt_pk_bf16_f32 v39, v40, v41
	global_store_dwordx2 v[104:105], v[38:39], off offset:1024
	global_load_dwordx4 v[38:41], v[122:123], off
	s_nop 0
	global_load_dwordx4 v[42:45], v[108:109], off offset:3072
	v_pk_mul_f32 v[36:37], v[36:37], v[50:51] op_sel_hi:[1,0]
	v_pk_mul_f32 v[34:35], v[34:35], v[50:51] op_sel_hi:[1,0]
	v_pk_mul_f32 v[36:37], v[36:37], v[16:17]
	v_pk_mul_f32 v[34:35], v[34:35], v[14:15]
	ds_bpermute_b32 v46, v149, v51
	s_waitcnt lgkmcnt(0)
	v_add_f32_e32 v46, v51, v46
	ds_bpermute_b32 v47, v150, v46
	s_waitcnt lgkmcnt(0)
	v_add_f32_e32 v46, v46, v47
	ds_bpermute_b32 v47, v151, v46
	s_waitcnt lgkmcnt(0)
	v_add_f32_e32 v46, v46, v47
	ds_bpermute_b32 v47, v152, v46
	s_waitcnt lgkmcnt(0)
	v_add_f32_e32 v46, v46, v47
	v_fmamk_f32 v46, v46, 0x3a800000, v153
	v_mul_f32_e32 v47, 0x4f800000, v46
	v_cmp_gt_f32_e32 vcc, s17, v46
	s_waitcnt vmcnt(0)
	v_pk_add_f32 v[40:41], v[40:41], 1.0 op_sel_hi:[1,0]
	v_pk_add_f32 v[38:39], v[38:39], 1.0 op_sel_hi:[1,0]
	v_pk_fma_f32 v[36:37], v[36:37], v[40:41], v[44:45]
	v_pk_fma_f32 v[34:35], v[34:35], v[38:39], v[42:43]
	v_cvt_pk_bf16_f32 v34, v34, v35
	v_cvt_pk_bf16_f32 v35, v36, v37
	global_store_dwordx2 v[104:105], v[34:35], off offset:1536
	global_load_dwordx4 v[34:37], v[118:119], off
	s_nop 0
	global_load_dwordx4 v[38:41], v[106:107], off
	v_cndmask_b32_e32 v42, v46, v47, vcc
	v_sqrt_f32_e32 v43, v42
	s_waitcnt vmcnt(0) lgkmcnt(0)
	v_pk_add_f32 v[36:37], v[36:37], 1.0 op_sel_hi:[1,0]
	v_add_u32_e32 v44, -1, v43
	v_add_u32_e32 v45, 1, v43
	v_fma_f32 v46, -v44, v43, v42
	v_fma_f32 v47, -v45, v43, v42
	v_cmp_ge_f32_e64 s[6:7], 0, v46
	v_pk_add_f32 v[34:35], v[34:35], 1.0 op_sel_hi:[1,0]
	s_nop 0
	v_cndmask_b32_e64 v43, v43, v44, s[6:7]
	v_cmp_lt_f32_e64 s[6:7], 0, v47
	s_nop 1
	v_cndmask_b32_e64 v43, v43, v45, s[6:7]
	v_mul_f32_e32 v44, 0x37800000, v43
	v_cndmask_b32_e32 v43, v43, v44, vcc
	v_cmp_class_f32_e32 vcc, v42, v154
	s_nop 1
	v_cndmask_b32_e32 v42, v43, v42, vcc
	v_div_scale_f32 v43, s[6:7], v42, v42, 1.0
	v_rcp_f32_e32 v45, v43
	v_div_scale_f32 v44, vcc, 1.0, v42, 1.0
	v_fma_f32 v46, -v43, v45, 1.0
	v_fmac_f32_e32 v45, v46, v45
	v_mul_f32_e32 v46, v44, v45
	v_fma_f32 v47, -v43, v46, v44
	v_fmac_f32_e32 v46, v47, v45
	v_fma_f32 v43, -v43, v46, v44
	v_div_fmas_f32 v43, v43, v45, v46
	v_div_fixup_f32 v42, v43, v42, 1.0
	v_pk_mul_f32 v[32:33], v[32:33], v[42:43] op_sel_hi:[1,0]
	v_pk_mul_f32 v[30:31], v[30:31], v[42:43] op_sel_hi:[1,0]
	v_pk_mul_f32 v[32:33], v[32:33], v[4:5]
	v_pk_mul_f32 v[30:31], v[30:31], v[2:3]
	v_pk_fma_f32 v[32:33], v[32:33], v[36:37], v[40:41]
	v_pk_fma_f32 v[30:31], v[30:31], v[34:35], v[38:39]
	v_cvt_pk_bf16_f32 v30, v30, v31
	v_cvt_pk_bf16_f32 v31, v32, v33
	global_store_dwordx2 v[104:105], v[30:31], off offset:2048
	global_load_dwordx4 v[30:33], v[114:115], off
	s_nop 0
	global_load_dwordx4 v[34:37], v[106:107], off offset:1024
	v_pk_mul_f32 v[28:29], v[28:29], v[42:43] op_sel_hi:[1,0]
	v_pk_mul_f32 v[26:27], v[26:27], v[42:43] op_sel_hi:[1,0]
	v_pk_mul_f32 v[28:29], v[28:29], v[8:9]
	v_pk_mul_f32 v[26:27], v[26:27], v[6:7]
	v_lshl_add_u64 v[38:39], s[40:41], 0, v[98:99]
	v_pk_mul_f32 v[24:25], v[24:25], v[42:43] op_sel_hi:[1,0]
	v_pk_mul_f32 v[22:23], v[22:23], v[42:43] op_sel_hi:[1,0]
	v_pk_mul_f32 v[24:25], v[24:25], v[12:13]
	v_pk_mul_f32 v[22:23], v[22:23], v[10:11]
	v_pk_mul_f32 v[20:21], v[20:21], v[42:43] op_sel_hi:[1,0]
	v_pk_mul_f32 v[18:19], v[18:19], v[42:43] op_sel_hi:[1,0]
	v_pk_mul_f32 v[20:21], v[20:21], v[16:17]
	v_pk_mul_f32 v[18:19], v[18:19], v[14:15]
	s_waitcnt vmcnt(0) lgkmcnt(0)
	v_pk_add_f32 v[32:33], v[32:33], 1.0 op_sel_hi:[1,0]
	v_pk_add_f32 v[30:31], v[30:31], 1.0 op_sel_hi:[1,0]
	v_pk_fma_f32 v[28:29], v[28:29], v[32:33], v[36:37]
	v_pk_fma_f32 v[26:27], v[26:27], v[30:31], v[34:35]
	v_cvt_pk_bf16_f32 v26, v26, v27
	v_cvt_pk_bf16_f32 v27, v28, v29
	global_store_dwordx2 v[104:105], v[26:27], off offset:2560
	global_load_dwordx4 v[26:29], v[38:39], off
	s_nop 0
	global_load_dwordx4 v[30:33], v[106:107], off offset:2048
	v_lshl_add_u64 v[34:35], s[40:41], 0, v[100:101]
	s_waitcnt vmcnt(0) lgkmcnt(0)
	v_pk_add_f32 v[28:29], v[28:29], 1.0 op_sel_hi:[1,0]
	v_pk_add_f32 v[26:27], v[26:27], 1.0 op_sel_hi:[1,0]
	v_pk_fma_f32 v[24:25], v[24:25], v[28:29], v[32:33]
	v_pk_fma_f32 v[22:23], v[22:23], v[26:27], v[30:31]
	v_cvt_pk_bf16_f32 v22, v22, v23
	v_cvt_pk_bf16_f32 v23, v24, v25
	global_store_dwordx2 v[104:105], v[22:23], off offset:3072
	global_load_dwordx4 v[22:25], v[34:35], off
	s_nop 0
	global_load_dwordx4 v[26:29], v[106:107], off offset:3072
	s_waitcnt vmcnt(0) lgkmcnt(0)
	v_pk_add_f32 v[24:25], v[24:25], 1.0 op_sel_hi:[1,0]
	v_pk_add_f32 v[22:23], v[22:23], 1.0 op_sel_hi:[1,0]
	v_pk_fma_f32 v[20:21], v[20:21], v[24:25], v[28:29]
	v_pk_fma_f32 v[18:19], v[18:19], v[22:23], v[26:27]
	v_cvt_pk_bf16_f32 v18, v18, v19
	v_cvt_pk_bf16_f32 v19, v20, v21
	global_store_dwordx2 v[104:105], v[18:19], off offset:3584
	s_cbranch_scc1 .LBB0_3194

.LBB0_3341:
	v_lshl_add_u64 v[18:19], s[12:13], 0, v[94:95]
	v_lshl_add_u64 v[22:23], s[12:13], 0, v[92:93]
	v_add_co_u32_e32 v20, vcc, 0x7800000, v18
	v_add_co_u32_e64 v102, s[6:7], s28, v22
	s_nop 0
	v_addc_co_u32_e32 v21, vcc, 0, v19, vcc
	v_addc_co_u32_e64 v103, s[6:7], 0, v23, s[6:7]
	v_add_co_u32_e64 v104, s[6:7], s29, v22
	v_add_co_u32_e32 v22, vcc, 0x7801000, v18
	s_nop 0
	v_addc_co_u32_e64 v105, s[6:7], 0, v23, s[6:7]
	global_load_dwordx4 v[78:81], v[20:21], off
	global_load_dwordx4 v[74:77], v[20:21], off offset:1024
	global_load_dwordx4 v[70:73], v[20:21], off offset:2048
	global_load_dwordx4 v[66:69], v[20:21], off offset:3072
	v_addc_co_u32_e32 v23, vcc, 0, v19, vcc
	v_add_co_u32_e32 v20, vcc, 0x7802000, v18
	global_load_dwordx4 v[62:65], v[22:23], off
	global_load_dwordx4 v[58:61], v[22:23], off offset:1024
	global_load_dwordx4 v[54:57], v[22:23], off offset:2048
	global_load_dwordx4 v[50:53], v[22:23], off offset:3072
	v_addc_co_u32_e32 v21, vcc, 0, v19, vcc
	v_add_co_u32_e32 v82, vcc, 0x7803000, v18
	global_load_dwordx4 v[46:49], v[20:21], off
	global_load_dwordx4 v[42:45], v[20:21], off offset:1024
	global_load_dwordx4 v[38:41], v[20:21], off offset:2048
	global_load_dwordx4 v[34:37], v[20:21], off offset:3072
	v_addc_co_u32_e32 v83, vcc, 0, v19, vcc
	global_load_dwordx4 v[30:33], v[82:83], off
	global_load_dwordx4 v[26:29], v[82:83], off offset:1024
	global_load_dwordx4 v[22:25], v[82:83], off offset:2048
	global_load_dwordx4 v[18:21], v[82:83], off offset:3072
	s_add_i32 s30, s8, 32
	s_add_i32 s10, s8, 0xffffc022
	s_ashr_i32 s9, s30, 13
	s_cmpk_lt_i32 s30, 0x4000
	s_cselect_b32 s6, s9, s10
	s_addk_i32 s6, 0x82
	s_mul_hi_i32 s7, s6, 0x9000
	s_mul_i32 s6, s6, 0x9000
	s_add_u32 s6, s14, s6
	s_addc_u32 s7, s15, s7
	s_add_u32 s10, s6, 0x1000
	s_addc_u32 s11, s7, 0
	v_lshl_add_u64 v[124:125], s[6:7], 0, v[90:91]
	v_lshl_add_u64 v[86:87], s[10:11], 0, v[90:91]
	global_load_dwordx4 v[82:85], v[124:125], off
	s_add_i32 s6, s8, 0xffffc023
	global_load_dwordx4 v[86:89], v[86:87], off
	s_cmpk_lt_i32 s30, 0x3fff
	s_cselect_b32 s6, s9, s6
	s_addk_i32 s6, 0x82
	s_mul_hi_i32 s7, s6, 0x9000
	s_mul_i32 s6, s6, 0x9000
	s_add_u32 s6, s14, s6
	s_addc_u32 s7, s15, s7
	v_lshl_add_u64 v[134:135], s[10:11], 0, v[96:97]
	v_lshl_add_u64 v[130:131], s[10:11], 0, v[98:99]
	v_lshl_add_u64 v[128:129], s[10:11], 0, v[100:101]
	s_add_u32 s10, s6, 0x1000
	v_lshl_add_u64 v[110:111], s[6:7], 0, v[90:91]
	s_addc_u32 s11, s7, 0
	s_add_i32 s6, s8, 0xffffc024
	s_cmpk_lt_i32 s30, 0x3ffe
	s_cselect_b32 s6, s9, s6
	s_addk_i32 s6, 0x82
	s_mul_hi_i32 s7, s6, 0x9000
	s_mul_i32 s6, s6, 0x9000
	v_lshl_add_u64 v[126:127], s[10:11], 0, v[90:91]
	v_lshl_add_u64 v[120:121], s[10:11], 0, v[96:97]
	v_lshl_add_u64 v[116:117], s[10:11], 0, v[98:99]
	v_lshl_add_u64 v[112:113], s[10:11], 0, v[100:101]
	s_add_u32 s10, s14, s6
	s_addc_u32 s11, s15, s7
	s_add_u32 s6, s10, 0x1000
	s_addc_u32 s7, s11, 0
	s_addk_i32 s8, 0xc025
	s_cmpk_lt_i32 s30, 0x3ffd
	v_lshl_add_u64 v[138:139], s[6:7], 0, v[90:91]
	v_lshl_add_u64 v[136:137], s[6:7], 0, v[96:97]
	v_lshl_add_u64 v[132:133], s[6:7], 0, v[98:99]
	v_lshl_add_u64 v[122:123], s[6:7], 0, v[100:101]
	s_cselect_b32 s6, s9, s8
	s_addk_i32 s6, 0x82
	s_mul_hi_i32 s7, s6, 0x9000
	s_mul_i32 s6, s6, 0x9000
	s_add_u32 s6, s14, s6
	s_addc_u32 s7, s15, s7
	s_add_u32 s22, s6, 0x1000
	v_lshl_add_u64 v[106:107], s[6:7], 0, v[90:91]
	s_addc_u32 s23, s7, 0
	v_lshl_add_u64 v[108:109], s[10:11], 0, v[90:91]
	v_lshl_add_u64 v[118:119], s[22:23], 0, v[90:91]
	v_lshl_add_u64 v[114:115], s[22:23], 0, v[96:97]
	v_lshl_add_u64 v[92:93], v[92:93], 0, s[16:17]
	s_waitcnt vmcnt(0) lgkmcnt(0)
	v_pk_mul_f32 v[140:141], v[80:81], v[80:81]
	v_pk_mul_f32 v[142:143], v[78:79], v[78:79]
	v_pk_mul_f32 v[144:145], v[76:77], v[76:77]
	v_pk_mul_f32 v[146:147], v[74:75], v[74:75]
	v_mul_f32_e32 v156, v71, v71
	v_mul_f32_e32 v158, v73, v73
	v_mul_f32_e32 v169, v68, v68
	v_mul_f32_e32 v171, v69, v69
	v_pk_mov_b32 v[160:161], v[142:143], v[140:141] op_sel:[1,0]
	v_mov_b32_e32 v143, v141
	v_pk_mov_b32 v[140:141], v[146:147], v[144:145] op_sel:[1,0]
	v_mov_b32_e32 v147, v145
	v_pk_fma_f32 v[144:145], v[70:71], v[70:71], v[156:157] op_sel_hi:[1,1,0]
	v_pk_fma_f32 v[156:157], v[72:73], v[72:73], v[158:159] op_sel_hi:[1,1,0]
	v_pk_mul_f32 v[158:159], v[64:65], v[64:65]
	v_pk_mul_f32 v[162:163], v[62:63], v[62:63]
	v_pk_mul_f32 v[164:165], v[60:61], v[60:61]
	v_pk_mul_f32 v[166:167], v[58:59], v[58:59]
	v_mul_f32_e32 v168, v55, v55
	v_mul_f32_e32 v170, v57, v57
	v_pk_add_f32 v[142:143], v[160:161], v[142:143]
	v_pk_add_f32 v[140:141], v[140:141], v[146:147]
	v_mov_b32_e32 v145, v169
	v_mov_b32_e32 v157, v171
	v_pk_mov_b32 v[146:147], v[162:163], v[158:159] op_sel:[1,0]
	v_mov_b32_e32 v163, v159
	v_pk_mov_b32 v[158:159], v[166:167], v[164:165] op_sel:[1,0]
	v_mov_b32_e32 v167, v165
	v_pk_fma_f32 v[160:161], v[54:55], v[54:55], v[168:169] op_sel_hi:[1,1,0]
	v_pk_fma_f32 v[164:165], v[56:57], v[56:57], v[170:171] op_sel_hi:[1,1,0]
	v_pk_mul_f32 v[168:169], v[48:49], v[48:49]
	v_pk_mul_f32 v[170:171], v[46:47], v[46:47]
	v_pk_mul_f32 v[172:173], v[44:45], v[44:45]
	v_pk_mul_f32 v[174:175], v[42:43], v[42:43]
	v_mul_f32_e32 v155, v66, v66
	v_mul_f32_e32 v179, v67, v67
	v_mul_f32_e32 v177, v52, v52
	v_mul_f32_e32 v184, v53, v53
	v_mul_f32_e32 v176, v39, v39
	v_mul_f32_e32 v178, v41, v41
	v_pk_add_f32 v[180:181], v[142:143], v[142:143] op_sel:[0,1] op_sel_hi:[1,0]
	v_pk_add_f32 v[182:183], v[140:141], v[140:141] op_sel:[0,1] op_sel_hi:[1,0]
	v_pk_add_f32 v[156:157], v[144:145], v[156:157]
	v_pk_add_f32 v[140:141], v[146:147], v[162:163]
	v_pk_add_f32 v[142:143], v[158:159], v[166:167]
	v_pk_mov_b32 v[144:145], v[170:171], v[168:169] op_sel:[1,0]
	v_mov_b32_e32 v171, v169
	v_pk_mov_b32 v[146:147], v[174:175], v[172:173] op_sel:[1,0]
	v_mov_b32_e32 v175, v173
	v_mul_f32_e32 v185, v50, v50
	v_mul_f32_e32 v190, v51, v51
	v_mul_f32_e32 v193, v36, v36
	v_mul_f32_e32 v194, v37, v37
	v_mov_b32_e32 v161, v177
	v_mov_b32_e32 v165, v184
	v_pk_fma_f32 v[158:159], v[38:39], v[38:39], v[176:177] op_sel_hi:[1,1,0]
	v_pk_fma_f32 v[162:163], v[40:41], v[40:41], v[178:179] op_sel_hi:[1,1,0]
	v_pk_mul_f32 v[166:167], v[32:33], v[32:33]
	v_pk_mul_f32 v[168:169], v[30:31], v[30:31]
	v_pk_mul_f32 v[172:173], v[28:29], v[28:29]
	v_pk_mul_f32 v[176:177], v[26:27], v[26:27]
	v_mov_b32_e32 v181, v155
	v_mov_b32_e32 v183, v179
	v_pk_add_f32 v[186:187], v[140:141], v[140:141] op_sel:[0,1] op_sel_hi:[1,0]
	v_pk_add_f32 v[188:189], v[142:143], v[142:143] op_sel:[0,1] op_sel_hi:[1,0]
	v_pk_add_f32 v[144:145], v[144:145], v[170:171]
	v_pk_add_f32 v[146:147], v[146:147], v[174:175]
	v_mul_f32_e32 v191, v34, v34
	v_mul_f32_e32 v192, v35, v35
	v_pk_add_f32 v[160:161], v[160:161], v[164:165]
	v_mov_b32_e32 v159, v193
	v_mov_b32_e32 v163, v194
	v_pk_mov_b32 v[164:165], v[168:169], v[166:167] op_sel:[1,0]
	v_mov_b32_e32 v169, v167
	v_pk_mov_b32 v[166:167], v[176:177], v[172:173] op_sel:[1,0]
	v_mov_b32_e32 v177, v173
	v_pk_add_f32 v[170:171], v[180:181], v[182:183]
	v_mov_b32_e32 v187, v185
	v_mov_b32_e32 v189, v190
	v_pk_add_f32 v[172:173], v[144:145], v[144:145] op_sel:[0,1] op_sel_hi:[1,0]
	v_pk_add_f32 v[174:175], v[146:147], v[146:147] op_sel:[0,1] op_sel_hi:[1,0]
	v_pk_add_f32 v[158:159], v[158:159], v[162:163]
	v_pk_add_f32 v[156:157], v[170:171], v[156:157]
	v_pk_add_f32 v[162:163], v[186:187], v[188:189]
	v_mov_b32_e32 v173, v191
	v_mov_b32_e32 v175, v192
	v_add_f32_e32 v155, v156, v157
	v_pk_add_f32 v[156:157], v[162:163], v[160:161]
	v_pk_add_f32 v[160:161], v[172:173], v[174:175]
	v_add_f32_e32 v162, v156, v157
	v_pk_add_f32 v[156:157], v[160:161], v[158:159]
	ds_bpermute_b32 v158, v1, v155
	ds_bpermute_b32 v159, v1, v162
	v_add_f32_e32 v156, v156, v157
	ds_bpermute_b32 v157, v1, v156
	v_pk_add_f32 v[144:145], v[164:165], v[168:169]
	s_waitcnt lgkmcnt(2)
	v_add_f32_e32 v155, v155, v158
	ds_bpermute_b32 v158, v148, v155
	s_waitcnt lgkmcnt(2)
	v_add_f32_e32 v159, v162, v159
	ds_bpermute_b32 v160, v148, v159
	s_waitcnt lgkmcnt(2)
	v_add_f32_e32 v156, v156, v157
	ds_bpermute_b32 v157, v148, v156
	s_waitcnt lgkmcnt(2)
	v_add_f32_e32 v155, v155, v158
	ds_bpermute_b32 v158, v149, v155
	s_waitcnt lgkmcnt(2)
	v_add_f32_e32 v159, v159, v160
	ds_bpermute_b32 v160, v149, v159
	s_waitcnt lgkmcnt(2)
	v_add_f32_e32 v156, v156, v157
	ds_bpermute_b32 v157, v149, v156
	s_waitcnt lgkmcnt(2)
	v_add_f32_e32 v155, v155, v158
	ds_bpermute_b32 v158, v150, v155
	s_waitcnt lgkmcnt(2)
	v_add_f32_e32 v159, v159, v160
	ds_bpermute_b32 v160, v150, v159
	s_waitcnt lgkmcnt(2)
	v_add_f32_e32 v156, v156, v157
	ds_bpermute_b32 v157, v150, v156
	s_waitcnt lgkmcnt(2)
	v_add_f32_e32 v155, v155, v158
	ds_bpermute_b32 v158, v151, v155
	s_waitcnt lgkmcnt(2)
	v_add_f32_e32 v159, v159, v160
	ds_bpermute_b32 v160, v151, v159
	s_waitcnt lgkmcnt(2)
	v_add_f32_e32 v156, v156, v157
	ds_bpermute_b32 v157, v151, v156
	s_waitcnt lgkmcnt(2)
	v_add_f32_e32 v155, v155, v158
	ds_bpermute_b32 v158, v152, v155
	s_waitcnt lgkmcnt(2)
	v_add_f32_e32 v159, v159, v160
	ds_bpermute_b32 v160, v152, v159
	s_waitcnt lgkmcnt(2)
	v_add_f32_e32 v156, v156, v157
	ds_bpermute_b32 v157, v152, v156
	s_waitcnt lgkmcnt(2)
	v_add_f32_e32 v155, v155, v158
	v_fmamk_f32 v155, v155, 0x3a800000, v153
	s_waitcnt lgkmcnt(1)
	v_add_f32_e32 v158, v159, v160
	v_mul_f32_e32 v159, 0x4f800000, v155
	v_cmp_gt_f32_e32 vcc, s25, v155
	v_fmamk_f32 v158, v158, 0x3a800000, v153
	s_waitcnt lgkmcnt(0)
	v_add_f32_e32 v156, v156, v157
	v_cndmask_b32_e32 v155, v155, v159, vcc
	v_mul_f32_e32 v157, 0x4f800000, v158
	v_cmp_gt_f32_e64 s[6:7], s25, v158
	v_sqrt_f32_e32 v159, v155
	v_fmamk_f32 v156, v156, 0x3a800000, v153
	v_cndmask_b32_e64 v157, v158, v157, s[6:7]
	v_mul_f32_e32 v158, 0x4f800000, v156
	v_cmp_gt_f32_e64 s[8:9], s25, v156
	v_sqrt_f32_e32 v160, v157
	v_add_u32_e32 v161, -1, v159
	v_cndmask_b32_e64 v156, v156, v158, s[8:9]
	v_sqrt_f32_e32 v158, v156
	v_add_u32_e32 v162, 1, v159
	v_fma_f32 v163, -v161, v159, v155
	v_fma_f32 v164, -v162, v159, v155
	v_add_u32_e32 v165, -1, v160
	v_cmp_ge_f32_e64 s[10:11], 0, v163
	v_pk_add_f32 v[146:147], v[166:167], v[176:177]
	v_add_u32_e32 v166, 1, v160
	v_cndmask_b32_e64 v159, v159, v161, s[10:11]
	v_fma_f32 v161, -v165, v160, v157
	v_cmp_lt_f32_e64 s[10:11], 0, v164
	v_fma_f32 v163, -v166, v160, v157
	v_add_u32_e32 v167, -1, v158
	v_cndmask_b32_e64 v159, v159, v162, s[10:11]
	v_cmp_ge_f32_e64 s[10:11], 0, v161
	v_add_u32_e32 v168, 1, v158
	v_fma_f32 v161, -v167, v158, v156
	v_cndmask_b32_e64 v160, v160, v165, s[10:11]
	v_cmp_lt_f32_e64 s[10:11], 0, v163
	v_fma_f32 v162, -v168, v158, v156
	v_mul_f32_e32 v163, 0x37800000, v159
	v_cndmask_b32_e64 v160, v160, v166, s[10:11]
	v_cmp_ge_f32_e64 s[10:11], 0, v161
	v_cndmask_b32_e32 v159, v159, v163, vcc
	v_cmp_class_f32_e32 vcc, v155, v154
	v_cndmask_b32_e64 v158, v158, v167, s[10:11]
	v_cmp_lt_f32_e64 s[10:11], 0, v162
	v_mul_f32_e32 v161, 0x37800000, v160
	v_cndmask_b32_e32 v155, v159, v155, vcc
	v_cndmask_b32_e64 v158, v158, v168, s[10:11]
	v_cndmask_b32_e64 v159, v160, v161, s[6:7]
	v_cmp_class_f32_e32 vcc, v157, v154
	v_mul_f32_e32 v160, 0x37800000, v158
	v_div_scale_f32 v161, s[6:7], v155, v155, 1.0
	v_cndmask_b32_e32 v157, v159, v157, vcc
	v_cndmask_b32_e64 v158, v158, v160, s[8:9]
	v_cmp_class_f32_e32 vcc, v156, v154
	v_rcp_f32_e32 v159, v161
	v_div_scale_f32 v160, s[8:9], v157, v157, 1.0
	v_cndmask_b32_e32 v158, v158, v156, vcc
	v_rcp_f32_e32 v164, v160
	v_div_scale_f32 v165, s[10:11], v158, v158, 1.0
	v_rcp_f32_e32 v167, v165
	v_fma_f32 v156, -v161, v159, 1.0
	v_div_scale_f32 v162, s[6:7], 1.0, v155, 1.0
	v_fmac_f32_e32 v159, v156, v159
	v_fma_f32 v156, -v160, v164, 1.0
	v_mul_f32_e32 v168, v162, v159
	v_div_scale_f32 v163, s[8:9], 1.0, v157, 1.0
	v_fmac_f32_e32 v164, v156, v164
	v_fma_f32 v156, -v165, v167, 1.0
	v_fma_f32 v169, -v161, v168, v162
	v_div_scale_f32 v166, s[10:11], 1.0, v158, 1.0
	v_mul_f32_e32 v170, v163, v164
	v_fmac_f32_e32 v167, v156, v167
	v_fmac_f32_e32 v168, v169, v159
	v_fma_f32 v156, -v160, v170, v163
	v_mul_f32_e32 v169, v166, v167
	v_fma_f32 v161, -v161, v168, v162
	s_mov_b64 vcc, s[6:7]
	v_fmac_f32_e32 v170, v156, v164
	v_fma_f32 v156, -v165, v169, v166
	v_div_fmas_f32 v159, v161, v159, v168
	v_fma_f32 v160, -v160, v170, v163
	v_fmac_f32_e32 v169, v156, v167
	v_div_fixup_f32 v156, v159, v155, 1.0
	s_mov_b64 vcc, s[8:9]
	v_div_fmas_f32 v155, v160, v164, v170
	v_fma_f32 v159, -v165, v169, v166
	v_pk_mul_f32 v[80:81], v[80:81], v[156:157] op_sel_hi:[1,0]
	v_pk_mul_f32 v[78:79], v[78:79], v[156:157] op_sel_hi:[1,0]
	s_mov_b64 vcc, s[10:11]
	v_pk_add_f32 v[88:89], v[88:89], 1.0 op_sel_hi:[1,0]
	v_pk_add_f32 v[86:87], v[86:87], 1.0 op_sel_hi:[1,0]
	v_pk_mul_f32 v[76:77], v[76:77], v[156:157] op_sel_hi:[1,0]
	v_pk_mul_f32 v[74:75], v[74:75], v[156:157] op_sel_hi:[1,0]
	v_pk_mul_f32 v[72:73], v[72:73], v[156:157] op_sel_hi:[1,0]
	v_pk_mul_f32 v[70:71], v[70:71], v[156:157] op_sel_hi:[1,0]
	v_pk_mul_f32 v[68:69], v[68:69], v[156:157] op_sel_hi:[1,0]
	v_pk_mul_f32 v[66:67], v[66:67], v[156:157] op_sel_hi:[1,0]
	v_div_fixup_f32 v156, v155, v157, 1.0
	v_div_fmas_f32 v155, v159, v167, v169
	v_pk_mul_f32 v[78:79], v[78:79], v[2:3]
	v_pk_mul_f32 v[80:81], v[80:81], v[4:5]
	v_pk_mul_f32 v[64:65], v[64:65], v[156:157] op_sel_hi:[1,0]
	v_pk_mul_f32 v[62:63], v[62:63], v[156:157] op_sel_hi:[1,0]
	v_pk_mul_f32 v[60:61], v[60:61], v[156:157] op_sel_hi:[1,0]
	v_pk_mul_f32 v[58:59], v[58:59], v[156:157] op_sel_hi:[1,0]
	v_pk_mul_f32 v[56:57], v[56:57], v[156:157] op_sel_hi:[1,0]
	v_pk_mul_f32 v[54:55], v[54:55], v[156:157] op_sel_hi:[1,0]
	v_pk_mul_f32 v[52:53], v[52:53], v[156:157] op_sel_hi:[1,0]
	v_pk_mul_f32 v[156:157], v[50:51], v[156:157] op_sel_hi:[1,0]
	v_div_fixup_f32 v50, v155, v158, 1.0
	v_pk_fma_f32 v[80:81], v[80:81], v[88:89], v[84:85]
	v_pk_fma_f32 v[78:79], v[78:79], v[86:87], v[82:83]
	v_pk_mul_f32 v[86:87], v[52:53], v[16:17]
	v_pk_mul_f32 v[48:49], v[48:49], v[50:51] op_sel_hi:[1,0]
	v_pk_mul_f32 v[46:47], v[46:47], v[50:51] op_sel_hi:[1,0]
	v_pk_mul_f32 v[82:83], v[54:55], v[10:11]
	v_pk_mul_f32 v[84:85], v[156:157], v[14:15]
	v_pk_mul_f32 v[88:89], v[46:47], v[2:3]
	v_pk_mul_f32 v[156:157], v[48:49], v[4:5]
	v_cvt_pk_bf16_f32 v46, v78, v79
	v_cvt_pk_bf16_f32 v47, v80, v81
	global_store_dwordx2 v[102:103], v[46:47], off
	global_load_dwordx4 v[46:49], v[134:135], off
	s_nop 0
	global_load_dwordx4 v[52:55], v[124:125], off offset:1024
	v_pk_mul_f32 v[74:75], v[74:75], v[6:7]
	v_pk_mul_f32 v[76:77], v[76:77], v[8:9]
	v_pk_mul_f32 v[70:71], v[70:71], v[10:11]
	v_pk_mul_f32 v[72:73], v[72:73], v[12:13]
	v_pk_mul_f32 v[66:67], v[66:67], v[14:15]
	v_pk_mul_f32 v[68:69], v[68:69], v[16:17]
	v_pk_mul_f32 v[62:63], v[62:63], v[2:3]
	v_pk_mul_f32 v[64:65], v[64:65], v[4:5]
	v_pk_mul_f32 v[58:59], v[58:59], v[6:7]
	v_pk_mul_f32 v[60:61], v[60:61], v[8:9]
	v_pk_mul_f32 v[56:57], v[56:57], v[12:13]
	v_mul_f32_e32 v178, v23, v23
	v_mul_f32_e32 v184, v25, v25
	v_mul_f32_e32 v195, v18, v18
	v_mul_f32_e32 v196, v19, v19
	v_mul_f32_e32 v197, v20, v20
	v_mul_f32_e32 v198, v21, v21
	v_pk_fma_f32 v[140:141], v[22:23], v[22:23], v[178:179] op_sel_hi:[1,1,0]
	v_pk_fma_f32 v[142:143], v[24:25], v[24:25], v[184:185] op_sel_hi:[1,1,0]
	v_mov_b32_e32 v141, v197
	v_mov_b32_e32 v143, v198
	v_lshl_add_u64 v[94:95], v[94:95], 0, s[18:19]
	s_mov_b32 s8, s30
	s_cmp_lt_i32 s30, s24
	s_waitcnt vmcnt(0) lgkmcnt(0)
	v_pk_add_f32 v[48:49], v[48:49], 1.0 op_sel_hi:[1,0]
	v_pk_add_f32 v[46:47], v[46:47], 1.0 op_sel_hi:[1,0]
	v_pk_fma_f32 v[48:49], v[76:77], v[48:49], v[54:55]
	v_pk_fma_f32 v[46:47], v[74:75], v[46:47], v[52:53]
	v_cvt_pk_bf16_f32 v46, v46, v47
	v_cvt_pk_bf16_f32 v47, v48, v49
	global_store_dwordx2 v[102:103], v[46:47], off offset:512
	global_load_dwordx4 v[46:49], v[130:131], off
	s_nop 0
	global_load_dwordx4 v[52:55], v[124:125], off offset:2048
	s_waitcnt vmcnt(0) lgkmcnt(0)
	v_pk_add_f32 v[48:49], v[48:49], 1.0 op_sel_hi:[1,0]
	v_pk_add_f32 v[46:47], v[46:47], 1.0 op_sel_hi:[1,0]
	v_pk_fma_f32 v[48:49], v[72:73], v[48:49], v[54:55]
	v_pk_fma_f32 v[46:47], v[70:71], v[46:47], v[52:53]
	v_cvt_pk_bf16_f32 v46, v46, v47
	v_cvt_pk_bf16_f32 v47, v48, v49
	global_store_dwordx2 v[102:103], v[46:47], off offset:1024
	global_load_dwordx4 v[46:49], v[128:129], off
	s_nop 0
	global_load_dwordx4 v[52:55], v[124:125], off offset:3072
	s_waitcnt vmcnt(0) lgkmcnt(0)
	v_pk_add_f32 v[48:49], v[48:49], 1.0 op_sel_hi:[1,0]
	v_pk_add_f32 v[46:47], v[46:47], 1.0 op_sel_hi:[1,0]
	v_pk_fma_f32 v[48:49], v[68:69], v[48:49], v[54:55]
	v_pk_fma_f32 v[46:47], v[66:67], v[46:47], v[52:53]
	v_cvt_pk_bf16_f32 v46, v46, v47
	v_cvt_pk_bf16_f32 v47, v48, v49
	global_store_dwordx2 v[102:103], v[46:47], off offset:1536
	global_load_dwordx4 v[46:49], v[126:127], off
	s_nop 0
	global_load_dwordx4 v[52:55], v[110:111], off
	s_waitcnt vmcnt(0) lgkmcnt(0)
	v_pk_add_f32 v[48:49], v[48:49], 1.0 op_sel_hi:[1,0]
	v_pk_add_f32 v[46:47], v[46:47], 1.0 op_sel_hi:[1,0]
	v_pk_fma_f32 v[48:49], v[64:65], v[48:49], v[54:55]
	v_pk_fma_f32 v[46:47], v[62:63], v[46:47], v[52:53]
	v_cvt_pk_bf16_f32 v46, v46, v47
	v_cvt_pk_bf16_f32 v47, v48, v49
	global_store_dwordx2 v[102:103], v[46:47], off offset:2048
	global_load_dwordx4 v[46:49], v[120:121], off
	s_nop 0
	global_load_dwordx4 v[52:55], v[110:111], off offset:1024
	s_waitcnt vmcnt(0) lgkmcnt(0)
	v_pk_add_f32 v[48:49], v[48:49], 1.0 op_sel_hi:[1,0]
	v_pk_add_f32 v[46:47], v[46:47], 1.0 op_sel_hi:[1,0]
	v_pk_fma_f32 v[48:49], v[60:61], v[48:49], v[54:55]
	v_pk_fma_f32 v[46:47], v[58:59], v[46:47], v[52:53]
	v_cvt_pk_bf16_f32 v46, v46, v47
	v_cvt_pk_bf16_f32 v47, v48, v49
	global_store_dwordx2 v[102:103], v[46:47], off offset:2560
	global_load_dwordx4 v[46:49], v[116:117], off
	s_nop 0
	global_load_dwordx4 v[52:55], v[110:111], off offset:2048
	v_pk_add_f32 v[58:59], v[146:147], v[146:147] op_sel:[0,1] op_sel_hi:[1,0]
	v_pk_add_f32 v[60:61], v[140:141], v[142:143]
	v_mov_b32_e32 v59, v196
	s_waitcnt vmcnt(0) lgkmcnt(0)
	v_pk_add_f32 v[48:49], v[48:49], 1.0 op_sel_hi:[1,0]
	v_pk_add_f32 v[46:47], v[46:47], 1.0 op_sel_hi:[1,0]
	v_pk_fma_f32 v[48:49], v[56:57], v[48:49], v[54:55]
	v_pk_fma_f32 v[46:47], v[82:83], v[46:47], v[52:53]
	v_cvt_pk_bf16_f32 v46, v46, v47
	v_cvt_pk_bf16_f32 v47, v48, v49
	global_store_dwordx2 v[102:103], v[46:47], off offset:3072
	global_load_dwordx4 v[46:49], v[112:113], off
	s_nop 0
	global_load_dwordx4 v[52:55], v[110:111], off offset:3072
	v_pk_add_f32 v[56:57], v[144:145], v[144:145] op_sel:[0,1] op_sel_hi:[1,0]
	s_waitcnt vmcnt(0) lgkmcnt(0)
	v_pk_add_f32 v[48:49], v[48:49], 1.0 op_sel_hi:[1,0]
	v_pk_add_f32 v[46:47], v[46:47], 1.0 op_sel_hi:[1,0]
	v_pk_fma_f32 v[48:49], v[86:87], v[48:49], v[54:55]
	v_pk_fma_f32 v[46:47], v[84:85], v[46:47], v[52:53]
	v_cvt_pk_bf16_f32 v46, v46, v47
	v_cvt_pk_bf16_f32 v47, v48, v49
	global_store_dwordx2 v[102:103], v[46:47], off offset:3584
	global_load_dwordx4 v[46:49], v[138:139], off
	s_nop 0
	global_load_dwordx4 v[52:55], v[108:109], off
	v_mov_b32_e32 v57, v195
	s_waitcnt vmcnt(0) lgkmcnt(0)
	v_pk_add_f32 v[48:49], v[48:49], 1.0 op_sel_hi:[1,0]
	v_pk_add_f32 v[46:47], v[46:47], 1.0 op_sel_hi:[1,0]
	v_pk_fma_f32 v[48:49], v[156:157], v[48:49], v[54:55]
	v_pk_fma_f32 v[46:47], v[88:89], v[46:47], v[52:53]
	v_bfe_u32 v51, v46, 16, 1
	v_bfe_u32 v52, v47, 16, 1
	v_add3_u32 v46, v46, v51, s26
	v_add3_u32 v47, v47, v52, s26
	v_lshrrev_b32_e32 v46, 16, v46
	v_and_or_b32 v46, v47, s27, v46
	v_cvt_pk_bf16_f32 v47, v48, v49
	global_store_dwordx2 v[104:105], v[46:47], off
	global_load_dwordx4 v[46:49], v[136:137], off
	s_nop 0
	global_load_dwordx4 v[52:55], v[108:109], off offset:1024
	v_pk_mul_f32 v[44:45], v[44:45], v[50:51] op_sel_hi:[1,0]
	v_pk_mul_f32 v[42:43], v[42:43], v[50:51] op_sel_hi:[1,0]
	v_pk_mul_f32 v[44:45], v[44:45], v[8:9]
	v_pk_mul_f32 v[42:43], v[42:43], v[6:7]
	s_waitcnt vmcnt(0) lgkmcnt(0)
	v_pk_add_f32 v[48:49], v[48:49], 1.0 op_sel_hi:[1,0]
	v_pk_add_f32 v[46:47], v[46:47], 1.0 op_sel_hi:[1,0]
	v_pk_fma_f32 v[44:45], v[44:45], v[48:49], v[54:55]
	v_pk_fma_f32 v[42:43], v[42:43], v[46:47], v[52:53]
	v_cvt_pk_bf16_f32 v42, v42, v43
	v_cvt_pk_bf16_f32 v43, v44, v45
	global_store_dwordx2 v[104:105], v[42:43], off offset:512
	global_load_dwordx4 v[42:45], v[132:133], off
	s_nop 0
	global_load_dwordx4 v[46:49], v[108:109], off offset:2048
	v_pk_add_f32 v[52:53], v[56:57], v[58:59]
	s_waitcnt vmcnt(0) lgkmcnt(0)
	v_pk_add_f32 v[44:45], v[44:45], 1.0 op_sel_hi:[1,0]
	v_pk_add_f32 v[52:53], v[52:53], v[60:61]
	v_pk_add_f32 v[42:43], v[42:43], 1.0 op_sel_hi:[1,0]
	v_add_f32_e32 v51, v52, v53
	ds_bpermute_b32 v52, v1, v51
	s_waitcnt lgkmcnt(0)
	v_add_f32_e32 v51, v51, v52
	ds_bpermute_b32 v52, v148, v51
	s_waitcnt lgkmcnt(0)
	v_add_f32_e32 v51, v51, v52
	v_pk_mul_f32 v[40:41], v[40:41], v[50:51] op_sel_hi:[1,0]
	v_pk_mul_f32 v[38:39], v[38:39], v[50:51] op_sel_hi:[1,0]
	v_pk_mul_f32 v[40:41], v[40:41], v[12:13]
	v_pk_mul_f32 v[38:39], v[38:39], v[10:11]
	v_pk_fma_f32 v[40:41], v[40:41], v[44:45], v[48:49]
	v_pk_fma_f32 v[38:39], v[38:39], v[42:43], v[46:47]
	v_cvt_pk_bf16_f32 v38, v38, v39
	v_cvt_pk_bf16_f32 v39, v40, v41
	global_store_dwordx2 v[104:105], v[38:39], off offset:1024
	global_load_dwordx4 v[38:41], v[122:123], off
	s_nop 0
	global_load_dwordx4 v[42:45], v[108:109], off offset:3072
	v_pk_mul_f32 v[36:37], v[36:37], v[50:51] op_sel_hi:[1,0]
	v_pk_mul_f32 v[34:35], v[34:35], v[50:51] op_sel_hi:[1,0]
	v_pk_mul_f32 v[36:37], v[36:37], v[16:17]
	v_pk_mul_f32 v[34:35], v[34:35], v[14:15]
	ds_bpermute_b32 v46, v149, v51
	s_waitcnt lgkmcnt(0)
	v_add_f32_e32 v46, v51, v46
	ds_bpermute_b32 v47, v150, v46
	s_waitcnt lgkmcnt(0)
	v_add_f32_e32 v46, v46, v47
	ds_bpermute_b32 v47, v151, v46
	s_waitcnt lgkmcnt(0)
	v_add_f32_e32 v46, v46, v47
	ds_bpermute_b32 v47, v152, v46
	s_waitcnt lgkmcnt(0)
	v_add_f32_e32 v46, v46, v47
	v_fmamk_f32 v46, v46, 0x3a800000, v153
	v_mul_f32_e32 v47, 0x4f800000, v46
	v_cmp_gt_f32_e32 vcc, s25, v46
	s_waitcnt vmcnt(0)
	v_pk_add_f32 v[40:41], v[40:41], 1.0 op_sel_hi:[1,0]
	v_pk_add_f32 v[38:39], v[38:39], 1.0 op_sel_hi:[1,0]
	v_pk_fma_f32 v[36:37], v[36:37], v[40:41], v[44:45]
	v_pk_fma_f32 v[34:35], v[34:35], v[38:39], v[42:43]
	v_cvt_pk_bf16_f32 v34, v34, v35
	v_cvt_pk_bf16_f32 v35, v36, v37
	global_store_dwordx2 v[104:105], v[34:35], off offset:1536
	global_load_dwordx4 v[34:37], v[118:119], off
	s_nop 0
	global_load_dwordx4 v[38:41], v[106:107], off
	v_cndmask_b32_e32 v42, v46, v47, vcc
	v_sqrt_f32_e32 v43, v42
	s_waitcnt vmcnt(0) lgkmcnt(0)
	v_pk_add_f32 v[36:37], v[36:37], 1.0 op_sel_hi:[1,0]
	v_add_u32_e32 v44, -1, v43
	v_add_u32_e32 v45, 1, v43
	v_fma_f32 v46, -v44, v43, v42
	v_fma_f32 v47, -v45, v43, v42
	v_cmp_ge_f32_e64 s[6:7], 0, v46
	v_pk_add_f32 v[34:35], v[34:35], 1.0 op_sel_hi:[1,0]
	s_nop 0
	v_cndmask_b32_e64 v43, v43, v44, s[6:7]
	v_cmp_lt_f32_e64 s[6:7], 0, v47
	s_nop 1
	v_cndmask_b32_e64 v43, v43, v45, s[6:7]
	v_mul_f32_e32 v44, 0x37800000, v43
	v_cndmask_b32_e32 v43, v43, v44, vcc
	v_cmp_class_f32_e32 vcc, v42, v154
	s_nop 1
	v_cndmask_b32_e32 v42, v43, v42, vcc
	v_div_scale_f32 v43, s[6:7], v42, v42, 1.0
	v_rcp_f32_e32 v45, v43
	v_div_scale_f32 v44, vcc, 1.0, v42, 1.0
	v_fma_f32 v46, -v43, v45, 1.0
	v_fmac_f32_e32 v45, v46, v45
	v_mul_f32_e32 v46, v44, v45
	v_fma_f32 v47, -v43, v46, v44
	v_fmac_f32_e32 v46, v47, v45
	v_fma_f32 v43, -v43, v46, v44
	v_div_fmas_f32 v43, v43, v45, v46
	v_div_fixup_f32 v42, v43, v42, 1.0
	v_pk_mul_f32 v[32:33], v[32:33], v[42:43] op_sel_hi:[1,0]
	v_pk_mul_f32 v[30:31], v[30:31], v[42:43] op_sel_hi:[1,0]
	v_pk_mul_f32 v[32:33], v[32:33], v[4:5]
	v_pk_mul_f32 v[30:31], v[30:31], v[2:3]
	v_pk_fma_f32 v[32:33], v[32:33], v[36:37], v[40:41]
	v_pk_fma_f32 v[30:31], v[30:31], v[34:35], v[38:39]
	v_cvt_pk_bf16_f32 v30, v30, v31
	v_cvt_pk_bf16_f32 v31, v32, v33
	global_store_dwordx2 v[104:105], v[30:31], off offset:2048
	global_load_dwordx4 v[30:33], v[114:115], off
	s_nop 0
	global_load_dwordx4 v[34:37], v[106:107], off offset:1024
	v_pk_mul_f32 v[28:29], v[28:29], v[42:43] op_sel_hi:[1,0]
	v_pk_mul_f32 v[26:27], v[26:27], v[42:43] op_sel_hi:[1,0]
	v_pk_mul_f32 v[28:29], v[28:29], v[8:9]
	v_pk_mul_f32 v[26:27], v[26:27], v[6:7]
	v_lshl_add_u64 v[38:39], s[22:23], 0, v[98:99]
	v_pk_mul_f32 v[24:25], v[24:25], v[42:43] op_sel_hi:[1,0]
	v_pk_mul_f32 v[22:23], v[22:23], v[42:43] op_sel_hi:[1,0]
	v_pk_mul_f32 v[24:25], v[24:25], v[12:13]
	v_pk_mul_f32 v[22:23], v[22:23], v[10:11]
	v_pk_mul_f32 v[20:21], v[20:21], v[42:43] op_sel_hi:[1,0]
	v_pk_mul_f32 v[18:19], v[18:19], v[42:43] op_sel_hi:[1,0]
	v_pk_mul_f32 v[20:21], v[20:21], v[16:17]
	v_pk_mul_f32 v[18:19], v[18:19], v[14:15]
	s_waitcnt vmcnt(0) lgkmcnt(0)
	v_pk_add_f32 v[32:33], v[32:33], 1.0 op_sel_hi:[1,0]
	v_pk_add_f32 v[30:31], v[30:31], 1.0 op_sel_hi:[1,0]
	v_pk_fma_f32 v[28:29], v[28:29], v[32:33], v[36:37]
	v_pk_fma_f32 v[26:27], v[26:27], v[30:31], v[34:35]
	v_cvt_pk_bf16_f32 v26, v26, v27
	v_cvt_pk_bf16_f32 v27, v28, v29
	global_store_dwordx2 v[104:105], v[26:27], off offset:2560
	global_load_dwordx4 v[26:29], v[38:39], off
	s_nop 0
	global_load_dwordx4 v[30:33], v[106:107], off offset:2048
	v_lshl_add_u64 v[34:35], s[22:23], 0, v[100:101]
	s_waitcnt vmcnt(0) lgkmcnt(0)
	v_pk_add_f32 v[28:29], v[28:29], 1.0 op_sel_hi:[1,0]
	v_pk_add_f32 v[26:27], v[26:27], 1.0 op_sel_hi:[1,0]
	v_pk_fma_f32 v[24:25], v[24:25], v[28:29], v[32:33]
	v_pk_fma_f32 v[22:23], v[22:23], v[26:27], v[30:31]
	v_cvt_pk_bf16_f32 v22, v22, v23
	v_cvt_pk_bf16_f32 v23, v24, v25
	global_store_dwordx2 v[104:105], v[22:23], off offset:3072
	global_load_dwordx4 v[22:25], v[34:35], off
	s_nop 0
	global_load_dwordx4 v[26:29], v[106:107], off offset:3072
	s_waitcnt vmcnt(0) lgkmcnt(0)
	v_pk_add_f32 v[24:25], v[24:25], 1.0 op_sel_hi:[1,0]
	v_pk_add_f32 v[22:23], v[22:23], 1.0 op_sel_hi:[1,0]
	v_pk_fma_f32 v[20:21], v[20:21], v[24:25], v[28:29]
	v_pk_fma_f32 v[18:19], v[18:19], v[22:23], v[26:27]
	v_cvt_pk_bf16_f32 v18, v18, v19
	v_cvt_pk_bf16_f32 v19, v20, v21
	global_store_dwordx2 v[104:105], v[18:19], off offset:3584
	s_cbranch_scc1 .LBB0_3341

.LBB0_3449:
	v_lshl_add_u64 v[18:19], s[38:39], 0, v[94:95]
	v_lshl_add_u64 v[22:23], s[38:39], 0, v[92:93]
	v_add_co_u32_e32 v20, vcc, 0x7800000, v18
	v_add_co_u32_e64 v102, s[6:7], s30, v22
	s_nop 0
	v_addc_co_u32_e32 v21, vcc, 0, v19, vcc
	v_addc_co_u32_e64 v103, s[6:7], 0, v23, s[6:7]
	v_add_co_u32_e64 v104, s[6:7], s31, v22
	v_add_co_u32_e32 v22, vcc, 0x7801000, v18
	s_nop 0
	v_addc_co_u32_e64 v105, s[6:7], 0, v23, s[6:7]
	global_load_dwordx4 v[78:81], v[20:21], off
	global_load_dwordx4 v[74:77], v[20:21], off offset:1024
	global_load_dwordx4 v[70:73], v[20:21], off offset:2048
	global_load_dwordx4 v[66:69], v[20:21], off offset:3072
	v_addc_co_u32_e32 v23, vcc, 0, v19, vcc
	v_add_co_u32_e32 v20, vcc, 0x7802000, v18
	global_load_dwordx4 v[62:65], v[22:23], off
	global_load_dwordx4 v[58:61], v[22:23], off offset:1024
	global_load_dwordx4 v[54:57], v[22:23], off offset:2048
	global_load_dwordx4 v[50:53], v[22:23], off offset:3072
	v_addc_co_u32_e32 v21, vcc, 0, v19, vcc
	global_load_dwordx4 v[46:49], v[20:21], off
	global_load_dwordx4 v[42:45], v[20:21], off offset:1024
	global_load_dwordx4 v[38:41], v[20:21], off offset:2048
	global_load_dwordx4 v[34:37], v[20:21], off offset:3072
	v_add_co_u32_e32 v18, vcc, 0x7803000, v18
	s_ashr_i32 s8, s20, 13
	s_nop 0
	v_addc_co_u32_e32 v19, vcc, 0, v19, vcc
	global_load_dwordx4 v[30:33], v[18:19], off
	global_load_dwordx4 v[26:29], v[18:19], off offset:1024
	global_load_dwordx4 v[22:25], v[18:19], off offset:2048
	s_nop 0
	global_load_dwordx4 v[18:21], v[18:19], off offset:3072
	s_add_i32 s9, s20, 0xffffc002
	s_cmpk_lt_i32 s20, 0x4000
	s_cselect_b32 s6, s8, s9
	s_addk_i32 s6, 0x82
	s_mul_hi_i32 s7, s6, 0x9000
	s_mul_i32 s6, s6, 0x9000
	s_add_u32 s6, s26, s6
	s_addc_u32 s7, s27, s7
	s_add_u32 s10, s6, 0x1000
	s_addc_u32 s11, s7, 0
	v_lshl_add_u64 v[122:123], s[6:7], 0, v[90:91]
	v_lshl_add_u64 v[86:87], s[10:11], 0, v[90:91]
	global_load_dwordx4 v[82:85], v[122:123], off
	s_add_i32 s6, s20, 0xffffc003
	global_load_dwordx4 v[86:89], v[86:87], off
	s_cmpk_lt_i32 s20, 0x3fff
	s_cselect_b32 s6, s8, s6
	s_addk_i32 s6, 0x82
	s_mul_hi_i32 s7, s6, 0x9000
	s_mul_i32 s6, s6, 0x9000
	s_add_u32 s6, s26, s6
	s_addc_u32 s7, s27, s7
	v_lshl_add_u64 v[138:139], s[10:11], 0, v[96:97]
	v_lshl_add_u64 v[134:135], s[10:11], 0, v[98:99]
	v_lshl_add_u64 v[128:129], s[10:11], 0, v[100:101]
	s_add_u32 s10, s6, 0x1000
	v_lshl_add_u64 v[110:111], s[6:7], 0, v[90:91]
	s_addc_u32 s11, s7, 0
	s_add_i32 s6, s20, 0xffffc004
	s_cmpk_lt_i32 s20, 0x3ffe
	s_cselect_b32 s6, s8, s6
	s_addk_i32 s6, 0x82
	s_mul_hi_i32 s7, s6, 0x9000
	s_mul_i32 s6, s6, 0x9000
	v_lshl_add_u64 v[124:125], s[10:11], 0, v[90:91]
	v_lshl_add_u64 v[118:119], s[10:11], 0, v[96:97]
	v_lshl_add_u64 v[114:115], s[10:11], 0, v[98:99]
	v_lshl_add_u64 v[112:113], s[10:11], 0, v[100:101]
	s_add_u32 s10, s26, s6
	s_addc_u32 s11, s27, s7
	s_add_u32 s6, s10, 0x1000
	s_addc_u32 s7, s11, 0
	s_add_i32 s9, s20, 0xffffc005
	s_cmpk_lt_i32 s20, 0x3ffd
	v_lshl_add_u64 v[142:143], s[6:7], 0, v[90:91]
	v_lshl_add_u64 v[140:141], s[6:7], 0, v[96:97]
	v_lshl_add_u64 v[136:137], s[6:7], 0, v[98:99]
	v_lshl_add_u64 v[126:127], s[6:7], 0, v[100:101]
	s_cselect_b32 s6, s8, s9
	s_addk_i32 s6, 0x82
	s_mul_hi_i32 s7, s6, 0x9000
	s_mul_i32 s6, s6, 0x9000
	s_add_u32 s6, s26, s6
	s_addc_u32 s7, s27, s7
	s_add_u32 s44, s6, 0x1000
	v_lshl_add_u64 v[106:107], s[6:7], 0, v[90:91]
	s_addc_u32 s45, s7, 0
	v_lshl_add_u64 v[108:109], s[10:11], 0, v[90:91]
	v_lshl_add_u64 v[120:121], s[44:45], 0, v[90:91]
	v_lshl_add_u64 v[116:117], s[44:45], 0, v[96:97]
	s_add_i32 s20, s20, 32
	v_lshl_add_u64 v[92:93], v[92:93], 0, s[22:23]
	s_waitcnt vmcnt(0) lgkmcnt(0)
	v_pk_mul_f32 v[144:145], v[80:81], v[80:81]
	v_pk_mul_f32 v[146:147], v[78:79], v[78:79]
	v_pk_mul_f32 v[148:149], v[76:77], v[76:77]
	v_pk_mul_f32 v[150:151], v[74:75], v[74:75]
	v_mul_f32_e32 v160, v71, v71
	v_mul_f32_e32 v162, v73, v73
	v_pk_mov_b32 v[164:165], v[146:147], v[144:145] op_sel:[1,0]
	v_mov_b32_e32 v147, v145
	v_pk_mov_b32 v[144:145], v[150:151], v[148:149] op_sel:[1,0]
	v_mov_b32_e32 v151, v149
	v_mul_f32_e32 v173, v68, v68
	v_mul_f32_e32 v175, v69, v69
	v_pk_fma_f32 v[148:149], v[70:71], v[70:71], v[160:161] op_sel_hi:[1,1,0]
	v_pk_fma_f32 v[160:161], v[72:73], v[72:73], v[162:163] op_sel_hi:[1,1,0]
	v_pk_mul_f32 v[162:163], v[64:65], v[64:65]
	v_pk_mul_f32 v[166:167], v[62:63], v[62:63]
	v_pk_mul_f32 v[168:169], v[60:61], v[60:61]
	v_pk_mul_f32 v[170:171], v[58:59], v[58:59]
	v_mul_f32_e32 v172, v55, v55
	v_mul_f32_e32 v174, v57, v57
	v_pk_add_f32 v[146:147], v[164:165], v[146:147]
	v_pk_add_f32 v[144:145], v[144:145], v[150:151]
	v_mul_f32_e32 v159, v66, v66
	v_mul_f32_e32 v183, v67, v67
	v_mov_b32_e32 v149, v173
	v_mov_b32_e32 v161, v175
	v_pk_mov_b32 v[150:151], v[166:167], v[162:163] op_sel:[1,0]
	v_mov_b32_e32 v167, v163
	v_pk_mov_b32 v[162:163], v[170:171], v[168:169] op_sel:[1,0]
	v_mov_b32_e32 v171, v169
	v_pk_fma_f32 v[164:165], v[54:55], v[54:55], v[172:173] op_sel_hi:[1,1,0]
	v_pk_fma_f32 v[168:169], v[56:57], v[56:57], v[174:175] op_sel_hi:[1,1,0]
	v_pk_mul_f32 v[172:173], v[48:49], v[48:49]
	v_pk_mul_f32 v[174:175], v[46:47], v[46:47]
	v_pk_add_f32 v[184:185], v[146:147], v[146:147] op_sel:[0,1] op_sel_hi:[1,0]
	v_pk_add_f32 v[186:187], v[144:145], v[144:145] op_sel:[0,1] op_sel_hi:[1,0]
	v_mul_f32_e32 v181, v52, v52
	v_pk_mul_f32 v[176:177], v[44:45], v[44:45]
	v_pk_mul_f32 v[178:179], v[42:43], v[42:43]
	v_mul_f32_e32 v180, v39, v39
	v_mul_f32_e32 v182, v41, v41
	v_pk_add_f32 v[160:161], v[148:149], v[160:161]
	v_pk_add_f32 v[144:145], v[150:151], v[166:167]
	v_pk_add_f32 v[146:147], v[162:163], v[170:171]
	v_pk_mov_b32 v[148:149], v[174:175], v[172:173] op_sel:[1,0]
	v_mov_b32_e32 v175, v173
	v_mov_b32_e32 v185, v159
	v_mov_b32_e32 v187, v183
	v_mul_f32_e32 v189, v50, v50
	v_mul_f32_e32 v194, v51, v51
	v_mul_f32_e32 v188, v53, v53
	v_mul_f32_e32 v197, v36, v36
	v_mul_f32_e32 v198, v37, v37
	v_pk_mov_b32 v[150:151], v[178:179], v[176:177] op_sel:[1,0]
	v_mov_b32_e32 v179, v177
	v_pk_fma_f32 v[162:163], v[38:39], v[38:39], v[180:181] op_sel_hi:[1,1,0]
	v_pk_fma_f32 v[166:167], v[40:41], v[40:41], v[182:183] op_sel_hi:[1,1,0]
	v_pk_add_f32 v[190:191], v[144:145], v[144:145] op_sel:[0,1] op_sel_hi:[1,0]
	v_pk_add_f32 v[192:193], v[146:147], v[146:147] op_sel:[0,1] op_sel_hi:[1,0]
	v_pk_add_f32 v[148:149], v[148:149], v[174:175]
	v_pk_add_f32 v[174:175], v[184:185], v[186:187]
	v_mov_b32_e32 v165, v181
	v_mov_b32_e32 v169, v188
	v_pk_mul_f32 v[170:171], v[32:33], v[32:33]
	v_pk_mul_f32 v[172:173], v[30:31], v[30:31]
	v_pk_mul_f32 v[176:177], v[28:29], v[28:29]
	v_pk_mul_f32 v[180:181], v[26:27], v[26:27]
	v_pk_add_f32 v[150:151], v[150:151], v[178:179]
	v_mov_b32_e32 v163, v197
	v_mov_b32_e32 v167, v198
	v_mov_b32_e32 v191, v189
	v_mov_b32_e32 v193, v194
	v_pk_add_f32 v[160:161], v[174:175], v[160:161]
	v_mul_f32_e32 v195, v34, v34
	v_mul_f32_e32 v196, v35, v35
	v_pk_add_f32 v[164:165], v[164:165], v[168:169]
	v_pk_mov_b32 v[168:169], v[172:173], v[170:171] op_sel:[1,0]
	v_mov_b32_e32 v173, v171
	v_pk_mov_b32 v[170:171], v[180:181], v[176:177] op_sel:[1,0]
	v_mov_b32_e32 v181, v177
	v_pk_add_f32 v[176:177], v[148:149], v[148:149] op_sel:[0,1] op_sel_hi:[1,0]
	v_pk_add_f32 v[178:179], v[150:151], v[150:151] op_sel:[0,1] op_sel_hi:[1,0]
	v_pk_add_f32 v[162:163], v[162:163], v[166:167]
	v_pk_add_f32 v[166:167], v[190:191], v[192:193]
	v_add_f32_e32 v159, v160, v161
	v_mov_b32_e32 v177, v195
	v_mov_b32_e32 v179, v196
	v_pk_add_f32 v[160:161], v[166:167], v[164:165]
	ds_bpermute_b32 v167, v133, v159
	v_pk_add_f32 v[164:165], v[176:177], v[178:179]
	v_add_f32_e32 v166, v160, v161
	v_pk_add_f32 v[160:161], v[164:165], v[162:163]
	ds_bpermute_b32 v162, v133, v166
	v_add_f32_e32 v160, v160, v161
	ds_bpermute_b32 v161, v133, v160
	s_waitcnt lgkmcnt(2)
	v_add_f32_e32 v159, v159, v167
	ds_bpermute_b32 v163, v152, v159
	s_waitcnt lgkmcnt(2)
	v_add_f32_e32 v162, v166, v162
	ds_bpermute_b32 v164, v152, v162
	s_waitcnt lgkmcnt(2)
	v_add_f32_e32 v160, v160, v161
	ds_bpermute_b32 v161, v152, v160
	s_waitcnt lgkmcnt(2)
	v_add_f32_e32 v159, v159, v163
	ds_bpermute_b32 v163, v153, v159
	s_waitcnt lgkmcnt(2)
	v_add_f32_e32 v162, v162, v164
	ds_bpermute_b32 v164, v153, v162
	s_waitcnt lgkmcnt(2)
	v_add_f32_e32 v160, v160, v161
	ds_bpermute_b32 v161, v153, v160
	s_waitcnt lgkmcnt(2)
	v_add_f32_e32 v159, v159, v163
	ds_bpermute_b32 v163, v154, v159
	s_waitcnt lgkmcnt(2)
	v_add_f32_e32 v162, v162, v164
	ds_bpermute_b32 v164, v154, v162
	s_waitcnt lgkmcnt(2)
	v_add_f32_e32 v160, v160, v161
	ds_bpermute_b32 v161, v154, v160
	s_waitcnt lgkmcnt(2)
	v_add_f32_e32 v159, v159, v163
	ds_bpermute_b32 v163, v155, v159
	s_waitcnt lgkmcnt(2)
	v_add_f32_e32 v162, v162, v164
	ds_bpermute_b32 v164, v155, v162
	s_waitcnt lgkmcnt(2)
	v_add_f32_e32 v160, v160, v161
	ds_bpermute_b32 v161, v155, v160
	s_waitcnt lgkmcnt(2)
	v_add_f32_e32 v159, v159, v163
	ds_bpermute_b32 v163, v156, v159
	s_waitcnt lgkmcnt(2)
	v_add_f32_e32 v162, v162, v164
	ds_bpermute_b32 v164, v156, v162
	s_waitcnt lgkmcnt(2)
	v_add_f32_e32 v160, v160, v161
	ds_bpermute_b32 v161, v156, v160
	s_waitcnt lgkmcnt(2)
	v_add_f32_e32 v159, v159, v163
	v_fmamk_f32 v159, v159, 0x3a800000, v157
	s_waitcnt lgkmcnt(1)
	v_add_f32_e32 v162, v162, v164
	v_mul_f32_e32 v163, 0x4f800000, v159
	v_cmp_gt_f32_e32 vcc, s21, v159
	v_fmamk_f32 v162, v162, 0x3a800000, v157
	s_waitcnt lgkmcnt(0)
	v_add_f32_e32 v160, v160, v161
	v_cndmask_b32_e32 v159, v159, v163, vcc
	v_mul_f32_e32 v161, 0x4f800000, v162
	v_cmp_gt_f32_e64 s[6:7], s21, v162
	v_sqrt_f32_e32 v163, v159
	v_fmamk_f32 v160, v160, 0x3a800000, v157
	v_cndmask_b32_e64 v161, v162, v161, s[6:7]
	v_mul_f32_e32 v162, 0x4f800000, v160
	v_cmp_gt_f32_e64 s[8:9], s21, v160
	v_sqrt_f32_e32 v164, v161
	v_add_u32_e32 v165, -1, v163
	v_cndmask_b32_e64 v160, v160, v162, s[8:9]
	v_sqrt_f32_e32 v162, v160
	v_add_u32_e32 v166, 1, v163
	v_fma_f32 v167, -v165, v163, v159
	v_pk_add_f32 v[148:149], v[168:169], v[172:173]
	v_fma_f32 v168, -v166, v163, v159
	v_add_u32_e32 v169, -1, v164
	v_cmp_ge_f32_e64 s[10:11], 0, v167
	v_pk_add_f32 v[150:151], v[170:171], v[180:181]
	v_add_u32_e32 v170, 1, v164
	v_cndmask_b32_e64 v163, v163, v165, s[10:11]
	v_fma_f32 v165, -v169, v164, v161
	v_cmp_lt_f32_e64 s[10:11], 0, v168
	v_fma_f32 v167, -v170, v164, v161
	v_add_u32_e32 v171, -1, v162
	v_cndmask_b32_e64 v163, v163, v166, s[10:11]
	v_cmp_ge_f32_e64 s[10:11], 0, v165
	v_add_u32_e32 v172, 1, v162
	v_fma_f32 v165, -v171, v162, v160
	v_cndmask_b32_e64 v164, v164, v169, s[10:11]
	v_cmp_lt_f32_e64 s[10:11], 0, v167
	v_fma_f32 v166, -v172, v162, v160
	v_mul_f32_e32 v167, 0x37800000, v163
	v_cndmask_b32_e64 v164, v164, v170, s[10:11]
	v_cmp_ge_f32_e64 s[10:11], 0, v165
	v_cndmask_b32_e32 v163, v163, v167, vcc
	v_cmp_class_f32_e32 vcc, v159, v158
	v_cndmask_b32_e64 v162, v162, v171, s[10:11]
	v_cmp_lt_f32_e64 s[10:11], 0, v166
	v_mul_f32_e32 v165, 0x37800000, v164
	v_cndmask_b32_e32 v159, v163, v159, vcc
	v_cndmask_b32_e64 v162, v162, v172, s[10:11]
	v_cndmask_b32_e64 v163, v164, v165, s[6:7]
	v_cmp_class_f32_e32 vcc, v161, v158
	v_mul_f32_e32 v164, 0x37800000, v162
	v_div_scale_f32 v165, s[6:7], v159, v159, 1.0
	v_cndmask_b32_e32 v161, v163, v161, vcc
	v_cndmask_b32_e64 v162, v162, v164, s[8:9]
	v_cmp_class_f32_e32 vcc, v160, v158
	v_rcp_f32_e32 v163, v165
	v_div_scale_f32 v164, s[8:9], v161, v161, 1.0
	v_cndmask_b32_e32 v162, v162, v160, vcc
	v_rcp_f32_e32 v168, v164
	v_div_scale_f32 v169, s[10:11], v162, v162, 1.0
	v_rcp_f32_e32 v171, v169
	v_fma_f32 v160, -v165, v163, 1.0
	v_div_scale_f32 v166, s[6:7], 1.0, v159, 1.0
	v_fmac_f32_e32 v163, v160, v163
	v_fma_f32 v160, -v164, v168, 1.0
	v_mul_f32_e32 v172, v166, v163
	v_div_scale_f32 v167, s[8:9], 1.0, v161, 1.0
	v_fmac_f32_e32 v168, v160, v168
	v_fma_f32 v160, -v169, v171, 1.0
	v_fma_f32 v173, -v165, v172, v166
	v_div_scale_f32 v170, s[10:11], 1.0, v162, 1.0
	v_mul_f32_e32 v174, v167, v168
	v_fmac_f32_e32 v171, v160, v171
	v_fmac_f32_e32 v172, v173, v163
	v_fma_f32 v160, -v164, v174, v167
	v_mul_f32_e32 v173, v170, v171
	v_fma_f32 v165, -v165, v172, v166
	s_mov_b64 vcc, s[6:7]
	v_fmac_f32_e32 v174, v160, v168
	v_fma_f32 v160, -v169, v173, v170
	v_div_fmas_f32 v163, v165, v163, v172
	v_fma_f32 v164, -v164, v174, v167
	v_fmac_f32_e32 v173, v160, v171
	v_div_fixup_f32 v160, v163, v159, 1.0
	s_mov_b64 vcc, s[8:9]
	v_div_fmas_f32 v159, v164, v168, v174
	v_fma_f32 v163, -v169, v173, v170
	v_pk_mul_f32 v[80:81], v[80:81], v[160:161] op_sel_hi:[1,0]
	v_pk_mul_f32 v[78:79], v[78:79], v[160:161] op_sel_hi:[1,0]
	s_mov_b64 vcc, s[10:11]
	v_pk_add_f32 v[88:89], v[88:89], 1.0 op_sel_hi:[1,0]
	v_pk_add_f32 v[86:87], v[86:87], 1.0 op_sel_hi:[1,0]
	v_pk_mul_f32 v[76:77], v[76:77], v[160:161] op_sel_hi:[1,0]
	v_pk_mul_f32 v[74:75], v[74:75], v[160:161] op_sel_hi:[1,0]
	v_pk_mul_f32 v[72:73], v[72:73], v[160:161] op_sel_hi:[1,0]
	v_pk_mul_f32 v[70:71], v[70:71], v[160:161] op_sel_hi:[1,0]
	v_pk_mul_f32 v[68:69], v[68:69], v[160:161] op_sel_hi:[1,0]
	v_pk_mul_f32 v[66:67], v[66:67], v[160:161] op_sel_hi:[1,0]
	v_div_fixup_f32 v160, v159, v161, 1.0
	v_div_fmas_f32 v159, v163, v171, v173
	v_pk_mul_f32 v[78:79], v[78:79], v[2:3]
	v_pk_mul_f32 v[80:81], v[80:81], v[4:5]
	v_pk_mul_f32 v[64:65], v[64:65], v[160:161] op_sel_hi:[1,0]
	v_pk_mul_f32 v[62:63], v[62:63], v[160:161] op_sel_hi:[1,0]
	v_pk_mul_f32 v[60:61], v[60:61], v[160:161] op_sel_hi:[1,0]
	v_pk_mul_f32 v[58:59], v[58:59], v[160:161] op_sel_hi:[1,0]
	v_pk_mul_f32 v[56:57], v[56:57], v[160:161] op_sel_hi:[1,0]
	v_pk_mul_f32 v[54:55], v[54:55], v[160:161] op_sel_hi:[1,0]
	v_pk_mul_f32 v[52:53], v[52:53], v[160:161] op_sel_hi:[1,0]
	v_pk_mul_f32 v[50:51], v[50:51], v[160:161] op_sel_hi:[1,0]
	v_div_fixup_f32 v160, v159, v162, 1.0
	v_pk_fma_f32 v[80:81], v[80:81], v[88:89], v[84:85]
	v_pk_fma_f32 v[78:79], v[78:79], v[86:87], v[82:83]
	v_pk_mul_f32 v[82:83], v[50:51], v[14:15]
	v_pk_mul_f32 v[84:85], v[52:53], v[16:17]
	v_pk_mul_f32 v[48:49], v[48:49], v[160:161] op_sel_hi:[1,0]
	v_pk_mul_f32 v[46:47], v[46:47], v[160:161] op_sel_hi:[1,0]
	v_pk_mul_f32 v[86:87], v[46:47], v[2:3]
	v_pk_mul_f32 v[88:89], v[48:49], v[4:5]
	v_cvt_pk_bf16_f32 v46, v78, v79
	v_cvt_pk_bf16_f32 v47, v80, v81
	global_store_dwordx2 v[102:103], v[46:47], off
	global_load_dwordx4 v[46:49], v[138:139], off
	s_nop 0
	global_load_dwordx4 v[50:53], v[122:123], off offset:1024
	v_pk_mul_f32 v[74:75], v[74:75], v[6:7]
	v_pk_mul_f32 v[76:77], v[76:77], v[8:9]
	v_pk_mul_f32 v[70:71], v[70:71], v[10:11]
	v_pk_mul_f32 v[72:73], v[72:73], v[12:13]
	v_pk_mul_f32 v[66:67], v[66:67], v[14:15]
	v_pk_mul_f32 v[68:69], v[68:69], v[16:17]
	v_pk_mul_f32 v[62:63], v[62:63], v[2:3]
	v_pk_mul_f32 v[64:65], v[64:65], v[4:5]
	v_pk_mul_f32 v[58:59], v[58:59], v[6:7]
	v_pk_mul_f32 v[60:61], v[60:61], v[8:9]
	v_pk_mul_f32 v[54:55], v[54:55], v[10:11]
	v_pk_mul_f32 v[56:57], v[56:57], v[12:13]
	v_pk_mul_f32 v[44:45], v[44:45], v[160:161] op_sel_hi:[1,0]
	v_pk_mul_f32 v[42:43], v[42:43], v[160:161] op_sel_hi:[1,0]
	v_pk_mul_f32 v[44:45], v[44:45], v[8:9]
	v_pk_mul_f32 v[42:43], v[42:43], v[6:7]
	v_pk_mul_f32 v[40:41], v[40:41], v[160:161] op_sel_hi:[1,0]
	v_pk_mul_f32 v[38:39], v[38:39], v[160:161] op_sel_hi:[1,0]
	v_pk_mul_f32 v[40:41], v[40:41], v[12:13]
	v_pk_mul_f32 v[38:39], v[38:39], v[10:11]
	v_pk_mul_f32 v[36:37], v[36:37], v[160:161] op_sel_hi:[1,0]
	v_pk_mul_f32 v[34:35], v[34:35], v[160:161] op_sel_hi:[1,0]
	v_pk_mul_f32 v[36:37], v[36:37], v[16:17]
	v_pk_mul_f32 v[34:35], v[34:35], v[14:15]
	v_mul_f32_e32 v182, v23, v23
	v_mul_f32_e32 v188, v25, v25
	v_mul_f32_e32 v199, v18, v18
	v_mul_f32_e32 v200, v19, v19
	v_mul_f32_e32 v201, v20, v20
	v_mul_f32_e32 v202, v21, v21
	v_pk_fma_f32 v[144:145], v[22:23], v[22:23], v[182:183] op_sel_hi:[1,1,0]
	v_pk_fma_f32 v[146:147], v[24:25], v[24:25], v[188:189] op_sel_hi:[1,1,0]
	v_mov_b32_e32 v145, v201
	v_mov_b32_e32 v147, v202
	v_lshl_add_u64 v[94:95], v[94:95], 0, s[24:25]
	s_cmp_lt_i32 s20, s13
	s_waitcnt vmcnt(0) lgkmcnt(0)
	v_pk_add_f32 v[48:49], v[48:49], 1.0 op_sel_hi:[1,0]
	v_pk_add_f32 v[46:47], v[46:47], 1.0 op_sel_hi:[1,0]
	v_pk_fma_f32 v[48:49], v[76:77], v[48:49], v[52:53]
	v_pk_fma_f32 v[46:47], v[74:75], v[46:47], v[50:51]
	v_cvt_pk_bf16_f32 v46, v46, v47
	v_cvt_pk_bf16_f32 v47, v48, v49
	global_store_dwordx2 v[102:103], v[46:47], off offset:512
	global_load_dwordx4 v[46:49], v[134:135], off
	s_nop 0
	global_load_dwordx4 v[50:53], v[122:123], off offset:2048
	s_waitcnt vmcnt(0) lgkmcnt(0)
	v_pk_add_f32 v[48:49], v[48:49], 1.0 op_sel_hi:[1,0]
	v_pk_add_f32 v[46:47], v[46:47], 1.0 op_sel_hi:[1,0]
	v_pk_fma_f32 v[48:49], v[72:73], v[48:49], v[52:53]
	v_pk_fma_f32 v[46:47], v[70:71], v[46:47], v[50:51]
	v_cvt_pk_bf16_f32 v46, v46, v47
	v_cvt_pk_bf16_f32 v47, v48, v49
	global_store_dwordx2 v[102:103], v[46:47], off offset:1024
	global_load_dwordx4 v[46:49], v[128:129], off
	s_nop 0
	global_load_dwordx4 v[50:53], v[122:123], off offset:3072
	s_waitcnt vmcnt(0) lgkmcnt(0)
	v_pk_add_f32 v[48:49], v[48:49], 1.0 op_sel_hi:[1,0]
	v_pk_add_f32 v[46:47], v[46:47], 1.0 op_sel_hi:[1,0]
	v_pk_fma_f32 v[48:49], v[68:69], v[48:49], v[52:53]
	v_pk_fma_f32 v[46:47], v[66:67], v[46:47], v[50:51]
	v_cvt_pk_bf16_f32 v46, v46, v47
	v_cvt_pk_bf16_f32 v47, v48, v49
	global_store_dwordx2 v[102:103], v[46:47], off offset:1536
	global_load_dwordx4 v[46:49], v[124:125], off
	s_nop 0
	global_load_dwordx4 v[50:53], v[110:111], off
	s_waitcnt vmcnt(0) lgkmcnt(0)
	v_pk_add_f32 v[48:49], v[48:49], 1.0 op_sel_hi:[1,0]
	v_pk_add_f32 v[46:47], v[46:47], 1.0 op_sel_hi:[1,0]
	v_pk_fma_f32 v[48:49], v[64:65], v[48:49], v[52:53]
	v_pk_fma_f32 v[46:47], v[62:63], v[46:47], v[50:51]
	v_cvt_pk_bf16_f32 v46, v46, v47
	v_cvt_pk_bf16_f32 v47, v48, v49
	global_store_dwordx2 v[102:103], v[46:47], off offset:2048
	global_load_dwordx4 v[46:49], v[118:119], off
	s_nop 0
	global_load_dwordx4 v[50:53], v[110:111], off offset:1024
	s_waitcnt vmcnt(0) lgkmcnt(0)
	v_pk_add_f32 v[48:49], v[48:49], 1.0 op_sel_hi:[1,0]
	v_pk_add_f32 v[46:47], v[46:47], 1.0 op_sel_hi:[1,0]
	v_pk_fma_f32 v[48:49], v[60:61], v[48:49], v[52:53]
	v_pk_fma_f32 v[46:47], v[58:59], v[46:47], v[50:51]
	v_cvt_pk_bf16_f32 v46, v46, v47
	v_cvt_pk_bf16_f32 v47, v48, v49
	global_store_dwordx2 v[102:103], v[46:47], off offset:2560
	global_load_dwordx4 v[46:49], v[114:115], off
	s_nop 0
	global_load_dwordx4 v[50:53], v[110:111], off offset:2048
	v_pk_add_f32 v[58:59], v[144:145], v[146:147]
	s_waitcnt vmcnt(0) lgkmcnt(0)
	v_pk_add_f32 v[48:49], v[48:49], 1.0 op_sel_hi:[1,0]
	v_pk_add_f32 v[46:47], v[46:47], 1.0 op_sel_hi:[1,0]
	v_pk_fma_f32 v[48:49], v[56:57], v[48:49], v[52:53]
	v_pk_fma_f32 v[46:47], v[54:55], v[46:47], v[50:51]
	v_cvt_pk_bf16_f32 v46, v46, v47
	v_cvt_pk_bf16_f32 v47, v48, v49
	global_store_dwordx2 v[102:103], v[46:47], off offset:3072
	global_load_dwordx4 v[46:49], v[112:113], off
	s_nop 0
	global_load_dwordx4 v[50:53], v[110:111], off offset:3072
	v_pk_add_f32 v[54:55], v[148:149], v[148:149] op_sel:[0,1] op_sel_hi:[1,0]
	v_pk_add_f32 v[56:57], v[150:151], v[150:151] op_sel:[0,1] op_sel_hi:[1,0]
	v_mov_b32_e32 v55, v199
	v_mov_b32_e32 v57, v200
	s_waitcnt vmcnt(0) lgkmcnt(0)
	v_pk_add_f32 v[48:49], v[48:49], 1.0 op_sel_hi:[1,0]
	v_pk_add_f32 v[46:47], v[46:47], 1.0 op_sel_hi:[1,0]
	v_pk_fma_f32 v[48:49], v[84:85], v[48:49], v[52:53]
	v_pk_fma_f32 v[46:47], v[82:83], v[46:47], v[50:51]
	v_cvt_pk_bf16_f32 v46, v46, v47
	v_cvt_pk_bf16_f32 v47, v48, v49
	global_store_dwordx2 v[102:103], v[46:47], off offset:3584
	global_load_dwordx4 v[46:49], v[142:143], off
	s_nop 0
	global_load_dwordx4 v[50:53], v[108:109], off
	s_waitcnt vmcnt(0) lgkmcnt(0)
	v_pk_add_f32 v[48:49], v[48:49], 1.0 op_sel_hi:[1,0]
	v_pk_add_f32 v[46:47], v[46:47], 1.0 op_sel_hi:[1,0]
	v_pk_fma_f32 v[48:49], v[88:89], v[48:49], v[52:53]
	v_pk_fma_f32 v[46:47], v[86:87], v[46:47], v[50:51]
	v_cvt_pk_bf16_f32 v46, v46, v47
	v_cvt_pk_bf16_f32 v47, v48, v49
	global_store_dwordx2 v[104:105], v[46:47], off
	global_load_dwordx4 v[46:49], v[140:141], off
	s_nop 0
	global_load_dwordx4 v[50:53], v[108:109], off offset:1024
	s_waitcnt vmcnt(0) lgkmcnt(0)
	v_pk_add_f32 v[48:49], v[48:49], 1.0 op_sel_hi:[1,0]
	v_pk_add_f32 v[46:47], v[46:47], 1.0 op_sel_hi:[1,0]
	v_pk_fma_f32 v[44:45], v[44:45], v[48:49], v[52:53]
	v_pk_fma_f32 v[42:43], v[42:43], v[46:47], v[50:51]
	v_cvt_pk_bf16_f32 v42, v42, v43
	v_cvt_pk_bf16_f32 v43, v44, v45
	global_store_dwordx2 v[104:105], v[42:43], off offset:512
	global_load_dwordx4 v[42:45], v[136:137], off
	s_nop 0
	global_load_dwordx4 v[46:49], v[108:109], off offset:2048
	v_pk_add_f32 v[50:51], v[54:55], v[56:57]
	s_waitcnt vmcnt(0) lgkmcnt(0)
	v_pk_add_f32 v[44:45], v[44:45], 1.0 op_sel_hi:[1,0]
	v_pk_add_f32 v[42:43], v[42:43], 1.0 op_sel_hi:[1,0]
	v_pk_fma_f32 v[40:41], v[40:41], v[44:45], v[48:49]
	v_pk_fma_f32 v[38:39], v[38:39], v[42:43], v[46:47]
	v_cvt_pk_bf16_f32 v38, v38, v39
	v_cvt_pk_bf16_f32 v39, v40, v41
	global_store_dwordx2 v[104:105], v[38:39], off offset:1024
	global_load_dwordx4 v[38:41], v[126:127], off
	s_nop 0
	global_load_dwordx4 v[42:45], v[108:109], off offset:3072
	v_pk_add_f32 v[50:51], v[50:51], v[58:59]
	s_waitcnt vmcnt(0) lgkmcnt(0)
	v_pk_add_f32 v[40:41], v[40:41], 1.0 op_sel_hi:[1,0]
	v_pk_add_f32 v[38:39], v[38:39], 1.0 op_sel_hi:[1,0]
	v_pk_fma_f32 v[36:37], v[36:37], v[40:41], v[44:45]
	v_pk_fma_f32 v[34:35], v[34:35], v[38:39], v[42:43]
	v_cvt_pk_bf16_f32 v34, v34, v35
	v_cvt_pk_bf16_f32 v35, v36, v37
	global_store_dwordx2 v[104:105], v[34:35], off offset:1536
	global_load_dwordx4 v[34:37], v[120:121], off
	s_nop 0
	global_load_dwordx4 v[38:41], v[106:107], off
	v_add_f32_e32 v50, v50, v51
	ds_bpermute_b32 v51, v133, v50
	s_waitcnt lgkmcnt(0)
	v_add_f32_e32 v50, v50, v51
	ds_bpermute_b32 v51, v152, v50
	s_waitcnt lgkmcnt(0)
	v_add_f32_e32 v50, v50, v51
	ds_bpermute_b32 v46, v153, v50
	s_waitcnt lgkmcnt(0)
	v_add_f32_e32 v46, v50, v46
	ds_bpermute_b32 v47, v154, v46
	s_waitcnt lgkmcnt(0)
	v_add_f32_e32 v46, v46, v47
	ds_bpermute_b32 v47, v155, v46
	s_waitcnt lgkmcnt(0)
	v_add_f32_e32 v46, v46, v47
	ds_bpermute_b32 v47, v156, v46
	s_waitcnt lgkmcnt(0)
	v_add_f32_e32 v46, v46, v47
	v_fmamk_f32 v46, v46, 0x3a800000, v157
	v_mul_f32_e32 v47, 0x4f800000, v46
	v_cmp_gt_f32_e32 vcc, s21, v46
	s_waitcnt vmcnt(0)
	v_pk_add_f32 v[36:37], v[36:37], 1.0 op_sel_hi:[1,0]
	v_cndmask_b32_e32 v42, v46, v47, vcc
	v_sqrt_f32_e32 v43, v42
	v_pk_add_f32 v[34:35], v[34:35], 1.0 op_sel_hi:[1,0]
	v_add_u32_e32 v44, -1, v43
	v_add_u32_e32 v45, 1, v43
	v_fma_f32 v46, -v44, v43, v42
	v_fma_f32 v47, -v45, v43, v42
	v_cmp_ge_f32_e64 s[6:7], 0, v46
	s_nop 1
	v_cndmask_b32_e64 v43, v43, v44, s[6:7]
	v_cmp_lt_f32_e64 s[6:7], 0, v47
	s_nop 1
	v_cndmask_b32_e64 v43, v43, v45, s[6:7]
	v_mul_f32_e32 v44, 0x37800000, v43
	v_cndmask_b32_e32 v43, v43, v44, vcc
	v_cmp_class_f32_e32 vcc, v42, v158
	s_nop 1
	v_cndmask_b32_e32 v42, v43, v42, vcc
	v_div_scale_f32 v43, s[6:7], v42, v42, 1.0
	v_rcp_f32_e32 v45, v43
	v_div_scale_f32 v44, vcc, 1.0, v42, 1.0
	v_fma_f32 v46, -v43, v45, 1.0
	v_fmac_f32_e32 v45, v46, v45
	v_mul_f32_e32 v46, v44, v45
	v_fma_f32 v47, -v43, v46, v44
	v_fmac_f32_e32 v46, v47, v45
	v_fma_f32 v43, -v43, v46, v44
	v_div_fmas_f32 v43, v43, v45, v46
	v_div_fixup_f32 v42, v43, v42, 1.0
	v_pk_mul_f32 v[32:33], v[32:33], v[42:43] op_sel_hi:[1,0]
	v_pk_mul_f32 v[30:31], v[30:31], v[42:43] op_sel_hi:[1,0]
	v_pk_mul_f32 v[32:33], v[32:33], v[4:5]
	v_pk_mul_f32 v[30:31], v[30:31], v[2:3]
	v_pk_fma_f32 v[32:33], v[32:33], v[36:37], v[40:41]
	v_pk_fma_f32 v[30:31], v[30:31], v[34:35], v[38:39]
	v_cvt_pk_bf16_f32 v30, v30, v31
	v_cvt_pk_bf16_f32 v31, v32, v33
	global_store_dwordx2 v[104:105], v[30:31], off offset:2048
	global_load_dwordx4 v[30:33], v[116:117], off
	s_nop 0
	global_load_dwordx4 v[34:37], v[106:107], off offset:1024
	v_pk_mul_f32 v[28:29], v[28:29], v[42:43] op_sel_hi:[1,0]
	v_pk_mul_f32 v[26:27], v[26:27], v[42:43] op_sel_hi:[1,0]
	v_pk_mul_f32 v[28:29], v[28:29], v[8:9]
	v_pk_mul_f32 v[26:27], v[26:27], v[6:7]
	v_lshl_add_u64 v[38:39], s[44:45], 0, v[98:99]
	v_pk_mul_f32 v[24:25], v[24:25], v[42:43] op_sel_hi:[1,0]
	v_pk_mul_f32 v[22:23], v[22:23], v[42:43] op_sel_hi:[1,0]
	v_pk_mul_f32 v[24:25], v[24:25], v[12:13]
	v_pk_mul_f32 v[22:23], v[22:23], v[10:11]
	v_pk_mul_f32 v[20:21], v[20:21], v[42:43] op_sel_hi:[1,0]
	v_pk_mul_f32 v[18:19], v[18:19], v[42:43] op_sel_hi:[1,0]
	v_pk_mul_f32 v[20:21], v[20:21], v[16:17]
	v_pk_mul_f32 v[18:19], v[18:19], v[14:15]
	s_waitcnt vmcnt(0) lgkmcnt(0)
	v_pk_add_f32 v[32:33], v[32:33], 1.0 op_sel_hi:[1,0]
	v_pk_add_f32 v[30:31], v[30:31], 1.0 op_sel_hi:[1,0]
	v_pk_fma_f32 v[28:29], v[28:29], v[32:33], v[36:37]
	v_pk_fma_f32 v[26:27], v[26:27], v[30:31], v[34:35]
	v_cvt_pk_bf16_f32 v26, v26, v27
	v_cvt_pk_bf16_f32 v27, v28, v29
	global_store_dwordx2 v[104:105], v[26:27], off offset:2560
	global_load_dwordx4 v[26:29], v[38:39], off
	s_nop 0
	global_load_dwordx4 v[30:33], v[106:107], off offset:2048
	v_lshl_add_u64 v[34:35], s[44:45], 0, v[100:101]
	s_waitcnt vmcnt(0) lgkmcnt(0)
	v_pk_add_f32 v[28:29], v[28:29], 1.0 op_sel_hi:[1,0]
	v_pk_add_f32 v[26:27], v[26:27], 1.0 op_sel_hi:[1,0]
	v_pk_fma_f32 v[24:25], v[24:25], v[28:29], v[32:33]
	v_pk_fma_f32 v[22:23], v[22:23], v[26:27], v[30:31]
	v_cvt_pk_bf16_f32 v22, v22, v23
	v_cvt_pk_bf16_f32 v23, v24, v25
	global_store_dwordx2 v[104:105], v[22:23], off offset:3072
	global_load_dwordx4 v[22:25], v[34:35], off
	s_nop 0
	global_load_dwordx4 v[26:29], v[106:107], off offset:3072
	s_waitcnt vmcnt(0) lgkmcnt(0)
	v_pk_add_f32 v[24:25], v[24:25], 1.0 op_sel_hi:[1,0]
	v_pk_add_f32 v[22:23], v[22:23], 1.0 op_sel_hi:[1,0]
	v_pk_fma_f32 v[20:21], v[20:21], v[24:25], v[28:29]
	v_pk_fma_f32 v[18:19], v[18:19], v[22:23], v[26:27]
	v_cvt_pk_bf16_f32 v18, v18, v19
	v_cvt_pk_bf16_f32 v19, v20, v21
	global_store_dwordx2 v[104:105], v[18:19], off offset:3584
	s_cbranch_scc1 .LBB0_3449

.LBB0_3611:
	v_lshl_add_u64 v[18:19], s[38:39], 0, v[94:95]
	v_lshl_add_u64 v[22:23], s[38:39], 0, v[92:93]
	v_add_co_u32_e32 v20, vcc, 0x7800000, v18
	v_add_co_u32_e64 v102, s[6:7], s23, v22
	s_nop 0
	v_addc_co_u32_e32 v21, vcc, 0, v19, vcc
	v_addc_co_u32_e64 v103, s[6:7], 0, v23, s[6:7]
	v_add_co_u32_e64 v104, s[6:7], s24, v22
	v_add_co_u32_e32 v22, vcc, 0x7801000, v18
	s_nop 0
	v_addc_co_u32_e64 v105, s[6:7], 0, v23, s[6:7]
	global_load_dwordx4 v[78:81], v[20:21], off
	global_load_dwordx4 v[74:77], v[20:21], off offset:1024
	global_load_dwordx4 v[70:73], v[20:21], off offset:2048
	global_load_dwordx4 v[66:69], v[20:21], off offset:3072
	v_addc_co_u32_e32 v23, vcc, 0, v19, vcc
	v_add_co_u32_e32 v20, vcc, 0x7802000, v18
	global_load_dwordx4 v[62:65], v[22:23], off
	global_load_dwordx4 v[58:61], v[22:23], off offset:1024
	global_load_dwordx4 v[54:57], v[22:23], off offset:2048
	global_load_dwordx4 v[50:53], v[22:23], off offset:3072
	v_addc_co_u32_e32 v21, vcc, 0, v19, vcc
	v_add_co_u32_e32 v82, vcc, 0x7803000, v18
	global_load_dwordx4 v[46:49], v[20:21], off
	global_load_dwordx4 v[42:45], v[20:21], off offset:1024
	global_load_dwordx4 v[38:41], v[20:21], off offset:2048
	global_load_dwordx4 v[34:37], v[20:21], off offset:3072
	v_addc_co_u32_e32 v83, vcc, 0, v19, vcc
	global_load_dwordx4 v[30:33], v[82:83], off
	global_load_dwordx4 v[26:29], v[82:83], off offset:1024
	global_load_dwordx4 v[22:25], v[82:83], off offset:2048
	global_load_dwordx4 v[18:21], v[82:83], off offset:3072
	s_add_i32 s25, s8, 32
	s_add_i32 s10, s8, 0xffffc022
	s_ashr_i32 s9, s25, 13
	s_cmpk_lt_i32 s25, 0x4000
	s_cselect_b32 s6, s9, s10
	s_addk_i32 s6, 0x82
	s_mul_hi_i32 s7, s6, 0x9000
	s_mul_i32 s6, s6, 0x9000
	s_add_u32 s6, s2, s6
	s_addc_u32 s7, s5, s7
	s_add_u32 s10, s6, 0x1000
	s_addc_u32 s11, s7, 0
	v_lshl_add_u64 v[124:125], s[6:7], 0, v[90:91]
	v_lshl_add_u64 v[86:87], s[10:11], 0, v[90:91]
	global_load_dwordx4 v[82:85], v[124:125], off
	s_add_i32 s6, s8, 0xffffc023
	global_load_dwordx4 v[86:89], v[86:87], off
	s_cmpk_lt_i32 s25, 0x3fff
	s_cselect_b32 s6, s9, s6
	s_addk_i32 s6, 0x82
	s_mul_hi_i32 s7, s6, 0x9000
	s_mul_i32 s6, s6, 0x9000
	s_add_u32 s6, s2, s6
	s_addc_u32 s7, s5, s7
	v_lshl_add_u64 v[138:139], s[10:11], 0, v[96:97]
	v_lshl_add_u64 v[134:135], s[10:11], 0, v[98:99]
	v_lshl_add_u64 v[128:129], s[10:11], 0, v[100:101]
	s_add_u32 s10, s6, 0x1000
	v_lshl_add_u64 v[110:111], s[6:7], 0, v[90:91]
	s_addc_u32 s11, s7, 0
	s_add_i32 s6, s8, 0xffffc024
	s_cmpk_lt_i32 s25, 0x3ffe
	s_cselect_b32 s6, s9, s6
	s_addk_i32 s6, 0x82
	s_mul_hi_i32 s7, s6, 0x9000
	s_mul_i32 s6, s6, 0x9000
	v_lshl_add_u64 v[126:127], s[10:11], 0, v[90:91]
	v_lshl_add_u64 v[120:121], s[10:11], 0, v[96:97]
	v_lshl_add_u64 v[116:117], s[10:11], 0, v[98:99]
	v_lshl_add_u64 v[112:113], s[10:11], 0, v[100:101]
	s_add_u32 s10, s2, s6
	s_addc_u32 s11, s5, s7
	s_add_u32 s6, s10, 0x1000
	s_addc_u32 s7, s11, 0
	s_addk_i32 s8, 0xc025
	s_cmpk_lt_i32 s25, 0x3ffd
	v_lshl_add_u64 v[142:143], s[6:7], 0, v[90:91]
	v_lshl_add_u64 v[140:141], s[6:7], 0, v[96:97]
	v_lshl_add_u64 v[136:137], s[6:7], 0, v[98:99]
	v_lshl_add_u64 v[122:123], s[6:7], 0, v[100:101]
	s_cselect_b32 s6, s9, s8
	s_addk_i32 s6, 0x82
	s_mul_hi_i32 s7, s6, 0x9000
	s_mul_i32 s6, s6, 0x9000
	s_add_u32 s6, s2, s6
	s_addc_u32 s7, s5, s7
	s_add_u32 s20, s6, 0x1000
	v_lshl_add_u64 v[106:107], s[6:7], 0, v[90:91]
	s_addc_u32 s21, s7, 0
	v_lshl_add_u64 v[108:109], s[10:11], 0, v[90:91]
	v_lshl_add_u64 v[118:119], s[20:21], 0, v[90:91]
	v_lshl_add_u64 v[114:115], s[20:21], 0, v[96:97]
	v_lshl_add_u64 v[92:93], v[92:93], 0, s[14:15]
	s_waitcnt vmcnt(0) lgkmcnt(0)
	v_pk_mul_f32 v[144:145], v[80:81], v[80:81]
	v_pk_mul_f32 v[146:147], v[78:79], v[78:79]
	v_pk_mul_f32 v[148:149], v[76:77], v[76:77]
	v_pk_mul_f32 v[150:151], v[74:75], v[74:75]
	v_mul_f32_e32 v158, v71, v71
	v_mul_f32_e32 v160, v73, v73
	v_mul_f32_e32 v171, v68, v68
	v_mul_f32_e32 v173, v69, v69
	v_pk_mov_b32 v[162:163], v[146:147], v[144:145] op_sel:[1,0]
	v_mov_b32_e32 v147, v145
	v_pk_mov_b32 v[144:145], v[150:151], v[148:149] op_sel:[1,0]
	v_mov_b32_e32 v151, v149
	v_pk_fma_f32 v[148:149], v[70:71], v[70:71], v[158:159] op_sel_hi:[1,1,0]
	v_pk_fma_f32 v[158:159], v[72:73], v[72:73], v[160:161] op_sel_hi:[1,1,0]
	v_pk_mul_f32 v[160:161], v[64:65], v[64:65]
	v_pk_mul_f32 v[164:165], v[62:63], v[62:63]
	v_pk_mul_f32 v[166:167], v[60:61], v[60:61]
	v_pk_mul_f32 v[168:169], v[58:59], v[58:59]
	v_mul_f32_e32 v170, v55, v55
	v_mul_f32_e32 v172, v57, v57
	v_pk_add_f32 v[146:147], v[162:163], v[146:147]
	v_pk_add_f32 v[144:145], v[144:145], v[150:151]
	v_mov_b32_e32 v149, v171
	v_mov_b32_e32 v159, v173
	v_pk_mov_b32 v[150:151], v[164:165], v[160:161] op_sel:[1,0]
	v_mov_b32_e32 v165, v161
	v_pk_mov_b32 v[160:161], v[168:169], v[166:167] op_sel:[1,0]
	v_mov_b32_e32 v169, v167
	v_pk_fma_f32 v[162:163], v[54:55], v[54:55], v[170:171] op_sel_hi:[1,1,0]
	v_pk_fma_f32 v[166:167], v[56:57], v[56:57], v[172:173] op_sel_hi:[1,1,0]
	v_pk_mul_f32 v[170:171], v[48:49], v[48:49]
	v_pk_mul_f32 v[172:173], v[46:47], v[46:47]
	v_pk_mul_f32 v[174:175], v[44:45], v[44:45]
	v_pk_mul_f32 v[176:177], v[42:43], v[42:43]
	v_mul_f32_e32 v157, v66, v66
	v_mul_f32_e32 v181, v67, v67
	v_mul_f32_e32 v179, v52, v52
	v_mul_f32_e32 v186, v53, v53
	v_mul_f32_e32 v178, v39, v39
	v_mul_f32_e32 v180, v41, v41
	v_pk_add_f32 v[182:183], v[146:147], v[146:147] op_sel:[0,1] op_sel_hi:[1,0]
	v_pk_add_f32 v[184:185], v[144:145], v[144:145] op_sel:[0,1] op_sel_hi:[1,0]
	v_pk_add_f32 v[158:159], v[148:149], v[158:159]
	v_pk_add_f32 v[144:145], v[150:151], v[164:165]
	v_pk_add_f32 v[146:147], v[160:161], v[168:169]
	v_pk_mov_b32 v[148:149], v[172:173], v[170:171] op_sel:[1,0]
	v_mov_b32_e32 v173, v171
	v_pk_mov_b32 v[150:151], v[176:177], v[174:175] op_sel:[1,0]
	v_mov_b32_e32 v177, v175
	v_mul_f32_e32 v187, v50, v50
	v_mul_f32_e32 v192, v51, v51
	v_mul_f32_e32 v195, v36, v36
	v_mul_f32_e32 v196, v37, v37
	v_mov_b32_e32 v163, v179
	v_mov_b32_e32 v167, v186
	v_pk_fma_f32 v[160:161], v[38:39], v[38:39], v[178:179] op_sel_hi:[1,1,0]
	v_pk_fma_f32 v[164:165], v[40:41], v[40:41], v[180:181] op_sel_hi:[1,1,0]
	v_pk_mul_f32 v[168:169], v[32:33], v[32:33]
	v_pk_mul_f32 v[170:171], v[30:31], v[30:31]
	v_pk_mul_f32 v[174:175], v[28:29], v[28:29]
	v_pk_mul_f32 v[178:179], v[26:27], v[26:27]
	v_mov_b32_e32 v183, v157
	v_mov_b32_e32 v185, v181
	v_pk_add_f32 v[188:189], v[144:145], v[144:145] op_sel:[0,1] op_sel_hi:[1,0]
	v_pk_add_f32 v[190:191], v[146:147], v[146:147] op_sel:[0,1] op_sel_hi:[1,0]
	v_pk_add_f32 v[148:149], v[148:149], v[172:173]
	v_pk_add_f32 v[150:151], v[150:151], v[176:177]
	v_mul_f32_e32 v193, v34, v34
	v_mul_f32_e32 v194, v35, v35
	v_pk_add_f32 v[162:163], v[162:163], v[166:167]
	v_mov_b32_e32 v161, v195
	v_mov_b32_e32 v165, v196
	v_pk_mov_b32 v[166:167], v[170:171], v[168:169] op_sel:[1,0]
	v_mov_b32_e32 v171, v169
	v_pk_mov_b32 v[168:169], v[178:179], v[174:175] op_sel:[1,0]
	v_mov_b32_e32 v179, v175
	v_pk_add_f32 v[172:173], v[182:183], v[184:185]
	v_mov_b32_e32 v189, v187
	v_mov_b32_e32 v191, v192
	v_pk_add_f32 v[174:175], v[148:149], v[148:149] op_sel:[0,1] op_sel_hi:[1,0]
	v_pk_add_f32 v[176:177], v[150:151], v[150:151] op_sel:[0,1] op_sel_hi:[1,0]
	v_pk_add_f32 v[160:161], v[160:161], v[164:165]
	v_pk_add_f32 v[158:159], v[172:173], v[158:159]
	v_pk_add_f32 v[164:165], v[188:189], v[190:191]
	v_mov_b32_e32 v175, v193
	v_mov_b32_e32 v177, v194
	v_add_f32_e32 v157, v158, v159
	v_pk_add_f32 v[158:159], v[164:165], v[162:163]
	v_pk_add_f32 v[162:163], v[174:175], v[176:177]
	v_add_f32_e32 v164, v158, v159
	v_pk_add_f32 v[158:159], v[162:163], v[160:161]
	ds_bpermute_b32 v160, v1, v157
	ds_bpermute_b32 v161, v1, v164
	v_add_f32_e32 v158, v158, v159
	ds_bpermute_b32 v159, v1, v158
	v_pk_add_f32 v[148:149], v[166:167], v[170:171]
	s_waitcnt lgkmcnt(2)
	v_add_f32_e32 v157, v157, v160
	ds_bpermute_b32 v160, v131, v157
	s_waitcnt lgkmcnt(2)
	v_add_f32_e32 v161, v164, v161
	ds_bpermute_b32 v162, v131, v161
	s_waitcnt lgkmcnt(2)
	v_add_f32_e32 v158, v158, v159
	ds_bpermute_b32 v159, v131, v158
	s_waitcnt lgkmcnt(2)
	v_add_f32_e32 v157, v157, v160
	ds_bpermute_b32 v160, v133, v157
	s_waitcnt lgkmcnt(2)
	v_add_f32_e32 v161, v161, v162
	ds_bpermute_b32 v162, v133, v161
	s_waitcnt lgkmcnt(2)
	v_add_f32_e32 v158, v158, v159
	ds_bpermute_b32 v159, v133, v158
	s_waitcnt lgkmcnt(2)
	v_add_f32_e32 v157, v157, v160
	ds_bpermute_b32 v160, v152, v157
	s_waitcnt lgkmcnt(2)
	v_add_f32_e32 v161, v161, v162
	ds_bpermute_b32 v162, v152, v161
	s_waitcnt lgkmcnt(2)
	v_add_f32_e32 v158, v158, v159
	ds_bpermute_b32 v159, v152, v158
	s_waitcnt lgkmcnt(2)
	v_add_f32_e32 v157, v157, v160
	ds_bpermute_b32 v160, v153, v157
	s_waitcnt lgkmcnt(2)
	v_add_f32_e32 v161, v161, v162
	ds_bpermute_b32 v162, v153, v161
	s_waitcnt lgkmcnt(2)
	v_add_f32_e32 v158, v158, v159
	ds_bpermute_b32 v159, v153, v158
	s_waitcnt lgkmcnt(2)
	v_add_f32_e32 v157, v157, v160
	ds_bpermute_b32 v160, v154, v157
	s_waitcnt lgkmcnt(2)
	v_add_f32_e32 v161, v161, v162
	ds_bpermute_b32 v162, v154, v161
	s_waitcnt lgkmcnt(2)
	v_add_f32_e32 v158, v158, v159
	ds_bpermute_b32 v159, v154, v158
	s_waitcnt lgkmcnt(2)
	v_add_f32_e32 v157, v157, v160
	v_fmamk_f32 v157, v157, 0x3a800000, v155
	s_waitcnt lgkmcnt(1)
	v_add_f32_e32 v160, v161, v162
	v_mul_f32_e32 v161, 0x4f800000, v157
	v_cmp_gt_f32_e32 vcc, s3, v157
	v_fmamk_f32 v160, v160, 0x3a800000, v155
	s_waitcnt lgkmcnt(0)
	v_add_f32_e32 v158, v158, v159
	v_cndmask_b32_e32 v157, v157, v161, vcc
	v_mul_f32_e32 v159, 0x4f800000, v160
	v_cmp_gt_f32_e64 s[6:7], s3, v160
	v_sqrt_f32_e32 v161, v157
	v_fmamk_f32 v158, v158, 0x3a800000, v155
	v_cndmask_b32_e64 v159, v160, v159, s[6:7]
	v_mul_f32_e32 v160, 0x4f800000, v158
	v_cmp_gt_f32_e64 s[8:9], s3, v158
	v_sqrt_f32_e32 v162, v159
	v_add_u32_e32 v163, -1, v161
	v_cndmask_b32_e64 v158, v158, v160, s[8:9]
	v_sqrt_f32_e32 v160, v158
	v_add_u32_e32 v164, 1, v161
	v_fma_f32 v165, -v163, v161, v157
	v_fma_f32 v166, -v164, v161, v157
	v_add_u32_e32 v167, -1, v162
	v_cmp_ge_f32_e64 s[10:11], 0, v165
	v_pk_add_f32 v[150:151], v[168:169], v[178:179]
	v_add_u32_e32 v168, 1, v162
	v_cndmask_b32_e64 v161, v161, v163, s[10:11]
	v_fma_f32 v163, -v167, v162, v159
	v_cmp_lt_f32_e64 s[10:11], 0, v166
	v_fma_f32 v165, -v168, v162, v159
	v_add_u32_e32 v169, -1, v160
	v_cndmask_b32_e64 v161, v161, v164, s[10:11]
	v_cmp_ge_f32_e64 s[10:11], 0, v163
	v_add_u32_e32 v170, 1, v160
	v_fma_f32 v163, -v169, v160, v158
	v_cndmask_b32_e64 v162, v162, v167, s[10:11]
	v_cmp_lt_f32_e64 s[10:11], 0, v165
	v_fma_f32 v164, -v170, v160, v158
	v_mul_f32_e32 v165, 0x37800000, v161
	v_cndmask_b32_e64 v162, v162, v168, s[10:11]
	v_cmp_ge_f32_e64 s[10:11], 0, v163
	v_cndmask_b32_e32 v161, v161, v165, vcc
	v_cmp_class_f32_e32 vcc, v157, v156
	v_cndmask_b32_e64 v160, v160, v169, s[10:11]
	v_cmp_lt_f32_e64 s[10:11], 0, v164
	v_mul_f32_e32 v163, 0x37800000, v162
	v_cndmask_b32_e32 v157, v161, v157, vcc
	v_cndmask_b32_e64 v160, v160, v170, s[10:11]
	v_cndmask_b32_e64 v161, v162, v163, s[6:7]
	v_cmp_class_f32_e32 vcc, v159, v156
	v_mul_f32_e32 v162, 0x37800000, v160
	v_div_scale_f32 v163, s[6:7], v157, v157, 1.0
	v_cndmask_b32_e32 v159, v161, v159, vcc
	v_cndmask_b32_e64 v160, v160, v162, s[8:9]
	v_cmp_class_f32_e32 vcc, v158, v156
	v_rcp_f32_e32 v161, v163
	v_div_scale_f32 v162, s[8:9], v159, v159, 1.0
	v_cndmask_b32_e32 v160, v160, v158, vcc
	v_rcp_f32_e32 v166, v162
	v_div_scale_f32 v167, s[10:11], v160, v160, 1.0
	v_rcp_f32_e32 v169, v167
	v_fma_f32 v158, -v163, v161, 1.0
	v_div_scale_f32 v164, s[6:7], 1.0, v157, 1.0
	v_fmac_f32_e32 v161, v158, v161
	v_fma_f32 v158, -v162, v166, 1.0
	v_mul_f32_e32 v170, v164, v161
	v_div_scale_f32 v165, s[8:9], 1.0, v159, 1.0
	v_fmac_f32_e32 v166, v158, v166
	v_fma_f32 v158, -v167, v169, 1.0
	v_fma_f32 v171, -v163, v170, v164
	v_div_scale_f32 v168, s[10:11], 1.0, v160, 1.0
	v_mul_f32_e32 v172, v165, v166
	v_fmac_f32_e32 v169, v158, v169
	v_fmac_f32_e32 v170, v171, v161
	v_fma_f32 v158, -v162, v172, v165
	v_mul_f32_e32 v171, v168, v169
	v_fma_f32 v163, -v163, v170, v164
	s_mov_b64 vcc, s[6:7]
	v_fmac_f32_e32 v172, v158, v166
	v_fma_f32 v158, -v167, v171, v168
	v_div_fmas_f32 v161, v163, v161, v170
	v_fma_f32 v162, -v162, v172, v165
	v_fmac_f32_e32 v171, v158, v169
	v_div_fixup_f32 v158, v161, v157, 1.0
	s_mov_b64 vcc, s[8:9]
	v_div_fmas_f32 v157, v162, v166, v172
	v_fma_f32 v161, -v167, v171, v168
	v_pk_mul_f32 v[80:81], v[80:81], v[158:159] op_sel_hi:[1,0]
	v_pk_mul_f32 v[78:79], v[78:79], v[158:159] op_sel_hi:[1,0]
	s_mov_b64 vcc, s[10:11]
	v_pk_add_f32 v[88:89], v[88:89], 1.0 op_sel_hi:[1,0]
	v_pk_add_f32 v[86:87], v[86:87], 1.0 op_sel_hi:[1,0]
	v_pk_mul_f32 v[76:77], v[76:77], v[158:159] op_sel_hi:[1,0]
	v_pk_mul_f32 v[74:75], v[74:75], v[158:159] op_sel_hi:[1,0]
	v_pk_mul_f32 v[72:73], v[72:73], v[158:159] op_sel_hi:[1,0]
	v_pk_mul_f32 v[70:71], v[70:71], v[158:159] op_sel_hi:[1,0]
	v_pk_mul_f32 v[68:69], v[68:69], v[158:159] op_sel_hi:[1,0]
	v_pk_mul_f32 v[66:67], v[66:67], v[158:159] op_sel_hi:[1,0]
	v_div_fixup_f32 v158, v157, v159, 1.0
	v_div_fmas_f32 v157, v161, v169, v171
	v_pk_mul_f32 v[78:79], v[78:79], v[2:3]
	v_pk_mul_f32 v[80:81], v[80:81], v[4:5]
	v_pk_mul_f32 v[64:65], v[64:65], v[158:159] op_sel_hi:[1,0]
	v_pk_mul_f32 v[62:63], v[62:63], v[158:159] op_sel_hi:[1,0]
	v_pk_mul_f32 v[60:61], v[60:61], v[158:159] op_sel_hi:[1,0]
	v_pk_mul_f32 v[58:59], v[58:59], v[158:159] op_sel_hi:[1,0]
	v_pk_mul_f32 v[56:57], v[56:57], v[158:159] op_sel_hi:[1,0]
	v_pk_mul_f32 v[54:55], v[54:55], v[158:159] op_sel_hi:[1,0]
	v_pk_mul_f32 v[52:53], v[52:53], v[158:159] op_sel_hi:[1,0]
	v_pk_mul_f32 v[158:159], v[50:51], v[158:159] op_sel_hi:[1,0]
	v_div_fixup_f32 v50, v157, v160, 1.0
	v_pk_fma_f32 v[80:81], v[80:81], v[88:89], v[84:85]
	v_pk_fma_f32 v[78:79], v[78:79], v[86:87], v[82:83]
	v_pk_mul_f32 v[86:87], v[52:53], v[16:17]
	v_pk_mul_f32 v[48:49], v[48:49], v[50:51] op_sel_hi:[1,0]
	v_pk_mul_f32 v[46:47], v[46:47], v[50:51] op_sel_hi:[1,0]
	v_pk_mul_f32 v[82:83], v[54:55], v[10:11]
	v_pk_mul_f32 v[84:85], v[158:159], v[14:15]
	v_pk_mul_f32 v[88:89], v[46:47], v[2:3]
	v_pk_mul_f32 v[158:159], v[48:49], v[4:5]
	v_cvt_pk_bf16_f32 v46, v78, v79
	v_cvt_pk_bf16_f32 v47, v80, v81
	global_store_dwordx2 v[102:103], v[46:47], off
	global_load_dwordx4 v[46:49], v[138:139], off
	s_nop 0
	global_load_dwordx4 v[52:55], v[124:125], off offset:1024
	v_pk_mul_f32 v[74:75], v[74:75], v[6:7]
	v_pk_mul_f32 v[76:77], v[76:77], v[8:9]
	v_pk_mul_f32 v[70:71], v[70:71], v[10:11]
	v_pk_mul_f32 v[72:73], v[72:73], v[12:13]
	v_pk_mul_f32 v[66:67], v[66:67], v[14:15]
	v_pk_mul_f32 v[68:69], v[68:69], v[16:17]
	v_pk_mul_f32 v[62:63], v[62:63], v[2:3]
	v_pk_mul_f32 v[64:65], v[64:65], v[4:5]
	v_pk_mul_f32 v[58:59], v[58:59], v[6:7]
	v_pk_mul_f32 v[60:61], v[60:61], v[8:9]
	v_pk_mul_f32 v[56:57], v[56:57], v[12:13]
	v_mul_f32_e32 v180, v23, v23
	v_mul_f32_e32 v186, v25, v25
	v_mul_f32_e32 v197, v18, v18
	v_mul_f32_e32 v198, v19, v19
	v_mul_f32_e32 v199, v20, v20
	v_mul_f32_e32 v200, v21, v21
	v_pk_fma_f32 v[144:145], v[22:23], v[22:23], v[180:181] op_sel_hi:[1,1,0]
	v_pk_fma_f32 v[146:147], v[24:25], v[24:25], v[186:187] op_sel_hi:[1,1,0]
	v_mov_b32_e32 v145, v199
	v_mov_b32_e32 v147, v200
	v_lshl_add_u64 v[94:95], v[94:95], 0, s[18:19]
	s_mov_b32 s8, s25
	s_cmp_lt_i32 s25, s13
	s_waitcnt vmcnt(0) lgkmcnt(0)
	v_pk_add_f32 v[48:49], v[48:49], 1.0 op_sel_hi:[1,0]
	v_pk_add_f32 v[46:47], v[46:47], 1.0 op_sel_hi:[1,0]
	v_pk_fma_f32 v[48:49], v[76:77], v[48:49], v[54:55]
	v_pk_fma_f32 v[46:47], v[74:75], v[46:47], v[52:53]
	v_cvt_pk_bf16_f32 v46, v46, v47
	v_cvt_pk_bf16_f32 v47, v48, v49
	global_store_dwordx2 v[102:103], v[46:47], off offset:512
	global_load_dwordx4 v[46:49], v[134:135], off
	s_nop 0
	global_load_dwordx4 v[52:55], v[124:125], off offset:2048
	s_waitcnt vmcnt(0) lgkmcnt(0)
	v_pk_add_f32 v[48:49], v[48:49], 1.0 op_sel_hi:[1,0]
	v_pk_add_f32 v[46:47], v[46:47], 1.0 op_sel_hi:[1,0]
	v_pk_fma_f32 v[48:49], v[72:73], v[48:49], v[54:55]
	v_pk_fma_f32 v[46:47], v[70:71], v[46:47], v[52:53]
	v_cvt_pk_bf16_f32 v46, v46, v47
	v_cvt_pk_bf16_f32 v47, v48, v49
	global_store_dwordx2 v[102:103], v[46:47], off offset:1024
	global_load_dwordx4 v[46:49], v[128:129], off
	s_nop 0
	global_load_dwordx4 v[52:55], v[124:125], off offset:3072
	s_waitcnt vmcnt(0) lgkmcnt(0)
	v_pk_add_f32 v[48:49], v[48:49], 1.0 op_sel_hi:[1,0]
	v_pk_add_f32 v[46:47], v[46:47], 1.0 op_sel_hi:[1,0]
	v_pk_fma_f32 v[48:49], v[68:69], v[48:49], v[54:55]
	v_pk_fma_f32 v[46:47], v[66:67], v[46:47], v[52:53]
	v_cvt_pk_bf16_f32 v46, v46, v47
	v_cvt_pk_bf16_f32 v47, v48, v49
	global_store_dwordx2 v[102:103], v[46:47], off offset:1536
	global_load_dwordx4 v[46:49], v[126:127], off
	s_nop 0
	global_load_dwordx4 v[52:55], v[110:111], off
	s_waitcnt vmcnt(0) lgkmcnt(0)
	v_pk_add_f32 v[48:49], v[48:49], 1.0 op_sel_hi:[1,0]
	v_pk_add_f32 v[46:47], v[46:47], 1.0 op_sel_hi:[1,0]
	v_pk_fma_f32 v[48:49], v[64:65], v[48:49], v[54:55]
	v_pk_fma_f32 v[46:47], v[62:63], v[46:47], v[52:53]
	v_cvt_pk_bf16_f32 v46, v46, v47
	v_cvt_pk_bf16_f32 v47, v48, v49
	global_store_dwordx2 v[102:103], v[46:47], off offset:2048
	global_load_dwordx4 v[46:49], v[120:121], off
	s_nop 0
	global_load_dwordx4 v[52:55], v[110:111], off offset:1024
	s_waitcnt vmcnt(0) lgkmcnt(0)
	v_pk_add_f32 v[48:49], v[48:49], 1.0 op_sel_hi:[1,0]
	v_pk_add_f32 v[46:47], v[46:47], 1.0 op_sel_hi:[1,0]
	v_pk_fma_f32 v[48:49], v[60:61], v[48:49], v[54:55]
	v_pk_fma_f32 v[46:47], v[58:59], v[46:47], v[52:53]
	v_cvt_pk_bf16_f32 v46, v46, v47
	v_cvt_pk_bf16_f32 v47, v48, v49
	global_store_dwordx2 v[102:103], v[46:47], off offset:2560
	global_load_dwordx4 v[46:49], v[116:117], off
	s_nop 0
	global_load_dwordx4 v[52:55], v[110:111], off offset:2048
	v_pk_add_f32 v[58:59], v[150:151], v[150:151] op_sel:[0,1] op_sel_hi:[1,0]
	v_pk_add_f32 v[60:61], v[144:145], v[146:147]
	v_mov_b32_e32 v59, v198
	s_waitcnt vmcnt(0) lgkmcnt(0)
	v_pk_add_f32 v[48:49], v[48:49], 1.0 op_sel_hi:[1,0]
	v_pk_add_f32 v[46:47], v[46:47], 1.0 op_sel_hi:[1,0]
	v_pk_fma_f32 v[48:49], v[56:57], v[48:49], v[54:55]
	v_pk_fma_f32 v[46:47], v[82:83], v[46:47], v[52:53]
	v_cvt_pk_bf16_f32 v46, v46, v47
	v_cvt_pk_bf16_f32 v47, v48, v49
	global_store_dwordx2 v[102:103], v[46:47], off offset:3072
	global_load_dwordx4 v[46:49], v[112:113], off
	s_nop 0
	global_load_dwordx4 v[52:55], v[110:111], off offset:3072
	v_pk_add_f32 v[56:57], v[148:149], v[148:149] op_sel:[0,1] op_sel_hi:[1,0]
	s_waitcnt vmcnt(0) lgkmcnt(0)
	v_pk_add_f32 v[48:49], v[48:49], 1.0 op_sel_hi:[1,0]
	v_pk_add_f32 v[46:47], v[46:47], 1.0 op_sel_hi:[1,0]
	v_pk_fma_f32 v[48:49], v[86:87], v[48:49], v[54:55]
	v_pk_fma_f32 v[46:47], v[84:85], v[46:47], v[52:53]
	v_cvt_pk_bf16_f32 v46, v46, v47
	v_cvt_pk_bf16_f32 v47, v48, v49
	global_store_dwordx2 v[102:103], v[46:47], off offset:3584
	global_load_dwordx4 v[46:49], v[142:143], off
	s_nop 0
	global_load_dwordx4 v[52:55], v[108:109], off
	v_mov_b32_e32 v57, v197
	s_waitcnt vmcnt(0) lgkmcnt(0)
	v_pk_add_f32 v[48:49], v[48:49], 1.0 op_sel_hi:[1,0]
	v_pk_add_f32 v[46:47], v[46:47], 1.0 op_sel_hi:[1,0]
	v_pk_fma_f32 v[48:49], v[158:159], v[48:49], v[54:55]
	v_pk_fma_f32 v[46:47], v[88:89], v[46:47], v[52:53]
	v_bfe_u32 v51, v46, 16, 1
	v_bfe_u32 v52, v47, 16, 1
	v_add3_u32 v46, v46, v51, s4
	v_add3_u32 v47, v47, v52, s4
	v_lshrrev_b32_e32 v46, 16, v46
	v_and_or_b32 v46, v47, s22, v46
	v_cvt_pk_bf16_f32 v47, v48, v49
	global_store_dwordx2 v[104:105], v[46:47], off
	global_load_dwordx4 v[46:49], v[140:141], off
	s_nop 0
	global_load_dwordx4 v[52:55], v[108:109], off offset:1024
	v_pk_mul_f32 v[44:45], v[44:45], v[50:51] op_sel_hi:[1,0]
	v_pk_mul_f32 v[42:43], v[42:43], v[50:51] op_sel_hi:[1,0]
	v_pk_mul_f32 v[44:45], v[44:45], v[8:9]
	v_pk_mul_f32 v[42:43], v[42:43], v[6:7]
	s_waitcnt vmcnt(0) lgkmcnt(0)
	v_pk_add_f32 v[48:49], v[48:49], 1.0 op_sel_hi:[1,0]
	v_pk_add_f32 v[46:47], v[46:47], 1.0 op_sel_hi:[1,0]
	v_pk_fma_f32 v[44:45], v[44:45], v[48:49], v[54:55]
	v_pk_fma_f32 v[42:43], v[42:43], v[46:47], v[52:53]
	v_cvt_pk_bf16_f32 v42, v42, v43
	v_cvt_pk_bf16_f32 v43, v44, v45
	global_store_dwordx2 v[104:105], v[42:43], off offset:512
	global_load_dwordx4 v[42:45], v[136:137], off
	s_nop 0
	global_load_dwordx4 v[46:49], v[108:109], off offset:2048
	v_pk_add_f32 v[52:53], v[56:57], v[58:59]
	s_waitcnt vmcnt(0) lgkmcnt(0)
	v_pk_add_f32 v[44:45], v[44:45], 1.0 op_sel_hi:[1,0]
	v_pk_add_f32 v[52:53], v[52:53], v[60:61]
	v_pk_add_f32 v[42:43], v[42:43], 1.0 op_sel_hi:[1,0]
	v_add_f32_e32 v51, v52, v53
	ds_bpermute_b32 v52, v1, v51
	s_waitcnt lgkmcnt(0)
	v_add_f32_e32 v51, v51, v52
	ds_bpermute_b32 v52, v131, v51
	s_waitcnt lgkmcnt(0)
	v_add_f32_e32 v51, v51, v52
	v_pk_mul_f32 v[40:41], v[40:41], v[50:51] op_sel_hi:[1,0]
	v_pk_mul_f32 v[38:39], v[38:39], v[50:51] op_sel_hi:[1,0]
	v_pk_mul_f32 v[40:41], v[40:41], v[12:13]
	v_pk_mul_f32 v[38:39], v[38:39], v[10:11]
	v_pk_fma_f32 v[40:41], v[40:41], v[44:45], v[48:49]
	v_pk_fma_f32 v[38:39], v[38:39], v[42:43], v[46:47]
	v_cvt_pk_bf16_f32 v38, v38, v39
	v_cvt_pk_bf16_f32 v39, v40, v41
	global_store_dwordx2 v[104:105], v[38:39], off offset:1024
	global_load_dwordx4 v[38:41], v[122:123], off
	s_nop 0
	global_load_dwordx4 v[42:45], v[108:109], off offset:3072
	v_pk_mul_f32 v[36:37], v[36:37], v[50:51] op_sel_hi:[1,0]
	v_pk_mul_f32 v[34:35], v[34:35], v[50:51] op_sel_hi:[1,0]
	v_pk_mul_f32 v[36:37], v[36:37], v[16:17]
	v_pk_mul_f32 v[34:35], v[34:35], v[14:15]
	ds_bpermute_b32 v46, v133, v51
	s_waitcnt lgkmcnt(0)
	v_add_f32_e32 v46, v51, v46
	ds_bpermute_b32 v47, v152, v46
	s_waitcnt lgkmcnt(0)
	v_add_f32_e32 v46, v46, v47
	ds_bpermute_b32 v47, v153, v46
	s_waitcnt lgkmcnt(0)
	v_add_f32_e32 v46, v46, v47
	ds_bpermute_b32 v47, v154, v46
	s_waitcnt lgkmcnt(0)
	v_add_f32_e32 v46, v46, v47
	v_fmamk_f32 v46, v46, 0x3a800000, v155
	v_mul_f32_e32 v47, 0x4f800000, v46
	v_cmp_gt_f32_e32 vcc, s3, v46
	s_waitcnt vmcnt(0)
	v_pk_add_f32 v[40:41], v[40:41], 1.0 op_sel_hi:[1,0]
	v_pk_add_f32 v[38:39], v[38:39], 1.0 op_sel_hi:[1,0]
	v_pk_fma_f32 v[36:37], v[36:37], v[40:41], v[44:45]
	v_pk_fma_f32 v[34:35], v[34:35], v[38:39], v[42:43]
	v_cvt_pk_bf16_f32 v34, v34, v35
	v_cvt_pk_bf16_f32 v35, v36, v37
	global_store_dwordx2 v[104:105], v[34:35], off offset:1536
	global_load_dwordx4 v[34:37], v[118:119], off
	s_nop 0
	global_load_dwordx4 v[38:41], v[106:107], off
	v_cndmask_b32_e32 v42, v46, v47, vcc
	v_sqrt_f32_e32 v43, v42
	s_waitcnt vmcnt(0) lgkmcnt(0)
	v_pk_add_f32 v[36:37], v[36:37], 1.0 op_sel_hi:[1,0]
	v_add_u32_e32 v44, -1, v43
	v_add_u32_e32 v45, 1, v43
	v_fma_f32 v46, -v44, v43, v42
	v_fma_f32 v47, -v45, v43, v42
	v_cmp_ge_f32_e64 s[6:7], 0, v46
	v_pk_add_f32 v[34:35], v[34:35], 1.0 op_sel_hi:[1,0]
	s_nop 0
	v_cndmask_b32_e64 v43, v43, v44, s[6:7]
	v_cmp_lt_f32_e64 s[6:7], 0, v47
	s_nop 1
	v_cndmask_b32_e64 v43, v43, v45, s[6:7]
	v_mul_f32_e32 v44, 0x37800000, v43
	v_cndmask_b32_e32 v43, v43, v44, vcc
	v_cmp_class_f32_e32 vcc, v42, v156
	s_nop 1
	v_cndmask_b32_e32 v42, v43, v42, vcc
	v_div_scale_f32 v43, s[6:7], v42, v42, 1.0
	v_rcp_f32_e32 v45, v43
	v_div_scale_f32 v44, vcc, 1.0, v42, 1.0
	v_fma_f32 v46, -v43, v45, 1.0
	v_fmac_f32_e32 v45, v46, v45
	v_mul_f32_e32 v46, v44, v45
	v_fma_f32 v47, -v43, v46, v44
	v_fmac_f32_e32 v46, v47, v45
	v_fma_f32 v43, -v43, v46, v44
	v_div_fmas_f32 v43, v43, v45, v46
	v_div_fixup_f32 v42, v43, v42, 1.0
	v_pk_mul_f32 v[32:33], v[32:33], v[42:43] op_sel_hi:[1,0]
	v_pk_mul_f32 v[30:31], v[30:31], v[42:43] op_sel_hi:[1,0]
	v_pk_mul_f32 v[32:33], v[32:33], v[4:5]
	v_pk_mul_f32 v[30:31], v[30:31], v[2:3]
	v_pk_fma_f32 v[32:33], v[32:33], v[36:37], v[40:41]
	v_pk_fma_f32 v[30:31], v[30:31], v[34:35], v[38:39]
	v_cvt_pk_bf16_f32 v30, v30, v31
	v_cvt_pk_bf16_f32 v31, v32, v33
	global_store_dwordx2 v[104:105], v[30:31], off offset:2048
	global_load_dwordx4 v[30:33], v[114:115], off
	s_nop 0
	global_load_dwordx4 v[34:37], v[106:107], off offset:1024
	v_pk_mul_f32 v[28:29], v[28:29], v[42:43] op_sel_hi:[1,0]
	v_pk_mul_f32 v[26:27], v[26:27], v[42:43] op_sel_hi:[1,0]
	v_pk_mul_f32 v[28:29], v[28:29], v[8:9]
	v_pk_mul_f32 v[26:27], v[26:27], v[6:7]
	v_lshl_add_u64 v[38:39], s[20:21], 0, v[98:99]
	v_pk_mul_f32 v[24:25], v[24:25], v[42:43] op_sel_hi:[1,0]
	v_pk_mul_f32 v[22:23], v[22:23], v[42:43] op_sel_hi:[1,0]
	v_pk_mul_f32 v[24:25], v[24:25], v[12:13]
	v_pk_mul_f32 v[22:23], v[22:23], v[10:11]
	v_pk_mul_f32 v[20:21], v[20:21], v[42:43] op_sel_hi:[1,0]
	v_pk_mul_f32 v[18:19], v[18:19], v[42:43] op_sel_hi:[1,0]
	v_pk_mul_f32 v[20:21], v[20:21], v[16:17]
	v_pk_mul_f32 v[18:19], v[18:19], v[14:15]
	s_waitcnt vmcnt(0) lgkmcnt(0)
	v_pk_add_f32 v[32:33], v[32:33], 1.0 op_sel_hi:[1,0]
	v_pk_add_f32 v[30:31], v[30:31], 1.0 op_sel_hi:[1,0]
	v_pk_fma_f32 v[28:29], v[28:29], v[32:33], v[36:37]
	v_pk_fma_f32 v[26:27], v[26:27], v[30:31], v[34:35]
	v_cvt_pk_bf16_f32 v26, v26, v27
	v_cvt_pk_bf16_f32 v27, v28, v29
	global_store_dwordx2 v[104:105], v[26:27], off offset:2560
	global_load_dwordx4 v[26:29], v[38:39], off
	s_nop 0
	global_load_dwordx4 v[30:33], v[106:107], off offset:2048
	v_lshl_add_u64 v[34:35], s[20:21], 0, v[100:101]
	s_waitcnt vmcnt(0) lgkmcnt(0)
	v_pk_add_f32 v[28:29], v[28:29], 1.0 op_sel_hi:[1,0]
	v_pk_add_f32 v[26:27], v[26:27], 1.0 op_sel_hi:[1,0]
	v_pk_fma_f32 v[24:25], v[24:25], v[28:29], v[32:33]
	v_pk_fma_f32 v[22:23], v[22:23], v[26:27], v[30:31]
	v_cvt_pk_bf16_f32 v22, v22, v23
	v_cvt_pk_bf16_f32 v23, v24, v25
	global_store_dwordx2 v[104:105], v[22:23], off offset:3072
	global_load_dwordx4 v[22:25], v[34:35], off
	s_nop 0
	global_load_dwordx4 v[26:29], v[106:107], off offset:3072
	s_waitcnt vmcnt(0) lgkmcnt(0)
	v_pk_add_f32 v[24:25], v[24:25], 1.0 op_sel_hi:[1,0]
	v_pk_add_f32 v[22:23], v[22:23], 1.0 op_sel_hi:[1,0]
	v_pk_fma_f32 v[20:21], v[20:21], v[24:25], v[28:29]
	v_pk_fma_f32 v[18:19], v[18:19], v[22:23], v[26:27]
	v_cvt_pk_bf16_f32 v18, v18, v19
	v_cvt_pk_bf16_f32 v19, v20, v21
	global_store_dwordx2 v[104:105], v[18:19], off offset:3584
	s_cbranch_scc1 .LBB0_3611

.LBB0_3685:
	v_mov_b32_e32 v138, v1
	v_mov_b32_e32 v145, v131
	s_lshl_b32 s6, s14, 8
	s_add_i32 s6, s6, s57
	v_add_u32_e32 v154, s6, v138
	v_lshlrev_b32_e32 v138, 6, v138
	v_lshl_add_u32 v146, v145, 2, s70
	v_and_b32_e32 v145, 0x3c0, v138
	v_ashrrev_i32_e32 v138, 10, v154
	v_ashrrev_i32_e32 v155, 31, v154
	v_and_b32_e32 v168, -2, v138
	v_lshrrev_b32_e32 v138, 3, v154
	v_lshlrev_b64 v[158:159], 9, v[154:155]
	v_lshlrev_b64 v[156:157], 10, v[154:155]
	v_and_b32_e32 v155, 0xfe, v138
	v_and_b32_e32 v138, 0x1fff, v154
	s_cmp_gt_i32 s10, 1
	v_cmp_lt_u32_e64 s[8:9], s77, v138
	v_add_u32_e32 v138, 0xffffe200, v138
	s_cselect_b64 s[68:69], -1, 0
	s_cmp_lt_i32 s10, 2
	v_ashrrev_i32_e32 v160, 13, v154
	v_lshlrev_b64 v[162:163], 10, v[138:139]
	s_mov_b64 s[6:7], -1
	s_cbranch_scc1 .LBB0_3697
	v_cvt_pk_bf16_f32 v148, v126, v127
	v_cvt_pk_bf16_f32 v149, v128, v129
	s_cmp_lt_i32 s10, 3
	s_cbranch_scc1 .LBB0_3694
	s_cmp_lg_u32 s10, 3
	s_cbranch_scc0 .LBB0_3691
	v_lshlrev_b32_e32 v152, 1, v146
	v_lshl_add_u64 v[150:151], s[50:51], 0, v[158:159]
	v_ashrrev_i32_e32 v153, 31, v152
	v_lshl_add_u64 v[150:151], v[150:151], 0, v[152:153]
	global_store_dwordx2 v[150:151], v[148:149], off
	s_and_saveexec_b64 s[6:7], s[8:9]
	s_cbranch_execz .LBB0_3690
	v_ashrrev_i32_e32 v161, 31, v160
	v_lshlrev_b64 v[150:151], 19, v[160:161]
	v_lshl_add_u64 v[150:151], s[52:53], 0, v[150:151]
	v_lshl_add_u64 v[150:151], v[150:151], 0, v[162:163]
	v_ashrrev_i32_e32 v147, 31, v146
	v_lshl_add_u64 v[150:151], v[146:147], 2, v[150:151]
	v_add_co_u32_e32 v150, vcc, 0x100000, v150
	s_nop 1
	v_addc_co_u32_e32 v151, vcc, 0, v151, vcc
	global_store_dwordx4 v[150:151], v[126:129], off

.LBB0_3699:
	v_cndmask_b32_e64 v138, 0, 1, s[68:69]
	v_add_u32_e32 v178, 16, v146
	v_cmp_ne_u32_e64 s[6:7], 1, v138
	s_andn2_b64 vcc, exec, s[68:69]
	s_mov_b64 s[68:69], -1
	s_cbranch_vccnz .LBB0_3735
	v_cvt_pk_bf16_f32 v150, v122, v123
	v_cvt_pk_bf16_f32 v151, v124, v125
	s_cmp_lt_i32 s10, 3
	s_cbranch_scc1 .LBB0_3708
	s_cmp_lg_u32 s10, 3
	s_cbranch_scc0 .LBB0_3705
	v_lshlrev_b32_e32 v166, 1, v178
	v_lshl_add_u64 v[152:153], s[50:51], 0, v[158:159]
	v_ashrrev_i32_e32 v167, 31, v166
	v_lshl_add_u64 v[152:153], v[152:153], 0, v[166:167]
	global_store_dwordx2 v[152:153], v[150:151], off
	s_and_saveexec_b64 s[68:69], s[8:9]
	s_cbranch_execz .LBB0_3704
	v_ashrrev_i32_e32 v161, 31, v160
	v_lshlrev_b64 v[152:153], 19, v[160:161]
	v_lshl_add_u64 v[152:153], s[52:53], 0, v[152:153]
	v_lshl_add_u64 v[152:153], v[152:153], 0, v[162:163]
	v_ashrrev_i32_e32 v147, 31, v146
	v_lshl_add_u64 v[152:153], v[146:147], 2, v[152:153]
	v_add_co_u32_e32 v152, vcc, 0x100000, v152
	s_nop 1
	v_addc_co_u32_e32 v153, vcc, 0, v153, vcc
	global_store_dwordx4 v[152:153], v[122:125], off offset:64

.LBB0_3712:
	v_cvt_pk_bf16_f32 v152, v106, v107
	v_cvt_pk_bf16_f32 v153, v108, v109
	s_cmp_lt_i32 s10, 3
	s_cbranch_scc1 .LBB0_3720
	s_cmp_lg_u32 s10, 3
	s_cbranch_scc0 .LBB0_3717
	v_lshlrev_b32_e32 v182, 1, v180
	v_lshl_add_u64 v[166:167], s[50:51], 0, v[158:159]
	v_ashrrev_i32_e32 v183, 31, v182
	v_lshl_add_u64 v[166:167], v[166:167], 0, v[182:183]
	global_store_dwordx2 v[166:167], v[152:153], off
	s_and_saveexec_b64 s[68:69], s[8:9]
	s_cbranch_execz .LBB0_3716
	v_ashrrev_i32_e32 v161, 31, v160
	v_lshlrev_b64 v[166:167], 19, v[160:161]
	v_lshl_add_u64 v[166:167], s[52:53], 0, v[166:167]
	v_lshl_add_u64 v[166:167], v[166:167], 0, v[162:163]
	v_ashrrev_i32_e32 v147, 31, v146
	v_lshl_add_u64 v[166:167], v[146:147], 2, v[166:167]
	v_add_co_u32_e32 v166, vcc, 0x100000, v166
	s_nop 1
	v_addc_co_u32_e32 v167, vcc, 0, v167, vcc
	global_store_dwordx4 v[166:167], v[106:109], off offset:512

.LBB0_3724:
	v_cvt_pk_bf16_f32 v166, v98, v99
	v_cvt_pk_bf16_f32 v167, v100, v101
	s_cmp_lt_i32 s10, 3
	s_cbranch_scc1 .LBB0_3732
	s_cmp_lg_u32 s10, 3
	s_cbranch_scc0 .LBB0_3729
	v_lshlrev_b32_e32 v184, 1, v179
	v_lshl_add_u64 v[182:183], s[50:51], 0, v[158:159]
	v_ashrrev_i32_e32 v185, 31, v184
	v_lshl_add_u64 v[182:183], v[182:183], 0, v[184:185]
	global_store_dwordx2 v[182:183], v[166:167], off
	s_and_saveexec_b64 s[68:69], s[8:9]
	s_cbranch_execz .LBB0_3728
	v_ashrrev_i32_e32 v161, 31, v160
	v_lshlrev_b64 v[160:161], 19, v[160:161]
	v_lshl_add_u64 v[160:161], s[52:53], 0, v[160:161]
	v_lshl_add_u64 v[160:161], v[160:161], 0, v[162:163]
	v_ashrrev_i32_e32 v147, 31, v146
	v_lshl_add_u64 v[160:161], v[146:147], 2, v[160:161]
	v_add_co_u32_e32 v160, vcc, 0x100000, v160
	s_nop 1
	v_addc_co_u32_e32 v161, vcc, 0, v161, vcc
	global_store_dwordx4 v[160:161], v[98:101], off offset:576

.LBB0_3741:
	v_add_u32_e32 v162, 16, v154
	v_ashrrev_i32_e32 v138, 10, v162
	v_and_b32_e32 v181, -2, v138
	v_lshrrev_b32_e32 v138, 3, v162
	v_and_b32_e32 v155, 0xfe, v138
	v_and_b32_e32 v138, 0x1fff, v162
	v_ashrrev_i32_e32 v163, 31, v162
	v_cmp_lt_u32_e64 s[8:9], s77, v138
	v_add_u32_e32 v138, 0xffffe200, v138
	v_lshlrev_b64 v[160:161], 9, v[162:163]
	v_lshlrev_b64 v[158:159], 10, v[162:163]
	v_ashrrev_i32_e32 v162, 13, v162
	v_lshlrev_b64 v[164:165], 10, v[138:139]
	s_and_b64 vcc, exec, s[6:7]
	s_mov_b64 s[68:69], -1
	s_cbranch_vccnz .LBB0_3789
	v_cvt_pk_bf16_f32 v166, v118, v119
	v_cvt_pk_bf16_f32 v167, v120, v121
	s_cmp_lt_i32 s10, 3
	s_cbranch_scc1 .LBB0_3750
	s_cmp_lg_u32 s10, 3
	s_cbranch_scc0 .LBB0_3747
	v_lshlrev_b32_e32 v182, 1, v146
	v_lshl_add_u64 v[168:169], s[50:51], 0, v[160:161]
	v_ashrrev_i32_e32 v183, 31, v182
	v_lshl_add_u64 v[168:169], v[168:169], 0, v[182:183]
	global_store_dwordx2 v[168:169], v[166:167], off
	s_and_saveexec_b64 s[68:69], s[8:9]
	s_cbranch_execz .LBB0_3746
	v_ashrrev_i32_e32 v163, 31, v162
	v_lshlrev_b64 v[168:169], 19, v[162:163]
	v_lshl_add_u64 v[168:169], s[52:53], 0, v[168:169]
	v_lshl_add_u64 v[168:169], v[168:169], 0, v[164:165]
	v_ashrrev_i32_e32 v147, 31, v146
	v_lshl_add_u64 v[168:169], v[146:147], 2, v[168:169]
	v_add_co_u32_e32 v168, vcc, 0x100000, v168
	s_nop 1
	v_addc_co_u32_e32 v169, vcc, 0, v169, vcc
	global_store_dwordx4 v[168:169], v[118:121], off

.LBB0_3754:
	v_cvt_pk_bf16_f32 v168, v114, v115
	v_cvt_pk_bf16_f32 v169, v116, v117
	s_cmp_lt_i32 s10, 3
	s_cbranch_scc1 .LBB0_3762
	s_cmp_lg_u32 s10, 3
	s_cbranch_scc0 .LBB0_3759
	v_lshlrev_b32_e32 v184, 1, v178
	v_lshl_add_u64 v[182:183], s[50:51], 0, v[160:161]
	v_ashrrev_i32_e32 v185, 31, v184
	v_lshl_add_u64 v[182:183], v[182:183], 0, v[184:185]
	global_store_dwordx2 v[182:183], v[168:169], off
	s_and_saveexec_b64 s[68:69], s[8:9]
	s_cbranch_execz .LBB0_3758
	v_ashrrev_i32_e32 v163, 31, v162
	v_lshlrev_b64 v[182:183], 19, v[162:163]
	v_lshl_add_u64 v[182:183], s[52:53], 0, v[182:183]
	v_lshl_add_u64 v[182:183], v[182:183], 0, v[164:165]
	v_ashrrev_i32_e32 v147, 31, v146
	v_lshl_add_u64 v[182:183], v[146:147], 2, v[182:183]
	v_add_co_u32_e32 v182, vcc, 0x100000, v182
	s_nop 1
	v_addc_co_u32_e32 v183, vcc, 0, v183, vcc
	global_store_dwordx4 v[182:183], v[114:117], off offset:64

.LBB0_3766:
	v_cvt_pk_bf16_f32 v168, v90, v91
	v_cvt_pk_bf16_f32 v169, v92, v93
	s_cmp_lt_i32 s10, 3
	s_cbranch_scc1 .LBB0_3774
	s_cmp_lg_u32 s10, 3
	s_cbranch_scc0 .LBB0_3771
	v_lshlrev_b32_e32 v184, 1, v180
	v_lshl_add_u64 v[182:183], s[50:51], 0, v[160:161]
	v_ashrrev_i32_e32 v185, 31, v184
	v_lshl_add_u64 v[182:183], v[182:183], 0, v[184:185]
	global_store_dwordx2 v[182:183], v[168:169], off
	s_and_saveexec_b64 s[68:69], s[8:9]
	s_cbranch_execz .LBB0_3770
	v_ashrrev_i32_e32 v163, 31, v162
	v_lshlrev_b64 v[182:183], 19, v[162:163]
	v_lshl_add_u64 v[182:183], s[52:53], 0, v[182:183]
	v_lshl_add_u64 v[182:183], v[182:183], 0, v[164:165]
	v_ashrrev_i32_e32 v147, 31, v146
	v_lshl_add_u64 v[182:183], v[146:147], 2, v[182:183]
	v_add_co_u32_e32 v182, vcc, 0x100000, v182
	s_nop 1
	v_addc_co_u32_e32 v183, vcc, 0, v183, vcc
	global_store_dwordx4 v[182:183], v[90:93], off offset:512

.LBB0_3778:
	v_cvt_pk_bf16_f32 v168, v82, v83
	v_cvt_pk_bf16_f32 v169, v84, v85
	s_cmp_lt_i32 s10, 3
	s_cbranch_scc1 .LBB0_3786
	s_cmp_lg_u32 s10, 3
	s_cbranch_scc0 .LBB0_3783
	v_lshlrev_b32_e32 v184, 1, v179
	v_lshl_add_u64 v[182:183], s[50:51], 0, v[160:161]
	v_ashrrev_i32_e32 v185, 31, v184
	v_lshl_add_u64 v[182:183], v[182:183], 0, v[184:185]
	global_store_dwordx2 v[182:183], v[168:169], off
	s_and_saveexec_b64 s[68:69], s[8:9]
	s_cbranch_execz .LBB0_3782
	v_ashrrev_i32_e32 v163, 31, v162
	v_lshlrev_b64 v[162:163], 19, v[162:163]
	v_lshl_add_u64 v[162:163], s[52:53], 0, v[162:163]
	v_lshl_add_u64 v[162:163], v[162:163], 0, v[164:165]
	v_ashrrev_i32_e32 v147, 31, v146
	v_lshl_add_u64 v[162:163], v[146:147], 2, v[162:163]
	v_add_co_u32_e32 v162, vcc, 0x100000, v162
	s_nop 1
	v_addc_co_u32_e32 v163, vcc, 0, v163, vcc
	global_store_dwordx4 v[162:163], v[82:85], off offset:576

.LBB0_3797:
	v_add_u32_e32 v162, 32, v154
	v_ashrrev_i32_e32 v138, 10, v162
	v_and_b32_e32 v181, -2, v138
	v_lshrrev_b32_e32 v138, 3, v162
	v_and_b32_e32 v155, 0xfe, v138
	v_and_b32_e32 v138, 0x1fff, v162
	v_ashrrev_i32_e32 v163, 31, v162
	v_cmp_lt_u32_e64 s[8:9], s77, v138
	v_add_u32_e32 v138, 0xffffe200, v138
	v_lshlrev_b64 v[160:161], 9, v[162:163]
	v_lshlrev_b64 v[158:159], 10, v[162:163]
	v_ashrrev_i32_e32 v162, 13, v162
	v_lshlrev_b64 v[164:165], 10, v[138:139]
	s_and_b64 vcc, exec, s[6:7]
	s_mov_b64 s[68:69], -1
	s_cbranch_vccnz .LBB0_3845
	v_cvt_pk_bf16_f32 v166, v110, v111
	v_cvt_pk_bf16_f32 v167, v112, v113
	s_cmp_lt_i32 s10, 3
	s_cbranch_scc1 .LBB0_3806
	s_cmp_lg_u32 s10, 3
	s_cbranch_scc0 .LBB0_3803
	v_lshlrev_b32_e32 v182, 1, v146
	v_lshl_add_u64 v[168:169], s[50:51], 0, v[160:161]
	v_ashrrev_i32_e32 v183, 31, v182
	v_lshl_add_u64 v[168:169], v[168:169], 0, v[182:183]
	global_store_dwordx2 v[168:169], v[166:167], off
	s_and_saveexec_b64 s[68:69], s[8:9]
	s_cbranch_execz .LBB0_3802
	v_ashrrev_i32_e32 v163, 31, v162
	v_lshlrev_b64 v[168:169], 19, v[162:163]
	v_lshl_add_u64 v[168:169], s[52:53], 0, v[168:169]
	v_lshl_add_u64 v[168:169], v[168:169], 0, v[164:165]
	v_ashrrev_i32_e32 v147, 31, v146
	v_lshl_add_u64 v[168:169], v[146:147], 2, v[168:169]
	v_add_co_u32_e32 v168, vcc, 0x100000, v168
	s_nop 1
	v_addc_co_u32_e32 v169, vcc, 0, v169, vcc
	global_store_dwordx4 v[168:169], v[110:113], off

.LBB0_3810:
	v_cvt_pk_bf16_f32 v168, v102, v103
	v_cvt_pk_bf16_f32 v169, v104, v105
	s_cmp_lt_i32 s10, 3
	s_cbranch_scc1 .LBB0_3818
	s_cmp_lg_u32 s10, 3
	s_cbranch_scc0 .LBB0_3815
	v_lshlrev_b32_e32 v184, 1, v178
	v_lshl_add_u64 v[182:183], s[50:51], 0, v[160:161]
	v_ashrrev_i32_e32 v185, 31, v184
	v_lshl_add_u64 v[182:183], v[182:183], 0, v[184:185]
	global_store_dwordx2 v[182:183], v[168:169], off
	s_and_saveexec_b64 s[68:69], s[8:9]
	s_cbranch_execz .LBB0_3814
	v_ashrrev_i32_e32 v163, 31, v162
	v_lshlrev_b64 v[182:183], 19, v[162:163]
	v_lshl_add_u64 v[182:183], s[52:53], 0, v[182:183]
	v_lshl_add_u64 v[182:183], v[182:183], 0, v[164:165]
	v_ashrrev_i32_e32 v147, 31, v146
	v_lshl_add_u64 v[182:183], v[146:147], 2, v[182:183]
	v_add_co_u32_e32 v182, vcc, 0x100000, v182
	s_nop 1
	v_addc_co_u32_e32 v183, vcc, 0, v183, vcc
	global_store_dwordx4 v[182:183], v[102:105], off offset:64

.LBB0_3822:
	v_cvt_pk_bf16_f32 v168, v78, v79
	v_cvt_pk_bf16_f32 v169, v80, v81
	s_cmp_lt_i32 s10, 3
	s_cbranch_scc1 .LBB0_3830
	s_cmp_lg_u32 s10, 3
	s_cbranch_scc0 .LBB0_3827
	v_lshlrev_b32_e32 v184, 1, v180
	v_lshl_add_u64 v[182:183], s[50:51], 0, v[160:161]
	v_ashrrev_i32_e32 v185, 31, v184
	v_lshl_add_u64 v[182:183], v[182:183], 0, v[184:185]
	global_store_dwordx2 v[182:183], v[168:169], off
	s_and_saveexec_b64 s[68:69], s[8:9]
	s_cbranch_execz .LBB0_3826
	v_ashrrev_i32_e32 v163, 31, v162
	v_lshlrev_b64 v[182:183], 19, v[162:163]
	v_lshl_add_u64 v[182:183], s[52:53], 0, v[182:183]
	v_lshl_add_u64 v[182:183], v[182:183], 0, v[164:165]
	v_ashrrev_i32_e32 v147, 31, v146
	v_lshl_add_u64 v[182:183], v[146:147], 2, v[182:183]
	v_add_co_u32_e32 v182, vcc, 0x100000, v182
	s_nop 1
	v_addc_co_u32_e32 v183, vcc, 0, v183, vcc
	global_store_dwordx4 v[182:183], v[78:81], off offset:512

.LBB0_3834:
	v_cvt_pk_bf16_f32 v168, v74, v75
	v_cvt_pk_bf16_f32 v169, v76, v77
	s_cmp_lt_i32 s10, 3
	s_cbranch_scc1 .LBB0_3842
	s_cmp_lg_u32 s10, 3
	s_cbranch_scc0 .LBB0_3839
	v_lshlrev_b32_e32 v184, 1, v179
	v_lshl_add_u64 v[182:183], s[50:51], 0, v[160:161]
	v_ashrrev_i32_e32 v185, 31, v184
	v_lshl_add_u64 v[182:183], v[182:183], 0, v[184:185]
	global_store_dwordx2 v[182:183], v[168:169], off
	s_and_saveexec_b64 s[68:69], s[8:9]
	s_cbranch_execz .LBB0_3838
	v_ashrrev_i32_e32 v163, 31, v162
	v_lshlrev_b64 v[162:163], 19, v[162:163]
	v_lshl_add_u64 v[162:163], s[52:53], 0, v[162:163]
	v_lshl_add_u64 v[162:163], v[162:163], 0, v[164:165]
	v_ashrrev_i32_e32 v147, 31, v146
	v_lshl_add_u64 v[162:163], v[146:147], 2, v[162:163]
	v_add_co_u32_e32 v162, vcc, 0x100000, v162
	s_nop 1
	v_addc_co_u32_e32 v163, vcc, 0, v163, vcc
	global_store_dwordx4 v[162:163], v[74:77], off offset:576

.LBB0_3853:
	v_add_u32_e32 v162, 48, v154
	v_ashrrev_i32_e32 v138, 10, v162
	v_and_b32_e32 v181, -2, v138
	v_lshrrev_b32_e32 v138, 3, v162
	v_and_b32_e32 v155, 0xfe, v138
	v_and_b32_e32 v138, 0x1fff, v162
	v_ashrrev_i32_e32 v163, 31, v162
	v_cmp_lt_u32_e64 s[8:9], s77, v138
	v_add_u32_e32 v138, 0xffffe200, v138
	v_lshlrev_b64 v[160:161], 9, v[162:163]
	v_lshlrev_b64 v[158:159], 10, v[162:163]
	v_ashrrev_i32_e32 v162, 13, v162
	v_lshlrev_b64 v[164:165], 10, v[138:139]
	s_and_b64 vcc, exec, s[6:7]
	s_mov_b64 s[68:69], -1
	s_cbranch_vccnz .LBB0_3901
	v_cvt_pk_bf16_f32 v166, v94, v95
	v_cvt_pk_bf16_f32 v167, v96, v97
	s_cmp_lt_i32 s10, 3
	s_cbranch_scc1 .LBB0_3862
	s_cmp_lg_u32 s10, 3
	s_cbranch_scc0 .LBB0_3859
	v_lshlrev_b32_e32 v182, 1, v146
	v_lshl_add_u64 v[168:169], s[50:51], 0, v[160:161]
	v_ashrrev_i32_e32 v183, 31, v182
	v_lshl_add_u64 v[168:169], v[168:169], 0, v[182:183]
	global_store_dwordx2 v[168:169], v[166:167], off
	s_and_saveexec_b64 s[68:69], s[8:9]
	s_cbranch_execz .LBB0_3858
	v_ashrrev_i32_e32 v163, 31, v162
	v_lshlrev_b64 v[168:169], 19, v[162:163]
	v_lshl_add_u64 v[168:169], s[52:53], 0, v[168:169]
	v_lshl_add_u64 v[168:169], v[168:169], 0, v[164:165]
	v_ashrrev_i32_e32 v147, 31, v146
	v_lshl_add_u64 v[168:169], v[146:147], 2, v[168:169]
	v_add_co_u32_e32 v168, vcc, 0x100000, v168
	s_nop 1
	v_addc_co_u32_e32 v169, vcc, 0, v169, vcc
	global_store_dwordx4 v[168:169], v[94:97], off

.LBB0_3866:
	v_cvt_pk_bf16_f32 v168, v86, v87
	v_cvt_pk_bf16_f32 v169, v88, v89
	s_cmp_lt_i32 s10, 3
	s_cbranch_scc1 .LBB0_3874
	s_cmp_lg_u32 s10, 3
	s_cbranch_scc0 .LBB0_3871
	v_lshlrev_b32_e32 v184, 1, v178
	v_lshl_add_u64 v[182:183], s[50:51], 0, v[160:161]
	v_ashrrev_i32_e32 v185, 31, v184
	v_lshl_add_u64 v[182:183], v[182:183], 0, v[184:185]
	global_store_dwordx2 v[182:183], v[168:169], off
	s_and_saveexec_b64 s[68:69], s[8:9]
	s_cbranch_execz .LBB0_3870
	v_ashrrev_i32_e32 v163, 31, v162
	v_lshlrev_b64 v[182:183], 19, v[162:163]
	v_lshl_add_u64 v[182:183], s[52:53], 0, v[182:183]
	v_lshl_add_u64 v[182:183], v[182:183], 0, v[164:165]
	v_ashrrev_i32_e32 v147, 31, v146
	v_lshl_add_u64 v[182:183], v[146:147], 2, v[182:183]
	v_add_co_u32_e32 v182, vcc, 0x100000, v182
	s_nop 1
	v_addc_co_u32_e32 v183, vcc, 0, v183, vcc
	global_store_dwordx4 v[182:183], v[86:89], off offset:64

.LBB0_3878:
	v_cvt_pk_bf16_f32 v168, v70, v71
	v_cvt_pk_bf16_f32 v169, v72, v73
	s_cmp_lt_i32 s10, 3
	s_cbranch_scc1 .LBB0_3886
	s_cmp_lg_u32 s10, 3
	s_cbranch_scc0 .LBB0_3883
	v_lshlrev_b32_e32 v184, 1, v180
	v_lshl_add_u64 v[182:183], s[50:51], 0, v[160:161]
	v_ashrrev_i32_e32 v185, 31, v184
	v_lshl_add_u64 v[182:183], v[182:183], 0, v[184:185]
	global_store_dwordx2 v[182:183], v[168:169], off
	s_and_saveexec_b64 s[68:69], s[8:9]
	s_cbranch_execz .LBB0_3882
	v_ashrrev_i32_e32 v163, 31, v162
	v_lshlrev_b64 v[182:183], 19, v[162:163]
	v_lshl_add_u64 v[182:183], s[52:53], 0, v[182:183]
	v_lshl_add_u64 v[182:183], v[182:183], 0, v[164:165]
	v_ashrrev_i32_e32 v147, 31, v146
	v_lshl_add_u64 v[182:183], v[146:147], 2, v[182:183]
	v_add_co_u32_e32 v182, vcc, 0x100000, v182
	s_nop 1
	v_addc_co_u32_e32 v183, vcc, 0, v183, vcc
	global_store_dwordx4 v[182:183], v[70:73], off offset:512

.LBB0_3890:
	v_cvt_pk_bf16_f32 v168, v66, v67
	v_cvt_pk_bf16_f32 v169, v68, v69
	s_cmp_lt_i32 s10, 3
	s_cbranch_scc1 .LBB0_3898
	s_cmp_lg_u32 s10, 3
	s_cbranch_scc0 .LBB0_3895
	v_lshlrev_b32_e32 v184, 1, v179
	v_lshl_add_u64 v[182:183], s[50:51], 0, v[160:161]
	v_ashrrev_i32_e32 v185, 31, v184
	v_lshl_add_u64 v[182:183], v[182:183], 0, v[184:185]
	global_store_dwordx2 v[182:183], v[168:169], off
	s_and_saveexec_b64 s[68:69], s[8:9]
	s_cbranch_execz .LBB0_3894
	v_ashrrev_i32_e32 v163, 31, v162
	v_lshlrev_b64 v[162:163], 19, v[162:163]
	v_lshl_add_u64 v[162:163], s[52:53], 0, v[162:163]
	v_lshl_add_u64 v[162:163], v[162:163], 0, v[164:165]
	v_ashrrev_i32_e32 v147, 31, v146
	v_lshl_add_u64 v[162:163], v[146:147], 2, v[162:163]
	v_add_co_u32_e32 v162, vcc, 0x100000, v162
	s_nop 1
	v_addc_co_u32_e32 v163, vcc, 0, v163, vcc
	global_store_dwordx4 v[162:163], v[66:69], off offset:576

.LBB0_3909:
	v_add_u32_e32 v162, 0x80, v154
	v_ashrrev_i32_e32 v138, 10, v162
	v_and_b32_e32 v181, -2, v138
	v_lshrrev_b32_e32 v138, 3, v162
	v_and_b32_e32 v155, 0xfe, v138
	v_and_b32_e32 v138, 0x1fff, v162
	v_ashrrev_i32_e32 v163, 31, v162
	v_cmp_lt_u32_e64 s[8:9], s77, v138
	v_add_u32_e32 v138, 0xffffe200, v138
	v_lshlrev_b64 v[160:161], 9, v[162:163]
	v_lshlrev_b64 v[158:159], 10, v[162:163]
	v_ashrrev_i32_e32 v162, 13, v162
	v_lshlrev_b64 v[164:165], 10, v[138:139]
	s_and_b64 vcc, exec, s[6:7]
	s_mov_b64 s[68:69], -1
	s_cbranch_vccnz .LBB0_3957
	v_cvt_pk_bf16_f32 v166, v62, v63
	v_cvt_pk_bf16_f32 v167, v64, v65
	s_cmp_lt_i32 s10, 3
	s_cbranch_scc1 .LBB0_3918
	s_cmp_lg_u32 s10, 3
	s_cbranch_scc0 .LBB0_3915
	v_lshlrev_b32_e32 v182, 1, v146
	v_lshl_add_u64 v[168:169], s[50:51], 0, v[160:161]
	v_ashrrev_i32_e32 v183, 31, v182
	v_lshl_add_u64 v[168:169], v[168:169], 0, v[182:183]
	global_store_dwordx2 v[168:169], v[166:167], off
	s_and_saveexec_b64 s[68:69], s[8:9]
	s_cbranch_execz .LBB0_3914
	v_ashrrev_i32_e32 v163, 31, v162
	v_lshlrev_b64 v[168:169], 19, v[162:163]
	v_lshl_add_u64 v[168:169], s[52:53], 0, v[168:169]
	v_lshl_add_u64 v[168:169], v[168:169], 0, v[164:165]
	v_ashrrev_i32_e32 v147, 31, v146
	v_lshl_add_u64 v[168:169], v[146:147], 2, v[168:169]
	v_add_co_u32_e32 v168, vcc, 0x100000, v168
	s_nop 1
	v_addc_co_u32_e32 v169, vcc, 0, v169, vcc
	global_store_dwordx4 v[168:169], v[62:65], off

.LBB0_3922:
	v_cvt_pk_bf16_f32 v168, v58, v59
	v_cvt_pk_bf16_f32 v169, v60, v61
	s_cmp_lt_i32 s10, 3
	s_cbranch_scc1 .LBB0_3930
	s_cmp_lg_u32 s10, 3
	s_cbranch_scc0 .LBB0_3927
	v_lshlrev_b32_e32 v184, 1, v178
	v_lshl_add_u64 v[182:183], s[50:51], 0, v[160:161]
	v_ashrrev_i32_e32 v185, 31, v184
	v_lshl_add_u64 v[182:183], v[182:183], 0, v[184:185]
	global_store_dwordx2 v[182:183], v[168:169], off
	s_and_saveexec_b64 s[68:69], s[8:9]
	s_cbranch_execz .LBB0_3926
	v_ashrrev_i32_e32 v163, 31, v162
	v_lshlrev_b64 v[182:183], 19, v[162:163]
	v_lshl_add_u64 v[182:183], s[52:53], 0, v[182:183]
	v_lshl_add_u64 v[182:183], v[182:183], 0, v[164:165]
	v_ashrrev_i32_e32 v147, 31, v146
	v_lshl_add_u64 v[182:183], v[146:147], 2, v[182:183]
	v_add_co_u32_e32 v182, vcc, 0x100000, v182
	s_nop 1
	v_addc_co_u32_e32 v183, vcc, 0, v183, vcc
	global_store_dwordx4 v[182:183], v[58:61], off offset:64

.LBB0_3934:
	v_cvt_pk_bf16_f32 v168, v42, v43
	v_cvt_pk_bf16_f32 v169, v44, v45
	s_cmp_lt_i32 s10, 3
	s_cbranch_scc1 .LBB0_3942
	s_cmp_lg_u32 s10, 3
	s_cbranch_scc0 .LBB0_3939
	v_lshlrev_b32_e32 v184, 1, v180
	v_lshl_add_u64 v[182:183], s[50:51], 0, v[160:161]
	v_ashrrev_i32_e32 v185, 31, v184
	v_lshl_add_u64 v[182:183], v[182:183], 0, v[184:185]
	global_store_dwordx2 v[182:183], v[168:169], off
	s_and_saveexec_b64 s[68:69], s[8:9]
	s_cbranch_execz .LBB0_3938
	v_ashrrev_i32_e32 v163, 31, v162
	v_lshlrev_b64 v[182:183], 19, v[162:163]
	v_lshl_add_u64 v[182:183], s[52:53], 0, v[182:183]
	v_lshl_add_u64 v[182:183], v[182:183], 0, v[164:165]
	v_ashrrev_i32_e32 v147, 31, v146
	v_lshl_add_u64 v[182:183], v[146:147], 2, v[182:183]
	v_add_co_u32_e32 v182, vcc, 0x100000, v182
	s_nop 1
	v_addc_co_u32_e32 v183, vcc, 0, v183, vcc
	global_store_dwordx4 v[182:183], v[42:45], off offset:512

.LBB0_3946:
	v_cvt_pk_bf16_f32 v168, v34, v35
	v_cvt_pk_bf16_f32 v169, v36, v37
	s_cmp_lt_i32 s10, 3
	s_cbranch_scc1 .LBB0_3954
	s_cmp_lg_u32 s10, 3
	s_cbranch_scc0 .LBB0_3951
	v_lshlrev_b32_e32 v184, 1, v179
	v_lshl_add_u64 v[182:183], s[50:51], 0, v[160:161]
	v_ashrrev_i32_e32 v185, 31, v184
	v_lshl_add_u64 v[182:183], v[182:183], 0, v[184:185]
	global_store_dwordx2 v[182:183], v[168:169], off
	s_and_saveexec_b64 s[68:69], s[8:9]
	s_cbranch_execz .LBB0_3950
	v_ashrrev_i32_e32 v163, 31, v162
	v_lshlrev_b64 v[162:163], 19, v[162:163]
	v_lshl_add_u64 v[162:163], s[52:53], 0, v[162:163]
	v_lshl_add_u64 v[162:163], v[162:163], 0, v[164:165]
	v_ashrrev_i32_e32 v147, 31, v146
	v_lshl_add_u64 v[162:163], v[146:147], 2, v[162:163]
	v_add_co_u32_e32 v162, vcc, 0x100000, v162
	s_nop 1
	v_addc_co_u32_e32 v163, vcc, 0, v163, vcc
	global_store_dwordx4 v[162:163], v[34:37], off offset:576

.LBB0_3965:
	v_add_u32_e32 v162, 0x90, v154
	v_ashrrev_i32_e32 v138, 10, v162
	v_and_b32_e32 v181, -2, v138
	v_lshrrev_b32_e32 v138, 3, v162
	v_and_b32_e32 v155, 0xfe, v138
	v_and_b32_e32 v138, 0x1fff, v162
	v_ashrrev_i32_e32 v163, 31, v162
	v_cmp_lt_u32_e64 s[8:9], s77, v138
	v_add_u32_e32 v138, 0xffffe200, v138
	v_lshlrev_b64 v[160:161], 9, v[162:163]
	v_lshlrev_b64 v[158:159], 10, v[162:163]
	v_ashrrev_i32_e32 v162, 13, v162
	v_lshlrev_b64 v[164:165], 10, v[138:139]
	s_and_b64 vcc, exec, s[6:7]
	s_mov_b64 s[68:69], -1
	s_cbranch_vccnz .LBB0_4013
	v_cvt_pk_bf16_f32 v166, v54, v55
	v_cvt_pk_bf16_f32 v167, v56, v57
	s_cmp_lt_i32 s10, 3
	s_cbranch_scc1 .LBB0_3974
	s_cmp_lg_u32 s10, 3
	s_cbranch_scc0 .LBB0_3971
	v_lshlrev_b32_e32 v182, 1, v146
	v_lshl_add_u64 v[168:169], s[50:51], 0, v[160:161]
	v_ashrrev_i32_e32 v183, 31, v182
	v_lshl_add_u64 v[168:169], v[168:169], 0, v[182:183]
	global_store_dwordx2 v[168:169], v[166:167], off
	s_and_saveexec_b64 s[68:69], s[8:9]
	s_cbranch_execz .LBB0_3970
	v_ashrrev_i32_e32 v163, 31, v162
	v_lshlrev_b64 v[168:169], 19, v[162:163]
	v_lshl_add_u64 v[168:169], s[52:53], 0, v[168:169]
	v_lshl_add_u64 v[168:169], v[168:169], 0, v[164:165]
	v_ashrrev_i32_e32 v147, 31, v146
	v_lshl_add_u64 v[168:169], v[146:147], 2, v[168:169]
	v_add_co_u32_e32 v168, vcc, 0x100000, v168
	s_nop 1
	v_addc_co_u32_e32 v169, vcc, 0, v169, vcc
	global_store_dwordx4 v[168:169], v[54:57], off

.LBB0_3978:
	v_cvt_pk_bf16_f32 v168, v50, v51
	v_cvt_pk_bf16_f32 v169, v52, v53
	s_cmp_lt_i32 s10, 3
	s_cbranch_scc1 .LBB0_3986
	s_cmp_lg_u32 s10, 3
	s_cbranch_scc0 .LBB0_3983
	v_lshlrev_b32_e32 v184, 1, v178
	v_lshl_add_u64 v[182:183], s[50:51], 0, v[160:161]
	v_ashrrev_i32_e32 v185, 31, v184
	v_lshl_add_u64 v[182:183], v[182:183], 0, v[184:185]
	global_store_dwordx2 v[182:183], v[168:169], off
	s_and_saveexec_b64 s[68:69], s[8:9]
	s_cbranch_execz .LBB0_3982
	v_ashrrev_i32_e32 v163, 31, v162
	v_lshlrev_b64 v[182:183], 19, v[162:163]
	v_lshl_add_u64 v[182:183], s[52:53], 0, v[182:183]
	v_lshl_add_u64 v[182:183], v[182:183], 0, v[164:165]
	v_ashrrev_i32_e32 v147, 31, v146
	v_lshl_add_u64 v[182:183], v[146:147], 2, v[182:183]
	v_add_co_u32_e32 v182, vcc, 0x100000, v182
	s_nop 1
	v_addc_co_u32_e32 v183, vcc, 0, v183, vcc
	global_store_dwordx4 v[182:183], v[50:53], off offset:64

.LBB0_3990:
	v_cvt_pk_bf16_f32 v168, v26, v27
	v_cvt_pk_bf16_f32 v169, v28, v29
	s_cmp_lt_i32 s10, 3
	s_cbranch_scc1 .LBB0_3998
	s_cmp_lg_u32 s10, 3
	s_cbranch_scc0 .LBB0_3995
	v_lshlrev_b32_e32 v184, 1, v180
	v_lshl_add_u64 v[182:183], s[50:51], 0, v[160:161]
	v_ashrrev_i32_e32 v185, 31, v184
	v_lshl_add_u64 v[182:183], v[182:183], 0, v[184:185]
	global_store_dwordx2 v[182:183], v[168:169], off
	s_and_saveexec_b64 s[68:69], s[8:9]
	s_cbranch_execz .LBB0_3994
	v_ashrrev_i32_e32 v163, 31, v162
	v_lshlrev_b64 v[182:183], 19, v[162:163]
	v_lshl_add_u64 v[182:183], s[52:53], 0, v[182:183]
	v_lshl_add_u64 v[182:183], v[182:183], 0, v[164:165]
	v_ashrrev_i32_e32 v147, 31, v146
	v_lshl_add_u64 v[182:183], v[146:147], 2, v[182:183]
	v_add_co_u32_e32 v182, vcc, 0x100000, v182
	s_nop 1
	v_addc_co_u32_e32 v183, vcc, 0, v183, vcc
	global_store_dwordx4 v[182:183], v[26:29], off offset:512

.LBB0_4002:
	v_cvt_pk_bf16_f32 v168, v18, v19
	v_cvt_pk_bf16_f32 v169, v20, v21
	s_cmp_lt_i32 s10, 3
	s_cbranch_scc1 .LBB0_4010
	s_cmp_lg_u32 s10, 3
	s_cbranch_scc0 .LBB0_4007
	v_lshlrev_b32_e32 v184, 1, v179
	v_lshl_add_u64 v[182:183], s[50:51], 0, v[160:161]
	v_ashrrev_i32_e32 v185, 31, v184
	v_lshl_add_u64 v[182:183], v[182:183], 0, v[184:185]
	global_store_dwordx2 v[182:183], v[168:169], off
	s_and_saveexec_b64 s[68:69], s[8:9]
	s_cbranch_execz .LBB0_4006
	v_ashrrev_i32_e32 v163, 31, v162
	v_lshlrev_b64 v[162:163], 19, v[162:163]
	v_lshl_add_u64 v[162:163], s[52:53], 0, v[162:163]
	v_lshl_add_u64 v[162:163], v[162:163], 0, v[164:165]
	v_ashrrev_i32_e32 v147, 31, v146
	v_lshl_add_u64 v[162:163], v[146:147], 2, v[162:163]
	v_add_co_u32_e32 v162, vcc, 0x100000, v162
	s_nop 1
	v_addc_co_u32_e32 v163, vcc, 0, v163, vcc
	global_store_dwordx4 v[162:163], v[18:21], off offset:576

.LBB0_4021:
	v_add_u32_e32 v162, 0xa0, v154
	v_ashrrev_i32_e32 v138, 10, v162
	v_and_b32_e32 v181, -2, v138
	v_lshrrev_b32_e32 v138, 3, v162
	v_and_b32_e32 v155, 0xfe, v138
	v_and_b32_e32 v138, 0x1fff, v162
	v_ashrrev_i32_e32 v163, 31, v162
	v_cmp_lt_u32_e64 s[8:9], s77, v138
	v_add_u32_e32 v138, 0xffffe200, v138
	v_lshlrev_b64 v[160:161], 9, v[162:163]
	v_lshlrev_b64 v[158:159], 10, v[162:163]
	v_ashrrev_i32_e32 v162, 13, v162
	v_lshlrev_b64 v[164:165], 10, v[138:139]
	s_and_b64 vcc, exec, s[6:7]
	s_mov_b64 s[68:69], -1
	s_cbranch_vccnz .LBB0_4069
	v_cvt_pk_bf16_f32 v166, v46, v47
	v_cvt_pk_bf16_f32 v167, v48, v49
	s_cmp_lt_i32 s10, 3
	s_cbranch_scc1 .LBB0_4030
	s_cmp_lg_u32 s10, 3
	s_cbranch_scc0 .LBB0_4027
	v_lshlrev_b32_e32 v182, 1, v146
	v_lshl_add_u64 v[168:169], s[50:51], 0, v[160:161]
	v_ashrrev_i32_e32 v183, 31, v182
	v_lshl_add_u64 v[168:169], v[168:169], 0, v[182:183]
	global_store_dwordx2 v[168:169], v[166:167], off
	s_and_saveexec_b64 s[68:69], s[8:9]
	s_cbranch_execz .LBB0_4026
	v_ashrrev_i32_e32 v163, 31, v162
	v_lshlrev_b64 v[168:169], 19, v[162:163]
	v_lshl_add_u64 v[168:169], s[52:53], 0, v[168:169]
	v_lshl_add_u64 v[168:169], v[168:169], 0, v[164:165]
	v_ashrrev_i32_e32 v147, 31, v146
	v_lshl_add_u64 v[168:169], v[146:147], 2, v[168:169]
	v_add_co_u32_e32 v168, vcc, 0x100000, v168
	s_nop 1
	v_addc_co_u32_e32 v169, vcc, 0, v169, vcc
	global_store_dwordx4 v[168:169], v[46:49], off

.LBB0_4034:
	v_cvt_pk_bf16_f32 v168, v38, v39
	v_cvt_pk_bf16_f32 v169, v40, v41
	s_cmp_lt_i32 s10, 3
	s_cbranch_scc1 .LBB0_4042
	s_cmp_lg_u32 s10, 3
	s_cbranch_scc0 .LBB0_4039
	v_lshlrev_b32_e32 v184, 1, v178
	v_lshl_add_u64 v[182:183], s[50:51], 0, v[160:161]
	v_ashrrev_i32_e32 v185, 31, v184
	v_lshl_add_u64 v[182:183], v[182:183], 0, v[184:185]
	global_store_dwordx2 v[182:183], v[168:169], off
	s_and_saveexec_b64 s[68:69], s[8:9]
	s_cbranch_execz .LBB0_4038
	v_ashrrev_i32_e32 v163, 31, v162
	v_lshlrev_b64 v[182:183], 19, v[162:163]
	v_lshl_add_u64 v[182:183], s[52:53], 0, v[182:183]
	v_lshl_add_u64 v[182:183], v[182:183], 0, v[164:165]
	v_ashrrev_i32_e32 v147, 31, v146
	v_lshl_add_u64 v[182:183], v[146:147], 2, v[182:183]
	v_add_co_u32_e32 v182, vcc, 0x100000, v182
	s_nop 1
	v_addc_co_u32_e32 v183, vcc, 0, v183, vcc
	global_store_dwordx4 v[182:183], v[38:41], off offset:64

.LBB0_4046:
	v_cvt_pk_bf16_f32 v168, v14, v15
	v_cvt_pk_bf16_f32 v169, v16, v17
	s_cmp_lt_i32 s10, 3
	s_cbranch_scc1 .LBB0_4054
	s_cmp_lg_u32 s10, 3
	s_cbranch_scc0 .LBB0_4051
	v_lshlrev_b32_e32 v184, 1, v180
	v_lshl_add_u64 v[182:183], s[50:51], 0, v[160:161]
	v_ashrrev_i32_e32 v185, 31, v184
	v_lshl_add_u64 v[182:183], v[182:183], 0, v[184:185]
	global_store_dwordx2 v[182:183], v[168:169], off
	s_and_saveexec_b64 s[68:69], s[8:9]
	s_cbranch_execz .LBB0_4050
	v_ashrrev_i32_e32 v163, 31, v162
	v_lshlrev_b64 v[182:183], 19, v[162:163]
	v_lshl_add_u64 v[182:183], s[52:53], 0, v[182:183]
	v_lshl_add_u64 v[182:183], v[182:183], 0, v[164:165]
	v_ashrrev_i32_e32 v147, 31, v146
	v_lshl_add_u64 v[182:183], v[146:147], 2, v[182:183]
	v_add_co_u32_e32 v182, vcc, 0x100000, v182
	s_nop 1
	v_addc_co_u32_e32 v183, vcc, 0, v183, vcc
	global_store_dwordx4 v[182:183], v[14:17], off offset:512

.LBB0_4058:
	v_cvt_pk_bf16_f32 v168, v10, v11
	v_cvt_pk_bf16_f32 v169, v12, v13
	s_cmp_lt_i32 s10, 3
	s_cbranch_scc1 .LBB0_4066
	s_cmp_lg_u32 s10, 3
	s_cbranch_scc0 .LBB0_4063
	v_lshlrev_b32_e32 v184, 1, v179
	v_lshl_add_u64 v[182:183], s[50:51], 0, v[160:161]
	v_ashrrev_i32_e32 v185, 31, v184
	v_lshl_add_u64 v[182:183], v[182:183], 0, v[184:185]
	global_store_dwordx2 v[182:183], v[168:169], off
	s_and_saveexec_b64 s[68:69], s[8:9]
	s_cbranch_execz .LBB0_4062
	v_ashrrev_i32_e32 v163, 31, v162
	v_lshlrev_b64 v[162:163], 19, v[162:163]
	v_lshl_add_u64 v[162:163], s[52:53], 0, v[162:163]
	v_lshl_add_u64 v[162:163], v[162:163], 0, v[164:165]
	v_ashrrev_i32_e32 v147, 31, v146
	v_lshl_add_u64 v[162:163], v[146:147], 2, v[162:163]
	v_add_co_u32_e32 v162, vcc, 0x100000, v162
	s_nop 1
	v_addc_co_u32_e32 v163, vcc, 0, v163, vcc
	global_store_dwordx4 v[162:163], v[10:13], off offset:576

.LBB0_4077:
	v_add_u32_e32 v160, 0xb0, v154
	v_ashrrev_i32_e32 v138, 10, v160
	v_and_b32_e32 v169, -2, v138
	v_lshrrev_b32_e32 v138, 3, v160
	v_and_b32_e32 v168, 0xfe, v138
	v_and_b32_e32 v138, 0x1fff, v160
	v_ashrrev_i32_e32 v161, 31, v160
	v_cmp_lt_u32_e64 s[8:9], s77, v138
	v_add_u32_e32 v138, 0xffffe200, v138
	v_lshlrev_b64 v[158:159], 9, v[160:161]
	v_lshlrev_b64 v[154:155], 10, v[160:161]
	v_ashrrev_i32_e32 v160, 13, v160
	v_lshlrev_b64 v[162:163], 10, v[138:139]
	s_and_b64 vcc, exec, s[6:7]
	s_mov_b64 s[68:69], -1
	s_cbranch_vccnz .LBB0_4125
	v_cvt_pk_bf16_f32 v164, v30, v31
	v_cvt_pk_bf16_f32 v165, v32, v33
	s_cmp_lt_i32 s10, 3
	s_cbranch_scc1 .LBB0_4086
	v_lshlrev_b32_e32 v166, 1, v146
	s_cmp_lg_u32 s10, 3
	v_ashrrev_i32_e32 v167, 31, v166
	s_cbranch_scc0 .LBB0_4083
	v_lshl_add_u64 v[182:183], s[50:51], 0, v[158:159]
	v_lshl_add_u64 v[182:183], v[182:183], 0, v[166:167]
	global_store_dwordx2 v[182:183], v[164:165], off
	s_and_saveexec_b64 s[68:69], s[8:9]
	s_cbranch_execz .LBB0_4082
	v_ashrrev_i32_e32 v161, 31, v160
	v_lshlrev_b64 v[182:183], 19, v[160:161]
	v_lshl_add_u64 v[182:183], s[52:53], 0, v[182:183]
	v_lshl_add_u64 v[182:183], v[182:183], 0, v[162:163]
	v_ashrrev_i32_e32 v147, 31, v146
	v_lshl_add_u64 v[182:183], v[146:147], 2, v[182:183]
	v_add_co_u32_e32 v182, vcc, 0x100000, v182
	s_nop 1
	v_addc_co_u32_e32 v183, vcc, 0, v183, vcc
	global_store_dwordx4 v[182:183], v[30:33], off

.LBB0_4090:
	v_cvt_pk_bf16_f32 v148, v22, v23
	v_cvt_pk_bf16_f32 v149, v24, v25
	s_cmp_lt_i32 s10, 3
	s_cbranch_scc1 .LBB0_4098
	v_lshlrev_b32_e32 v166, 1, v178
	s_cmp_lg_u32 s10, 3
	v_ashrrev_i32_e32 v167, 31, v166
	s_cbranch_scc0 .LBB0_4095
	v_lshl_add_u64 v[182:183], s[50:51], 0, v[158:159]
	v_lshl_add_u64 v[182:183], v[182:183], 0, v[166:167]
	global_store_dwordx2 v[182:183], v[148:149], off
	s_and_saveexec_b64 s[68:69], s[8:9]
	s_cbranch_execz .LBB0_4094
	v_ashrrev_i32_e32 v161, 31, v160
	v_lshlrev_b64 v[182:183], 19, v[160:161]
	v_lshl_add_u64 v[182:183], s[52:53], 0, v[182:183]
	v_lshl_add_u64 v[182:183], v[182:183], 0, v[162:163]
	v_ashrrev_i32_e32 v147, 31, v146
	v_lshl_add_u64 v[182:183], v[146:147], 2, v[182:183]
	v_add_co_u32_e32 v182, vcc, 0x100000, v182
	s_nop 1
	v_addc_co_u32_e32 v183, vcc, 0, v183, vcc
	global_store_dwordx4 v[182:183], v[22:25], off offset:64

.LBB0_4102:
	v_cvt_pk_bf16_f32 v148, v6, v7
	v_cvt_pk_bf16_f32 v149, v8, v9
	s_cmp_lt_i32 s10, 3
	s_cbranch_scc1 .LBB0_4110
	v_lshlrev_b32_e32 v150, 1, v180
	s_cmp_lg_u32 s10, 3
	v_ashrrev_i32_e32 v151, 31, v150
	s_cbranch_scc0 .LBB0_4107
	v_lshl_add_u64 v[166:167], s[50:51], 0, v[158:159]
	v_lshl_add_u64 v[166:167], v[166:167], 0, v[150:151]
	global_store_dwordx2 v[166:167], v[148:149], off
	s_and_saveexec_b64 s[68:69], s[8:9]
	s_cbranch_execz .LBB0_4106
	v_ashrrev_i32_e32 v161, 31, v160
	v_lshlrev_b64 v[166:167], 19, v[160:161]
	v_lshl_add_u64 v[166:167], s[52:53], 0, v[166:167]
	v_lshl_add_u64 v[166:167], v[166:167], 0, v[162:163]
	v_ashrrev_i32_e32 v147, 31, v146
	v_lshl_add_u64 v[166:167], v[146:147], 2, v[166:167]
	v_add_co_u32_e32 v166, vcc, 0x100000, v166
	s_nop 1
	v_addc_co_u32_e32 v167, vcc, 0, v167, vcc
	global_store_dwordx4 v[166:167], v[6:9], off offset:512

.LBB0_4114:
	v_cvt_pk_bf16_f32 v148, v2, v3
	v_cvt_pk_bf16_f32 v149, v4, v5
	s_cmp_lt_i32 s10, 3
	s_cbranch_scc1 .LBB0_4122
	v_lshlrev_b32_e32 v150, 1, v179
	s_cmp_lg_u32 s10, 3
	v_ashrrev_i32_e32 v151, 31, v150
	s_cbranch_scc0 .LBB0_4119
	v_lshl_add_u64 v[152:153], s[50:51], 0, v[158:159]
	v_lshl_add_u64 v[152:153], v[152:153], 0, v[150:151]
	global_store_dwordx2 v[152:153], v[148:149], off
	s_and_saveexec_b64 s[6:7], s[8:9]
	s_cbranch_execz .LBB0_4118
	v_ashrrev_i32_e32 v161, 31, v160
	v_lshlrev_b64 v[152:153], 19, v[160:161]
	v_lshl_add_u64 v[152:153], s[52:53], 0, v[152:153]
	v_lshl_add_u64 v[152:153], v[152:153], 0, v[162:163]
	v_ashrrev_i32_e32 v147, 31, v146
	v_lshl_add_u64 v[152:153], v[146:147], 2, v[152:153]
	v_add_co_u32_e32 v152, vcc, 0x100000, v152
	s_nop 1
	v_addc_co_u32_e32 v153, vcc, 0, v153, vcc
	global_store_dwordx4 v[152:153], v[2:5], off offset:576

.LBB0_4328:
	s_or_b64 exec, exec, s[14:15]
	s_ashr_i32 s5, s40, 1
	s_cmp_lt_i32 s5, 8
	s_cselect_b64 s[72:73], -1, 0
	s_cmp_gt_i32 s5, 7
	s_cselect_b64 s[14:15], -1, 0
	s_and_b32 s9, s5, 3
	s_cmp_eq_u32 s9, 3
	v_lshl_add_u32 v2, v132, 2, s94
	s_cselect_b64 s[28:29], -1, 0
	s_waitcnt lgkmcnt(0)
	s_barrier
	ds_read2st64_b32 v[18:19], v2 offset0:128 offset1:129
	s_or_b64 s[14:15], s[14:15], s[28:29]
	s_cmp_gt_i32 s96, 7
	s_cselect_b64 s[28:29], -1, 0
	s_and_b64 s[28:29], s[14:15], s[28:29]
	s_mov_b64 s[90:91], -1
	s_xor_b64 s[92:93], s[28:29], -1
	v_mov_b32_e32 v2, 0
	s_and_b64 vcc, exec, s[28:29]
	v_mov_b32_e32 v3, 0
	s_cbranch_vccnz .LBB0_4330
	s_waitcnt lgkmcnt(0)
	v_pk_add_f32 v[2:3], v[20:21], v[18:19]
	s_nop 0
	v_pk_add_f32 v[2:3], v[22:23], v[2:3]
	s_nop 0
	v_mul_f32_e32 v4, 0x3d372713, v2
	v_mul_f32_e32 v5, 0x3d372713, v3
	v_mul_f32_e32 v4, v2, v4
	v_mul_f32_e32 v5, v3, v5
	v_fma_f32 v4, v2, v4, v2
	v_fma_f32 v5, v3, v5, v3
	v_mul_f32_e32 v4, 0x3f4c422a, v4
	v_mul_f32_e32 v5, 0x3f4c422a, v5
	v_mul_f32_e32 v4, -2.0, v4
	v_mul_f32_e32 v5, -2.0, v5
	v_mul_f32_e32 v4, 0x3fb8aa3b, v4
	v_mul_f32_e32 v5, 0x3fb8aa3b, v5
	v_exp_f32_e32 v4, v4
	v_exp_f32_e32 v5, v5
	s_nop 0
	v_pk_add_f32 v[4:5], v[4:5], 1.0 op_sel_hi:[1,0]
	s_nop 0
	s_nop 0
	v_rcp_f32_e32 v6, v4
	s_nop 0
	v_mul_f32_e32 v2, v2, v6
	v_rcp_f32_e32 v4, v5
	s_nop 0
	v_mul_f32_e32 v3, v3, v4
.LBB0_4330:
	s_mul_i32 s4, s96, 0x2040
	s_add_i32 s7, s94, s4
	v_lshl_add_u32 v76, v132, 2, s7
	s_andn2_b64 vcc, exec, s[92:93]
	ds_write2st64_b32 v76, v2, v3 offset0:130 offset1:131
	s_cbranch_vccnz .LBB0_4332
	s_waitcnt lgkmcnt(1)
	v_add_f32_e32 v2, v107, v18
	v_add_f32_e32 v2, v108, v2
	v_mul_f32_e32 v3, 0x3d372713, v2
	v_mul_f32_e32 v3, v2, v3
	v_fma_f32 v3, v2, v3, v2
	v_mul_f32_e32 v3, 0x3f4c422a, v3
	v_mul_f32_e32 v3, -2.0, v3
	v_mul_f32_e32 v3, 0x3fb8aa3b, v3
	v_exp_f32_e32 v3, v3
	v_add_f32_e32 v4, v105, v19
	v_add_f32_e32 v4, v106, v4
	v_mul_f32_e32 v7, 0x3d372713, v4
	v_add_f32_e32 v3, 1.0, v3
	v_mul_f32_e32 v7, v4, v7
	v_fma_f32 v7, v4, v7, v4
	v_mul_f32_e32 v7, 0x3f4c422a, v7
	v_mul_f32_e32 v7, -2.0, v7
	v_mul_f32_e32 v7, 0x3fb8aa3b, v7
	v_exp_f32_e32 v7, v7
	s_nop 0
	v_add_f32_e32 v7, 1.0, v7
	v_rcp_f32_e32 v5, v3
	s_nop 0
	v_mul_f32_e32 v2, v2, v5
	ds_write_b32 v76, v2 offset:33796
	v_rcp_f32_e32 v2, v7
	s_nop 0
	v_mul_f32_e32 v2, v4, v2
	s_mov_b64 s[90:91], 0

.LBB0_4334:
	s_load_dwordx2 s[90:91], s[0:1], 0xe0
	s_cmpk_gt_i32 s88, 0xfd
	s_cselect_b64 s[28:29], -1, 0
	s_and_b64 s[28:29], s[14:15], s[28:29]
	s_and_b64 vcc, exec, s[28:29]
	ds_write_b32 v76, v2 offset:34052
	s_cbranch_vccnz .LBB0_4336
	s_waitcnt lgkmcnt(0)
	v_add_f32_e32 v2, v103, v18
	v_add_f32_e32 v2, v104, v2
	v_mul_f32_e32 v3, 0x3d372713, v2
	v_mul_f32_e32 v3, v2, v3
	v_fma_f32 v3, v2, v3, v2
	v_mul_f32_e32 v3, 0x3f4c422a, v3
	v_mul_f32_e32 v3, -2.0, v3
	v_mul_f32_e32 v3, 0x3fb8aa3b, v3
	v_exp_f32_e32 v3, v3
	v_add_f32_e32 v4, v100, v19
	v_add_f32_e32 v4, v102, v4
	v_mul_f32_e32 v7, 0x3d372713, v4
	v_add_f32_e32 v3, 1.0, v3
	v_mul_f32_e32 v7, v4, v7
	v_fma_f32 v7, v4, v7, v4
	v_mul_f32_e32 v7, 0x3f4c422a, v7
	v_mul_f32_e32 v7, -2.0, v7
	v_mul_f32_e32 v7, 0x3fb8aa3b, v7
	v_exp_f32_e32 v7, v7
	s_nop 0
	v_add_f32_e32 v7, 1.0, v7
	v_rcp_f32_e32 v5, v3
	s_nop 0
	v_mul_f32_e32 v2, v2, v5
	ds_write_b32 v76, v2 offset:34312
	v_rcp_f32_e32 v2, v7
	s_nop 0
	v_mul_f32_e32 v2, v4, v2
	s_cbranch_execz .LBB0_4337
	s_branch .LBB0_4338

.LBB0_4338:
	s_cmpk_gt_i32 s86, 0xfd
	s_cselect_b64 s[28:29], -1, 0
	s_and_b64 s[28:29], s[14:15], s[28:29]
	s_and_b64 vcc, exec, s[28:29]
	ds_write_b32 v76, v2 offset:34568
	s_cbranch_vccnz .LBB0_4340
	s_waitcnt lgkmcnt(0)
	v_add_f32_e32 v2, v98, v18
	v_add_f32_e32 v2, v101, v2
	v_mul_f32_e32 v3, 0x3d372713, v2
	v_mul_f32_e32 v3, v2, v3
	v_fma_f32 v3, v2, v3, v2
	v_mul_f32_e32 v3, 0x3f4c422a, v3
	v_mul_f32_e32 v3, -2.0, v3
	v_mul_f32_e32 v3, 0x3fb8aa3b, v3
	v_exp_f32_e32 v3, v3
	v_add_f32_e32 v4, v97, v19
	v_add_f32_e32 v4, v99, v4
	v_mul_f32_e32 v7, 0x3d372713, v4
	v_add_f32_e32 v3, 1.0, v3
	v_mul_f32_e32 v7, v4, v7
	v_fma_f32 v7, v4, v7, v4
	v_mul_f32_e32 v7, 0x3f4c422a, v7
	v_mul_f32_e32 v7, -2.0, v7
	v_mul_f32_e32 v7, 0x3fb8aa3b, v7
	v_exp_f32_e32 v7, v7
	s_nop 0
	v_add_f32_e32 v7, 1.0, v7
	v_rcp_f32_e32 v5, v3
	s_nop 0
	v_mul_f32_e32 v2, v2, v5
	ds_write_b32 v76, v2 offset:34828
	v_rcp_f32_e32 v2, v7
	s_nop 0
	v_mul_f32_e32 v2, v4, v2
	s_cbranch_execz .LBB0_4341
	s_branch .LBB0_4342

.LBB0_4342:
	s_cmpk_gt_i32 s84, 0xfd
	s_cselect_b64 s[28:29], -1, 0
	s_and_b64 s[28:29], s[14:15], s[28:29]
	s_and_b64 vcc, exec, s[28:29]
	ds_write_b32 v76, v2 offset:35084
	s_cbranch_vccnz .LBB0_4344
	s_waitcnt lgkmcnt(0)
	v_add_f32_e32 v2, v94, v18
	v_add_f32_e32 v2, v96, v2
	v_mul_f32_e32 v3, 0x3d372713, v2
	v_mul_f32_e32 v3, v2, v3
	v_fma_f32 v3, v2, v3, v2
	v_mul_f32_e32 v3, 0x3f4c422a, v3
	v_mul_f32_e32 v3, -2.0, v3
	v_mul_f32_e32 v3, 0x3fb8aa3b, v3
	v_exp_f32_e32 v3, v3
	v_add_f32_e32 v4, v93, v19
	v_add_f32_e32 v4, v95, v4
	v_mul_f32_e32 v7, 0x3d372713, v4
	v_add_f32_e32 v3, 1.0, v3
	v_mul_f32_e32 v7, v4, v7
	v_fma_f32 v7, v4, v7, v4
	v_mul_f32_e32 v7, 0x3f4c422a, v7
	v_mul_f32_e32 v7, -2.0, v7
	v_mul_f32_e32 v7, 0x3fb8aa3b, v7
	v_exp_f32_e32 v7, v7
	s_nop 0
	v_add_f32_e32 v7, 1.0, v7
	v_rcp_f32_e32 v5, v3
	s_nop 0
	v_mul_f32_e32 v2, v2, v5
	ds_write_b32 v76, v2 offset:35344
	v_rcp_f32_e32 v2, v7
	s_nop 0
	v_mul_f32_e32 v2, v4, v2
	s_cbranch_execz .LBB0_4345
	s_branch .LBB0_4346

.LBB0_4346:
	s_cmpk_gt_i32 s82, 0xfd
	s_cselect_b64 s[28:29], -1, 0
	s_and_b64 s[28:29], s[14:15], s[28:29]
	s_and_b64 vcc, exec, s[28:29]
	ds_write_b32 v76, v2 offset:35600
	s_cbranch_vccnz .LBB0_4348
	s_waitcnt lgkmcnt(0)
	v_add_f32_e32 v2, v90, v18
	v_add_f32_e32 v2, v92, v2
	v_mul_f32_e32 v3, 0x3d372713, v2
	v_mul_f32_e32 v3, v2, v3
	v_fma_f32 v3, v2, v3, v2
	v_mul_f32_e32 v3, 0x3f4c422a, v3
	v_mul_f32_e32 v3, -2.0, v3
	v_mul_f32_e32 v3, 0x3fb8aa3b, v3
	v_exp_f32_e32 v3, v3
	v_add_f32_e32 v4, v89, v19
	v_add_f32_e32 v4, v91, v4
	v_mul_f32_e32 v7, 0x3d372713, v4
	v_add_f32_e32 v3, 1.0, v3
	v_mul_f32_e32 v7, v4, v7
	v_fma_f32 v7, v4, v7, v4
	v_mul_f32_e32 v7, 0x3f4c422a, v7
	v_mul_f32_e32 v7, -2.0, v7
	v_mul_f32_e32 v7, 0x3fb8aa3b, v7
	v_exp_f32_e32 v7, v7
	s_nop 0
	v_add_f32_e32 v7, 1.0, v7
	v_rcp_f32_e32 v5, v3
	s_nop 0
	v_mul_f32_e32 v2, v2, v5
	ds_write_b32 v76, v2 offset:35860
	v_rcp_f32_e32 v2, v7
	s_nop 0
	v_mul_f32_e32 v2, v4, v2
	s_cbranch_execz .LBB0_4349
	s_branch .LBB0_4350

.LBB0_4350:
	s_cmpk_gt_i32 s80, 0xfd
	s_cselect_b64 s[28:29], -1, 0
	s_and_b64 s[28:29], s[14:15], s[28:29]
	s_and_b64 vcc, exec, s[28:29]
	ds_write_b32 v76, v2 offset:36116
	s_cbranch_vccnz .LBB0_4352
	s_waitcnt lgkmcnt(0)
	v_add_f32_e32 v2, v87, v18
	v_add_f32_e32 v2, v88, v2
	v_mul_f32_e32 v3, 0x3d372713, v2
	v_mul_f32_e32 v3, v2, v3
	v_fma_f32 v3, v2, v3, v2
	v_mul_f32_e32 v3, 0x3f4c422a, v3
	v_mul_f32_e32 v3, -2.0, v3
	v_mul_f32_e32 v3, 0x3fb8aa3b, v3
	v_exp_f32_e32 v3, v3
	v_add_f32_e32 v4, v85, v19
	v_add_f32_e32 v4, v86, v4
	v_mul_f32_e32 v7, 0x3d372713, v4
	v_add_f32_e32 v3, 1.0, v3
	v_mul_f32_e32 v7, v4, v7
	v_fma_f32 v7, v4, v7, v4
	v_mul_f32_e32 v7, 0x3f4c422a, v7
	v_mul_f32_e32 v7, -2.0, v7
	v_mul_f32_e32 v7, 0x3fb8aa3b, v7
	v_exp_f32_e32 v7, v7
	s_nop 0
	v_add_f32_e32 v7, 1.0, v7
	v_rcp_f32_e32 v5, v3
	s_nop 0
	v_mul_f32_e32 v2, v2, v5
	ds_write_b32 v76, v2 offset:36376
	v_rcp_f32_e32 v2, v7
	s_nop 0
	v_mul_f32_e32 v2, v4, v2
	s_cbranch_execz .LBB0_4353
	s_branch .LBB0_4354

.LBB0_4354:
	s_cmpk_gt_i32 s78, 0xfd
	s_cselect_b64 s[28:29], -1, 0
	s_and_b64 s[28:29], s[14:15], s[28:29]
	s_and_b64 vcc, exec, s[28:29]
	ds_write_b32 v76, v2 offset:36632
	s_cbranch_vccnz .LBB0_4356
	s_waitcnt lgkmcnt(0)
	v_add_f32_e32 v2, v82, v18
	v_add_f32_e32 v2, v84, v2
	v_mul_f32_e32 v3, 0x3d372713, v2
	v_mul_f32_e32 v3, v2, v3
	v_fma_f32 v3, v2, v3, v2
	v_mul_f32_e32 v3, 0x3f4c422a, v3
	v_mul_f32_e32 v3, -2.0, v3
	v_mul_f32_e32 v3, 0x3fb8aa3b, v3
	v_exp_f32_e32 v3, v3
	v_add_f32_e32 v4, v81, v19
	v_add_f32_e32 v4, v83, v4
	v_mul_f32_e32 v7, 0x3d372713, v4
	v_add_f32_e32 v3, 1.0, v3
	v_mul_f32_e32 v7, v4, v7
	v_fma_f32 v7, v4, v7, v4
	v_mul_f32_e32 v7, 0x3f4c422a, v7
	v_mul_f32_e32 v7, -2.0, v7
	v_mul_f32_e32 v7, 0x3fb8aa3b, v7
	v_exp_f32_e32 v7, v7
	s_nop 0
	v_add_f32_e32 v7, 1.0, v7
	v_rcp_f32_e32 v5, v3
	s_nop 0
	v_mul_f32_e32 v2, v2, v5
	ds_write_b32 v76, v2 offset:36892
	v_rcp_f32_e32 v2, v7
	s_nop 0
	v_mul_f32_e32 v2, v4, v2
	s_cbranch_execz .LBB0_4357
	s_branch .LBB0_4358

.LBB0_4358:
	s_cmpk_gt_i32 s76, 0xfd
	s_cselect_b64 s[28:29], -1, 0
	s_and_b64 s[28:29], s[14:15], s[28:29]
	s_and_b64 vcc, exec, s[28:29]
	ds_write_b32 v76, v2 offset:37148
	s_cbranch_vccnz .LBB0_4360
	s_waitcnt lgkmcnt(0)
	v_add_f32_e32 v2, v79, v18
	v_add_f32_e32 v2, v80, v2
	v_mul_f32_e32 v3, 0x3d372713, v2
	v_mul_f32_e32 v3, v2, v3
	v_fma_f32 v3, v2, v3, v2
	v_mul_f32_e32 v3, 0x3f4c422a, v3
	v_mul_f32_e32 v3, -2.0, v3
	v_mul_f32_e32 v3, 0x3fb8aa3b, v3
	v_exp_f32_e32 v3, v3
	v_add_f32_e32 v4, v77, v19
	v_add_f32_e32 v4, v78, v4
	v_mul_f32_e32 v7, 0x3d372713, v4
	v_add_f32_e32 v3, 1.0, v3
	v_mul_f32_e32 v7, v4, v7
	v_fma_f32 v7, v4, v7, v4
	v_mul_f32_e32 v7, 0x3f4c422a, v7
	v_mul_f32_e32 v7, -2.0, v7
	v_mul_f32_e32 v7, 0x3fb8aa3b, v7
	v_exp_f32_e32 v7, v7
	s_nop 0
	v_add_f32_e32 v7, 1.0, v7
	v_rcp_f32_e32 v5, v3
	s_nop 0
	v_mul_f32_e32 v2, v2, v5
	ds_write_b32 v76, v2 offset:37408
	v_rcp_f32_e32 v2, v7
	s_nop 0
	v_mul_f32_e32 v2, v4, v2
	s_cbranch_execz .LBB0_4361
	s_branch .LBB0_4362

.LBB0_4362:
	s_cmpk_gt_i32 s74, 0xfd
	s_cselect_b64 s[28:29], -1, 0
	s_and_b64 s[28:29], s[14:15], s[28:29]
	s_and_b64 vcc, exec, s[28:29]
	ds_write_b32 v76, v2 offset:37664
	s_cbranch_vccnz .LBB0_4364
	s_waitcnt lgkmcnt(0)
	v_add_f32_e32 v2, v73, v18
	v_add_f32_e32 v2, v75, v2
	v_mul_f32_e32 v3, 0x3d372713, v2
	v_mul_f32_e32 v3, v2, v3
	v_fma_f32 v3, v2, v3, v2
	v_mul_f32_e32 v3, 0x3f4c422a, v3
	v_mul_f32_e32 v3, -2.0, v3
	v_mul_f32_e32 v3, 0x3fb8aa3b, v3
	v_exp_f32_e32 v3, v3
	v_add_f32_e32 v4, v72, v19
	v_add_f32_e32 v4, v74, v4
	v_mul_f32_e32 v7, 0x3d372713, v4
	v_add_f32_e32 v3, 1.0, v3
	v_mul_f32_e32 v7, v4, v7
	v_fma_f32 v7, v4, v7, v4
	v_mul_f32_e32 v7, 0x3f4c422a, v7
	v_mul_f32_e32 v7, -2.0, v7
	v_mul_f32_e32 v7, 0x3fb8aa3b, v7
	v_exp_f32_e32 v7, v7
	s_nop 0
	v_add_f32_e32 v7, 1.0, v7
	v_rcp_f32_e32 v5, v3
	s_nop 0
	v_mul_f32_e32 v2, v2, v5
	ds_write_b32 v76, v2 offset:37924
	v_rcp_f32_e32 v2, v7
	s_nop 0
	v_mul_f32_e32 v2, v4, v2
	s_cbranch_execz .LBB0_4365
	s_branch .LBB0_4366

.LBB0_4366:
	s_cmpk_gt_i32 s70, 0xfd
	s_cselect_b64 s[28:29], -1, 0
	s_and_b64 s[28:29], s[14:15], s[28:29]
	s_and_b64 vcc, exec, s[28:29]
	ds_write_b32 v76, v2 offset:38180
	s_cbranch_vccnz .LBB0_4368
	s_waitcnt lgkmcnt(0)
	v_add_f32_e32 v2, v70, v18
	v_add_f32_e32 v2, v71, v2
	v_mul_f32_e32 v3, 0x3d372713, v2
	v_mul_f32_e32 v3, v2, v3
	v_fma_f32 v3, v2, v3, v2
	v_mul_f32_e32 v3, 0x3f4c422a, v3
	v_mul_f32_e32 v3, -2.0, v3
	v_mul_f32_e32 v3, 0x3fb8aa3b, v3
	v_exp_f32_e32 v3, v3
	v_add_f32_e32 v4, v68, v19
	v_add_f32_e32 v4, v69, v4
	v_mul_f32_e32 v7, 0x3d372713, v4
	v_add_f32_e32 v3, 1.0, v3
	v_mul_f32_e32 v7, v4, v7
	v_fma_f32 v7, v4, v7, v4
	v_mul_f32_e32 v7, 0x3f4c422a, v7
	v_mul_f32_e32 v7, -2.0, v7
	v_mul_f32_e32 v7, 0x3fb8aa3b, v7
	v_exp_f32_e32 v7, v7
	s_nop 0
	v_add_f32_e32 v7, 1.0, v7
	v_rcp_f32_e32 v5, v3
	s_nop 0
	v_mul_f32_e32 v2, v2, v5
	ds_write_b32 v76, v2 offset:38440
	v_rcp_f32_e32 v2, v7
	s_nop 0
	v_mul_f32_e32 v2, v4, v2
	s_cbranch_execz .LBB0_4369
	s_branch .LBB0_4370

.LBB0_4370:
	s_cmpk_gt_i32 s68, 0xfd
	s_cselect_b64 s[28:29], -1, 0
	s_and_b64 s[28:29], s[14:15], s[28:29]
	s_and_b64 vcc, exec, s[28:29]
	ds_write_b32 v76, v2 offset:38696
	s_cbranch_vccnz .LBB0_4372
	s_waitcnt lgkmcnt(0)
	v_add_f32_e32 v2, v65, v18
	v_add_f32_e32 v2, v67, v2
	v_mul_f32_e32 v3, 0x3d372713, v2
	v_mul_f32_e32 v3, v2, v3
	v_fma_f32 v3, v2, v3, v2
	v_mul_f32_e32 v3, 0x3f4c422a, v3
	v_mul_f32_e32 v3, -2.0, v3
	v_mul_f32_e32 v3, 0x3fb8aa3b, v3
	v_exp_f32_e32 v3, v3
	v_add_f32_e32 v4, v64, v19
	v_add_f32_e32 v4, v66, v4
	v_mul_f32_e32 v7, 0x3d372713, v4
	v_add_f32_e32 v3, 1.0, v3
	v_mul_f32_e32 v7, v4, v7
	v_fma_f32 v7, v4, v7, v4
	v_mul_f32_e32 v7, 0x3f4c422a, v7
	v_mul_f32_e32 v7, -2.0, v7
	v_mul_f32_e32 v7, 0x3fb8aa3b, v7
	v_exp_f32_e32 v7, v7
	s_nop 0
	v_add_f32_e32 v7, 1.0, v7
	v_rcp_f32_e32 v5, v3
	s_nop 0
	v_mul_f32_e32 v2, v2, v5
	ds_write_b32 v76, v2 offset:38956
	v_rcp_f32_e32 v2, v7
	s_nop 0
	v_mul_f32_e32 v2, v4, v2
	s_cbranch_execz .LBB0_4373
	s_branch .LBB0_4374

.LBB0_4374:
	s_cmpk_gt_i32 s66, 0xfd
	s_cselect_b64 s[28:29], -1, 0
	s_and_b64 s[28:29], s[14:15], s[28:29]
	s_and_b64 vcc, exec, s[28:29]
	ds_write_b32 v76, v2 offset:39212
	s_cbranch_vccnz .LBB0_4376
	s_waitcnt lgkmcnt(0)
	v_add_f32_e32 v2, v62, v18
	v_add_f32_e32 v2, v63, v2
	v_mul_f32_e32 v3, 0x3d372713, v2
	v_mul_f32_e32 v3, v2, v3
	v_fma_f32 v3, v2, v3, v2
	v_mul_f32_e32 v3, 0x3f4c422a, v3
	v_mul_f32_e32 v3, -2.0, v3
	v_mul_f32_e32 v3, 0x3fb8aa3b, v3
	v_exp_f32_e32 v3, v3
	v_add_f32_e32 v4, v60, v19
	v_add_f32_e32 v4, v61, v4
	v_mul_f32_e32 v7, 0x3d372713, v4
	v_add_f32_e32 v3, 1.0, v3
	v_mul_f32_e32 v7, v4, v7
	v_fma_f32 v7, v4, v7, v4
	v_mul_f32_e32 v7, 0x3f4c422a, v7
	v_mul_f32_e32 v7, -2.0, v7
	v_mul_f32_e32 v7, 0x3fb8aa3b, v7
	v_exp_f32_e32 v7, v7
	s_nop 0
	v_add_f32_e32 v7, 1.0, v7
	v_rcp_f32_e32 v5, v3
	s_nop 0
	v_mul_f32_e32 v2, v2, v5
	ds_write_b32 v76, v2 offset:39472
	v_rcp_f32_e32 v2, v7
	s_nop 0
	v_mul_f32_e32 v2, v4, v2
	s_cbranch_execz .LBB0_4377
	s_branch .LBB0_4378

.LBB0_4378:
	s_cmpk_gt_i32 s64, 0xfd
	s_cselect_b64 s[28:29], -1, 0
	s_and_b64 s[28:29], s[14:15], s[28:29]
	s_and_b64 vcc, exec, s[28:29]
	ds_write_b32 v76, v2 offset:39728
	s_cbranch_vccnz .LBB0_4380
	s_waitcnt lgkmcnt(0)
	v_add_f32_e32 v2, v56, v18
	v_add_f32_e32 v2, v58, v2
	v_mul_f32_e32 v3, 0x3d372713, v2
	v_mul_f32_e32 v3, v2, v3
	v_fma_f32 v3, v2, v3, v2
	v_mul_f32_e32 v3, 0x3f4c422a, v3
	v_mul_f32_e32 v3, -2.0, v3
	v_mul_f32_e32 v3, 0x3fb8aa3b, v3
	v_exp_f32_e32 v3, v3
	v_add_f32_e32 v4, v55, v19
	v_add_f32_e32 v4, v57, v4
	v_mul_f32_e32 v7, 0x3d372713, v4
	v_add_f32_e32 v3, 1.0, v3
	v_mul_f32_e32 v7, v4, v7
	v_fma_f32 v7, v4, v7, v4
	v_mul_f32_e32 v7, 0x3f4c422a, v7
	v_mul_f32_e32 v7, -2.0, v7
	v_mul_f32_e32 v7, 0x3fb8aa3b, v7
	v_exp_f32_e32 v7, v7
	s_nop 0
	v_add_f32_e32 v7, 1.0, v7
	v_rcp_f32_e32 v5, v3
	s_nop 0
	v_mul_f32_e32 v2, v2, v5
	ds_write_b32 v76, v2 offset:39988
	v_rcp_f32_e32 v2, v7
	s_nop 0
	v_mul_f32_e32 v2, v4, v2
	s_cbranch_execz .LBB0_4381
	s_branch .LBB0_4382

.LBB0_4382:
	s_cmpk_gt_i32 s10, 0xfd
	s_cselect_b64 s[10:11], -1, 0
	s_and_b64 s[10:11], s[14:15], s[10:11]
	s_and_b64 vcc, exec, s[10:11]
	ds_write_b32 v76, v2 offset:40244
	s_cbranch_vccnz .LBB0_4384
	s_waitcnt lgkmcnt(0)
	v_add_f32_e32 v2, v53, v18
	v_add_f32_e32 v2, v54, v2
	v_mul_f32_e32 v3, 0x3d372713, v2
	v_mul_f32_e32 v3, v2, v3
	v_fma_f32 v3, v2, v3, v2
	v_mul_f32_e32 v3, 0x3f4c422a, v3
	v_mul_f32_e32 v3, -2.0, v3
	v_mul_f32_e32 v3, 0x3fb8aa3b, v3
	v_exp_f32_e32 v3, v3
	v_add_f32_e32 v4, v51, v19
	v_add_f32_e32 v4, v52, v4
	v_mul_f32_e32 v7, 0x3d372713, v4
	v_add_f32_e32 v3, 1.0, v3
	v_mul_f32_e32 v7, v4, v7
	v_fma_f32 v7, v4, v7, v4
	v_mul_f32_e32 v7, 0x3f4c422a, v7
	v_mul_f32_e32 v7, -2.0, v7
	v_mul_f32_e32 v7, 0x3fb8aa3b, v7
	v_exp_f32_e32 v7, v7
	s_nop 0
	v_add_f32_e32 v7, 1.0, v7
	v_rcp_f32_e32 v5, v3
	s_nop 0
	v_mul_f32_e32 v2, v2, v5
	ds_write_b32 v76, v2 offset:40504
	v_rcp_f32_e32 v2, v7
	s_nop 0
	v_mul_f32_e32 v2, v4, v2
	s_cbranch_execz .LBB0_4385
	s_branch .LBB0_4386

.LBB0_4386:
	s_cmpk_gt_i32 s6, 0xfd
	s_cselect_b64 s[6:7], -1, 0
	s_and_b64 s[6:7], s[14:15], s[6:7]
	s_and_b64 vcc, exec, s[6:7]
	ds_write_b32 v76, v2 offset:40760
	s_cbranch_vccnz .LBB0_4388
	s_waitcnt lgkmcnt(0)
	v_add_f32_e32 v2, v49, v18
	v_add_f32_e32 v2, v50, v2
	v_mul_f32_e32 v3, 0x3d372713, v2
	v_mul_f32_e32 v3, v2, v3
	v_fma_f32 v3, v2, v3, v2
	v_mul_f32_e32 v3, 0x3f4c422a, v3
	v_mul_f32_e32 v3, -2.0, v3
	v_mul_f32_e32 v3, 0x3fb8aa3b, v3
	v_exp_f32_e32 v3, v3
	v_add_f32_e32 v4, v1, v19
	v_add_f32_e32 v4, v48, v4
	v_mul_f32_e32 v7, 0x3d372713, v4
	v_add_f32_e32 v3, 1.0, v3
	v_mul_f32_e32 v7, v4, v7
	v_fma_f32 v7, v4, v7, v4
	v_mul_f32_e32 v7, 0x3f4c422a, v7
	v_mul_f32_e32 v7, -2.0, v7
	v_mul_f32_e32 v7, 0x3fb8aa3b, v7
	v_exp_f32_e32 v7, v7
	s_nop 0
	v_add_f32_e32 v7, 1.0, v7
	v_rcp_f32_e32 v5, v3
	s_nop 0
	v_mul_f32_e32 v2, v2, v5
	ds_write_b32 v76, v2 offset:41020
	v_rcp_f32_e32 v2, v7
	s_nop 0
	v_mul_f32_e32 v2, v4, v2
	s_cbranch_execz .LBB0_4389
	s_branch .LBB0_4390

.LBB0_4488:
	s_cmpk_gt_i32 s12, 0xfd
	s_cselect_b64 s[28:29], -1, 0
	s_and_b64 s[28:29], s[14:15], s[28:29]
	v_mov_b32_e32 v2, 0
	s_and_b64 vcc, exec, s[28:29]
	v_mov_b32_e32 v3, 0
	s_cbranch_vccnz .LBB0_4490
	v_pk_add_f32 v[2:3], v[38:39], v[18:19]
	s_nop 0
	v_pk_add_f32 v[2:3], v[36:37], v[2:3]
	s_nop 0
	v_mul_f32_e32 v4, 0x3d372713, v2
	v_mul_f32_e32 v5, 0x3d372713, v3
	v_mul_f32_e32 v4, v2, v4
	v_mul_f32_e32 v5, v3, v5
	v_fma_f32 v4, v2, v4, v2
	v_fma_f32 v5, v3, v5, v3
	v_mul_f32_e32 v4, 0x3f4c422a, v4
	v_mul_f32_e32 v5, 0x3f4c422a, v5
	v_mul_f32_e32 v4, -2.0, v4
	v_mul_f32_e32 v5, -2.0, v5
	v_mul_f32_e32 v4, 0x3fb8aa3b, v4
	v_mul_f32_e32 v5, 0x3fb8aa3b, v5
	v_exp_f32_e32 v4, v4
	v_exp_f32_e32 v5, v5
	s_nop 0
	v_pk_add_f32 v[4:5], v[4:5], 1.0 op_sel_hi:[1,0]
	s_nop 0
	s_nop 0
	v_rcp_f32_e32 v6, v4
	s_nop 0
	v_mul_f32_e32 v2, v2, v6
	v_rcp_f32_e32 v4, v5
	s_nop 0
	v_mul_f32_e32 v3, v3, v4
.LBB0_4490:
	s_cmpk_gt_i32 s62, 0xfd
	s_cselect_b64 s[28:29], -1, 0
	s_and_b64 s[28:29], s[14:15], s[28:29]
	s_and_b64 vcc, exec, s[28:29]
	ds_write2st64_b32 v76, v2, v3 offset0:130 offset1:131
	s_cbranch_vccnz .LBB0_4492
	v_add_f32_e32 v2, v177, v18
	v_add_f32_e32 v2, v178, v2
	v_mul_f32_e32 v3, 0x3d372713, v2
	v_mul_f32_e32 v3, v2, v3
	v_fma_f32 v3, v2, v3, v2
	v_mul_f32_e32 v3, 0x3f4c422a, v3
	v_mul_f32_e32 v3, -2.0, v3
	v_mul_f32_e32 v3, 0x3fb8aa3b, v3
	v_exp_f32_e32 v3, v3
	v_add_f32_e32 v4, v175, v19
	v_add_f32_e32 v4, v176, v4
	v_mul_f32_e32 v7, 0x3d372713, v4
	v_add_f32_e32 v3, 1.0, v3
	v_mul_f32_e32 v7, v4, v7
	v_fma_f32 v7, v4, v7, v4
	v_mul_f32_e32 v7, 0x3f4c422a, v7
	v_mul_f32_e32 v7, -2.0, v7
	v_mul_f32_e32 v7, 0x3fb8aa3b, v7
	v_exp_f32_e32 v7, v7
	s_nop 0
	v_add_f32_e32 v7, 1.0, v7
	v_rcp_f32_e32 v5, v3
	s_nop 0
	v_mul_f32_e32 v2, v2, v5
	ds_write_b32 v76, v2 offset:33796
	v_rcp_f32_e32 v2, v7
	s_nop 0
	v_mul_f32_e32 v2, v4, v2
	s_cbranch_execz .LBB0_4493
	s_branch .LBB0_4494

.LBB0_4494:
	s_cmpk_gt_i32 s60, 0xfd
	s_cselect_b64 s[28:29], -1, 0
	s_and_b64 s[28:29], s[14:15], s[28:29]
	s_and_b64 vcc, exec, s[28:29]
	ds_write_b32 v76, v2 offset:34052
	s_cbranch_vccnz .LBB0_4496
	v_add_f32_e32 v2, v173, v18
	v_add_f32_e32 v2, v174, v2
	v_mul_f32_e32 v3, 0x3d372713, v2
	v_mul_f32_e32 v3, v2, v3
	v_fma_f32 v3, v2, v3, v2
	v_mul_f32_e32 v3, 0x3f4c422a, v3
	v_mul_f32_e32 v3, -2.0, v3
	v_mul_f32_e32 v3, 0x3fb8aa3b, v3
	v_exp_f32_e32 v3, v3
	v_add_f32_e32 v4, v171, v19
	v_add_f32_e32 v4, v172, v4
	v_mul_f32_e32 v7, 0x3d372713, v4
	v_add_f32_e32 v3, 1.0, v3
	v_mul_f32_e32 v7, v4, v7
	v_fma_f32 v7, v4, v7, v4
	v_mul_f32_e32 v7, 0x3f4c422a, v7
	v_mul_f32_e32 v7, -2.0, v7
	v_mul_f32_e32 v7, 0x3fb8aa3b, v7
	v_exp_f32_e32 v7, v7
	s_nop 0
	v_add_f32_e32 v7, 1.0, v7
	v_rcp_f32_e32 v5, v3
	s_nop 0
	v_mul_f32_e32 v2, v2, v5
	ds_write_b32 v76, v2 offset:34312
	v_rcp_f32_e32 v2, v7
	s_nop 0
	v_mul_f32_e32 v2, v4, v2
	s_cbranch_execz .LBB0_4497
	s_branch .LBB0_4498

.LBB0_4498:
	s_cmpk_gt_i32 s58, 0xfd
	s_cselect_b64 s[28:29], -1, 0
	s_and_b64 s[28:29], s[14:15], s[28:29]
	s_and_b64 vcc, exec, s[28:29]
	ds_write_b32 v76, v2 offset:34568
	s_cbranch_vccnz .LBB0_4500
	v_add_f32_e32 v2, v169, v18
	v_add_f32_e32 v2, v170, v2
	v_mul_f32_e32 v3, 0x3d372713, v2
	v_mul_f32_e32 v3, v2, v3
	v_fma_f32 v3, v2, v3, v2
	v_mul_f32_e32 v3, 0x3f4c422a, v3
	v_mul_f32_e32 v3, -2.0, v3
	v_mul_f32_e32 v3, 0x3fb8aa3b, v3
	v_exp_f32_e32 v3, v3
	v_add_f32_e32 v4, v167, v19
	v_add_f32_e32 v4, v168, v4
	v_mul_f32_e32 v7, 0x3d372713, v4
	v_add_f32_e32 v3, 1.0, v3
	v_mul_f32_e32 v7, v4, v7
	v_fma_f32 v7, v4, v7, v4
	v_mul_f32_e32 v7, 0x3f4c422a, v7
	v_mul_f32_e32 v7, -2.0, v7
	v_mul_f32_e32 v7, 0x3fb8aa3b, v7
	v_exp_f32_e32 v7, v7
	s_nop 0
	v_add_f32_e32 v7, 1.0, v7
	v_rcp_f32_e32 v5, v3
	s_nop 0
	v_mul_f32_e32 v2, v2, v5
	ds_write_b32 v76, v2 offset:34828
	v_rcp_f32_e32 v2, v7
	s_nop 0
	v_mul_f32_e32 v2, v4, v2
	s_cbranch_execz .LBB0_4501
	s_branch .LBB0_4502

.LBB0_4502:
	s_cmpk_gt_i32 s56, 0xfd
	s_cselect_b64 s[28:29], -1, 0
	s_and_b64 s[28:29], s[14:15], s[28:29]
	s_and_b64 vcc, exec, s[28:29]
	ds_write_b32 v76, v2 offset:35084
	s_cbranch_vccnz .LBB0_4504
	v_add_f32_e32 v2, v165, v18
	v_add_f32_e32 v2, v166, v2
	v_mul_f32_e32 v3, 0x3d372713, v2
	v_mul_f32_e32 v3, v2, v3
	v_fma_f32 v3, v2, v3, v2
	v_mul_f32_e32 v3, 0x3f4c422a, v3
	v_mul_f32_e32 v3, -2.0, v3
	v_mul_f32_e32 v3, 0x3fb8aa3b, v3
	v_exp_f32_e32 v3, v3
	v_add_f32_e32 v4, v163, v19
	v_add_f32_e32 v4, v164, v4
	v_mul_f32_e32 v7, 0x3d372713, v4
	v_add_f32_e32 v3, 1.0, v3
	v_mul_f32_e32 v7, v4, v7
	v_fma_f32 v7, v4, v7, v4
	v_mul_f32_e32 v7, 0x3f4c422a, v7
	v_mul_f32_e32 v7, -2.0, v7
	v_mul_f32_e32 v7, 0x3fb8aa3b, v7
	v_exp_f32_e32 v7, v7
	s_nop 0
	v_add_f32_e32 v7, 1.0, v7
	v_rcp_f32_e32 v5, v3
	s_nop 0
	v_mul_f32_e32 v2, v2, v5
	ds_write_b32 v76, v2 offset:35344
	v_rcp_f32_e32 v2, v7
	s_nop 0
	v_mul_f32_e32 v2, v4, v2
	s_cbranch_execz .LBB0_4505
	s_branch .LBB0_4506

.LBB0_4506:
	s_cmpk_gt_i32 s54, 0xfd
	s_cselect_b64 s[28:29], -1, 0
	s_and_b64 s[28:29], s[14:15], s[28:29]
	s_and_b64 vcc, exec, s[28:29]
	ds_write_b32 v76, v2 offset:35600
	s_cbranch_vccnz .LBB0_4508
	v_add_f32_e32 v2, v161, v18
	v_add_f32_e32 v2, v162, v2
	v_mul_f32_e32 v3, 0x3d372713, v2
	v_mul_f32_e32 v3, v2, v3
	v_fma_f32 v3, v2, v3, v2
	v_mul_f32_e32 v3, 0x3f4c422a, v3
	v_mul_f32_e32 v3, -2.0, v3
	v_mul_f32_e32 v3, 0x3fb8aa3b, v3
	v_exp_f32_e32 v3, v3
	v_add_f32_e32 v4, v159, v19
	v_add_f32_e32 v4, v160, v4
	v_mul_f32_e32 v7, 0x3d372713, v4
	v_add_f32_e32 v3, 1.0, v3
	v_mul_f32_e32 v7, v4, v7
	v_fma_f32 v7, v4, v7, v4
	v_mul_f32_e32 v7, 0x3f4c422a, v7
	v_mul_f32_e32 v7, -2.0, v7
	v_mul_f32_e32 v7, 0x3fb8aa3b, v7
	v_exp_f32_e32 v7, v7
	s_nop 0
	v_add_f32_e32 v7, 1.0, v7
	v_rcp_f32_e32 v5, v3
	s_nop 0
	v_mul_f32_e32 v2, v2, v5
	ds_write_b32 v76, v2 offset:35860
	v_rcp_f32_e32 v2, v7
	s_nop 0
	v_mul_f32_e32 v2, v4, v2
	s_cbranch_execz .LBB0_4509
	s_branch .LBB0_4510

.LBB0_4510:
	s_cmpk_gt_i32 s52, 0xfd
	s_cselect_b64 s[28:29], -1, 0
	s_and_b64 s[28:29], s[14:15], s[28:29]
	s_and_b64 vcc, exec, s[28:29]
	ds_write_b32 v76, v2 offset:36116
	s_cbranch_vccnz .LBB0_4512
	v_add_f32_e32 v2, v157, v18
	v_add_f32_e32 v2, v158, v2
	v_mul_f32_e32 v3, 0x3d372713, v2
	v_mul_f32_e32 v3, v2, v3
	v_fma_f32 v3, v2, v3, v2
	v_mul_f32_e32 v3, 0x3f4c422a, v3
	v_mul_f32_e32 v3, -2.0, v3
	v_mul_f32_e32 v3, 0x3fb8aa3b, v3
	v_exp_f32_e32 v3, v3
	v_add_f32_e32 v4, v155, v19
	v_add_f32_e32 v4, v156, v4
	v_mul_f32_e32 v7, 0x3d372713, v4
	v_add_f32_e32 v3, 1.0, v3
	v_mul_f32_e32 v7, v4, v7
	v_fma_f32 v7, v4, v7, v4
	v_mul_f32_e32 v7, 0x3f4c422a, v7
	v_mul_f32_e32 v7, -2.0, v7
	v_mul_f32_e32 v7, 0x3fb8aa3b, v7
	v_exp_f32_e32 v7, v7
	s_nop 0
	v_add_f32_e32 v7, 1.0, v7
	v_rcp_f32_e32 v5, v3
	s_nop 0
	v_mul_f32_e32 v2, v2, v5
	ds_write_b32 v76, v2 offset:36376
	v_rcp_f32_e32 v2, v7
	s_nop 0
	v_mul_f32_e32 v2, v4, v2
	s_cbranch_execz .LBB0_4513
	s_branch .LBB0_4514

.LBB0_4514:
	s_cmpk_gt_i32 s50, 0xfd
	s_cselect_b64 s[28:29], -1, 0
	s_and_b64 s[28:29], s[14:15], s[28:29]
	s_and_b64 vcc, exec, s[28:29]
	ds_write_b32 v76, v2 offset:36632
	s_cbranch_vccnz .LBB0_4516
	v_add_f32_e32 v2, v153, v18
	v_add_f32_e32 v2, v154, v2
	v_mul_f32_e32 v3, 0x3d372713, v2
	v_mul_f32_e32 v3, v2, v3
	v_fma_f32 v3, v2, v3, v2
	v_mul_f32_e32 v3, 0x3f4c422a, v3
	v_mul_f32_e32 v3, -2.0, v3
	v_mul_f32_e32 v3, 0x3fb8aa3b, v3
	v_exp_f32_e32 v3, v3
	v_add_f32_e32 v4, v151, v19
	v_add_f32_e32 v4, v152, v4
	v_mul_f32_e32 v7, 0x3d372713, v4
	v_add_f32_e32 v3, 1.0, v3
	v_mul_f32_e32 v7, v4, v7
	v_fma_f32 v7, v4, v7, v4
	v_mul_f32_e32 v7, 0x3f4c422a, v7
	v_mul_f32_e32 v7, -2.0, v7
	v_mul_f32_e32 v7, 0x3fb8aa3b, v7
	v_exp_f32_e32 v7, v7
	s_nop 0
	v_add_f32_e32 v7, 1.0, v7
	v_rcp_f32_e32 v5, v3
	s_nop 0
	v_mul_f32_e32 v2, v2, v5
	ds_write_b32 v76, v2 offset:36892
	v_rcp_f32_e32 v2, v7
	s_nop 0
	v_mul_f32_e32 v2, v4, v2
	s_cbranch_execz .LBB0_4517
	s_branch .LBB0_4518

.LBB0_4518:
	s_cmpk_gt_i32 s48, 0xfd
	s_cselect_b64 s[28:29], -1, 0
	s_and_b64 s[28:29], s[14:15], s[28:29]
	s_and_b64 vcc, exec, s[28:29]
	ds_write_b32 v76, v2 offset:37148
	s_cbranch_vccnz .LBB0_4520
	v_add_f32_e32 v2, v149, v18
	v_add_f32_e32 v2, v150, v2
	v_mul_f32_e32 v3, 0x3d372713, v2
	v_mul_f32_e32 v3, v2, v3
	v_fma_f32 v3, v2, v3, v2
	v_mul_f32_e32 v3, 0x3f4c422a, v3
	v_mul_f32_e32 v3, -2.0, v3
	v_mul_f32_e32 v3, 0x3fb8aa3b, v3
	v_exp_f32_e32 v3, v3
	v_add_f32_e32 v4, v147, v19
	v_add_f32_e32 v4, v148, v4
	v_mul_f32_e32 v7, 0x3d372713, v4
	v_add_f32_e32 v3, 1.0, v3
	v_mul_f32_e32 v7, v4, v7
	v_fma_f32 v7, v4, v7, v4
	v_mul_f32_e32 v7, 0x3f4c422a, v7
	v_mul_f32_e32 v7, -2.0, v7
	v_mul_f32_e32 v7, 0x3fb8aa3b, v7
	v_exp_f32_e32 v7, v7
	s_nop 0
	v_add_f32_e32 v7, 1.0, v7
	v_rcp_f32_e32 v5, v3
	s_nop 0
	v_mul_f32_e32 v2, v2, v5
	ds_write_b32 v76, v2 offset:37408
	v_rcp_f32_e32 v2, v7
	s_nop 0
	v_mul_f32_e32 v2, v4, v2
	s_cbranch_execz .LBB0_4521
	s_branch .LBB0_4522

.LBB0_4522:
	s_cmpk_gt_i32 s46, 0xfd
	s_cselect_b64 s[28:29], -1, 0
	s_and_b64 s[28:29], s[14:15], s[28:29]
	s_and_b64 vcc, exec, s[28:29]
	ds_write_b32 v76, v2 offset:37664
	s_cbranch_vccnz .LBB0_4524
	v_add_f32_e32 v2, v145, v18
	v_add_f32_e32 v2, v146, v2
	v_mul_f32_e32 v3, 0x3d372713, v2
	v_mul_f32_e32 v3, v2, v3
	v_fma_f32 v3, v2, v3, v2
	v_mul_f32_e32 v3, 0x3f4c422a, v3
	v_mul_f32_e32 v3, -2.0, v3
	v_mul_f32_e32 v3, 0x3fb8aa3b, v3
	v_exp_f32_e32 v3, v3
	v_add_f32_e32 v4, v143, v19
	v_add_f32_e32 v4, v144, v4
	v_mul_f32_e32 v7, 0x3d372713, v4
	v_add_f32_e32 v3, 1.0, v3
	v_mul_f32_e32 v7, v4, v7
	v_fma_f32 v7, v4, v7, v4
	v_mul_f32_e32 v7, 0x3f4c422a, v7
	v_mul_f32_e32 v7, -2.0, v7
	v_mul_f32_e32 v7, 0x3fb8aa3b, v7
	v_exp_f32_e32 v7, v7
	s_nop 0
	v_add_f32_e32 v7, 1.0, v7
	v_rcp_f32_e32 v5, v3
	s_nop 0
	v_mul_f32_e32 v2, v2, v5
	ds_write_b32 v76, v2 offset:37924
	v_rcp_f32_e32 v2, v7
	s_nop 0
	v_mul_f32_e32 v2, v4, v2
	s_cbranch_execz .LBB0_4525
	s_branch .LBB0_4526

.LBB0_4526:
	s_cmpk_gt_i32 s44, 0xfd
	s_cselect_b64 s[28:29], -1, 0
	s_and_b64 s[28:29], s[14:15], s[28:29]
	s_and_b64 vcc, exec, s[28:29]
	ds_write_b32 v76, v2 offset:38180
	s_cbranch_vccnz .LBB0_4528
	v_add_f32_e32 v2, v141, v18
	v_add_f32_e32 v2, v142, v2
	v_mul_f32_e32 v3, 0x3d372713, v2
	v_mul_f32_e32 v3, v2, v3
	v_fma_f32 v3, v2, v3, v2
	v_mul_f32_e32 v3, 0x3f4c422a, v3
	v_mul_f32_e32 v3, -2.0, v3
	v_mul_f32_e32 v3, 0x3fb8aa3b, v3
	v_exp_f32_e32 v3, v3
	v_add_f32_e32 v4, v139, v19
	v_add_f32_e32 v4, v140, v4
	v_mul_f32_e32 v7, 0x3d372713, v4
	v_add_f32_e32 v3, 1.0, v3
	v_mul_f32_e32 v7, v4, v7
	v_fma_f32 v7, v4, v7, v4
	v_mul_f32_e32 v7, 0x3f4c422a, v7
	v_mul_f32_e32 v7, -2.0, v7
	v_mul_f32_e32 v7, 0x3fb8aa3b, v7
	v_exp_f32_e32 v7, v7
	s_nop 0
	v_add_f32_e32 v7, 1.0, v7
	v_rcp_f32_e32 v5, v3
	s_nop 0
	v_mul_f32_e32 v2, v2, v5
	ds_write_b32 v76, v2 offset:38440
	v_rcp_f32_e32 v2, v7
	s_nop 0
	v_mul_f32_e32 v2, v4, v2
	s_cbranch_execz .LBB0_4529
	s_branch .LBB0_4530

.LBB0_4530:
	s_cmpk_gt_i32 s24, 0xfd
	s_cselect_b64 s[24:25], -1, 0
	s_and_b64 s[24:25], s[14:15], s[24:25]
	s_and_b64 vcc, exec, s[24:25]
	ds_write_b32 v76, v2 offset:38696
	s_cbranch_vccnz .LBB0_4532
	v_add_f32_e32 v2, v137, v18
	v_add_f32_e32 v2, v138, v2
	v_mul_f32_e32 v3, 0x3d372713, v2
	v_mul_f32_e32 v3, v2, v3
	v_fma_f32 v3, v2, v3, v2
	v_mul_f32_e32 v3, 0x3f4c422a, v3
	v_mul_f32_e32 v3, -2.0, v3
	v_mul_f32_e32 v3, 0x3fb8aa3b, v3
	v_exp_f32_e32 v3, v3
	v_add_f32_e32 v4, v135, v19
	v_add_f32_e32 v4, v136, v4
	v_mul_f32_e32 v7, 0x3d372713, v4
	v_add_f32_e32 v3, 1.0, v3
	v_mul_f32_e32 v7, v4, v7
	v_fma_f32 v7, v4, v7, v4
	v_mul_f32_e32 v7, 0x3f4c422a, v7
	v_mul_f32_e32 v7, -2.0, v7
	v_mul_f32_e32 v7, 0x3fb8aa3b, v7
	v_exp_f32_e32 v7, v7
	s_nop 0
	v_add_f32_e32 v7, 1.0, v7
	v_rcp_f32_e32 v5, v3
	s_nop 0
	v_mul_f32_e32 v2, v2, v5
	ds_write_b32 v76, v2 offset:38956
	v_rcp_f32_e32 v2, v7
	s_nop 0
	v_mul_f32_e32 v2, v4, v2
	s_cbranch_execz .LBB0_4533
	s_branch .LBB0_4534

.LBB0_4534:
	s_cmpk_gt_i32 s22, 0xfd
	s_cselect_b64 s[22:23], -1, 0
	s_and_b64 s[22:23], s[14:15], s[22:23]
	s_and_b64 vcc, exec, s[22:23]
	ds_write_b32 v76, v2 offset:39212
	s_cbranch_vccnz .LBB0_4536
	v_add_f32_e32 v2, v129, v18
	v_add_f32_e32 v2, v134, v2
	v_mul_f32_e32 v3, 0x3d372713, v2
	v_mul_f32_e32 v3, v2, v3
	v_fma_f32 v3, v2, v3, v2
	v_mul_f32_e32 v3, 0x3f4c422a, v3
	v_mul_f32_e32 v3, -2.0, v3
	v_mul_f32_e32 v3, 0x3fb8aa3b, v3
	v_exp_f32_e32 v3, v3
	v_add_f32_e32 v4, v127, v19
	v_add_f32_e32 v4, v128, v4
	v_mul_f32_e32 v7, 0x3d372713, v4
	v_add_f32_e32 v3, 1.0, v3
	v_mul_f32_e32 v7, v4, v7
	v_fma_f32 v7, v4, v7, v4
	v_mul_f32_e32 v7, 0x3f4c422a, v7
	v_mul_f32_e32 v7, -2.0, v7
	v_mul_f32_e32 v7, 0x3fb8aa3b, v7
	v_exp_f32_e32 v7, v7
	s_nop 0
	v_add_f32_e32 v7, 1.0, v7
	v_rcp_f32_e32 v5, v3
	s_nop 0
	v_mul_f32_e32 v2, v2, v5
	ds_write_b32 v76, v2 offset:39472
	v_rcp_f32_e32 v2, v7
	s_nop 0
	v_mul_f32_e32 v2, v4, v2
	s_cbranch_execz .LBB0_4537
	s_branch .LBB0_4538

.LBB0_4538:
	s_cmpk_gt_i32 s20, 0xfd
	s_cselect_b64 s[20:21], -1, 0
	s_and_b64 s[20:21], s[14:15], s[20:21]
	s_and_b64 vcc, exec, s[20:21]
	ds_write_b32 v76, v2 offset:39728
	s_cbranch_vccnz .LBB0_4540
	v_add_f32_e32 v2, v125, v18
	v_add_f32_e32 v2, v126, v2
	v_mul_f32_e32 v3, 0x3d372713, v2
	v_mul_f32_e32 v3, v2, v3
	v_fma_f32 v3, v2, v3, v2
	v_mul_f32_e32 v3, 0x3f4c422a, v3
	v_mul_f32_e32 v3, -2.0, v3
	v_mul_f32_e32 v3, 0x3fb8aa3b, v3
	v_exp_f32_e32 v3, v3
	v_add_f32_e32 v4, v123, v19
	v_add_f32_e32 v4, v124, v4
	v_mul_f32_e32 v7, 0x3d372713, v4
	v_add_f32_e32 v3, 1.0, v3
	v_mul_f32_e32 v7, v4, v7
	v_fma_f32 v7, v4, v7, v4
	v_mul_f32_e32 v7, 0x3f4c422a, v7
	v_mul_f32_e32 v7, -2.0, v7
	v_mul_f32_e32 v7, 0x3fb8aa3b, v7
	v_exp_f32_e32 v7, v7
	s_nop 0
	v_add_f32_e32 v7, 1.0, v7
	v_rcp_f32_e32 v5, v3
	s_nop 0
	v_mul_f32_e32 v2, v2, v5
	ds_write_b32 v76, v2 offset:39988
	v_rcp_f32_e32 v2, v7
	s_nop 0
	v_mul_f32_e32 v2, v4, v2
	s_cbranch_execz .LBB0_4541
	s_branch .LBB0_4542

.LBB0_4542:
	s_cmpk_gt_i32 s18, 0xfd
	s_cselect_b64 s[18:19], -1, 0
	s_and_b64 s[18:19], s[14:15], s[18:19]
	s_and_b64 vcc, exec, s[18:19]
	ds_write_b32 v76, v2 offset:40244
	s_cbranch_vccnz .LBB0_4544
	v_add_f32_e32 v2, v121, v18
	v_add_f32_e32 v2, v122, v2
	v_mul_f32_e32 v3, 0x3d372713, v2
	v_mul_f32_e32 v3, v2, v3
	v_fma_f32 v3, v2, v3, v2
	v_mul_f32_e32 v3, 0x3f4c422a, v3
	v_mul_f32_e32 v3, -2.0, v3
	v_mul_f32_e32 v3, 0x3fb8aa3b, v3
	v_exp_f32_e32 v3, v3
	v_add_f32_e32 v4, v119, v19
	v_add_f32_e32 v4, v120, v4
	v_mul_f32_e32 v7, 0x3d372713, v4
	v_add_f32_e32 v3, 1.0, v3
	v_mul_f32_e32 v7, v4, v7
	v_fma_f32 v7, v4, v7, v4
	v_mul_f32_e32 v7, 0x3f4c422a, v7
	v_mul_f32_e32 v7, -2.0, v7
	v_mul_f32_e32 v7, 0x3fb8aa3b, v7
	v_exp_f32_e32 v7, v7
	s_nop 0
	v_add_f32_e32 v7, 1.0, v7
	v_rcp_f32_e32 v5, v3
	s_nop 0
	v_mul_f32_e32 v2, v2, v5
	ds_write_b32 v76, v2 offset:40504
	v_rcp_f32_e32 v2, v7
	s_nop 0
	v_mul_f32_e32 v2, v4, v2
	s_cbranch_execz .LBB0_4545
	s_branch .LBB0_4546

.LBB0_4546:
	s_cmpk_gt_i32 s16, 0xfd
	s_cselect_b64 s[16:17], -1, 0
	s_and_b64 s[16:17], s[14:15], s[16:17]
	s_and_b64 vcc, exec, s[16:17]
	ds_write_b32 v76, v2 offset:40760
	s_cbranch_vccnz .LBB0_4548
	v_add_f32_e32 v2, v117, v18
	v_add_f32_e32 v2, v118, v2
	v_mul_f32_e32 v3, 0x3d372713, v2
	v_mul_f32_e32 v3, v2, v3
	v_fma_f32 v3, v2, v3, v2
	v_mul_f32_e32 v3, 0x3f4c422a, v3
	v_mul_f32_e32 v3, -2.0, v3
	v_mul_f32_e32 v3, 0x3fb8aa3b, v3
	v_exp_f32_e32 v3, v3
	v_add_f32_e32 v4, v115, v19
	v_add_f32_e32 v4, v116, v4
	v_mul_f32_e32 v7, 0x3d372713, v4
	v_add_f32_e32 v3, 1.0, v3
	v_mul_f32_e32 v7, v4, v7
	v_fma_f32 v7, v4, v7, v4
	v_mul_f32_e32 v7, 0x3f4c422a, v7
	v_mul_f32_e32 v7, -2.0, v7
	v_mul_f32_e32 v7, 0x3fb8aa3b, v7
	v_exp_f32_e32 v7, v7
	s_nop 0
	v_add_f32_e32 v7, 1.0, v7
	v_rcp_f32_e32 v5, v3
	s_nop 0
	v_mul_f32_e32 v2, v2, v5
	ds_write_b32 v76, v2 offset:41020
	v_rcp_f32_e32 v2, v7
	s_nop 0
	v_mul_f32_e32 v2, v4, v2
	s_cbranch_execz .LBB0_4549
	s_branch .LBB0_4550

.LBB0_4651:
	s_ashr_i32 s2, s6, 1
	s_cmp_lt_i32 s2, 8
	s_cselect_b64 s[14:15], -1, 0
	s_cmp_gt_i32 s2, 7
	s_cselect_b64 s[12:13], -1, 0
	s_and_b32 s3, s2, 3
	s_cmp_eq_u32 s3, 3
	s_cselect_b64 s[16:17], -1, 0
	s_or_b64 s[12:13], s[12:13], s[16:17]
	s_cmpk_gt_i32 s8, 0xfd
	s_cselect_b64 s[16:17], -1, 0
	s_and_b64 s[16:17], s[16:17], s[12:13]
	v_mov_b32_e32 v2, 0
	s_and_b64 vcc, exec, s[16:17]
	v_mov_b32_e32 v3, 0
	s_cbranch_vccnz .LBB0_4653
	s_waitcnt vmcnt(0) lgkmcnt(0)
	v_pk_add_f32 v[2:3], v[18:19], v[20:21]
	s_nop 0
	v_pk_add_f32 v[2:3], v[2:3], v[22:23]
	s_nop 0
	v_mul_f32_e32 v4, 0x3d372713, v2
	v_mul_f32_e32 v5, 0x3d372713, v3
	v_mul_f32_e32 v4, v2, v4
	v_mul_f32_e32 v5, v3, v5
	v_fma_f32 v4, v2, v4, v2
	v_fma_f32 v5, v3, v5, v3
	v_mul_f32_e32 v4, 0x3f4c422a, v4
	v_mul_f32_e32 v5, 0x3f4c422a, v5
	v_mul_f32_e32 v4, -2.0, v4
	v_mul_f32_e32 v5, -2.0, v5
	v_mul_f32_e32 v4, 0x3fb8aa3b, v4
	v_mul_f32_e32 v5, 0x3fb8aa3b, v5
	v_exp_f32_e32 v4, v4
	v_exp_f32_e32 v5, v5
	s_nop 0
	v_pk_add_f32 v[4:5], v[4:5], 1.0 op_sel_hi:[1,0]
	s_nop 0
	s_nop 0
	v_rcp_f32_e32 v6, v4
	s_nop 0
	v_mul_f32_e32 v2, v2, v6
	v_rcp_f32_e32 v4, v5
	s_nop 0
	v_mul_f32_e32 v3, v3, v4
.LBB0_4653:
	s_cmpk_gt_i32 s8, 0xfc
	s_cselect_b64 s[16:17], -1, 0
	s_and_b64 s[16:17], s[16:17], s[12:13]
	s_and_b64 vcc, exec, s[16:17]
	ds_write2st64_b32 v76, v2, v3 offset0:130 offset1:131
	s_cbranch_vccnz .LBB0_4655
	s_waitcnt vmcnt(0) lgkmcnt(0)
	v_add_f32_e32 v2, v18, v107
	v_add_f32_e32 v2, v2, v108
	v_mul_f32_e32 v3, 0x3d372713, v2
	v_mul_f32_e32 v3, v2, v3
	v_fma_f32 v3, v2, v3, v2
	v_mul_f32_e32 v3, 0x3f4c422a, v3
	v_mul_f32_e32 v3, -2.0, v3
	v_mul_f32_e32 v3, 0x3fb8aa3b, v3
	v_exp_f32_e32 v3, v3
	v_add_f32_e32 v4, v19, v105
	v_add_f32_e32 v4, v4, v106
	v_mul_f32_e32 v7, 0x3d372713, v4
	v_add_f32_e32 v3, 1.0, v3
	v_mul_f32_e32 v7, v4, v7
	v_fma_f32 v7, v4, v7, v4
	v_mul_f32_e32 v7, 0x3f4c422a, v7
	v_mul_f32_e32 v7, -2.0, v7
	v_mul_f32_e32 v7, 0x3fb8aa3b, v7
	v_exp_f32_e32 v7, v7
	s_nop 0
	v_add_f32_e32 v7, 1.0, v7
	v_rcp_f32_e32 v5, v3
	s_nop 0
	v_mul_f32_e32 v2, v2, v5
	ds_write_b32 v76, v2 offset:33796
	v_rcp_f32_e32 v2, v7
	s_nop 0
	v_mul_f32_e32 v2, v4, v2
	s_cbranch_execz .LBB0_4656
	s_branch .LBB0_4657

.LBB0_4657:
	s_or_b32 s7, s8, 2
	s_cmpk_gt_i32 s7, 0xfd
	s_cselect_b64 s[16:17], -1, 0
	s_and_b64 s[16:17], s[16:17], s[12:13]
	s_and_b64 vcc, exec, s[16:17]
	ds_write_b32 v76, v2 offset:34052
	s_cbranch_vccnz .LBB0_4659
	s_waitcnt vmcnt(0) lgkmcnt(0)
	v_add_f32_e32 v2, v18, v103
	v_add_f32_e32 v2, v2, v104
	v_mul_f32_e32 v3, 0x3d372713, v2
	v_mul_f32_e32 v3, v2, v3
	v_fma_f32 v3, v2, v3, v2
	v_mul_f32_e32 v3, 0x3f4c422a, v3
	v_mul_f32_e32 v3, -2.0, v3
	v_mul_f32_e32 v3, 0x3fb8aa3b, v3
	v_exp_f32_e32 v3, v3
	v_add_f32_e32 v4, v19, v100
	v_add_f32_e32 v4, v4, v102
	v_mul_f32_e32 v7, 0x3d372713, v4
	v_add_f32_e32 v3, 1.0, v3
	v_mul_f32_e32 v7, v4, v7
	v_fma_f32 v7, v4, v7, v4
	v_mul_f32_e32 v7, 0x3f4c422a, v7
	v_mul_f32_e32 v7, -2.0, v7
	v_mul_f32_e32 v7, 0x3fb8aa3b, v7
	v_exp_f32_e32 v7, v7
	s_nop 0
	v_add_f32_e32 v7, 1.0, v7
	v_rcp_f32_e32 v5, v3
	s_nop 0
	v_mul_f32_e32 v2, v2, v5
	ds_write_b32 v76, v2 offset:34312
	v_rcp_f32_e32 v2, v7
	s_nop 0
	v_mul_f32_e32 v2, v4, v2
	s_cbranch_execz .LBB0_4660
	s_branch .LBB0_4661

.LBB0_4661:
	s_or_b32 s7, s8, 3
	s_cmpk_gt_i32 s7, 0xfd
	s_cselect_b64 s[16:17], -1, 0
	s_and_b64 s[16:17], s[16:17], s[12:13]
	s_and_b64 vcc, exec, s[16:17]
	ds_write_b32 v76, v2 offset:34568
	s_cbranch_vccnz .LBB0_4663
	s_waitcnt vmcnt(0) lgkmcnt(0)
	v_add_f32_e32 v2, v18, v98
	v_add_f32_e32 v2, v2, v101
	v_mul_f32_e32 v3, 0x3d372713, v2
	v_mul_f32_e32 v3, v2, v3
	v_fma_f32 v3, v2, v3, v2
	v_mul_f32_e32 v3, 0x3f4c422a, v3
	v_mul_f32_e32 v3, -2.0, v3
	v_mul_f32_e32 v3, 0x3fb8aa3b, v3
	v_exp_f32_e32 v3, v3
	v_add_f32_e32 v4, v19, v97
	v_add_f32_e32 v4, v4, v99
	v_mul_f32_e32 v7, 0x3d372713, v4
	v_add_f32_e32 v3, 1.0, v3
	v_mul_f32_e32 v7, v4, v7
	v_fma_f32 v7, v4, v7, v4
	v_mul_f32_e32 v7, 0x3f4c422a, v7
	v_mul_f32_e32 v7, -2.0, v7
	v_mul_f32_e32 v7, 0x3fb8aa3b, v7
	v_exp_f32_e32 v7, v7
	s_nop 0
	v_add_f32_e32 v7, 1.0, v7
	v_rcp_f32_e32 v5, v3
	s_nop 0
	v_mul_f32_e32 v2, v2, v5
	ds_write_b32 v76, v2 offset:34828
	v_rcp_f32_e32 v2, v7
	s_nop 0
	v_mul_f32_e32 v2, v4, v2
	s_cbranch_execz .LBB0_4664
	s_branch .LBB0_4665

.LBB0_4665:
	s_or_b32 s7, s8, 4
	s_cmpk_gt_i32 s7, 0xfd
	s_cselect_b64 s[16:17], -1, 0
	s_and_b64 s[16:17], s[16:17], s[12:13]
	s_and_b64 vcc, exec, s[16:17]
	ds_write_b32 v76, v2 offset:35084
	s_cbranch_vccnz .LBB0_4667
	s_waitcnt vmcnt(0) lgkmcnt(0)
	v_add_f32_e32 v2, v18, v94
	v_add_f32_e32 v2, v2, v96
	v_mul_f32_e32 v3, 0x3d372713, v2
	v_mul_f32_e32 v3, v2, v3
	v_fma_f32 v3, v2, v3, v2
	v_mul_f32_e32 v3, 0x3f4c422a, v3
	v_mul_f32_e32 v3, -2.0, v3
	v_mul_f32_e32 v3, 0x3fb8aa3b, v3
	v_exp_f32_e32 v3, v3
	v_add_f32_e32 v4, v19, v93
	v_add_f32_e32 v4, v4, v95
	v_mul_f32_e32 v7, 0x3d372713, v4
	v_add_f32_e32 v3, 1.0, v3
	v_mul_f32_e32 v7, v4, v7
	v_fma_f32 v7, v4, v7, v4
	v_mul_f32_e32 v7, 0x3f4c422a, v7
	v_mul_f32_e32 v7, -2.0, v7
	v_mul_f32_e32 v7, 0x3fb8aa3b, v7
	v_exp_f32_e32 v7, v7
	s_nop 0
	v_add_f32_e32 v7, 1.0, v7
	v_rcp_f32_e32 v5, v3
	s_nop 0
	v_mul_f32_e32 v2, v2, v5
	ds_write_b32 v76, v2 offset:35344
	v_rcp_f32_e32 v2, v7
	s_nop 0
	v_mul_f32_e32 v2, v4, v2
	s_cbranch_execz .LBB0_4668
	s_branch .LBB0_4669

.LBB0_4669:
	s_or_b32 s7, s8, 5
	s_cmpk_gt_i32 s7, 0xfd
	s_cselect_b64 s[16:17], -1, 0
	s_and_b64 s[16:17], s[16:17], s[12:13]
	s_and_b64 vcc, exec, s[16:17]
	ds_write_b32 v76, v2 offset:35600
	s_cbranch_vccnz .LBB0_4671
	s_waitcnt vmcnt(0) lgkmcnt(0)
	v_add_f32_e32 v2, v18, v90
	v_add_f32_e32 v2, v2, v92
	v_mul_f32_e32 v3, 0x3d372713, v2
	v_mul_f32_e32 v3, v2, v3
	v_fma_f32 v3, v2, v3, v2
	v_mul_f32_e32 v3, 0x3f4c422a, v3
	v_mul_f32_e32 v3, -2.0, v3
	v_mul_f32_e32 v3, 0x3fb8aa3b, v3
	v_exp_f32_e32 v3, v3
	v_add_f32_e32 v4, v19, v89
	v_add_f32_e32 v4, v4, v91
	v_mul_f32_e32 v7, 0x3d372713, v4
	v_add_f32_e32 v3, 1.0, v3
	v_mul_f32_e32 v7, v4, v7
	v_fma_f32 v7, v4, v7, v4
	v_mul_f32_e32 v7, 0x3f4c422a, v7
	v_mul_f32_e32 v7, -2.0, v7
	v_mul_f32_e32 v7, 0x3fb8aa3b, v7
	v_exp_f32_e32 v7, v7
	s_nop 0
	v_add_f32_e32 v7, 1.0, v7
	v_rcp_f32_e32 v5, v3
	s_nop 0
	v_mul_f32_e32 v2, v2, v5
	ds_write_b32 v76, v2 offset:35860
	v_rcp_f32_e32 v2, v7
	s_nop 0
	v_mul_f32_e32 v2, v4, v2
	s_cbranch_execz .LBB0_4672
	s_branch .LBB0_4673

.LBB0_4673:
	s_or_b32 s7, s8, 6
	s_cmpk_gt_i32 s7, 0xfd
	s_cselect_b64 s[16:17], -1, 0
	s_and_b64 s[16:17], s[16:17], s[12:13]
	s_and_b64 vcc, exec, s[16:17]
	ds_write_b32 v76, v2 offset:36116
	s_cbranch_vccnz .LBB0_4675
	s_waitcnt vmcnt(0) lgkmcnt(0)
	v_add_f32_e32 v2, v18, v87
	v_add_f32_e32 v2, v2, v88
	v_mul_f32_e32 v3, 0x3d372713, v2
	v_mul_f32_e32 v3, v2, v3
	v_fma_f32 v3, v2, v3, v2
	v_mul_f32_e32 v3, 0x3f4c422a, v3
	v_mul_f32_e32 v3, -2.0, v3
	v_mul_f32_e32 v3, 0x3fb8aa3b, v3
	v_exp_f32_e32 v3, v3
	v_add_f32_e32 v4, v19, v85
	v_add_f32_e32 v4, v4, v86
	v_mul_f32_e32 v7, 0x3d372713, v4
	v_add_f32_e32 v3, 1.0, v3
	v_mul_f32_e32 v7, v4, v7
	v_fma_f32 v7, v4, v7, v4
	v_mul_f32_e32 v7, 0x3f4c422a, v7
	v_mul_f32_e32 v7, -2.0, v7
	v_mul_f32_e32 v7, 0x3fb8aa3b, v7
	v_exp_f32_e32 v7, v7
	s_nop 0
	v_add_f32_e32 v7, 1.0, v7
	v_rcp_f32_e32 v5, v3
	s_nop 0
	v_mul_f32_e32 v2, v2, v5
	ds_write_b32 v76, v2 offset:36376
	v_rcp_f32_e32 v2, v7
	s_nop 0
	v_mul_f32_e32 v2, v4, v2
	s_cbranch_execz .LBB0_4676
	s_branch .LBB0_4677

.LBB0_4677:
	s_or_b32 s7, s8, 7
	s_cmpk_gt_i32 s7, 0xfd
	s_cselect_b64 s[16:17], -1, 0
	s_and_b64 s[16:17], s[16:17], s[12:13]
	s_and_b64 vcc, exec, s[16:17]
	ds_write_b32 v76, v2 offset:36632
	s_cbranch_vccnz .LBB0_4679
	s_waitcnt vmcnt(0) lgkmcnt(0)
	v_add_f32_e32 v2, v18, v82
	v_add_f32_e32 v2, v2, v84
	v_mul_f32_e32 v3, 0x3d372713, v2
	v_mul_f32_e32 v3, v2, v3
	v_fma_f32 v3, v2, v3, v2
	v_mul_f32_e32 v3, 0x3f4c422a, v3
	v_mul_f32_e32 v3, -2.0, v3
	v_mul_f32_e32 v3, 0x3fb8aa3b, v3
	v_exp_f32_e32 v3, v3
	v_add_f32_e32 v4, v19, v81
	v_add_f32_e32 v4, v4, v83
	v_mul_f32_e32 v7, 0x3d372713, v4
	v_add_f32_e32 v3, 1.0, v3
	v_mul_f32_e32 v7, v4, v7
	v_fma_f32 v7, v4, v7, v4
	v_mul_f32_e32 v7, 0x3f4c422a, v7
	v_mul_f32_e32 v7, -2.0, v7
	v_mul_f32_e32 v7, 0x3fb8aa3b, v7
	v_exp_f32_e32 v7, v7
	s_nop 0
	v_add_f32_e32 v7, 1.0, v7
	v_rcp_f32_e32 v5, v3
	s_nop 0
	v_mul_f32_e32 v2, v2, v5
	ds_write_b32 v76, v2 offset:36892
	v_rcp_f32_e32 v2, v7
	s_nop 0
	v_mul_f32_e32 v2, v4, v2
	s_cbranch_execz .LBB0_4680
	s_branch .LBB0_4681

.LBB0_4681:
	s_or_b32 s7, s8, 8
	s_cmpk_gt_i32 s7, 0xfd
	s_cselect_b64 s[16:17], -1, 0
	s_and_b64 s[16:17], s[16:17], s[12:13]
	s_and_b64 vcc, exec, s[16:17]
	ds_write_b32 v76, v2 offset:37148
	s_cbranch_vccnz .LBB0_4683
	s_waitcnt vmcnt(0) lgkmcnt(0)
	v_add_f32_e32 v2, v18, v79
	v_add_f32_e32 v2, v2, v80
	v_mul_f32_e32 v3, 0x3d372713, v2
	v_mul_f32_e32 v3, v2, v3
	v_fma_f32 v3, v2, v3, v2
	v_mul_f32_e32 v3, 0x3f4c422a, v3
	v_mul_f32_e32 v3, -2.0, v3
	v_mul_f32_e32 v3, 0x3fb8aa3b, v3
	v_exp_f32_e32 v3, v3
	v_add_f32_e32 v4, v19, v77
	v_add_f32_e32 v4, v4, v78
	v_mul_f32_e32 v7, 0x3d372713, v4
	v_add_f32_e32 v3, 1.0, v3
	v_mul_f32_e32 v7, v4, v7
	v_fma_f32 v7, v4, v7, v4
	v_mul_f32_e32 v7, 0x3f4c422a, v7
	v_mul_f32_e32 v7, -2.0, v7
	v_mul_f32_e32 v7, 0x3fb8aa3b, v7
	v_exp_f32_e32 v7, v7
	s_nop 0
	v_add_f32_e32 v7, 1.0, v7
	v_rcp_f32_e32 v5, v3
	s_nop 0
	v_mul_f32_e32 v2, v2, v5
	ds_write_b32 v76, v2 offset:37408
	v_rcp_f32_e32 v2, v7
	s_nop 0
	v_mul_f32_e32 v2, v4, v2
	s_cbranch_execz .LBB0_4684
	s_branch .LBB0_4685

.LBB0_4685:
	s_or_b32 s7, s8, 9
	s_cmpk_gt_i32 s7, 0xfd
	s_cselect_b64 s[16:17], -1, 0
	s_and_b64 s[16:17], s[16:17], s[12:13]
	s_and_b64 vcc, exec, s[16:17]
	ds_write_b32 v76, v2 offset:37664
	s_cbranch_vccnz .LBB0_4687
	s_waitcnt vmcnt(0) lgkmcnt(0)
	v_add_f32_e32 v2, v18, v73
	v_add_f32_e32 v2, v2, v75
	v_mul_f32_e32 v3, 0x3d372713, v2
	v_mul_f32_e32 v3, v2, v3
	v_fma_f32 v3, v2, v3, v2
	v_mul_f32_e32 v3, 0x3f4c422a, v3
	v_mul_f32_e32 v3, -2.0, v3
	v_mul_f32_e32 v3, 0x3fb8aa3b, v3
	v_exp_f32_e32 v3, v3
	v_add_f32_e32 v4, v19, v72
	v_add_f32_e32 v4, v4, v74
	v_mul_f32_e32 v7, 0x3d372713, v4
	v_add_f32_e32 v3, 1.0, v3
	v_mul_f32_e32 v7, v4, v7
	v_fma_f32 v7, v4, v7, v4
	v_mul_f32_e32 v7, 0x3f4c422a, v7
	v_mul_f32_e32 v7, -2.0, v7
	v_mul_f32_e32 v7, 0x3fb8aa3b, v7
	v_exp_f32_e32 v7, v7
	s_nop 0
	v_add_f32_e32 v7, 1.0, v7
	v_rcp_f32_e32 v5, v3
	s_nop 0
	v_mul_f32_e32 v2, v2, v5
	ds_write_b32 v76, v2 offset:37924
	v_rcp_f32_e32 v2, v7
	s_nop 0
	v_mul_f32_e32 v2, v4, v2
	s_cbranch_execz .LBB0_4688
	s_branch .LBB0_4689

.LBB0_4689:
	s_or_b32 s7, s8, 10
	s_cmpk_gt_i32 s7, 0xfd
	s_cselect_b64 s[16:17], -1, 0
	s_and_b64 s[16:17], s[16:17], s[12:13]
	s_and_b64 vcc, exec, s[16:17]
	ds_write_b32 v76, v2 offset:38180
	s_cbranch_vccnz .LBB0_4691
	s_waitcnt vmcnt(0) lgkmcnt(0)
	v_add_f32_e32 v2, v18, v70
	v_add_f32_e32 v2, v2, v71
	v_mul_f32_e32 v3, 0x3d372713, v2
	v_mul_f32_e32 v3, v2, v3
	v_fma_f32 v3, v2, v3, v2
	v_mul_f32_e32 v3, 0x3f4c422a, v3
	v_mul_f32_e32 v3, -2.0, v3
	v_mul_f32_e32 v3, 0x3fb8aa3b, v3
	v_exp_f32_e32 v3, v3
	v_add_f32_e32 v4, v19, v68
	v_add_f32_e32 v4, v4, v69
	v_mul_f32_e32 v7, 0x3d372713, v4
	v_add_f32_e32 v3, 1.0, v3
	v_mul_f32_e32 v7, v4, v7
	v_fma_f32 v7, v4, v7, v4
	v_mul_f32_e32 v7, 0x3f4c422a, v7
	v_mul_f32_e32 v7, -2.0, v7
	v_mul_f32_e32 v7, 0x3fb8aa3b, v7
	v_exp_f32_e32 v7, v7
	s_nop 0
	v_add_f32_e32 v7, 1.0, v7
	v_rcp_f32_e32 v5, v3
	s_nop 0
	v_mul_f32_e32 v2, v2, v5
	ds_write_b32 v76, v2 offset:38440
	v_rcp_f32_e32 v2, v7
	s_nop 0
	v_mul_f32_e32 v2, v4, v2
	s_cbranch_execz .LBB0_4692
	s_branch .LBB0_4693

.LBB0_4693:
	s_or_b32 s7, s8, 11
	s_cmpk_gt_i32 s7, 0xfd
	s_cselect_b64 s[16:17], -1, 0
	s_and_b64 s[16:17], s[16:17], s[12:13]
	s_and_b64 vcc, exec, s[16:17]
	ds_write_b32 v76, v2 offset:38696
	s_cbranch_vccnz .LBB0_4695
	s_waitcnt vmcnt(0) lgkmcnt(0)
	v_add_f32_e32 v2, v18, v65
	v_add_f32_e32 v2, v2, v67
	v_mul_f32_e32 v3, 0x3d372713, v2
	v_mul_f32_e32 v3, v2, v3
	v_fma_f32 v3, v2, v3, v2
	v_mul_f32_e32 v3, 0x3f4c422a, v3
	v_mul_f32_e32 v3, -2.0, v3
	v_mul_f32_e32 v3, 0x3fb8aa3b, v3
	v_exp_f32_e32 v3, v3
	v_add_f32_e32 v4, v19, v64
	v_add_f32_e32 v4, v4, v66
	v_mul_f32_e32 v7, 0x3d372713, v4
	v_add_f32_e32 v3, 1.0, v3
	v_mul_f32_e32 v7, v4, v7
	v_fma_f32 v7, v4, v7, v4
	v_mul_f32_e32 v7, 0x3f4c422a, v7
	v_mul_f32_e32 v7, -2.0, v7
	v_mul_f32_e32 v7, 0x3fb8aa3b, v7
	v_exp_f32_e32 v7, v7
	s_nop 0
	v_add_f32_e32 v7, 1.0, v7
	v_rcp_f32_e32 v5, v3
	s_nop 0
	v_mul_f32_e32 v2, v2, v5
	ds_write_b32 v76, v2 offset:38956
	v_rcp_f32_e32 v2, v7
	s_nop 0
	v_mul_f32_e32 v2, v4, v2
	s_cbranch_execz .LBB0_4696
	s_branch .LBB0_4697

.LBB0_4697:
	s_or_b32 s7, s8, 12
	s_cmpk_gt_i32 s7, 0xfd
	s_cselect_b64 s[16:17], -1, 0
	s_and_b64 s[16:17], s[16:17], s[12:13]
	s_and_b64 vcc, exec, s[16:17]
	ds_write_b32 v76, v2 offset:39212
	s_cbranch_vccnz .LBB0_4699
	s_waitcnt vmcnt(0) lgkmcnt(0)
	v_add_f32_e32 v2, v18, v62
	v_add_f32_e32 v2, v2, v63
	v_mul_f32_e32 v3, 0x3d372713, v2
	v_mul_f32_e32 v3, v2, v3
	v_fma_f32 v3, v2, v3, v2
	v_mul_f32_e32 v3, 0x3f4c422a, v3
	v_mul_f32_e32 v3, -2.0, v3
	v_mul_f32_e32 v3, 0x3fb8aa3b, v3
	v_exp_f32_e32 v3, v3
	v_add_f32_e32 v4, v19, v60
	v_add_f32_e32 v4, v4, v61
	v_mul_f32_e32 v7, 0x3d372713, v4
	v_add_f32_e32 v3, 1.0, v3
	v_mul_f32_e32 v7, v4, v7
	v_fma_f32 v7, v4, v7, v4
	v_mul_f32_e32 v7, 0x3f4c422a, v7
	v_mul_f32_e32 v7, -2.0, v7
	v_mul_f32_e32 v7, 0x3fb8aa3b, v7
	v_exp_f32_e32 v7, v7
	s_nop 0
	v_add_f32_e32 v7, 1.0, v7
	v_rcp_f32_e32 v5, v3
	s_nop 0
	v_mul_f32_e32 v2, v2, v5
	ds_write_b32 v76, v2 offset:39472
	v_rcp_f32_e32 v2, v7
	s_nop 0
	v_mul_f32_e32 v2, v4, v2
	s_cbranch_execz .LBB0_4700
	s_branch .LBB0_4701

.LBB0_4701:
	s_or_b32 s7, s8, 13
	s_cmpk_gt_i32 s7, 0xfd
	s_cselect_b64 s[16:17], -1, 0
	s_and_b64 s[16:17], s[16:17], s[12:13]
	s_and_b64 vcc, exec, s[16:17]
	ds_write_b32 v76, v2 offset:39728
	s_cbranch_vccnz .LBB0_4703
	s_waitcnt vmcnt(0) lgkmcnt(0)
	v_add_f32_e32 v2, v18, v56
	v_add_f32_e32 v2, v2, v58
	v_mul_f32_e32 v3, 0x3d372713, v2
	v_mul_f32_e32 v3, v2, v3
	v_fma_f32 v3, v2, v3, v2
	v_mul_f32_e32 v3, 0x3f4c422a, v3
	v_mul_f32_e32 v3, -2.0, v3
	v_mul_f32_e32 v3, 0x3fb8aa3b, v3
	v_exp_f32_e32 v3, v3
	v_add_f32_e32 v4, v19, v55
	v_add_f32_e32 v4, v4, v57
	v_mul_f32_e32 v7, 0x3d372713, v4
	v_add_f32_e32 v3, 1.0, v3
	v_mul_f32_e32 v7, v4, v7
	v_fma_f32 v7, v4, v7, v4
	v_mul_f32_e32 v7, 0x3f4c422a, v7
	v_mul_f32_e32 v7, -2.0, v7
	v_mul_f32_e32 v7, 0x3fb8aa3b, v7
	v_exp_f32_e32 v7, v7
	s_nop 0
	v_add_f32_e32 v7, 1.0, v7
	v_rcp_f32_e32 v5, v3
	s_nop 0
	v_mul_f32_e32 v2, v2, v5
	ds_write_b32 v76, v2 offset:39988
	v_rcp_f32_e32 v2, v7
	s_nop 0
	v_mul_f32_e32 v2, v4, v2
	s_cbranch_execz .LBB0_4704
	s_branch .LBB0_4705

.LBB0_4705:
	s_or_b32 s7, s8, 14
	s_cmpk_gt_i32 s7, 0xfd
	s_cselect_b64 s[16:17], -1, 0
	s_and_b64 s[16:17], s[16:17], s[12:13]
	s_and_b64 vcc, exec, s[16:17]
	ds_write_b32 v76, v2 offset:40244
	s_cbranch_vccnz .LBB0_4707
	s_waitcnt vmcnt(0) lgkmcnt(0)
	v_add_f32_e32 v2, v18, v53
	v_add_f32_e32 v2, v2, v54
	v_mul_f32_e32 v3, 0x3d372713, v2
	v_mul_f32_e32 v3, v2, v3
	v_fma_f32 v3, v2, v3, v2
	v_mul_f32_e32 v3, 0x3f4c422a, v3
	v_mul_f32_e32 v3, -2.0, v3
	v_mul_f32_e32 v3, 0x3fb8aa3b, v3
	v_exp_f32_e32 v3, v3
	v_add_f32_e32 v4, v19, v51
	v_add_f32_e32 v4, v4, v52
	v_mul_f32_e32 v7, 0x3d372713, v4
	v_add_f32_e32 v3, 1.0, v3
	v_mul_f32_e32 v7, v4, v7
	v_fma_f32 v7, v4, v7, v4
	v_mul_f32_e32 v7, 0x3f4c422a, v7
	v_mul_f32_e32 v7, -2.0, v7
	v_mul_f32_e32 v7, 0x3fb8aa3b, v7
	v_exp_f32_e32 v7, v7
	s_nop 0
	v_add_f32_e32 v7, 1.0, v7
	v_rcp_f32_e32 v5, v3
	s_nop 0
	v_mul_f32_e32 v2, v2, v5
	ds_write_b32 v76, v2 offset:40504
	v_rcp_f32_e32 v2, v7
	s_nop 0
	v_mul_f32_e32 v2, v4, v2
	s_cbranch_execz .LBB0_4708
	s_branch .LBB0_4709

.LBB0_4709:
	s_or_b32 s7, s8, 15
	s_cmpk_gt_i32 s7, 0xfd
	s_cselect_b64 s[16:17], -1, 0
	s_and_b64 s[16:17], s[16:17], s[12:13]
	s_and_b64 vcc, exec, s[16:17]
	ds_write_b32 v76, v2 offset:40760
	s_cbranch_vccnz .LBB0_4711
	s_waitcnt vmcnt(0) lgkmcnt(0)
	v_add_f32_e32 v2, v18, v49
	v_add_f32_e32 v2, v2, v50
	v_mul_f32_e32 v3, 0x3d372713, v2
	v_mul_f32_e32 v3, v2, v3
	v_fma_f32 v3, v2, v3, v2
	v_mul_f32_e32 v3, 0x3f4c422a, v3
	v_mul_f32_e32 v3, -2.0, v3
	v_mul_f32_e32 v3, 0x3fb8aa3b, v3
	v_exp_f32_e32 v3, v3
	v_add_f32_e32 v1, v19, v1
	v_add_f32_e32 v1, v1, v48
	v_mul_f32_e32 v6, 0x3d372713, v1
	v_add_f32_e32 v3, 1.0, v3
	v_mul_f32_e32 v6, v1, v6
	v_fma_f32 v6, v1, v6, v1
	v_mul_f32_e32 v6, 0x3f4c422a, v6
	v_mul_f32_e32 v6, -2.0, v6
	v_mul_f32_e32 v6, 0x3fb8aa3b, v6
	v_exp_f32_e32 v6, v6
	s_nop 0
	v_add_f32_e32 v6, 1.0, v6
	v_rcp_f32_e32 v4, v3
	s_nop 0
	v_mul_f32_e32 v2, v2, v4
	ds_write_b32 v76, v2 offset:41020
	v_rcp_f32_e32 v2, v6
	s_nop 0
	v_mul_f32_e32 v1, v1, v2
	s_cbranch_execz .LBB0_4712
	s_branch .LBB0_4713

.LBB0_5499:
	s_or_b64 exec, exec, s[8:9]
	s_and_saveexec_b64 s[8:9], s[6:7]
	ds_write_b32 v141, v35 offset:33024
	s_or_b64 exec, exec, s[8:9]
	s_waitcnt lgkmcnt(0)
	ds_read_b32 v38, v1 offset:33024
	ds_read2_b32 v[34:35], v142 offset1:32
	ds_read2_b32 v[36:37], v106 offset1:32
	s_or_b32 s6, s50, s52
	s_add_u32 s6, s6, s70
	s_addc_u32 s7, 0, s71
	s_waitcnt lgkmcnt(0)
	v_fma_f32 v18, v18, v38, v34
	v_fmac_f32_e32 v35, v2, v38
	ds_write2_b32 v142, v18, v35 offset1:32
	ds_read_b32 v2, v1 offset:33028
	ds_read2_b32 v[34:35], v107 offset1:32
	s_mov_b64 s[8:9], 0xdc00000
	s_waitcnt lgkmcnt(0)
	v_fma_f32 v18, v19, v2, v36
	v_fmac_f32_e32 v37, v3, v2
	ds_write2_b32 v106, v18, v37 offset1:32
	ds_read_b32 v18, v1 offset:33032
	ds_read2_b32 v[2:3], v108 offset1:32
	s_waitcnt lgkmcnt(0)
	v_fma_f32 v19, v20, v18, v34
	v_fmac_f32_e32 v35, v4, v18
	ds_write2_b32 v107, v19, v35 offset1:32
	ds_read_b32 v4, v1 offset:33036
	ds_read2_b32 v[18:19], v109 offset1:32
	s_waitcnt lgkmcnt(0)
	v_fma_f32 v2, v21, v4, v2
	v_fmac_f32_e32 v3, v5, v4
	ds_write2_b32 v108, v2, v3 offset1:32
	ds_read_b32 v4, v1 offset:33056
	ds_read2_b32 v[2:3], v110 offset1:32
	s_waitcnt lgkmcnt(0)
	v_fma_f32 v5, v22, v4, v18
	v_fmac_f32_e32 v19, v6, v4
	ds_write2_b32 v109, v5, v19 offset1:32
	ds_read_b32 v6, v1 offset:33060
	ds_read2_b32 v[4:5], v112 offset1:32
	s_waitcnt lgkmcnt(0)
	v_fma_f32 v2, v23, v6, v2
	v_fmac_f32_e32 v3, v7, v6
	ds_write2_b32 v110, v2, v3 offset1:32
	ds_read_b32 v6, v1 offset:33064
	ds_read2_b32 v[2:3], v113 offset1:32
	v_lshlrev_b32_e32 v7, 3, v139
	s_waitcnt lgkmcnt(0)
	v_fma_f32 v4, v24, v6, v4
	v_fmac_f32_e32 v5, v8, v6
	ds_write2_b32 v112, v4, v5 offset1:32
	ds_read_b32 v6, v1 offset:33068
	ds_read2_b32 v[4:5], v114 offset1:32
	v_and_or_b32 v8, v93, 3, s77
	v_lshlrev_b32_e32 v98, 7, v8
	s_waitcnt lgkmcnt(0)
	v_fma_f32 v2, v25, v6, v2
	v_fmac_f32_e32 v3, v9, v6
	ds_write2_b32 v113, v2, v3 offset1:32
	ds_read_b32 v6, v1 offset:33088
	ds_read2_b32 v[2:3], v115 offset1:32
	v_and_b32_e32 v9, 56, v7
	s_waitcnt lgkmcnt(0)
	v_fma_f32 v4, v26, v6, v4
	v_fmac_f32_e32 v5, v10, v6
	ds_write2_b32 v114, v4, v5 offset1:32
	ds_read_b32 v6, v1 offset:33092
	ds_read2_b32 v[4:5], v117 offset1:32
	s_waitcnt lgkmcnt(0)
	v_fma_f32 v2, v27, v6, v2
	v_fmac_f32_e32 v3, v11, v6
	ds_write2_b32 v115, v2, v3 offset1:32
	ds_read_b32 v6, v1 offset:33096
	ds_read2_b32 v[2:3], v118 offset1:32
	s_waitcnt lgkmcnt(0)
	v_fma_f32 v4, v28, v6, v4
	v_fmac_f32_e32 v5, v12, v6
	ds_write2_b32 v117, v4, v5 offset1:32
	ds_read_b32 v6, v1 offset:33100
	ds_read2_b32 v[4:5], v91 offset1:32
	s_waitcnt lgkmcnt(0)
	v_fma_f32 v2, v29, v6, v2
	v_fmac_f32_e32 v3, v13, v6
	ds_write2_b32 v118, v2, v3 offset1:32
	ds_read_b32 v6, v1 offset:33120
	ds_read2_b32 v[2:3], v102 offset1:32
	s_waitcnt lgkmcnt(0)
	v_fma_f32 v4, v30, v6, v4
	v_fmac_f32_e32 v5, v14, v6
	ds_write2_b32 v91, v4, v5 offset1:32
	ds_read_b32 v6, v1 offset:33124
	ds_read2_b32 v[4:5], v111 offset1:32
	v_lshl_add_u32 v14, v9, 2, s54
	v_lshl_add_u32 v8, v93, 8, v14
	s_waitcnt lgkmcnt(0)
	v_fma_f32 v2, v31, v6, v2
	v_fmac_f32_e32 v3, v15, v6
	ds_write2_b32 v102, v2, v3 offset1:32
	ds_read_b32 v6, v1 offset:33128
	ds_read2_b32 v[2:3], v116 offset1:32
	s_waitcnt lgkmcnt(0)
	v_fma_f32 v4, v32, v6, v4
	v_fmac_f32_e32 v5, v16, v6
	ds_write2_b32 v111, v4, v5 offset1:32
	ds_read_b32 v1, v1 offset:33132
	v_lshl_add_u64 v[6:7], s[68:69], 0, v[98:99]
	v_lshlrev_b32_e32 v98, 1, v9
	v_lshl_add_u64 v[6:7], v[6:7], 0, v[98:99]
	v_lshl_add_u64 v[6:7], v[6:7], 0, s[8:9]
	s_waitcnt lgkmcnt(0)
	v_fma_f32 v2, v33, v1, v2
	v_fmac_f32_e32 v3, v17, v1
	ds_write2_b32 v116, v2, v3 offset1:32
	s_waitcnt lgkmcnt(0)
	ds_read_b128 v[2:5], v8 offset:36864
	ds_read_b128 v[8:11], v8 offset:36880
	s_waitcnt lgkmcnt(0)
	v_bfe_u32 v1, v2, 16, 1
	v_bfe_u32 v12, v3, 16, 1
	v_add3_u32 v1, v2, v1, s35
	v_bfe_u32 v13, v4, 16, 1
	v_bfe_u32 v15, v5, 16, 1
	v_add3_u32 v2, v3, v12, s35
	v_lshrrev_b32_e32 v1, 16, v1
	v_add3_u32 v3, v4, v13, s35
	v_add3_u32 v4, v5, v15, s35
	v_and_or_b32 v2, v2, s45, v1
	v_lshrrev_b32_e32 v1, 5, v139
	v_lshrrev_b32_e32 v3, 16, v3
	v_or_b32_e32 v12, s6, v1
	v_mov_b32_e32 v13, s7
	v_and_or_b32 v3, v4, s45, v3
	v_cvt_pk_bf16_f32 v4, v8, v9
	v_cvt_pk_bf16_f32 v5, v10, v11
	v_lshlrev_b64 v[8:9], 11, v[12:13]
	v_lshl_add_u64 v[8:9], v[6:7], 0, v[8:9]
	v_or_b32_e32 v1, 8, v93
	global_store_dwordx4 v[8:9], v[2:5], off
	v_lshl_add_u32 v8, v1, 8, v14
	ds_read_b128 v[2:5], v8 offset:36864
	ds_read_b128 v[8:11], v8 offset:36880
	v_lshrrev_b32_e32 v1, 2, v1
	s_waitcnt lgkmcnt(0)
	v_cvt_pk_bf16_f32 v2, v2, v3
	v_cvt_pk_bf16_f32 v3, v4, v5
	v_cvt_pk_bf16_f32 v4, v8, v9
	v_or_b32_e32 v12, s6, v1
	v_cvt_pk_bf16_f32 v5, v10, v11
	v_lshlrev_b64 v[8:9], 11, v[12:13]
	v_lshl_add_u64 v[8:9], v[6:7], 0, v[8:9]
	v_or_b32_e32 v1, 16, v93
	global_store_dwordx4 v[8:9], v[2:5], off
	v_lshl_add_u32 v8, v1, 8, v14
	ds_read_b128 v[2:5], v8 offset:36864
	ds_read_b128 v[8:11], v8 offset:36880
	v_lshrrev_b32_e32 v1, 2, v1
	s_waitcnt lgkmcnt(0)
	v_cvt_pk_bf16_f32 v2, v2, v3
	v_cvt_pk_bf16_f32 v3, v4, v5
	v_cvt_pk_bf16_f32 v4, v8, v9
	v_or_b32_e32 v12, s6, v1
	v_cvt_pk_bf16_f32 v5, v10, v11
	v_lshlrev_b64 v[8:9], 11, v[12:13]
	v_lshl_add_u64 v[8:9], v[6:7], 0, v[8:9]
	v_or_b32_e32 v1, 24, v93
	global_store_dwordx4 v[8:9], v[2:5], off
	v_lshl_add_u32 v8, v1, 8, v14
	ds_read_b128 v[2:5], v8 offset:36864
	ds_read_b128 v[8:11], v8 offset:36880
	v_lshrrev_b32_e32 v1, 2, v1
	s_waitcnt lgkmcnt(0)
	v_cvt_pk_bf16_f32 v2, v2, v3
	v_cvt_pk_bf16_f32 v3, v4, v5
	v_cvt_pk_bf16_f32 v4, v8, v9
	v_or_b32_e32 v12, s6, v1
	v_cvt_pk_bf16_f32 v5, v10, v11
	v_lshlrev_b64 v[8:9], 11, v[12:13]
	v_lshl_add_u64 v[6:7], v[6:7], 0, v[8:9]
	global_store_dwordx4 v[6:7], v[2:5], off
	s_waitcnt lgkmcnt(0)
	s_waitcnt lgkmcnt(0)
	s_barrier

.LBB0_5544:
	v_lshl_add_u64 v[18:19], s[68:69], 0, v[94:95]
	v_lshl_add_u64 v[22:23], s[68:69], 0, v[92:93]
	v_add_co_u32_e32 v20, vcc, 0x7800000, v18
	v_add_co_u32_e64 v102, s[6:7], s24, v22
	s_nop 0
	v_addc_co_u32_e32 v21, vcc, 0, v19, vcc
	v_addc_co_u32_e64 v103, s[6:7], 0, v23, s[6:7]
	v_add_co_u32_e64 v104, s[6:7], s25, v22
	v_add_co_u32_e32 v22, vcc, 0x7801000, v18
	s_nop 0
	v_addc_co_u32_e64 v105, s[6:7], 0, v23, s[6:7]
	global_load_dwordx4 v[78:81], v[20:21], off
	global_load_dwordx4 v[74:77], v[20:21], off offset:1024
	global_load_dwordx4 v[70:73], v[20:21], off offset:2048
	global_load_dwordx4 v[66:69], v[20:21], off offset:3072
	v_addc_co_u32_e32 v23, vcc, 0, v19, vcc
	v_add_co_u32_e32 v20, vcc, 0x7802000, v18
	global_load_dwordx4 v[62:65], v[22:23], off
	global_load_dwordx4 v[58:61], v[22:23], off offset:1024
	global_load_dwordx4 v[54:57], v[22:23], off offset:2048
	global_load_dwordx4 v[50:53], v[22:23], off offset:3072
	v_addc_co_u32_e32 v21, vcc, 0, v19, vcc
	v_add_co_u32_e32 v82, vcc, 0x7803000, v18
	global_load_dwordx4 v[46:49], v[20:21], off
	global_load_dwordx4 v[42:45], v[20:21], off offset:1024
	global_load_dwordx4 v[38:41], v[20:21], off offset:2048
	global_load_dwordx4 v[34:37], v[20:21], off offset:3072
	v_addc_co_u32_e32 v83, vcc, 0, v19, vcc
	global_load_dwordx4 v[30:33], v[82:83], off
	global_load_dwordx4 v[26:29], v[82:83], off offset:1024
	global_load_dwordx4 v[22:25], v[82:83], off offset:2048
	global_load_dwordx4 v[18:21], v[82:83], off offset:3072
	s_ashr_i32 s8, s12, 13
	s_add_i32 s9, s12, 0xffffc002
	s_cmpk_lt_i32 s12, 0x4000
	s_cselect_b32 s6, s8, s9
	s_addk_i32 s6, 0x82
	s_mul_hi_i32 s7, s6, 0x9000
	s_mul_i32 s6, s6, 0x9000
	s_add_u32 s9, s3, s6
	s_addc_u32 s11, s4, s7
	s_add_u32 s6, s9, 0x6000
	s_addc_u32 s7, s11, 0
	s_add_u32 s10, s9, 0x7000
	s_addc_u32 s11, s11, 0
	v_lshl_add_u64 v[82:83], s[6:7], 0, v[90:91]
	v_lshl_add_u64 v[86:87], s[10:11], 0, v[90:91]
	global_load_dwordx4 v[82:85], v[82:83], off
	v_lshl_add_u64 v[148:149], s[6:7], 0, v[96:97]
	global_load_dwordx4 v[86:89], v[86:87], off
	v_lshl_add_u64 v[142:143], s[6:7], 0, v[98:99]
	v_lshl_add_u64 v[132:133], s[6:7], 0, v[100:101]
	s_add_i32 s6, s12, 0xffffc003
	s_cmpk_lt_i32 s12, 0x3fff
	s_cselect_b32 s6, s8, s6
	s_addk_i32 s6, 0x82
	s_mul_hi_i32 s7, s6, 0x9000
	s_mul_i32 s6, s6, 0x9000
	s_add_u32 s9, s3, s6
	v_lshl_add_u64 v[152:153], s[10:11], 0, v[96:97]
	v_lshl_add_u64 v[146:147], s[10:11], 0, v[98:99]
	v_lshl_add_u64 v[140:141], s[10:11], 0, v[100:101]
	s_addc_u32 s11, s4, s7
	s_add_u32 s6, s9, 0x6000
	s_addc_u32 s7, s11, 0
	s_add_u32 s10, s9, 0x7000
	v_lshl_add_u64 v[134:135], s[6:7], 0, v[90:91]
	v_lshl_add_u64 v[126:127], s[6:7], 0, v[96:97]
	v_lshl_add_u64 v[118:119], s[6:7], 0, v[98:99]
	v_lshl_add_u64 v[114:115], s[6:7], 0, v[100:101]
	s_addc_u32 s11, s11, 0
	s_add_i32 s6, s12, 0xffffc004
	s_cmpk_lt_i32 s12, 0x3ffe
	s_cselect_b32 s6, s8, s6
	s_addk_i32 s6, 0x82
	s_mul_hi_i32 s7, s6, 0x9000
	s_mul_i32 s6, s6, 0x9000
	s_add_u32 s6, s3, s6
	s_addc_u32 s7, s4, s7
	v_lshl_add_u64 v[136:137], s[10:11], 0, v[90:91]
	v_lshl_add_u64 v[130:131], s[10:11], 0, v[96:97]
	v_lshl_add_u64 v[122:123], s[10:11], 0, v[98:99]
	v_lshl_add_u64 v[116:117], s[10:11], 0, v[100:101]
	s_add_u32 s10, s6, 0x6000
	s_addc_u32 s11, s7, 0
	s_add_u32 s6, s6, 0x7000
	s_addc_u32 s7, s7, 0
	s_add_i32 s9, s12, 0xffffc005
	s_cmpk_lt_i32 s12, 0x3ffd
	v_lshl_add_u64 v[156:157], s[6:7], 0, v[90:91]
	v_lshl_add_u64 v[154:155], s[6:7], 0, v[96:97]
	v_lshl_add_u64 v[150:151], s[6:7], 0, v[98:99]
	v_lshl_add_u64 v[138:139], s[6:7], 0, v[100:101]
	s_cselect_b32 s6, s8, s9
	s_addk_i32 s6, 0x82
	s_waitcnt vmcnt(0) lgkmcnt(0)
	v_pk_mul_f32 v[158:159], v[80:81], v[80:81]
	v_pk_mul_f32 v[160:161], v[78:79], v[78:79]
	v_pk_mul_f32 v[162:163], v[76:77], v[76:77]
	v_pk_mul_f32 v[164:165], v[74:75], v[74:75]
	v_mul_f32_e32 v174, v71, v71
	v_mul_f32_e32 v176, v73, v73
	v_mul_f32_e32 v187, v68, v68
	v_mul_f32_e32 v189, v69, v69
	v_pk_mov_b32 v[178:179], v[160:161], v[158:159] op_sel:[1,0]
	v_mov_b32_e32 v161, v159
	v_pk_mov_b32 v[158:159], v[164:165], v[162:163] op_sel:[1,0]
	v_mov_b32_e32 v165, v163
	v_pk_fma_f32 v[162:163], v[70:71], v[70:71], v[174:175] op_sel_hi:[1,1,0]
	v_pk_fma_f32 v[174:175], v[72:73], v[72:73], v[176:177] op_sel_hi:[1,1,0]
	v_pk_mul_f32 v[176:177], v[64:65], v[64:65]
	v_pk_mul_f32 v[180:181], v[62:63], v[62:63]
	v_pk_mul_f32 v[182:183], v[60:61], v[60:61]
	v_pk_mul_f32 v[184:185], v[58:59], v[58:59]
	v_mul_f32_e32 v186, v55, v55
	v_mul_f32_e32 v188, v57, v57
	v_pk_add_f32 v[160:161], v[178:179], v[160:161]
	v_pk_add_f32 v[158:159], v[158:159], v[164:165]
	v_mov_b32_e32 v163, v187
	v_mov_b32_e32 v175, v189
	v_pk_mov_b32 v[164:165], v[180:181], v[176:177] op_sel:[1,0]
	v_mov_b32_e32 v181, v177
	v_pk_mov_b32 v[176:177], v[184:185], v[182:183] op_sel:[1,0]
	v_mov_b32_e32 v185, v183
	v_pk_fma_f32 v[178:179], v[54:55], v[54:55], v[186:187] op_sel_hi:[1,1,0]
	v_pk_fma_f32 v[182:183], v[56:57], v[56:57], v[188:189] op_sel_hi:[1,1,0]
	v_pk_mul_f32 v[186:187], v[48:49], v[48:49]
	v_pk_mul_f32 v[188:189], v[46:47], v[46:47]
	v_pk_mul_f32 v[190:191], v[44:45], v[44:45]
	v_pk_mul_f32 v[192:193], v[42:43], v[42:43]
	v_mul_f32_e32 v197, v66, v66
	v_mul_f32_e32 v203, v67, v67
	v_mul_f32_e32 v195, v52, v52
	v_mul_f32_e32 v202, v53, v53
	v_mul_f32_e32 v194, v39, v39
	v_mul_f32_e32 v196, v41, v41
	v_pk_add_f32 v[198:199], v[160:161], v[160:161] op_sel:[0,1] op_sel_hi:[1,0]
	v_pk_add_f32 v[200:201], v[158:159], v[158:159] op_sel:[0,1] op_sel_hi:[1,0]
	v_pk_add_f32 v[174:175], v[162:163], v[174:175]
	v_pk_add_f32 v[158:159], v[164:165], v[180:181]
	v_pk_add_f32 v[160:161], v[176:177], v[184:185]
	v_pk_mov_b32 v[162:163], v[188:189], v[186:187] op_sel:[1,0]
	v_mov_b32_e32 v189, v187
	v_pk_mov_b32 v[164:165], v[192:193], v[190:191] op_sel:[1,0]
	v_mov_b32_e32 v193, v191
	v_mul_f32_e32 v208, v50, v50
	v_mul_f32_e32 v209, v51, v51
	v_mul_f32_e32 v212, v36, v36
	v_mul_f32_e32 v213, v37, v37
	v_mov_b32_e32 v179, v195
	v_mov_b32_e32 v183, v202
	v_pk_fma_f32 v[176:177], v[38:39], v[38:39], v[194:195] op_sel_hi:[1,1,0]
	v_pk_fma_f32 v[180:181], v[40:41], v[40:41], v[196:197] op_sel_hi:[1,1,0]
	v_pk_mul_f32 v[184:185], v[32:33], v[32:33]
	v_pk_mul_f32 v[186:187], v[30:31], v[30:31]
	v_pk_mul_f32 v[190:191], v[28:29], v[28:29]
	v_pk_mul_f32 v[194:195], v[26:27], v[26:27]
	v_mov_b32_e32 v199, v197
	v_mov_b32_e32 v201, v203
	v_pk_add_f32 v[204:205], v[158:159], v[158:159] op_sel:[0,1] op_sel_hi:[1,0]
	v_pk_add_f32 v[206:207], v[160:161], v[160:161] op_sel:[0,1] op_sel_hi:[1,0]
	v_pk_add_f32 v[162:163], v[162:163], v[188:189]
	v_pk_add_f32 v[164:165], v[164:165], v[192:193]
	v_mul_f32_e32 v210, v34, v34
	v_mul_f32_e32 v211, v35, v35
	v_pk_add_f32 v[178:179], v[178:179], v[182:183]
	v_mov_b32_e32 v177, v212
	v_mov_b32_e32 v181, v213
	v_pk_mov_b32 v[182:183], v[186:187], v[184:185] op_sel:[1,0]
	v_mov_b32_e32 v187, v185
	v_pk_mov_b32 v[184:185], v[194:195], v[190:191] op_sel:[1,0]
	v_mov_b32_e32 v195, v191
	v_pk_add_f32 v[188:189], v[198:199], v[200:201]
	v_mov_b32_e32 v205, v208
	v_mov_b32_e32 v207, v209
	v_pk_add_f32 v[190:191], v[162:163], v[162:163] op_sel:[0,1] op_sel_hi:[1,0]
	v_pk_add_f32 v[192:193], v[164:165], v[164:165] op_sel:[0,1] op_sel_hi:[1,0]
	v_pk_add_f32 v[176:177], v[176:177], v[180:181]
	v_pk_add_f32 v[174:175], v[188:189], v[174:175]
	v_pk_add_f32 v[180:181], v[204:205], v[206:207]
	v_mov_b32_e32 v191, v210
	v_mov_b32_e32 v193, v211
	v_pk_add_f32 v[162:163], v[182:183], v[186:187]
	v_add_f32_e32 v182, v174, v175
	v_pk_add_f32 v[174:175], v[180:181], v[178:179]
	v_pk_add_f32 v[178:179], v[190:191], v[192:193]
	v_add_f32_e32 v180, v174, v175
	v_pk_add_f32 v[174:175], v[178:179], v[176:177]
	ds_bpermute_b32 v176, v1, v182
	v_add_f32_e32 v174, v174, v175
	ds_bpermute_b32 v175, v1, v180
	ds_bpermute_b32 v177, v1, v174
	s_mul_hi_i32 s7, s6, 0x9000
	s_waitcnt lgkmcnt(2)
	v_add_f32_e32 v176, v182, v176
	ds_bpermute_b32 v178, v167, v176
	s_waitcnt lgkmcnt(2)
	v_add_f32_e32 v175, v180, v175
	ds_bpermute_b32 v179, v167, v175
	s_waitcnt lgkmcnt(2)
	v_add_f32_e32 v174, v174, v177
	ds_bpermute_b32 v177, v167, v174
	s_waitcnt lgkmcnt(2)
	v_add_f32_e32 v176, v176, v178
	ds_bpermute_b32 v178, v168, v176
	s_waitcnt lgkmcnt(2)
	v_add_f32_e32 v175, v175, v179
	ds_bpermute_b32 v179, v168, v175
	s_waitcnt lgkmcnt(2)
	v_add_f32_e32 v174, v174, v177
	ds_bpermute_b32 v177, v168, v174
	s_waitcnt lgkmcnt(2)
	v_add_f32_e32 v176, v176, v178
	ds_bpermute_b32 v178, v169, v176
	s_waitcnt lgkmcnt(2)
	v_add_f32_e32 v175, v175, v179
	ds_bpermute_b32 v179, v169, v175
	s_waitcnt lgkmcnt(2)
	v_add_f32_e32 v174, v174, v177
	ds_bpermute_b32 v177, v169, v174
	s_waitcnt lgkmcnt(2)
	v_add_f32_e32 v176, v176, v178
	ds_bpermute_b32 v178, v170, v176
	s_waitcnt lgkmcnt(2)
	v_add_f32_e32 v175, v175, v179
	ds_bpermute_b32 v179, v170, v175
	s_waitcnt lgkmcnt(2)
	v_add_f32_e32 v174, v174, v177
	ds_bpermute_b32 v177, v170, v174
	s_waitcnt lgkmcnt(2)
	v_add_f32_e32 v176, v176, v178
	ds_bpermute_b32 v178, v171, v176
	s_waitcnt lgkmcnt(2)
	v_add_f32_e32 v175, v175, v179
	ds_bpermute_b32 v179, v171, v175
	s_mul_i32 s6, s6, 0x9000
	s_waitcnt lgkmcnt(2)
	v_add_f32_e32 v174, v174, v177
	s_add_u32 s6, s3, s6
	ds_bpermute_b32 v177, v171, v174
	s_addc_u32 s7, s4, s7
	s_waitcnt lgkmcnt(2)
	v_add_f32_e32 v176, v176, v178
	s_add_u32 s18, s6, 0x6000
	v_fmamk_f32 v176, v176, 0x3a800000, v172
	s_addc_u32 s19, s7, 0
	s_waitcnt lgkmcnt(1)
	v_add_f32_e32 v175, v175, v179
	v_mul_f32_e32 v178, 0x4f800000, v176
	v_cmp_gt_f32_e32 vcc, s13, v176
	s_add_u32 s20, s6, 0x7000
	v_fmamk_f32 v175, v175, 0x3a800000, v172
	v_cndmask_b32_e32 v176, v176, v178, vcc
	s_addc_u32 s21, s7, 0
	s_waitcnt lgkmcnt(0)
	v_add_f32_e32 v174, v174, v177
	v_mul_f32_e32 v177, 0x4f800000, v175
	v_cmp_gt_f32_e64 s[6:7], s13, v175
	v_sqrt_f32_e32 v178, v176
	v_fmamk_f32 v174, v174, 0x3a800000, v172
	v_cndmask_b32_e64 v175, v175, v177, s[6:7]
	v_mul_f32_e32 v177, 0x4f800000, v174
	v_cmp_gt_f32_e64 s[8:9], s13, v174
	v_sqrt_f32_e32 v179, v175
	v_add_u32_e32 v180, -1, v178
	v_cndmask_b32_e64 v174, v174, v177, s[8:9]
	v_sqrt_f32_e32 v177, v174
	v_add_u32_e32 v181, 1, v178
	v_fma_f32 v182, -v180, v178, v176
	v_lshl_add_u64 v[112:113], s[10:11], 0, v[90:91]
	v_lshl_add_u64 v[106:107], s[10:11], 0, v[96:97]
	v_lshl_add_u64 v[110:111], s[10:11], 0, v[98:99]
	v_lshl_add_u64 v[108:109], s[10:11], 0, v[100:101]
	v_pk_add_f32 v[164:165], v[184:185], v[194:195]
	v_fma_f32 v183, -v181, v178, v176
	v_add_u32_e32 v184, -1, v179
	v_cmp_ge_f32_e64 s[10:11], 0, v182
	v_add_u32_e32 v185, 1, v179
	v_fma_f32 v182, -v185, v179, v175
	v_cndmask_b32_e64 v178, v178, v180, s[10:11]
	v_fma_f32 v180, -v184, v179, v175
	v_cmp_lt_f32_e64 s[10:11], 0, v183
	v_add_u32_e32 v186, -1, v177
	v_add_u32_e32 v187, 1, v177
	v_cndmask_b32_e64 v178, v178, v181, s[10:11]
	v_cmp_ge_f32_e64 s[10:11], 0, v180
	v_fma_f32 v180, -v186, v177, v174
	v_fma_f32 v181, -v187, v177, v174
	v_cndmask_b32_e64 v179, v179, v184, s[10:11]
	v_cmp_lt_f32_e64 s[10:11], 0, v182
	v_mul_f32_e32 v182, 0x37800000, v178
	v_cndmask_b32_e32 v178, v178, v182, vcc
	v_cndmask_b32_e64 v179, v179, v185, s[10:11]
	v_cmp_ge_f32_e64 s[10:11], 0, v180
	v_cmp_class_f32_e32 vcc, v176, v173
	v_mul_f32_e32 v180, 0x37800000, v179
	v_cndmask_b32_e64 v177, v177, v186, s[10:11]
	v_cmp_lt_f32_e64 s[10:11], 0, v181
	v_cndmask_b32_e32 v176, v178, v176, vcc
	v_cndmask_b32_e64 v178, v179, v180, s[6:7]
	v_cndmask_b32_e64 v177, v177, v187, s[10:11]
	v_cmp_class_f32_e32 vcc, v175, v173
	v_mul_f32_e32 v179, 0x37800000, v177
	v_div_scale_f32 v180, s[6:7], v176, v176, 1.0
	v_cndmask_b32_e32 v175, v178, v175, vcc
	v_cndmask_b32_e64 v177, v177, v179, s[8:9]
	v_cmp_class_f32_e32 vcc, v174, v173
	v_rcp_f32_e32 v178, v180
	v_div_scale_f32 v179, s[8:9], v175, v175, 1.0
	v_cndmask_b32_e32 v177, v177, v174, vcc
	v_rcp_f32_e32 v183, v179
	v_div_scale_f32 v184, s[10:11], v177, v177, 1.0
	v_rcp_f32_e32 v186, v184
	v_fma_f32 v174, -v180, v178, 1.0
	v_div_scale_f32 v181, s[6:7], 1.0, v176, 1.0
	v_fmac_f32_e32 v178, v174, v178
	v_fma_f32 v174, -v179, v183, 1.0
	v_mul_f32_e32 v187, v181, v178
	v_div_scale_f32 v182, s[8:9], 1.0, v175, 1.0
	v_fmac_f32_e32 v183, v174, v183
	v_fma_f32 v174, -v184, v186, 1.0
	v_fma_f32 v188, -v180, v187, v181
	v_div_scale_f32 v185, s[10:11], 1.0, v177, 1.0
	v_mul_f32_e32 v189, v182, v183
	v_fmac_f32_e32 v186, v174, v186
	v_fmac_f32_e32 v187, v188, v178
	v_fma_f32 v174, -v179, v189, v182
	v_mul_f32_e32 v188, v185, v186
	v_fma_f32 v180, -v180, v187, v181
	s_mov_b64 vcc, s[6:7]
	v_fmac_f32_e32 v189, v174, v183
	v_fma_f32 v174, -v184, v188, v185
	v_div_fmas_f32 v178, v180, v178, v187
	v_fma_f32 v179, -v179, v189, v182
	v_fmac_f32_e32 v188, v174, v186
	v_div_fixup_f32 v174, v178, v176, 1.0
	s_mov_b64 vcc, s[8:9]
	v_div_fmas_f32 v176, v179, v183, v189
	v_fma_f32 v178, -v184, v188, v185
	v_pk_mul_f32 v[80:81], v[80:81], v[174:175] op_sel_hi:[1,0]
	v_pk_mul_f32 v[78:79], v[78:79], v[174:175] op_sel_hi:[1,0]
	s_mov_b64 vcc, s[10:11]
	v_pk_add_f32 v[88:89], v[88:89], 1.0 op_sel_hi:[1,0]
	v_pk_add_f32 v[86:87], v[86:87], 1.0 op_sel_hi:[1,0]
	v_pk_mul_f32 v[76:77], v[76:77], v[174:175] op_sel_hi:[1,0]
	v_pk_mul_f32 v[74:75], v[74:75], v[174:175] op_sel_hi:[1,0]
	v_pk_mul_f32 v[72:73], v[72:73], v[174:175] op_sel_hi:[1,0]
	v_pk_mul_f32 v[70:71], v[70:71], v[174:175] op_sel_hi:[1,0]
	v_pk_mul_f32 v[68:69], v[68:69], v[174:175] op_sel_hi:[1,0]
	v_pk_mul_f32 v[66:67], v[66:67], v[174:175] op_sel_hi:[1,0]
	v_div_fixup_f32 v174, v176, v175, 1.0
	v_div_fmas_f32 v176, v178, v186, v188
	v_pk_mul_f32 v[78:79], v[2:3], v[78:79]
	v_pk_mul_f32 v[80:81], v[4:5], v[80:81]
	v_pk_mul_f32 v[64:65], v[64:65], v[174:175] op_sel_hi:[1,0]
	v_pk_mul_f32 v[62:63], v[62:63], v[174:175] op_sel_hi:[1,0]
	v_pk_mul_f32 v[60:61], v[60:61], v[174:175] op_sel_hi:[1,0]
	v_pk_mul_f32 v[58:59], v[58:59], v[174:175] op_sel_hi:[1,0]
	v_pk_mul_f32 v[56:57], v[56:57], v[174:175] op_sel_hi:[1,0]
	v_pk_mul_f32 v[54:55], v[54:55], v[174:175] op_sel_hi:[1,0]
	v_pk_mul_f32 v[52:53], v[52:53], v[174:175] op_sel_hi:[1,0]
	v_pk_mul_f32 v[174:175], v[50:51], v[174:175] op_sel_hi:[1,0]
	v_div_fixup_f32 v50, v176, v177, 1.0
	v_pk_fma_f32 v[80:81], v[88:89], v[80:81], v[84:85]
	v_pk_fma_f32 v[78:79], v[86:87], v[78:79], v[82:83]
	v_pk_mul_f32 v[86:87], v[16:17], v[52:53]
	v_pk_mul_f32 v[48:49], v[48:49], v[50:51] op_sel_hi:[1,0]
	v_pk_mul_f32 v[46:47], v[46:47], v[50:51] op_sel_hi:[1,0]
	v_pk_mul_f32 v[82:83], v[10:11], v[54:55]
	v_pk_mul_f32 v[84:85], v[14:15], v[174:175]
	v_pk_mul_f32 v[88:89], v[2:3], v[46:47]
	v_pk_mul_f32 v[174:175], v[4:5], v[48:49]
	v_cvt_pk_bf16_f32 v46, v78, v79
	v_cvt_pk_bf16_f32 v47, v80, v81
	global_store_dwordx2 v[102:103], v[46:47], off
	global_load_dwordx4 v[46:49], v[152:153], off
	s_nop 0
	global_load_dwordx4 v[52:55], v[148:149], off
	v_pk_mul_f32 v[74:75], v[6:7], v[74:75]
	v_pk_mul_f32 v[76:77], v[8:9], v[76:77]
	v_pk_mul_f32 v[70:71], v[10:11], v[70:71]
	v_pk_mul_f32 v[72:73], v[12:13], v[72:73]
	v_pk_mul_f32 v[66:67], v[66:67], v[14:15]
	v_pk_mul_f32 v[68:69], v[68:69], v[16:17]
	v_pk_mul_f32 v[62:63], v[2:3], v[62:63]
	v_pk_mul_f32 v[64:65], v[4:5], v[64:65]
	v_pk_mul_f32 v[58:59], v[6:7], v[58:59]
	v_pk_mul_f32 v[60:61], v[8:9], v[60:61]
	v_pk_mul_f32 v[56:57], v[12:13], v[56:57]
	v_mul_f32_e32 v196, v23, v23
	v_mul_f32_e32 v202, v25, v25
	v_mul_f32_e32 v214, v18, v18
	v_mul_f32_e32 v215, v19, v19
	v_mul_f32_e32 v216, v20, v20
	v_mul_f32_e32 v217, v21, v21
	v_pk_fma_f32 v[158:159], v[22:23], v[22:23], v[196:197] op_sel_hi:[1,1,0]
	v_pk_fma_f32 v[160:161], v[24:25], v[24:25], v[202:203] op_sel_hi:[1,1,0]
	v_mov_b32_e32 v159, v216
	v_mov_b32_e32 v161, v217
	v_lshl_add_u64 v[144:145], s[20:21], 0, v[90:91]
	v_lshl_add_u64 v[128:129], s[18:19], 0, v[90:91]
	v_lshl_add_u64 v[124:125], s[20:21], 0, v[96:97]
	v_lshl_add_u64 v[120:121], s[18:19], 0, v[96:97]
	s_add_i32 s12, s12, 32
	v_lshl_add_u64 v[92:93], v[92:93], 0, s[14:15]
	v_lshl_add_u64 v[94:95], v[94:95], 0, s[16:17]
	s_cmp_lt_i32 s12, s2
	s_waitcnt vmcnt(0) lgkmcnt(0)
	v_pk_add_f32 v[48:49], v[48:49], 1.0 op_sel_hi:[1,0]
	v_pk_add_f32 v[46:47], v[46:47], 1.0 op_sel_hi:[1,0]
	v_pk_fma_f32 v[48:49], v[48:49], v[76:77], v[54:55]
	v_pk_fma_f32 v[46:47], v[46:47], v[74:75], v[52:53]
	v_cvt_pk_bf16_f32 v46, v46, v47
	v_cvt_pk_bf16_f32 v47, v48, v49
	global_store_dwordx2 v[102:103], v[46:47], off offset:512
	global_load_dwordx4 v[46:49], v[146:147], off
	s_nop 0
	global_load_dwordx4 v[52:55], v[142:143], off
	s_waitcnt vmcnt(0) lgkmcnt(0)
	v_pk_add_f32 v[48:49], v[48:49], 1.0 op_sel_hi:[1,0]
	v_pk_add_f32 v[46:47], v[46:47], 1.0 op_sel_hi:[1,0]
	v_pk_fma_f32 v[48:49], v[72:73], v[48:49], v[54:55]
	v_pk_fma_f32 v[46:47], v[70:71], v[46:47], v[52:53]
	v_cvt_pk_bf16_f32 v46, v46, v47
	v_cvt_pk_bf16_f32 v47, v48, v49
	global_store_dwordx2 v[102:103], v[46:47], off offset:1024
	global_load_dwordx4 v[46:49], v[140:141], off
	s_nop 0
	global_load_dwordx4 v[52:55], v[132:133], off
	s_waitcnt vmcnt(0) lgkmcnt(0)
	v_pk_add_f32 v[48:49], v[48:49], 1.0 op_sel_hi:[1,0]
	v_pk_add_f32 v[46:47], v[46:47], 1.0 op_sel_hi:[1,0]
	v_pk_fma_f32 v[48:49], v[68:69], v[48:49], v[54:55]
	v_pk_fma_f32 v[46:47], v[66:67], v[46:47], v[52:53]
	v_cvt_pk_bf16_f32 v46, v46, v47
	v_cvt_pk_bf16_f32 v47, v48, v49
	global_store_dwordx2 v[102:103], v[46:47], off offset:1536
	global_load_dwordx4 v[46:49], v[136:137], off
	s_nop 0
	global_load_dwordx4 v[52:55], v[134:135], off
	s_waitcnt vmcnt(0) lgkmcnt(0)
	v_pk_add_f32 v[48:49], v[48:49], 1.0 op_sel_hi:[1,0]
	v_pk_add_f32 v[46:47], v[46:47], 1.0 op_sel_hi:[1,0]
	v_pk_fma_f32 v[48:49], v[48:49], v[64:65], v[54:55]
	v_pk_fma_f32 v[46:47], v[46:47], v[62:63], v[52:53]
	v_cvt_pk_bf16_f32 v46, v46, v47
	v_cvt_pk_bf16_f32 v47, v48, v49
	global_store_dwordx2 v[102:103], v[46:47], off offset:2048
	global_load_dwordx4 v[46:49], v[130:131], off
	s_nop 0
	global_load_dwordx4 v[52:55], v[126:127], off
	s_waitcnt vmcnt(0) lgkmcnt(0)
	v_pk_add_f32 v[48:49], v[48:49], 1.0 op_sel_hi:[1,0]
	v_pk_add_f32 v[46:47], v[46:47], 1.0 op_sel_hi:[1,0]
	v_pk_fma_f32 v[48:49], v[48:49], v[60:61], v[54:55]
	v_pk_fma_f32 v[46:47], v[46:47], v[58:59], v[52:53]
	v_cvt_pk_bf16_f32 v46, v46, v47
	v_cvt_pk_bf16_f32 v47, v48, v49
	global_store_dwordx2 v[102:103], v[46:47], off offset:2560
	global_load_dwordx4 v[46:49], v[122:123], off
	s_nop 0
	global_load_dwordx4 v[52:55], v[118:119], off
	v_pk_add_f32 v[58:59], v[164:165], v[164:165] op_sel:[0,1] op_sel_hi:[1,0]
	v_pk_add_f32 v[60:61], v[158:159], v[160:161]
	v_mov_b32_e32 v59, v215
	s_waitcnt vmcnt(0) lgkmcnt(0)
	v_pk_add_f32 v[48:49], v[48:49], 1.0 op_sel_hi:[1,0]
	v_pk_add_f32 v[46:47], v[46:47], 1.0 op_sel_hi:[1,0]
	v_pk_fma_f32 v[48:49], v[48:49], v[56:57], v[54:55]
	v_pk_fma_f32 v[46:47], v[46:47], v[82:83], v[52:53]
	v_cvt_pk_bf16_f32 v46, v46, v47
	v_cvt_pk_bf16_f32 v47, v48, v49
	global_store_dwordx2 v[102:103], v[46:47], off offset:3072
	global_load_dwordx4 v[46:49], v[116:117], off
	s_nop 0
	global_load_dwordx4 v[52:55], v[114:115], off
	v_pk_add_f32 v[56:57], v[162:163], v[162:163] op_sel:[0,1] op_sel_hi:[1,0]
	s_waitcnt vmcnt(0) lgkmcnt(0)
	v_pk_add_f32 v[48:49], v[48:49], 1.0 op_sel_hi:[1,0]
	v_pk_add_f32 v[46:47], v[46:47], 1.0 op_sel_hi:[1,0]
	v_pk_fma_f32 v[48:49], v[86:87], v[48:49], v[54:55]
	v_pk_fma_f32 v[46:47], v[84:85], v[46:47], v[52:53]
	v_cvt_pk_bf16_f32 v46, v46, v47
	v_cvt_pk_bf16_f32 v47, v48, v49
	global_store_dwordx2 v[102:103], v[46:47], off offset:3584
	global_load_dwordx4 v[46:49], v[156:157], off
	s_nop 0
	global_load_dwordx4 v[52:55], v[112:113], off
	v_mov_b32_e32 v57, v214
	s_waitcnt vmcnt(0) lgkmcnt(0)
	v_pk_add_f32 v[48:49], v[48:49], 1.0 op_sel_hi:[1,0]
	v_pk_add_f32 v[46:47], v[46:47], 1.0 op_sel_hi:[1,0]
	v_pk_fma_f32 v[48:49], v[48:49], v[174:175], v[54:55]
	v_pk_fma_f32 v[46:47], v[46:47], v[88:89], v[52:53]
	v_bfe_u32 v51, v46, 16, 1
	v_bfe_u32 v52, v47, 16, 1
	v_add3_u32 v46, v46, v51, s22
	v_add3_u32 v47, v47, v52, s22
	v_lshrrev_b32_e32 v46, 16, v46
	v_and_or_b32 v46, v47, s23, v46
	v_cvt_pk_bf16_f32 v47, v48, v49
	global_store_dwordx2 v[104:105], v[46:47], off
	global_load_dwordx4 v[46:49], v[154:155], off
	s_nop 0
	global_load_dwordx4 v[52:55], v[106:107], off
	v_pk_mul_f32 v[44:45], v[44:45], v[50:51] op_sel_hi:[1,0]
	v_pk_mul_f32 v[42:43], v[42:43], v[50:51] op_sel_hi:[1,0]
	v_pk_mul_f32 v[44:45], v[8:9], v[44:45]
	v_pk_mul_f32 v[42:43], v[6:7], v[42:43]
	s_waitcnt vmcnt(0) lgkmcnt(0)
	v_pk_add_f32 v[48:49], v[48:49], 1.0 op_sel_hi:[1,0]
	v_pk_add_f32 v[46:47], v[46:47], 1.0 op_sel_hi:[1,0]
	v_pk_fma_f32 v[44:45], v[48:49], v[44:45], v[54:55]
	v_pk_fma_f32 v[42:43], v[46:47], v[42:43], v[52:53]
	v_cvt_pk_bf16_f32 v42, v42, v43
	v_cvt_pk_bf16_f32 v43, v44, v45
	global_store_dwordx2 v[104:105], v[42:43], off offset:512
	global_load_dwordx4 v[42:45], v[150:151], off
	s_nop 0
	global_load_dwordx4 v[46:49], v[110:111], off
	v_pk_add_f32 v[52:53], v[56:57], v[58:59]
	s_waitcnt vmcnt(0) lgkmcnt(0)
	v_pk_add_f32 v[44:45], v[44:45], 1.0 op_sel_hi:[1,0]
	v_pk_add_f32 v[52:53], v[52:53], v[60:61]
	v_pk_add_f32 v[42:43], v[42:43], 1.0 op_sel_hi:[1,0]
	v_add_f32_e32 v51, v52, v53
	ds_bpermute_b32 v52, v1, v51
	s_waitcnt lgkmcnt(0)
	v_add_f32_e32 v51, v51, v52
	ds_bpermute_b32 v52, v167, v51
	s_waitcnt lgkmcnt(0)
	v_add_f32_e32 v51, v51, v52
	v_pk_mul_f32 v[40:41], v[40:41], v[50:51] op_sel_hi:[1,0]
	v_pk_mul_f32 v[38:39], v[38:39], v[50:51] op_sel_hi:[1,0]
	v_pk_mul_f32 v[40:41], v[12:13], v[40:41]
	v_pk_mul_f32 v[38:39], v[10:11], v[38:39]
	v_pk_fma_f32 v[40:41], v[44:45], v[40:41], v[48:49]
	v_pk_fma_f32 v[38:39], v[42:43], v[38:39], v[46:47]
	v_cvt_pk_bf16_f32 v38, v38, v39
	v_cvt_pk_bf16_f32 v39, v40, v41
	global_store_dwordx2 v[104:105], v[38:39], off offset:1024
	global_load_dwordx4 v[38:41], v[138:139], off
	s_nop 0
	global_load_dwordx4 v[42:45], v[108:109], off
	v_pk_mul_f32 v[36:37], v[36:37], v[50:51] op_sel_hi:[1,0]
	v_pk_mul_f32 v[34:35], v[34:35], v[50:51] op_sel_hi:[1,0]
	v_pk_mul_f32 v[36:37], v[16:17], v[36:37]
	v_pk_mul_f32 v[34:35], v[14:15], v[34:35]
	ds_bpermute_b32 v46, v168, v51
	s_waitcnt lgkmcnt(0)
	v_add_f32_e32 v46, v51, v46
	ds_bpermute_b32 v47, v169, v46
	s_waitcnt lgkmcnt(0)
	v_add_f32_e32 v46, v46, v47
	ds_bpermute_b32 v47, v170, v46
	s_waitcnt lgkmcnt(0)
	v_add_f32_e32 v46, v46, v47
	ds_bpermute_b32 v47, v171, v46
	s_waitcnt lgkmcnt(0)
	v_add_f32_e32 v46, v46, v47
	v_fmamk_f32 v46, v46, 0x3a800000, v172
	v_mul_f32_e32 v47, 0x4f800000, v46
	v_cmp_gt_f32_e32 vcc, s13, v46
	s_waitcnt vmcnt(0)
	v_pk_add_f32 v[40:41], v[40:41], 1.0 op_sel_hi:[1,0]
	v_pk_add_f32 v[38:39], v[38:39], 1.0 op_sel_hi:[1,0]
	v_pk_fma_f32 v[36:37], v[36:37], v[40:41], v[44:45]
	v_pk_fma_f32 v[34:35], v[34:35], v[38:39], v[42:43]
	v_cvt_pk_bf16_f32 v34, v34, v35
	v_cvt_pk_bf16_f32 v35, v36, v37
	global_store_dwordx2 v[104:105], v[34:35], off offset:1536
	global_load_dwordx4 v[34:37], v[144:145], off
	s_nop 0
	global_load_dwordx4 v[38:41], v[128:129], off
	v_cndmask_b32_e32 v42, v46, v47, vcc
	v_sqrt_f32_e32 v43, v42
	s_waitcnt vmcnt(0) lgkmcnt(0)
	v_pk_add_f32 v[36:37], v[36:37], 1.0 op_sel_hi:[1,0]
	v_add_u32_e32 v44, -1, v43
	v_add_u32_e32 v45, 1, v43
	v_fma_f32 v46, -v44, v43, v42
	v_fma_f32 v47, -v45, v43, v42
	v_cmp_ge_f32_e64 s[6:7], 0, v46
	v_pk_add_f32 v[34:35], v[34:35], 1.0 op_sel_hi:[1,0]
	s_nop 0
	v_cndmask_b32_e64 v43, v43, v44, s[6:7]
	v_cmp_lt_f32_e64 s[6:7], 0, v47
	s_nop 1
	v_cndmask_b32_e64 v43, v43, v45, s[6:7]
	v_mul_f32_e32 v44, 0x37800000, v43
	v_cndmask_b32_e32 v43, v43, v44, vcc
	v_cmp_class_f32_e32 vcc, v42, v173
	s_nop 1
	v_cndmask_b32_e32 v42, v43, v42, vcc
	v_div_scale_f32 v43, s[6:7], v42, v42, 1.0
	v_rcp_f32_e32 v45, v43
	v_div_scale_f32 v44, vcc, 1.0, v42, 1.0
	v_fma_f32 v46, -v43, v45, 1.0
	v_fmac_f32_e32 v45, v46, v45
	v_mul_f32_e32 v46, v44, v45
	v_fma_f32 v47, -v43, v46, v44
	v_fmac_f32_e32 v46, v47, v45
	v_fma_f32 v43, -v43, v46, v44
	v_div_fmas_f32 v43, v43, v45, v46
	v_div_fixup_f32 v42, v43, v42, 1.0
	v_pk_mul_f32 v[32:33], v[32:33], v[42:43] op_sel_hi:[1,0]
	v_pk_mul_f32 v[30:31], v[30:31], v[42:43] op_sel_hi:[1,0]
	v_pk_mul_f32 v[32:33], v[4:5], v[32:33]
	v_pk_mul_f32 v[30:31], v[2:3], v[30:31]
	v_pk_fma_f32 v[32:33], v[36:37], v[32:33], v[40:41]
	v_pk_fma_f32 v[30:31], v[34:35], v[30:31], v[38:39]
	v_cvt_pk_bf16_f32 v30, v30, v31
	v_cvt_pk_bf16_f32 v31, v32, v33
	global_store_dwordx2 v[104:105], v[30:31], off offset:2048
	global_load_dwordx4 v[30:33], v[124:125], off
	s_nop 0
	global_load_dwordx4 v[34:37], v[120:121], off
	v_pk_mul_f32 v[28:29], v[28:29], v[42:43] op_sel_hi:[1,0]
	v_pk_mul_f32 v[26:27], v[26:27], v[42:43] op_sel_hi:[1,0]
	v_pk_mul_f32 v[28:29], v[8:9], v[28:29]
	v_pk_mul_f32 v[26:27], v[6:7], v[26:27]
	v_lshl_add_u64 v[40:41], s[20:21], 0, v[98:99]
	v_lshl_add_u64 v[38:39], s[18:19], 0, v[98:99]
	v_pk_mul_f32 v[24:25], v[24:25], v[42:43] op_sel_hi:[1,0]
	v_pk_mul_f32 v[22:23], v[22:23], v[42:43] op_sel_hi:[1,0]
	v_pk_mul_f32 v[24:25], v[12:13], v[24:25]
	v_pk_mul_f32 v[22:23], v[10:11], v[22:23]
	v_pk_mul_f32 v[20:21], v[20:21], v[42:43] op_sel_hi:[1,0]
	v_pk_mul_f32 v[18:19], v[18:19], v[42:43] op_sel_hi:[1,0]
	v_pk_mul_f32 v[20:21], v[16:17], v[20:21]
	v_pk_mul_f32 v[18:19], v[14:15], v[18:19]
	s_waitcnt vmcnt(0) lgkmcnt(0)
	v_pk_add_f32 v[32:33], v[32:33], 1.0 op_sel_hi:[1,0]
	v_pk_add_f32 v[30:31], v[30:31], 1.0 op_sel_hi:[1,0]
	v_pk_fma_f32 v[28:29], v[32:33], v[28:29], v[36:37]
	v_pk_fma_f32 v[26:27], v[30:31], v[26:27], v[34:35]
	v_cvt_pk_bf16_f32 v26, v26, v27
	v_cvt_pk_bf16_f32 v27, v28, v29
	global_store_dwordx2 v[104:105], v[26:27], off offset:2560
	global_load_dwordx4 v[26:29], v[40:41], off
	s_nop 0
	global_load_dwordx4 v[30:33], v[38:39], off
	v_lshl_add_u64 v[36:37], s[20:21], 0, v[100:101]
	v_lshl_add_u64 v[34:35], s[18:19], 0, v[100:101]
	s_waitcnt vmcnt(0) lgkmcnt(0)
	v_pk_add_f32 v[28:29], v[28:29], 1.0 op_sel_hi:[1,0]
	v_pk_add_f32 v[26:27], v[26:27], 1.0 op_sel_hi:[1,0]
	v_pk_fma_f32 v[24:25], v[28:29], v[24:25], v[32:33]
	v_pk_fma_f32 v[22:23], v[26:27], v[22:23], v[30:31]
	v_cvt_pk_bf16_f32 v22, v22, v23
	v_cvt_pk_bf16_f32 v23, v24, v25
	global_store_dwordx2 v[104:105], v[22:23], off offset:3072
	global_load_dwordx4 v[22:25], v[36:37], off
	s_nop 0
	global_load_dwordx4 v[26:29], v[34:35], off
	s_waitcnt vmcnt(0) lgkmcnt(0)
	v_pk_add_f32 v[24:25], v[24:25], 1.0 op_sel_hi:[1,0]
	v_pk_add_f32 v[22:23], v[22:23], 1.0 op_sel_hi:[1,0]
	v_pk_fma_f32 v[20:21], v[20:21], v[24:25], v[28:29]
	v_pk_fma_f32 v[18:19], v[18:19], v[22:23], v[26:27]
	v_cvt_pk_bf16_f32 v18, v18, v19
	v_cvt_pk_bf16_f32 v19, v20, v21
	global_store_dwordx2 v[104:105], v[18:19], off offset:3584
	s_cbranch_scc1 .LBB0_5544

.LBB0_5572:
	ds_read2_b32 v[20:21], v18 offset1:2
	ds_read2st64_b32 v[22:23], v19 offset1:4
	s_add_i32 s8, s8, -8
	s_cmp_lg_u32 s8, 0
	s_waitcnt lgkmcnt(0)
	v_mfma_f32_32x32x2_f32 v[2:17], v20, v22, v[2:17]
	v_mfma_f32_32x32x2_f32 v[2:17], v21, v23, v[2:17]
	ds_read2_b32 v[20:21], v18 offset0:4 offset1:6
	ds_read2st64_b32 v[22:23], v19 offset0:8 offset1:12
	s_waitcnt lgkmcnt(0)
	v_mfma_f32_32x32x2_f32 v[2:17], v20, v22, v[2:17]
	v_mfma_f32_32x32x2_f32 v[2:17], v21, v23, v[2:17]
	ds_read2_b32 v[20:21], v18 offset0:8 offset1:10
	ds_read2st64_b32 v[22:23], v19 offset0:16 offset1:20
	s_waitcnt lgkmcnt(0)
	v_mfma_f32_32x32x2_f32 v[2:17], v20, v22, v[2:17]
	v_mfma_f32_32x32x2_f32 v[2:17], v21, v23, v[2:17]
	ds_read2_b32 v[20:21], v18 offset0:12 offset1:14
	ds_read2st64_b32 v[22:23], v19 offset0:24 offset1:28
	v_add_u32_e32 v19, 0x2000, v19
	v_add_u32_e32 v18, 64, v18
	s_waitcnt lgkmcnt(0)
	v_mfma_f32_32x32x2_f32 v[2:17], v20, v22, v[2:17]
	v_mfma_f32_32x32x2_f32 v[2:17], v21, v23, v[2:17]
	s_cbranch_scc1 .LBB0_5572
	v_add_u32_e32 v18, 0xc200, v103
	s_barrier
	s_nop 14
	ds_write2_b32 v18, v2, v3 offset0:64 offset1:196
	v_add_u32_e32 v2, 0xc600, v103
	ds_write2_b32 v2, v4, v5 offset0:72 offset1:204
	v_add_u32_e32 v2, 0xd200, v103
	ds_write2_b32 v2, v6, v7 offset0:96 offset1:228
	v_add_u32_e32 v2, 0xd600, v103
	ds_write2_b32 v2, v8, v9 offset0:104 offset1:236
	v_add_u32_e32 v2, 0xe400, v103
	ds_write2_b32 v2, v10, v11 offset1:132
	v_add_u32_e32 v2, 0xe800, v103
	ds_write2_b32 v2, v12, v13 offset0:8 offset1:140
	v_add_u32_e32 v2, 0xf400, v103
	ds_write2_b32 v2, v14, v15 offset0:32 offset1:164
	v_add_u32_e32 v2, 0xf800, v103
	v_mov_b64_e32 v[18:19], s[0:1]
	ds_write2_b32 v2, v16, v17 offset0:40 offset1:172
	s_waitcnt lgkmcnt(0)
	s_barrier
	ds_read_b128 v[14:17], v95 offset:49920
	ds_read_b128 v[10:13], v95 offset:49936
	ds_read_b128 v[6:9], v95 offset:49952
	ds_read_b128 v[2:5], v95 offset:49968
	global_load_dwordx2 v[22:23], v[18:19], off offset:168 sc0 sc1
	s_waitcnt vmcnt(0)
	v_add_u32_e32 v60, s36, v94
	v_mov_b64_e32 v[18:19], s[12:13]
	v_and_b32_e32 v21, 64, v166
	s_lshl_b32 s70, s35, 2
	v_mad_i64_i32 v[18:19], s[8:9], v60, s29, v[18:19]
	v_xor_b32_e32 v20, 1, v166
	v_lshlrev_b32_e32 v42, 2, v54
	v_add_u32_e32 v59, 64, v21
	v_lshl_add_u64 v[18:19], v[18:19], 0, s[70:71]
	v_cmp_lt_i32_e32 vcc, v20, v59
	v_lshl_add_u64 v[30:31], v[18:19], 0, v[42:43]
	s_waitcnt lgkmcnt(0)
	v_mov_b32_e32 v26, v15
	v_cndmask_b32_e32 v20, v166, v20, vcc
	v_add_co_u32_e32 v18, vcc, s28, v30
	v_lshlrev_b32_e32 v61, 2, v20
	s_nop 0
	v_addc_co_u32_e32 v19, vcc, 0, v31, vcc
	global_load_dwordx4 v[18:21], v[18:19], off offset:1184
	v_mov_b32_e32 v27, v11
	v_mov_b32_e32 v24, v14
	v_mov_b32_e32 v25, v10
	v_mov_b32_e32 v36, v7
	v_mov_b32_e32 v37, v3
	v_pk_mul_f32 v[26:27], v[26:27], v[26:27]
	v_mov_b32_e32 v28, v16
	v_mov_b32_e32 v29, v12
	v_mov_b32_e32 v34, v6
	v_mov_b32_e32 v35, v2
	v_pk_mul_f32 v[36:37], v[36:37], v[36:37]
	v_pk_fma_f32 v[24:25], v[24:25], v[24:25], v[26:27]
	v_mov_b32_e32 v32, v17
	v_mov_b32_e32 v33, v13
	v_mov_b32_e32 v38, v8
	v_mov_b32_e32 v39, v4
	v_pk_fma_f32 v[26:27], v[34:35], v[34:35], v[36:37]
	v_pk_fma_f32 v[24:25], v[28:29], v[28:29], v[24:25]
	v_mov_b32_e32 v40, v9
	v_mov_b32_e32 v41, v5
	v_pk_fma_f32 v[26:27], v[38:39], v[38:39], v[26:27]
	v_pk_fma_f32 v[24:25], v[32:33], v[32:33], v[24:25]
	v_pk_fma_f32 v[26:27], v[40:41], v[40:41], v[26:27]
	v_add_f32_e32 v24, v24, v25
	v_add_f32_e32 v24, v24, v26
	v_add_f32_e32 v24, v24, v27
	ds_bpermute_b32 v25, v61, v24
	v_xor_b32_e32 v26, 2, v166
	v_cmp_lt_i32_e32 vcc, v26, v59
	v_lshl_add_u64 v[62:63], v[30:31], 0, s[72:73]
	v_mov_b32_e32 v38, v14
	v_cndmask_b32_e32 v26, v166, v26, vcc
	v_lshlrev_b32_e32 v26, 2, v26
	s_waitcnt lgkmcnt(0)
	v_add_f32_e32 v24, v24, v25
	ds_bpermute_b32 v25, v26, v24
	v_ashrrev_i32_e32 v61, 31, v60
	s_lshl_b32 s70, s35, 1
	s_mov_b64 s[76:77], 0
	s_waitcnt lgkmcnt(0)
	v_add_f32_e32 v32, v24, v25
	v_lshl_add_u64 v[64:65], v[22:23], 0, v[42:43]
	global_load_dwordx4 v[26:29], v[64:65], off offset:512
	v_xor_b32_e32 v22, 4, v166
	v_cmp_lt_i32_e32 vcc, v22, v59
	s_nop 1
	v_cndmask_b32_e32 v22, v166, v22, vcc
	v_lshlrev_b32_e32 v22, 2, v22
	ds_bpermute_b32 v33, v22, v32
	global_load_dwordx4 v[22:25], v[64:65], off offset:528
	s_waitcnt lgkmcnt(0)
	v_add_f32_e32 v30, v32, v33
	v_fmamk_f32 v30, v30, 0x3c000000, v104
	v_mul_f32_e32 v31, 0x4f800000, v30
	v_cmp_gt_f32_e32 vcc, s31, v30
	s_nop 1
	v_cndmask_b32_e32 v39, v30, v31, vcc
	v_sqrt_f32_e32 v40, v39
	global_load_dwordx4 v[30:33], v[62:63], off offset:16
	global_load_dwordx4 v[34:37], v[62:63], off offset:48
	v_add_u32_e32 v14, -1, v40
	v_add_u32_e32 v41, 1, v40
	v_fma_f32 v42, -v14, v40, v39
	v_fma_f32 v59, -v41, v40, v39
	v_cmp_ge_f32_e64 s[8:9], 0, v42
	s_nop 1
	v_cndmask_b32_e64 v14, v40, v14, s[8:9]
	v_cmp_lt_f32_e64 s[8:9], 0, v59
	s_nop 1
	v_cndmask_b32_e64 v14, v14, v41, s[8:9]
	v_mul_f32_e32 v40, 0x37800000, v14
	v_cndmask_b32_e32 v14, v14, v40, vcc
	v_cmp_class_f32_e32 vcc, v39, v105
	s_nop 1
	v_cndmask_b32_e32 v14, v14, v39, vcc
	v_div_scale_f32 v40, s[8:9], v14, v14, 1.0
	v_rcp_f32_e32 v41, v40
	v_mov_b32_e32 v39, v16
	v_div_scale_f32 v16, vcc, 1.0, v14, 1.0
	v_fma_f32 v42, -v40, v41, 1.0
	v_fmac_f32_e32 v41, v42, v41
	v_mul_f32_e32 v42, v16, v41
	v_fma_f32 v59, -v40, v42, v16
	v_fmac_f32_e32 v42, v59, v41
	v_fma_f32 v16, -v40, v42, v16
	v_div_fmas_f32 v16, v16, v41, v42
	v_div_fixup_f32 v14, v16, v14, 1.0
	v_pk_mul_f32 v[110:111], v[38:39], v[14:15] op_sel_hi:[1,0]
	s_waitcnt vmcnt(0)
	v_mul_f32_e32 v16, 0xbfb8aa3b, v18
	v_mul_f32_e32 v38, 0xbfb8aa3b, v20
	v_exp_f32_e32 v112, v16
	v_exp_f32_e32 v113, v38
	v_mul_f32_e32 v16, 0xbfb8aa3b, v19
	global_load_dwordx4 v[38:41], v[64:65], off offset:560
	global_load_dwordx4 v[106:109], v[64:65], off offset:544
	v_exp_f32_e32 v64, v16
	v_pk_add_f32 v[112:113], v[112:113], 1.0 op_sel_hi:[1,0]
	s_nop 0
	v_div_scale_f32 v16, s[8:9], v113, v113, v20
	v_rcp_f32_e32 v65, v16
	v_div_scale_f32 v59, s[8:9], v112, v112, v18
	v_rcp_f32_e32 v116, v59
	v_fma_f32 v114, -v16, v65, 1.0
	v_div_scale_f32 v42, vcc, v20, v113, v20
	v_fmac_f32_e32 v65, v114, v65
	v_fma_f32 v115, -v59, v116, 1.0
	v_mul_f32_e32 v114, v42, v65
	v_fmac_f32_e32 v116, v115, v116
	v_fma_f32 v115, -v16, v114, v42
	v_fmac_f32_e32 v114, v115, v65
	v_fma_f32 v16, -v16, v114, v42
	v_div_fmas_f32 v16, v16, v65, v114
	v_div_scale_f32 v117, s[8:9], v18, v112, v18
	v_div_fixup_f32 v113, v16, v113, v20
	v_mul_f32_e32 v20, 0xbfb8aa3b, v21
	v_mul_f32_e32 v118, v117, v116
	v_exp_f32_e32 v65, v20
	v_fma_f32 v119, -v59, v118, v117
	v_fmac_f32_e32 v118, v119, v116
	v_fma_f32 v16, -v59, v118, v117
	s_mov_b64 vcc, s[8:9]
	v_div_fmas_f32 v16, v16, v116, v118
	v_pk_add_f32 v[64:65], v[64:65], 1.0 op_sel_hi:[1,0]
	v_div_fixup_f32 v112, v16, v112, v18
	v_mov_b32_e32 v16, v15
	v_div_scale_f32 v15, s[8:9], v65, v65, v21
	v_rcp_f32_e32 v18, v15
	v_mov_b32_e32 v114, v26
	v_mov_b32_e32 v115, v28
	v_mov_b32_e32 v28, v27
	v_fma_f32 v20, -v15, v18, 1.0
	v_fmac_f32_e32 v18, v20, v18
	v_div_scale_f32 v20, vcc, v21, v65, v21
	v_mul_f32_e32 v26, v20, v18
	v_fma_f32 v27, -v15, v26, v20
	v_fmac_f32_e32 v26, v27, v18
	v_pk_mul_f32 v[16:17], v[16:17], v[14:15] op_sel_hi:[1,0]
	v_fma_f32 v15, -v15, v26, v20
	v_div_scale_f32 v20, s[8:9], v64, v64, v19
	v_rcp_f32_e32 v27, v20
	v_div_fmas_f32 v15, v15, v18, v26
	v_div_fixup_f32 v21, v15, v65, v21
	v_pk_mul_f32 v[16:17], v[28:29], v[16:17]
	v_fma_f32 v15, -v20, v27, 1.0
	v_fmac_f32_e32 v27, v15, v27
	v_div_scale_f32 v15, vcc, v19, v64, v19
	v_mul_f32_e32 v18, v15, v27
	v_fma_f32 v26, -v20, v18, v15
	v_fmac_f32_e32 v18, v26, v27
	v_fma_f32 v15, -v20, v18, v15
	v_div_fmas_f32 v15, v15, v27, v18
	v_div_fixup_f32 v20, v15, v64, v19
	v_pk_mul_f32 v[20:21], v[20:21], v[16:17]
	global_load_dwordx4 v[16:19], v[62:63], off offset:32
	s_waitcnt lgkmcnt(0)
	v_mul_f32_e32 v15, 0xbfb8aa3b, v30
	v_exp_f32_e32 v26, v15
	v_mul_f32_e32 v15, 0xbfb8aa3b, v31
	v_exp_f32_e32 v28, v15
	v_mul_f32_e32 v15, 0xbfb8aa3b, v32
	v_exp_f32_e32 v27, v15
	v_mov_b32_e32 v62, v10
	v_mov_b32_e32 v63, v12
	v_pk_mul_f32 v[62:63], v[62:63], v[14:15] op_sel_hi:[1,0]
	v_pk_add_f32 v[26:27], v[26:27], 1.0 op_sel_hi:[1,0]
	v_mov_b32_e32 v64, v22
	v_div_scale_f32 v10, s[8:9], v27, v27, v32
	v_rcp_f32_e32 v12, v10
	v_mov_b32_e32 v65, v24
	v_pk_mul_f32 v[110:111], v[114:115], v[110:111]
	v_pk_mul_f32 v[62:63], v[62:63], v[64:65]
	v_fma_f32 v15, -v10, v12, 1.0
	v_fmac_f32_e32 v12, v15, v12
	v_div_scale_f32 v15, vcc, v32, v27, v32
	v_mul_f32_e32 v22, v15, v12
	v_fma_f32 v24, -v10, v22, v15
	v_fmac_f32_e32 v22, v24, v12
	v_fma_f32 v10, -v10, v22, v15
	v_div_scale_f32 v15, s[8:9], v26, v26, v30
	v_rcp_f32_e32 v24, v15
	v_div_fmas_f32 v10, v10, v12, v22
	v_div_fixup_f32 v27, v10, v27, v32
	v_pk_mul_f32 v[110:111], v[112:113], v[110:111]
	v_fma_f32 v10, -v15, v24, 1.0
	v_fmac_f32_e32 v24, v10, v24
	v_div_scale_f32 v10, vcc, v30, v26, v30
	v_mul_f32_e32 v12, v10, v24
	v_fma_f32 v22, -v15, v12, v10
	v_fmac_f32_e32 v12, v22, v24
	v_fma_f32 v10, -v15, v12, v10
	v_div_fmas_f32 v10, v10, v24, v12
	v_mul_f32_e32 v12, 0xbfb8aa3b, v33
	v_exp_f32_e32 v29, v12
	v_div_fixup_f32 v26, v10, v26, v30
	v_mov_b32_e32 v12, v11
	v_mov_b32_e32 v24, v23
	v_pk_add_f32 v[10:11], v[28:29], 1.0 op_sel_hi:[1,0]
	v_pk_mul_f32 v[26:27], v[62:63], v[26:27]
	v_div_scale_f32 v15, s[8:9], v11, v11, v33
	v_rcp_f32_e32 v22, v15
	v_pk_mul_f32 v[12:13], v[12:13], v[14:15] op_sel_hi:[1,0]
	v_lshlrev_b32_e32 v42, 1, v54
	v_pk_mul_f32 v[12:13], v[12:13], v[24:25]
	v_fma_f32 v23, -v15, v22, 1.0
	v_fmac_f32_e32 v22, v23, v22
	v_div_scale_f32 v23, vcc, v33, v11, v33
	v_mul_f32_e32 v24, v23, v22
	v_fma_f32 v25, -v15, v24, v23
	v_fmac_f32_e32 v24, v25, v22
	v_fma_f32 v15, -v15, v24, v23
	v_div_scale_f32 v23, s[8:9], v10, v10, v31
	v_rcp_f32_e32 v25, v23
	v_div_fmas_f32 v15, v15, v22, v24
	v_div_fixup_f32 v11, v15, v11, v33
	v_fma_f32 v15, -v23, v25, 1.0
	v_fmac_f32_e32 v25, v15, v25
	v_div_scale_f32 v15, vcc, v31, v10, v31
	v_mul_f32_e32 v22, v15, v25
	v_fma_f32 v24, -v23, v22, v15
	v_fmac_f32_e32 v22, v24, v25
	v_fma_f32 v15, -v23, v22, v15
	v_div_fmas_f32 v15, v15, v25, v22
	v_div_fixup_f32 v10, v15, v10, v31
	v_pk_mul_f32 v[10:11], v[12:13], v[10:11]
	v_cvt_pk_bf16_f32 v13, v27, v11
	v_cvt_pk_bf16_f32 v11, v111, v21
	s_waitcnt vmcnt(0)
	v_mul_f32_e32 v15, 0xbfb8aa3b, v16
	v_cvt_pk_bf16_f32 v12, v26, v10
	v_cvt_pk_bf16_f32 v10, v110, v20
	v_exp_f32_e32 v20, v15
	v_mul_f32_e32 v15, 0xbfb8aa3b, v17
	v_exp_f32_e32 v22, v15
	v_mul_f32_e32 v15, 0xbfb8aa3b, v18
	v_exp_f32_e32 v21, v15
	v_mov_b32_e32 v24, v6
	v_mov_b32_e32 v25, v8
	v_pk_mul_f32 v[24:25], v[24:25], v[14:15] op_sel_hi:[1,0]
	v_pk_add_f32 v[20:21], v[20:21], 1.0 op_sel_hi:[1,0]
	v_mov_b32_e32 v26, v106
	v_div_scale_f32 v6, s[8:9], v21, v21, v18
	v_rcp_f32_e32 v8, v6
	v_mov_b32_e32 v27, v108
	v_pk_mul_f32 v[24:25], v[24:25], v[26:27]
	v_mov_b32_e32 v108, v107
	v_fma_f32 v15, -v6, v8, 1.0
	v_fmac_f32_e32 v8, v15, v8
	v_div_scale_f32 v15, vcc, v18, v21, v18
	v_mul_f32_e32 v23, v15, v8
	v_fma_f32 v26, -v6, v23, v15
	v_fmac_f32_e32 v23, v26, v8
	v_fma_f32 v6, -v6, v23, v15
	v_div_scale_f32 v15, s[8:9], v20, v20, v16
	v_rcp_f32_e32 v26, v15
	v_div_fmas_f32 v6, v6, v8, v23
	v_div_fixup_f32 v21, v6, v21, v18
	v_fma_f32 v6, -v15, v26, 1.0
	v_fmac_f32_e32 v26, v6, v26
	v_div_scale_f32 v6, vcc, v16, v20, v16
	v_mul_f32_e32 v8, v6, v26
	v_fma_f32 v18, -v15, v8, v6
	v_fmac_f32_e32 v8, v18, v26
	v_fma_f32 v6, -v15, v8, v6
	v_div_fmas_f32 v6, v6, v26, v8
	v_mul_f32_e32 v8, 0xbfb8aa3b, v19
	v_exp_f32_e32 v23, v8
	v_div_fixup_f32 v20, v6, v20, v16
	v_mov_b32_e32 v8, v7
	v_pk_mul_f32 v[20:21], v[24:25], v[20:21]
	v_pk_add_f32 v[6:7], v[22:23], 1.0 op_sel_hi:[1,0]
	s_nop 0
	v_div_scale_f32 v15, s[8:9], v7, v7, v19
	v_rcp_f32_e32 v16, v15
	v_pk_mul_f32 v[8:9], v[8:9], v[14:15] op_sel_hi:[1,0]
	v_fma_f32 v18, -v15, v16, 1.0
	v_fmac_f32_e32 v16, v18, v16
	v_div_scale_f32 v18, vcc, v19, v7, v19
	v_mul_f32_e32 v22, v18, v16
	v_fma_f32 v23, -v15, v22, v18
	v_fmac_f32_e32 v22, v23, v16
	v_fma_f32 v15, -v15, v22, v18
	v_div_scale_f32 v18, s[8:9], v6, v6, v17
	v_rcp_f32_e32 v23, v18
	v_div_fmas_f32 v15, v15, v16, v22
	v_div_fixup_f32 v7, v15, v7, v19
	v_pk_mul_f32 v[8:9], v[8:9], v[108:109]
	v_fma_f32 v15, -v18, v23, 1.0
	v_fmac_f32_e32 v23, v15, v23
	v_div_scale_f32 v15, vcc, v17, v6, v17
	v_mul_f32_e32 v16, v15, v23
	v_fma_f32 v19, -v18, v16, v15
	v_fmac_f32_e32 v16, v19, v23
	v_fma_f32 v15, -v18, v16, v15
	v_div_fmas_f32 v15, v15, v23, v16
	v_div_fixup_f32 v6, v15, v6, v17
	v_pk_mul_f32 v[6:7], v[8:9], v[6:7]
	v_mul_f32_e32 v9, 0xbfb8aa3b, v35
	v_mul_f32_e32 v8, 0xbfb8aa3b, v34
	v_exp_f32_e32 v16, v9
	v_mul_f32_e32 v9, 0xbfb8aa3b, v36
	v_exp_f32_e32 v8, v8
	v_exp_f32_e32 v9, v9
	v_mov_b32_e32 v18, v2
	v_mov_b32_e32 v19, v4
	v_pk_mul_f32 v[18:19], v[18:19], v[14:15] op_sel_hi:[1,0]
	v_pk_add_f32 v[8:9], v[8:9], 1.0 op_sel_hi:[1,0]
	v_mov_b32_e32 v22, v38
	v_div_scale_f32 v2, s[8:9], v9, v9, v36
	v_rcp_f32_e32 v4, v2
	v_mov_b32_e32 v23, v40
	v_pk_mul_f32 v[18:19], v[18:19], v[22:23]
	v_mov_b32_e32 v40, v39
	v_fma_f32 v15, -v2, v4, 1.0
	v_fmac_f32_e32 v4, v15, v4
	v_div_scale_f32 v15, vcc, v36, v9, v36
	v_mul_f32_e32 v17, v15, v4
	v_fma_f32 v22, -v2, v17, v15
	v_fmac_f32_e32 v17, v22, v4
	v_fma_f32 v2, -v2, v17, v15
	v_div_scale_f32 v15, s[8:9], v8, v8, v34
	v_rcp_f32_e32 v22, v15
	v_div_fmas_f32 v2, v2, v4, v17
	v_div_fixup_f32 v9, v2, v9, v36
	v_fma_f32 v2, -v15, v22, 1.0
	v_fmac_f32_e32 v22, v2, v22
	v_div_scale_f32 v2, vcc, v34, v8, v34
	v_mul_f32_e32 v4, v2, v22
	v_fma_f32 v17, -v15, v4, v2
	v_fmac_f32_e32 v4, v17, v22
	v_fma_f32 v2, -v15, v4, v2
	v_div_fmas_f32 v2, v2, v22, v4
	v_mul_f32_e32 v4, 0xbfb8aa3b, v37
	v_exp_f32_e32 v17, v4
	v_div_fixup_f32 v8, v2, v8, v34
	v_mov_b32_e32 v4, v3
	v_pk_mul_f32 v[8:9], v[18:19], v[8:9]
	v_pk_add_f32 v[2:3], v[16:17], 1.0 op_sel_hi:[1,0]
	s_nop 0
	v_div_scale_f32 v15, s[8:9], v3, v3, v37
	v_rcp_f32_e32 v16, v15
	v_pk_mul_f32 v[4:5], v[4:5], v[14:15] op_sel_hi:[1,0]
	v_fma_f32 v14, -v15, v16, 1.0
	v_fmac_f32_e32 v16, v14, v16
	v_div_scale_f32 v14, vcc, v37, v3, v37
	v_mul_f32_e32 v17, v14, v16
	v_fma_f32 v18, -v15, v17, v14
	v_fmac_f32_e32 v17, v18, v16
	v_fma_f32 v14, -v15, v17, v14
	v_div_scale_f32 v15, s[8:9], v2, v2, v35
	v_rcp_f32_e32 v18, v15
	v_div_fmas_f32 v14, v14, v16, v17
	v_div_fixup_f32 v3, v14, v3, v37
	v_pk_mul_f32 v[4:5], v[4:5], v[40:41]
	v_fma_f32 v14, -v15, v18, 1.0
	v_fmac_f32_e32 v18, v14, v18
	v_div_scale_f32 v14, vcc, v35, v2, v35
	v_mul_f32_e32 v16, v14, v18
	v_fma_f32 v17, -v15, v16, v14
	v_fmac_f32_e32 v16, v17, v18
	v_fma_f32 v14, -v15, v16, v14
	v_div_fmas_f32 v14, v14, v18, v16
	v_div_fixup_f32 v2, v14, v2, v35
	v_pk_mul_f32 v[2:3], v[4:5], v[2:3]
	v_bfe_u32 v5, v2, 16, 1
	v_add3_u32 v2, v2, v5, s33
	v_bfe_u32 v14, v8, 16, 1
	v_add3_u32 v8, v8, v14, s33
	v_lshrrev_b32_e32 v4, 16, v8
	v_cvt_pk_bf16_f32 v5, v9, v3
	v_and_or_b32 v4, v2, s34, v4
	v_cvt_pk_bf16_f32 v3, v21, v7
	v_cvt_pk_bf16_f32 v2, v20, v6
	v_lshlrev_b64 v[6:7], 11, v[60:61]
	v_lshl_add_u64 v[6:7], s[68:69], 0, v[6:7]
	v_lshl_add_u64 v[6:7], v[6:7], 0, s[70:71]
	v_lshl_add_u64 v[6:7], v[6:7], 0, v[42:43]
	v_lshl_add_u64 v[8:9], v[6:7], 0, s[74:75]
	v_add_co_u32_e32 v6, vcc, 0xdc00000, v6
	s_nop 1
	v_addc_co_u32_e32 v7, vcc, 0, v7, vcc
	global_store_dwordx4 v[6:7], v[10:13], off offset:1024
	global_store_dwordx4 v[8:9], v[2:5], off offset:16
	s_branch .LBB0_5556

.LBB0_5693:
	v_lshl_add_u64 v[18:19], s[68:69], 0, v[94:95]
	v_lshl_add_u64 v[22:23], s[68:69], 0, v[92:93]
	v_add_co_u32_e32 v20, vcc, 0x7800000, v18
	v_add_co_u32_e64 v102, s[6:7], s22, v22
	s_nop 0
	v_addc_co_u32_e32 v21, vcc, 0, v19, vcc
	v_addc_co_u32_e64 v103, s[6:7], 0, v23, s[6:7]
	v_add_co_u32_e64 v104, s[6:7], s23, v22
	v_add_co_u32_e32 v22, vcc, 0x7801000, v18
	s_nop 0
	v_addc_co_u32_e64 v105, s[6:7], 0, v23, s[6:7]
	global_load_dwordx4 v[78:81], v[20:21], off
	global_load_dwordx4 v[74:77], v[20:21], off offset:1024
	global_load_dwordx4 v[70:73], v[20:21], off offset:2048
	global_load_dwordx4 v[66:69], v[20:21], off offset:3072
	v_addc_co_u32_e32 v23, vcc, 0, v19, vcc
	v_add_co_u32_e32 v20, vcc, 0x7802000, v18
	global_load_dwordx4 v[62:65], v[22:23], off
	global_load_dwordx4 v[58:61], v[22:23], off offset:1024
	global_load_dwordx4 v[54:57], v[22:23], off offset:2048
	global_load_dwordx4 v[50:53], v[22:23], off offset:3072
	v_addc_co_u32_e32 v21, vcc, 0, v19, vcc
	v_add_co_u32_e32 v82, vcc, 0x7803000, v18
	global_load_dwordx4 v[46:49], v[20:21], off
	global_load_dwordx4 v[42:45], v[20:21], off offset:1024
	global_load_dwordx4 v[38:41], v[20:21], off offset:2048
	global_load_dwordx4 v[34:37], v[20:21], off offset:3072
	v_addc_co_u32_e32 v83, vcc, 0, v19, vcc
	global_load_dwordx4 v[30:33], v[82:83], off
	global_load_dwordx4 v[26:29], v[82:83], off offset:1024
	global_load_dwordx4 v[22:25], v[82:83], off offset:2048
	global_load_dwordx4 v[18:21], v[82:83], off offset:3072
	s_add_i32 s24, s8, 32
	s_add_i32 s10, s8, 0xffffc022
	s_ashr_i32 s9, s24, 13
	s_cmpk_lt_i32 s24, 0x4000
	s_cselect_b32 s6, s9, s10
	s_addk_i32 s6, 0x82
	s_mul_hi_i32 s7, s6, 0x9000
	s_mul_i32 s6, s6, 0x9000
	s_add_u32 s10, s4, s6
	s_addc_u32 s11, s5, s7
	s_add_u32 s6, s10, 0x6000
	s_addc_u32 s7, s11, 0
	s_add_u32 s10, s10, 0x7000
	s_addc_u32 s11, s11, 0
	v_lshl_add_u64 v[82:83], s[6:7], 0, v[90:91]
	v_lshl_add_u64 v[86:87], s[10:11], 0, v[90:91]
	global_load_dwordx4 v[82:85], v[82:83], off
	v_lshl_add_u64 v[148:149], s[6:7], 0, v[96:97]
	global_load_dwordx4 v[86:89], v[86:87], off
	v_lshl_add_u64 v[142:143], s[6:7], 0, v[98:99]
	v_lshl_add_u64 v[132:133], s[6:7], 0, v[100:101]
	s_add_i32 s6, s8, 0xffffc023
	s_cmpk_lt_i32 s24, 0x3fff
	s_cselect_b32 s6, s9, s6
	s_addk_i32 s6, 0x82
	s_mul_hi_i32 s7, s6, 0x9000
	s_mul_i32 s6, s6, 0x9000
	v_lshl_add_u64 v[152:153], s[10:11], 0, v[96:97]
	v_lshl_add_u64 v[146:147], s[10:11], 0, v[98:99]
	v_lshl_add_u64 v[140:141], s[10:11], 0, v[100:101]
	s_add_u32 s10, s4, s6
	s_addc_u32 s11, s5, s7
	s_add_u32 s6, s10, 0x6000
	s_addc_u32 s7, s11, 0
	s_add_u32 s10, s10, 0x7000
	v_lshl_add_u64 v[134:135], s[6:7], 0, v[90:91]
	v_lshl_add_u64 v[126:127], s[6:7], 0, v[96:97]
	v_lshl_add_u64 v[118:119], s[6:7], 0, v[98:99]
	v_lshl_add_u64 v[114:115], s[6:7], 0, v[100:101]
	s_addc_u32 s11, s11, 0
	s_add_i32 s6, s8, 0xffffc024
	s_cmpk_lt_i32 s24, 0x3ffe
	s_cselect_b32 s6, s9, s6
	s_addk_i32 s6, 0x82
	s_mul_hi_i32 s7, s6, 0x9000
	s_mul_i32 s6, s6, 0x9000
	s_add_u32 s6, s4, s6
	s_addc_u32 s7, s5, s7
	v_lshl_add_u64 v[136:137], s[10:11], 0, v[90:91]
	v_lshl_add_u64 v[130:131], s[10:11], 0, v[96:97]
	v_lshl_add_u64 v[122:123], s[10:11], 0, v[98:99]
	v_lshl_add_u64 v[116:117], s[10:11], 0, v[100:101]
	s_add_u32 s10, s6, 0x6000
	s_addc_u32 s11, s7, 0
	s_add_u32 s6, s6, 0x7000
	s_addc_u32 s7, s7, 0
	s_addk_i32 s8, 0xc025
	s_cmpk_lt_i32 s24, 0x3ffd
	v_lshl_add_u64 v[156:157], s[6:7], 0, v[90:91]
	v_lshl_add_u64 v[154:155], s[6:7], 0, v[96:97]
	v_lshl_add_u64 v[150:151], s[6:7], 0, v[98:99]
	v_lshl_add_u64 v[138:139], s[6:7], 0, v[100:101]
	s_cselect_b32 s6, s9, s8
	s_waitcnt vmcnt(0) lgkmcnt(0)
	v_pk_mul_f32 v[158:159], v[80:81], v[80:81]
	v_pk_mul_f32 v[160:161], v[78:79], v[78:79]
	v_pk_mul_f32 v[162:163], v[76:77], v[76:77]
	v_pk_mul_f32 v[164:165], v[74:75], v[74:75]
	v_mul_f32_e32 v174, v71, v71
	v_mul_f32_e32 v176, v73, v73
	v_mul_f32_e32 v187, v68, v68
	v_mul_f32_e32 v189, v69, v69
	v_pk_mov_b32 v[178:179], v[160:161], v[158:159] op_sel:[1,0]
	v_mov_b32_e32 v161, v159
	v_pk_mov_b32 v[158:159], v[164:165], v[162:163] op_sel:[1,0]
	v_mov_b32_e32 v165, v163
	v_pk_fma_f32 v[162:163], v[70:71], v[70:71], v[174:175] op_sel_hi:[1,1,0]
	v_pk_fma_f32 v[174:175], v[72:73], v[72:73], v[176:177] op_sel_hi:[1,1,0]
	v_pk_mul_f32 v[176:177], v[64:65], v[64:65]
	v_pk_mul_f32 v[180:181], v[62:63], v[62:63]
	v_pk_mul_f32 v[182:183], v[60:61], v[60:61]
	v_pk_mul_f32 v[184:185], v[58:59], v[58:59]
	v_mul_f32_e32 v186, v55, v55
	v_mul_f32_e32 v188, v57, v57
	v_pk_add_f32 v[160:161], v[178:179], v[160:161]
	v_pk_add_f32 v[158:159], v[158:159], v[164:165]
	v_mov_b32_e32 v163, v187
	v_mov_b32_e32 v175, v189
	v_pk_mov_b32 v[164:165], v[180:181], v[176:177] op_sel:[1,0]
	v_mov_b32_e32 v181, v177
	v_pk_mov_b32 v[176:177], v[184:185], v[182:183] op_sel:[1,0]
	v_mov_b32_e32 v185, v183
	v_pk_fma_f32 v[178:179], v[54:55], v[54:55], v[186:187] op_sel_hi:[1,1,0]
	v_pk_fma_f32 v[182:183], v[56:57], v[56:57], v[188:189] op_sel_hi:[1,1,0]
	v_pk_mul_f32 v[186:187], v[48:49], v[48:49]
	v_pk_mul_f32 v[188:189], v[46:47], v[46:47]
	v_pk_mul_f32 v[190:191], v[44:45], v[44:45]
	v_pk_mul_f32 v[192:193], v[42:43], v[42:43]
	v_mul_f32_e32 v173, v66, v66
	v_mul_f32_e32 v197, v67, v67
	v_mul_f32_e32 v195, v52, v52
	v_mul_f32_e32 v202, v53, v53
	v_mul_f32_e32 v194, v39, v39
	v_mul_f32_e32 v196, v41, v41
	v_pk_add_f32 v[198:199], v[160:161], v[160:161] op_sel:[0,1] op_sel_hi:[1,0]
	v_pk_add_f32 v[200:201], v[158:159], v[158:159] op_sel:[0,1] op_sel_hi:[1,0]
	v_pk_add_f32 v[174:175], v[162:163], v[174:175]
	v_pk_add_f32 v[158:159], v[164:165], v[180:181]
	v_pk_add_f32 v[160:161], v[176:177], v[184:185]
	v_pk_mov_b32 v[162:163], v[188:189], v[186:187] op_sel:[1,0]
	v_mov_b32_e32 v189, v187
	v_pk_mov_b32 v[164:165], v[192:193], v[190:191] op_sel:[1,0]
	v_mov_b32_e32 v193, v191
	v_mul_f32_e32 v203, v50, v50
	v_mul_f32_e32 v208, v51, v51
	v_mul_f32_e32 v211, v36, v36
	v_mul_f32_e32 v212, v37, v37
	v_mov_b32_e32 v179, v195
	v_mov_b32_e32 v183, v202
	v_pk_fma_f32 v[176:177], v[38:39], v[38:39], v[194:195] op_sel_hi:[1,1,0]
	v_pk_fma_f32 v[180:181], v[40:41], v[40:41], v[196:197] op_sel_hi:[1,1,0]
	v_pk_mul_f32 v[184:185], v[32:33], v[32:33]
	v_pk_mul_f32 v[186:187], v[30:31], v[30:31]
	v_pk_mul_f32 v[190:191], v[28:29], v[28:29]
	v_pk_mul_f32 v[194:195], v[26:27], v[26:27]
	v_mov_b32_e32 v199, v173
	v_mov_b32_e32 v201, v197
	v_pk_add_f32 v[204:205], v[158:159], v[158:159] op_sel:[0,1] op_sel_hi:[1,0]
	v_pk_add_f32 v[206:207], v[160:161], v[160:161] op_sel:[0,1] op_sel_hi:[1,0]
	v_pk_add_f32 v[162:163], v[162:163], v[188:189]
	v_pk_add_f32 v[164:165], v[164:165], v[192:193]
	v_mul_f32_e32 v209, v34, v34
	v_mul_f32_e32 v210, v35, v35
	v_pk_add_f32 v[178:179], v[178:179], v[182:183]
	v_mov_b32_e32 v177, v211
	v_mov_b32_e32 v181, v212
	v_pk_mov_b32 v[182:183], v[186:187], v[184:185] op_sel:[1,0]
	v_mov_b32_e32 v187, v185
	v_pk_mov_b32 v[184:185], v[194:195], v[190:191] op_sel:[1,0]
	v_mov_b32_e32 v195, v191
	v_pk_add_f32 v[188:189], v[198:199], v[200:201]
	v_mov_b32_e32 v205, v203
	v_mov_b32_e32 v207, v208
	v_pk_add_f32 v[190:191], v[162:163], v[162:163] op_sel:[0,1] op_sel_hi:[1,0]
	v_pk_add_f32 v[192:193], v[164:165], v[164:165] op_sel:[0,1] op_sel_hi:[1,0]
	v_pk_add_f32 v[176:177], v[176:177], v[180:181]
	v_pk_add_f32 v[174:175], v[188:189], v[174:175]
	v_pk_add_f32 v[180:181], v[204:205], v[206:207]
	v_mov_b32_e32 v191, v209
	v_mov_b32_e32 v193, v210
	v_add_f32_e32 v173, v174, v175
	v_pk_add_f32 v[174:175], v[180:181], v[178:179]
	v_pk_add_f32 v[178:179], v[190:191], v[192:193]
	v_add_f32_e32 v180, v174, v175
	v_pk_add_f32 v[174:175], v[178:179], v[176:177]
	ds_bpermute_b32 v176, v1, v173
	v_add_f32_e32 v174, v174, v175
	ds_bpermute_b32 v175, v1, v180
	ds_bpermute_b32 v177, v1, v174
	s_addk_i32 s6, 0x82
	s_waitcnt lgkmcnt(2)
	v_add_f32_e32 v173, v173, v176
	ds_bpermute_b32 v176, v166, v173
	s_waitcnt lgkmcnt(2)
	v_add_f32_e32 v175, v180, v175
	ds_bpermute_b32 v178, v166, v175
	s_waitcnt lgkmcnt(2)
	v_add_f32_e32 v174, v174, v177
	ds_bpermute_b32 v177, v166, v174
	s_waitcnt lgkmcnt(2)
	v_add_f32_e32 v173, v173, v176
	ds_bpermute_b32 v176, v167, v173
	s_waitcnt lgkmcnt(2)
	v_add_f32_e32 v175, v175, v178
	ds_bpermute_b32 v178, v167, v175
	s_waitcnt lgkmcnt(2)
	v_add_f32_e32 v174, v174, v177
	ds_bpermute_b32 v177, v167, v174
	s_waitcnt lgkmcnt(2)
	v_add_f32_e32 v173, v173, v176
	ds_bpermute_b32 v176, v168, v173
	s_waitcnt lgkmcnt(2)
	v_add_f32_e32 v175, v175, v178
	ds_bpermute_b32 v178, v168, v175
	s_waitcnt lgkmcnt(2)
	v_add_f32_e32 v174, v174, v177
	ds_bpermute_b32 v177, v168, v174
	s_waitcnt lgkmcnt(2)
	v_add_f32_e32 v173, v173, v176
	ds_bpermute_b32 v176, v169, v173
	s_waitcnt lgkmcnt(2)
	v_add_f32_e32 v175, v175, v178
	ds_bpermute_b32 v178, v169, v175
	s_waitcnt lgkmcnt(2)
	v_add_f32_e32 v174, v174, v177
	ds_bpermute_b32 v177, v169, v174
	s_waitcnt lgkmcnt(2)
	v_add_f32_e32 v173, v173, v176
	ds_bpermute_b32 v176, v170, v173
	s_waitcnt lgkmcnt(2)
	v_add_f32_e32 v175, v175, v178
	ds_bpermute_b32 v178, v170, v175
	s_mul_hi_i32 s7, s6, 0x9000
	s_mul_i32 s6, s6, 0x9000
	s_waitcnt lgkmcnt(2)
	v_add_f32_e32 v174, v174, v177
	s_add_u32 s6, s4, s6
	ds_bpermute_b32 v177, v170, v174
	s_addc_u32 s7, s5, s7
	s_waitcnt lgkmcnt(2)
	v_add_f32_e32 v173, v173, v176
	s_add_u32 s16, s6, 0x6000
	v_fmamk_f32 v173, v173, 0x3a800000, v171
	s_addc_u32 s17, s7, 0
	s_waitcnt lgkmcnt(1)
	v_add_f32_e32 v175, v175, v178
	v_mul_f32_e32 v176, 0x4f800000, v173
	v_cmp_gt_f32_e32 vcc, s2, v173
	s_add_u32 s18, s6, 0x7000
	v_fmamk_f32 v175, v175, 0x3a800000, v171
	v_cndmask_b32_e32 v173, v173, v176, vcc
	s_addc_u32 s19, s7, 0
	s_waitcnt lgkmcnt(0)
	v_add_f32_e32 v174, v174, v177
	v_mul_f32_e32 v176, 0x4f800000, v175
	v_cmp_gt_f32_e64 s[6:7], s2, v175
	v_sqrt_f32_e32 v177, v173
	v_fmamk_f32 v174, v174, 0x3a800000, v171
	v_cndmask_b32_e64 v175, v175, v176, s[6:7]
	v_mul_f32_e32 v176, 0x4f800000, v174
	v_cmp_gt_f32_e64 s[8:9], s2, v174
	v_sqrt_f32_e32 v178, v175
	v_add_u32_e32 v179, -1, v177
	v_cndmask_b32_e64 v174, v174, v176, s[8:9]
	v_sqrt_f32_e32 v176, v174
	v_add_u32_e32 v180, 1, v177
	v_fma_f32 v181, -v179, v177, v173
	v_lshl_add_u64 v[112:113], s[10:11], 0, v[90:91]
	v_lshl_add_u64 v[106:107], s[10:11], 0, v[96:97]
	v_lshl_add_u64 v[110:111], s[10:11], 0, v[98:99]
	v_lshl_add_u64 v[108:109], s[10:11], 0, v[100:101]
	v_pk_add_f32 v[162:163], v[182:183], v[186:187]
	v_fma_f32 v182, -v180, v177, v173
	v_add_u32_e32 v183, -1, v178
	v_cmp_ge_f32_e64 s[10:11], 0, v181
	v_pk_add_f32 v[164:165], v[184:185], v[194:195]
	v_add_u32_e32 v184, 1, v178
	v_cndmask_b32_e64 v177, v177, v179, s[10:11]
	v_fma_f32 v179, -v183, v178, v175
	v_cmp_lt_f32_e64 s[10:11], 0, v182
	v_fma_f32 v181, -v184, v178, v175
	v_add_u32_e32 v185, -1, v176
	v_cndmask_b32_e64 v177, v177, v180, s[10:11]
	v_cmp_ge_f32_e64 s[10:11], 0, v179
	v_add_u32_e32 v186, 1, v176
	v_fma_f32 v179, -v185, v176, v174
	v_cndmask_b32_e64 v178, v178, v183, s[10:11]
	v_cmp_lt_f32_e64 s[10:11], 0, v181
	v_fma_f32 v180, -v186, v176, v174
	v_mul_f32_e32 v181, 0x37800000, v177
	v_cndmask_b32_e64 v178, v178, v184, s[10:11]
	v_cmp_ge_f32_e64 s[10:11], 0, v179
	v_cndmask_b32_e32 v177, v177, v181, vcc
	v_cmp_class_f32_e32 vcc, v173, v172
	v_cndmask_b32_e64 v176, v176, v185, s[10:11]
	v_cmp_lt_f32_e64 s[10:11], 0, v180
	v_mul_f32_e32 v179, 0x37800000, v178
	v_cndmask_b32_e32 v173, v177, v173, vcc
	v_cndmask_b32_e64 v176, v176, v186, s[10:11]
	v_cndmask_b32_e64 v177, v178, v179, s[6:7]
	v_cmp_class_f32_e32 vcc, v175, v172
	v_mul_f32_e32 v178, 0x37800000, v176
	v_div_scale_f32 v179, s[6:7], v173, v173, 1.0
	v_cndmask_b32_e32 v175, v177, v175, vcc
	v_cndmask_b32_e64 v176, v176, v178, s[8:9]
	v_cmp_class_f32_e32 vcc, v174, v172
	v_rcp_f32_e32 v177, v179
	v_div_scale_f32 v178, s[8:9], v175, v175, 1.0
	v_cndmask_b32_e32 v176, v176, v174, vcc
	v_rcp_f32_e32 v182, v178
	v_div_scale_f32 v183, s[10:11], v176, v176, 1.0
	v_rcp_f32_e32 v185, v183
	v_fma_f32 v174, -v179, v177, 1.0
	v_div_scale_f32 v180, s[6:7], 1.0, v173, 1.0
	v_fmac_f32_e32 v177, v174, v177
	v_fma_f32 v174, -v178, v182, 1.0
	v_mul_f32_e32 v186, v180, v177
	v_div_scale_f32 v181, s[8:9], 1.0, v175, 1.0
	v_fmac_f32_e32 v182, v174, v182
	v_fma_f32 v174, -v183, v185, 1.0
	v_fma_f32 v187, -v179, v186, v180
	v_div_scale_f32 v184, s[10:11], 1.0, v176, 1.0
	v_mul_f32_e32 v188, v181, v182
	v_fmac_f32_e32 v185, v174, v185
	v_fmac_f32_e32 v186, v187, v177
	v_fma_f32 v174, -v178, v188, v181
	v_mul_f32_e32 v187, v184, v185
	v_fma_f32 v179, -v179, v186, v180
	s_mov_b64 vcc, s[6:7]
	v_fmac_f32_e32 v188, v174, v182
	v_fma_f32 v174, -v183, v187, v184
	v_div_fmas_f32 v177, v179, v177, v186
	v_fma_f32 v178, -v178, v188, v181
	v_fmac_f32_e32 v187, v174, v185
	v_div_fixup_f32 v174, v177, v173, 1.0
	s_mov_b64 vcc, s[8:9]
	v_div_fmas_f32 v173, v178, v182, v188
	v_fma_f32 v177, -v183, v187, v184
	v_pk_mul_f32 v[80:81], v[80:81], v[174:175] op_sel_hi:[1,0]
	v_pk_mul_f32 v[78:79], v[78:79], v[174:175] op_sel_hi:[1,0]
	s_mov_b64 vcc, s[10:11]
	v_pk_add_f32 v[88:89], v[88:89], 1.0 op_sel_hi:[1,0]
	v_pk_add_f32 v[86:87], v[86:87], 1.0 op_sel_hi:[1,0]
	v_pk_mul_f32 v[76:77], v[76:77], v[174:175] op_sel_hi:[1,0]
	v_pk_mul_f32 v[74:75], v[74:75], v[174:175] op_sel_hi:[1,0]
	v_pk_mul_f32 v[72:73], v[72:73], v[174:175] op_sel_hi:[1,0]
	v_pk_mul_f32 v[70:71], v[70:71], v[174:175] op_sel_hi:[1,0]
	v_pk_mul_f32 v[68:69], v[68:69], v[174:175] op_sel_hi:[1,0]
	v_pk_mul_f32 v[66:67], v[66:67], v[174:175] op_sel_hi:[1,0]
	v_div_fixup_f32 v174, v173, v175, 1.0
	v_div_fmas_f32 v173, v177, v185, v187
	v_pk_mul_f32 v[78:79], v[2:3], v[78:79]
	v_pk_mul_f32 v[80:81], v[4:5], v[80:81]
	v_pk_mul_f32 v[64:65], v[64:65], v[174:175] op_sel_hi:[1,0]
	v_pk_mul_f32 v[62:63], v[62:63], v[174:175] op_sel_hi:[1,0]
	v_pk_mul_f32 v[60:61], v[60:61], v[174:175] op_sel_hi:[1,0]
	v_pk_mul_f32 v[58:59], v[58:59], v[174:175] op_sel_hi:[1,0]
	v_pk_mul_f32 v[56:57], v[56:57], v[174:175] op_sel_hi:[1,0]
	v_pk_mul_f32 v[54:55], v[54:55], v[174:175] op_sel_hi:[1,0]
	v_pk_mul_f32 v[52:53], v[52:53], v[174:175] op_sel_hi:[1,0]
	v_pk_mul_f32 v[174:175], v[50:51], v[174:175] op_sel_hi:[1,0]
	v_div_fixup_f32 v50, v173, v176, 1.0
	v_pk_fma_f32 v[80:81], v[88:89], v[80:81], v[84:85]
	v_pk_fma_f32 v[78:79], v[86:87], v[78:79], v[82:83]
	v_pk_mul_f32 v[86:87], v[16:17], v[52:53]
	v_pk_mul_f32 v[48:49], v[48:49], v[50:51] op_sel_hi:[1,0]
	v_pk_mul_f32 v[46:47], v[46:47], v[50:51] op_sel_hi:[1,0]
	v_pk_mul_f32 v[82:83], v[10:11], v[54:55]
	v_pk_mul_f32 v[84:85], v[14:15], v[174:175]
	v_pk_mul_f32 v[88:89], v[2:3], v[46:47]
	v_pk_mul_f32 v[174:175], v[4:5], v[48:49]
	v_cvt_pk_bf16_f32 v46, v78, v79
	v_cvt_pk_bf16_f32 v47, v80, v81
	global_store_dwordx2 v[102:103], v[46:47], off
	global_load_dwordx4 v[46:49], v[152:153], off
	s_nop 0
	global_load_dwordx4 v[52:55], v[148:149], off
	v_pk_mul_f32 v[74:75], v[6:7], v[74:75]
	v_pk_mul_f32 v[76:77], v[8:9], v[76:77]
	v_pk_mul_f32 v[70:71], v[10:11], v[70:71]
	v_pk_mul_f32 v[72:73], v[12:13], v[72:73]
	v_pk_mul_f32 v[66:67], v[66:67], v[14:15]
	v_pk_mul_f32 v[68:69], v[68:69], v[16:17]
	v_pk_mul_f32 v[62:63], v[2:3], v[62:63]
	v_pk_mul_f32 v[64:65], v[4:5], v[64:65]
	v_pk_mul_f32 v[58:59], v[6:7], v[58:59]
	v_pk_mul_f32 v[60:61], v[8:9], v[60:61]
	v_pk_mul_f32 v[56:57], v[12:13], v[56:57]
	v_mul_f32_e32 v196, v23, v23
	v_mul_f32_e32 v202, v25, v25
	v_mul_f32_e32 v213, v18, v18
	v_mul_f32_e32 v214, v19, v19
	v_mul_f32_e32 v215, v20, v20
	v_mul_f32_e32 v216, v21, v21
	v_pk_fma_f32 v[158:159], v[22:23], v[22:23], v[196:197] op_sel_hi:[1,1,0]
	v_pk_fma_f32 v[160:161], v[24:25], v[24:25], v[202:203] op_sel_hi:[1,1,0]
	v_mov_b32_e32 v159, v215
	v_mov_b32_e32 v161, v216
	v_lshl_add_u64 v[144:145], s[18:19], 0, v[90:91]
	v_lshl_add_u64 v[128:129], s[16:17], 0, v[90:91]
	v_lshl_add_u64 v[124:125], s[18:19], 0, v[96:97]
	v_lshl_add_u64 v[120:121], s[16:17], 0, v[96:97]
	v_lshl_add_u64 v[92:93], v[92:93], 0, s[12:13]
	v_lshl_add_u64 v[94:95], v[94:95], 0, s[14:15]
	s_mov_b32 s8, s24
	s_cmp_lt_i32 s24, s20
	s_waitcnt vmcnt(0) lgkmcnt(0)
	v_pk_add_f32 v[48:49], v[48:49], 1.0 op_sel_hi:[1,0]
	v_pk_add_f32 v[46:47], v[46:47], 1.0 op_sel_hi:[1,0]
	v_pk_fma_f32 v[48:49], v[48:49], v[76:77], v[54:55]
	v_pk_fma_f32 v[46:47], v[46:47], v[74:75], v[52:53]
	v_cvt_pk_bf16_f32 v46, v46, v47
	v_cvt_pk_bf16_f32 v47, v48, v49
	global_store_dwordx2 v[102:103], v[46:47], off offset:512
	global_load_dwordx4 v[46:49], v[146:147], off
	s_nop 0
	global_load_dwordx4 v[52:55], v[142:143], off
	s_waitcnt vmcnt(0) lgkmcnt(0)
	v_pk_add_f32 v[48:49], v[48:49], 1.0 op_sel_hi:[1,0]
	v_pk_add_f32 v[46:47], v[46:47], 1.0 op_sel_hi:[1,0]
	v_pk_fma_f32 v[48:49], v[72:73], v[48:49], v[54:55]
	v_pk_fma_f32 v[46:47], v[70:71], v[46:47], v[52:53]
	v_cvt_pk_bf16_f32 v46, v46, v47
	v_cvt_pk_bf16_f32 v47, v48, v49
	global_store_dwordx2 v[102:103], v[46:47], off offset:1024
	global_load_dwordx4 v[46:49], v[140:141], off
	s_nop 0
	global_load_dwordx4 v[52:55], v[132:133], off
	s_waitcnt vmcnt(0) lgkmcnt(0)
	v_pk_add_f32 v[48:49], v[48:49], 1.0 op_sel_hi:[1,0]
	v_pk_add_f32 v[46:47], v[46:47], 1.0 op_sel_hi:[1,0]
	v_pk_fma_f32 v[48:49], v[68:69], v[48:49], v[54:55]
	v_pk_fma_f32 v[46:47], v[66:67], v[46:47], v[52:53]
	v_cvt_pk_bf16_f32 v46, v46, v47
	v_cvt_pk_bf16_f32 v47, v48, v49
	global_store_dwordx2 v[102:103], v[46:47], off offset:1536
	global_load_dwordx4 v[46:49], v[136:137], off
	s_nop 0
	global_load_dwordx4 v[52:55], v[134:135], off
	s_waitcnt vmcnt(0) lgkmcnt(0)
	v_pk_add_f32 v[48:49], v[48:49], 1.0 op_sel_hi:[1,0]
	v_pk_add_f32 v[46:47], v[46:47], 1.0 op_sel_hi:[1,0]
	v_pk_fma_f32 v[48:49], v[48:49], v[64:65], v[54:55]
	v_pk_fma_f32 v[46:47], v[46:47], v[62:63], v[52:53]
	v_cvt_pk_bf16_f32 v46, v46, v47
	v_cvt_pk_bf16_f32 v47, v48, v49
	global_store_dwordx2 v[102:103], v[46:47], off offset:2048
	global_load_dwordx4 v[46:49], v[130:131], off
	s_nop 0
	global_load_dwordx4 v[52:55], v[126:127], off
	s_waitcnt vmcnt(0) lgkmcnt(0)
	v_pk_add_f32 v[48:49], v[48:49], 1.0 op_sel_hi:[1,0]
	v_pk_add_f32 v[46:47], v[46:47], 1.0 op_sel_hi:[1,0]
	v_pk_fma_f32 v[48:49], v[48:49], v[60:61], v[54:55]
	v_pk_fma_f32 v[46:47], v[46:47], v[58:59], v[52:53]
	v_cvt_pk_bf16_f32 v46, v46, v47
	v_cvt_pk_bf16_f32 v47, v48, v49
	global_store_dwordx2 v[102:103], v[46:47], off offset:2560
	global_load_dwordx4 v[46:49], v[122:123], off
	s_nop 0
	global_load_dwordx4 v[52:55], v[118:119], off
	v_pk_add_f32 v[58:59], v[164:165], v[164:165] op_sel:[0,1] op_sel_hi:[1,0]
	v_pk_add_f32 v[60:61], v[158:159], v[160:161]
	v_mov_b32_e32 v59, v214
	s_waitcnt vmcnt(0) lgkmcnt(0)
	v_pk_add_f32 v[48:49], v[48:49], 1.0 op_sel_hi:[1,0]
	v_pk_add_f32 v[46:47], v[46:47], 1.0 op_sel_hi:[1,0]
	v_pk_fma_f32 v[48:49], v[48:49], v[56:57], v[54:55]
	v_pk_fma_f32 v[46:47], v[46:47], v[82:83], v[52:53]
	v_cvt_pk_bf16_f32 v46, v46, v47
	v_cvt_pk_bf16_f32 v47, v48, v49
	global_store_dwordx2 v[102:103], v[46:47], off offset:3072
	global_load_dwordx4 v[46:49], v[116:117], off
	s_nop 0
	global_load_dwordx4 v[52:55], v[114:115], off
	v_pk_add_f32 v[56:57], v[162:163], v[162:163] op_sel:[0,1] op_sel_hi:[1,0]
	s_waitcnt vmcnt(0) lgkmcnt(0)
	v_pk_add_f32 v[48:49], v[48:49], 1.0 op_sel_hi:[1,0]
	v_pk_add_f32 v[46:47], v[46:47], 1.0 op_sel_hi:[1,0]
	v_pk_fma_f32 v[48:49], v[86:87], v[48:49], v[54:55]
	v_pk_fma_f32 v[46:47], v[84:85], v[46:47], v[52:53]
	v_cvt_pk_bf16_f32 v46, v46, v47
	v_cvt_pk_bf16_f32 v47, v48, v49
	global_store_dwordx2 v[102:103], v[46:47], off offset:3584
	global_load_dwordx4 v[46:49], v[156:157], off
	s_nop 0
	global_load_dwordx4 v[52:55], v[112:113], off
	v_mov_b32_e32 v57, v213
	s_waitcnt vmcnt(0) lgkmcnt(0)
	v_pk_add_f32 v[48:49], v[48:49], 1.0 op_sel_hi:[1,0]
	v_pk_add_f32 v[46:47], v[46:47], 1.0 op_sel_hi:[1,0]
	v_pk_fma_f32 v[48:49], v[48:49], v[174:175], v[54:55]
	v_pk_fma_f32 v[46:47], v[46:47], v[88:89], v[52:53]
	v_bfe_u32 v51, v46, 16, 1
	v_bfe_u32 v52, v47, 16, 1
	v_add3_u32 v46, v46, v51, s3
	v_add3_u32 v47, v47, v52, s3
	v_lshrrev_b32_e32 v46, 16, v46
	v_and_or_b32 v46, v47, s21, v46
	v_cvt_pk_bf16_f32 v47, v48, v49
	global_store_dwordx2 v[104:105], v[46:47], off
	global_load_dwordx4 v[46:49], v[154:155], off
	s_nop 0
	global_load_dwordx4 v[52:55], v[106:107], off
	v_pk_mul_f32 v[44:45], v[44:45], v[50:51] op_sel_hi:[1,0]
	v_pk_mul_f32 v[42:43], v[42:43], v[50:51] op_sel_hi:[1,0]
	v_pk_mul_f32 v[44:45], v[8:9], v[44:45]
	v_pk_mul_f32 v[42:43], v[6:7], v[42:43]
	s_waitcnt vmcnt(0) lgkmcnt(0)
	v_pk_add_f32 v[48:49], v[48:49], 1.0 op_sel_hi:[1,0]
	v_pk_add_f32 v[46:47], v[46:47], 1.0 op_sel_hi:[1,0]
	v_pk_fma_f32 v[44:45], v[48:49], v[44:45], v[54:55]
	v_pk_fma_f32 v[42:43], v[46:47], v[42:43], v[52:53]
	v_cvt_pk_bf16_f32 v42, v42, v43
	v_cvt_pk_bf16_f32 v43, v44, v45
	global_store_dwordx2 v[104:105], v[42:43], off offset:512
	global_load_dwordx4 v[42:45], v[150:151], off
	s_nop 0
	global_load_dwordx4 v[46:49], v[110:111], off
	v_pk_add_f32 v[52:53], v[56:57], v[58:59]
	s_waitcnt vmcnt(0) lgkmcnt(0)
	v_pk_add_f32 v[44:45], v[44:45], 1.0 op_sel_hi:[1,0]
	v_pk_add_f32 v[52:53], v[52:53], v[60:61]
	v_pk_add_f32 v[42:43], v[42:43], 1.0 op_sel_hi:[1,0]
	v_add_f32_e32 v51, v52, v53
	ds_bpermute_b32 v52, v1, v51
	s_waitcnt lgkmcnt(0)
	v_add_f32_e32 v51, v51, v52
	ds_bpermute_b32 v52, v166, v51
	s_waitcnt lgkmcnt(0)
	v_add_f32_e32 v51, v51, v52
	v_pk_mul_f32 v[40:41], v[40:41], v[50:51] op_sel_hi:[1,0]
	v_pk_mul_f32 v[38:39], v[38:39], v[50:51] op_sel_hi:[1,0]
	v_pk_mul_f32 v[40:41], v[12:13], v[40:41]
	v_pk_mul_f32 v[38:39], v[10:11], v[38:39]
	v_pk_fma_f32 v[40:41], v[44:45], v[40:41], v[48:49]
	v_pk_fma_f32 v[38:39], v[42:43], v[38:39], v[46:47]
	v_cvt_pk_bf16_f32 v38, v38, v39
	v_cvt_pk_bf16_f32 v39, v40, v41
	global_store_dwordx2 v[104:105], v[38:39], off offset:1024
	global_load_dwordx4 v[38:41], v[138:139], off
	s_nop 0
	global_load_dwordx4 v[42:45], v[108:109], off
	v_pk_mul_f32 v[36:37], v[36:37], v[50:51] op_sel_hi:[1,0]
	v_pk_mul_f32 v[34:35], v[34:35], v[50:51] op_sel_hi:[1,0]
	v_pk_mul_f32 v[36:37], v[16:17], v[36:37]
	v_pk_mul_f32 v[34:35], v[14:15], v[34:35]
	ds_bpermute_b32 v46, v167, v51
	s_waitcnt lgkmcnt(0)
	v_add_f32_e32 v46, v51, v46
	ds_bpermute_b32 v47, v168, v46
	s_waitcnt lgkmcnt(0)
	v_add_f32_e32 v46, v46, v47
	ds_bpermute_b32 v47, v169, v46
	s_waitcnt lgkmcnt(0)
	v_add_f32_e32 v46, v46, v47
	ds_bpermute_b32 v47, v170, v46
	s_waitcnt lgkmcnt(0)
	v_add_f32_e32 v46, v46, v47
	v_fmamk_f32 v46, v46, 0x3a800000, v171
	v_mul_f32_e32 v47, 0x4f800000, v46
	v_cmp_gt_f32_e32 vcc, s2, v46
	s_waitcnt vmcnt(0)
	v_pk_add_f32 v[40:41], v[40:41], 1.0 op_sel_hi:[1,0]
	v_pk_add_f32 v[38:39], v[38:39], 1.0 op_sel_hi:[1,0]
	v_pk_fma_f32 v[36:37], v[36:37], v[40:41], v[44:45]
	v_pk_fma_f32 v[34:35], v[34:35], v[38:39], v[42:43]
	v_cvt_pk_bf16_f32 v34, v34, v35
	v_cvt_pk_bf16_f32 v35, v36, v37
	global_store_dwordx2 v[104:105], v[34:35], off offset:1536
	global_load_dwordx4 v[34:37], v[144:145], off
	s_nop 0
	global_load_dwordx4 v[38:41], v[128:129], off
	v_cndmask_b32_e32 v42, v46, v47, vcc
	v_sqrt_f32_e32 v43, v42
	s_waitcnt vmcnt(0) lgkmcnt(0)
	v_pk_add_f32 v[36:37], v[36:37], 1.0 op_sel_hi:[1,0]
	v_add_u32_e32 v44, -1, v43
	v_add_u32_e32 v45, 1, v43
	v_fma_f32 v46, -v44, v43, v42
	v_fma_f32 v47, -v45, v43, v42
	v_cmp_ge_f32_e64 s[6:7], 0, v46
	v_pk_add_f32 v[34:35], v[34:35], 1.0 op_sel_hi:[1,0]
	s_nop 0
	v_cndmask_b32_e64 v43, v43, v44, s[6:7]
	v_cmp_lt_f32_e64 s[6:7], 0, v47
	s_nop 1
	v_cndmask_b32_e64 v43, v43, v45, s[6:7]
	v_mul_f32_e32 v44, 0x37800000, v43
	v_cndmask_b32_e32 v43, v43, v44, vcc
	v_cmp_class_f32_e32 vcc, v42, v172
	s_nop 1
	v_cndmask_b32_e32 v42, v43, v42, vcc
	v_div_scale_f32 v43, s[6:7], v42, v42, 1.0
	v_rcp_f32_e32 v45, v43
	v_div_scale_f32 v44, vcc, 1.0, v42, 1.0
	v_fma_f32 v46, -v43, v45, 1.0
	v_fmac_f32_e32 v45, v46, v45
	v_mul_f32_e32 v46, v44, v45
	v_fma_f32 v47, -v43, v46, v44
	v_fmac_f32_e32 v46, v47, v45
	v_fma_f32 v43, -v43, v46, v44
	v_div_fmas_f32 v43, v43, v45, v46
	v_div_fixup_f32 v42, v43, v42, 1.0
	v_pk_mul_f32 v[32:33], v[32:33], v[42:43] op_sel_hi:[1,0]
	v_pk_mul_f32 v[30:31], v[30:31], v[42:43] op_sel_hi:[1,0]
	v_pk_mul_f32 v[32:33], v[4:5], v[32:33]
	v_pk_mul_f32 v[30:31], v[2:3], v[30:31]
	v_pk_fma_f32 v[32:33], v[36:37], v[32:33], v[40:41]
	v_pk_fma_f32 v[30:31], v[34:35], v[30:31], v[38:39]
	v_cvt_pk_bf16_f32 v30, v30, v31
	v_cvt_pk_bf16_f32 v31, v32, v33
	global_store_dwordx2 v[104:105], v[30:31], off offset:2048
	global_load_dwordx4 v[30:33], v[124:125], off
	s_nop 0
	global_load_dwordx4 v[34:37], v[120:121], off
	v_pk_mul_f32 v[28:29], v[28:29], v[42:43] op_sel_hi:[1,0]
	v_pk_mul_f32 v[26:27], v[26:27], v[42:43] op_sel_hi:[1,0]
	v_pk_mul_f32 v[28:29], v[8:9], v[28:29]
	v_pk_mul_f32 v[26:27], v[6:7], v[26:27]
	v_lshl_add_u64 v[40:41], s[18:19], 0, v[98:99]
	v_lshl_add_u64 v[38:39], s[16:17], 0, v[98:99]
	v_pk_mul_f32 v[24:25], v[24:25], v[42:43] op_sel_hi:[1,0]
	v_pk_mul_f32 v[22:23], v[22:23], v[42:43] op_sel_hi:[1,0]
	v_pk_mul_f32 v[24:25], v[12:13], v[24:25]
	v_pk_mul_f32 v[22:23], v[10:11], v[22:23]
	v_pk_mul_f32 v[20:21], v[20:21], v[42:43] op_sel_hi:[1,0]
	v_pk_mul_f32 v[18:19], v[18:19], v[42:43] op_sel_hi:[1,0]
	v_pk_mul_f32 v[20:21], v[16:17], v[20:21]
	v_pk_mul_f32 v[18:19], v[14:15], v[18:19]
	s_waitcnt vmcnt(0) lgkmcnt(0)
	v_pk_add_f32 v[32:33], v[32:33], 1.0 op_sel_hi:[1,0]
	v_pk_add_f32 v[30:31], v[30:31], 1.0 op_sel_hi:[1,0]
	v_pk_fma_f32 v[28:29], v[32:33], v[28:29], v[36:37]
	v_pk_fma_f32 v[26:27], v[30:31], v[26:27], v[34:35]
	v_cvt_pk_bf16_f32 v26, v26, v27
	v_cvt_pk_bf16_f32 v27, v28, v29
	global_store_dwordx2 v[104:105], v[26:27], off offset:2560
	global_load_dwordx4 v[26:29], v[40:41], off
	s_nop 0
	global_load_dwordx4 v[30:33], v[38:39], off
	v_lshl_add_u64 v[36:37], s[18:19], 0, v[100:101]
	v_lshl_add_u64 v[34:35], s[16:17], 0, v[100:101]
	s_waitcnt vmcnt(0) lgkmcnt(0)
	v_pk_add_f32 v[28:29], v[28:29], 1.0 op_sel_hi:[1,0]
	v_pk_add_f32 v[26:27], v[26:27], 1.0 op_sel_hi:[1,0]
	v_pk_fma_f32 v[24:25], v[28:29], v[24:25], v[32:33]
	v_pk_fma_f32 v[22:23], v[26:27], v[22:23], v[30:31]
	v_cvt_pk_bf16_f32 v22, v22, v23
	v_cvt_pk_bf16_f32 v23, v24, v25
	global_store_dwordx2 v[104:105], v[22:23], off offset:3072
	global_load_dwordx4 v[22:25], v[36:37], off
	s_nop 0
	global_load_dwordx4 v[26:29], v[34:35], off
	s_waitcnt vmcnt(0) lgkmcnt(0)
	v_pk_add_f32 v[24:25], v[24:25], 1.0 op_sel_hi:[1,0]
	v_pk_add_f32 v[22:23], v[22:23], 1.0 op_sel_hi:[1,0]
	v_pk_fma_f32 v[20:21], v[20:21], v[24:25], v[28:29]
	v_pk_fma_f32 v[18:19], v[18:19], v[22:23], v[26:27]
	v_cvt_pk_bf16_f32 v18, v18, v19
	v_cvt_pk_bf16_f32 v19, v20, v21
	global_store_dwordx2 v[104:105], v[18:19], off offset:3584
	s_cbranch_scc1 .LBB0_5693
